# rotate fold extended: producers sunk past readers of the old pair (10 sites) + second fold iteration (5 sites), pad rule kept
# speedup vs baseline: 1.0112x; 1.0104x over previous
.LBB0_134:
	global_load_dword v6, v[22:23], off
	v_lshrrev_b32_e32 v26, 2, v11
	v_add_u32_e32 v25, 0x200, v25
	v_and_b32_e32 v26, 0x3ffffff8, v26
	v_cmp_lt_u32_e32 vcc, s34, v25
	v_add_u32_e32 v11, 8, v11
	v_lshl_add_u64 v[22:23], v[22:23], 0, s[26:27]
	v_add_u32_e32 v26, v24, v26
	v_add_u32_e32 v24, 64, v24
	s_or_b64 s[62:63], vcc, s[62:63]
	s_waitcnt vmcnt(0)
	ds_write_b64 v26, v[6:7]
	s_andn2_b64 exec, exec, s[62:63]
	s_cbranch_execnz .LBB0_134
	s_or_b64 exec, exec, s[62:63]
	v_mov_b32_e32 v6, v62
	s_waitcnt lgkmcnt(0)
	s_barrier
	s_mov_b32 s43, s40
	v_and_b32_e32 v11, 15, v6
	v_cvt_f32_ubyte0_e32 v22, v11
	v_mul_f32_e32 v23, 0x3b800000, v22
	v_sin_f32_e32 v22, v23
	v_cos_f32_e32 v24, v23
	v_lshlrev_b32_e32 v6, 4, v6
	v_and_b32_e32 v6, 0xffffff00, v6
	v_xor_b32_e32 v25, 0x80000000, v22
	v_mov_b32_e32 v23, v25
	v_pk_mul_f32 v[26:27], v[24:25], v[22:23] op_sel:[1,0] op_sel_hi:[0,1]
	v_pk_fma_f32 v[26:27], v[24:25], v[24:25], v[26:27] op_sel_hi:[1,0,1]
	v_lshlrev_b32_e32 v11, 3, v11
	v_xor_b32_e32 v32, 0x80000000, v27
	v_mov_b32_e32 v33, v27
	v_pk_mul_f32 v[30:31], v[26:27], v[32:33] op_sel:[1,0] op_sel_hi:[0,1]
	v_pk_fma_f32 v[30:31], v[26:27], v[26:27], v[30:31] op_sel_hi:[1,0,1]
	v_pk_mul_f32 v[28:29], v[22:23], v[26:27] op_sel:[0,1] op_sel_hi:[1,0]
	v_xor_b32_e32 v34, 0x80000000, v31
	v_mov_b32_e32 v35, v31
	v_pk_mul_f32 v[50:51], v[30:31], v[34:35] op_sel:[1,0] op_sel_hi:[0,1]
	v_pk_fma_f32 v[50:51], v[30:31], v[30:31], v[50:51] op_sel_hi:[1,0,1]
	v_pk_mul_f32 v[36:37], v[22:23], v[30:31] op_sel:[0,1] op_sel_hi:[1,0]
	v_pk_mul_f32 v[70:71], v[34:35], v[50:51] op_sel:[0,1] op_sel_hi:[1,0]
	v_pk_mul_f32 v[54:55], v[22:23], v[50:51] op_sel:[0,1] op_sel_hi:[1,0]
	v_pk_fma_f32 v[70:71], v[30:31], v[50:51], v[70:71] op_sel_hi:[0,1,1]
	v_pk_mul_f32 v[74:75], v[22:23], v[70:71] op_sel:[0,1] op_sel_hi:[1,0]
	v_pk_fma_f32 v[28:29], v[24:25], v[26:27], v[28:29] op_sel_hi:[0,1,1]
	v_pk_fma_f32 v[36:37], v[24:25], v[30:31], v[36:37] op_sel_hi:[0,1,1]
	v_pk_fma_f32 v[54:55], v[24:25], v[50:51], v[54:55] op_sel_hi:[0,1,1]
	v_pk_fma_f32 v[74:75], v[24:25], v[70:71], v[74:75] op_sel_hi:[0,1,1]
	v_lshlrev_b32_e32 v25, 3, v6
	v_add3_u32 v11, 0, v11, v25
	v_ashrrev_i32_e32 v25, 2, v6
	v_add_u32_e32 v25, v11, v25
	ds_read2_b64 v[92:95], v25 offset1:16
	ds_read2_b64 v[96:99], v25 offset0:33 offset1:49
	ds_read2_b64 v[100:103], v25 offset0:66 offset1:82
	ds_read2_b64 v[104:107], v25 offset0:132 offset1:148
	ds_read2_b64 v[108:111], v25 offset0:99 offset1:115
	ds_read2_b64 v[112:115], v25 offset0:165 offset1:181
	ds_read2_b64 v[116:119], v25 offset0:198 offset1:214
	ds_read2_b64 v[120:123], v25 offset0:231 offset1:247
	s_waitcnt lgkmcnt(4)
	v_pk_add_f32 v[124:125], v[92:93], v[104:105]
	v_pk_add_f32 v[92:93], v[92:93], v[104:105] neg_lo:[0,1] neg_hi:[0,1]
	v_pk_add_f32 v[104:105], v[94:95], v[106:107]
	v_pk_add_f32 v[94:95], v[94:95], v[106:107] neg_lo:[0,1] neg_hi:[0,1]
	s_mov_b32 s45, s36
	v_pk_mul_f32 v[106:107], v[94:95], s[38:39]
	s_waitcnt lgkmcnt(1)
	v_pk_add_f32 v[126:127], v[102:103], v[118:119]
	v_pk_fma_f32 v[94:95], v[94:95], s[36:37], v[106:107] op_sel:[0,0,1] op_sel_hi:[1,0,0]
	v_pk_add_f32 v[106:107], v[96:97], v[112:113]
	v_pk_add_f32 v[96:97], v[96:97], v[112:113] neg_lo:[0,1] neg_hi:[0,1]
	v_pk_add_f32 v[102:103], v[102:103], v[118:119] neg_lo:[0,1] neg_hi:[0,1]
	v_pk_mul_f32 v[112:113], v[96:97], s[42:43]
	s_mov_b32 s62, s39
	v_pk_mul_f32 v[118:119], v[102:103], s[44:45]
	v_pk_fma_f32 v[96:97], v[96:97], s[40:41], v[112:113] op_sel:[0,0,1] op_sel_hi:[1,0,0]
	v_pk_add_f32 v[112:113], v[98:99], v[114:115]
	v_pk_add_f32 v[98:99], v[98:99], v[114:115] neg_lo:[0,1] neg_hi:[0,1]
	v_pk_fma_f32 v[102:103], v[102:103], s[62:63], v[118:119] op_sel:[0,0,1] op_sel_hi:[1,0,0] neg_lo:[1,0,0] neg_hi:[1,0,0]
	s_waitcnt lgkmcnt(0)
	v_pk_add_f32 v[118:119], v[108:109], v[120:121]
	v_pk_add_f32 v[108:109], v[108:109], v[120:121] neg_lo:[0,1] neg_hi:[0,1]
	v_pk_mul_f32 v[114:115], v[98:99], s[44:45]
	v_pk_mul_f32 v[120:121], v[108:109], s[42:43]
	v_pk_fma_f32 v[98:99], v[98:99], s[62:63], v[114:115] op_sel:[0,0,1] op_sel_hi:[1,0,0]
	v_pk_add_f32 v[114:115], v[100:101], v[116:117]
	v_pk_add_f32 v[116:117], v[100:101], v[116:117] neg_lo:[0,1] neg_hi:[0,1]
	v_pk_fma_f32 v[108:109], v[108:109], s[40:41], v[120:121] op_sel:[0,0,1] op_sel_hi:[1,0,0] neg_lo:[1,0,0] neg_hi:[1,0,0]
	v_pk_add_f32 v[120:121], v[110:111], v[122:123]
	v_pk_add_f32 v[110:111], v[110:111], v[122:123] neg_lo:[0,1] neg_hi:[0,1]
	s_nop 0
	v_pk_mul_f32 v[122:123], v[110:111], s[38:39]
	s_nop 0
	v_pk_fma_f32 v[110:111], v[110:111], s[36:37], v[122:123] op_sel:[0,0,1] op_sel_hi:[1,0,0] neg_lo:[1,0,0] neg_hi:[1,0,0]
	v_pk_add_f32 v[122:123], v[124:125], v[114:115]
	v_pk_add_f32 v[114:115], v[124:125], v[114:115] neg_lo:[0,1] neg_hi:[0,1]
	v_pk_add_f32 v[124:125], v[104:105], v[126:127]
	v_pk_add_f32 v[104:105], v[104:105], v[126:127] neg_lo:[0,1] neg_hi:[0,1]
	v_pk_add_f32 v[128:129], v[112:113], v[120:121]
	v_pk_add_f32 v[112:113], v[112:113], v[120:121] neg_lo:[0,1] neg_hi:[0,1]
	v_pk_add_f32 v[100:101], v[92:93], v[116:117] op_sel:[0,1] op_sel_hi:[1,0] neg_hi:[0,1]
	v_pk_add_f32 v[92:93], v[92:93], v[116:117] op_sel:[0,1] op_sel_hi:[1,0] neg_lo:[0,1]
	v_pk_add_f32 v[116:117], v[94:95], v[102:103]
	v_pk_add_f32 v[94:95], v[94:95], v[102:103] neg_lo:[0,1] neg_hi:[0,1]
	v_pk_mul_f32 v[126:127], v[104:105], s[42:43]
	v_pk_mul_f32 v[120:121], v[112:113], s[42:43]
	v_pk_mul_f32 v[102:103], v[94:95], s[42:43]
	v_pk_fma_f32 v[104:105], v[104:105], s[40:41], v[126:127] op_sel:[0,0,1] op_sel_hi:[1,0,0]
	v_pk_add_f32 v[126:127], v[106:107], v[118:119]
	v_pk_add_f32 v[118:119], v[106:107], v[118:119] neg_lo:[0,1] neg_hi:[0,1]
	v_pk_fma_f32 v[112:113], v[112:113], s[40:41], v[120:121] op_sel:[0,0,1] op_sel_hi:[1,0,0] neg_lo:[1,0,0] neg_hi:[1,0,0]
	v_pk_fma_f32 v[94:95], v[94:95], s[40:41], v[102:103] op_sel:[0,0,1] op_sel_hi:[1,0,0]
	v_pk_add_f32 v[102:103], v[96:97], v[108:109]
	v_pk_add_f32 v[120:121], v[98:99], v[110:111]
	v_pk_add_f32 v[98:99], v[98:99], v[110:111] neg_lo:[0,1] neg_hi:[0,1]
	v_pk_add_f32 v[108:109], v[96:97], v[108:109] neg_lo:[0,1] neg_hi:[0,1]
	v_pk_mul_f32 v[110:111], v[98:99], s[42:43]
	v_pk_add_f32 v[130:131], v[100:101], v[102:103]
	v_pk_add_f32 v[100:101], v[100:101], v[102:103] neg_lo:[0,1] neg_hi:[0,1]
	v_pk_add_f32 v[102:103], v[116:117], v[120:121]
	v_pk_add_f32 v[120:121], v[116:117], v[120:121] neg_lo:[0,1] neg_hi:[0,1]
	v_xor_b32_e32 v38, 0x80000000, v29
	v_mov_b32_e32 v39, v29
	v_pk_mul_f32 v[42:43], v[32:33], v[30:31] op_sel:[0,1] op_sel_hi:[1,0]
	v_pk_fma_f32 v[98:99], v[98:99], s[40:41], v[110:111] op_sel:[0,0,1] op_sel_hi:[1,0,0] neg_lo:[1,0,0] neg_hi:[1,0,0]
	v_pk_add_f32 v[106:107], v[114:115], v[118:119] op_sel:[0,1] op_sel_hi:[1,0] neg_hi:[0,1]
	v_pk_add_f32 v[114:115], v[114:115], v[118:119] op_sel:[0,1] op_sel_hi:[1,0] neg_lo:[0,1]
	v_pk_add_f32 v[118:119], v[104:105], v[112:113]
	v_pk_add_f32 v[112:113], v[104:105], v[112:113] neg_lo:[0,1] neg_hi:[0,1]
	v_xor_b32_e32 v40, 0x80000000, v37
	v_mov_b32_e32 v41, v37
	v_pk_fma_f32 v[42:43], v[26:27], v[30:31], v[42:43] op_sel_hi:[0,1,1]
	v_pk_mul_f32 v[46:47], v[30:31], v[38:39] op_sel:[1,0] op_sel_hi:[0,1]
	v_pk_add_f32 v[96:97], v[92:93], v[108:109] op_sel:[0,1] op_sel_hi:[1,0] neg_hi:[0,1]
	v_pk_add_f32 v[92:93], v[92:93], v[108:109] op_sel:[0,1] op_sel_hi:[1,0] neg_lo:[0,1]
	v_pk_add_f32 v[108:109], v[94:95], v[98:99]
	v_pk_add_f32 v[98:99], v[94:95], v[98:99] neg_lo:[0,1] neg_hi:[0,1]
	v_pk_add_f32 v[116:117], v[100:101], v[120:121] op_sel:[0,1] op_sel_hi:[1,0] neg_hi:[0,1]
	v_xor_b32_e32 v44, 0x80000000, v43
	v_mov_b32_e32 v45, v43
	v_pk_fma_f32 v[46:47], v[30:31], v[28:29], v[46:47] op_sel_hi:[1,0,1]
	v_pk_add_f32 v[104:105], v[114:115], v[112:113] op_sel:[0,1] op_sel_hi:[1,0] neg_hi:[0,1]
	v_pk_add_f32 v[100:101], v[100:101], v[120:121] op_sel:[0,1] op_sel_hi:[1,0] neg_lo:[0,1]
	v_pk_mul_f32 v[120:121], v[40:41], v[116:117] op_sel:[0,1] op_sel_hi:[1,0]
	v_xor_b32_e32 v48, 0x80000000, v47
	v_mov_b32_e32 v49, v47
	v_pk_add_f32 v[110:111], v[122:123], v[126:127]
	v_pk_add_f32 v[122:123], v[122:123], v[126:127] neg_lo:[0,1] neg_hi:[0,1]
	v_pk_add_f32 v[126:127], v[124:125], v[128:129]
	v_pk_add_f32 v[94:95], v[92:93], v[98:99] op_sel:[0,1] op_sel_hi:[1,0] neg_hi:[0,1]
	v_pk_fma_f32 v[116:117], v[36:37], v[116:117], v[120:121] op_sel_hi:[0,1,1]
	v_pk_mul_f32 v[120:121], v[44:45], v[104:105] op_sel:[0,1] op_sel_hi:[1,0]
	v_xor_b32_e32 v52, 0x80000000, v51
	v_mov_b32_e32 v53, v51
	v_pk_mul_f32 v[58:59], v[32:33], v[50:51] op_sel:[0,1] op_sel_hi:[1,0]
	v_pk_add_f32 v[132:133], v[110:111], v[126:127]
	v_pk_add_f32 v[110:111], v[110:111], v[126:127] neg_lo:[0,1] neg_hi:[0,1]
	v_pk_fma_f32 v[104:105], v[42:43], v[104:105], v[120:121] op_sel_hi:[0,1,1]
	v_pk_mul_f32 v[120:121], v[48:49], v[94:95] op_sel:[0,1] op_sel_hi:[1,0]
	v_xor_b32_e32 v56, 0x80000000, v55
	v_mov_b32_e32 v57, v55
	v_pk_fma_f32 v[58:59], v[26:27], v[50:51], v[58:59] op_sel_hi:[0,1,1]
	v_pk_mul_f32 v[66:67], v[38:39], v[50:51] op_sel:[0,1] op_sel_hi:[1,0]
	v_pk_add_f32 v[112:113], v[114:115], v[112:113] op_sel:[0,1] op_sel_hi:[1,0] neg_lo:[0,1]
	v_pk_add_f32 v[114:115], v[130:131], v[102:103]
	v_pk_add_f32 v[102:103], v[130:131], v[102:103] neg_lo:[0,1] neg_hi:[0,1]
	v_pk_fma_f32 v[94:95], v[46:47], v[94:95], v[120:121] op_sel_hi:[0,1,1]
	v_pk_mul_f32 v[120:121], v[52:53], v[110:111] op_sel:[0,1] op_sel_hi:[1,0]
	v_xor_b32_e32 v60, 0x80000000, v59
	v_mov_b32_e32 v61, v59
	v_pk_fma_f32 v[66:67], v[28:29], v[50:51], v[66:67] op_sel_hi:[0,1,1]
	v_pk_add_f32 v[128:129], v[124:125], v[128:129] neg_lo:[0,1] neg_hi:[0,1]
	v_pk_add_f32 v[126:127], v[106:107], v[118:119]
	v_pk_add_f32 v[106:107], v[106:107], v[118:119] neg_lo:[0,1] neg_hi:[0,1]
	v_pk_fma_f32 v[110:111], v[50:51], v[110:111], v[120:121] op_sel_hi:[0,1,1]
	v_pk_mul_f32 v[120:121], v[56:57], v[102:103] op_sel:[0,1] op_sel_hi:[1,0]
	v_xor_b32_e32 v68, 0x80000000, v67
	v_mov_b32_e32 v69, v67
	v_pk_add_f32 v[118:119], v[96:97], v[108:109]
	v_pk_add_f32 v[96:97], v[96:97], v[108:109] neg_lo:[0,1] neg_hi:[0,1]
	v_pk_fma_f32 v[102:103], v[54:55], v[102:103], v[120:121] op_sel_hi:[0,1,1]
	v_pk_mul_f32 v[120:121], v[60:61], v[106:107] op_sel:[0,1] op_sel_hi:[1,0]
	v_xor_b32_e32 v72, 0x80000000, v71
	v_mov_b32_e32 v73, v71
	v_pk_mul_f32 v[78:79], v[32:33], v[70:71] op_sel:[0,1] op_sel_hi:[1,0]
	v_pk_add_f32 v[124:125], v[122:123], v[128:129] op_sel:[0,1] op_sel_hi:[1,0] neg_hi:[0,1]
	v_pk_add_f32 v[122:123], v[122:123], v[128:129] op_sel:[0,1] op_sel_hi:[1,0] neg_lo:[0,1]
	v_pk_fma_f32 v[106:107], v[58:59], v[106:107], v[120:121] op_sel_hi:[0,1,1]
	v_pk_mul_f32 v[120:121], v[68:69], v[96:97] op_sel:[0,1] op_sel_hi:[1,0]
	v_xor_b32_e32 v76, 0x80000000, v75
	v_mov_b32_e32 v77, v75
	v_pk_fma_f32 v[78:79], v[26:27], v[70:71], v[78:79] op_sel_hi:[0,1,1]
	v_pk_mul_f32 v[82:83], v[38:39], v[70:71] op_sel:[0,1] op_sel_hi:[1,0]
	v_pk_fma_f32 v[96:97], v[66:67], v[96:97], v[120:121] op_sel_hi:[0,1,1]
	v_pk_mul_f32 v[120:121], v[72:73], v[122:123] op_sel:[0,1] op_sel_hi:[1,0]
	v_xor_b32_e32 v80, 0x80000000, v79
	v_mov_b32_e32 v81, v79
	v_pk_fma_f32 v[82:83], v[28:29], v[70:71], v[82:83] op_sel_hi:[0,1,1]
	v_pk_add_f32 v[92:93], v[92:93], v[98:99] op_sel:[0,1] op_sel_hi:[1,0] neg_lo:[0,1]
	v_pk_mul_f32 v[98:99], v[22:23], v[114:115] op_sel:[0,1] op_sel_hi:[1,0]
	v_pk_fma_f32 v[120:121], v[70:71], v[122:123], v[120:121] op_sel_hi:[0,1,1]
	v_pk_mul_f32 v[122:123], v[76:77], v[100:101] op_sel:[0,1] op_sel_hi:[1,0]
	v_xor_b32_e32 v84, 0x80000000, v83
	v_mov_b32_e32 v85, v83
	v_pk_fma_f32 v[98:99], v[24:25], v[114:115], v[98:99] op_sel_hi:[0,1,1]
	v_pk_mul_f32 v[114:115], v[38:39], v[118:119] op_sel:[0,1] op_sel_hi:[1,0]
	v_pk_fma_f32 v[100:101], v[74:75], v[100:101], v[122:123] op_sel_hi:[0,1,1]
	v_pk_mul_f32 v[122:123], v[80:81], v[112:113] op_sel:[0,1] op_sel_hi:[1,0]
	v_add_u32_e32 v6, 0x2000, v6
	v_pk_mul_f32 v[108:109], v[32:33], v[126:127] op_sel:[0,1] op_sel_hi:[1,0]
	v_pk_fma_f32 v[114:115], v[28:29], v[118:119], v[114:115] op_sel_hi:[0,1,1]
	v_pk_mul_f32 v[118:119], v[34:35], v[124:125] op_sel:[0,1] op_sel_hi:[1,0]
	v_pk_fma_f32 v[112:113], v[78:79], v[112:113], v[122:123] op_sel_hi:[0,1,1]
	v_pk_mul_f32 v[122:123], v[84:85], v[92:93] op_sel:[0,1] op_sel_hi:[1,0]
	v_ashrrev_i32_e32 v6, 2, v6
	v_pk_fma_f32 v[108:109], v[26:27], v[126:127], v[108:109] op_sel_hi:[0,1,1]
	v_pk_fma_f32 v[118:119], v[30:31], v[124:125], v[118:119] op_sel_hi:[0,1,1]
	v_pk_fma_f32 v[92:93], v[82:83], v[92:93], v[122:123] op_sel_hi:[0,1,1]
	ds_write2_b64 v25, v[132:133], v[110:111] offset1:16
	ds_write2_b64 v25, v[118:119], v[120:121] offset0:33 offset1:49
	ds_write2_b64 v25, v[108:109], v[106:107] offset0:66 offset1:82
	ds_write2_b64 v25, v[104:105], v[112:113] offset0:99 offset1:115
	ds_write2_b64 v25, v[98:99], v[102:103] offset0:132 offset1:148
	ds_write2_b64 v25, v[116:117], v[100:101] offset0:165 offset1:181
	ds_write2_b64 v25, v[114:115], v[96:97] offset0:198 offset1:214
	ds_write2_b64 v25, v[94:95], v[92:93] offset0:231 offset1:247
	v_add3_u32 v6, v11, v6, s35
	ds_read2_b64 v[92:95], v6 offset1:16
	ds_read2_b64 v[96:99], v6 offset0:33 offset1:49
	ds_read2_b64 v[100:103], v6 offset0:66 offset1:82
	ds_read2_b64 v[104:107], v6 offset0:132 offset1:148
	ds_read2_b64 v[108:111], v6 offset0:99 offset1:115
	ds_read2_b64 v[112:115], v6 offset0:165 offset1:181
	ds_read2_b64 v[116:119], v6 offset0:198 offset1:214
	ds_read2_b64 v[120:123], v6 offset0:231 offset1:247
	s_waitcnt lgkmcnt(4)
	v_pk_add_f32 v[124:125], v[92:93], v[104:105]
	v_pk_add_f32 v[92:93], v[92:93], v[104:105] neg_lo:[0,1] neg_hi:[0,1]
	v_pk_add_f32 v[104:105], v[94:95], v[106:107]
	v_pk_add_f32 v[94:95], v[94:95], v[106:107] neg_lo:[0,1] neg_hi:[0,1]
	s_waitcnt lgkmcnt(1)
	v_pk_add_f32 v[126:127], v[102:103], v[118:119]
	v_pk_mul_f32 v[106:107], v[94:95], s[38:39]
	v_pk_add_f32 v[102:103], v[102:103], v[118:119] neg_lo:[0,1] neg_hi:[0,1]
	v_pk_fma_f32 v[94:95], v[94:95], s[36:37], v[106:107] op_sel:[0,0,1] op_sel_hi:[1,0,0]
	v_pk_add_f32 v[106:107], v[96:97], v[112:113]
	v_pk_add_f32 v[96:97], v[96:97], v[112:113] neg_lo:[0,1] neg_hi:[0,1]
	v_pk_mul_f32 v[118:119], v[102:103], s[44:45]
	v_pk_mul_f32 v[112:113], v[96:97], s[42:43]
	v_pk_fma_f32 v[102:103], v[102:103], s[62:63], v[118:119] op_sel:[0,0,1] op_sel_hi:[1,0,0] neg_lo:[1,0,0] neg_hi:[1,0,0]
	s_waitcnt lgkmcnt(0)
	v_pk_add_f32 v[118:119], v[108:109], v[120:121]
	v_pk_add_f32 v[108:109], v[108:109], v[120:121] neg_lo:[0,1] neg_hi:[0,1]
	v_pk_fma_f32 v[96:97], v[96:97], s[40:41], v[112:113] op_sel:[0,0,1] op_sel_hi:[1,0,0]
	v_pk_add_f32 v[112:113], v[98:99], v[114:115]
	v_pk_add_f32 v[98:99], v[98:99], v[114:115] neg_lo:[0,1] neg_hi:[0,1]
	v_pk_mul_f32 v[120:121], v[108:109], s[42:43]
	v_pk_mul_f32 v[114:115], v[98:99], s[44:45]
	v_pk_fma_f32 v[108:109], v[108:109], s[40:41], v[120:121] op_sel:[0,0,1] op_sel_hi:[1,0,0] neg_lo:[1,0,0] neg_hi:[1,0,0]
	v_pk_add_f32 v[120:121], v[110:111], v[122:123]
	v_pk_add_f32 v[110:111], v[110:111], v[122:123] neg_lo:[0,1] neg_hi:[0,1]
	v_pk_fma_f32 v[98:99], v[98:99], s[62:63], v[114:115] op_sel:[0,0,1] op_sel_hi:[1,0,0]
	v_pk_add_f32 v[114:115], v[100:101], v[116:117]
	v_pk_mul_f32 v[122:123], v[110:111], s[38:39]
	v_pk_add_f32 v[116:117], v[100:101], v[116:117] neg_lo:[0,1] neg_hi:[0,1]
	v_pk_fma_f32 v[110:111], v[110:111], s[36:37], v[122:123] op_sel:[0,0,1] op_sel_hi:[1,0,0] neg_lo:[1,0,0] neg_hi:[1,0,0]
	v_pk_add_f32 v[122:123], v[124:125], v[114:115]
	v_pk_add_f32 v[114:115], v[124:125], v[114:115] neg_lo:[0,1] neg_hi:[0,1]
	v_pk_add_f32 v[124:125], v[104:105], v[126:127]
	v_pk_add_f32 v[104:105], v[104:105], v[126:127] neg_lo:[0,1] neg_hi:[0,1]
	s_nop 0
	v_pk_mul_f32 v[126:127], v[104:105], s[42:43]
	v_pk_add_f32 v[128:129], v[112:113], v[120:121]
	v_pk_add_f32 v[112:113], v[112:113], v[120:121] neg_lo:[0,1] neg_hi:[0,1]
	v_pk_fma_f32 v[104:105], v[104:105], s[40:41], v[126:127] op_sel:[0,0,1] op_sel_hi:[1,0,0]
	v_pk_add_f32 v[126:127], v[106:107], v[118:119]
	v_pk_add_f32 v[118:119], v[106:107], v[118:119] neg_lo:[0,1] neg_hi:[0,1]
	v_pk_mul_f32 v[120:121], v[112:113], s[42:43]
	v_pk_add_f32 v[100:101], v[92:93], v[116:117] op_sel:[0,1] op_sel_hi:[1,0] neg_hi:[0,1]
	v_pk_add_f32 v[92:93], v[92:93], v[116:117] op_sel:[0,1] op_sel_hi:[1,0] neg_lo:[0,1]
	v_pk_add_f32 v[116:117], v[94:95], v[102:103]
	v_pk_add_f32 v[94:95], v[94:95], v[102:103] neg_lo:[0,1] neg_hi:[0,1]
	v_pk_fma_f32 v[112:113], v[112:113], s[40:41], v[120:121] op_sel:[0,0,1] op_sel_hi:[1,0,0] neg_lo:[1,0,0] neg_hi:[1,0,0]
	v_pk_mul_f32 v[102:103], v[94:95], s[42:43]
	s_nop 0
	v_pk_fma_f32 v[94:95], v[94:95], s[40:41], v[102:103] op_sel:[0,0,1] op_sel_hi:[1,0,0]
	v_pk_add_f32 v[102:103], v[96:97], v[108:109]
	v_pk_add_f32 v[120:121], v[98:99], v[110:111]
	v_pk_add_f32 v[98:99], v[98:99], v[110:111] neg_lo:[0,1] neg_hi:[0,1]
	v_pk_add_f32 v[106:107], v[114:115], v[118:119] op_sel:[0,1] op_sel_hi:[1,0] neg_hi:[0,1]
	v_pk_add_f32 v[114:115], v[114:115], v[118:119] op_sel:[0,1] op_sel_hi:[1,0] neg_lo:[0,1]
	v_pk_add_f32 v[118:119], v[104:105], v[112:113]
	v_pk_add_f32 v[112:113], v[104:105], v[112:113] neg_lo:[0,1] neg_hi:[0,1]
	v_pk_add_f32 v[108:109], v[96:97], v[108:109] neg_lo:[0,1] neg_hi:[0,1]
	v_pk_mul_f32 v[110:111], v[98:99], s[42:43]
	v_pk_add_f32 v[130:131], v[100:101], v[102:103]
	v_pk_add_f32 v[100:101], v[100:101], v[102:103] neg_lo:[0,1] neg_hi:[0,1]
	v_pk_add_f32 v[102:103], v[116:117], v[120:121]
	v_pk_fma_f32 v[98:99], v[98:99], s[40:41], v[110:111] op_sel:[0,0,1] op_sel_hi:[1,0,0] neg_lo:[1,0,0] neg_hi:[1,0,0]
	v_pk_add_f32 v[110:111], v[122:123], v[126:127]
	v_pk_add_f32 v[122:123], v[122:123], v[126:127] neg_lo:[0,1] neg_hi:[0,1]
	v_pk_add_f32 v[126:127], v[124:125], v[128:129]
	v_pk_add_f32 v[104:105], v[114:115], v[112:113] op_sel:[0,1] op_sel_hi:[1,0] neg_hi:[0,1]
	v_pk_add_f32 v[112:113], v[114:115], v[112:113] op_sel:[0,1] op_sel_hi:[1,0] neg_lo:[0,1]
	v_pk_add_f32 v[114:115], v[130:131], v[102:103]
	v_pk_add_f32 v[124:125], v[124:125], v[128:129] neg_lo:[0,1] neg_hi:[0,1]
	v_pk_add_f32 v[96:97], v[92:93], v[108:109] op_sel:[0,1] op_sel_hi:[1,0] neg_hi:[0,1]
	v_pk_add_f32 v[92:93], v[92:93], v[108:109] op_sel:[0,1] op_sel_hi:[1,0] neg_lo:[0,1]
	v_pk_add_f32 v[108:109], v[94:95], v[98:99]
	v_pk_add_f32 v[132:133], v[110:111], v[126:127]
	v_pk_add_f32 v[110:111], v[110:111], v[126:127] neg_lo:[0,1] neg_hi:[0,1]
	v_pk_add_f32 v[126:127], v[106:107], v[118:119]
	v_pk_mul_f32 v[22:23], v[22:23], v[114:115] op_sel:[0,1] op_sel_hi:[1,0]
	v_xor_b32_e32 v129, 0x80000000, v124
	v_pk_add_f32 v[116:117], v[116:117], v[120:121] neg_lo:[0,1] neg_hi:[0,1]
	v_mov_b32_e32 v128, v125
	v_pk_add_f32 v[106:107], v[106:107], v[118:119] neg_lo:[0,1] neg_hi:[0,1]
	v_pk_add_f32 v[118:119], v[96:97], v[108:109]
	v_pk_fma_f32 v[22:23], v[24:25], v[114:115], v[22:23] op_sel_hi:[0,1,1]
	v_pk_mul_f32 v[24:25], v[32:33], v[126:127] op_sel:[0,1] op_sel_hi:[1,0]
	v_xor_b32_e32 v121, 0x80000000, v116
	v_pk_add_f32 v[94:95], v[94:95], v[98:99] neg_lo:[0,1] neg_hi:[0,1]
	v_pk_add_f32 v[124:125], v[122:123], v[128:129]
	v_mov_b32_e32 v120, v117
	v_pk_fma_f32 v[24:25], v[26:27], v[126:127], v[24:25] op_sel_hi:[0,1,1]
	v_pk_mul_f32 v[26:27], v[38:39], v[118:119] op_sel:[0,1] op_sel_hi:[1,0]
	v_xor_b32_e32 v99, 0x80000000, v94
	v_pk_add_f32 v[116:117], v[100:101], v[120:121]
	v_mov_b32_e32 v98, v95
	v_pk_fma_f32 v[26:27], v[28:29], v[118:119], v[26:27] op_sel_hi:[0,1,1]
	v_pk_mul_f32 v[28:29], v[34:35], v[124:125] op_sel:[0,1] op_sel_hi:[1,0]
	v_pk_add_f32 v[94:95], v[92:93], v[98:99]
	v_pk_fma_f32 v[28:29], v[30:31], v[124:125], v[28:29] op_sel_hi:[0,1,1]
	v_pk_mul_f32 v[30:31], v[40:41], v[116:117] op_sel:[0,1] op_sel_hi:[1,0]
	v_pk_add_f32 v[122:123], v[122:123], v[128:129] neg_lo:[0,1] neg_hi:[0,1]
	v_pk_add_f32 v[102:103], v[130:131], v[102:103] neg_lo:[0,1] neg_hi:[0,1]
	v_pk_add_f32 v[100:101], v[100:101], v[120:121] neg_lo:[0,1] neg_hi:[0,1]
	v_pk_add_f32 v[96:97], v[96:97], v[108:109] neg_lo:[0,1] neg_hi:[0,1]
	v_pk_add_f32 v[92:93], v[92:93], v[98:99] neg_lo:[0,1] neg_hi:[0,1]
	v_pk_fma_f32 v[30:31], v[36:37], v[116:117], v[30:31] op_sel_hi:[0,1,1]
	v_pk_mul_f32 v[32:33], v[44:45], v[104:105] op_sel:[0,1] op_sel_hi:[1,0]
	v_pk_mul_f32 v[34:35], v[48:49], v[94:95] op_sel:[0,1] op_sel_hi:[1,0]
	v_pk_mul_f32 v[36:37], v[52:53], v[110:111] op_sel:[0,1] op_sel_hi:[1,0]
	v_pk_fma_f32 v[32:33], v[42:43], v[104:105], v[32:33] op_sel_hi:[0,1,1]
	v_pk_fma_f32 v[34:35], v[46:47], v[94:95], v[34:35] op_sel_hi:[0,1,1]
	v_pk_fma_f32 v[36:37], v[50:51], v[110:111], v[36:37] op_sel_hi:[0,1,1]
	v_pk_mul_f32 v[38:39], v[56:57], v[102:103] op_sel:[0,1] op_sel_hi:[1,0]
	v_pk_mul_f32 v[40:41], v[60:61], v[106:107] op_sel:[0,1] op_sel_hi:[1,0]
	v_pk_mul_f32 v[42:43], v[68:69], v[96:97] op_sel:[0,1] op_sel_hi:[1,0]
	v_pk_mul_f32 v[44:45], v[72:73], v[122:123] op_sel:[0,1] op_sel_hi:[1,0]
	v_pk_mul_f32 v[46:47], v[76:77], v[100:101] op_sel:[0,1] op_sel_hi:[1,0]
	v_pk_mul_f32 v[48:49], v[80:81], v[112:113] op_sel:[0,1] op_sel_hi:[1,0]
	v_pk_mul_f32 v[50:51], v[84:85], v[92:93] op_sel:[0,1] op_sel_hi:[1,0]
	v_pk_fma_f32 v[38:39], v[54:55], v[102:103], v[38:39] op_sel_hi:[0,1,1]
	v_pk_fma_f32 v[40:41], v[58:59], v[106:107], v[40:41] op_sel_hi:[0,1,1]
	v_pk_fma_f32 v[42:43], v[66:67], v[96:97], v[42:43] op_sel_hi:[0,1,1]
	v_pk_fma_f32 v[44:45], v[70:71], v[122:123], v[44:45] op_sel_hi:[0,1,1]
	v_pk_fma_f32 v[46:47], v[74:75], v[100:101], v[46:47] op_sel_hi:[0,1,1]
	v_pk_fma_f32 v[48:49], v[78:79], v[112:113], v[48:49] op_sel_hi:[0,1,1]
	v_pk_fma_f32 v[50:51], v[82:83], v[92:93], v[50:51] op_sel_hi:[0,1,1]
	ds_write2_b64 v6, v[132:133], v[36:37] offset1:16
	ds_write2_b64 v6, v[28:29], v[44:45] offset0:33 offset1:49
	ds_write2_b64 v6, v[24:25], v[40:41] offset0:66 offset1:82
	ds_write2_b64 v6, v[32:33], v[48:49] offset0:99 offset1:115
	ds_write2_b64 v6, v[22:23], v[38:39] offset0:132 offset1:148
	ds_write2_b64 v6, v[30:31], v[46:47] offset0:165 offset1:181
	ds_write2_b64 v6, v[26:27], v[42:43] offset0:198 offset1:214
	ds_write2_b64 v6, v[34:35], v[50:51] offset0:231 offset1:247
	v_mov_b32_e32 v6, v62
	s_waitcnt lgkmcnt(0)
	s_barrier
	s_lshl_b32 s24, s71, 6
	v_bfe_i32 v11, v6, 1, 27
	v_lshl_add_u32 v68, v6, 7, 0
	v_lshl_add_u32 v11, v11, 3, v68
	ds_read2_b64 v[22:25], v11 offset1:1
	ds_read2_b64 v[26:29], v11 offset0:2 offset1:3
	ds_read2_b64 v[30:33], v11 offset0:8 offset1:9
	ds_read2_b64 v[34:37], v11 offset0:4 offset1:5
	ds_read2_b64 v[38:41], v11 offset0:6 offset1:7
	ds_read2_b64 v[42:45], v11 offset0:10 offset1:11
	ds_read2_b64 v[46:49], v11 offset0:12 offset1:13
	ds_read2_b64 v[50:53], v11 offset0:14 offset1:15
	s_waitcnt lgkmcnt(5)
	v_pk_add_f32 v[54:55], v[22:23], v[30:31]
	v_pk_add_f32 v[22:23], v[22:23], v[30:31] neg_lo:[0,1] neg_hi:[0,1]
	v_pk_add_f32 v[30:31], v[24:25], v[32:33]
	v_pk_add_f32 v[24:25], v[24:25], v[32:33] neg_lo:[0,1] neg_hi:[0,1]
	s_waitcnt lgkmcnt(1)
	v_pk_add_f32 v[56:57], v[36:37], v[48:49]
	v_pk_mul_f32 v[32:33], v[24:25], s[38:39]
	v_pk_add_f32 v[36:37], v[36:37], v[48:49] neg_lo:[0,1] neg_hi:[0,1]
	v_pk_fma_f32 v[24:25], v[24:25], s[36:37], v[32:33] op_sel:[0,0,1] op_sel_hi:[1,0,0]
	v_pk_add_f32 v[32:33], v[26:27], v[42:43]
	v_pk_add_f32 v[26:27], v[26:27], v[42:43] neg_lo:[0,1] neg_hi:[0,1]
	v_pk_mul_f32 v[48:49], v[36:37], s[44:45]
	v_pk_mul_f32 v[42:43], v[26:27], s[42:43]
	v_pk_fma_f32 v[36:37], v[36:37], s[62:63], v[48:49] op_sel:[0,0,1] op_sel_hi:[1,0,0] neg_lo:[1,0,0] neg_hi:[1,0,0]
	v_pk_fma_f32 v[26:27], v[26:27], s[40:41], v[42:43] op_sel:[0,0,1] op_sel_hi:[1,0,0]
	v_pk_add_f32 v[42:43], v[28:29], v[44:45]
	v_pk_add_f32 v[28:29], v[28:29], v[44:45] neg_lo:[0,1] neg_hi:[0,1]
	s_waitcnt lgkmcnt(0)
	v_pk_add_f32 v[48:49], v[38:39], v[50:51]
	v_pk_add_f32 v[38:39], v[38:39], v[50:51] neg_lo:[0,1] neg_hi:[0,1]
	v_pk_mul_f32 v[44:45], v[28:29], s[44:45]
	v_pk_mul_f32 v[50:51], v[38:39], s[42:43]
	v_pk_fma_f32 v[28:29], v[28:29], s[62:63], v[44:45] op_sel:[0,0,1] op_sel_hi:[1,0,0]
	v_pk_add_f32 v[44:45], v[34:35], v[46:47]
	v_pk_add_f32 v[46:47], v[34:35], v[46:47] neg_lo:[0,1] neg_hi:[0,1]
	v_pk_fma_f32 v[38:39], v[38:39], s[40:41], v[50:51] op_sel:[0,0,1] op_sel_hi:[1,0,0] neg_lo:[1,0,0] neg_hi:[1,0,0]
	v_pk_add_f32 v[50:51], v[40:41], v[52:53]
	v_pk_add_f32 v[40:41], v[40:41], v[52:53] neg_lo:[0,1] neg_hi:[0,1]
	s_nop 0
	v_pk_mul_f32 v[52:53], v[40:41], s[38:39]
	v_pk_add_f32 v[58:59], v[42:43], v[50:51]
	v_pk_add_f32 v[42:43], v[42:43], v[50:51] neg_lo:[0,1] neg_hi:[0,1]
	v_pk_fma_f32 v[40:41], v[40:41], s[36:37], v[52:53] op_sel:[0,0,1] op_sel_hi:[1,0,0] neg_lo:[1,0,0] neg_hi:[1,0,0]
	v_pk_add_f32 v[52:53], v[54:55], v[44:45]
	v_pk_add_f32 v[44:45], v[54:55], v[44:45] neg_lo:[0,1] neg_hi:[0,1]
	v_pk_add_f32 v[54:55], v[30:31], v[56:57]
	v_pk_add_f32 v[30:31], v[30:31], v[56:57] neg_lo:[0,1] neg_hi:[0,1]
	v_pk_mul_f32 v[50:51], v[42:43], s[42:43]
	v_pk_add_f32 v[34:35], v[22:23], v[46:47] op_sel:[0,1] op_sel_hi:[1,0] neg_hi:[0,1]
	v_pk_add_f32 v[22:23], v[22:23], v[46:47] op_sel:[0,1] op_sel_hi:[1,0] neg_lo:[0,1]
	v_pk_add_f32 v[46:47], v[24:25], v[36:37]
	v_pk_add_f32 v[24:25], v[24:25], v[36:37] neg_lo:[0,1] neg_hi:[0,1]
	v_pk_mul_f32 v[56:57], v[30:31], s[42:43]
	v_pk_fma_f32 v[42:43], v[42:43], s[40:41], v[50:51] op_sel:[0,0,1] op_sel_hi:[1,0,0] neg_lo:[1,0,0] neg_hi:[1,0,0]
	v_pk_mul_f32 v[36:37], v[24:25], s[42:43]
	v_pk_add_f32 v[50:51], v[28:29], v[40:41]
	v_pk_add_f32 v[28:29], v[28:29], v[40:41] neg_lo:[0,1] neg_hi:[0,1]
	v_pk_fma_f32 v[30:31], v[30:31], s[40:41], v[56:57] op_sel:[0,0,1] op_sel_hi:[1,0,0]
	v_pk_add_f32 v[56:57], v[32:33], v[48:49]
	v_pk_add_f32 v[48:49], v[32:33], v[48:49] neg_lo:[0,1] neg_hi:[0,1]
	v_pk_fma_f32 v[24:25], v[24:25], s[40:41], v[36:37] op_sel:[0,0,1] op_sel_hi:[1,0,0]
	v_pk_add_f32 v[36:37], v[26:27], v[38:39]
	v_pk_add_f32 v[38:39], v[26:27], v[38:39] neg_lo:[0,1] neg_hi:[0,1]
	v_pk_mul_f32 v[40:41], v[28:29], s[42:43]
	s_nop 0
	v_pk_fma_f32 v[28:29], v[28:29], s[40:41], v[40:41] op_sel:[0,0,1] op_sel_hi:[1,0,0] neg_lo:[1,0,0] neg_hi:[1,0,0]
	v_lshl_add_u32 v6, v6, 4, v90
	v_pk_add_f32 v[40:41], v[52:53], v[56:57]
	v_pk_add_f32 v[52:53], v[52:53], v[56:57] neg_lo:[0,1] neg_hi:[0,1]
	v_pk_add_f32 v[56:57], v[54:55], v[58:59]
	v_pk_add_f32 v[58:59], v[54:55], v[58:59] neg_lo:[0,1] neg_hi:[0,1]
	v_pk_add_f32 v[32:33], v[44:45], v[48:49] op_sel:[0,1] op_sel_hi:[1,0] neg_hi:[0,1]
	v_pk_add_f32 v[44:45], v[44:45], v[48:49] op_sel:[0,1] op_sel_hi:[1,0] neg_lo:[0,1]
	v_pk_add_f32 v[48:49], v[30:31], v[42:43]
	v_pk_add_f32 v[42:43], v[30:31], v[42:43] neg_lo:[0,1] neg_hi:[0,1]
	v_pk_add_f32 v[60:61], v[34:35], v[36:37]
	v_pk_add_f32 v[34:35], v[34:35], v[36:37] neg_lo:[0,1] neg_hi:[0,1]
	v_pk_add_f32 v[36:37], v[46:47], v[50:51]
	v_pk_add_f32 v[50:51], v[46:47], v[50:51] neg_lo:[0,1] neg_hi:[0,1]
	v_pk_add_f32 v[26:27], v[22:23], v[38:39] op_sel:[0,1] op_sel_hi:[1,0] neg_hi:[0,1]
	v_pk_add_f32 v[22:23], v[22:23], v[38:39] op_sel:[0,1] op_sel_hi:[1,0] neg_lo:[0,1]
	v_pk_add_f32 v[38:39], v[24:25], v[28:29]
	v_pk_add_f32 v[28:29], v[24:25], v[28:29] neg_lo:[0,1] neg_hi:[0,1]
	v_ashrrev_i32_e32 v6, 5, v6
	v_pk_add_f32 v[66:67], v[40:41], v[56:57]
	v_pk_add_f32 v[40:41], v[40:41], v[56:57] neg_lo:[0,1] neg_hi:[0,1]
	v_lshlrev_b32_e32 v6, 3, v6
	v_pk_add_f32 v[54:55], v[52:53], v[58:59] op_sel:[0,1] op_sel_hi:[1,0] neg_hi:[0,1]
	v_pk_add_f32 v[52:53], v[52:53], v[58:59] op_sel:[0,1] op_sel_hi:[1,0] neg_lo:[0,1]
	v_pk_add_f32 v[56:57], v[32:33], v[48:49]
	v_pk_add_f32 v[32:33], v[32:33], v[48:49] neg_lo:[0,1] neg_hi:[0,1]
	v_pk_add_f32 v[30:31], v[44:45], v[42:43] op_sel:[0,1] op_sel_hi:[1,0] neg_hi:[0,1]
	v_pk_add_f32 v[42:43], v[44:45], v[42:43] op_sel:[0,1] op_sel_hi:[1,0] neg_lo:[0,1]
	v_pk_add_f32 v[44:45], v[60:61], v[36:37]
	v_pk_add_f32 v[36:37], v[60:61], v[36:37] neg_lo:[0,1] neg_hi:[0,1]
	v_pk_add_f32 v[46:47], v[34:35], v[50:51] op_sel:[0,1] op_sel_hi:[1,0] neg_hi:[0,1]
	v_pk_add_f32 v[34:35], v[34:35], v[50:51] op_sel:[0,1] op_sel_hi:[1,0] neg_lo:[0,1]
	v_pk_add_f32 v[48:49], v[26:27], v[38:39]
	v_pk_add_f32 v[26:27], v[26:27], v[38:39] neg_lo:[0,1] neg_hi:[0,1]
	v_pk_add_f32 v[24:25], v[22:23], v[28:29] op_sel:[0,1] op_sel_hi:[1,0] neg_hi:[0,1]
	v_pk_add_f32 v[22:23], v[22:23], v[28:29] op_sel:[0,1] op_sel_hi:[1,0] neg_lo:[0,1]
	ds_write2_b64 v11, v[66:67], v[40:41] offset1:1
	ds_write2_b64 v11, v[54:55], v[52:53] offset0:2 offset1:3
	ds_write2_b64 v11, v[56:57], v[32:33] offset0:4 offset1:5
	ds_write2_b64 v11, v[30:31], v[42:43] offset0:6 offset1:7
	ds_write2_b64 v11, v[44:45], v[36:37] offset0:8 offset1:9
	ds_write2_b64 v11, v[46:47], v[34:35] offset0:10 offset1:11
	ds_write2_b64 v11, v[48:49], v[26:27] offset0:12 offset1:13
	ds_write2_b64 v11, v[24:25], v[22:23] offset0:14 offset1:15
	v_add3_u32 v6, v68, v6, s35
	ds_read2_b64 v[22:25], v6 offset1:1
	ds_read2_b64 v[26:29], v6 offset0:2 offset1:3
	ds_read2_b64 v[30:33], v6 offset0:8 offset1:9
	ds_read2_b64 v[34:37], v6 offset0:4 offset1:5
	ds_read2_b64 v[38:41], v6 offset0:6 offset1:7
	ds_read2_b64 v[42:45], v6 offset0:10 offset1:11
	ds_read2_b64 v[46:49], v6 offset0:12 offset1:13
	ds_read2_b64 v[50:53], v6 offset0:14 offset1:15
	s_waitcnt lgkmcnt(5)
	v_pk_add_f32 v[54:55], v[22:23], v[30:31]
	v_pk_add_f32 v[22:23], v[22:23], v[30:31] neg_lo:[0,1] neg_hi:[0,1]
	v_pk_add_f32 v[30:31], v[24:25], v[32:33]
	v_pk_add_f32 v[24:25], v[24:25], v[32:33] neg_lo:[0,1] neg_hi:[0,1]
	s_waitcnt lgkmcnt(1)
	v_pk_add_f32 v[56:57], v[36:37], v[48:49]
	v_pk_mul_f32 v[32:33], v[24:25], s[38:39]
	v_pk_add_f32 v[36:37], v[36:37], v[48:49] neg_lo:[0,1] neg_hi:[0,1]
	v_pk_fma_f32 v[24:25], v[24:25], s[36:37], v[32:33] op_sel:[0,0,1] op_sel_hi:[1,0,0]
	v_pk_add_f32 v[32:33], v[26:27], v[42:43]
	v_pk_add_f32 v[26:27], v[26:27], v[42:43] neg_lo:[0,1] neg_hi:[0,1]
	v_pk_mul_f32 v[48:49], v[36:37], s[44:45]
	v_pk_mul_f32 v[42:43], v[26:27], s[42:43]
	v_pk_fma_f32 v[36:37], v[36:37], s[62:63], v[48:49] op_sel:[0,0,1] op_sel_hi:[1,0,0] neg_lo:[1,0,0] neg_hi:[1,0,0]
	v_pk_fma_f32 v[26:27], v[26:27], s[40:41], v[42:43] op_sel:[0,0,1] op_sel_hi:[1,0,0]
	v_pk_add_f32 v[42:43], v[28:29], v[44:45]
	v_pk_add_f32 v[28:29], v[28:29], v[44:45] neg_lo:[0,1] neg_hi:[0,1]
	s_waitcnt lgkmcnt(0)
	v_pk_add_f32 v[48:49], v[38:39], v[50:51]
	v_pk_add_f32 v[38:39], v[38:39], v[50:51] neg_lo:[0,1] neg_hi:[0,1]
	v_pk_mul_f32 v[44:45], v[28:29], s[44:45]
	v_pk_mul_f32 v[50:51], v[38:39], s[42:43]
	v_pk_fma_f32 v[28:29], v[28:29], s[62:63], v[44:45] op_sel:[0,0,1] op_sel_hi:[1,0,0]
	v_pk_add_f32 v[44:45], v[34:35], v[46:47]
	v_pk_add_f32 v[46:47], v[34:35], v[46:47] neg_lo:[0,1] neg_hi:[0,1]
	v_pk_fma_f32 v[38:39], v[38:39], s[40:41], v[50:51] op_sel:[0,0,1] op_sel_hi:[1,0,0] neg_lo:[1,0,0] neg_hi:[1,0,0]
	v_pk_add_f32 v[50:51], v[40:41], v[52:53]
	v_pk_add_f32 v[40:41], v[40:41], v[52:53] neg_lo:[0,1] neg_hi:[0,1]
	s_nop 0
	v_pk_mul_f32 v[52:53], v[40:41], s[38:39]
	v_pk_add_f32 v[58:59], v[42:43], v[50:51]
	v_pk_add_f32 v[42:43], v[42:43], v[50:51] neg_lo:[0,1] neg_hi:[0,1]
	v_pk_fma_f32 v[40:41], v[40:41], s[36:37], v[52:53] op_sel:[0,0,1] op_sel_hi:[1,0,0] neg_lo:[1,0,0] neg_hi:[1,0,0]
	v_pk_mul_f32 v[50:51], v[42:43], s[42:43]
	v_pk_add_f32 v[34:35], v[22:23], v[46:47] op_sel:[0,1] op_sel_hi:[1,0] neg_hi:[0,1]
	v_pk_add_f32 v[22:23], v[22:23], v[46:47] op_sel:[0,1] op_sel_hi:[1,0] neg_lo:[0,1]
	v_pk_add_f32 v[46:47], v[24:25], v[36:37]
	v_pk_add_f32 v[24:25], v[24:25], v[36:37] neg_lo:[0,1] neg_hi:[0,1]
	v_pk_add_f32 v[52:53], v[54:55], v[44:45]
	v_pk_add_f32 v[44:45], v[54:55], v[44:45] neg_lo:[0,1] neg_hi:[0,1]
	v_pk_add_f32 v[54:55], v[30:31], v[56:57]
	v_pk_add_f32 v[30:31], v[30:31], v[56:57] neg_lo:[0,1] neg_hi:[0,1]
	v_pk_fma_f32 v[42:43], v[42:43], s[40:41], v[50:51] op_sel:[0,0,1] op_sel_hi:[1,0,0] neg_lo:[1,0,0] neg_hi:[1,0,0]
	v_pk_mul_f32 v[36:37], v[24:25], s[42:43]
	v_pk_add_f32 v[50:51], v[28:29], v[40:41]
	v_pk_add_f32 v[28:29], v[28:29], v[40:41] neg_lo:[0,1] neg_hi:[0,1]
	s_and_b32 s24, s24, 0xc0
	v_pk_mul_f32 v[56:57], v[30:31], s[42:43]
	v_pk_fma_f32 v[24:25], v[24:25], s[40:41], v[36:37] op_sel:[0,0,1] op_sel_hi:[1,0,0]
	v_pk_add_f32 v[36:37], v[26:27], v[38:39]
	v_pk_add_f32 v[38:39], v[26:27], v[38:39] neg_lo:[0,1] neg_hi:[0,1]
	v_pk_mul_f32 v[40:41], v[28:29], s[42:43]
	s_lshl_b64 s[62:63], s[50:51], 19
	v_pk_fma_f32 v[30:31], v[30:31], s[40:41], v[56:57] op_sel:[0,0,1] op_sel_hi:[1,0,0]
	v_pk_add_f32 v[56:57], v[32:33], v[48:49]
	v_pk_add_f32 v[48:49], v[32:33], v[48:49] neg_lo:[0,1] neg_hi:[0,1]
	s_nop 0
	v_pk_fma_f32 v[28:29], v[28:29], s[40:41], v[40:41] op_sel:[0,0,1] op_sel_hi:[1,0,0] neg_lo:[1,0,0] neg_hi:[1,0,0]
	s_add_u32 s43, s3, s62
	s_nop 0
	s_nop 0
	v_pk_add_f32 v[26:27], v[22:23], v[38:39] op_sel:[0,1] op_sel_hi:[1,0] neg_hi:[0,1]
	v_pk_add_f32 v[22:23], v[22:23], v[38:39] op_sel:[0,1] op_sel_hi:[1,0] neg_lo:[0,1]
	v_pk_add_f32 v[38:39], v[24:25], v[28:29]
	v_pk_add_f32 v[24:25], v[24:25], v[28:29] neg_lo:[0,1] neg_hi:[0,1]
	s_addc_u32 s45, s29, s63
	s_lshl_b32 s64, s24, 2
	v_pk_add_f32 v[40:41], v[52:53], v[56:57]
	v_pk_add_f32 v[52:53], v[52:53], v[56:57] neg_lo:[0,1] neg_hi:[0,1]
	v_pk_add_f32 v[56:57], v[54:55], v[58:59]
	v_pk_add_f32 v[54:55], v[54:55], v[58:59] neg_lo:[0,1] neg_hi:[0,1]
	v_pk_add_f32 v[32:33], v[44:45], v[48:49] op_sel:[0,1] op_sel_hi:[1,0] neg_hi:[0,1]
	v_pk_add_f32 v[44:45], v[44:45], v[48:49] op_sel:[0,1] op_sel_hi:[1,0] neg_lo:[0,1]
	v_pk_add_f32 v[48:49], v[30:31], v[42:43]
	v_pk_add_f32 v[42:43], v[30:31], v[42:43] neg_lo:[0,1] neg_hi:[0,1]
	v_pk_add_f32 v[60:61], v[34:35], v[36:37]
	v_pk_add_f32 v[34:35], v[34:35], v[36:37] neg_lo:[0,1] neg_hi:[0,1]
	v_pk_add_f32 v[36:37], v[46:47], v[50:51]
	v_pk_add_f32 v[46:47], v[46:47], v[50:51] neg_lo:[0,1] neg_hi:[0,1]
	v_xor_b32_e32 v29, 0x80000000, v24
	v_mov_b32_e32 v28, v25
	s_add_u32 s64, s43, s64
	v_xor_b32_e32 v59, 0x80000000, v54
	s_nop 0
	v_xor_b32_e32 v51, 0x80000000, v46
	v_pk_add_f32 v[66:67], v[40:41], v[56:57]
	v_pk_add_f32 v[40:41], v[40:41], v[56:57] neg_lo:[0,1] neg_hi:[0,1]
	v_mov_b32_e32 v58, v55
	v_mov_b32_e32 v50, v47
	v_pk_add_f32 v[24:25], v[22:23], v[28:29]
	v_pk_add_f32 v[22:23], v[22:23], v[28:29] neg_lo:[0,1] neg_hi:[0,1]
	s_addc_u32 s65, s45, 0
	v_pk_add_f32 v[54:55], v[52:53], v[58:59]
	v_pk_add_f32 v[52:53], v[52:53], v[58:59] neg_lo:[0,1] neg_hi:[0,1]
	v_pk_add_f32 v[56:57], v[32:33], v[48:49]
	v_pk_add_f32 v[32:33], v[32:33], v[48:49] neg_lo:[0,1] neg_hi:[0,1]
	v_pk_add_f32 v[30:31], v[44:45], v[42:43] op_sel:[0,1] op_sel_hi:[1,0] neg_hi:[0,1]
	v_pk_add_f32 v[42:43], v[44:45], v[42:43] op_sel:[0,1] op_sel_hi:[1,0] neg_lo:[0,1]
	v_pk_add_f32 v[44:45], v[60:61], v[36:37]
	v_pk_add_f32 v[36:37], v[60:61], v[36:37] neg_lo:[0,1] neg_hi:[0,1]
	v_pk_add_f32 v[46:47], v[34:35], v[50:51]
	v_pk_add_f32 v[34:35], v[34:35], v[50:51] neg_lo:[0,1] neg_hi:[0,1]
	v_pk_add_f32 v[48:49], v[26:27], v[38:39]
	v_pk_add_f32 v[26:27], v[26:27], v[38:39] neg_lo:[0,1] neg_hi:[0,1]
	ds_write2_b64 v6, v[66:67], v[40:41] offset1:1
	ds_write2_b64 v6, v[54:55], v[52:53] offset0:2 offset1:3
	ds_write2_b64 v6, v[56:57], v[32:33] offset0:4 offset1:5
	ds_write2_b64 v6, v[30:31], v[42:43] offset0:6 offset1:7
	ds_write2_b64 v6, v[44:45], v[36:37] offset0:8 offset1:9
	ds_write2_b64 v6, v[46:47], v[34:35] offset0:10 offset1:11
	ds_write2_b64 v6, v[48:49], v[26:27] offset0:12 offset1:13
	ds_write2_b64 v6, v[24:25], v[22:23] offset0:14 offset1:15
	v_lshl_add_u64 v[22:23], s[64:65], 0, v[20:21]
	s_mov_b64 s[64:65], 0
	v_mov_b32_e32 v11, v9
	v_mov_b64_e32 v[24:25], v[62:63]
	s_waitcnt lgkmcnt(0)
	s_barrier

.LBB0_428:
	s_ashr_i32 s17, s16, 31
	s_lshl_b64 s[6:7], s[16:17], 2
	s_add_u32 s6, s48, s6
	s_addc_u32 s7, s49, s7
	global_load_dwordx2 v[40:41], v151, s[6:7]
	s_waitcnt vmcnt(0)
	v_cvt_f32_f16_e32 v36, v10
	v_cvt_f32_f16_sdwa v42, v10 dst_sel:DWORD dst_unused:UNUSED_PAD src0_sel:WORD_1
	v_cvt_f32_f16_e32 v43, v11
	v_cvt_f32_f16_e32 v45, v12
	v_cvt_f32_f16_sdwa v46, v12 dst_sel:DWORD dst_unused:UNUSED_PAD src0_sel:WORD_1
	v_cvt_f32_f16_e32 v47, v13
	v_cvt_f32_f16_sdwa v12, v13 dst_sel:DWORD dst_unused:UNUSED_PAD src0_sel:WORD_1
	v_cvt_f32_f16_e32 v13, v30
	v_cvt_f32_f16_sdwa v50, v26 dst_sel:DWORD dst_unused:UNUSED_PAD src0_sel:WORD_1
	v_cvt_f32_f16_e32 v51, v27
	v_cvt_f32_f16_sdwa v44, v11 dst_sel:DWORD dst_unused:UNUSED_PAD src0_sel:WORD_1
	v_cvt_f32_f16_sdwa v48, v30 dst_sel:DWORD dst_unused:UNUSED_PAD src0_sel:WORD_1
	v_cvt_f32_f16_e32 v49, v31
	v_cvt_f32_f16_sdwa v30, v31 dst_sel:DWORD dst_unused:UNUSED_PAD src0_sel:WORD_1
	v_cvt_f32_f16_e32 v31, v32
	v_cvt_f32_f16_sdwa v11, v33 dst_sel:DWORD dst_unused:UNUSED_PAD src0_sel:WORD_1
	v_cvt_f32_f16_sdwa v32, v32 dst_sel:DWORD dst_unused:UNUSED_PAD src0_sel:WORD_1
	v_cvt_f32_f16_e32 v33, v33
	v_cvt_f32_f16_sdwa v26, v27 dst_sel:DWORD dst_unused:UNUSED_PAD src0_sel:WORD_1
	v_cvt_f32_f16_e32 v27, v28
	v_cvt_f32_f16_sdwa v52, v28 dst_sel:DWORD dst_unused:UNUSED_PAD src0_sel:WORD_1
	v_cvt_f32_f16_e32 v53, v29
	v_cvt_f32_f16_e32 v28, v22
	v_cvt_f32_f16_sdwa v54, v22 dst_sel:DWORD dst_unused:UNUSED_PAD src0_sel:WORD_1
	v_cvt_f32_f16_e32 v55, v23
	v_cvt_f32_f16_sdwa v22, v23 dst_sel:DWORD dst_unused:UNUSED_PAD src0_sel:WORD_1
	v_cvt_f32_f16_e32 v23, v24
	v_cvt_f32_f16_sdwa v56, v24 dst_sel:DWORD dst_unused:UNUSED_PAD src0_sel:WORD_1
	v_cvt_f32_f16_e32 v57, v25
	v_cvt_f32_f16_sdwa v29, v29 dst_sel:DWORD dst_unused:UNUSED_PAD src0_sel:WORD_1
	v_cvt_f32_f16_sdwa v25, v25 dst_sel:DWORD dst_unused:UNUSED_PAD src0_sel:WORD_1
	v_cvt_f32_f16_e32 v24, v38
	v_cvt_f32_f16_sdwa v60, v19 dst_sel:DWORD dst_unused:UNUSED_PAD src0_sel:WORD_1
	v_cvt_f32_f16_e32 v61, v20
	v_cvt_f32_f16_e32 v38, v18
	v_cvt_f32_f16_e32 v59, v19
	v_mul_f32_e32 v19, 0x3b800000, v36
	v_pk_mul_f32 v[42:43], v[42:43], s[24:25] op_sel_hi:[1,0]
	v_pk_mul_f32 v[12:13], v[12:13], s[24:25] op_sel_hi:[1,0]
	v_pk_mul_f32 v[50:51], v[50:51], s[24:25] op_sel_hi:[1,0]
	v_pk_mul_f32 v[44:45], v[44:45], s[24:25] op_sel_hi:[1,0]
	v_pk_mul_f32 v[46:47], v[46:47], s[24:25] op_sel_hi:[1,0]
	v_pk_mul_f32 v[48:49], v[48:49], s[24:25] op_sel_hi:[1,0]
	v_pk_mul_f32 v[30:31], v[30:31], s[24:25] op_sel_hi:[1,0]
	v_mul_f32_e32 v11, 0x3b800000, v11
	v_pk_mul_f32 v[32:33], v[32:33], s[24:25] op_sel_hi:[1,0]
	v_pk_mul_f32 v[26:27], v[26:27], s[24:25] op_sel_hi:[1,0]
	v_pk_mul_f32 v[52:53], v[52:53], s[24:25] op_sel_hi:[1,0]
	v_pk_mul_f32 v[54:55], v[54:55], s[24:25] op_sel_hi:[1,0]
	v_pk_mul_f32 v[22:23], v[22:23], s[24:25] op_sel_hi:[1,0]
	v_pk_mul_f32 v[56:57], v[56:57], s[24:25] op_sel_hi:[1,0]
	ds_write2_b32 v131, v42, v43 offset0:1 offset1:2
	ds_write2_b32 v131, v44, v45 offset0:3 offset1:4
	ds_write2_b32 v131, v46, v47 offset0:5 offset1:6
	ds_write2_b32 v131, v12, v13 offset0:7 offset1:8
	ds_write2_b32 v131, v48, v49 offset0:9 offset1:10
	ds_write2_b32 v131, v30, v31 offset0:11 offset1:12
	ds_write2_b32 v131, v32, v33 offset0:13 offset1:14
	v_pk_mov_b32 v[12:13], v[50:51], v[50:51] op_sel:[1,0]
	v_pk_mul_f32 v[28:29], v[28:29], s[24:25] op_sel_hi:[1,0]
	v_pk_mul_f32 v[24:25], v[24:25], s[24:25] op_sel_hi:[1,0]
	v_pk_mov_b32 v[26:27], v[26:27], v[26:27] op_sel:[1,0]
	v_pk_mov_b32 v[30:31], v[52:53], v[52:53] op_sel:[1,0]
	v_pk_mov_b32 v[32:33], v[54:55], v[54:55] op_sel:[1,0]
	v_pk_mov_b32 v[22:23], v[22:23], v[22:23] op_sel:[1,0]
	v_pk_mov_b32 v[42:43], v[56:57], v[56:57] op_sel:[1,0]
	v_cvt_f32_f16_sdwa v58, v18 dst_sel:DWORD dst_unused:UNUSED_PAD src0_sel:WORD_1
	v_mul_f32_e32 v36, 0x3b800000, v38
	s_mov_b32 s6, s65
	v_pk_mul_f32 v[58:59], v[58:59], s[24:25] op_sel_hi:[1,0]
	v_fma_mix_f32 v10, v10, s24, v40 op_sel_hi:[1,0,0]
	s_nop 0
	v_cndmask_b32_e64 v10, v19, v10, s[4:5]
	ds_write2_b32 v131, v10, v11 offset1:15
	ds_write_b64 v132, v[12:13] offset:32824
	ds_write_b64 v133, v[26:27] offset:32824
	ds_write_b64 v134, v[30:31] offset:32824
	ds_write_b64 v135, v[28:29] offset:32824
	ds_write_b64 v136, v[32:33] offset:32824
	ds_write_b64 v137, v[22:23] offset:32824
	ds_write_b64 v138, v[42:43] offset:32824
	ds_write_b64 v139, v[24:25] offset:32824
	v_cvt_f32_f16_sdwa v10, v20 dst_sel:DWORD dst_unused:UNUSED_PAD src0_sel:WORD_1
	v_cvt_f32_f16_e32 v11, v21
	v_pk_mul_f32 v[12:13], v[60:61], s[24:25] op_sel_hi:[1,0]
	v_fma_mix_f32 v18, v18, s24, v41 op_sel_hi:[1,0,0]
	ds_write2_b32 v140, v12, v13 offset0:3 offset1:4
	v_cvt_f32_f16_sdwa v12, v21 dst_sel:DWORD dst_unused:UNUSED_PAD src0_sel:WORD_1
	v_cvt_f32_f16_e32 v13, v14
	v_cndmask_b32_e64 v36, v36, v18, s[4:5]
	v_cvt_f32_f16_sdwa v18, v14 dst_sel:DWORD dst_unused:UNUSED_PAD src0_sel:WORD_1
	v_cvt_f32_f16_e32 v19, v15
	v_pk_mul_f32 v[10:11], v[10:11], s[24:25] op_sel_hi:[1,0]
	ds_write2_b32 v140, v10, v11 offset0:5 offset1:6
	v_pk_mul_f32 v[10:11], v[12:13], s[24:25] op_sel_hi:[1,0]
	ds_write2_b32 v140, v10, v11 offset0:7 offset1:8
	v_pk_mul_f32 v[10:11], v[18:19], s[24:25] op_sel_hi:[1,0]
	ds_write2_b32 v140, v10, v11 offset0:9 offset1:10
	v_cvt_f32_f16_sdwa v10, v15 dst_sel:DWORD dst_unused:UNUSED_PAD src0_sel:WORD_1
	v_cvt_f32_f16_e32 v11, v16
	v_cvt_f32_f16_sdwa v12, v16 dst_sel:DWORD dst_unused:UNUSED_PAD src0_sel:WORD_1
	v_cvt_f32_f16_e32 v13, v17
	v_cvt_f32_f16_sdwa v14, v17 dst_sel:DWORD dst_unused:UNUSED_PAD src0_sel:WORD_1
	v_pk_mul_f32 v[10:11], v[10:11], s[24:25] op_sel_hi:[1,0]
	ds_write2_b32 v140, v10, v11 offset0:11 offset1:12
	v_pk_mul_f32 v[10:11], v[12:13], s[24:25] op_sel_hi:[1,0]
	ds_write2_b32 v140, v10, v11 offset0:13 offset1:14
	v_cvt_f32_f16_sdwa v10, v6 dst_sel:DWORD dst_unused:UNUSED_PAD src0_sel:WORD_1
	v_cvt_f32_f16_e32 v11, v7
	v_cvt_f32_f16_sdwa v6, v7 dst_sel:DWORD dst_unused:UNUSED_PAD src0_sel:WORD_1
	v_cvt_f32_f16_e32 v7, v8
	v_mul_f32_e32 v14, 0x3b800000, v14
	v_pk_mul_f32 v[10:11], v[10:11], s[24:25] op_sel_hi:[1,0]
	ds_write2_b32 v140, v58, v59 offset0:1 offset1:2
	v_pk_mov_b32 v[10:11], v[10:11], v[10:11] op_sel:[1,0]
	ds_write2_b32 v140, v36, v14 offset1:15
	ds_write_b64 v141, v[10:11] offset:32824
	v_cvt_f32_f16_sdwa v10, v8 dst_sel:DWORD dst_unused:UNUSED_PAD src0_sel:WORD_1
	v_cvt_f32_f16_e32 v11, v9
	v_pk_mul_f32 v[6:7], v[6:7], s[24:25] op_sel_hi:[1,0]
	s_nop 0
	v_pk_mov_b32 v[6:7], v[6:7], v[6:7] op_sel:[1,0]
	ds_write_b64 v142, v[6:7] offset:32824
	v_cvt_f32_f16_sdwa v7, v9 dst_sel:DWORD dst_unused:UNUSED_PAD src0_sel:WORD_1
	v_pk_mul_f32 v[8:9], v[10:11], s[24:25] op_sel_hi:[1,0]
	v_cvt_f32_f16_e32 v6, v2
	v_pk_mov_b32 v[8:9], v[8:9], v[8:9] op_sel:[1,0]
	ds_write_b64 v143, v[8:9] offset:32824
	v_cvt_f32_f16_sdwa v8, v2 dst_sel:DWORD dst_unused:UNUSED_PAD src0_sel:WORD_1
	v_cvt_f32_f16_e32 v9, v3
	v_cvt_f32_f16_sdwa v2, v3 dst_sel:DWORD dst_unused:UNUSED_PAD src0_sel:WORD_1
	v_cvt_f32_f16_e32 v3, v4
	v_pk_mul_f32 v[6:7], v[6:7], s[24:25] op_sel_hi:[1,0]
	ds_write_b64 v144, v[6:7] offset:32824
	v_pk_mul_f32 v[6:7], v[8:9], s[24:25] op_sel_hi:[1,0]
	v_pk_mul_f32 v[2:3], v[2:3], s[24:25] op_sel_hi:[1,0]
	v_pk_mov_b32 v[6:7], v[6:7], v[6:7] op_sel:[1,0]
	ds_write_b64 v145, v[6:7] offset:32824
	v_pk_mov_b32 v[2:3], v[2:3], v[2:3] op_sel:[1,0]
	v_cvt_f32_f16_sdwa v6, v4 dst_sel:DWORD dst_unused:UNUSED_PAD src0_sel:WORD_1
	v_cvt_f32_f16_e32 v7, v5
	ds_write_b64 v148, v[2:3] offset:32824
	v_cvt_f32_f16_sdwa v3, v5 dst_sel:DWORD dst_unused:UNUSED_PAD src0_sel:WORD_1
	v_cvt_f32_f16_e32 v2, v39
	v_pk_mul_f32 v[4:5], v[6:7], s[24:25] op_sel_hi:[1,0]
	v_pk_mul_f32 v[2:3], v[2:3], s[24:25] op_sel_hi:[1,0]
	v_pk_mov_b32 v[4:5], v[4:5], v[4:5] op_sel:[1,0]
	ds_write_b64 v149, v[4:5] offset:32824
	ds_write_b64 v150, v[2:3] offset:32824
	v_mov_b32_e32 v2, v130
	s_waitcnt lgkmcnt(0)
	s_barrier
	s_nop 0
	v_and_b32_e32 v3, 0xff, v2
	v_lshlrev_b32_e32 v4, 5, v2
	v_and_or_b32 v3, v4, s29, v3
	v_ashrrev_i32_e32 v4, 5, v3
	v_lshlrev_b32_e32 v3, 3, v3
	v_lshlrev_b32_e32 v6, 3, v4
	v_add3_u32 v36, 0, v3, v6
	ds_read_b64 v[154:155], v36
	ds_read_b64 v[156:157], v36 offset:2112
	ds_read_b64 v[158:159], v36 offset:4224
	ds_read_b64 v[160:161], v36 offset:6336
	ds_read_b64 v[162:163], v36 offset:8448
	ds_read_b64 v[164:165], v36 offset:10560
	ds_read_b64 v[166:167], v36 offset:12672
	ds_read_b64 v[168:169], v36 offset:14784
	ds_read_b64 v[170:171], v36 offset:16896
	ds_read_b64 v[172:173], v36 offset:19008
	ds_read_b64 v[174:175], v36 offset:21120
	ds_read_b64 v[176:177], v36 offset:23232
	ds_read_b64 v[178:179], v36 offset:25344
	ds_read_b64 v[180:181], v36 offset:27456
	ds_read_b64 v[182:183], v36 offset:29568
	ds_read_b64 v[184:185], v36 offset:31680
	ds_read_b64 v[186:187], v36 offset:33792
	ds_read_b64 v[188:189], v36 offset:35904
	ds_read_b64 v[190:191], v36 offset:38016
	ds_read_b64 v[192:193], v36 offset:40128
	ds_read_b64 v[194:195], v36 offset:42240
	ds_read_b64 v[196:197], v36 offset:44352
	ds_read_b64 v[198:199], v36 offset:46464
	ds_read_b64 v[204:205], v36 offset:48576
	ds_read_b64 v[206:207], v36 offset:50688
	ds_read_b64 v[208:209], v36 offset:52800
	ds_read_b64 v[210:211], v36 offset:54912
	ds_read_b64 v[212:213], v36 offset:57024
	ds_read_b64 v[214:215], v36 offset:59136
	ds_read_b64 v[216:217], v36 offset:61248
	ds_read_b64 v[218:219], v36 offset:63360
	ds_read_b64 v[220:221], v36 offset:65472
	s_waitcnt lgkmcnt(14)
	v_pk_add_f32 v[222:223], v[154:155], v[186:187]
	v_pk_add_f32 v[154:155], v[154:155], v[186:187] neg_lo:[0,1] neg_hi:[0,1]
	v_pk_add_f32 v[186:187], v[156:157], v[188:189]
	v_pk_add_f32 v[156:157], v[156:157], v[188:189] neg_lo:[0,1] neg_hi:[0,1]
	v_cvt_f32_ubyte0_e32 v2, v2
	v_pk_mul_f32 v[188:189], v[156:157], s[40:41]
	v_mul_f32_e32 v5, 0x39000000, v2
	v_pk_fma_f32 v[156:157], v[156:157], s[36:37], v[188:189] op_sel:[0,0,1] op_sel_hi:[1,0,0]
	s_waitcnt lgkmcnt(13)
	v_pk_add_f32 v[188:189], v[158:159], v[190:191]
	v_pk_add_f32 v[158:159], v[158:159], v[190:191] neg_lo:[0,1] neg_hi:[0,1]
	v_sin_f32_e32 v2, v5
	v_pk_mul_f32 v[190:191], v[158:159], s[44:45]
	v_cos_f32_e32 v4, v5
	v_pk_fma_f32 v[158:159], v[158:159], s[42:43], v[190:191] op_sel:[0,0,1] op_sel_hi:[1,0,0]
	s_waitcnt lgkmcnt(12)
	v_pk_add_f32 v[190:191], v[160:161], v[192:193]
	v_pk_add_f32 v[160:161], v[160:161], v[192:193] neg_lo:[0,1] neg_hi:[0,1]
	v_xor_b32_e32 v5, 0x80000000, v2
	v_pk_mul_f32 v[192:193], v[160:161], s[62:63]
	v_mov_b32_e32 v3, v5
	v_pk_fma_f32 v[160:161], v[160:161], s[50:51], v[192:193] op_sel:[0,0,1] op_sel_hi:[1,0,0]
	s_waitcnt lgkmcnt(11)
	v_pk_add_f32 v[192:193], v[162:163], v[194:195]
	v_pk_add_f32 v[162:163], v[162:163], v[194:195] neg_lo:[0,1] neg_hi:[0,1]
	v_pk_mul_f32 v[6:7], v[4:5], v[2:3] op_sel:[1,0] op_sel_hi:[0,1]
	v_pk_mul_f32 v[194:195], v[162:163], s[68:69]
	v_pk_fma_f32 v[6:7], v[4:5], v[4:5], v[6:7] op_sel_hi:[1,0,1]
	v_pk_fma_f32 v[162:163], v[162:163], s[64:65], v[194:195] op_sel:[0,0,1] op_sel_hi:[1,0,0]
	s_waitcnt lgkmcnt(10)
	v_pk_add_f32 v[194:195], v[164:165], v[196:197]
	v_pk_add_f32 v[164:165], v[164:165], v[196:197] neg_lo:[0,1] neg_hi:[0,1]
	v_xor_b32_e32 v12, 0x80000000, v7
	v_pk_mul_f32 v[196:197], v[164:165], s[70:71]
	v_mov_b32_e32 v13, v7
	v_pk_fma_f32 v[164:165], v[164:165], s[46:47], v[196:197] op_sel:[0,0,1] op_sel_hi:[1,0,0]
	s_waitcnt lgkmcnt(9)
	v_pk_add_f32 v[196:197], v[166:167], v[198:199]
	v_pk_add_f32 v[166:167], v[166:167], v[198:199] neg_lo:[0,1] neg_hi:[0,1]
	v_pk_mul_f32 v[10:11], v[6:7], v[12:13] op_sel:[1,0] op_sel_hi:[0,1]
	v_pk_mul_f32 v[198:199], v[166:167], s[76:77]
	v_pk_fma_f32 v[10:11], v[6:7], v[6:7], v[10:11] op_sel_hi:[1,0,1]
	v_pk_fma_f32 v[166:167], v[166:167], s[72:73], v[198:199] op_sel:[0,0,1] op_sel_hi:[1,0,0]
	s_waitcnt lgkmcnt(8)
	v_pk_add_f32 v[198:199], v[168:169], v[204:205]
	v_pk_add_f32 v[168:169], v[168:169], v[204:205] neg_lo:[0,1] neg_hi:[0,1]
	v_xor_b32_e32 v14, 0x80000000, v11
	v_pk_mul_f32 v[204:205], v[168:169], s[26:27]
	v_mov_b32_e32 v15, v11
	v_pk_fma_f32 v[168:169], v[168:169], s[38:39], v[204:205] op_sel:[0,0,1] op_sel_hi:[1,0,0]
	s_waitcnt lgkmcnt(7)
	v_pk_add_f32 v[204:205], v[170:171], v[206:207]
	v_pk_add_f32 v[206:207], v[170:171], v[206:207] neg_lo:[0,1] neg_hi:[0,1]
	v_pk_mul_f32 v[26:27], v[10:11], v[14:15] op_sel:[1,0] op_sel_hi:[0,1]
	s_waitcnt lgkmcnt(6)
	v_pk_add_f32 v[170:171], v[172:173], v[208:209]
	v_pk_add_f32 v[172:173], v[172:173], v[208:209] neg_lo:[0,1] neg_hi:[0,1]
	v_pk_fma_f32 v[26:27], v[10:11], v[10:11], v[26:27] op_sel_hi:[1,0,1]
	v_pk_mul_f32 v[208:209], v[172:173], s[26:27]
	v_pk_mul_f32 v[46:47], v[14:15], v[26:27] op_sel:[0,1] op_sel_hi:[1,0]
	v_pk_fma_f32 v[172:173], v[172:173], s[38:39], v[208:209] op_sel:[0,0,1] op_sel_hi:[1,0,0] neg_lo:[1,0,0] neg_hi:[1,0,0]
	s_waitcnt lgkmcnt(5)
	v_pk_add_f32 v[208:209], v[174:175], v[210:211]
	v_pk_add_f32 v[174:175], v[174:175], v[210:211] neg_lo:[0,1] neg_hi:[0,1]
	v_pk_fma_f32 v[46:47], v[10:11], v[26:27], v[46:47] op_sel_hi:[0,1,1]
	v_pk_mul_f32 v[210:211], v[174:175], s[76:77]
	v_pk_mul_f32 v[62:63], v[14:15], v[46:47] op_sel:[0,1] op_sel_hi:[1,0]
	v_pk_fma_f32 v[174:175], v[174:175], s[72:73], v[210:211] op_sel:[0,0,1] op_sel_hi:[1,0,0] neg_lo:[1,0,0] neg_hi:[1,0,0]
	s_waitcnt lgkmcnt(4)
	v_pk_add_f32 v[210:211], v[176:177], v[212:213]
	v_pk_add_f32 v[176:177], v[176:177], v[212:213] neg_lo:[0,1] neg_hi:[0,1]
	v_pk_fma_f32 v[62:63], v[10:11], v[46:47], v[62:63] op_sel_hi:[0,1,1]
	v_pk_mul_f32 v[212:213], v[176:177], s[70:71]
	v_pk_mul_f32 v[78:79], v[14:15], v[62:63] op_sel:[0,1] op_sel_hi:[1,0]
	v_pk_fma_f32 v[176:177], v[176:177], s[46:47], v[212:213] op_sel:[0,0,1] op_sel_hi:[1,0,0] neg_lo:[1,0,0] neg_hi:[1,0,0]
	s_waitcnt lgkmcnt(3)
	v_pk_add_f32 v[212:213], v[178:179], v[214:215]
	v_pk_add_f32 v[178:179], v[178:179], v[214:215] neg_lo:[0,1] neg_hi:[0,1]
	v_pk_fma_f32 v[78:79], v[10:11], v[62:63], v[78:79] op_sel_hi:[0,1,1]
	v_pk_mul_f32 v[214:215], v[178:179], s[68:69]
	v_pk_mul_f32 v[94:95], v[14:15], v[78:79] op_sel:[0,1] op_sel_hi:[1,0]
	v_pk_fma_f32 v[178:179], v[178:179], s[64:65], v[214:215] op_sel:[0,0,1] op_sel_hi:[1,0,0] neg_lo:[1,0,0] neg_hi:[1,0,0]
	s_waitcnt lgkmcnt(2)
	v_pk_add_f32 v[214:215], v[180:181], v[216:217]
	v_pk_add_f32 v[180:181], v[180:181], v[216:217] neg_lo:[0,1] neg_hi:[0,1]
	v_pk_fma_f32 v[94:95], v[10:11], v[78:79], v[94:95] op_sel_hi:[0,1,1]
	v_pk_mul_f32 v[216:217], v[180:181], s[62:63]
	v_pk_mul_f32 v[110:111], v[14:15], v[94:95] op_sel:[0,1] op_sel_hi:[1,0]
	v_pk_fma_f32 v[180:181], v[180:181], s[50:51], v[216:217] op_sel:[0,0,1] op_sel_hi:[1,0,0] neg_lo:[1,0,0] neg_hi:[1,0,0]
	s_waitcnt lgkmcnt(1)
	v_pk_add_f32 v[216:217], v[182:183], v[218:219]
	v_pk_add_f32 v[182:183], v[182:183], v[218:219] neg_lo:[0,1] neg_hi:[0,1]
	v_pk_mul_f32 v[8:9], v[2:3], v[6:7] op_sel:[0,1] op_sel_hi:[1,0]
	v_pk_mul_f32 v[218:219], v[182:183], s[44:45]
	v_pk_fma_f32 v[110:111], v[10:11], v[94:95], v[110:111] op_sel_hi:[0,1,1]
	v_pk_fma_f32 v[182:183], v[182:183], s[42:43], v[218:219] op_sel:[0,0,1] op_sel_hi:[1,0,0] neg_lo:[1,0,0] neg_hi:[1,0,0]
	s_waitcnt lgkmcnt(0)
	v_pk_add_f32 v[218:219], v[184:185], v[220:221]
	v_pk_add_f32 v[184:185], v[184:185], v[220:221] neg_lo:[0,1] neg_hi:[0,1]
	v_pk_fma_f32 v[8:9], v[4:5], v[6:7], v[8:9] op_sel_hi:[0,1,1]
	v_pk_mul_f32 v[220:221], v[184:185], s[40:41]
	v_pk_mul_f32 v[16:17], v[2:3], v[10:11] op_sel:[0,1] op_sel_hi:[1,0]
	v_pk_fma_f32 v[184:185], v[184:185], s[36:37], v[220:221] op_sel:[0,0,1] op_sel_hi:[1,0,0] neg_lo:[1,0,0] neg_hi:[1,0,0]
	v_pk_add_f32 v[220:221], v[222:223], v[204:205]
	v_pk_add_f32 v[204:205], v[222:223], v[204:205] neg_lo:[0,1] neg_hi:[0,1]
	v_pk_add_f32 v[222:223], v[186:187], v[170:171]
	v_pk_add_f32 v[170:171], v[186:187], v[170:171] neg_lo:[0,1] neg_hi:[0,1]
	v_pk_mul_f32 v[30:31], v[2:3], v[26:27] op_sel:[0,1] op_sel_hi:[1,0]
	v_pk_mul_f32 v[186:187], v[170:171], s[44:45]
	v_pk_mul_f32 v[50:51], v[2:3], v[46:47] op_sel:[0,1] op_sel_hi:[1,0]
	v_pk_fma_f32 v[170:171], v[170:171], s[42:43], v[186:187] op_sel:[0,0,1] op_sel_hi:[1,0,0]
	v_pk_add_f32 v[186:187], v[188:189], v[208:209]
	v_pk_add_f32 v[188:189], v[188:189], v[208:209] neg_lo:[0,1] neg_hi:[0,1]
	v_pk_mul_f32 v[66:67], v[2:3], v[62:63] op_sel:[0,1] op_sel_hi:[1,0]
	v_pk_mul_f32 v[208:209], v[188:189], s[68:69]
	v_pk_mul_f32 v[82:83], v[2:3], v[78:79] op_sel:[0,1] op_sel_hi:[1,0]
	v_pk_fma_f32 v[188:189], v[188:189], s[64:65], v[208:209] op_sel:[0,0,1] op_sel_hi:[1,0,0]
	v_pk_add_f32 v[208:209], v[190:191], v[210:211]
	v_pk_add_f32 v[190:191], v[190:191], v[210:211] neg_lo:[0,1] neg_hi:[0,1]
	v_pk_mul_f32 v[98:99], v[2:3], v[94:95] op_sel:[0,1] op_sel_hi:[1,0]
	v_pk_mul_f32 v[210:211], v[190:191], s[76:77]
	v_pk_mul_f32 v[114:115], v[2:3], v[110:111] op_sel:[0,1] op_sel_hi:[1,0]
	v_pk_fma_f32 v[190:191], v[190:191], s[72:73], v[210:211] op_sel:[0,0,1] op_sel_hi:[1,0,0]
	v_pk_add_f32 v[210:211], v[192:193], v[212:213]
	v_pk_add_f32 v[212:213], v[192:193], v[212:213] neg_lo:[0,1] neg_hi:[0,1]
	v_xor_b32_e32 v20, 0x80000000, v9
	v_pk_add_f32 v[192:193], v[194:195], v[214:215]
	v_pk_add_f32 v[194:195], v[194:195], v[214:215] neg_lo:[0,1] neg_hi:[0,1]
	v_mov_b32_e32 v21, v9
	v_pk_mul_f32 v[214:215], v[194:195], s[76:77]
	v_pk_fma_f32 v[16:17], v[4:5], v[10:11], v[16:17] op_sel_hi:[0,1,1]
	v_pk_fma_f32 v[194:195], v[194:195], s[72:73], v[214:215] op_sel:[0,0,1] op_sel_hi:[1,0,0] neg_lo:[1,0,0] neg_hi:[1,0,0]
	v_pk_add_f32 v[214:215], v[196:197], v[216:217]
	v_pk_add_f32 v[196:197], v[196:197], v[216:217] neg_lo:[0,1] neg_hi:[0,1]
	v_pk_mul_f32 v[18:19], v[12:13], v[10:11] op_sel:[0,1] op_sel_hi:[1,0]
	v_pk_mul_f32 v[216:217], v[196:197], s[68:69]
	v_pk_fma_f32 v[30:31], v[4:5], v[26:27], v[30:31] op_sel_hi:[0,1,1]
	v_pk_fma_f32 v[196:197], v[196:197], s[64:65], v[216:217] op_sel:[0,0,1] op_sel_hi:[1,0,0] neg_lo:[1,0,0] neg_hi:[1,0,0]
	v_pk_add_f32 v[216:217], v[198:199], v[218:219]
	v_pk_add_f32 v[198:199], v[198:199], v[218:219] neg_lo:[0,1] neg_hi:[0,1]
	v_pk_mul_f32 v[38:39], v[12:13], v[26:27] op_sel:[0,1] op_sel_hi:[1,0]
	v_pk_mul_f32 v[218:219], v[198:199], s[44:45]
	v_pk_fma_f32 v[50:51], v[4:5], v[46:47], v[50:51] op_sel_hi:[0,1,1]
	v_pk_fma_f32 v[198:199], v[198:199], s[42:43], v[218:219] op_sel:[0,0,1] op_sel_hi:[1,0,0] neg_lo:[1,0,0] neg_hi:[1,0,0]
	v_pk_add_f32 v[218:219], v[154:155], v[206:207] op_sel:[0,1] op_sel_hi:[1,0] neg_hi:[0,1]
	v_pk_add_f32 v[154:155], v[154:155], v[206:207] op_sel:[0,1] op_sel_hi:[1,0] neg_lo:[0,1]
	v_pk_add_f32 v[206:207], v[156:157], v[172:173]
	v_pk_add_f32 v[156:157], v[156:157], v[172:173] neg_lo:[0,1] neg_hi:[0,1]
	v_pk_mul_f32 v[54:55], v[12:13], v[46:47] op_sel:[0,1] op_sel_hi:[1,0]
	v_pk_mul_f32 v[172:173], v[156:157], s[44:45]
	v_pk_fma_f32 v[66:67], v[4:5], v[62:63], v[66:67] op_sel_hi:[0,1,1]
	v_pk_fma_f32 v[156:157], v[156:157], s[42:43], v[172:173] op_sel:[0,0,1] op_sel_hi:[1,0,0]
	v_pk_add_f32 v[172:173], v[158:159], v[174:175]
	v_pk_add_f32 v[158:159], v[158:159], v[174:175] neg_lo:[0,1] neg_hi:[0,1]
	v_pk_mul_f32 v[70:71], v[12:13], v[62:63] op_sel:[0,1] op_sel_hi:[1,0]
	v_pk_mul_f32 v[174:175], v[158:159], s[68:69]
	v_pk_fma_f32 v[82:83], v[4:5], v[78:79], v[82:83] op_sel_hi:[0,1,1]
	v_pk_fma_f32 v[158:159], v[158:159], s[64:65], v[174:175] op_sel:[0,0,1] op_sel_hi:[1,0,0]
	v_pk_add_f32 v[174:175], v[160:161], v[176:177]
	v_pk_add_f32 v[160:161], v[160:161], v[176:177] neg_lo:[0,1] neg_hi:[0,1]
	v_pk_mul_f32 v[86:87], v[12:13], v[78:79] op_sel:[0,1] op_sel_hi:[1,0]
	v_pk_mul_f32 v[176:177], v[160:161], s[76:77]
	v_pk_fma_f32 v[98:99], v[4:5], v[94:95], v[98:99] op_sel_hi:[0,1,1]
	v_pk_fma_f32 v[160:161], v[160:161], s[72:73], v[176:177] op_sel:[0,0,1] op_sel_hi:[1,0,0]
	v_pk_add_f32 v[176:177], v[162:163], v[178:179]
	v_pk_add_f32 v[178:179], v[162:163], v[178:179] neg_lo:[0,1] neg_hi:[0,1]
	v_pk_mul_f32 v[102:103], v[12:13], v[94:95] op_sel:[0,1] op_sel_hi:[1,0]
	v_pk_add_f32 v[162:163], v[164:165], v[180:181]
	v_pk_add_f32 v[164:165], v[164:165], v[180:181] neg_lo:[0,1] neg_hi:[0,1]
	v_pk_fma_f32 v[114:115], v[4:5], v[110:111], v[114:115] op_sel_hi:[0,1,1]
	v_pk_mul_f32 v[180:181], v[164:165], s[76:77]
	v_pk_mul_f32 v[118:119], v[12:13], v[110:111] op_sel:[0,1] op_sel_hi:[1,0]
	v_pk_fma_f32 v[164:165], v[164:165], s[72:73], v[180:181] op_sel:[0,0,1] op_sel_hi:[1,0,0] neg_lo:[1,0,0] neg_hi:[1,0,0]
	v_pk_add_f32 v[180:181], v[166:167], v[182:183]
	v_pk_add_f32 v[166:167], v[166:167], v[182:183] neg_lo:[0,1] neg_hi:[0,1]
	v_pk_fma_f32 v[18:19], v[6:7], v[10:11], v[18:19] op_sel_hi:[0,1,1]
	v_pk_mul_f32 v[182:183], v[166:167], s[68:69]
	v_pk_mul_f32 v[22:23], v[10:11], v[20:21] op_sel:[1,0] op_sel_hi:[0,1]
	v_pk_fma_f32 v[166:167], v[166:167], s[64:65], v[182:183] op_sel:[0,0,1] op_sel_hi:[1,0,0] neg_lo:[1,0,0] neg_hi:[1,0,0]
	v_pk_add_f32 v[182:183], v[168:169], v[184:185]
	v_pk_add_f32 v[168:169], v[168:169], v[184:185] neg_lo:[0,1] neg_hi:[0,1]
	v_pk_fma_f32 v[38:39], v[6:7], v[26:27], v[38:39] op_sel_hi:[0,1,1]
	v_pk_mul_f32 v[184:185], v[168:169], s[44:45]
	v_pk_mul_f32 v[42:43], v[20:21], v[26:27] op_sel:[0,1] op_sel_hi:[1,0]
	v_pk_fma_f32 v[168:169], v[168:169], s[42:43], v[184:185] op_sel:[0,0,1] op_sel_hi:[1,0,0] neg_lo:[1,0,0] neg_hi:[1,0,0]
	v_pk_add_f32 v[184:185], v[220:221], v[210:211]
	v_pk_add_f32 v[210:211], v[220:221], v[210:211] neg_lo:[0,1] neg_hi:[0,1]
	v_pk_add_f32 v[220:221], v[222:223], v[192:193]
	v_pk_add_f32 v[192:193], v[222:223], v[192:193] neg_lo:[0,1] neg_hi:[0,1]
	v_pk_fma_f32 v[54:55], v[6:7], v[46:47], v[54:55] op_sel_hi:[0,1,1]
	v_pk_mul_f32 v[222:223], v[192:193], s[68:69]
	v_pk_mul_f32 v[58:59], v[20:21], v[46:47] op_sel:[0,1] op_sel_hi:[1,0]
	v_pk_fma_f32 v[192:193], v[192:193], s[64:65], v[222:223] op_sel:[0,0,1] op_sel_hi:[1,0,0]
	v_pk_add_f32 v[222:223], v[186:187], v[214:215]
	v_pk_add_f32 v[214:215], v[186:187], v[214:215] neg_lo:[0,1] neg_hi:[0,1]
	v_pk_fma_f32 v[70:71], v[6:7], v[62:63], v[70:71] op_sel_hi:[0,1,1]
	v_pk_add_f32 v[186:187], v[208:209], v[216:217]
	v_pk_add_f32 v[208:209], v[208:209], v[216:217] neg_lo:[0,1] neg_hi:[0,1]
	v_pk_mul_f32 v[74:75], v[20:21], v[62:63] op_sel:[0,1] op_sel_hi:[1,0]
	v_pk_mul_f32 v[216:217], v[208:209], s[68:69]
	v_pk_fma_f32 v[86:87], v[6:7], v[78:79], v[86:87] op_sel_hi:[0,1,1]
	v_pk_fma_f32 v[208:209], v[208:209], s[64:65], v[216:217] op_sel:[0,0,1] op_sel_hi:[1,0,0] neg_lo:[1,0,0] neg_hi:[1,0,0]
	v_pk_add_f32 v[216:217], v[204:205], v[212:213] op_sel:[0,1] op_sel_hi:[1,0] neg_hi:[0,1]
	v_pk_add_f32 v[204:205], v[204:205], v[212:213] op_sel:[0,1] op_sel_hi:[1,0] neg_lo:[0,1]
	v_pk_add_f32 v[212:213], v[170:171], v[194:195]
	v_pk_add_f32 v[170:171], v[170:171], v[194:195] neg_lo:[0,1] neg_hi:[0,1]
	v_pk_mul_f32 v[90:91], v[20:21], v[78:79] op_sel:[0,1] op_sel_hi:[1,0]
	v_pk_mul_f32 v[194:195], v[170:171], s[68:69]
	v_pk_fma_f32 v[102:103], v[6:7], v[94:95], v[102:103] op_sel_hi:[0,1,1]
	v_pk_fma_f32 v[170:171], v[170:171], s[64:65], v[194:195] op_sel:[0,0,1] op_sel_hi:[1,0,0]
	v_pk_add_f32 v[194:195], v[188:189], v[196:197]
	v_pk_add_f32 v[196:197], v[188:189], v[196:197] neg_lo:[0,1] neg_hi:[0,1]
	v_pk_mul_f32 v[106:107], v[20:21], v[94:95] op_sel:[0,1] op_sel_hi:[1,0]
	v_pk_add_f32 v[188:189], v[190:191], v[198:199]
	v_pk_add_f32 v[190:191], v[190:191], v[198:199] neg_lo:[0,1] neg_hi:[0,1]
	v_pk_fma_f32 v[118:119], v[6:7], v[110:111], v[118:119] op_sel_hi:[0,1,1]
	v_pk_mul_f32 v[198:199], v[190:191], s[68:69]
	v_pk_mul_f32 v[122:123], v[20:21], v[110:111] op_sel:[0,1] op_sel_hi:[1,0]
	v_pk_fma_f32 v[190:191], v[190:191], s[64:65], v[198:199] op_sel:[0,0,1] op_sel_hi:[1,0,0] neg_lo:[1,0,0] neg_hi:[1,0,0]
	v_pk_add_f32 v[198:199], v[218:219], v[176:177]
	v_pk_add_f32 v[176:177], v[218:219], v[176:177] neg_lo:[0,1] neg_hi:[0,1]
	v_pk_add_f32 v[218:219], v[206:207], v[162:163]
	v_pk_add_f32 v[162:163], v[206:207], v[162:163] neg_lo:[0,1] neg_hi:[0,1]
	v_xor_b32_e32 v24, 0x80000000, v17
	v_pk_mul_f32 v[206:207], v[162:163], s[68:69]
	v_xor_b32_e32 v28, 0x80000000, v19
	v_pk_fma_f32 v[162:163], v[162:163], s[64:65], v[206:207] op_sel:[0,0,1] op_sel_hi:[1,0,0]
	v_pk_add_f32 v[206:207], v[172:173], v[180:181]
	v_pk_add_f32 v[180:181], v[172:173], v[180:181] neg_lo:[0,1] neg_hi:[0,1]
	v_pk_fma_f32 v[22:23], v[10:11], v[8:9], v[22:23] op_sel_hi:[1,0,1]
	v_pk_add_f32 v[172:173], v[174:175], v[182:183]
	v_pk_add_f32 v[174:175], v[174:175], v[182:183] neg_lo:[0,1] neg_hi:[0,1]
	v_pk_fma_f32 v[42:43], v[8:9], v[26:27], v[42:43] op_sel_hi:[0,1,1]
	v_pk_mul_f32 v[182:183], v[174:175], s[68:69]
	v_pk_fma_f32 v[58:59], v[8:9], v[46:47], v[58:59] op_sel_hi:[0,1,1]
	v_pk_fma_f32 v[174:175], v[174:175], s[64:65], v[182:183] op_sel:[0,0,1] op_sel_hi:[1,0,0] neg_lo:[1,0,0] neg_hi:[1,0,0]
	v_pk_add_f32 v[182:183], v[154:155], v[178:179] op_sel:[0,1] op_sel_hi:[1,0] neg_hi:[0,1]
	v_pk_add_f32 v[154:155], v[154:155], v[178:179] op_sel:[0,1] op_sel_hi:[1,0] neg_lo:[0,1]
	v_pk_add_f32 v[178:179], v[156:157], v[164:165]
	v_pk_add_f32 v[156:157], v[156:157], v[164:165] neg_lo:[0,1] neg_hi:[0,1]
	v_pk_fma_f32 v[74:75], v[8:9], v[62:63], v[74:75] op_sel_hi:[0,1,1]
	v_pk_mul_f32 v[164:165], v[156:157], s[68:69]
	v_pk_fma_f32 v[90:91], v[8:9], v[78:79], v[90:91] op_sel_hi:[0,1,1]
	v_pk_fma_f32 v[156:157], v[156:157], s[64:65], v[164:165] op_sel:[0,0,1] op_sel_hi:[1,0,0]
	v_pk_add_f32 v[164:165], v[158:159], v[166:167]
	v_pk_add_f32 v[166:167], v[158:159], v[166:167] neg_lo:[0,1] neg_hi:[0,1]
	v_pk_fma_f32 v[106:107], v[8:9], v[94:95], v[106:107] op_sel_hi:[0,1,1]
	v_pk_add_f32 v[158:159], v[160:161], v[168:169]
	v_pk_add_f32 v[160:161], v[160:161], v[168:169] neg_lo:[0,1] neg_hi:[0,1]
	v_pk_fma_f32 v[122:123], v[8:9], v[110:111], v[122:123] op_sel_hi:[0,1,1]
	v_pk_mul_f32 v[168:169], v[160:161], s[68:69]
	v_mov_b32_e32 v25, v17
	v_pk_fma_f32 v[160:161], v[160:161], s[64:65], v[168:169] op_sel:[0,0,1] op_sel_hi:[1,0,0] neg_lo:[1,0,0] neg_hi:[1,0,0]
	v_pk_add_f32 v[168:169], v[184:185], v[222:223]
	v_pk_add_f32 v[184:185], v[184:185], v[222:223] neg_lo:[0,1] neg_hi:[0,1]
	v_pk_add_f32 v[222:223], v[220:221], v[186:187]
	v_pk_add_f32 v[220:221], v[220:221], v[186:187] neg_lo:[0,1] neg_hi:[0,1]
	v_mov_b32_e32 v29, v19
	v_pk_add_f32 v[186:187], v[210:211], v[214:215] op_sel:[0,1] op_sel_hi:[1,0] neg_hi:[0,1]
	v_pk_add_f32 v[210:211], v[210:211], v[214:215] op_sel:[0,1] op_sel_hi:[1,0] neg_lo:[0,1]
	v_pk_add_f32 v[214:215], v[192:193], v[208:209]
	v_pk_add_f32 v[208:209], v[192:193], v[208:209] neg_lo:[0,1] neg_hi:[0,1]
	v_xor_b32_e32 v32, 0x80000000, v23
	v_pk_add_f32 v[192:193], v[216:217], v[194:195]
	v_pk_add_f32 v[194:195], v[216:217], v[194:195] neg_lo:[0,1] neg_hi:[0,1]
	v_pk_add_f32 v[216:217], v[212:213], v[188:189]
	v_pk_add_f32 v[212:213], v[212:213], v[188:189] neg_lo:[0,1] neg_hi:[0,1]
	v_xor_b32_e32 v40, 0x80000000, v27
	v_pk_add_f32 v[188:189], v[204:205], v[196:197] op_sel:[0,1] op_sel_hi:[1,0] neg_hi:[0,1]
	v_pk_add_f32 v[196:197], v[204:205], v[196:197] op_sel:[0,1] op_sel_hi:[1,0] neg_lo:[0,1]
	v_pk_add_f32 v[204:205], v[170:171], v[190:191]
	v_pk_add_f32 v[190:191], v[170:171], v[190:191] neg_lo:[0,1] neg_hi:[0,1]
	v_xor_b32_e32 v44, 0x80000000, v31
	v_pk_add_f32 v[170:171], v[198:199], v[206:207]
	v_pk_add_f32 v[198:199], v[198:199], v[206:207] neg_lo:[0,1] neg_hi:[0,1]
	v_pk_add_f32 v[206:207], v[218:219], v[172:173]
	v_pk_add_f32 v[218:219], v[218:219], v[172:173] neg_lo:[0,1] neg_hi:[0,1]
	v_xor_b32_e32 v48, 0x80000000, v39
	v_pk_add_f32 v[172:173], v[176:177], v[180:181] op_sel:[0,1] op_sel_hi:[1,0] neg_hi:[0,1]
	v_pk_add_f32 v[176:177], v[176:177], v[180:181] op_sel:[0,1] op_sel_hi:[1,0] neg_lo:[0,1]
	v_pk_add_f32 v[180:181], v[162:163], v[174:175]
	v_pk_add_f32 v[174:175], v[162:163], v[174:175] neg_lo:[0,1] neg_hi:[0,1]
	v_mov_b32_e32 v33, v23
	v_pk_add_f32 v[162:163], v[182:183], v[164:165]
	v_pk_add_f32 v[164:165], v[182:183], v[164:165] neg_lo:[0,1] neg_hi:[0,1]
	v_pk_add_f32 v[182:183], v[178:179], v[158:159]
	v_pk_add_f32 v[178:179], v[178:179], v[158:159] neg_lo:[0,1] neg_hi:[0,1]
	v_mov_b32_e32 v41, v27
	v_pk_add_f32 v[158:159], v[154:155], v[166:167] op_sel:[0,1] op_sel_hi:[1,0] neg_hi:[0,1]
	v_pk_add_f32 v[154:155], v[154:155], v[166:167] op_sel:[0,1] op_sel_hi:[1,0] neg_lo:[0,1]
	v_pk_add_f32 v[166:167], v[156:157], v[160:161]
	v_pk_add_f32 v[156:157], v[156:157], v[160:161] neg_lo:[0,1] neg_hi:[0,1]
	v_mov_b32_e32 v45, v31
	v_xor_b32_e32 v161, 0x80000000, v156
	v_mov_b32_e32 v160, v157
	v_pk_add_f32 v[156:157], v[168:169], v[222:223]
	v_pk_add_f32 v[168:169], v[168:169], v[222:223] neg_lo:[0,1] neg_hi:[0,1]
	v_pk_add_f32 v[222:223], v[184:185], v[220:221] op_sel:[0,1] op_sel_hi:[1,0] neg_hi:[0,1]
	v_pk_add_f32 v[184:185], v[184:185], v[220:221] op_sel:[0,1] op_sel_hi:[1,0] neg_lo:[0,1]
	v_pk_add_f32 v[220:221], v[186:187], v[214:215]
	v_pk_add_f32 v[186:187], v[186:187], v[214:215] neg_lo:[0,1] neg_hi:[0,1]
	v_pk_add_f32 v[214:215], v[210:211], v[208:209] op_sel:[0,1] op_sel_hi:[1,0] neg_hi:[0,1]
	v_pk_add_f32 v[208:209], v[210:211], v[208:209] op_sel:[0,1] op_sel_hi:[1,0] neg_lo:[0,1]
	v_pk_add_f32 v[210:211], v[192:193], v[216:217]
	v_pk_add_f32 v[192:193], v[192:193], v[216:217] neg_lo:[0,1] neg_hi:[0,1]
	v_pk_add_f32 v[216:217], v[194:195], v[212:213] op_sel:[0,1] op_sel_hi:[1,0] neg_hi:[0,1]
	v_pk_add_f32 v[194:195], v[194:195], v[212:213] op_sel:[0,1] op_sel_hi:[1,0] neg_lo:[0,1]
	v_pk_add_f32 v[212:213], v[188:189], v[204:205]
	v_pk_add_f32 v[188:189], v[188:189], v[204:205] neg_lo:[0,1] neg_hi:[0,1]
	v_pk_add_f32 v[204:205], v[196:197], v[190:191] op_sel:[0,1] op_sel_hi:[1,0] neg_hi:[0,1]
	v_pk_add_f32 v[190:191], v[196:197], v[190:191] op_sel:[0,1] op_sel_hi:[1,0] neg_lo:[0,1]
	v_pk_add_f32 v[196:197], v[170:171], v[206:207]
	v_pk_add_f32 v[170:171], v[170:171], v[206:207] neg_lo:[0,1] neg_hi:[0,1]
	v_pk_mul_f32 v[2:3], v[2:3], v[196:197] op_sel:[0,1] op_sel_hi:[1,0]
	v_pk_add_f32 v[206:207], v[198:199], v[218:219] op_sel:[0,1] op_sel_hi:[1,0] neg_hi:[0,1]
	v_pk_add_f32 v[198:199], v[198:199], v[218:219] op_sel:[0,1] op_sel_hi:[1,0] neg_lo:[0,1]
	v_pk_add_f32 v[218:219], v[172:173], v[180:181]
	v_pk_add_f32 v[172:173], v[172:173], v[180:181] neg_lo:[0,1] neg_hi:[0,1]
	v_pk_add_f32 v[180:181], v[176:177], v[174:175] op_sel:[0,1] op_sel_hi:[1,0] neg_hi:[0,1]
	v_pk_add_f32 v[174:175], v[176:177], v[174:175] op_sel:[0,1] op_sel_hi:[1,0] neg_lo:[0,1]
	v_pk_add_f32 v[176:177], v[162:163], v[182:183]
	v_pk_fma_f32 v[2:3], v[4:5], v[196:197], v[2:3] op_sel_hi:[0,1,1]
	v_pk_mul_f32 v[4:5], v[12:13], v[210:211] op_sel:[0,1] op_sel_hi:[1,0]
	v_mov_b32_e32 v49, v39
	v_pk_fma_f32 v[4:5], v[6:7], v[210:211], v[4:5] op_sel_hi:[0,1,1]
	v_pk_mul_f32 v[6:7], v[20:21], v[176:177] op_sel:[0,1] op_sel_hi:[1,0]
	v_pk_add_f32 v[162:163], v[162:163], v[182:183] neg_lo:[0,1] neg_hi:[0,1]
	v_pk_fma_f32 v[6:7], v[8:9], v[176:177], v[6:7] op_sel_hi:[0,1,1]
	v_pk_mul_f32 v[8:9], v[14:15], v[220:221] op_sel:[0,1] op_sel_hi:[1,0]
	v_pk_add_f32 v[182:183], v[164:165], v[178:179] op_sel:[0,1] op_sel_hi:[1,0] neg_hi:[0,1]
	v_pk_add_f32 v[164:165], v[164:165], v[178:179] op_sel:[0,1] op_sel_hi:[1,0] neg_lo:[0,1]
	v_pk_add_f32 v[178:179], v[158:159], v[166:167]
	v_pk_fma_f32 v[8:9], v[10:11], v[220:221], v[8:9] op_sel_hi:[0,1,1]
	v_pk_mul_f32 v[10:11], v[24:25], v[218:219] op_sel:[0,1] op_sel_hi:[1,0]
	v_pk_mul_f32 v[12:13], v[28:29], v[212:213] op_sel:[0,1] op_sel_hi:[1,0]
	v_xor_b32_e32 v52, 0x80000000, v43
	v_xor_b32_e32 v56, 0x80000000, v47
	v_xor_b32_e32 v60, 0x80000000, v51
	v_xor_b32_e32 v64, 0x80000000, v55
	v_xor_b32_e32 v68, 0x80000000, v59
	v_xor_b32_e32 v72, 0x80000000, v63
	v_xor_b32_e32 v76, 0x80000000, v67
	v_mov_b32_e32 v53, v43
	v_mov_b32_e32 v57, v47
	v_mov_b32_e32 v61, v51
	v_mov_b32_e32 v65, v55
	v_mov_b32_e32 v69, v59
	v_mov_b32_e32 v73, v63
	v_mov_b32_e32 v77, v67
	v_pk_add_f32 v[158:159], v[158:159], v[166:167] neg_lo:[0,1] neg_hi:[0,1]
	v_pk_add_f32 v[166:167], v[154:155], v[160:161]
	v_pk_fma_f32 v[10:11], v[16:17], v[218:219], v[10:11] op_sel_hi:[0,1,1]
	v_pk_fma_f32 v[12:13], v[18:19], v[212:213], v[12:13] op_sel_hi:[0,1,1]
	v_pk_mul_f32 v[14:15], v[32:33], v[178:179] op_sel:[0,1] op_sel_hi:[1,0]
	v_pk_mul_f32 v[16:17], v[40:41], v[222:223] op_sel:[0,1] op_sel_hi:[1,0]
	v_pk_mul_f32 v[18:19], v[44:45], v[206:207] op_sel:[0,1] op_sel_hi:[1,0]
	v_pk_mul_f32 v[20:21], v[48:49], v[216:217] op_sel:[0,1] op_sel_hi:[1,0]
	v_xor_b32_e32 v80, 0x80000000, v71
	v_xor_b32_e32 v84, 0x80000000, v75
	v_xor_b32_e32 v88, 0x80000000, v79
	v_xor_b32_e32 v92, 0x80000000, v83
	v_xor_b32_e32 v96, 0x80000000, v87
	v_xor_b32_e32 v100, 0x80000000, v91
	v_xor_b32_e32 v104, 0x80000000, v95
	v_xor_b32_e32 v108, 0x80000000, v99
	v_xor_b32_e32 v112, 0x80000000, v103
	v_xor_b32_e32 v116, 0x80000000, v107
	v_xor_b32_e32 v120, 0x80000000, v111
	v_xor_b32_e32 v124, 0x80000000, v115
	v_xor_b32_e32 v126, 0x80000000, v119
	v_xor_b32_e32 v128, 0x80000000, v123
	v_mov_b32_e32 v81, v71
	v_mov_b32_e32 v85, v75
	v_mov_b32_e32 v89, v79
	v_mov_b32_e32 v93, v83
	v_mov_b32_e32 v97, v87
	v_mov_b32_e32 v101, v91
	v_mov_b32_e32 v105, v95
	v_mov_b32_e32 v109, v99
	v_mov_b32_e32 v113, v103
	v_mov_b32_e32 v117, v107
	v_mov_b32_e32 v121, v111
	v_mov_b32_e32 v125, v115
	v_mov_b32_e32 v127, v119
	v_mov_b32_e32 v129, v123
	v_pk_add_f32 v[154:155], v[154:155], v[160:161] neg_lo:[0,1] neg_hi:[0,1]
	v_pk_fma_f32 v[14:15], v[22:23], v[178:179], v[14:15] op_sel_hi:[0,1,1]
	v_pk_fma_f32 v[16:17], v[26:27], v[222:223], v[16:17] op_sel_hi:[0,1,1]
	v_pk_fma_f32 v[18:19], v[30:31], v[206:207], v[18:19] op_sel_hi:[0,1,1]
	v_pk_fma_f32 v[20:21], v[38:39], v[216:217], v[20:21] op_sel_hi:[0,1,1]
	v_pk_mul_f32 v[22:23], v[52:53], v[182:183] op_sel:[0,1] op_sel_hi:[1,0]
	v_pk_mul_f32 v[24:25], v[56:57], v[214:215] op_sel:[0,1] op_sel_hi:[1,0]
	v_pk_mul_f32 v[26:27], v[60:61], v[180:181] op_sel:[0,1] op_sel_hi:[1,0]
	v_pk_mul_f32 v[28:29], v[64:65], v[204:205] op_sel:[0,1] op_sel_hi:[1,0]
	v_pk_mul_f32 v[30:31], v[68:69], v[166:167] op_sel:[0,1] op_sel_hi:[1,0]
	v_pk_mul_f32 v[32:33], v[72:73], v[168:169] op_sel:[0,1] op_sel_hi:[1,0]
	v_pk_mul_f32 v[38:39], v[76:77], v[170:171] op_sel:[0,1] op_sel_hi:[1,0]
	v_pk_fma_f32 v[22:23], v[42:43], v[182:183], v[22:23] op_sel_hi:[0,1,1]
	v_pk_fma_f32 v[24:25], v[46:47], v[214:215], v[24:25] op_sel_hi:[0,1,1]
	v_pk_fma_f32 v[26:27], v[50:51], v[180:181], v[26:27] op_sel_hi:[0,1,1]
	v_pk_fma_f32 v[28:29], v[54:55], v[204:205], v[28:29] op_sel_hi:[0,1,1]
	v_pk_fma_f32 v[30:31], v[58:59], v[166:167], v[30:31] op_sel_hi:[0,1,1]
	v_pk_fma_f32 v[32:33], v[62:63], v[168:169], v[32:33] op_sel_hi:[0,1,1]
	v_pk_fma_f32 v[38:39], v[66:67], v[170:171], v[38:39] op_sel_hi:[0,1,1]
	v_pk_mul_f32 v[40:41], v[80:81], v[192:193] op_sel:[0,1] op_sel_hi:[1,0]
	v_pk_mul_f32 v[42:43], v[84:85], v[162:163] op_sel:[0,1] op_sel_hi:[1,0]
	v_pk_mul_f32 v[44:45], v[88:89], v[186:187] op_sel:[0,1] op_sel_hi:[1,0]
	v_pk_mul_f32 v[46:47], v[92:93], v[172:173] op_sel:[0,1] op_sel_hi:[1,0]
	v_pk_mul_f32 v[48:49], v[96:97], v[188:189] op_sel:[0,1] op_sel_hi:[1,0]
	v_pk_mul_f32 v[50:51], v[100:101], v[158:159] op_sel:[0,1] op_sel_hi:[1,0]
	v_pk_mul_f32 v[52:53], v[104:105], v[184:185] op_sel:[0,1] op_sel_hi:[1,0]
	v_pk_mul_f32 v[54:55], v[108:109], v[198:199] op_sel:[0,1] op_sel_hi:[1,0]
	v_pk_mul_f32 v[56:57], v[112:113], v[194:195] op_sel:[0,1] op_sel_hi:[1,0]
	v_pk_mul_f32 v[58:59], v[116:117], v[164:165] op_sel:[0,1] op_sel_hi:[1,0]
	v_pk_mul_f32 v[60:61], v[120:121], v[208:209] op_sel:[0,1] op_sel_hi:[1,0]
	v_pk_mul_f32 v[62:63], v[124:125], v[174:175] op_sel:[0,1] op_sel_hi:[1,0]
	v_pk_mul_f32 v[64:65], v[126:127], v[190:191] op_sel:[0,1] op_sel_hi:[1,0]
	v_pk_mul_f32 v[66:67], v[128:129], v[154:155] op_sel:[0,1] op_sel_hi:[1,0]
	v_pk_fma_f32 v[40:41], v[70:71], v[192:193], v[40:41] op_sel_hi:[0,1,1]
	v_pk_fma_f32 v[42:43], v[74:75], v[162:163], v[42:43] op_sel_hi:[0,1,1]
	v_pk_fma_f32 v[44:45], v[78:79], v[186:187], v[44:45] op_sel_hi:[0,1,1]
	v_pk_fma_f32 v[46:47], v[82:83], v[172:173], v[46:47] op_sel_hi:[0,1,1]
	v_pk_fma_f32 v[48:49], v[86:87], v[188:189], v[48:49] op_sel_hi:[0,1,1]
	v_pk_fma_f32 v[50:51], v[90:91], v[158:159], v[50:51] op_sel_hi:[0,1,1]
	v_pk_fma_f32 v[52:53], v[94:95], v[184:185], v[52:53] op_sel_hi:[0,1,1]
	v_pk_fma_f32 v[54:55], v[98:99], v[198:199], v[54:55] op_sel_hi:[0,1,1]
	v_pk_fma_f32 v[56:57], v[102:103], v[194:195], v[56:57] op_sel_hi:[0,1,1]
	v_pk_fma_f32 v[58:59], v[106:107], v[164:165], v[58:59] op_sel_hi:[0,1,1]
	v_pk_fma_f32 v[60:61], v[110:111], v[208:209], v[60:61] op_sel_hi:[0,1,1]
	v_pk_fma_f32 v[62:63], v[114:115], v[174:175], v[62:63] op_sel_hi:[0,1,1]
	v_pk_fma_f32 v[64:65], v[118:119], v[190:191], v[64:65] op_sel_hi:[0,1,1]
	v_pk_fma_f32 v[66:67], v[122:123], v[154:155], v[66:67] op_sel_hi:[0,1,1]
	ds_write_b64 v36, v[156:157]
	ds_write_b64 v36, v[32:33] offset:2112
	ds_write_b64 v36, v[16:17] offset:4224
	ds_write_b64 v36, v[52:53] offset:6336
	ds_write_b64 v36, v[8:9] offset:8448
	ds_write_b64 v36, v[44:45] offset:10560
	ds_write_b64 v36, v[24:25] offset:12672
	ds_write_b64 v36, v[60:61] offset:14784
	ds_write_b64 v36, v[4:5] offset:16896
	ds_write_b64 v36, v[40:41] offset:19008
	ds_write_b64 v36, v[20:21] offset:21120
	ds_write_b64 v36, v[56:57] offset:23232
	ds_write_b64 v36, v[12:13] offset:25344
	ds_write_b64 v36, v[48:49] offset:27456
	ds_write_b64 v36, v[28:29] offset:29568
	ds_write_b64 v36, v[64:65] offset:31680
	ds_write_b64 v36, v[2:3] offset:33792
	ds_write_b64 v36, v[38:39] offset:35904
	ds_write_b64 v36, v[18:19] offset:38016
	ds_write_b64 v36, v[54:55] offset:40128
	ds_write_b64 v36, v[10:11] offset:42240
	ds_write_b64 v36, v[46:47] offset:44352
	ds_write_b64 v36, v[26:27] offset:46464
	ds_write_b64 v36, v[62:63] offset:48576
	ds_write_b64 v36, v[6:7] offset:50688
	ds_write_b64 v36, v[42:43] offset:52800
	ds_write_b64 v36, v[22:23] offset:54912
	ds_write_b64 v36, v[58:59] offset:57024
	ds_write_b64 v36, v[14:15] offset:59136
	ds_write_b64 v36, v[50:51] offset:61248
	ds_write_b64 v36, v[30:31] offset:63360
	ds_write_b64 v36, v[66:67] offset:65472
	v_mov_b32_e32 v3, v130
	s_waitcnt lgkmcnt(0)
	s_barrier
	s_nop 0
	v_and_b32_e32 v5, 15, v3
	v_cvt_f32_ubyte0_e32 v2, v5
	v_mul_f32_e32 v4, 0x3b800000, v2
	v_sin_f32_e32 v2, v4
	v_cos_f32_e32 v4, v4
	v_lshlrev_b32_e32 v66, 3, v5
	v_lshlrev_b32_e32 v36, 4, v3
	v_xor_b32_e32 v5, 0x80000000, v2
	v_mov_b32_e32 v3, v5
	v_pk_mul_f32 v[6:7], v[4:5], v[2:3] op_sel:[1,0] op_sel_hi:[0,1]
	v_pk_fma_f32 v[6:7], v[4:5], v[4:5], v[6:7] op_sel_hi:[0,1,1]
	v_xor_b32_e32 v12, 0x80000000, v7
	v_mov_b32_e32 v13, v7
	v_pk_mul_f32 v[10:11], v[6:7], v[12:13] op_sel:[1,0] op_sel_hi:[0,1]
	v_pk_fma_f32 v[10:11], v[6:7], v[6:7], v[10:11] op_sel_hi:[1,0,1]
	v_pk_mul_f32 v[8:9], v[2:3], v[6:7] op_sel:[0,1] op_sel_hi:[1,0]
	v_xor_b32_e32 v14, 0x80000000, v11
	v_mov_b32_e32 v15, v11
	v_pk_mul_f32 v[30:31], v[10:11], v[14:15] op_sel:[1,0] op_sel_hi:[0,1]
	v_pk_fma_f32 v[30:31], v[10:11], v[10:11], v[30:31] op_sel_hi:[1,0,1]
	v_pk_mul_f32 v[16:17], v[2:3], v[10:11] op_sel:[0,1] op_sel_hi:[1,0]
	v_pk_mul_f32 v[50:51], v[14:15], v[30:31] op_sel:[0,1] op_sel_hi:[1,0]
	v_pk_mul_f32 v[38:39], v[2:3], v[30:31] op_sel:[0,1] op_sel_hi:[1,0]
	v_pk_fma_f32 v[50:51], v[10:11], v[30:31], v[50:51] op_sel_hi:[0,1,1]
	v_pk_mul_f32 v[54:55], v[2:3], v[50:51] op_sel:[0,1] op_sel_hi:[1,0]
	v_pk_fma_f32 v[8:9], v[4:5], v[6:7], v[8:9] op_sel_hi:[0,1,1]
	v_pk_fma_f32 v[16:17], v[4:5], v[10:11], v[16:17] op_sel_hi:[0,1,1]
	v_pk_fma_f32 v[38:39], v[4:5], v[30:31], v[38:39] op_sel_hi:[0,1,1]
	v_pk_fma_f32 v[54:55], v[4:5], v[50:51], v[54:55] op_sel_hi:[0,1,1]
	v_and_b32_e32 v5, 0xffffff00, v36
	v_lshlrev_b32_e32 v36, 3, v5
	v_add3_u32 v36, 0, v66, v36
	v_ashrrev_i32_e32 v66, 2, v5
	v_add_u32_e32 v108, v36, v66
	ds_read2_b64 v[66:69], v108 offset1:16
	ds_read2_b64 v[70:73], v108 offset0:33 offset1:49
	ds_read2_b64 v[74:77], v108 offset0:66 offset1:82
	ds_read2_b64 v[78:81], v108 offset0:132 offset1:148
	ds_read2_b64 v[82:85], v108 offset0:99 offset1:115
	ds_read2_b64 v[86:89], v108 offset0:165 offset1:181
	ds_read2_b64 v[90:93], v108 offset0:198 offset1:214
	ds_read2_b64 v[94:97], v108 offset0:231 offset1:247
	s_waitcnt lgkmcnt(4)
	v_pk_add_f32 v[98:99], v[66:67], v[78:79]
	v_pk_add_f32 v[66:67], v[66:67], v[78:79] neg_lo:[0,1] neg_hi:[0,1]
	v_pk_add_f32 v[78:79], v[68:69], v[80:81]
	v_pk_add_f32 v[68:69], v[68:69], v[80:81] neg_lo:[0,1] neg_hi:[0,1]
	s_waitcnt lgkmcnt(1)
	v_pk_add_f32 v[100:101], v[76:77], v[92:93]
	v_pk_mul_f32 v[80:81], v[68:69], s[44:45]
	v_pk_add_f32 v[76:77], v[76:77], v[92:93] neg_lo:[0,1] neg_hi:[0,1]
	v_pk_fma_f32 v[68:69], v[68:69], s[42:43], v[80:81] op_sel:[0,0,1] op_sel_hi:[1,0,0]
	v_pk_add_f32 v[80:81], v[70:71], v[86:87]
	v_pk_add_f32 v[70:71], v[70:71], v[86:87] neg_lo:[0,1] neg_hi:[0,1]
	v_pk_mul_f32 v[92:93], v[76:77], s[76:77]
	v_pk_mul_f32 v[86:87], v[70:71], s[68:69]
	v_pk_fma_f32 v[76:77], v[76:77], s[72:73], v[92:93] op_sel:[0,0,1] op_sel_hi:[1,0,0] neg_lo:[1,0,0] neg_hi:[1,0,0]
	v_pk_fma_f32 v[70:71], v[70:71], s[64:65], v[86:87] op_sel:[0,0,1] op_sel_hi:[1,0,0]
	v_pk_add_f32 v[86:87], v[72:73], v[88:89]
	v_pk_add_f32 v[72:73], v[72:73], v[88:89] neg_lo:[0,1] neg_hi:[0,1]
	s_waitcnt lgkmcnt(0)
	v_pk_add_f32 v[92:93], v[82:83], v[94:95]
	v_pk_add_f32 v[82:83], v[82:83], v[94:95] neg_lo:[0,1] neg_hi:[0,1]
	v_pk_mul_f32 v[88:89], v[72:73], s[76:77]
	v_pk_mul_f32 v[94:95], v[82:83], s[68:69]
	v_pk_fma_f32 v[72:73], v[72:73], s[72:73], v[88:89] op_sel:[0,0,1] op_sel_hi:[1,0,0]
	v_pk_add_f32 v[88:89], v[74:75], v[90:91]
	v_pk_add_f32 v[90:91], v[74:75], v[90:91] neg_lo:[0,1] neg_hi:[0,1]
	v_pk_fma_f32 v[82:83], v[82:83], s[64:65], v[94:95] op_sel:[0,0,1] op_sel_hi:[1,0,0] neg_lo:[1,0,0] neg_hi:[1,0,0]
	v_pk_add_f32 v[94:95], v[84:85], v[96:97]
	v_pk_add_f32 v[84:85], v[84:85], v[96:97] neg_lo:[0,1] neg_hi:[0,1]
	s_nop 0
	v_pk_mul_f32 v[96:97], v[84:85], s[44:45]
	s_nop 0
	v_pk_fma_f32 v[84:85], v[84:85], s[42:43], v[96:97] op_sel:[0,0,1] op_sel_hi:[1,0,0] neg_lo:[1,0,0] neg_hi:[1,0,0]
	v_pk_add_f32 v[96:97], v[98:99], v[88:89]
	v_pk_add_f32 v[88:89], v[98:99], v[88:89] neg_lo:[0,1] neg_hi:[0,1]
	v_pk_add_f32 v[98:99], v[78:79], v[100:101]
	v_pk_add_f32 v[78:79], v[78:79], v[100:101] neg_lo:[0,1] neg_hi:[0,1]
	v_pk_add_f32 v[102:103], v[86:87], v[94:95]
	v_pk_add_f32 v[86:87], v[86:87], v[94:95] neg_lo:[0,1] neg_hi:[0,1]
	v_pk_add_f32 v[74:75], v[66:67], v[90:91] op_sel:[0,1] op_sel_hi:[1,0] neg_hi:[0,1]
	v_pk_add_f32 v[66:67], v[66:67], v[90:91] op_sel:[0,1] op_sel_hi:[1,0] neg_lo:[0,1]
	v_pk_add_f32 v[90:91], v[68:69], v[76:77]
	v_pk_add_f32 v[68:69], v[68:69], v[76:77] neg_lo:[0,1] neg_hi:[0,1]
	v_pk_mul_f32 v[100:101], v[78:79], s[68:69]
	v_pk_mul_f32 v[94:95], v[86:87], s[68:69]
	v_pk_mul_f32 v[76:77], v[68:69], s[68:69]
	v_pk_fma_f32 v[78:79], v[78:79], s[64:65], v[100:101] op_sel:[0,0,1] op_sel_hi:[1,0,0]
	v_pk_add_f32 v[100:101], v[80:81], v[92:93]
	v_pk_add_f32 v[92:93], v[80:81], v[92:93] neg_lo:[0,1] neg_hi:[0,1]
	v_pk_fma_f32 v[86:87], v[86:87], s[64:65], v[94:95] op_sel:[0,0,1] op_sel_hi:[1,0,0] neg_lo:[1,0,0] neg_hi:[1,0,0]
	v_pk_fma_f32 v[68:69], v[68:69], s[64:65], v[76:77] op_sel:[0,0,1] op_sel_hi:[1,0,0]
	v_pk_add_f32 v[76:77], v[70:71], v[82:83]
	v_pk_add_f32 v[94:95], v[72:73], v[84:85]
	v_pk_add_f32 v[72:73], v[72:73], v[84:85] neg_lo:[0,1] neg_hi:[0,1]
	v_pk_add_f32 v[82:83], v[70:71], v[82:83] neg_lo:[0,1] neg_hi:[0,1]
	v_pk_mul_f32 v[84:85], v[72:73], s[68:69]
	v_pk_add_f32 v[104:105], v[74:75], v[76:77]
	v_pk_add_f32 v[74:75], v[74:75], v[76:77] neg_lo:[0,1] neg_hi:[0,1]
	v_pk_add_f32 v[76:77], v[90:91], v[94:95]
	v_pk_add_f32 v[94:95], v[90:91], v[94:95] neg_lo:[0,1] neg_hi:[0,1]
	v_xor_b32_e32 v18, 0x80000000, v9
	v_mov_b32_e32 v19, v9
	v_pk_mul_f32 v[22:23], v[12:13], v[10:11] op_sel:[0,1] op_sel_hi:[1,0]
	v_pk_fma_f32 v[72:73], v[72:73], s[64:65], v[84:85] op_sel:[0,0,1] op_sel_hi:[1,0,0] neg_lo:[1,0,0] neg_hi:[1,0,0]
	v_pk_add_f32 v[80:81], v[88:89], v[92:93] op_sel:[0,1] op_sel_hi:[1,0] neg_hi:[0,1]
	v_pk_add_f32 v[88:89], v[88:89], v[92:93] op_sel:[0,1] op_sel_hi:[1,0] neg_lo:[0,1]
	v_pk_add_f32 v[92:93], v[78:79], v[86:87]
	v_pk_add_f32 v[86:87], v[78:79], v[86:87] neg_lo:[0,1] neg_hi:[0,1]
	v_xor_b32_e32 v20, 0x80000000, v17
	v_mov_b32_e32 v21, v17
	v_pk_fma_f32 v[22:23], v[6:7], v[10:11], v[22:23] op_sel_hi:[0,1,1]
	v_pk_mul_f32 v[26:27], v[10:11], v[18:19] op_sel:[1,0] op_sel_hi:[0,1]
	v_pk_add_f32 v[70:71], v[66:67], v[82:83] op_sel:[0,1] op_sel_hi:[1,0] neg_hi:[0,1]
	v_pk_add_f32 v[66:67], v[66:67], v[82:83] op_sel:[0,1] op_sel_hi:[1,0] neg_lo:[0,1]
	v_pk_add_f32 v[82:83], v[68:69], v[72:73]
	v_pk_add_f32 v[72:73], v[68:69], v[72:73] neg_lo:[0,1] neg_hi:[0,1]
	v_pk_add_f32 v[90:91], v[74:75], v[94:95] op_sel:[0,1] op_sel_hi:[1,0] neg_hi:[0,1]
	v_xor_b32_e32 v24, 0x80000000, v23
	v_mov_b32_e32 v25, v23
	v_pk_fma_f32 v[26:27], v[10:11], v[8:9], v[26:27] op_sel_hi:[1,0,1]
	v_pk_add_f32 v[78:79], v[88:89], v[86:87] op_sel:[0,1] op_sel_hi:[1,0] neg_hi:[0,1]
	v_pk_add_f32 v[74:75], v[74:75], v[94:95] op_sel:[0,1] op_sel_hi:[1,0] neg_lo:[0,1]
	v_pk_mul_f32 v[94:95], v[20:21], v[90:91] op_sel:[0,1] op_sel_hi:[1,0]
	v_xor_b32_e32 v28, 0x80000000, v27
	v_mov_b32_e32 v29, v27
	v_pk_add_f32 v[84:85], v[96:97], v[100:101]
	v_pk_add_f32 v[96:97], v[96:97], v[100:101] neg_lo:[0,1] neg_hi:[0,1]
	v_pk_add_f32 v[100:101], v[98:99], v[102:103]
	v_pk_add_f32 v[68:69], v[66:67], v[72:73] op_sel:[0,1] op_sel_hi:[1,0] neg_hi:[0,1]
	v_pk_fma_f32 v[90:91], v[16:17], v[90:91], v[94:95] op_sel_hi:[0,1,1]
	v_pk_mul_f32 v[94:95], v[24:25], v[78:79] op_sel:[0,1] op_sel_hi:[1,0]
	v_xor_b32_e32 v32, 0x80000000, v31
	v_mov_b32_e32 v33, v31
	v_pk_mul_f32 v[42:43], v[12:13], v[30:31] op_sel:[0,1] op_sel_hi:[1,0]
	v_pk_add_f32 v[106:107], v[84:85], v[100:101]
	v_pk_add_f32 v[84:85], v[84:85], v[100:101] neg_lo:[0,1] neg_hi:[0,1]
	v_pk_fma_f32 v[78:79], v[22:23], v[78:79], v[94:95] op_sel_hi:[0,1,1]
	v_pk_mul_f32 v[94:95], v[28:29], v[68:69] op_sel:[0,1] op_sel_hi:[1,0]
	v_xor_b32_e32 v40, 0x80000000, v39
	v_mov_b32_e32 v41, v39
	v_pk_fma_f32 v[42:43], v[6:7], v[30:31], v[42:43] op_sel_hi:[0,1,1]
	v_pk_mul_f32 v[46:47], v[18:19], v[30:31] op_sel:[0,1] op_sel_hi:[1,0]
	v_pk_add_f32 v[86:87], v[88:89], v[86:87] op_sel:[0,1] op_sel_hi:[1,0] neg_lo:[0,1]
	v_pk_add_f32 v[88:89], v[104:105], v[76:77]
	v_pk_add_f32 v[76:77], v[104:105], v[76:77] neg_lo:[0,1] neg_hi:[0,1]
	v_pk_fma_f32 v[68:69], v[26:27], v[68:69], v[94:95] op_sel_hi:[0,1,1]
	v_pk_mul_f32 v[94:95], v[32:33], v[84:85] op_sel:[0,1] op_sel_hi:[1,0]
	v_xor_b32_e32 v44, 0x80000000, v43
	v_mov_b32_e32 v45, v43
	v_pk_fma_f32 v[46:47], v[8:9], v[30:31], v[46:47] op_sel_hi:[0,1,1]
	v_pk_add_f32 v[102:103], v[98:99], v[102:103] neg_lo:[0,1] neg_hi:[0,1]
	v_pk_add_f32 v[100:101], v[80:81], v[92:93]
	v_pk_add_f32 v[80:81], v[80:81], v[92:93] neg_lo:[0,1] neg_hi:[0,1]
	v_pk_fma_f32 v[84:85], v[30:31], v[84:85], v[94:95] op_sel_hi:[0,1,1]
	v_pk_mul_f32 v[94:95], v[40:41], v[76:77] op_sel:[0,1] op_sel_hi:[1,0]
	v_xor_b32_e32 v48, 0x80000000, v47
	v_mov_b32_e32 v49, v47
	v_pk_add_f32 v[92:93], v[70:71], v[82:83]
	v_pk_add_f32 v[70:71], v[70:71], v[82:83] neg_lo:[0,1] neg_hi:[0,1]
	v_pk_fma_f32 v[76:77], v[38:39], v[76:77], v[94:95] op_sel_hi:[0,1,1]
	v_pk_mul_f32 v[94:95], v[44:45], v[80:81] op_sel:[0,1] op_sel_hi:[1,0]
	v_xor_b32_e32 v52, 0x80000000, v51
	v_mov_b32_e32 v53, v51
	v_pk_mul_f32 v[58:59], v[12:13], v[50:51] op_sel:[0,1] op_sel_hi:[1,0]
	v_pk_add_f32 v[98:99], v[96:97], v[102:103] op_sel:[0,1] op_sel_hi:[1,0] neg_hi:[0,1]
	v_pk_add_f32 v[96:97], v[96:97], v[102:103] op_sel:[0,1] op_sel_hi:[1,0] neg_lo:[0,1]
	v_pk_fma_f32 v[80:81], v[42:43], v[80:81], v[94:95] op_sel_hi:[0,1,1]
	v_pk_mul_f32 v[94:95], v[48:49], v[70:71] op_sel:[0,1] op_sel_hi:[1,0]
	v_xor_b32_e32 v56, 0x80000000, v55
	v_mov_b32_e32 v57, v55
	v_pk_fma_f32 v[58:59], v[6:7], v[50:51], v[58:59] op_sel_hi:[0,1,1]
	v_pk_mul_f32 v[62:63], v[18:19], v[50:51] op_sel:[0,1] op_sel_hi:[1,0]
	v_pk_fma_f32 v[70:71], v[46:47], v[70:71], v[94:95] op_sel_hi:[0,1,1]
	v_pk_mul_f32 v[94:95], v[52:53], v[96:97] op_sel:[0,1] op_sel_hi:[1,0]
	v_xor_b32_e32 v60, 0x80000000, v59
	v_mov_b32_e32 v61, v59
	v_pk_fma_f32 v[62:63], v[8:9], v[50:51], v[62:63] op_sel_hi:[0,1,1]
	v_pk_add_f32 v[66:67], v[66:67], v[72:73] op_sel:[0,1] op_sel_hi:[1,0] neg_lo:[0,1]
	v_pk_mul_f32 v[72:73], v[2:3], v[88:89] op_sel:[0,1] op_sel_hi:[1,0]
	v_pk_fma_f32 v[94:95], v[50:51], v[96:97], v[94:95] op_sel_hi:[0,1,1]
	v_pk_mul_f32 v[96:97], v[56:57], v[74:75] op_sel:[0,1] op_sel_hi:[1,0]
	v_xor_b32_e32 v64, 0x80000000, v63
	v_mov_b32_e32 v65, v63
	v_pk_fma_f32 v[72:73], v[4:5], v[88:89], v[72:73] op_sel_hi:[0,1,1]
	v_pk_mul_f32 v[88:89], v[18:19], v[92:93] op_sel:[0,1] op_sel_hi:[1,0]
	v_pk_fma_f32 v[74:75], v[54:55], v[74:75], v[96:97] op_sel_hi:[0,1,1]
	v_pk_mul_f32 v[96:97], v[60:61], v[86:87] op_sel:[0,1] op_sel_hi:[1,0]
	v_add_u32_e32 v5, 0x2000, v5
	v_pk_mul_f32 v[82:83], v[12:13], v[100:101] op_sel:[0,1] op_sel_hi:[1,0]
	v_pk_fma_f32 v[88:89], v[8:9], v[92:93], v[88:89] op_sel_hi:[0,1,1]
	v_pk_mul_f32 v[92:93], v[14:15], v[98:99] op_sel:[0,1] op_sel_hi:[1,0]
	v_pk_fma_f32 v[86:87], v[58:59], v[86:87], v[96:97] op_sel_hi:[0,1,1]
	v_pk_mul_f32 v[96:97], v[64:65], v[66:67] op_sel:[0,1] op_sel_hi:[1,0]
	v_ashrrev_i32_e32 v5, 2, v5
	v_pk_fma_f32 v[82:83], v[6:7], v[100:101], v[82:83] op_sel_hi:[0,1,1]
	v_pk_fma_f32 v[92:93], v[10:11], v[98:99], v[92:93] op_sel_hi:[0,1,1]
	v_pk_fma_f32 v[66:67], v[62:63], v[66:67], v[96:97] op_sel_hi:[0,1,1]
	ds_write2_b64 v108, v[106:107], v[84:85] offset1:16
	ds_write2_b64 v108, v[92:93], v[94:95] offset0:33 offset1:49
	ds_write2_b64 v108, v[82:83], v[80:81] offset0:66 offset1:82
	ds_write2_b64 v108, v[78:79], v[86:87] offset0:99 offset1:115
	ds_write2_b64 v108, v[72:73], v[76:77] offset0:132 offset1:148
	ds_write2_b64 v108, v[90:91], v[74:75] offset0:165 offset1:181
	ds_write2_b64 v108, v[88:89], v[70:71] offset0:198 offset1:214
	ds_write2_b64 v108, v[68:69], v[66:67] offset0:231 offset1:247
	v_add3_u32 v36, v36, v5, s30
	ds_read2_b64 v[66:69], v36 offset1:16
	ds_read2_b64 v[70:73], v36 offset0:33 offset1:49
	ds_read2_b64 v[74:77], v36 offset0:66 offset1:82
	ds_read2_b64 v[78:81], v36 offset0:132 offset1:148
	ds_read2_b64 v[82:85], v36 offset0:99 offset1:115
	ds_read2_b64 v[86:89], v36 offset0:165 offset1:181
	ds_read2_b64 v[90:93], v36 offset0:198 offset1:214
	ds_read2_b64 v[94:97], v36 offset0:231 offset1:247
	s_waitcnt lgkmcnt(4)
	v_pk_add_f32 v[98:99], v[66:67], v[78:79]
	v_pk_add_f32 v[66:67], v[66:67], v[78:79] neg_lo:[0,1] neg_hi:[0,1]
	v_pk_add_f32 v[78:79], v[68:69], v[80:81]
	v_pk_add_f32 v[68:69], v[68:69], v[80:81] neg_lo:[0,1] neg_hi:[0,1]
	s_waitcnt lgkmcnt(1)
	v_pk_add_f32 v[100:101], v[76:77], v[92:93]
	v_pk_mul_f32 v[80:81], v[68:69], s[44:45]
	v_pk_add_f32 v[76:77], v[76:77], v[92:93] neg_lo:[0,1] neg_hi:[0,1]
	v_pk_fma_f32 v[68:69], v[68:69], s[42:43], v[80:81] op_sel:[0,0,1] op_sel_hi:[1,0,0]
	v_pk_add_f32 v[80:81], v[70:71], v[86:87]
	v_pk_add_f32 v[70:71], v[70:71], v[86:87] neg_lo:[0,1] neg_hi:[0,1]
	v_pk_mul_f32 v[92:93], v[76:77], s[76:77]
	v_pk_mul_f32 v[86:87], v[70:71], s[68:69]
	v_pk_fma_f32 v[76:77], v[76:77], s[72:73], v[92:93] op_sel:[0,0,1] op_sel_hi:[1,0,0] neg_lo:[1,0,0] neg_hi:[1,0,0]
	s_waitcnt lgkmcnt(0)
	v_pk_add_f32 v[92:93], v[82:83], v[94:95]
	v_pk_add_f32 v[82:83], v[82:83], v[94:95] neg_lo:[0,1] neg_hi:[0,1]
	v_pk_fma_f32 v[70:71], v[70:71], s[64:65], v[86:87] op_sel:[0,0,1] op_sel_hi:[1,0,0]
	v_pk_add_f32 v[86:87], v[72:73], v[88:89]
	v_pk_add_f32 v[72:73], v[72:73], v[88:89] neg_lo:[0,1] neg_hi:[0,1]
	v_pk_mul_f32 v[94:95], v[82:83], s[68:69]
	v_pk_mul_f32 v[88:89], v[72:73], s[76:77]
	v_pk_fma_f32 v[82:83], v[82:83], s[64:65], v[94:95] op_sel:[0,0,1] op_sel_hi:[1,0,0] neg_lo:[1,0,0] neg_hi:[1,0,0]
	v_pk_add_f32 v[94:95], v[84:85], v[96:97]
	v_pk_add_f32 v[84:85], v[84:85], v[96:97] neg_lo:[0,1] neg_hi:[0,1]
	v_pk_fma_f32 v[72:73], v[72:73], s[72:73], v[88:89] op_sel:[0,0,1] op_sel_hi:[1,0,0]
	v_pk_add_f32 v[88:89], v[74:75], v[90:91]
	v_pk_mul_f32 v[96:97], v[84:85], s[44:45]
	v_pk_add_f32 v[90:91], v[74:75], v[90:91] neg_lo:[0,1] neg_hi:[0,1]
	v_pk_fma_f32 v[84:85], v[84:85], s[42:43], v[96:97] op_sel:[0,0,1] op_sel_hi:[1,0,0] neg_lo:[1,0,0] neg_hi:[1,0,0]
	v_pk_add_f32 v[96:97], v[98:99], v[88:89]
	v_pk_add_f32 v[88:89], v[98:99], v[88:89] neg_lo:[0,1] neg_hi:[0,1]
	v_pk_add_f32 v[98:99], v[78:79], v[100:101]
	v_pk_add_f32 v[78:79], v[78:79], v[100:101] neg_lo:[0,1] neg_hi:[0,1]
	v_pk_add_f32 v[102:103], v[86:87], v[94:95]
	v_pk_add_f32 v[86:87], v[86:87], v[94:95] neg_lo:[0,1] neg_hi:[0,1]
	v_pk_mul_f32 v[100:101], v[78:79], s[68:69]
	v_pk_mul_f32 v[94:95], v[86:87], s[68:69]
	v_pk_fma_f32 v[78:79], v[78:79], s[64:65], v[100:101] op_sel:[0,0,1] op_sel_hi:[1,0,0]
	v_pk_add_f32 v[100:101], v[80:81], v[92:93]
	v_pk_add_f32 v[92:93], v[80:81], v[92:93] neg_lo:[0,1] neg_hi:[0,1]
	v_pk_fma_f32 v[86:87], v[86:87], s[64:65], v[94:95] op_sel:[0,0,1] op_sel_hi:[1,0,0] neg_lo:[1,0,0] neg_hi:[1,0,0]
	v_pk_add_f32 v[74:75], v[66:67], v[90:91] op_sel:[0,1] op_sel_hi:[1,0] neg_hi:[0,1]
	v_pk_add_f32 v[66:67], v[66:67], v[90:91] op_sel:[0,1] op_sel_hi:[1,0] neg_lo:[0,1]
	v_pk_add_f32 v[90:91], v[68:69], v[76:77]
	v_pk_add_f32 v[68:69], v[68:69], v[76:77] neg_lo:[0,1] neg_hi:[0,1]
	v_pk_add_f32 v[94:95], v[72:73], v[84:85]
	v_pk_add_f32 v[72:73], v[72:73], v[84:85] neg_lo:[0,1] neg_hi:[0,1]
	v_pk_mul_f32 v[76:77], v[68:69], s[68:69]
	v_pk_mul_f32 v[84:85], v[72:73], s[68:69]
	v_pk_fma_f32 v[68:69], v[68:69], s[64:65], v[76:77] op_sel:[0,0,1] op_sel_hi:[1,0,0]
	v_pk_add_f32 v[76:77], v[70:71], v[82:83]
	v_pk_fma_f32 v[72:73], v[72:73], s[64:65], v[84:85] op_sel:[0,0,1] op_sel_hi:[1,0,0] neg_lo:[1,0,0] neg_hi:[1,0,0]
	v_pk_add_f32 v[80:81], v[88:89], v[92:93] op_sel:[0,1] op_sel_hi:[1,0] neg_hi:[0,1]
	v_pk_add_f32 v[88:89], v[88:89], v[92:93] op_sel:[0,1] op_sel_hi:[1,0] neg_lo:[0,1]
	v_pk_add_f32 v[92:93], v[78:79], v[86:87]
	v_pk_add_f32 v[86:87], v[78:79], v[86:87] neg_lo:[0,1] neg_hi:[0,1]
	s_add_i32 s65, s65, s28
	v_pk_add_f32 v[82:83], v[70:71], v[82:83] neg_lo:[0,1] neg_hi:[0,1]
	s_nop 0
	v_pk_add_f32 v[104:105], v[74:75], v[76:77]
	v_pk_add_f32 v[74:75], v[74:75], v[76:77] neg_lo:[0,1] neg_hi:[0,1]
	v_pk_add_f32 v[76:77], v[90:91], v[94:95]
	s_cmpk_gt_i32 s65, 0x3ff
	s_nop 0
	v_pk_add_f32 v[84:85], v[96:97], v[100:101]
	v_pk_add_f32 v[96:97], v[96:97], v[100:101] neg_lo:[0,1] neg_hi:[0,1]
	v_pk_add_f32 v[100:101], v[98:99], v[102:103]
	s_nop 0
	v_pk_add_f32 v[78:79], v[88:89], v[86:87] op_sel:[0,1] op_sel_hi:[1,0] neg_hi:[0,1]
	v_pk_add_f32 v[86:87], v[88:89], v[86:87] op_sel:[0,1] op_sel_hi:[1,0] neg_lo:[0,1]
	v_pk_add_f32 v[88:89], v[104:105], v[76:77]
	s_cselect_b64 s[80:81], -1, 0
	s_cmpk_lt_i32 s65, 0x400
	v_pk_add_f32 v[98:99], v[98:99], v[102:103] neg_lo:[0,1] neg_hi:[0,1]
	v_pk_add_f32 v[70:71], v[66:67], v[82:83] op_sel:[0,1] op_sel_hi:[1,0] neg_hi:[0,1]
	v_pk_add_f32 v[66:67], v[66:67], v[82:83] op_sel:[0,1] op_sel_hi:[1,0] neg_lo:[0,1]
	v_pk_add_f32 v[82:83], v[68:69], v[72:73]
	v_pk_add_f32 v[106:107], v[84:85], v[100:101]
	v_pk_add_f32 v[84:85], v[84:85], v[100:101] neg_lo:[0,1] neg_hi:[0,1]
	v_pk_add_f32 v[100:101], v[80:81], v[92:93]
	v_pk_mul_f32 v[2:3], v[2:3], v[88:89] op_sel:[0,1] op_sel_hi:[1,0]
	s_cselect_b32 s6, s65, s6
	v_xor_b32_e32 v103, 0x80000000, v98
	v_pk_add_f32 v[90:91], v[90:91], v[94:95] neg_lo:[0,1] neg_hi:[0,1]
	v_mov_b32_e32 v102, v99
	v_pk_add_f32 v[80:81], v[80:81], v[92:93] neg_lo:[0,1] neg_hi:[0,1]
	v_pk_add_f32 v[92:93], v[70:71], v[82:83]
	v_pk_fma_f32 v[2:3], v[4:5], v[88:89], v[2:3] op_sel_hi:[0,1,1]
	v_pk_mul_f32 v[4:5], v[12:13], v[100:101] op_sel:[0,1] op_sel_hi:[1,0]
	s_lshl_b32 s8, s6, 1
	s_lshl_b32 s6, s6, 2
	v_xor_b32_e32 v95, 0x80000000, v90
	v_pk_add_f32 v[68:69], v[68:69], v[72:73] neg_lo:[0,1] neg_hi:[0,1]
	v_pk_add_f32 v[98:99], v[96:97], v[102:103]
	v_mov_b32_e32 v94, v91
	v_pk_fma_f32 v[4:5], v[6:7], v[100:101], v[4:5] op_sel_hi:[0,1,1]
	v_pk_mul_f32 v[6:7], v[18:19], v[92:93] op_sel:[0,1] op_sel_hi:[1,0]
	s_and_b32 s7, s8, 0x3fe
	s_and_b32 s6, s6, 0xfffff800
	v_xor_b32_e32 v73, 0x80000000, v68
	v_pk_add_f32 v[90:91], v[74:75], v[94:95]
	v_mov_b32_e32 v72, v69
	v_pk_fma_f32 v[6:7], v[8:9], v[92:93], v[6:7] op_sel_hi:[0,1,1]
	v_pk_mul_f32 v[8:9], v[14:15], v[98:99] op_sel:[0,1] op_sel_hi:[1,0]
	s_or_b32 s6, s7, s6
	v_pk_add_f32 v[68:69], v[66:67], v[72:73]
	v_pk_fma_f32 v[8:9], v[10:11], v[98:99], v[8:9] op_sel_hi:[0,1,1]
	v_pk_mul_f32 v[10:11], v[20:21], v[90:91] op_sel:[0,1] op_sel_hi:[1,0]
	s_ashr_i32 s7, s6, 31
	v_pk_add_f32 v[96:97], v[96:97], v[102:103] neg_lo:[0,1] neg_hi:[0,1]
	v_pk_add_f32 v[76:77], v[104:105], v[76:77] neg_lo:[0,1] neg_hi:[0,1]
	v_pk_add_f32 v[74:75], v[74:75], v[94:95] neg_lo:[0,1] neg_hi:[0,1]
	v_pk_add_f32 v[70:71], v[70:71], v[82:83] neg_lo:[0,1] neg_hi:[0,1]
	v_pk_add_f32 v[66:67], v[66:67], v[72:73] neg_lo:[0,1] neg_hi:[0,1]
	v_pk_fma_f32 v[10:11], v[16:17], v[90:91], v[10:11] op_sel_hi:[0,1,1]
	v_pk_mul_f32 v[12:13], v[24:25], v[78:79] op_sel:[0,1] op_sel_hi:[1,0]
	v_pk_mul_f32 v[14:15], v[28:29], v[68:69] op_sel:[0,1] op_sel_hi:[1,0]
	v_pk_mul_f32 v[16:17], v[32:33], v[84:85] op_sel:[0,1] op_sel_hi:[1,0]
	s_lshl_b64 s[82:83], s[6:7], 14
	s_bitset1_b32 s6, 10
	v_pk_fma_f32 v[12:13], v[22:23], v[78:79], v[12:13] op_sel_hi:[0,1,1]
	v_pk_fma_f32 v[14:15], v[26:27], v[68:69], v[14:15] op_sel_hi:[0,1,1]
	v_pk_fma_f32 v[16:17], v[30:31], v[84:85], v[16:17] op_sel_hi:[0,1,1]
	v_pk_mul_f32 v[18:19], v[40:41], v[76:77] op_sel:[0,1] op_sel_hi:[1,0]
	v_pk_mul_f32 v[20:21], v[44:45], v[80:81] op_sel:[0,1] op_sel_hi:[1,0]
	v_pk_mul_f32 v[22:23], v[48:49], v[70:71] op_sel:[0,1] op_sel_hi:[1,0]
	v_pk_mul_f32 v[24:25], v[52:53], v[96:97] op_sel:[0,1] op_sel_hi:[1,0]
	v_pk_mul_f32 v[26:27], v[56:57], v[74:75] op_sel:[0,1] op_sel_hi:[1,0]
	v_pk_mul_f32 v[28:29], v[60:61], v[86:87] op_sel:[0,1] op_sel_hi:[1,0]
	v_pk_mul_f32 v[30:31], v[64:65], v[66:67] op_sel:[0,1] op_sel_hi:[1,0]
	s_ashr_i32 s7, s6, 31
	v_pk_fma_f32 v[18:19], v[38:39], v[76:77], v[18:19] op_sel_hi:[0,1,1]
	v_pk_fma_f32 v[20:21], v[42:43], v[80:81], v[20:21] op_sel_hi:[0,1,1]
	v_pk_fma_f32 v[22:23], v[46:47], v[70:71], v[22:23] op_sel_hi:[0,1,1]
	v_pk_fma_f32 v[24:25], v[50:51], v[96:97], v[24:25] op_sel_hi:[0,1,1]
	v_pk_fma_f32 v[26:27], v[54:55], v[74:75], v[26:27] op_sel_hi:[0,1,1]
	v_pk_fma_f32 v[28:29], v[58:59], v[86:87], v[28:29] op_sel_hi:[0,1,1]
	v_pk_fma_f32 v[30:31], v[62:63], v[66:67], v[30:31] op_sel_hi:[0,1,1]
	ds_write2_b64 v36, v[106:107], v[16:17] offset1:16
	ds_write2_b64 v36, v[8:9], v[24:25] offset0:33 offset1:49
	ds_write2_b64 v36, v[4:5], v[20:21] offset0:66 offset1:82
	ds_write2_b64 v36, v[12:13], v[28:29] offset0:99 offset1:115
	ds_write2_b64 v36, v[2:3], v[18:19] offset0:132 offset1:148
	ds_write2_b64 v36, v[10:11], v[26:27] offset0:165 offset1:181
	ds_write2_b64 v36, v[6:7], v[22:23] offset0:198 offset1:214
	ds_write2_b64 v36, v[14:15], v[30:31] offset0:231 offset1:247
	s_lshl_b64 s[6:7], s[6:7], 14
	v_lshl_add_u64 v[2:3], v[34:35], 0, s[82:83]
	s_waitcnt lgkmcnt(0)
	s_barrier
	global_load_dwordx4 v[10:13], v[2:3], off nt
	global_load_dwordx4 v[30:33], v[2:3], off offset:16 nt
	v_lshl_add_u64 v[2:3], v[34:35], 0, s[6:7]
	global_load_dwordx4 v[26:29], v[2:3], off nt
	global_load_dwordx4 v[22:25], v[2:3], off offset:16 nt
	v_mov_b32_e32 v38, 0
	s_and_saveexec_b64 s[6:7], s[0:1]
	s_cbranch_execz .LBB0_430
	global_load_ushort v38, v[2:3], off offset:32

.LBB0_432:
	s_or_b64 exec, exec, s[6:7]
	v_mov_b32_e32 v36, v130
	s_mov_b32 s75, s42
	v_ashrrev_i32_e32 v40, 31, v36
	v_add_u32_sdwa v40, v36, v40 dst_sel:DWORD dst_unused:UNUSED_PAD src0_sel:DWORD src1_sel:BYTE_3
	v_ashrrev_i32_e32 v40, 8, v40
	v_mul_i32_i24_e32 v41, 0x100, v40
	v_sub_u32_e32 v66, v36, v41
	v_lshlrev_b32_e32 v41, 1, v66
	v_bfrev_b32_e32 v41, v41
	v_lshrrev_b32_e32 v41, 23, v41
	v_sub_u32_e32 v41, 0x200, v41
	v_bfrev_b32_e32 v41, v41
	v_lshrrev_b32_e32 v41, 19, v41
	v_and_b32_e32 v41, 0x1ff0, v41
	v_cmp_eq_u32_e64 s[6:7], 0, v66
	v_lshlrev_b32_e32 v40, 13, v40
	v_lshl_add_u32 v42, v66, 5, v40
	v_cndmask_b32_e64 v41, v41, 16, s[6:7]
	v_or_b32_e32 v40, v41, v40
	v_lshlrev_b32_e32 v43, 3, v42
	v_ashrrev_i32_e32 v42, 2, v42
	v_ashrrev_i32_e32 v41, 5, v40
	v_add3_u32 v88, 0, v43, v42
	v_lshlrev_b32_e32 v40, 3, v40
	v_lshlrev_b32_e32 v41, 3, v41
	v_add_u32_e32 v36, 0xffffff00, v36
	v_add3_u32 v40, 0, v40, v41
	ds_read2_b64 v[42:45], v88 offset1:1
	ds_read2_b64 v[46:49], v88 offset0:2 offset1:3
	ds_read2_b64 v[72:75], v40 offset1:1
	ds_read2_b64 v[76:79], v40 offset0:2 offset1:3
	ds_read2_b64 v[50:53], v88 offset0:4 offset1:5
	ds_read2_b64 v[54:57], v88 offset0:6 offset1:7
	ds_read2_b64 v[80:83], v40 offset0:4 offset1:5
	ds_read2_b64 v[84:87], v40 offset0:6 offset1:7
	ds_read2_b64 v[58:61], v88 offset0:8 offset1:9
	ds_read2_b64 v[62:65], v88 offset0:10 offset1:11
	ds_read2_b64 v[96:99], v40 offset0:8 offset1:9
	ds_read2_b64 v[100:103], v40 offset0:10 offset1:11
	ds_read2_b64 v[68:71], v88 offset0:12 offset1:13
	ds_read2_b64 v[88:91], v88 offset0:14 offset1:15
	ds_read2_b64 v[104:107], v40 offset0:12 offset1:13
	ds_read2_b64 v[108:111], v40 offset0:14 offset1:15
	v_mov_b32_e32 v40, s16
	v_cmp_gt_u32_e64 s[8:9], s33, v36
	s_waitcnt lgkmcnt(7)
	v_pk_add_f32 v[92:93], v[42:43], v[58:59]
	v_pk_add_f32 v[42:43], v[42:43], v[58:59] neg_lo:[0,1] neg_hi:[0,1]
	v_pk_add_f32 v[58:59], v[44:45], v[60:61]
	v_pk_add_f32 v[44:45], v[44:45], v[60:61] neg_lo:[0,1] neg_hi:[0,1]
	v_addc_co_u32_e64 v40, s[8:9], 0, v40, s[8:9]
	v_pk_mul_f32 v[60:61], v[44:45], s[44:45]
	s_waitcnt lgkmcnt(3)
	v_pk_add_f32 v[94:95], v[52:53], v[70:71]
	v_pk_add_f32 v[52:53], v[52:53], v[70:71] neg_lo:[0,1] neg_hi:[0,1]
	v_pk_fma_f32 v[44:45], v[44:45], s[42:43], v[60:61] op_sel:[0,0,1] op_sel_hi:[1,0,0]
	v_pk_add_f32 v[60:61], v[46:47], v[62:63]
	v_pk_add_f32 v[46:47], v[46:47], v[62:63] neg_lo:[0,1] neg_hi:[0,1]
	s_mov_b32 s67, s64
	s_mov_b32 s8, s45
	v_pk_mul_f32 v[70:71], v[52:53], s[74:75]
	v_pk_mul_f32 v[62:63], v[46:47], s[66:67]
	v_pk_fma_f32 v[52:53], v[52:53], s[8:9], v[70:71] op_sel:[0,0,1] op_sel_hi:[1,0,0] neg_lo:[1,0,0] neg_hi:[1,0,0]
	s_waitcnt lgkmcnt(2)
	v_pk_add_f32 v[70:71], v[54:55], v[88:89]
	v_pk_add_f32 v[54:55], v[54:55], v[88:89] neg_lo:[0,1] neg_hi:[0,1]
	v_pk_fma_f32 v[46:47], v[46:47], s[64:65], v[62:63] op_sel:[0,0,1] op_sel_hi:[1,0,0]
	v_pk_add_f32 v[62:63], v[48:49], v[64:65]
	v_pk_add_f32 v[48:49], v[48:49], v[64:65] neg_lo:[0,1] neg_hi:[0,1]
	v_pk_mul_f32 v[88:89], v[54:55], s[66:67]
	v_pk_mul_f32 v[64:65], v[48:49], s[74:75]
	v_pk_fma_f32 v[54:55], v[54:55], s[64:65], v[88:89] op_sel:[0,0,1] op_sel_hi:[1,0,0] neg_lo:[1,0,0] neg_hi:[1,0,0]
	v_pk_add_f32 v[88:89], v[56:57], v[90:91]
	v_pk_add_f32 v[56:57], v[56:57], v[90:91] neg_lo:[0,1] neg_hi:[0,1]
	v_pk_fma_f32 v[48:49], v[48:49], s[8:9], v[64:65] op_sel:[0,0,1] op_sel_hi:[1,0,0]
	v_pk_add_f32 v[64:65], v[50:51], v[68:69]
	v_pk_add_f32 v[50:51], v[50:51], v[68:69] neg_lo:[0,1] neg_hi:[0,1]
	v_pk_mul_f32 v[90:91], v[56:57], s[44:45]
	v_pk_add_f32 v[112:113], v[62:63], v[88:89]
	v_pk_add_f32 v[62:63], v[62:63], v[88:89] neg_lo:[0,1] neg_hi:[0,1]
	v_xor_b32_e32 v69, 0x80000000, v50
	v_pk_fma_f32 v[56:57], v[56:57], s[42:43], v[90:91] op_sel:[0,0,1] op_sel_hi:[1,0,0] neg_lo:[1,0,0] neg_hi:[1,0,0]
	v_pk_add_f32 v[90:91], v[92:93], v[64:65]
	v_pk_add_f32 v[64:65], v[92:93], v[64:65] neg_lo:[0,1] neg_hi:[0,1]
	v_pk_add_f32 v[92:93], v[58:59], v[94:95]
	v_pk_add_f32 v[58:59], v[58:59], v[94:95] neg_lo:[0,1] neg_hi:[0,1]
	v_pk_mul_f32 v[88:89], v[62:63], s[66:67]
	v_mov_b32_e32 v68, v51
	v_pk_mul_f32 v[94:95], v[58:59], s[66:67]
	v_pk_fma_f32 v[62:63], v[62:63], s[64:65], v[88:89] op_sel:[0,0,1] op_sel_hi:[1,0,0] neg_lo:[1,0,0] neg_hi:[1,0,0]
	v_pk_add_f32 v[50:51], v[42:43], v[68:69]
	v_pk_add_f32 v[42:43], v[42:43], v[68:69] neg_lo:[0,1] neg_hi:[0,1]
	v_pk_add_f32 v[68:69], v[44:45], v[52:53]
	v_pk_add_f32 v[44:45], v[44:45], v[52:53] neg_lo:[0,1] neg_hi:[0,1]
	v_pk_add_f32 v[88:89], v[48:49], v[56:57]
	v_pk_add_f32 v[48:49], v[48:49], v[56:57] neg_lo:[0,1] neg_hi:[0,1]
	v_pk_fma_f32 v[58:59], v[58:59], s[64:65], v[94:95] op_sel:[0,0,1] op_sel_hi:[1,0,0]
	v_pk_add_f32 v[94:95], v[60:61], v[70:71]
	v_pk_mul_f32 v[52:53], v[44:45], s[66:67]
	v_pk_mul_f32 v[56:57], v[48:49], s[66:67]
	v_pk_fma_f32 v[44:45], v[44:45], s[64:65], v[52:53] op_sel:[0,0,1] op_sel_hi:[1,0,0]
	v_pk_add_f32 v[52:53], v[46:47], v[54:55]
	v_pk_fma_f32 v[48:49], v[48:49], s[64:65], v[56:57] op_sel:[0,0,1] op_sel_hi:[1,0,0] neg_lo:[1,0,0] neg_hi:[1,0,0]
	v_pk_add_f32 v[56:57], v[90:91], v[94:95]
	v_pk_add_f32 v[114:115], v[90:91], v[94:95] neg_lo:[0,1] neg_hi:[0,1]
	v_pk_add_f32 v[90:91], v[92:93], v[112:113]
	v_pk_add_f32 v[112:113], v[92:93], v[112:113] neg_lo:[0,1] neg_hi:[0,1]
	v_pk_add_f32 v[122:123], v[50:51], v[52:53]
	v_pk_add_f32 v[50:51], v[50:51], v[52:53] neg_lo:[0,1] neg_hi:[0,1]
	v_pk_add_f32 v[52:53], v[68:69], v[88:89]
	v_pk_add_f32 v[88:89], v[68:69], v[88:89] neg_lo:[0,1] neg_hi:[0,1]
	v_pk_add_f32 v[92:93], v[74:75], v[98:99]
	v_pk_add_f32 v[74:75], v[74:75], v[98:99] neg_lo:[0,1] neg_hi:[0,1]
	v_xor_b32_e32 v125, 0x80000000, v88
	v_mov_b32_e32 v124, v89
	v_pk_add_f32 v[88:89], v[72:73], v[96:97]
	v_pk_add_f32 v[72:73], v[72:73], v[96:97] neg_lo:[0,1] neg_hi:[0,1]
	v_pk_mul_f32 v[96:97], v[74:75], s[44:45]
	v_bfrev_b32_e32 v36, v66
	v_pk_fma_f32 v[74:75], v[74:75], s[42:43], v[96:97] op_sel:[0,0,1] op_sel_hi:[1,0,0]
	v_pk_add_f32 v[96:97], v[76:77], v[100:101]
	v_pk_add_f32 v[76:77], v[76:77], v[100:101] neg_lo:[0,1] neg_hi:[0,1]
	v_ashrrev_i32_e32 v41, 31, v40
	v_pk_mul_f32 v[98:99], v[76:77], s[66:67]
	v_cvt_f32_ubyte3_e32 v36, v36
	v_pk_fma_f32 v[76:77], v[76:77], s[64:65], v[98:99] op_sel:[0,0,1] op_sel_hi:[1,0,0]
	v_pk_add_f32 v[98:99], v[78:79], v[102:103]
	v_pk_add_f32 v[78:79], v[78:79], v[102:103] neg_lo:[0,1] neg_hi:[0,1]
	v_lshlrev_b64 v[40:41], 15, v[40:41]
	v_pk_mul_f32 v[100:101], v[78:79], s[74:75]
	v_mul_f32_e32 v36, 0x38800000, v36
	v_pk_fma_f32 v[78:79], v[78:79], s[8:9], v[100:101] op_sel:[0,0,1] op_sel_hi:[1,0,0]
	s_waitcnt lgkmcnt(1)
	v_pk_add_f32 v[100:101], v[80:81], v[104:105]
	v_pk_add_f32 v[102:103], v[80:81], v[104:105] neg_lo:[0,1] neg_hi:[0,1]
	v_ashrrev_i32_e32 v67, 31, v66
	v_pk_add_f32 v[80:81], v[82:83], v[106:107]
	v_pk_add_f32 v[82:83], v[82:83], v[106:107] neg_lo:[0,1] neg_hi:[0,1]
	v_lshl_add_u64 v[40:41], s[18:19], 0, v[40:41]
	v_pk_mul_f32 v[104:105], v[82:83], s[74:75]
	v_pk_add_f32 v[60:61], v[60:61], v[70:71] neg_lo:[0,1] neg_hi:[0,1]
	v_pk_fma_f32 v[82:83], v[82:83], s[8:9], v[104:105] op_sel:[0,0,1] op_sel_hi:[1,0,0] neg_lo:[1,0,0] neg_hi:[1,0,0]
	s_waitcnt lgkmcnt(0)
	v_pk_add_f32 v[104:105], v[84:85], v[108:109]
	v_pk_add_f32 v[84:85], v[84:85], v[108:109] neg_lo:[0,1] neg_hi:[0,1]
	v_cndmask_b32_e64 v36, v36, v152, s[6:7]
	v_pk_mul_f32 v[106:107], v[84:85], s[66:67]
	v_lshl_add_u64 v[40:41], v[66:67], 3, v[40:41]
	v_pk_fma_f32 v[84:85], v[84:85], s[64:65], v[106:107] op_sel:[0,0,1] op_sel_hi:[1,0,0] neg_lo:[1,0,0] neg_hi:[1,0,0]
	v_pk_add_f32 v[106:107], v[86:87], v[110:111]
	v_pk_add_f32 v[86:87], v[86:87], v[110:111] neg_lo:[0,1] neg_hi:[0,1]
	v_xor_b32_e32 v71, 0x80000000, v60
	v_pk_mul_f32 v[108:109], v[86:87], s[44:45]
	v_pk_add_f32 v[46:47], v[46:47], v[54:55] neg_lo:[0,1] neg_hi:[0,1]
	v_pk_fma_f32 v[86:87], v[86:87], s[42:43], v[108:109] op_sel:[0,0,1] op_sel_hi:[1,0,0] neg_lo:[1,0,0] neg_hi:[1,0,0]
	v_pk_add_f32 v[108:109], v[88:89], v[100:101]
	v_pk_add_f32 v[88:89], v[88:89], v[100:101] neg_lo:[0,1] neg_hi:[0,1]
	v_pk_add_f32 v[100:101], v[92:93], v[80:81]
	v_pk_add_f32 v[80:81], v[92:93], v[80:81] neg_lo:[0,1] neg_hi:[0,1]
	v_mov_b32_e32 v70, v61
	v_pk_mul_f32 v[92:93], v[80:81], s[66:67]
	v_pk_add_f32 v[118:119], v[58:59], v[62:63]
	v_pk_fma_f32 v[80:81], v[80:81], s[64:65], v[92:93] op_sel:[0,0,1] op_sel_hi:[1,0,0]
	v_pk_add_f32 v[92:93], v[96:97], v[104:105]
	v_pk_add_f32 v[104:105], v[96:97], v[104:105] neg_lo:[0,1] neg_hi:[0,1]
	v_pk_add_f32 v[120:121], v[58:59], v[62:63] neg_lo:[0,1] neg_hi:[0,1]
	v_pk_add_f32 v[96:97], v[98:99], v[106:107]
	v_pk_add_f32 v[98:99], v[98:99], v[106:107] neg_lo:[0,1] neg_hi:[0,1]
	v_cos_f32_e32 v67, v36
	v_pk_mul_f32 v[106:107], v[98:99], s[66:67]
	v_cmp_ne_u32_e32 vcc, 0, v66
	v_pk_fma_f32 v[98:99], v[98:99], s[64:65], v[106:107] op_sel:[0,0,1] op_sel_hi:[1,0,0] neg_lo:[1,0,0] neg_hi:[1,0,0]
	v_pk_add_f32 v[106:107], v[72:73], v[102:103] op_sel:[0,1] op_sel_hi:[1,0] neg_hi:[0,1]
	v_pk_add_f32 v[72:73], v[72:73], v[102:103] op_sel:[0,1] op_sel_hi:[1,0] neg_lo:[0,1]
	v_pk_add_f32 v[102:103], v[74:75], v[82:83]
	v_pk_add_f32 v[74:75], v[74:75], v[82:83] neg_lo:[0,1] neg_hi:[0,1]
	v_xor_b32_e32 v55, 0x80000000, v46
	v_pk_mul_f32 v[82:83], v[74:75], s[66:67]
	v_pk_add_f32 v[116:117], v[64:65], v[70:71] neg_lo:[0,1] neg_hi:[0,1]
	v_pk_fma_f32 v[74:75], v[74:75], s[64:65], v[82:83] op_sel:[0,0,1] op_sel_hi:[1,0,0]
	v_pk_add_f32 v[82:83], v[76:77], v[84:85]
	v_pk_add_f32 v[84:85], v[76:77], v[84:85] neg_lo:[0,1] neg_hi:[0,1]
	v_pk_add_f32 v[76:77], v[78:79], v[86:87]
	v_pk_add_f32 v[78:79], v[78:79], v[86:87] neg_lo:[0,1] neg_hi:[0,1]
	v_mov_b32_e32 v54, v47
	v_pk_mul_f32 v[86:87], v[78:79], s[66:67]
	s_nop 0
	v_pk_fma_f32 v[78:79], v[78:79], s[64:65], v[86:87] op_sel:[0,0,1] op_sel_hi:[1,0,0] neg_lo:[1,0,0] neg_hi:[1,0,0]
	v_pk_add_f32 v[86:87], v[108:109], v[92:93]
	v_pk_add_f32 v[92:93], v[108:109], v[92:93] neg_lo:[0,1] neg_hi:[0,1]
	v_pk_add_f32 v[108:109], v[100:101], v[96:97]
	v_pk_add_f32 v[96:97], v[100:101], v[96:97] neg_lo:[0,1] neg_hi:[0,1]
	v_sin_f32_e32 v66, v36
	v_pk_add_f32 v[60:61], v[64:65], v[70:71]
	v_pk_add_f32 v[126:127], v[42:43], v[54:55]
	v_pk_add_f32 v[128:129], v[42:43], v[54:55] neg_lo:[0,1] neg_hi:[0,1]
	v_pk_add_f32 v[42:43], v[44:45], v[48:49]
	v_pk_add_f32 v[48:49], v[44:45], v[48:49] neg_lo:[0,1] neg_hi:[0,1]
	v_pk_add_f32 v[94:95], v[56:57], v[90:91]
	v_pk_add_f32 v[90:91], v[56:57], v[90:91] neg_lo:[0,1] neg_hi:[0,1]
	v_pk_add_f32 v[70:71], v[114:115], v[112:113] op_sel:[0,1] op_sel_hi:[1,0] neg_hi:[0,1]
	v_pk_add_f32 v[64:65], v[114:115], v[112:113] op_sel:[0,1] op_sel_hi:[1,0] neg_lo:[0,1]
	v_pk_add_f32 v[56:57], v[116:117], v[120:121] op_sel:[0,1] op_sel_hi:[1,0] neg_hi:[0,1]
	v_pk_add_f32 v[62:63], v[116:117], v[120:121] op_sel:[0,1] op_sel_hi:[1,0] neg_lo:[0,1]
	v_xor_b32_e32 v101, 0x80000000, v96
	v_mov_b32_e32 v100, v97
	v_pk_add_f32 v[96:97], v[88:89], v[104:105] op_sel:[0,1] op_sel_hi:[1,0] neg_hi:[0,1]
	v_pk_add_f32 v[88:89], v[88:89], v[104:105] op_sel:[0,1] op_sel_hi:[1,0] neg_lo:[0,1]
	v_pk_add_f32 v[104:105], v[80:81], v[98:99]
	v_pk_add_f32 v[98:99], v[80:81], v[98:99] neg_lo:[0,1] neg_hi:[0,1]
	v_pk_add_f32 v[112:113], v[102:103], v[76:77]
	v_pk_add_f32 v[102:103], v[102:103], v[76:77] neg_lo:[0,1] neg_hi:[0,1]
	v_pk_add_f32 v[114:115], v[72:73], v[84:85] op_sel:[0,1] op_sel_hi:[1,0] neg_hi:[0,1]
	v_pk_add_f32 v[116:117], v[72:73], v[84:85] op_sel:[0,1] op_sel_hi:[1,0] neg_lo:[0,1]
	v_pk_add_f32 v[72:73], v[74:75], v[78:79] neg_lo:[0,1] neg_hi:[0,1]
	v_xor_b32_e32 v155, 0x80000000, v48
	v_pk_add_f32 v[68:69], v[60:61], v[118:119]
	v_pk_add_f32 v[58:59], v[60:61], v[118:119] neg_lo:[0,1] neg_hi:[0,1]
	v_mov_b32_e32 v154, v49
	v_pk_add_f32 v[110:111], v[106:107], v[82:83]
	v_pk_add_f32 v[106:107], v[106:107], v[82:83] neg_lo:[0,1] neg_hi:[0,1]
	v_pk_add_f32 v[118:119], v[74:75], v[78:79]
	v_xor_b32_e32 v121, 0x80000000, v72
	v_mov_b32_e32 v120, v73
	v_pk_add_f32 v[60:61], v[122:123], v[52:53]
	v_pk_add_f32 v[46:47], v[122:123], v[52:53] neg_lo:[0,1] neg_hi:[0,1]
	v_pk_add_f32 v[52:53], v[50:51], v[124:125]
	v_pk_add_f32 v[54:55], v[50:51], v[124:125] neg_lo:[0,1] neg_hi:[0,1]
	v_pk_add_f32 v[50:51], v[126:127], v[42:43]
	v_pk_add_f32 v[44:45], v[126:127], v[42:43] neg_lo:[0,1] neg_hi:[0,1]
	v_pk_add_f32 v[42:43], v[128:129], v[154:155]
	v_pk_add_f32 v[48:49], v[128:129], v[154:155] neg_lo:[0,1] neg_hi:[0,1]
	v_pk_add_f32 v[84:85], v[86:87], v[108:109]
	v_pk_add_f32 v[86:87], v[86:87], v[108:109] neg_lo:[0,1] neg_hi:[0,1]
	v_pk_add_f32 v[78:79], v[92:93], v[100:101]
	v_pk_add_f32 v[74:75], v[92:93], v[100:101] neg_lo:[0,1] neg_hi:[0,1]
	v_pk_add_f32 v[72:73], v[96:97], v[104:105]
	v_pk_add_f32 v[76:77], v[96:97], v[104:105] neg_lo:[0,1] neg_hi:[0,1]
	v_pk_add_f32 v[82:83], v[88:89], v[98:99] op_sel:[0,1] op_sel_hi:[1,0] neg_hi:[0,1]
	v_pk_add_f32 v[80:81], v[88:89], v[98:99] op_sel:[0,1] op_sel_hi:[1,0] neg_lo:[0,1]
	v_pk_add_f32 v[88:89], v[110:111], v[112:113]
	v_pk_add_f32 v[96:97], v[110:111], v[112:113] neg_lo:[0,1] neg_hi:[0,1]
	v_pk_add_f32 v[98:99], v[106:107], v[102:103] op_sel:[0,1] op_sel_hi:[1,0] neg_hi:[0,1]
	v_pk_add_f32 v[102:103], v[106:107], v[102:103] op_sel:[0,1] op_sel_hi:[1,0] neg_lo:[0,1]
	v_pk_add_f32 v[104:105], v[114:115], v[118:119]
	v_pk_add_f32 v[106:107], v[114:115], v[118:119] neg_lo:[0,1] neg_hi:[0,1]
	v_pk_add_f32 v[108:109], v[116:117], v[120:121]
	v_pk_add_f32 v[114:115], v[116:117], v[120:121] neg_lo:[0,1] neg_hi:[0,1]
	v_mul_f32_e32 v36, 0x3f3504f3, v67
	v_mul_f32_e32 v100, 0xbec3ef15, v67
	v_mul_f32_e32 v92, 0xbf6c835e, v67
	s_and_saveexec_b64 s[6:7], vcc
	s_xor_b64 s[6:7], exec, s[6:7]
	s_cbranch_execz .LBB0_434
	v_pk_add_f32 v[110:111], v[94:95], v[114:115]
	v_pk_add_f32 v[94:95], v[94:95], v[114:115] neg_lo:[0,1] neg_hi:[0,1]
	v_mul_f32_e32 v112, 0.5, v110
	v_pk_fma_f32 v[114:115], v[66:67], 0, v[66:67] op_sel:[0,0,1] op_sel_hi:[1,0,0] neg_lo:[1,0,0]
	v_mov_b32_e32 v110, v94
	v_pk_mul_f32 v[110:111], v[110:111], s[78:79]
	s_mov_b32 s8, s45
	v_pk_mul_f32 v[116:117], v[114:115], v[110:111] op_sel:[0,1] op_sel_hi:[1,0]
	v_pk_mul_f32 v[110:111], v[114:115], v[110:111]
	s_mov_b32 s9, s42
	v_sub_f32_e32 v93, v110, v111
	v_fma_mixlo_f16 v101, v95, s79, v93
	v_fma_f32 v93, v95, 0.5, -v93
	v_cvt_f16_f32_sdwa v93, -v93 dst_sel:WORD_1 dst_unused:UNUSED_PAD src0_sel:DWORD
	v_pk_add_f32 v[94:95], v[116:117], v[116:117] op_sel:[0,1] op_sel_hi:[0,1]
	v_pk_add_f32 v[110:111], v[112:113], v[94:95]
	v_pk_add_f32 v[94:95], v[112:113], v[94:95] op_sel_hi:[0,1] neg_lo:[0,1] neg_hi:[0,1]
	v_cvt_pk_f16_f32 v94, v110, v95
	v_lshlrev_b32_e32 v101, 16, v101
	v_or_b32_sdwa v95, v93, v94 dst_sel:DWORD dst_unused:UNUSED_PAD src0_sel:DWORD src1_sel:WORD_1
	v_or_b32_sdwa v94, v101, v94 dst_sel:DWORD dst_unused:UNUSED_PAD src0_sel:DWORD src1_sel:WORD_0
	global_store_dwordx2 v[40:41], v[94:95], off
	v_pk_add_f32 v[94:95], v[90:91], v[108:109]
	v_pk_add_f32 v[90:91], v[90:91], v[108:109] neg_lo:[0,1] neg_hi:[0,1]
	v_mul_f32_e32 v110, 0.5, v94
	v_mov_b32_e32 v94, v67
	v_mov_b32_e32 v108, v67
	v_mov_b32_e32 v109, v66
	v_pk_fma_f32 v[112:113], v[66:67], 0, v[108:109] op_sel_hi:[1,0,1] neg_lo:[0,0,1] neg_hi:[0,0,1]
	v_pk_fma_f32 v[114:115], v[66:67], 0, v[94:95] op_sel_hi:[1,0,1]
	v_mov_b32_e32 v94, v90
	v_pk_mov_b32 v[112:113], v[112:113], v[114:115] op_sel:[1,0]
	v_pk_mul_f32 v[94:95], v[94:95], s[78:79]
	s_mov_b32 s43, s45
	v_pk_mul_f32 v[114:115], v[112:113], v[94:95] op_sel:[0,1] op_sel_hi:[1,0]
	v_pk_mul_f32 v[94:95], v[112:113], v[94:95]
	v_pk_fma_f32 v[112:113], v[108:109], s[68:69], v[36:37] op_sel_hi:[1,1,0]
	v_sub_f32_e32 v90, v94, v95
	v_fma_mixlo_f16 v93, v91, s79, v90
	v_fma_f32 v90, v91, 0.5, -v90
	v_cvt_f16_f32_sdwa v101, -v90 dst_sel:WORD_1 dst_unused:UNUSED_PAD src0_sel:DWORD
	v_pk_add_f32 v[90:91], v[114:115], v[114:115] op_sel:[0,1] op_sel_hi:[0,1]
	v_pk_add_f32 v[94:95], v[110:111], v[90:91]
	v_pk_add_f32 v[90:91], v[110:111], v[90:91] op_sel_hi:[0,1] neg_lo:[0,1] neg_hi:[0,1]
	v_cvt_pk_f16_f32 v90, v94, v91
	v_lshlrev_b32_e32 v93, 16, v93
	v_or_b32_sdwa v91, v101, v90 dst_sel:DWORD dst_unused:UNUSED_PAD src0_sel:DWORD src1_sel:WORD_1
	v_or_b32_sdwa v90, v93, v90 dst_sel:DWORD dst_unused:UNUSED_PAD src0_sel:DWORD src1_sel:WORD_0
	global_store_dwordx2 v[40:41], v[90:91], off offset:2048
	v_pk_mul_f32 v[90:91], v[108:109], s[68:69]
	v_pk_add_f32 v[94:95], v[70:71], v[106:107]
	v_pk_add_f32 v[70:71], v[70:71], v[106:107] neg_lo:[0,1] neg_hi:[0,1]
	v_mul_f32_e32 v110, 0.5, v94
	v_pk_add_f32 v[106:107], v[36:37], v[90:91] op_sel:[0,1] op_sel_hi:[0,1] neg_lo:[0,1] neg_hi:[0,1]
	v_mov_b32_e32 v94, v70
	v_mov_b32_e32 v107, v113
	v_pk_mul_f32 v[94:95], v[94:95], s[78:79]
	v_mov_b32_e32 v101, v58
	v_pk_mul_f32 v[112:113], v[106:107], v[94:95] op_sel:[0,1] op_sel_hi:[1,0]
	v_pk_mul_f32 v[94:95], v[106:107], v[94:95]
	s_mov_b32 s39, s27
	v_sub_f32_e32 v36, v94, v95
	v_fma_mixlo_f16 v93, v71, s79, v36
	v_fma_f32 v36, v71, 0.5, -v36
	v_pk_add_f32 v[70:71], v[112:113], v[112:113] op_sel:[0,1] op_sel_hi:[0,1]
	v_cvt_f16_f32_sdwa v36, -v36 dst_sel:WORD_1 dst_unused:UNUSED_PAD src0_sel:DWORD
	v_pk_add_f32 v[94:95], v[110:111], v[70:71]
	v_pk_add_f32 v[70:71], v[110:111], v[70:71] op_sel_hi:[0,1] neg_lo:[0,1] neg_hi:[0,1]
	v_cvt_pk_f16_f32 v70, v94, v71
	v_add_co_u32_e32 v94, vcc, s34, v40
	v_lshlrev_b32_e32 v93, 16, v93
	s_nop 0
	v_addc_co_u32_e32 v95, vcc, 0, v41, vcc
	v_add_co_u32_e32 v110, vcc, s3, v40
	v_or_b32_sdwa v71, v36, v70 dst_sel:DWORD dst_unused:UNUSED_PAD src0_sel:DWORD src1_sel:WORD_1
	v_or_b32_sdwa v70, v93, v70 dst_sel:DWORD dst_unused:UNUSED_PAD src0_sel:DWORD src1_sel:WORD_0
	v_addc_co_u32_e32 v111, vcc, 0, v41, vcc
	global_store_dwordx2 v[110:111], v[70:71], off offset:-4096
	v_pk_fma_f32 v[70:71], v[108:109], s[68:69], v[90:91] op_sel:[0,0,1] op_sel_hi:[1,1,0] neg_lo:[0,0,1] neg_hi:[0,0,1]
	v_pk_add_f32 v[90:91], v[64:65], v[104:105]
	v_pk_add_f32 v[64:65], v[64:65], v[104:105] neg_lo:[0,1] neg_hi:[0,1]
	v_mul_f32_e32 v36, 0.5, v90
	v_mov_b32_e32 v90, v64
	v_pk_mul_f32 v[90:91], v[90:91], s[78:79]
	v_mov_b32_e32 v71, v106
	v_mov_b32_e32 v107, v70
	v_pk_mul_f32 v[70:71], v[70:71], v[90:91]
	v_pk_mul_f32 v[104:105], v[106:107], v[90:91]
	v_sub_f32_e32 v64, v70, v71
	v_fma_mixlo_f16 v90, v65, s79, v64
	v_fma_f32 v64, v65, 0.5, -v64
	v_cvt_f16_f32_sdwa v91, -v64 dst_sel:WORD_1 dst_unused:UNUSED_PAD src0_sel:DWORD
	v_pk_add_f32 v[64:65], v[104:105], v[104:105] op_sel:[1,0] op_sel_hi:[1,0]
	s_nop 0
	v_pk_add_f32 v[70:71], v[36:37], v[64:65]
	v_pk_add_f32 v[64:65], v[36:37], v[64:65] op_sel_hi:[0,1] neg_lo:[0,1] neg_hi:[0,1]
	v_cvt_pk_f16_f32 v36, v70, v65
	v_lshlrev_b32_e32 v64, 16, v90
	v_or_b32_sdwa v65, v91, v36 dst_sel:DWORD dst_unused:UNUSED_PAD src0_sel:DWORD src1_sel:WORD_1
	v_or_b32_sdwa v64, v64, v36 dst_sel:DWORD dst_unused:UNUSED_PAD src0_sel:DWORD src1_sel:WORD_0
	global_store_dwordx2 v[94:95], v[64:65], off offset:2048
	v_mov_b32_e32 v64, v67
	v_pk_mul_f32 v[70:71], v[66:67], s[8:9] op_sel_hi:[0,1]
	v_pk_add_f32 v[90:91], v[68:69], v[102:103]
	v_pk_add_f32 v[68:69], v[68:69], v[102:103] neg_lo:[0,1] neg_hi:[0,1]
	v_mul_f32_e32 v36, 0.5, v90
	v_pk_fma_f32 v[94:95], v[64:65], s[42:43], v[70:71] op_sel_hi:[0,1,1] neg_lo:[0,0,1] neg_hi:[0,0,1]
	v_pk_fma_f32 v[102:103], v[64:65], s[42:43], v[70:71] op_sel_hi:[0,1,1]
	v_mov_b32_e32 v90, v68
	v_mov_b32_e32 v104, v94
	v_mov_b32_e32 v105, v103
	v_pk_mul_f32 v[90:91], v[90:91], s[78:79]
	s_mov_b32 s8, s27
	v_pk_mul_f32 v[106:107], v[104:105], v[90:91] op_sel:[0,1] op_sel_hi:[1,0]
	v_pk_mul_f32 v[90:91], v[104:105], v[90:91]
	s_mov_b32 s9, s38
	v_sub_f32_e32 v65, v90, v91
	v_fma_mixlo_f16 v93, v69, s79, v65
	v_fma_f32 v65, v69, 0.5, -v65
	v_cvt_f16_f32_sdwa v65, -v65 dst_sel:WORD_1 dst_unused:UNUSED_PAD src0_sel:DWORD
	v_pk_add_f32 v[68:69], v[106:107], v[106:107] op_sel:[0,1] op_sel_hi:[0,1]
	v_pk_add_f32 v[90:91], v[36:37], v[68:69]
	v_pk_add_f32 v[68:69], v[36:37], v[68:69] op_sel_hi:[0,1] neg_lo:[0,1] neg_hi:[0,1]
	v_cvt_pk_f16_f32 v36, v90, v69
	v_lshlrev_b32_e32 v68, 16, v93
	v_or_b32_sdwa v69, v65, v36 dst_sel:DWORD dst_unused:UNUSED_PAD src0_sel:DWORD src1_sel:WORD_1
	v_or_b32_sdwa v68, v68, v36 dst_sel:DWORD dst_unused:UNUSED_PAD src0_sel:DWORD src1_sel:WORD_0
	global_store_dwordx2 v[110:111], v[68:69], off
	v_pk_add_f32 v[68:69], v[58:59], v[98:99]
	v_sub_f32_e32 v65, v59, v99
	v_pk_mov_b32 v[58:59], v[70:71], v[98:99] op_sel:[1,0]
	v_mul_f32_e32 v36, 0.5, v69
	v_pk_add_f32 v[58:59], v[100:101], v[58:59] neg_lo:[0,1] neg_hi:[0,1]
	v_mul_f32_e32 v90, 0.5, v68
	v_pk_mul_f32 v[98:99], v[58:59], v[36:37]
	v_mov_b32_e32 v93, v62
	v_mul_f32_e32 v58, v58, v99
	v_fma_f32 v36, -v94, v36, v58
	v_fma_mixlo_f16 v69, v65, s79, v36
	v_fma_f32 v36, v65, 0.5, -v36
	v_pk_fma_f32 v[100:101], v[94:95], v[98:99], v[98:99] op_sel:[0,1,0] op_sel_hi:[1,0,1]
	v_cvt_f16_f32_sdwa v36, -v36 dst_sel:WORD_1 dst_unused:UNUSED_PAD src0_sel:DWORD
	v_pk_add_f32 v[58:59], v[90:91], v[100:101]
	v_lshlrev_b32_e32 v65, 16, v69
	v_fma_f32 v59, v68, 0.5, -v100
	v_cvt_pk_f16_f32 v58, v58, v59
	v_or_b32_sdwa v59, v36, v58 dst_sel:DWORD dst_unused:UNUSED_PAD src0_sel:DWORD src1_sel:WORD_1
	v_or_b32_sdwa v58, v65, v58 dst_sel:DWORD dst_unused:UNUSED_PAD src0_sel:DWORD src1_sel:WORD_0
	global_store_dwordx2 v[110:111], v[58:59], off offset:2048
	v_pk_add_f32 v[58:59], v[96:97], v[56:57]
	v_pk_add_f32 v[56:57], v[56:57], v[96:97] neg_lo:[0,1] neg_hi:[0,1]
	v_mul_f32_e32 v36, 0.5, v58
	v_mov_b32_e32 v58, v56
	v_pk_mov_b32 v[68:69], v[94:95], v[102:103] op_sel:[1,0]
	v_pk_mul_f32 v[58:59], v[58:59], s[78:79]
	s_nop 0
	v_pk_mul_f32 v[90:91], v[68:69], v[58:59] op_sel:[0,1] op_sel_hi:[1,0]
	v_pk_mul_f32 v[58:59], v[68:69], v[58:59]
	s_nop 0
	v_sub_f32_e32 v56, v58, v59
	v_fma_mixlo_f16 v65, v57, s79, v56
	v_fma_f32 v56, v57, 0.5, -v56
	v_cvt_f16_f32_sdwa v71, -v56 dst_sel:WORD_1 dst_unused:UNUSED_PAD src0_sel:DWORD
	v_pk_add_f32 v[56:57], v[90:91], v[90:91] op_sel:[0,1] op_sel_hi:[0,1]
	v_pk_add_f32 v[58:59], v[36:37], v[56:57]
	v_pk_add_f32 v[56:57], v[36:37], v[56:57] op_sel_hi:[0,1] neg_lo:[0,1] neg_hi:[0,1]
	v_cvt_pk_f16_f32 v36, v58, v57
	v_add_co_u32_e32 v58, vcc, s35, v40
	v_lshlrev_b32_e32 v56, 16, v65
	s_nop 0
	v_addc_co_u32_e32 v59, vcc, 0, v41, vcc
	v_add_co_u32_e32 v90, vcc, s37, v40
	v_or_b32_sdwa v57, v71, v36 dst_sel:DWORD dst_unused:UNUSED_PAD src0_sel:DWORD src1_sel:WORD_1
	v_or_b32_sdwa v56, v56, v36 dst_sel:DWORD dst_unused:UNUSED_PAD src0_sel:DWORD src1_sel:WORD_0
	v_addc_co_u32_e32 v91, vcc, 0, v41, vcc
	global_store_dwordx2 v[90:91], v[56:57], off offset:-4096
	v_pk_add_f32 v[56:57], v[88:89], v[62:63]
	v_mov_b32_e32 v71, v88
	v_sub_f32_e32 v65, v63, v89
	v_mul_f32_e32 v36, 0.5, v57
	v_pk_add_f32 v[62:63], v[92:93], v[70:71] neg_lo:[0,1] neg_hi:[0,1]
	v_mul_f32_e32 v94, 0.5, v56
	v_pk_mul_f32 v[70:71], v[62:63], v[36:37]
	s_nop 0
	v_mul_f32_e32 v57, v62, v71
	v_fma_f32 v36, -v95, v36, v57
	v_fma_mixlo_f16 v57, v65, s79, v36
	v_fma_f32 v36, v65, 0.5, -v36
	v_cvt_f16_f32_sdwa v36, -v36 dst_sel:WORD_1 dst_unused:UNUSED_PAD src0_sel:DWORD
	v_pk_fma_f32 v[68:69], v[68:69], v[70:71], v[70:71] op_sel:[0,1,0] op_sel_hi:[1,0,1]
	s_nop 0
	v_pk_add_f32 v[62:63], v[94:95], v[68:69]
	v_fma_f32 v56, v56, 0.5, -v68
	v_cvt_pk_f16_f32 v56, v62, v56
	v_lshlrev_b32_e32 v62, 16, v57
	v_or_b32_sdwa v57, v36, v56 dst_sel:DWORD dst_unused:UNUSED_PAD src0_sel:DWORD src1_sel:WORD_1
	v_or_b32_sdwa v56, v62, v56 dst_sel:DWORD dst_unused:UNUSED_PAD src0_sel:DWORD src1_sel:WORD_0
	global_store_dwordx2 v[58:59], v[56:57], off offset:2048
	v_pk_mul_f32 v[56:57], v[66:67], s[38:39] op_sel_hi:[0,1]
	v_pk_add_f32 v[58:59], v[60:61], v[80:81]
	v_pk_add_f32 v[60:61], v[60:61], v[80:81] neg_lo:[0,1] neg_hi:[0,1]
	v_mul_f32_e32 v36, 0.5, v58
	v_pk_fma_f32 v[62:63], v[64:65], s[8:9], v[56:57] op_sel_hi:[0,1,1] neg_lo:[0,0,1] neg_hi:[0,0,1]
	v_pk_fma_f32 v[68:69], v[64:65], s[8:9], v[56:57] op_sel_hi:[0,1,1]
	v_mov_b32_e32 v58, v60
	v_mov_b32_e32 v70, v62
	v_mov_b32_e32 v71, v69
	v_pk_mul_f32 v[58:59], v[58:59], s[78:79]
	s_mov_b32 s8, s47
	v_pk_mul_f32 v[80:81], v[70:71], v[58:59] op_sel:[0,1] op_sel_hi:[1,0]
	v_pk_mul_f32 v[58:59], v[70:71], v[58:59]
	s_mov_b32 s9, s46
	v_sub_f32_e32 v58, v58, v59
	v_fma_mixlo_f16 v65, v61, s79, v58
	v_fma_f32 v58, v61, 0.5, -v58
	v_cvt_f16_f32_sdwa v70, -v58 dst_sel:WORD_1 dst_unused:UNUSED_PAD src0_sel:DWORD
	v_pk_add_f32 v[58:59], v[80:81], v[80:81] op_sel:[0,1] op_sel_hi:[0,1]
	v_pk_add_f32 v[60:61], v[36:37], v[58:59]
	v_pk_add_f32 v[58:59], v[36:37], v[58:59] op_sel_hi:[0,1] neg_lo:[0,1] neg_hi:[0,1]
	v_cvt_pk_f16_f32 v36, v60, v59
	v_lshlrev_b32_e32 v58, 16, v65
	v_or_b32_sdwa v59, v70, v36 dst_sel:DWORD dst_unused:UNUSED_PAD src0_sel:DWORD src1_sel:WORD_1
	v_or_b32_sdwa v58, v58, v36 dst_sel:DWORD dst_unused:UNUSED_PAD src0_sel:DWORD src1_sel:WORD_0
	global_store_dwordx2 v[90:91], v[58:59], off
	v_mul_f32_e32 v58, 0xbe47c5c2, v67
	v_pk_add_f32 v[60:61], v[46:47], v[82:83]
	v_sub_f32_e32 v65, v47, v83
	v_mov_b32_e32 v59, v46
	v_pk_mov_b32 v[46:47], v[56:57], v[82:83] op_sel:[1,0]
	v_mul_f32_e32 v36, 0.5, v61
	v_pk_add_f32 v[46:47], v[58:59], v[46:47] neg_lo:[0,1] neg_hi:[0,1]
	v_mul_f32_e32 v70, 0.5, v60
	v_pk_mul_f32 v[58:59], v[46:47], v[36:37]
	s_nop 0
	v_mul_f32_e32 v46, v46, v59
	v_fma_f32 v36, -v62, v36, v46
	v_fma_mixlo_f16 v57, v65, s79, v36
	v_fma_f32 v36, v65, 0.5, -v36
	v_pk_fma_f32 v[80:81], v[62:63], v[58:59], v[58:59] op_sel:[0,1,0] op_sel_hi:[1,0,1]
	v_cvt_f16_f32_sdwa v36, -v36 dst_sel:WORD_1 dst_unused:UNUSED_PAD src0_sel:DWORD
	v_pk_add_f32 v[46:47], v[70:71], v[80:81]
	v_lshlrev_b32_e32 v57, 16, v57
	v_fma_f32 v47, v60, 0.5, -v80
	v_cvt_pk_f16_f32 v46, v46, v47
	v_or_b32_sdwa v47, v36, v46 dst_sel:DWORD dst_unused:UNUSED_PAD src0_sel:DWORD src1_sel:WORD_1
	v_or_b32_sdwa v46, v57, v46 dst_sel:DWORD dst_unused:UNUSED_PAD src0_sel:DWORD src1_sel:WORD_0
	global_store_dwordx2 v[90:91], v[46:47], off offset:2048
	v_pk_mul_f32 v[46:47], v[66:67], s[8:9] op_sel_hi:[0,1]
	v_pk_add_f32 v[58:59], v[76:77], v[52:53]
	v_pk_add_f32 v[52:53], v[52:53], v[76:77] neg_lo:[0,1] neg_hi:[0,1]
	v_mul_f32_e32 v36, 0.5, v58
	v_pk_fma_f32 v[60:61], v[64:65], s[46:47], v[46:47] op_sel_hi:[0,1,1] neg_lo:[0,0,1] neg_hi:[0,0,1]
	v_pk_fma_f32 v[64:65], v[64:65], s[46:47], v[46:47] op_sel_hi:[0,1,1]
	v_mov_b32_e32 v58, v52
	v_mov_b32_e32 v70, v60
	v_mov_b32_e32 v71, v65
	v_pk_mul_f32 v[58:59], v[58:59], s[78:79]
	s_nop 0
	v_pk_mul_f32 v[76:77], v[70:71], v[58:59] op_sel:[0,1] op_sel_hi:[1,0]
	v_pk_mul_f32 v[58:59], v[70:71], v[58:59]
	s_nop 0
	v_sub_f32_e32 v52, v58, v59
	v_fma_mixlo_f16 v57, v53, s79, v52
	v_fma_f32 v52, v53, 0.5, -v52
	v_cvt_f16_f32_sdwa v66, -v52 dst_sel:WORD_1 dst_unused:UNUSED_PAD src0_sel:DWORD
	v_pk_add_f32 v[52:53], v[76:77], v[76:77] op_sel:[0,1] op_sel_hi:[0,1]
	v_pk_add_f32 v[58:59], v[36:37], v[52:53]
	v_pk_add_f32 v[52:53], v[36:37], v[52:53] op_sel_hi:[0,1] neg_lo:[0,1] neg_hi:[0,1]
	v_cvt_pk_f16_f32 v36, v58, v53
	v_add_co_u32_e32 v58, vcc, s51, v40
	v_lshlrev_b32_e32 v52, 16, v57
	s_nop 0
	v_addc_co_u32_e32 v59, vcc, 0, v41, vcc
	v_add_co_u32_e32 v70, vcc, s60, v40
	v_or_b32_sdwa v53, v66, v36 dst_sel:DWORD dst_unused:UNUSED_PAD src0_sel:DWORD src1_sel:WORD_1
	v_or_b32_sdwa v52, v52, v36 dst_sel:DWORD dst_unused:UNUSED_PAD src0_sel:DWORD src1_sel:WORD_0
	v_addc_co_u32_e32 v71, vcc, 0, v41, vcc
	global_store_dwordx2 v[70:71], v[52:53], off offset:-4096
	v_mul_f32_e32 v52, 0xbf54db31, v67
	v_pk_add_f32 v[76:77], v[72:73], v[54:55]
	v_sub_f32_e32 v57, v55, v73
	v_mov_b32_e32 v53, v54
	v_pk_mov_b32 v[54:55], v[46:47], v[72:73] op_sel:[1,0]
	v_mul_f32_e32 v36, 0.5, v77
	v_pk_add_f32 v[52:53], v[52:53], v[54:55] neg_lo:[0,1] neg_hi:[0,1]
	v_mul_f32_e32 v66, 0.5, v76
	v_pk_mul_f32 v[54:55], v[52:53], v[36:37]
	s_nop 0
	v_mul_f32_e32 v47, v52, v55
	v_fma_f32 v36, -v60, v36, v47
	v_fma_mixlo_f16 v47, v57, s79, v36
	v_fma_f32 v36, v57, 0.5, -v36
	v_pk_fma_f32 v[72:73], v[60:61], v[54:55], v[54:55] op_sel:[0,1,0] op_sel_hi:[1,0,1]
	v_cvt_f16_f32_sdwa v36, -v36 dst_sel:WORD_1 dst_unused:UNUSED_PAD src0_sel:DWORD
	v_pk_add_f32 v[52:53], v[66:67], v[72:73]
	v_lshlrev_b32_e32 v47, 16, v47
	v_fma_f32 v53, v76, 0.5, -v72
	v_cvt_pk_f16_f32 v52, v52, v53
	v_or_b32_sdwa v53, v36, v52 dst_sel:DWORD dst_unused:UNUSED_PAD src0_sel:DWORD src1_sel:WORD_1
	v_or_b32_sdwa v52, v47, v52 dst_sel:DWORD dst_unused:UNUSED_PAD src0_sel:DWORD src1_sel:WORD_0
	global_store_dwordx2 v[58:59], v[52:53], off offset:2048
	v_pk_add_f32 v[52:53], v[74:75], v[50:51]
	v_pk_add_f32 v[50:51], v[50:51], v[74:75] neg_lo:[0,1] neg_hi:[0,1]
	v_mul_f32_e32 v36, 0.5, v52
	v_mov_b32_e32 v52, v50
	v_pk_mov_b32 v[54:55], v[60:61], v[64:65] op_sel:[1,0]
	v_pk_mul_f32 v[52:53], v[52:53], s[78:79]
	s_nop 0
	v_pk_mul_f32 v[58:59], v[54:55], v[52:53] op_sel:[0,1] op_sel_hi:[1,0]
	v_pk_mul_f32 v[52:53], v[54:55], v[52:53]
	s_nop 0
	v_sub_f32_e32 v47, v52, v53
	v_fma_mixlo_f16 v57, v51, s79, v47
	v_fma_f32 v47, v51, 0.5, -v47
	v_cvt_f16_f32_sdwa v47, -v47 dst_sel:WORD_1 dst_unused:UNUSED_PAD src0_sel:DWORD
	v_pk_add_f32 v[50:51], v[58:59], v[58:59] op_sel:[0,1] op_sel_hi:[0,1]
	v_pk_add_f32 v[52:53], v[36:37], v[50:51]
	v_pk_add_f32 v[50:51], v[36:37], v[50:51] op_sel_hi:[0,1] neg_lo:[0,1] neg_hi:[0,1]
	v_cvt_pk_f16_f32 v36, v52, v51
	v_lshlrev_b32_e32 v50, 16, v57
	v_or_b32_sdwa v51, v47, v36 dst_sel:DWORD dst_unused:UNUSED_PAD src0_sel:DWORD src1_sel:WORD_1
	v_or_b32_sdwa v50, v50, v36 dst_sel:DWORD dst_unused:UNUSED_PAD src0_sel:DWORD src1_sel:WORD_0
	global_store_dwordx2 v[70:71], v[50:51], off
	v_mul_f32_e32 v50, 0xbf0e39da, v67
	v_pk_add_f32 v[52:53], v[78:79], v[44:45]
	v_mov_b32_e32 v51, v44
	v_mov_b32_e32 v47, v78
	v_sub_f32_e32 v57, v45, v79
	v_mul_f32_e32 v36, 0.5, v53
	v_pk_add_f32 v[44:45], v[50:51], v[46:47] neg_lo:[0,1] neg_hi:[0,1]
	v_mul_f32_e32 v58, 0.5, v52
	v_pk_mul_f32 v[46:47], v[44:45], v[36:37]
	s_nop 0
	v_mul_f32_e32 v44, v44, v47
	v_fma_f32 v36, -v61, v36, v44
	v_pk_fma_f32 v[50:51], v[54:55], v[46:47], v[46:47] op_sel:[0,1,0] op_sel_hi:[1,0,1]
	v_fma_mixlo_f16 v46, v57, s79, v36
	v_fma_f32 v36, v57, 0.5, -v36
	v_cvt_f16_f32_sdwa v36, -v36 dst_sel:WORD_1 dst_unused:UNUSED_PAD src0_sel:DWORD
	v_pk_add_f32 v[44:45], v[58:59], v[50:51]
	v_lshlrev_b32_e32 v46, 16, v46
	v_fma_f32 v45, v52, 0.5, -v50
	v_cvt_pk_f16_f32 v44, v44, v45
	v_or_b32_sdwa v45, v36, v44 dst_sel:DWORD dst_unused:UNUSED_PAD src0_sel:DWORD src1_sel:WORD_1
	v_or_b32_sdwa v44, v46, v44 dst_sel:DWORD dst_unused:UNUSED_PAD src0_sel:DWORD src1_sel:WORD_0
	global_store_dwordx2 v[70:71], v[44:45], off offset:2048
	v_pk_add_f32 v[44:45], v[86:87], v[42:43]
	v_pk_add_f32 v[42:43], v[42:43], v[86:87] neg_lo:[0,1] neg_hi:[0,1]
	v_mul_f32_e32 v36, 0.5, v44
	v_mov_b32_e32 v44, v42
	v_pk_mov_b32 v[46:47], v[62:63], v[68:69] op_sel:[1,0]
	v_pk_mul_f32 v[44:45], v[44:45], s[78:79]
	s_nop 0
	v_pk_mul_f32 v[50:51], v[46:47], v[44:45] op_sel:[0,1] op_sel_hi:[1,0]
	v_pk_mul_f32 v[44:45], v[46:47], v[44:45]
	s_nop 0
	v_sub_f32_e32 v42, v44, v45
	v_fma_mixlo_f16 v46, v43, s79, v42
	v_fma_f32 v42, v43, 0.5, -v42
	v_cvt_f16_f32_sdwa v47, -v42 dst_sel:WORD_1 dst_unused:UNUSED_PAD src0_sel:DWORD
	v_pk_add_f32 v[42:43], v[50:51], v[50:51] op_sel:[0,1] op_sel_hi:[0,1]
	v_pk_add_f32 v[44:45], v[36:37], v[42:43]
	v_pk_add_f32 v[42:43], v[36:37], v[42:43] op_sel_hi:[0,1] neg_lo:[0,1] neg_hi:[0,1]
	v_cvt_pk_f16_f32 v36, v44, v43
	v_lshlrev_b32_e32 v42, 16, v46
	v_or_b32_sdwa v43, v47, v36 dst_sel:DWORD dst_unused:UNUSED_PAD src0_sel:DWORD src1_sel:WORD_1
	v_pk_add_f32 v[44:45], v[48:49], v[84:85]
	v_pk_add_f32 v[46:47], v[48:49], v[84:85] neg_lo:[0,1] neg_hi:[0,1]
	v_mov_b32_e32 v48, v44
	v_mov_b32_e32 v49, v47
	v_mov_b32_e32 v47, v45
	v_pk_mul_f32 v[44:45], v[46:47], s[78:79]
	v_or_b32_sdwa v42, v42, v36 dst_sel:DWORD dst_unused:UNUSED_PAD src0_sel:DWORD src1_sel:WORD_0
	v_fma_f32 v36, v67, s26, -v56
	v_pk_mul_f32 v[46:47], v[62:63], v[44:45] op_sel:[1,0]
	s_nop 0
	v_pk_fma_f32 v[50:51], v[36:37], v[44:45], v[46:47] op_sel:[0,1,0] op_sel_hi:[0,0,1] neg_hi:[0,0,1]
	s_nop 0
	v_pk_fma_f32 v[44:45], v[48:49], 0.5, v[50:51] op_sel_hi:[1,0,1]
	v_pk_fma_f32 v[112:113], v[48:49], 0.5, v[50:51] op_sel_hi:[1,0,1] neg_lo:[0,0,1] neg_hi:[0,0,1]
	v_cvt_f16_f32_e32 v36, v44
	v_cvt_f16_f32_sdwa v46, v45 dst_sel:WORD_1 dst_unused:UNUSED_PAD src0_sel:DWORD
	v_add_co_u32_e32 v44, vcc, s61, v40
	v_or_b32_e32 v110, v46, v36
	s_nop 0
	v_addc_co_u32_e32 v45, vcc, 0, v41, vcc
	global_store_dwordx2 v[44:45], v[42:43], off

.LBB0_499:
	v_mov_b32_e32 v2, v210
	s_mov_b32 s43, s8
	v_and_b32_e32 v3, 0x1ff, v2
	v_lshlrev_b32_e32 v2, 5, v2
	v_and_or_b32 v2, v2, s94, v3
	v_ashrrev_i32_e32 v4, 5, v2
	v_lshlrev_b32_e32 v2, 3, v2
	v_lshlrev_b32_e32 v4, 3, v4
	v_add3_u32 v18, 0, v2, v4
	ds_read_b64 v[128:129], v18
	ds_read_b64 v[134:135], v18 offset:4224
	ds_read_b64 v[136:137], v18 offset:8448
	ds_read_b64 v[138:139], v18 offset:12672
	ds_read_b64 v[140:141], v18 offset:16896
	ds_read_b64 v[142:143], v18 offset:21120
	ds_read_b64 v[132:133], v18 offset:25344
	ds_read_b64 v[130:131], v18 offset:29568
	ds_read_b64 v[144:145], v18 offset:33792
	ds_read_b64 v[148:149], v18 offset:38016
	ds_read_b64 v[150:151], v18 offset:42240
	ds_read_b64 v[152:153], v18 offset:46464
	s_waitcnt lgkmcnt(10)
	v_pk_mul_f32 v[162:163], v[134:135], s[10:11]
	s_mov_b32 s74, s11
	v_pk_fma_f32 v[162:163], v[134:135], s[8:9], v[162:163] op_sel:[0,0,1] op_sel_hi:[1,0,0]
	s_waitcnt lgkmcnt(2)
	v_pk_mul_f32 v[178:179], v[148:149], s[42:43]
	v_pk_add_f32 v[194:195], v[134:135], v[148:149]
	v_pk_add_f32 v[134:135], v[134:135], v[148:149] neg_lo:[0,1] neg_hi:[0,1]
	v_pk_mul_f32 v[164:165], v[136:137], s[18:19]
	s_mov_b32 s41, s16
	v_pk_fma_f32 v[178:179], v[148:149], s[74:75], v[178:179] op_sel:[0,0,1] op_sel_hi:[1,0,0] neg_lo:[1,0,0] neg_hi:[1,0,0]
	v_pk_mul_f32 v[148:149], v[134:135], s[18:19]
	v_pk_fma_f32 v[164:165], v[136:137], s[16:17], v[164:165] op_sel:[0,0,1] op_sel_hi:[1,0,0]
	s_mov_b32 s80, s19
	s_waitcnt lgkmcnt(1)
	v_pk_mul_f32 v[180:181], v[150:151], s[40:41]
	v_pk_fma_f32 v[134:135], v[134:135], s[16:17], v[148:149] op_sel:[0,0,1] op_sel_hi:[1,0,0]
	v_pk_add_f32 v[148:149], v[136:137], v[150:151]
	v_pk_add_f32 v[136:137], v[136:137], v[150:151] neg_lo:[0,1] neg_hi:[0,1]
	v_pk_mul_f32 v[166:167], v[138:139], s[26:27]
	s_mov_b32 s78, s37
	s_mov_b32 s39, s24
	v_pk_fma_f32 v[180:181], v[150:151], s[80:81], v[180:181] op_sel:[0,0,1] op_sel_hi:[1,0,0] neg_lo:[1,0,0] neg_hi:[1,0,0]
	v_pk_mul_f32 v[150:151], v[136:137], s[36:37]
	ds_read_b64 v[154:155], v18 offset:50688
	ds_read_b64 v[156:157], v18 offset:54912
	ds_read_b64 v[158:159], v18 offset:59136
	ds_read_b64 v[160:161], v18 offset:63360
	v_pk_fma_f32 v[166:167], v[138:139], s[24:25], v[166:167] op_sel:[0,0,1] op_sel_hi:[1,0,0]
	s_mov_b32 s0, s27
	s_waitcnt lgkmcnt(4)
	v_pk_mul_f32 v[182:183], v[152:153], s[38:39]
	v_pk_fma_f32 v[136:137], v[136:137], s[78:79], v[150:151] op_sel:[0,0,1] op_sel_hi:[1,0,0]
	v_pk_add_f32 v[150:151], v[138:139], v[152:153]
	v_pk_add_f32 v[138:139], v[138:139], v[152:153] neg_lo:[0,1] neg_hi:[0,1]
	v_pk_mul_f32 v[168:169], v[140:141], s[36:37]
	v_pk_fma_f32 v[182:183], v[152:153], s[0:1], v[182:183] op_sel:[0,0,1] op_sel_hi:[1,0,0] neg_lo:[1,0,0] neg_hi:[1,0,0]
	v_pk_mul_f32 v[152:153], v[138:139], s[40:41]
	v_pk_fma_f32 v[168:169], v[140:141], s[78:79], v[168:169] op_sel:[0,0,1] op_sel_hi:[1,0,0]
	v_pk_mul_f32 v[170:171], v[142:143], s[38:39]
	s_waitcnt lgkmcnt(3)
	v_pk_mul_f32 v[184:185], v[154:155], s[36:37]
	v_pk_fma_f32 v[138:139], v[138:139], s[80:81], v[152:153] op_sel:[0,0,1] op_sel_hi:[1,0,0]
	v_pk_add_f32 v[152:153], v[140:141], v[154:155]
	v_pk_add_f32 v[140:141], v[140:141], v[154:155] neg_lo:[0,1] neg_hi:[0,1]
	v_pk_fma_f32 v[170:171], v[142:143], s[0:1], v[170:171] op_sel:[0,0,1] op_sel_hi:[1,0,0]
	v_pk_fma_f32 v[184:185], v[154:155], s[78:79], v[184:185] op_sel:[0,0,1] op_sel_hi:[1,0,0] neg_lo:[1,0,0] neg_hi:[1,0,0]
	s_waitcnt lgkmcnt(2)
	v_pk_mul_f32 v[186:187], v[156:157], s[26:27]
	v_xor_b32_e32 v155, 0x80000000, v140
	v_mov_b32_e32 v154, v141
	v_pk_add_f32 v[140:141], v[142:143], v[156:157]
	v_pk_add_f32 v[142:143], v[142:143], v[156:157] neg_lo:[0,1] neg_hi:[0,1]
	v_pk_mul_f32 v[172:173], v[132:133], s[40:41]
	v_pk_fma_f32 v[186:187], v[156:157], s[24:25], v[186:187] op_sel:[0,0,1] op_sel_hi:[1,0,0] neg_lo:[1,0,0] neg_hi:[1,0,0]
	v_pk_mul_f32 v[156:157], v[142:143], s[40:41]
	v_pk_fma_f32 v[172:173], v[132:133], s[80:81], v[172:173] op_sel:[0,0,1] op_sel_hi:[1,0,0]
	s_waitcnt lgkmcnt(1)
	v_pk_mul_f32 v[188:189], v[158:159], s[18:19]
	v_pk_fma_f32 v[142:143], v[142:143], s[80:81], v[156:157] op_sel:[0,0,1] op_sel_hi:[1,0,0] neg_lo:[1,0,0] neg_hi:[1,0,0]
	v_pk_add_f32 v[156:157], v[132:133], v[158:159]
	v_pk_add_f32 v[132:133], v[132:133], v[158:159] neg_lo:[0,1] neg_hi:[0,1]
	v_pk_mul_f32 v[174:175], v[130:131], s[42:43]
	v_pk_fma_f32 v[188:189], v[158:159], s[16:17], v[188:189] op_sel:[0,0,1] op_sel_hi:[1,0,0] neg_lo:[1,0,0] neg_hi:[1,0,0]
	v_pk_mul_f32 v[158:159], v[132:133], s[36:37]
	v_pk_fma_f32 v[174:175], v[130:131], s[74:75], v[174:175] op_sel:[0,0,1] op_sel_hi:[1,0,0]
	s_waitcnt lgkmcnt(0)
	v_pk_mul_f32 v[190:191], v[160:161], s[10:11]
	v_pk_fma_f32 v[132:133], v[132:133], s[78:79], v[158:159] op_sel:[0,0,1] op_sel_hi:[1,0,0] neg_lo:[1,0,0] neg_hi:[1,0,0]
	v_pk_add_f32 v[158:159], v[130:131], v[160:161]
	v_pk_add_f32 v[130:131], v[130:131], v[160:161] neg_lo:[0,1] neg_hi:[0,1]
	v_xor_b32_e32 v177, 0x80000000, v144
	v_mov_b32_e32 v176, v145
	v_pk_fma_f32 v[190:191], v[160:161], s[8:9], v[190:191] op_sel:[0,0,1] op_sel_hi:[1,0,0] neg_lo:[1,0,0] neg_hi:[1,0,0]
	v_pk_mul_f32 v[160:161], v[130:131], s[18:19]
	v_pk_add_f32 v[192:193], v[128:129], v[144:145]
	v_pk_add_f32 v[144:145], v[128:129], v[144:145] neg_lo:[0,1] neg_hi:[0,1]
	v_pk_fma_f32 v[130:131], v[130:131], s[16:17], v[160:161] op_sel:[0,0,1] op_sel_hi:[1,0,0] neg_lo:[1,0,0] neg_hi:[1,0,0]
	v_pk_add_f32 v[160:161], v[128:129], v[176:177]
	v_pk_add_f32 v[128:129], v[128:129], v[176:177] neg_lo:[0,1] neg_hi:[0,1]
	v_pk_add_f32 v[176:177], v[162:163], v[178:179]
	v_pk_add_f32 v[162:163], v[162:163], v[178:179] neg_lo:[0,1] neg_hi:[0,1]
	v_cvt_f32_u32_e32 v2, v3
	v_pk_mul_f32 v[178:179], v[162:163], s[18:19]
	s_add_i32 s76, s72, s48
	v_pk_fma_f32 v[162:163], v[162:163], s[16:17], v[178:179] op_sel:[0,0,1] op_sel_hi:[1,0,0]
	v_pk_add_f32 v[178:179], v[164:165], v[180:181]
	v_pk_add_f32 v[164:165], v[164:165], v[180:181] neg_lo:[0,1] neg_hi:[0,1]
	v_mul_f32_e32 v2, 0x38800000, v2
	v_pk_mul_f32 v[180:181], v[164:165], s[36:37]
	v_sin_f32_e32 v34, v2
	v_pk_fma_f32 v[164:165], v[164:165], s[78:79], v[180:181] op_sel:[0,0,1] op_sel_hi:[1,0,0]
	v_pk_add_f32 v[180:181], v[166:167], v[182:183]
	v_pk_add_f32 v[166:167], v[166:167], v[182:183] neg_lo:[0,1] neg_hi:[0,1]
	v_cos_f32_e32 v30, v2
	v_pk_mul_f32 v[182:183], v[166:167], s[40:41]
	v_xor_b32_e32 v31, 0x80000000, v34
	v_pk_fma_f32 v[166:167], v[166:167], s[80:81], v[182:183] op_sel:[0,0,1] op_sel_hi:[1,0,0]
	v_pk_add_f32 v[182:183], v[168:169], v[184:185]
	v_pk_add_f32 v[184:185], v[168:169], v[184:185] neg_lo:[0,1] neg_hi:[0,1]
	v_mov_b32_e32 v35, v31
	v_pk_add_f32 v[168:169], v[170:171], v[186:187]
	v_pk_add_f32 v[170:171], v[170:171], v[186:187] neg_lo:[0,1] neg_hi:[0,1]
	v_pk_mul_f32 v[2:3], v[30:31], v[34:35] op_sel:[1,0] op_sel_hi:[0,1]
	v_pk_mul_f32 v[186:187], v[170:171], s[40:41]
	v_pk_fma_f32 v[44:45], v[30:31], v[30:31], v[2:3] op_sel_hi:[1,0,1]
	v_pk_fma_f32 v[170:171], v[170:171], s[80:81], v[186:187] op_sel:[0,0,1] op_sel_hi:[1,0,0] neg_lo:[1,0,0] neg_hi:[1,0,0]
	v_pk_add_f32 v[186:187], v[172:173], v[188:189]
	v_pk_add_f32 v[172:173], v[172:173], v[188:189] neg_lo:[0,1] neg_hi:[0,1]
	v_pk_mul_f32 v[2:3], v[34:35], v[44:45] op_sel:[0,1] op_sel_hi:[1,0]
	v_pk_mul_f32 v[188:189], v[172:173], s[36:37]
	v_xor_b32_e32 v54, 0x80000000, v45
	v_pk_fma_f32 v[172:173], v[172:173], s[78:79], v[188:189] op_sel:[0,0,1] op_sel_hi:[1,0,0] neg_lo:[1,0,0] neg_hi:[1,0,0]
	v_pk_add_f32 v[188:189], v[174:175], v[190:191]
	v_pk_add_f32 v[174:175], v[174:175], v[190:191] neg_lo:[0,1] neg_hi:[0,1]
	v_mov_b32_e32 v55, v45
	v_pk_mul_f32 v[190:191], v[174:175], s[18:19]
	v_pk_fma_f32 v[46:47], v[30:31], v[44:45], v[2:3] op_sel_hi:[0,1,1]
	v_pk_fma_f32 v[174:175], v[174:175], s[16:17], v[190:191] op_sel:[0,0,1] op_sel_hi:[1,0,0] neg_lo:[1,0,0] neg_hi:[1,0,0]
	v_pk_add_f32 v[190:191], v[192:193], v[152:153]
	v_pk_add_f32 v[152:153], v[192:193], v[152:153] neg_lo:[0,1] neg_hi:[0,1]
	v_pk_add_f32 v[192:193], v[194:195], v[140:141]
	v_pk_add_f32 v[140:141], v[194:195], v[140:141] neg_lo:[0,1] neg_hi:[0,1]
	v_pk_mul_f32 v[2:3], v[44:45], v[54:55] op_sel:[1,0] op_sel_hi:[0,1]
	v_pk_mul_f32 v[194:195], v[140:141], s[36:37]
	v_pk_fma_f32 v[52:53], v[44:45], v[44:45], v[2:3] op_sel_hi:[1,0,1]
	v_pk_fma_f32 v[140:141], v[140:141], s[78:79], v[194:195] op_sel:[0,0,1] op_sel_hi:[1,0,0]
	v_pk_add_f32 v[194:195], v[148:149], v[156:157]
	v_pk_add_f32 v[156:157], v[148:149], v[156:157] neg_lo:[0,1] neg_hi:[0,1]
	v_xor_b32_e32 v58, 0x80000000, v53
	v_pk_add_f32 v[148:149], v[150:151], v[158:159]
	v_pk_add_f32 v[150:151], v[150:151], v[158:159] neg_lo:[0,1] neg_hi:[0,1]
	v_mov_b32_e32 v59, v53
	v_pk_mul_f32 v[158:159], v[150:151], s[36:37]
	v_pk_mul_f32 v[2:3], v[52:53], v[58:59] op_sel:[1,0] op_sel_hi:[0,1]
	v_pk_fma_f32 v[150:151], v[150:151], s[78:79], v[158:159] op_sel:[0,0,1] op_sel_hi:[1,0,0] neg_lo:[1,0,0] neg_hi:[1,0,0]
	v_pk_add_f32 v[158:159], v[144:145], v[154:155]
	v_pk_add_f32 v[144:145], v[144:145], v[154:155] neg_lo:[0,1] neg_hi:[0,1]
	v_pk_add_f32 v[154:155], v[134:135], v[142:143]
	v_pk_add_f32 v[134:135], v[134:135], v[142:143] neg_lo:[0,1] neg_hi:[0,1]
	v_pk_fma_f32 v[48:49], v[52:53], v[52:53], v[2:3] op_sel_hi:[1,0,1]
	v_pk_mul_f32 v[142:143], v[134:135], s[36:37]
	v_pk_mul_f32 v[2:3], v[58:59], v[48:49] op_sel:[0,1] op_sel_hi:[1,0]
	v_pk_fma_f32 v[134:135], v[134:135], s[78:79], v[142:143] op_sel:[0,0,1] op_sel_hi:[1,0,0]
	v_pk_add_f32 v[142:143], v[136:137], v[132:133]
	v_pk_add_f32 v[136:137], v[136:137], v[132:133] neg_lo:[0,1] neg_hi:[0,1]
	v_pk_fma_f32 v[36:37], v[52:53], v[48:49], v[2:3] op_sel_hi:[0,1,1]
	v_pk_add_f32 v[132:133], v[138:139], v[130:131]
	v_pk_add_f32 v[130:131], v[138:139], v[130:131] neg_lo:[0,1] neg_hi:[0,1]
	v_pk_mul_f32 v[2:3], v[58:59], v[36:37] op_sel:[0,1] op_sel_hi:[1,0]
	v_pk_mul_f32 v[138:139], v[130:131], s[36:37]
	v_pk_fma_f32 v[26:27], v[52:53], v[36:37], v[2:3] op_sel_hi:[0,1,1]
	v_pk_fma_f32 v[130:131], v[130:131], s[78:79], v[138:139] op_sel:[0,0,1] op_sel_hi:[1,0,0] neg_lo:[1,0,0] neg_hi:[1,0,0]
	v_pk_add_f32 v[138:139], v[160:161], v[182:183]
	v_pk_add_f32 v[160:161], v[160:161], v[182:183] neg_lo:[0,1] neg_hi:[0,1]
	v_pk_add_f32 v[182:183], v[176:177], v[168:169]
	v_pk_add_f32 v[168:169], v[176:177], v[168:169] neg_lo:[0,1] neg_hi:[0,1]
	v_pk_mul_f32 v[2:3], v[58:59], v[26:27] op_sel:[0,1] op_sel_hi:[1,0]
	v_pk_mul_f32 v[176:177], v[168:169], s[36:37]
	v_pk_fma_f32 v[20:21], v[52:53], v[26:27], v[2:3] op_sel_hi:[0,1,1]
	v_pk_fma_f32 v[168:169], v[168:169], s[78:79], v[176:177] op_sel:[0,0,1] op_sel_hi:[1,0,0]
	v_pk_add_f32 v[176:177], v[178:179], v[186:187]
	v_pk_add_f32 v[186:187], v[178:179], v[186:187] neg_lo:[0,1] neg_hi:[0,1]
	v_pk_mul_f32 v[2:3], v[58:59], v[20:21] op_sel:[0,1] op_sel_hi:[1,0]
	v_pk_add_f32 v[178:179], v[180:181], v[188:189]
	v_pk_add_f32 v[180:181], v[180:181], v[188:189] neg_lo:[0,1] neg_hi:[0,1]
	v_pk_fma_f32 v[10:11], v[52:53], v[20:21], v[2:3] op_sel_hi:[0,1,1]
	v_pk_mul_f32 v[188:189], v[180:181], s[36:37]
	v_pk_mul_f32 v[2:3], v[58:59], v[10:11] op_sel:[0,1] op_sel_hi:[1,0]
	v_pk_fma_f32 v[180:181], v[180:181], s[78:79], v[188:189] op_sel:[0,0,1] op_sel_hi:[1,0,0] neg_lo:[1,0,0] neg_hi:[1,0,0]
	v_pk_add_f32 v[188:189], v[128:129], v[184:185] op_sel:[0,1] op_sel_hi:[1,0] neg_hi:[0,1]
	v_pk_add_f32 v[128:129], v[128:129], v[184:185] op_sel:[0,1] op_sel_hi:[1,0] neg_lo:[0,1]
	v_pk_add_f32 v[184:185], v[162:163], v[170:171]
	v_pk_add_f32 v[162:163], v[162:163], v[170:171] neg_lo:[0,1] neg_hi:[0,1]
	v_pk_fma_f32 v[4:5], v[52:53], v[10:11], v[2:3] op_sel_hi:[0,1,1]
	v_pk_mul_f32 v[170:171], v[162:163], s[36:37]
	v_pk_mul_f32 v[8:9], v[54:55], v[4:5] op_sel:[0,1] op_sel_hi:[1,0]
	v_pk_fma_f32 v[162:163], v[162:163], s[78:79], v[170:171] op_sel:[0,0,1] op_sel_hi:[1,0,0]
	v_pk_add_f32 v[170:171], v[164:165], v[172:173]
	v_pk_add_f32 v[172:173], v[164:165], v[172:173] neg_lo:[0,1] neg_hi:[0,1]
	v_pk_mul_f32 v[14:15], v[34:35], v[4:5] op_sel:[0,1] op_sel_hi:[1,0]
	v_pk_add_f32 v[164:165], v[166:167], v[174:175]
	v_pk_add_f32 v[166:167], v[166:167], v[174:175] neg_lo:[0,1] neg_hi:[0,1]
	v_pk_mul_f32 v[32:33], v[54:55], v[10:11] op_sel:[0,1] op_sel_hi:[1,0]
	v_pk_mul_f32 v[174:175], v[166:167], s[36:37]
	v_pk_mul_f32 v[40:41], v[34:35], v[10:11] op_sel:[0,1] op_sel_hi:[1,0]
	v_pk_fma_f32 v[166:167], v[166:167], s[78:79], v[174:175] op_sel:[0,0,1] op_sel_hi:[1,0,0] neg_lo:[1,0,0] neg_hi:[1,0,0]
	v_pk_add_f32 v[174:175], v[190:191], v[194:195]
	v_pk_add_f32 v[190:191], v[190:191], v[194:195] neg_lo:[0,1] neg_hi:[0,1]
	v_pk_add_f32 v[194:195], v[192:193], v[148:149]
	v_pk_add_f32 v[192:193], v[192:193], v[148:149] neg_lo:[0,1] neg_hi:[0,1]
	v_pk_mul_f32 v[62:63], v[54:55], v[20:21] op_sel:[0,1] op_sel_hi:[1,0]
	v_pk_add_f32 v[148:149], v[152:153], v[156:157] op_sel:[0,1] op_sel_hi:[1,0] neg_hi:[0,1]
	v_pk_add_f32 v[152:153], v[152:153], v[156:157] op_sel:[0,1] op_sel_hi:[1,0] neg_lo:[0,1]
	v_pk_add_f32 v[156:157], v[140:141], v[150:151]
	v_pk_add_f32 v[150:151], v[140:141], v[150:151] neg_lo:[0,1] neg_hi:[0,1]
	v_pk_mul_f32 v[66:67], v[34:35], v[20:21] op_sel:[0,1] op_sel_hi:[1,0]
	v_pk_add_f32 v[140:141], v[158:159], v[142:143]
	v_pk_add_f32 v[142:143], v[158:159], v[142:143] neg_lo:[0,1] neg_hi:[0,1]
	v_pk_add_f32 v[158:159], v[154:155], v[132:133]
	v_pk_add_f32 v[154:155], v[154:155], v[132:133] neg_lo:[0,1] neg_hi:[0,1]
	v_pk_mul_f32 v[78:79], v[54:55], v[26:27] op_sel:[0,1] op_sel_hi:[1,0]
	v_pk_add_f32 v[132:133], v[144:145], v[136:137] op_sel:[0,1] op_sel_hi:[1,0] neg_hi:[0,1]
	v_pk_add_f32 v[136:137], v[144:145], v[136:137] op_sel:[0,1] op_sel_hi:[1,0] neg_lo:[0,1]
	v_pk_add_f32 v[144:145], v[134:135], v[130:131]
	v_pk_add_f32 v[134:135], v[134:135], v[130:131] neg_lo:[0,1] neg_hi:[0,1]
	v_pk_mul_f32 v[82:83], v[34:35], v[26:27] op_sel:[0,1] op_sel_hi:[1,0]
	v_pk_add_f32 v[130:131], v[138:139], v[176:177]
	v_pk_add_f32 v[138:139], v[138:139], v[176:177] neg_lo:[0,1] neg_hi:[0,1]
	v_pk_add_f32 v[176:177], v[182:183], v[178:179]
	v_pk_add_f32 v[182:183], v[182:183], v[178:179] neg_lo:[0,1] neg_hi:[0,1]
	v_pk_mul_f32 v[92:93], v[54:55], v[36:37] op_sel:[0,1] op_sel_hi:[1,0]
	v_pk_add_f32 v[178:179], v[160:161], v[186:187] op_sel:[0,1] op_sel_hi:[1,0] neg_hi:[0,1]
	v_pk_add_f32 v[160:161], v[160:161], v[186:187] op_sel:[0,1] op_sel_hi:[1,0] neg_lo:[0,1]
	v_pk_add_f32 v[186:187], v[168:169], v[180:181]
	v_pk_add_f32 v[180:181], v[168:169], v[180:181] neg_lo:[0,1] neg_hi:[0,1]
	v_pk_mul_f32 v[96:97], v[34:35], v[36:37] op_sel:[0,1] op_sel_hi:[1,0]
	v_pk_add_f32 v[168:169], v[188:189], v[170:171]
	v_pk_add_f32 v[170:171], v[188:189], v[170:171] neg_lo:[0,1] neg_hi:[0,1]
	v_pk_add_f32 v[188:189], v[184:185], v[164:165]
	v_pk_add_f32 v[184:185], v[184:185], v[164:165] neg_lo:[0,1] neg_hi:[0,1]
	v_pk_mul_f32 v[106:107], v[54:55], v[48:49] op_sel:[0,1] op_sel_hi:[1,0]
	v_pk_add_f32 v[164:165], v[128:129], v[172:173] op_sel:[0,1] op_sel_hi:[1,0] neg_hi:[0,1]
	v_pk_add_f32 v[128:129], v[128:129], v[172:173] op_sel:[0,1] op_sel_hi:[1,0] neg_lo:[0,1]
	v_pk_add_f32 v[172:173], v[162:163], v[166:167]
	v_pk_add_f32 v[166:167], v[162:163], v[166:167] neg_lo:[0,1] neg_hi:[0,1]
	v_pk_mul_f32 v[110:111], v[34:35], v[48:49] op_sel:[0,1] op_sel_hi:[1,0]
	v_pk_add_f32 v[162:163], v[174:175], v[194:195]
	v_pk_add_f32 v[174:175], v[174:175], v[194:195] neg_lo:[0,1] neg_hi:[0,1]
	v_pk_add_f32 v[194:195], v[190:191], v[192:193] op_sel:[0,1] op_sel_hi:[1,0] neg_hi:[0,1]
	v_pk_add_f32 v[190:191], v[190:191], v[192:193] op_sel:[0,1] op_sel_hi:[1,0] neg_lo:[0,1]
	v_pk_add_f32 v[192:193], v[148:149], v[156:157]
	v_pk_add_f32 v[148:149], v[148:149], v[156:157] neg_lo:[0,1] neg_hi:[0,1]
	v_pk_add_f32 v[156:157], v[152:153], v[150:151] op_sel:[0,1] op_sel_hi:[1,0] neg_hi:[0,1]
	v_pk_add_f32 v[150:151], v[152:153], v[150:151] op_sel:[0,1] op_sel_hi:[1,0] neg_lo:[0,1]
	v_pk_add_f32 v[152:153], v[140:141], v[158:159]
	v_pk_add_f32 v[140:141], v[140:141], v[158:159] neg_lo:[0,1] neg_hi:[0,1]
	v_pk_add_f32 v[158:159], v[142:143], v[154:155] op_sel:[0,1] op_sel_hi:[1,0] neg_hi:[0,1]
	v_pk_add_f32 v[142:143], v[142:143], v[154:155] op_sel:[0,1] op_sel_hi:[1,0] neg_lo:[0,1]
	v_pk_add_f32 v[154:155], v[132:133], v[144:145]
	v_pk_add_f32 v[132:133], v[132:133], v[144:145] neg_lo:[0,1] neg_hi:[0,1]
	v_pk_add_f32 v[144:145], v[136:137], v[134:135] op_sel:[0,1] op_sel_hi:[1,0] neg_hi:[0,1]
	v_pk_add_f32 v[134:135], v[136:137], v[134:135] op_sel:[0,1] op_sel_hi:[1,0] neg_lo:[0,1]
	v_pk_add_f32 v[136:137], v[130:131], v[176:177]
	v_pk_mul_f32 v[120:121], v[54:55], v[52:53] op_sel:[0,1] op_sel_hi:[1,0]
	v_pk_mul_f32 v[124:125], v[34:35], v[52:53] op_sel:[0,1] op_sel_hi:[1,0]
	v_pk_mul_f32 v[34:35], v[34:35], v[136:137] op_sel:[0,1] op_sel_hi:[1,0]
	v_xor_b32_e32 v72, 0x80000000, v47
	v_mov_b32_e32 v73, v47
	v_pk_fma_f32 v[8:9], v[44:45], v[4:5], v[8:9] op_sel_hi:[0,1,1]
	v_pk_fma_f32 v[14:15], v[30:31], v[4:5], v[14:15] op_sel_hi:[0,1,1]
	v_xor_b32_e32 v22, 0x80000000, v5
	v_pk_fma_f32 v[32:33], v[44:45], v[10:11], v[32:33] op_sel_hi:[0,1,1]
	v_pk_fma_f32 v[40:41], v[30:31], v[10:11], v[40:41] op_sel_hi:[0,1,1]
	v_pk_fma_f32 v[62:63], v[44:45], v[20:21], v[62:63] op_sel_hi:[0,1,1]
	v_pk_fma_f32 v[66:67], v[30:31], v[20:21], v[66:67] op_sel_hi:[0,1,1]
	v_pk_fma_f32 v[78:79], v[44:45], v[26:27], v[78:79] op_sel_hi:[0,1,1]
	v_pk_fma_f32 v[82:83], v[30:31], v[26:27], v[82:83] op_sel_hi:[0,1,1]
	v_pk_fma_f32 v[92:93], v[44:45], v[36:37], v[92:93] op_sel_hi:[0,1,1]
	v_pk_fma_f32 v[96:97], v[30:31], v[36:37], v[96:97] op_sel_hi:[0,1,1]
	v_pk_fma_f32 v[106:107], v[44:45], v[48:49], v[106:107] op_sel_hi:[0,1,1]
	v_pk_fma_f32 v[110:111], v[30:31], v[48:49], v[110:111] op_sel_hi:[0,1,1]
	v_pk_fma_f32 v[120:121], v[44:45], v[52:53], v[120:121] op_sel_hi:[0,1,1]
	v_pk_fma_f32 v[124:125], v[30:31], v[52:53], v[124:125] op_sel_hi:[0,1,1]
	v_mov_b32_e32 v23, v5
	v_pk_add_f32 v[130:131], v[130:131], v[176:177] neg_lo:[0,1] neg_hi:[0,1]
	v_pk_add_f32 v[176:177], v[138:139], v[182:183] op_sel:[0,1] op_sel_hi:[1,0] neg_hi:[0,1]
	v_pk_add_f32 v[138:139], v[138:139], v[182:183] op_sel:[0,1] op_sel_hi:[1,0] neg_lo:[0,1]
	v_pk_add_f32 v[182:183], v[178:179], v[186:187]
	v_pk_add_f32 v[178:179], v[178:179], v[186:187] neg_lo:[0,1] neg_hi:[0,1]
	v_pk_add_f32 v[186:187], v[160:161], v[180:181] op_sel:[0,1] op_sel_hi:[1,0] neg_hi:[0,1]
	v_pk_add_f32 v[160:161], v[160:161], v[180:181] op_sel:[0,1] op_sel_hi:[1,0] neg_lo:[0,1]
	v_pk_add_f32 v[180:181], v[168:169], v[188:189]
	v_pk_fma_f32 v[30:31], v[30:31], v[136:137], v[34:35] op_sel_hi:[0,1,1]
	v_pk_mul_f32 v[34:35], v[54:55], v[152:153] op_sel:[0,1] op_sel_hi:[1,0]
	v_pk_mul_f32 v[2:3], v[72:73], v[4:5] op_sel:[0,1] op_sel_hi:[1,0]
	v_xor_b32_e32 v12, 0x80000000, v9
	v_pk_mul_f32 v[24:25], v[72:73], v[10:11] op_sel:[0,1] op_sel_hi:[1,0]
	v_xor_b32_e32 v38, 0x80000000, v33
	v_xor_b32_e32 v50, 0x80000000, v11
	v_pk_mul_f32 v[56:57], v[72:73], v[20:21] op_sel:[0,1] op_sel_hi:[1,0]
	v_xor_b32_e32 v64, 0x80000000, v63
	v_xor_b32_e32 v70, 0x80000000, v21
	v_pk_mul_f32 v[74:75], v[72:73], v[26:27] op_sel:[0,1] op_sel_hi:[1,0]
	v_xor_b32_e32 v80, 0x80000000, v79
	v_xor_b32_e32 v86, 0x80000000, v27
	v_pk_mul_f32 v[88:89], v[72:73], v[36:37] op_sel:[0,1] op_sel_hi:[1,0]
	v_xor_b32_e32 v94, 0x80000000, v93
	v_xor_b32_e32 v100, 0x80000000, v37
	v_pk_mul_f32 v[102:103], v[72:73], v[48:49] op_sel:[0,1] op_sel_hi:[1,0]
	v_xor_b32_e32 v108, 0x80000000, v107
	v_xor_b32_e32 v114, 0x80000000, v49
	v_pk_mul_f32 v[116:117], v[52:53], v[72:73] op_sel:[1,0] op_sel_hi:[0,1]
	v_xor_b32_e32 v122, 0x80000000, v121
	v_mov_b32_e32 v123, v121
	v_mov_b32_e32 v115, v49
	v_mov_b32_e32 v109, v107
	v_mov_b32_e32 v101, v37
	v_mov_b32_e32 v95, v93
	v_mov_b32_e32 v87, v27
	v_mov_b32_e32 v81, v79
	v_mov_b32_e32 v71, v21
	v_mov_b32_e32 v65, v63
	v_mov_b32_e32 v51, v11
	v_mov_b32_e32 v39, v33
	v_mov_b32_e32 v13, v9
	v_pk_fma_f32 v[34:35], v[44:45], v[152:153], v[34:35] op_sel_hi:[0,1,1]
	v_pk_mul_f32 v[44:45], v[72:73], v[180:181] op_sel:[0,1] op_sel_hi:[1,0]
	v_pk_mul_f32 v[22:23], v[150:151], v[22:23] op_sel:[1,0] op_sel_hi:[0,1]
	v_pk_fma_f32 v[2:3], v[46:47], v[4:5], v[2:3] op_sel_hi:[0,1,1]
	v_pk_fma_f32 v[24:25], v[46:47], v[10:11], v[24:25] op_sel_hi:[0,1,1]
	v_pk_fma_f32 v[56:57], v[46:47], v[20:21], v[56:57] op_sel_hi:[0,1,1]
	v_pk_fma_f32 v[74:75], v[46:47], v[26:27], v[74:75] op_sel_hi:[0,1,1]
	v_xor_b32_e32 v84, 0x80000000, v83
	v_pk_fma_f32 v[88:89], v[46:47], v[36:37], v[88:89] op_sel_hi:[0,1,1]
	v_pk_fma_f32 v[102:103], v[46:47], v[48:49], v[102:103] op_sel_hi:[0,1,1]
	v_pk_fma_f32 v[116:117], v[52:53], v[46:47], v[116:117] op_sel_hi:[1,0,1]
	v_mov_b32_e32 v85, v83
	v_pk_fma_f32 v[44:45], v[46:47], v[180:181], v[44:45] op_sel_hi:[0,1,1]
	v_pk_mul_f32 v[46:47], v[58:59], v[192:193] op_sel:[0,1] op_sel_hi:[1,0]
	v_pk_mul_f32 v[54:55], v[122:123], v[154:155] op_sel:[0,1] op_sel_hi:[1,0]
	v_pk_mul_f32 v[72:73], v[114:115], v[194:195] op_sel:[0,1] op_sel_hi:[1,0]
	v_pk_mul_f32 v[108:109], v[108:109], v[158:159] op_sel:[0,1] op_sel_hi:[1,0]
	v_pk_mul_f32 v[100:101], v[100:101], v[156:157] op_sel:[0,1] op_sel_hi:[1,0]
	v_pk_mul_f32 v[94:95], v[94:95], v[144:145] op_sel:[0,1] op_sel_hi:[1,0]
	v_pk_mul_f32 v[86:87], v[174:175], v[86:87] op_sel:[1,0] op_sel_hi:[0,1]
	v_pk_mul_f32 v[80:81], v[140:141], v[80:81] op_sel:[1,0] op_sel_hi:[0,1]
	v_pk_mul_f32 v[70:71], v[148:149], v[70:71] op_sel:[1,0] op_sel_hi:[0,1]
	v_pk_mul_f32 v[64:65], v[132:133], v[64:65] op_sel:[1,0] op_sel_hi:[0,1]
	v_pk_mul_f32 v[50:51], v[190:191], v[50:51] op_sel:[1,0] op_sel_hi:[0,1]
	v_pk_mul_f32 v[38:39], v[142:143], v[38:39] op_sel:[1,0] op_sel_hi:[0,1]
	v_pk_fma_f32 v[4:5], v[150:151], v[4:5], v[22:23] op_sel_hi:[1,0,1]
	v_pk_mul_f32 v[12:13], v[134:135], v[12:13] op_sel:[1,0] op_sel_hi:[0,1]
	v_xor_b32_e32 v112, 0x80000000, v111
	v_mov_b32_e32 v113, v111
	v_pk_fma_f32 v[46:47], v[52:53], v[192:193], v[46:47] op_sel_hi:[0,1,1]
	v_pk_fma_f32 v[54:55], v[120:121], v[154:155], v[54:55] op_sel_hi:[0,1,1]
	v_pk_fma_f32 v[48:49], v[48:49], v[194:195], v[72:73] op_sel_hi:[0,1,1]
	v_pk_fma_f32 v[106:107], v[106:107], v[158:159], v[108:109] op_sel_hi:[0,1,1]
	v_pk_fma_f32 v[36:37], v[36:37], v[156:157], v[100:101] op_sel_hi:[0,1,1]
	v_pk_fma_f32 v[92:93], v[92:93], v[144:145], v[94:95] op_sel_hi:[0,1,1]
	v_pk_fma_f32 v[26:27], v[174:175], v[26:27], v[86:87] op_sel_hi:[1,0,1]
	v_pk_mul_f32 v[84:85], v[130:131], v[84:85] op_sel:[1,0] op_sel_hi:[0,1]
	v_pk_fma_f32 v[78:79], v[140:141], v[78:79], v[80:81] op_sel_hi:[1,0,1]
	v_pk_fma_f32 v[20:21], v[148:149], v[20:21], v[70:71] op_sel_hi:[1,0,1]
	v_pk_fma_f32 v[62:63], v[132:133], v[62:63], v[64:65] op_sel_hi:[1,0,1]
	v_pk_fma_f32 v[10:11], v[190:191], v[10:11], v[50:51] op_sel_hi:[1,0,1]
	v_pk_fma_f32 v[32:33], v[142:143], v[32:33], v[38:39] op_sel_hi:[1,0,1]
	v_pk_fma_f32 v[8:9], v[134:135], v[8:9], v[12:13] op_sel_hi:[1,0,1]
	ds_write_b64 v18, v[162:163]
	ds_write_b64 v18, v[26:27] offset:4224
	ds_write_b64 v18, v[48:49] offset:8448
	ds_write_b64 v18, v[10:11] offset:12672
	ds_write_b64 v18, v[46:47] offset:16896
	ds_write_b64 v18, v[20:21] offset:21120
	ds_write_b64 v18, v[36:37] offset:25344
	ds_write_b64 v18, v[4:5] offset:29568
	ds_write_b64 v18, v[34:35] offset:33792
	ds_write_b64 v18, v[78:79] offset:38016
	ds_write_b64 v18, v[106:107] offset:42240
	ds_write_b64 v18, v[32:33] offset:46464
	ds_write_b64 v18, v[54:55] offset:50688
	ds_write_b64 v18, v[62:63] offset:54912
	ds_write_b64 v18, v[92:93] offset:59136
	ds_write_b64 v18, v[8:9] offset:63360
	v_add_u32_e32 v4, 0x10800, v18
	v_xor_b32_e32 v42, 0x80000000, v41
	v_mov_b32_e32 v43, v41
	v_pk_mul_f32 v[72:73], v[112:113], v[176:177] op_sel:[0,1] op_sel_hi:[1,0]
	v_pk_fma_f32 v[82:83], v[130:131], v[82:83], v[84:85] op_sel_hi:[1,0,1]
	ds_write_b64 v4, v[30:31]
	v_add_u32_e32 v4, 0x11880, v18
	v_xor_b32_e32 v126, 0x80000000, v125
	v_mov_b32_e32 v127, v125
	v_pk_fma_f32 v[72:73], v[110:111], v[176:177], v[72:73] op_sel_hi:[0,1,1]
	v_pk_mul_f32 v[42:43], v[138:139], v[42:43] op_sel:[1,0] op_sel_hi:[0,1]
	ds_write_b64 v4, v[82:83]
	v_add_u32_e32 v4, 0x12900, v18
	v_xor_b32_e32 v68, 0x80000000, v67
	v_mov_b32_e32 v69, v67
	v_pk_mul_f32 v[52:53], v[126:127], v[182:183] op_sel:[0,1] op_sel_hi:[1,0]
	v_pk_fma_f32 v[40:41], v[138:139], v[40:41], v[42:43] op_sel_hi:[1,0,1]
	ds_write_b64 v4, v[72:73]
	v_add_u32_e32 v4, 0x13980, v18
	v_xor_b32_e32 v98, 0x80000000, v97
	v_mov_b32_e32 v99, v97
	v_pk_fma_f32 v[52:53], v[124:125], v[182:183], v[52:53] op_sel_hi:[0,1,1]
	v_pk_mul_f32 v[68:69], v[178:179], v[68:69] op_sel:[1,0] op_sel_hi:[0,1]
	ds_write_b64 v4, v[40:41]
	v_add_u32_e32 v4, 0x14a00, v18
	v_xor_b32_e32 v16, 0x80000000, v15
	v_mov_b32_e32 v17, v15
	v_pk_mul_f32 v[98:99], v[98:99], v[186:187] op_sel:[0,1] op_sel_hi:[1,0]
	v_pk_fma_f32 v[66:67], v[178:179], v[66:67], v[68:69] op_sel_hi:[1,0,1]
	ds_write_b64 v4, v[52:53]
	v_add_u32_e32 v4, 0x15a80, v18
	v_pk_fma_f32 v[96:97], v[96:97], v[186:187], v[98:99] op_sel_hi:[0,1,1]
	v_pk_mul_f32 v[16:17], v[160:161], v[16:17] op_sel:[1,0] op_sel_hi:[0,1]
	ds_write_b64 v4, v[66:67]
	v_add_u32_e32 v4, 0x16b00, v18
	v_xor_b32_e32 v76, 0x80000000, v75
	v_mov_b32_e32 v77, v75
	v_pk_add_f32 v[168:169], v[168:169], v[188:189] neg_lo:[0,1] neg_hi:[0,1]
	v_pk_fma_f32 v[14:15], v[160:161], v[14:15], v[16:17] op_sel_hi:[1,0,1]
	ds_write_b64 v4, v[96:97]
	v_add_u32_e32 v4, 0x17b80, v18
	v_xor_b32_e32 v104, 0x80000000, v103
	v_mov_b32_e32 v105, v103
	v_pk_add_f32 v[188:189], v[170:171], v[184:185] op_sel:[0,1] op_sel_hi:[1,0] neg_hi:[0,1]
	v_pk_mul_f32 v[76:77], v[168:169], v[76:77] op_sel:[1,0] op_sel_hi:[0,1]
	ds_write_b64 v4, v[14:15]
	v_add_u32_e32 v4, 0x18c00, v18
	v_xor_b32_e32 v28, 0x80000000, v25
	v_mov_b32_e32 v29, v25
	v_pk_add_f32 v[170:171], v[170:171], v[184:185] op_sel:[0,1] op_sel_hi:[1,0] neg_lo:[0,1]
	v_pk_mul_f32 v[104:105], v[104:105], v[188:189] op_sel:[0,1] op_sel_hi:[1,0]
	v_pk_fma_f32 v[74:75], v[168:169], v[74:75], v[76:77] op_sel_hi:[1,0,1]
	ds_write_b64 v4, v[44:45]
	v_add_u32_e32 v4, 0x19c80, v18
	v_xor_b32_e32 v118, 0x80000000, v117
	v_mov_b32_e32 v119, v117
	v_pk_add_f32 v[184:185], v[164:165], v[172:173]
	v_pk_fma_f32 v[102:103], v[102:103], v[188:189], v[104:105] op_sel_hi:[0,1,1]
	v_pk_mul_f32 v[28:29], v[170:171], v[28:29] op_sel:[1,0] op_sel_hi:[0,1]
	ds_write_b64 v4, v[74:75]
	v_add_u32_e32 v4, 0x1ad00, v18
	v_xor_b32_e32 v60, 0x80000000, v57
	v_mov_b32_e32 v61, v57
	v_pk_add_f32 v[164:165], v[164:165], v[172:173] neg_lo:[0,1] neg_hi:[0,1]
	v_pk_mul_f32 v[58:59], v[118:119], v[184:185] op_sel:[0,1] op_sel_hi:[1,0]
	v_pk_fma_f32 v[24:25], v[170:171], v[24:25], v[28:29] op_sel_hi:[1,0,1]
	ds_write_b64 v4, v[102:103]
	v_add_u32_e32 v4, 0x1bd80, v18
	v_xor_b32_e32 v90, 0x80000000, v89
	v_mov_b32_e32 v91, v89
	v_pk_add_f32 v[172:173], v[128:129], v[166:167] op_sel:[0,1] op_sel_hi:[1,0] neg_hi:[0,1]
	v_pk_fma_f32 v[58:59], v[116:117], v[184:185], v[58:59] op_sel_hi:[0,1,1]
	v_pk_mul_f32 v[60:61], v[164:165], v[60:61] op_sel:[1,0] op_sel_hi:[0,1]
	ds_write_b64 v4, v[24:25]
	v_add_u32_e32 v4, 0x1ce00, v18
	v_xor_b32_e32 v6, 0x80000000, v3
	v_mov_b32_e32 v7, v3
	v_pk_add_f32 v[128:129], v[128:129], v[166:167] op_sel:[0,1] op_sel_hi:[1,0] neg_lo:[0,1]
	v_pk_mul_f32 v[90:91], v[90:91], v[172:173] op_sel:[0,1] op_sel_hi:[1,0]
	v_pk_fma_f32 v[56:57], v[164:165], v[56:57], v[60:61] op_sel_hi:[1,0,1]
	ds_write_b64 v4, v[58:59]
	v_add_u32_e32 v4, 0x1de80, v18
	v_pk_fma_f32 v[88:89], v[88:89], v[172:173], v[90:91] op_sel_hi:[0,1,1]
	v_pk_mul_f32 v[6:7], v[128:129], v[6:7] op_sel:[1,0] op_sel_hi:[0,1]
	ds_write_b64 v4, v[56:57]
	v_add_u32_e32 v4, 0x1ef00, v18
	v_pk_fma_f32 v[2:3], v[128:129], v[2:3], v[6:7] op_sel_hi:[1,0,1]
	ds_write_b64 v4, v[88:89]
	v_add_u32_e32 v4, 0x1ff80, v18
	ds_write_b64 v4, v[2:3]
	v_mov_b32_e32 v2, v210
	s_waitcnt lgkmcnt(0)
	s_barrier
	s_ashr_i32 s77, s76, 31
	v_and_b32_e32 v3, 15, v2
	v_lshlrev_b32_e32 v2, 5, v2
	v_and_b32_e32 v4, 0xfffffe00, v2
	v_lshl_add_u32 v5, v4, 3, 0
	v_lshlrev_b32_e32 v6, 3, v3
	v_ashrrev_i32_e32 v7, 2, v4
	v_add3_u32 v18, v5, v6, v7
	v_add_u32_e32 v196, 0x800, v18
	ds_read2_b64 v[128:131], v18 offset1:16
	ds_read2_b64 v[132:135], v18 offset0:33 offset1:49
	ds_read2_b64 v[136:139], v18 offset0:66 offset1:82
	ds_read2_b64 v[140:143], v18 offset0:99 offset1:115
	ds_read2_b64 v[148:151], v18 offset0:132 offset1:148
	ds_read2_b64 v[152:155], v18 offset0:165 offset1:181
	ds_read2_b64 v[156:159], v18 offset0:198 offset1:214
	ds_read2_b64 v[160:163], v18 offset0:231 offset1:247
	ds_read2_b64 v[164:167], v196 offset0:8 offset1:24
	ds_read2_b64 v[168:171], v196 offset0:41 offset1:57
	ds_read2_b64 v[172:175], v196 offset0:74 offset1:90
	ds_read2_b64 v[176:179], v196 offset0:107 offset1:123
	ds_read2_b64 v[180:183], v196 offset0:140 offset1:156
	ds_read2_b64 v[184:187], v196 offset0:173 offset1:189
	ds_read2_b64 v[188:191], v196 offset0:206 offset1:222
	ds_read2_b64 v[192:195], v196 offset0:239 offset1:255
	s_waitcnt lgkmcnt(7)
	v_pk_add_f32 v[144:145], v[128:129], v[164:165]
	v_pk_add_f32 v[128:129], v[128:129], v[164:165] neg_lo:[0,1] neg_hi:[0,1]
	v_pk_add_f32 v[164:165], v[130:131], v[166:167]
	v_pk_add_f32 v[130:131], v[130:131], v[166:167] neg_lo:[0,1] neg_hi:[0,1]
	v_cvt_f32_ubyte0_e32 v2, v3
	v_pk_mul_f32 v[166:167], v[130:131], s[10:11]
	v_mul_f32_e32 v3, 0x3b000000, v2
	v_pk_fma_f32 v[130:131], v[130:131], s[8:9], v[166:167] op_sel:[0,0,1] op_sel_hi:[1,0,0]
	s_waitcnt lgkmcnt(6)
	v_pk_add_f32 v[166:167], v[132:133], v[168:169]
	v_pk_add_f32 v[132:133], v[132:133], v[168:169] neg_lo:[0,1] neg_hi:[0,1]
	v_sin_f32_e32 v2, v3
	v_pk_mul_f32 v[168:169], v[132:133], s[18:19]
	v_cos_f32_e32 v4, v3
	v_pk_fma_f32 v[132:133], v[132:133], s[16:17], v[168:169] op_sel:[0,0,1] op_sel_hi:[1,0,0]
	v_pk_add_f32 v[168:169], v[134:135], v[170:171]
	v_pk_add_f32 v[134:135], v[134:135], v[170:171] neg_lo:[0,1] neg_hi:[0,1]
	v_xor_b32_e32 v5, 0x80000000, v2
	v_pk_mul_f32 v[170:171], v[134:135], s[26:27]
	v_mov_b32_e32 v3, v5
	v_pk_fma_f32 v[134:135], v[134:135], s[24:25], v[170:171] op_sel:[0,0,1] op_sel_hi:[1,0,0]
	s_waitcnt lgkmcnt(5)
	v_pk_add_f32 v[170:171], v[136:137], v[172:173]
	v_pk_add_f32 v[136:137], v[136:137], v[172:173] neg_lo:[0,1] neg_hi:[0,1]
	v_pk_mul_f32 v[6:7], v[4:5], v[2:3] op_sel:[1,0] op_sel_hi:[0,1]
	v_pk_mul_f32 v[172:173], v[136:137], s[36:37]
	v_pk_fma_f32 v[6:7], v[4:5], v[4:5], v[6:7] op_sel_hi:[1,0,1]
	v_pk_fma_f32 v[136:137], v[136:137], s[78:79], v[172:173] op_sel:[0,0,1] op_sel_hi:[1,0,0]
	v_pk_add_f32 v[172:173], v[138:139], v[174:175]
	v_pk_add_f32 v[138:139], v[138:139], v[174:175] neg_lo:[0,1] neg_hi:[0,1]
	v_xor_b32_e32 v12, 0x80000000, v7
	v_pk_mul_f32 v[174:175], v[138:139], s[38:39]
	v_mov_b32_e32 v13, v7
	v_pk_fma_f32 v[138:139], v[138:139], s[0:1], v[174:175] op_sel:[0,0,1] op_sel_hi:[1,0,0]
	s_waitcnt lgkmcnt(4)
	v_pk_add_f32 v[174:175], v[140:141], v[176:177]
	v_pk_add_f32 v[140:141], v[140:141], v[176:177] neg_lo:[0,1] neg_hi:[0,1]
	v_pk_mul_f32 v[10:11], v[6:7], v[12:13] op_sel:[1,0] op_sel_hi:[0,1]
	v_pk_mul_f32 v[176:177], v[140:141], s[40:41]
	v_pk_fma_f32 v[10:11], v[6:7], v[6:7], v[10:11] op_sel_hi:[1,0,1]
	v_pk_fma_f32 v[140:141], v[140:141], s[80:81], v[176:177] op_sel:[0,0,1] op_sel_hi:[1,0,0]
	v_pk_add_f32 v[176:177], v[142:143], v[178:179]
	v_pk_add_f32 v[142:143], v[142:143], v[178:179] neg_lo:[0,1] neg_hi:[0,1]
	v_xor_b32_e32 v14, 0x80000000, v11
	v_pk_mul_f32 v[178:179], v[142:143], s[42:43]
	v_mov_b32_e32 v15, v11
	v_pk_fma_f32 v[142:143], v[142:143], s[74:75], v[178:179] op_sel:[0,0,1] op_sel_hi:[1,0,0]
	s_waitcnt lgkmcnt(3)
	v_pk_add_f32 v[178:179], v[148:149], v[180:181]
	v_pk_add_f32 v[180:181], v[148:149], v[180:181] neg_lo:[0,1] neg_hi:[0,1]
	v_pk_mul_f32 v[28:29], v[10:11], v[14:15] op_sel:[1,0] op_sel_hi:[0,1]
	v_pk_add_f32 v[148:149], v[150:151], v[182:183]
	v_pk_add_f32 v[150:151], v[150:151], v[182:183] neg_lo:[0,1] neg_hi:[0,1]
	v_pk_fma_f32 v[28:29], v[10:11], v[10:11], v[28:29] op_sel_hi:[1,0,1]
	v_pk_mul_f32 v[182:183], v[150:151], s[42:43]
	v_pk_mul_f32 v[44:45], v[14:15], v[28:29] op_sel:[0,1] op_sel_hi:[1,0]
	v_pk_fma_f32 v[150:151], v[150:151], s[74:75], v[182:183] op_sel:[0,0,1] op_sel_hi:[1,0,0] neg_lo:[1,0,0] neg_hi:[1,0,0]
	s_waitcnt lgkmcnt(2)
	v_pk_add_f32 v[182:183], v[152:153], v[184:185]
	v_pk_add_f32 v[152:153], v[152:153], v[184:185] neg_lo:[0,1] neg_hi:[0,1]
	v_pk_fma_f32 v[44:45], v[10:11], v[28:29], v[44:45] op_sel_hi:[0,1,1]
	v_pk_mul_f32 v[184:185], v[152:153], s[40:41]
	v_pk_mul_f32 v[60:61], v[14:15], v[44:45] op_sel:[0,1] op_sel_hi:[1,0]
	v_pk_fma_f32 v[152:153], v[152:153], s[80:81], v[184:185] op_sel:[0,0,1] op_sel_hi:[1,0,0] neg_lo:[1,0,0] neg_hi:[1,0,0]
	v_pk_add_f32 v[184:185], v[154:155], v[186:187]
	v_pk_add_f32 v[154:155], v[154:155], v[186:187] neg_lo:[0,1] neg_hi:[0,1]
	v_pk_fma_f32 v[60:61], v[10:11], v[44:45], v[60:61] op_sel_hi:[0,1,1]
	v_pk_mul_f32 v[186:187], v[154:155], s[38:39]
	v_pk_mul_f32 v[76:77], v[14:15], v[60:61] op_sel:[0,1] op_sel_hi:[1,0]
	v_pk_fma_f32 v[154:155], v[154:155], s[0:1], v[186:187] op_sel:[0,0,1] op_sel_hi:[1,0,0] neg_lo:[1,0,0] neg_hi:[1,0,0]
	s_waitcnt lgkmcnt(1)
	v_pk_add_f32 v[186:187], v[156:157], v[188:189]
	v_pk_add_f32 v[156:157], v[156:157], v[188:189] neg_lo:[0,1] neg_hi:[0,1]
	v_pk_fma_f32 v[76:77], v[10:11], v[60:61], v[76:77] op_sel_hi:[0,1,1]
	v_pk_mul_f32 v[188:189], v[156:157], s[36:37]
	v_pk_mul_f32 v[92:93], v[14:15], v[76:77] op_sel:[0,1] op_sel_hi:[1,0]
	v_pk_fma_f32 v[156:157], v[156:157], s[78:79], v[188:189] op_sel:[0,0,1] op_sel_hi:[1,0,0] neg_lo:[1,0,0] neg_hi:[1,0,0]
	v_pk_add_f32 v[188:189], v[158:159], v[190:191]
	v_pk_add_f32 v[158:159], v[158:159], v[190:191] neg_lo:[0,1] neg_hi:[0,1]
	v_pk_fma_f32 v[92:93], v[10:11], v[76:77], v[92:93] op_sel_hi:[0,1,1]
	v_pk_mul_f32 v[190:191], v[158:159], s[26:27]
	v_pk_mul_f32 v[108:109], v[14:15], v[92:93] op_sel:[0,1] op_sel_hi:[1,0]
	v_pk_fma_f32 v[158:159], v[158:159], s[24:25], v[190:191] op_sel:[0,0,1] op_sel_hi:[1,0,0] neg_lo:[1,0,0] neg_hi:[1,0,0]
	s_waitcnt lgkmcnt(0)
	v_pk_add_f32 v[190:191], v[160:161], v[192:193]
	v_pk_add_f32 v[160:161], v[160:161], v[192:193] neg_lo:[0,1] neg_hi:[0,1]
	v_pk_mul_f32 v[8:9], v[2:3], v[6:7] op_sel:[0,1] op_sel_hi:[1,0]
	v_pk_mul_f32 v[192:193], v[160:161], s[18:19]
	v_pk_fma_f32 v[108:109], v[10:11], v[92:93], v[108:109] op_sel_hi:[0,1,1]
	v_pk_fma_f32 v[160:161], v[160:161], s[16:17], v[192:193] op_sel:[0,0,1] op_sel_hi:[1,0,0] neg_lo:[1,0,0] neg_hi:[1,0,0]
	v_pk_add_f32 v[192:193], v[162:163], v[194:195]
	v_pk_add_f32 v[162:163], v[162:163], v[194:195] neg_lo:[0,1] neg_hi:[0,1]
	v_pk_fma_f32 v[8:9], v[4:5], v[6:7], v[8:9] op_sel_hi:[0,1,1]
	v_pk_mul_f32 v[194:195], v[162:163], s[10:11]
	v_pk_mul_f32 v[16:17], v[2:3], v[10:11] op_sel:[0,1] op_sel_hi:[1,0]
	v_pk_fma_f32 v[162:163], v[162:163], s[8:9], v[194:195] op_sel:[0,0,1] op_sel_hi:[1,0,0] neg_lo:[1,0,0] neg_hi:[1,0,0]
	v_pk_add_f32 v[194:195], v[144:145], v[178:179]
	v_pk_add_f32 v[144:145], v[144:145], v[178:179] neg_lo:[0,1] neg_hi:[0,1]
	v_pk_add_f32 v[178:179], v[164:165], v[148:149]
	v_pk_add_f32 v[148:149], v[164:165], v[148:149] neg_lo:[0,1] neg_hi:[0,1]
	v_pk_mul_f32 v[32:33], v[2:3], v[28:29] op_sel:[0,1] op_sel_hi:[1,0]
	v_pk_mul_f32 v[164:165], v[148:149], s[18:19]
	v_pk_mul_f32 v[48:49], v[2:3], v[44:45] op_sel:[0,1] op_sel_hi:[1,0]
	v_pk_fma_f32 v[148:149], v[148:149], s[16:17], v[164:165] op_sel:[0,0,1] op_sel_hi:[1,0,0]
	v_pk_add_f32 v[164:165], v[166:167], v[182:183]
	v_pk_add_f32 v[166:167], v[166:167], v[182:183] neg_lo:[0,1] neg_hi:[0,1]
	v_pk_mul_f32 v[64:65], v[2:3], v[60:61] op_sel:[0,1] op_sel_hi:[1,0]
	v_pk_mul_f32 v[182:183], v[166:167], s[36:37]
	v_pk_mul_f32 v[80:81], v[2:3], v[76:77] op_sel:[0,1] op_sel_hi:[1,0]
	v_pk_fma_f32 v[166:167], v[166:167], s[78:79], v[182:183] op_sel:[0,0,1] op_sel_hi:[1,0,0]
	v_pk_add_f32 v[182:183], v[168:169], v[184:185]
	v_pk_add_f32 v[168:169], v[168:169], v[184:185] neg_lo:[0,1] neg_hi:[0,1]
	v_pk_mul_f32 v[96:97], v[2:3], v[92:93] op_sel:[0,1] op_sel_hi:[1,0]
	v_pk_mul_f32 v[184:185], v[168:169], s[40:41]
	v_pk_mul_f32 v[112:113], v[2:3], v[108:109] op_sel:[0,1] op_sel_hi:[1,0]
	v_pk_fma_f32 v[168:169], v[168:169], s[80:81], v[184:185] op_sel:[0,0,1] op_sel_hi:[1,0,0]
	v_pk_add_f32 v[184:185], v[170:171], v[186:187]
	v_pk_add_f32 v[186:187], v[170:171], v[186:187] neg_lo:[0,1] neg_hi:[0,1]
	v_xor_b32_e32 v22, 0x80000000, v9
	v_pk_add_f32 v[170:171], v[172:173], v[188:189]
	v_pk_add_f32 v[172:173], v[172:173], v[188:189] neg_lo:[0,1] neg_hi:[0,1]
	v_mov_b32_e32 v23, v9
	v_pk_mul_f32 v[188:189], v[172:173], s[40:41]
	v_pk_fma_f32 v[16:17], v[4:5], v[10:11], v[16:17] op_sel_hi:[0,1,1]
	v_pk_fma_f32 v[172:173], v[172:173], s[80:81], v[188:189] op_sel:[0,0,1] op_sel_hi:[1,0,0] neg_lo:[1,0,0] neg_hi:[1,0,0]
	v_pk_add_f32 v[188:189], v[174:175], v[190:191]
	v_pk_add_f32 v[174:175], v[174:175], v[190:191] neg_lo:[0,1] neg_hi:[0,1]
	v_pk_mul_f32 v[20:21], v[12:13], v[10:11] op_sel:[0,1] op_sel_hi:[1,0]
	v_pk_mul_f32 v[190:191], v[174:175], s[36:37]
	v_pk_fma_f32 v[32:33], v[4:5], v[28:29], v[32:33] op_sel_hi:[0,1,1]
	v_pk_fma_f32 v[174:175], v[174:175], s[78:79], v[190:191] op_sel:[0,0,1] op_sel_hi:[1,0,0] neg_lo:[1,0,0] neg_hi:[1,0,0]
	v_pk_add_f32 v[190:191], v[176:177], v[192:193]
	v_pk_add_f32 v[176:177], v[176:177], v[192:193] neg_lo:[0,1] neg_hi:[0,1]
	v_pk_mul_f32 v[36:37], v[12:13], v[28:29] op_sel:[0,1] op_sel_hi:[1,0]
	v_pk_mul_f32 v[192:193], v[176:177], s[18:19]
	v_pk_fma_f32 v[48:49], v[4:5], v[44:45], v[48:49] op_sel_hi:[0,1,1]
	v_pk_fma_f32 v[176:177], v[176:177], s[16:17], v[192:193] op_sel:[0,0,1] op_sel_hi:[1,0,0] neg_lo:[1,0,0] neg_hi:[1,0,0]
	v_pk_add_f32 v[192:193], v[128:129], v[180:181] op_sel:[0,1] op_sel_hi:[1,0] neg_hi:[0,1]
	v_pk_add_f32 v[128:129], v[128:129], v[180:181] op_sel:[0,1] op_sel_hi:[1,0] neg_lo:[0,1]
	v_pk_add_f32 v[180:181], v[130:131], v[150:151]
	v_pk_add_f32 v[130:131], v[130:131], v[150:151] neg_lo:[0,1] neg_hi:[0,1]
	v_pk_mul_f32 v[52:53], v[12:13], v[44:45] op_sel:[0,1] op_sel_hi:[1,0]
	v_pk_mul_f32 v[150:151], v[130:131], s[18:19]
	v_pk_fma_f32 v[64:65], v[4:5], v[60:61], v[64:65] op_sel_hi:[0,1,1]
	v_pk_fma_f32 v[130:131], v[130:131], s[16:17], v[150:151] op_sel:[0,0,1] op_sel_hi:[1,0,0]
	v_pk_add_f32 v[150:151], v[132:133], v[152:153]
	v_pk_add_f32 v[132:133], v[132:133], v[152:153] neg_lo:[0,1] neg_hi:[0,1]
	v_pk_mul_f32 v[68:69], v[12:13], v[60:61] op_sel:[0,1] op_sel_hi:[1,0]
	v_pk_mul_f32 v[152:153], v[132:133], s[36:37]
	v_pk_fma_f32 v[80:81], v[4:5], v[76:77], v[80:81] op_sel_hi:[0,1,1]
	v_pk_fma_f32 v[132:133], v[132:133], s[78:79], v[152:153] op_sel:[0,0,1] op_sel_hi:[1,0,0]
	v_pk_add_f32 v[152:153], v[134:135], v[154:155]
	v_pk_add_f32 v[134:135], v[134:135], v[154:155] neg_lo:[0,1] neg_hi:[0,1]
	v_pk_mul_f32 v[84:85], v[12:13], v[76:77] op_sel:[0,1] op_sel_hi:[1,0]
	v_pk_mul_f32 v[154:155], v[134:135], s[40:41]
	v_pk_fma_f32 v[96:97], v[4:5], v[92:93], v[96:97] op_sel_hi:[0,1,1]
	v_pk_fma_f32 v[134:135], v[134:135], s[80:81], v[154:155] op_sel:[0,0,1] op_sel_hi:[1,0,0]
	v_pk_add_f32 v[154:155], v[136:137], v[156:157]
	v_pk_add_f32 v[156:157], v[136:137], v[156:157] neg_lo:[0,1] neg_hi:[0,1]
	v_pk_mul_f32 v[100:101], v[12:13], v[92:93] op_sel:[0,1] op_sel_hi:[1,0]
	v_pk_add_f32 v[136:137], v[138:139], v[158:159]
	v_pk_add_f32 v[138:139], v[138:139], v[158:159] neg_lo:[0,1] neg_hi:[0,1]
	v_pk_fma_f32 v[112:113], v[4:5], v[108:109], v[112:113] op_sel_hi:[0,1,1]
	v_pk_mul_f32 v[158:159], v[138:139], s[40:41]
	v_pk_mul_f32 v[116:117], v[12:13], v[108:109] op_sel:[0,1] op_sel_hi:[1,0]
	v_pk_fma_f32 v[138:139], v[138:139], s[80:81], v[158:159] op_sel:[0,0,1] op_sel_hi:[1,0,0] neg_lo:[1,0,0] neg_hi:[1,0,0]
	v_pk_add_f32 v[158:159], v[140:141], v[160:161]
	v_pk_add_f32 v[140:141], v[140:141], v[160:161] neg_lo:[0,1] neg_hi:[0,1]
	v_pk_fma_f32 v[20:21], v[6:7], v[10:11], v[20:21] op_sel_hi:[0,1,1]
	v_pk_mul_f32 v[160:161], v[140:141], s[36:37]
	v_pk_mul_f32 v[24:25], v[10:11], v[22:23] op_sel:[1,0] op_sel_hi:[0,1]
	v_pk_fma_f32 v[140:141], v[140:141], s[78:79], v[160:161] op_sel:[0,0,1] op_sel_hi:[1,0,0] neg_lo:[1,0,0] neg_hi:[1,0,0]
	v_pk_add_f32 v[160:161], v[142:143], v[162:163]
	v_pk_add_f32 v[142:143], v[142:143], v[162:163] neg_lo:[0,1] neg_hi:[0,1]
	v_pk_fma_f32 v[36:37], v[6:7], v[28:29], v[36:37] op_sel_hi:[0,1,1]
	v_pk_mul_f32 v[162:163], v[142:143], s[18:19]
	v_pk_mul_f32 v[40:41], v[22:23], v[28:29] op_sel:[0,1] op_sel_hi:[1,0]
	v_pk_fma_f32 v[142:143], v[142:143], s[16:17], v[162:163] op_sel:[0,0,1] op_sel_hi:[1,0,0] neg_lo:[1,0,0] neg_hi:[1,0,0]
	v_pk_add_f32 v[162:163], v[194:195], v[184:185]
	v_pk_add_f32 v[184:185], v[194:195], v[184:185] neg_lo:[0,1] neg_hi:[0,1]
	v_pk_add_f32 v[194:195], v[178:179], v[170:171]
	v_pk_add_f32 v[170:171], v[178:179], v[170:171] neg_lo:[0,1] neg_hi:[0,1]
	v_pk_fma_f32 v[52:53], v[6:7], v[44:45], v[52:53] op_sel_hi:[0,1,1]
	v_pk_mul_f32 v[178:179], v[170:171], s[36:37]
	v_pk_mul_f32 v[56:57], v[22:23], v[44:45] op_sel:[0,1] op_sel_hi:[1,0]
	v_pk_fma_f32 v[170:171], v[170:171], s[78:79], v[178:179] op_sel:[0,0,1] op_sel_hi:[1,0,0]
	v_pk_add_f32 v[178:179], v[164:165], v[188:189]
	v_pk_add_f32 v[188:189], v[164:165], v[188:189] neg_lo:[0,1] neg_hi:[0,1]
	v_pk_fma_f32 v[68:69], v[6:7], v[60:61], v[68:69] op_sel_hi:[0,1,1]
	v_pk_add_f32 v[164:165], v[182:183], v[190:191]
	v_pk_add_f32 v[182:183], v[182:183], v[190:191] neg_lo:[0,1] neg_hi:[0,1]
	v_pk_mul_f32 v[72:73], v[22:23], v[60:61] op_sel:[0,1] op_sel_hi:[1,0]
	v_pk_mul_f32 v[190:191], v[182:183], s[36:37]
	v_pk_fma_f32 v[84:85], v[6:7], v[76:77], v[84:85] op_sel_hi:[0,1,1]
	v_pk_fma_f32 v[182:183], v[182:183], s[78:79], v[190:191] op_sel:[0,0,1] op_sel_hi:[1,0,0] neg_lo:[1,0,0] neg_hi:[1,0,0]
	v_pk_add_f32 v[190:191], v[144:145], v[186:187] op_sel:[0,1] op_sel_hi:[1,0] neg_hi:[0,1]
	v_pk_add_f32 v[144:145], v[144:145], v[186:187] op_sel:[0,1] op_sel_hi:[1,0] neg_lo:[0,1]
	v_pk_add_f32 v[186:187], v[148:149], v[172:173]
	v_pk_add_f32 v[148:149], v[148:149], v[172:173] neg_lo:[0,1] neg_hi:[0,1]
	v_pk_mul_f32 v[88:89], v[22:23], v[76:77] op_sel:[0,1] op_sel_hi:[1,0]
	v_pk_mul_f32 v[172:173], v[148:149], s[36:37]
	v_pk_fma_f32 v[100:101], v[6:7], v[92:93], v[100:101] op_sel_hi:[0,1,1]
	v_pk_fma_f32 v[148:149], v[148:149], s[78:79], v[172:173] op_sel:[0,0,1] op_sel_hi:[1,0,0]
	v_pk_add_f32 v[172:173], v[166:167], v[174:175]
	v_pk_add_f32 v[174:175], v[166:167], v[174:175] neg_lo:[0,1] neg_hi:[0,1]
	v_pk_mul_f32 v[104:105], v[22:23], v[92:93] op_sel:[0,1] op_sel_hi:[1,0]
	v_pk_add_f32 v[166:167], v[168:169], v[176:177]
	v_pk_add_f32 v[168:169], v[168:169], v[176:177] neg_lo:[0,1] neg_hi:[0,1]
	v_pk_fma_f32 v[116:117], v[6:7], v[108:109], v[116:117] op_sel_hi:[0,1,1]
	v_pk_mul_f32 v[176:177], v[168:169], s[36:37]
	v_pk_mul_f32 v[120:121], v[22:23], v[108:109] op_sel:[0,1] op_sel_hi:[1,0]
	v_pk_fma_f32 v[168:169], v[168:169], s[78:79], v[176:177] op_sel:[0,0,1] op_sel_hi:[1,0,0] neg_lo:[1,0,0] neg_hi:[1,0,0]
	v_pk_add_f32 v[176:177], v[192:193], v[154:155]
	v_pk_add_f32 v[154:155], v[192:193], v[154:155] neg_lo:[0,1] neg_hi:[0,1]
	v_pk_add_f32 v[192:193], v[180:181], v[136:137]
	v_pk_add_f32 v[136:137], v[180:181], v[136:137] neg_lo:[0,1] neg_hi:[0,1]
	v_xor_b32_e32 v26, 0x80000000, v17
	v_pk_mul_f32 v[180:181], v[136:137], s[36:37]
	v_xor_b32_e32 v30, 0x80000000, v21
	v_pk_fma_f32 v[136:137], v[136:137], s[78:79], v[180:181] op_sel:[0,0,1] op_sel_hi:[1,0,0]
	v_pk_add_f32 v[180:181], v[150:151], v[158:159]
	v_pk_add_f32 v[158:159], v[150:151], v[158:159] neg_lo:[0,1] neg_hi:[0,1]
	v_pk_fma_f32 v[24:25], v[10:11], v[8:9], v[24:25] op_sel_hi:[1,0,1]
	v_pk_add_f32 v[150:151], v[152:153], v[160:161]
	v_pk_add_f32 v[152:153], v[152:153], v[160:161] neg_lo:[0,1] neg_hi:[0,1]
	v_pk_fma_f32 v[40:41], v[8:9], v[28:29], v[40:41] op_sel_hi:[0,1,1]
	v_pk_mul_f32 v[160:161], v[152:153], s[36:37]
	v_pk_fma_f32 v[56:57], v[8:9], v[44:45], v[56:57] op_sel_hi:[0,1,1]
	v_pk_fma_f32 v[152:153], v[152:153], s[78:79], v[160:161] op_sel:[0,0,1] op_sel_hi:[1,0,0] neg_lo:[1,0,0] neg_hi:[1,0,0]
	v_pk_add_f32 v[160:161], v[128:129], v[156:157] op_sel:[0,1] op_sel_hi:[1,0] neg_hi:[0,1]
	v_pk_add_f32 v[128:129], v[128:129], v[156:157] op_sel:[0,1] op_sel_hi:[1,0] neg_lo:[0,1]
	v_pk_add_f32 v[156:157], v[130:131], v[138:139]
	v_pk_add_f32 v[130:131], v[130:131], v[138:139] neg_lo:[0,1] neg_hi:[0,1]
	v_pk_fma_f32 v[72:73], v[8:9], v[60:61], v[72:73] op_sel_hi:[0,1,1]
	v_pk_mul_f32 v[138:139], v[130:131], s[36:37]
	v_pk_fma_f32 v[88:89], v[8:9], v[76:77], v[88:89] op_sel_hi:[0,1,1]
	v_pk_fma_f32 v[130:131], v[130:131], s[78:79], v[138:139] op_sel:[0,0,1] op_sel_hi:[1,0,0]
	v_pk_add_f32 v[138:139], v[132:133], v[140:141]
	v_pk_add_f32 v[140:141], v[132:133], v[140:141] neg_lo:[0,1] neg_hi:[0,1]
	v_pk_fma_f32 v[104:105], v[8:9], v[92:93], v[104:105] op_sel_hi:[0,1,1]
	v_pk_add_f32 v[132:133], v[134:135], v[142:143]
	v_pk_add_f32 v[134:135], v[134:135], v[142:143] neg_lo:[0,1] neg_hi:[0,1]
	v_pk_fma_f32 v[120:121], v[8:9], v[108:109], v[120:121] op_sel_hi:[0,1,1]
	v_pk_mul_f32 v[142:143], v[134:135], s[36:37]
	v_mov_b32_e32 v27, v17
	v_pk_fma_f32 v[134:135], v[134:135], s[78:79], v[142:143] op_sel:[0,0,1] op_sel_hi:[1,0,0] neg_lo:[1,0,0] neg_hi:[1,0,0]
	v_pk_add_f32 v[142:143], v[162:163], v[178:179]
	v_pk_add_f32 v[162:163], v[162:163], v[178:179] neg_lo:[0,1] neg_hi:[0,1]
	v_pk_add_f32 v[178:179], v[194:195], v[164:165]
	v_pk_add_f32 v[194:195], v[194:195], v[164:165] neg_lo:[0,1] neg_hi:[0,1]
	v_mov_b32_e32 v31, v21
	v_pk_add_f32 v[164:165], v[184:185], v[188:189] op_sel:[0,1] op_sel_hi:[1,0] neg_hi:[0,1]
	v_pk_add_f32 v[184:185], v[184:185], v[188:189] op_sel:[0,1] op_sel_hi:[1,0] neg_lo:[0,1]
	v_pk_add_f32 v[188:189], v[170:171], v[182:183]
	v_pk_add_f32 v[182:183], v[170:171], v[182:183] neg_lo:[0,1] neg_hi:[0,1]
	v_xor_b32_e32 v34, 0x80000000, v25
	v_pk_add_f32 v[170:171], v[190:191], v[172:173]
	v_pk_add_f32 v[172:173], v[190:191], v[172:173] neg_lo:[0,1] neg_hi:[0,1]
	v_pk_add_f32 v[190:191], v[186:187], v[166:167]
	v_pk_add_f32 v[186:187], v[186:187], v[166:167] neg_lo:[0,1] neg_hi:[0,1]
	v_xor_b32_e32 v38, 0x80000000, v29
	v_pk_add_f32 v[166:167], v[144:145], v[174:175] op_sel:[0,1] op_sel_hi:[1,0] neg_hi:[0,1]
	v_pk_add_f32 v[144:145], v[144:145], v[174:175] op_sel:[0,1] op_sel_hi:[1,0] neg_lo:[0,1]
	v_pk_add_f32 v[174:175], v[148:149], v[168:169]
	v_pk_add_f32 v[168:169], v[148:149], v[168:169] neg_lo:[0,1] neg_hi:[0,1]
	v_xor_b32_e32 v42, 0x80000000, v33
	v_pk_add_f32 v[148:149], v[176:177], v[180:181]
	v_pk_add_f32 v[176:177], v[176:177], v[180:181] neg_lo:[0,1] neg_hi:[0,1]
	v_pk_add_f32 v[180:181], v[192:193], v[150:151]
	v_pk_add_f32 v[192:193], v[192:193], v[150:151] neg_lo:[0,1] neg_hi:[0,1]
	v_xor_b32_e32 v46, 0x80000000, v37
	v_pk_add_f32 v[150:151], v[154:155], v[158:159] op_sel:[0,1] op_sel_hi:[1,0] neg_hi:[0,1]
	v_pk_add_f32 v[154:155], v[154:155], v[158:159] op_sel:[0,1] op_sel_hi:[1,0] neg_lo:[0,1]
	v_pk_add_f32 v[158:159], v[136:137], v[152:153]
	v_pk_add_f32 v[152:153], v[136:137], v[152:153] neg_lo:[0,1] neg_hi:[0,1]
	v_mov_b32_e32 v35, v25
	v_pk_add_f32 v[136:137], v[160:161], v[138:139]
	v_pk_add_f32 v[138:139], v[160:161], v[138:139] neg_lo:[0,1] neg_hi:[0,1]
	v_pk_add_f32 v[160:161], v[156:157], v[132:133]
	v_pk_add_f32 v[156:157], v[156:157], v[132:133] neg_lo:[0,1] neg_hi:[0,1]
	v_mov_b32_e32 v39, v29
	v_pk_add_f32 v[132:133], v[128:129], v[140:141] op_sel:[0,1] op_sel_hi:[1,0] neg_hi:[0,1]
	v_pk_add_f32 v[128:129], v[128:129], v[140:141] op_sel:[0,1] op_sel_hi:[1,0] neg_lo:[0,1]
	v_pk_add_f32 v[140:141], v[130:131], v[134:135]
	v_pk_add_f32 v[134:135], v[130:131], v[134:135] neg_lo:[0,1] neg_hi:[0,1]
	v_mov_b32_e32 v43, v33
	v_pk_add_f32 v[130:131], v[142:143], v[178:179]
	v_pk_add_f32 v[142:143], v[142:143], v[178:179] neg_lo:[0,1] neg_hi:[0,1]
	v_pk_add_f32 v[178:179], v[162:163], v[194:195] op_sel:[0,1] op_sel_hi:[1,0] neg_hi:[0,1]
	v_pk_add_f32 v[162:163], v[162:163], v[194:195] op_sel:[0,1] op_sel_hi:[1,0] neg_lo:[0,1]
	v_pk_add_f32 v[194:195], v[164:165], v[188:189]
	v_pk_add_f32 v[164:165], v[164:165], v[188:189] neg_lo:[0,1] neg_hi:[0,1]
	v_pk_add_f32 v[188:189], v[184:185], v[182:183] op_sel:[0,1] op_sel_hi:[1,0] neg_hi:[0,1]
	v_pk_add_f32 v[182:183], v[184:185], v[182:183] op_sel:[0,1] op_sel_hi:[1,0] neg_lo:[0,1]
	v_pk_add_f32 v[184:185], v[170:171], v[190:191]
	v_pk_add_f32 v[170:171], v[170:171], v[190:191] neg_lo:[0,1] neg_hi:[0,1]
	v_pk_add_f32 v[190:191], v[172:173], v[186:187] op_sel:[0,1] op_sel_hi:[1,0] neg_hi:[0,1]
	v_pk_add_f32 v[172:173], v[172:173], v[186:187] op_sel:[0,1] op_sel_hi:[1,0] neg_lo:[0,1]
	v_pk_add_f32 v[186:187], v[166:167], v[174:175]
	v_pk_add_f32 v[166:167], v[166:167], v[174:175] neg_lo:[0,1] neg_hi:[0,1]
	v_pk_add_f32 v[174:175], v[144:145], v[168:169] op_sel:[0,1] op_sel_hi:[1,0] neg_hi:[0,1]
	v_pk_add_f32 v[144:145], v[144:145], v[168:169] op_sel:[0,1] op_sel_hi:[1,0] neg_lo:[0,1]
	v_pk_add_f32 v[168:169], v[148:149], v[180:181]
	v_pk_add_f32 v[148:149], v[148:149], v[180:181] neg_lo:[0,1] neg_hi:[0,1]
	v_pk_mul_f32 v[2:3], v[2:3], v[168:169] op_sel:[0,1] op_sel_hi:[1,0]
	v_pk_add_f32 v[180:181], v[176:177], v[192:193] op_sel:[0,1] op_sel_hi:[1,0] neg_hi:[0,1]
	v_pk_add_f32 v[176:177], v[176:177], v[192:193] op_sel:[0,1] op_sel_hi:[1,0] neg_lo:[0,1]
	v_pk_add_f32 v[192:193], v[150:151], v[158:159]
	v_pk_add_f32 v[150:151], v[150:151], v[158:159] neg_lo:[0,1] neg_hi:[0,1]
	v_pk_add_f32 v[158:159], v[154:155], v[152:153] op_sel:[0,1] op_sel_hi:[1,0] neg_hi:[0,1]
	v_pk_add_f32 v[152:153], v[154:155], v[152:153] op_sel:[0,1] op_sel_hi:[1,0] neg_lo:[0,1]
	v_pk_add_f32 v[154:155], v[136:137], v[160:161]
	v_pk_fma_f32 v[2:3], v[4:5], v[168:169], v[2:3] op_sel_hi:[0,1,1]
	v_pk_mul_f32 v[4:5], v[12:13], v[184:185] op_sel:[0,1] op_sel_hi:[1,0]
	v_mov_b32_e32 v47, v37
	v_pk_fma_f32 v[4:5], v[6:7], v[184:185], v[4:5] op_sel_hi:[0,1,1]
	v_pk_mul_f32 v[6:7], v[22:23], v[154:155] op_sel:[0,1] op_sel_hi:[1,0]
	v_pk_add_f32 v[136:137], v[136:137], v[160:161] neg_lo:[0,1] neg_hi:[0,1]
	v_pk_fma_f32 v[6:7], v[8:9], v[154:155], v[6:7] op_sel_hi:[0,1,1]
	v_pk_mul_f32 v[8:9], v[14:15], v[194:195] op_sel:[0,1] op_sel_hi:[1,0]
	v_pk_add_f32 v[160:161], v[138:139], v[156:157] op_sel:[0,1] op_sel_hi:[1,0] neg_hi:[0,1]
	v_pk_add_f32 v[138:139], v[138:139], v[156:157] op_sel:[0,1] op_sel_hi:[1,0] neg_lo:[0,1]
	v_pk_add_f32 v[156:157], v[132:133], v[140:141]
	v_pk_fma_f32 v[8:9], v[10:11], v[194:195], v[8:9] op_sel_hi:[0,1,1]
	v_pk_mul_f32 v[10:11], v[26:27], v[192:193] op_sel:[0,1] op_sel_hi:[1,0]
	v_pk_mul_f32 v[12:13], v[30:31], v[186:187] op_sel:[0,1] op_sel_hi:[1,0]
	v_xor_b32_e32 v50, 0x80000000, v41
	v_xor_b32_e32 v54, 0x80000000, v45
	v_xor_b32_e32 v58, 0x80000000, v49
	v_xor_b32_e32 v62, 0x80000000, v53
	v_xor_b32_e32 v66, 0x80000000, v57
	v_xor_b32_e32 v70, 0x80000000, v61
	v_xor_b32_e32 v74, 0x80000000, v65
	v_mov_b32_e32 v51, v41
	v_mov_b32_e32 v55, v45
	v_mov_b32_e32 v59, v49
	v_mov_b32_e32 v63, v53
	v_mov_b32_e32 v67, v57
	v_mov_b32_e32 v71, v61
	v_mov_b32_e32 v75, v65
	v_pk_add_f32 v[132:133], v[132:133], v[140:141] neg_lo:[0,1] neg_hi:[0,1]
	v_pk_add_f32 v[140:141], v[128:129], v[134:135] op_sel:[0,1] op_sel_hi:[1,0] neg_hi:[0,1]
	v_pk_fma_f32 v[10:11], v[16:17], v[192:193], v[10:11] op_sel_hi:[0,1,1]
	v_pk_fma_f32 v[12:13], v[20:21], v[186:187], v[12:13] op_sel_hi:[0,1,1]
	v_pk_mul_f32 v[14:15], v[34:35], v[156:157] op_sel:[0,1] op_sel_hi:[1,0]
	v_pk_mul_f32 v[16:17], v[38:39], v[178:179] op_sel:[0,1] op_sel_hi:[1,0]
	v_pk_mul_f32 v[20:21], v[42:43], v[180:181] op_sel:[0,1] op_sel_hi:[1,0]
	v_pk_mul_f32 v[22:23], v[46:47], v[190:191] op_sel:[0,1] op_sel_hi:[1,0]
	v_xor_b32_e32 v78, 0x80000000, v69
	v_xor_b32_e32 v82, 0x80000000, v73
	v_xor_b32_e32 v86, 0x80000000, v77
	v_xor_b32_e32 v90, 0x80000000, v81
	v_xor_b32_e32 v94, 0x80000000, v85
	v_xor_b32_e32 v98, 0x80000000, v89
	v_xor_b32_e32 v102, 0x80000000, v93
	v_xor_b32_e32 v106, 0x80000000, v97
	v_xor_b32_e32 v110, 0x80000000, v101
	v_xor_b32_e32 v114, 0x80000000, v105
	v_xor_b32_e32 v118, 0x80000000, v109
	v_xor_b32_e32 v122, 0x80000000, v113
	v_xor_b32_e32 v124, 0x80000000, v117
	v_xor_b32_e32 v126, 0x80000000, v121
	v_mov_b32_e32 v79, v69
	v_mov_b32_e32 v83, v73
	v_mov_b32_e32 v87, v77
	v_mov_b32_e32 v91, v81
	v_mov_b32_e32 v95, v85
	v_mov_b32_e32 v99, v89
	v_mov_b32_e32 v103, v93
	v_mov_b32_e32 v107, v97
	v_mov_b32_e32 v111, v101
	v_mov_b32_e32 v115, v105
	v_mov_b32_e32 v119, v109
	v_mov_b32_e32 v123, v113
	v_mov_b32_e32 v125, v117
	v_mov_b32_e32 v127, v121
	v_pk_add_f32 v[128:129], v[128:129], v[134:135] op_sel:[0,1] op_sel_hi:[1,0] neg_lo:[0,1]
	v_pk_fma_f32 v[14:15], v[24:25], v[156:157], v[14:15] op_sel_hi:[0,1,1]
	v_pk_fma_f32 v[16:17], v[28:29], v[178:179], v[16:17] op_sel_hi:[0,1,1]
	v_pk_fma_f32 v[20:21], v[32:33], v[180:181], v[20:21] op_sel_hi:[0,1,1]
	v_pk_fma_f32 v[22:23], v[36:37], v[190:191], v[22:23] op_sel_hi:[0,1,1]
	v_pk_mul_f32 v[24:25], v[50:51], v[160:161] op_sel:[0,1] op_sel_hi:[1,0]
	v_pk_mul_f32 v[26:27], v[54:55], v[188:189] op_sel:[0,1] op_sel_hi:[1,0]
	v_pk_mul_f32 v[28:29], v[58:59], v[158:159] op_sel:[0,1] op_sel_hi:[1,0]
	v_pk_mul_f32 v[30:31], v[62:63], v[174:175] op_sel:[0,1] op_sel_hi:[1,0]
	v_pk_mul_f32 v[32:33], v[66:67], v[140:141] op_sel:[0,1] op_sel_hi:[1,0]
	v_pk_mul_f32 v[34:35], v[70:71], v[142:143] op_sel:[0,1] op_sel_hi:[1,0]
	v_pk_mul_f32 v[36:37], v[74:75], v[148:149] op_sel:[0,1] op_sel_hi:[1,0]
	v_pk_fma_f32 v[24:25], v[40:41], v[160:161], v[24:25] op_sel_hi:[0,1,1]
	v_pk_fma_f32 v[26:27], v[44:45], v[188:189], v[26:27] op_sel_hi:[0,1,1]
	v_pk_fma_f32 v[28:29], v[48:49], v[158:159], v[28:29] op_sel_hi:[0,1,1]
	v_pk_fma_f32 v[30:31], v[52:53], v[174:175], v[30:31] op_sel_hi:[0,1,1]
	v_pk_fma_f32 v[32:33], v[56:57], v[140:141], v[32:33] op_sel_hi:[0,1,1]
	v_pk_fma_f32 v[34:35], v[60:61], v[142:143], v[34:35] op_sel_hi:[0,1,1]
	v_pk_fma_f32 v[36:37], v[64:65], v[148:149], v[36:37] op_sel_hi:[0,1,1]
	v_pk_mul_f32 v[38:39], v[78:79], v[170:171] op_sel:[0,1] op_sel_hi:[1,0]
	v_pk_mul_f32 v[40:41], v[82:83], v[136:137] op_sel:[0,1] op_sel_hi:[1,0]
	v_pk_mul_f32 v[42:43], v[86:87], v[164:165] op_sel:[0,1] op_sel_hi:[1,0]
	v_pk_mul_f32 v[44:45], v[90:91], v[150:151] op_sel:[0,1] op_sel_hi:[1,0]
	v_pk_mul_f32 v[46:47], v[94:95], v[166:167] op_sel:[0,1] op_sel_hi:[1,0]
	v_pk_mul_f32 v[48:49], v[98:99], v[132:133] op_sel:[0,1] op_sel_hi:[1,0]
	v_pk_mul_f32 v[50:51], v[102:103], v[162:163] op_sel:[0,1] op_sel_hi:[1,0]
	v_pk_mul_f32 v[52:53], v[106:107], v[176:177] op_sel:[0,1] op_sel_hi:[1,0]
	v_pk_mul_f32 v[54:55], v[110:111], v[172:173] op_sel:[0,1] op_sel_hi:[1,0]
	v_pk_mul_f32 v[56:57], v[114:115], v[138:139] op_sel:[0,1] op_sel_hi:[1,0]
	v_pk_mul_f32 v[58:59], v[118:119], v[182:183] op_sel:[0,1] op_sel_hi:[1,0]
	v_pk_mul_f32 v[60:61], v[122:123], v[152:153] op_sel:[0,1] op_sel_hi:[1,0]
	v_pk_mul_f32 v[62:63], v[124:125], v[144:145] op_sel:[0,1] op_sel_hi:[1,0]
	v_pk_mul_f32 v[64:65], v[126:127], v[128:129] op_sel:[0,1] op_sel_hi:[1,0]
	v_pk_fma_f32 v[38:39], v[68:69], v[170:171], v[38:39] op_sel_hi:[0,1,1]
	v_pk_fma_f32 v[40:41], v[72:73], v[136:137], v[40:41] op_sel_hi:[0,1,1]
	v_pk_fma_f32 v[42:43], v[76:77], v[164:165], v[42:43] op_sel_hi:[0,1,1]
	v_pk_fma_f32 v[44:45], v[80:81], v[150:151], v[44:45] op_sel_hi:[0,1,1]
	v_pk_fma_f32 v[46:47], v[84:85], v[166:167], v[46:47] op_sel_hi:[0,1,1]
	v_pk_fma_f32 v[48:49], v[88:89], v[132:133], v[48:49] op_sel_hi:[0,1,1]
	v_pk_fma_f32 v[50:51], v[92:93], v[162:163], v[50:51] op_sel_hi:[0,1,1]
	v_pk_fma_f32 v[52:53], v[96:97], v[176:177], v[52:53] op_sel_hi:[0,1,1]
	v_pk_fma_f32 v[54:55], v[100:101], v[172:173], v[54:55] op_sel_hi:[0,1,1]
	v_pk_fma_f32 v[56:57], v[104:105], v[138:139], v[56:57] op_sel_hi:[0,1,1]
	v_pk_fma_f32 v[58:59], v[108:109], v[182:183], v[58:59] op_sel_hi:[0,1,1]
	v_pk_fma_f32 v[60:61], v[112:113], v[152:153], v[60:61] op_sel_hi:[0,1,1]
	v_pk_fma_f32 v[62:63], v[116:117], v[144:145], v[62:63] op_sel_hi:[0,1,1]
	v_pk_fma_f32 v[64:65], v[120:121], v[128:129], v[64:65] op_sel_hi:[0,1,1]
	ds_write2_b64 v18, v[130:131], v[34:35] offset1:16
	ds_write2_b64 v18, v[16:17], v[50:51] offset0:33 offset1:49
	ds_write2_b64 v18, v[8:9], v[42:43] offset0:66 offset1:82
	ds_write2_b64 v18, v[26:27], v[58:59] offset0:99 offset1:115
	ds_write2_b64 v18, v[4:5], v[38:39] offset0:132 offset1:148
	ds_write2_b64 v18, v[22:23], v[54:55] offset0:165 offset1:181
	ds_write2_b64 v18, v[12:13], v[46:47] offset0:198 offset1:214
	ds_write2_b64 v18, v[30:31], v[62:63] offset0:231 offset1:247
	ds_write2_b64 v196, v[2:3], v[36:37] offset0:8 offset1:24
	ds_write2_b64 v196, v[20:21], v[52:53] offset0:41 offset1:57
	ds_write2_b64 v196, v[10:11], v[44:45] offset0:74 offset1:90
	ds_write2_b64 v196, v[28:29], v[60:61] offset0:107 offset1:123
	ds_write2_b64 v196, v[6:7], v[40:41] offset0:140 offset1:156
	ds_write2_b64 v196, v[24:25], v[56:57] offset0:173 offset1:189
	ds_write2_b64 v196, v[14:15], v[48:49] offset0:206 offset1:222
	ds_write2_b64 v196, v[32:33], v[64:65] offset0:239 offset1:255
	v_ashrrev_i32_e32 v2, 31, v210
	v_lshrrev_b32_e32 v2, 23, v2
	v_add_u32_e32 v2, v210, v2
	s_lshl_b64 s[74:75], s[76:77], 16
	v_and_b32_e32 v2, 0xfffffe00, v2
	s_add_u32 s0, s54, s74
	v_sub_u32_e32 v2, v210, v2
	s_addc_u32 s1, s55, s75
	v_ashrrev_i32_e32 v3, 31, v2
	v_lshl_add_u64 v[14:15], v[2:3], 3, s[0:1]
	v_add_co_u32_e32 v2, vcc, s92, v14
	s_mov_b32 s0, 0x8000
	s_nop 0
	v_addc_co_u32_e32 v3, vcc, 0, v15, vcc
	v_add_co_u32_e32 v4, vcc, s95, v14
	s_waitcnt lgkmcnt(0)
	s_nop 0
	v_addc_co_u32_e32 v5, vcc, 0, v15, vcc
	v_add_co_u32_e32 v8, vcc, s96, v14
	s_barrier
	s_nop 0
	v_addc_co_u32_e32 v9, vcc, 0, v15, vcc
	global_load_dwordx2 v[24:25], v[4:5], off offset:-4096 nt
	global_load_dwordx2 v[12:13], v[4:5], off nt
	global_load_dwordx2 v[6:7], v[8:9], off offset:-4096 nt
	s_nop 0
	global_load_dwordx2 v[4:5], v[8:9], off nt
	v_add_co_u32_e32 v8, vcc, s0, v14
	s_waitcnt vmcnt(3)
	v_cvt_f32_f16_sdwa v174, v24 dst_sel:DWORD dst_unused:UNUSED_PAD src0_sel:WORD_1
	v_addc_co_u32_e32 v9, vcc, 0, v15, vcc
	v_add_co_u32_e32 v10, vcc, s34, v14
	v_cvt_f32_f16_e32 v175, v25
	s_nop 0
	v_addc_co_u32_e32 v11, vcc, 0, v15, vcc
	global_load_dwordx2 v[16:17], v[8:9], off offset:-4096 nt
	global_load_dwordx2 v[122:123], v[8:9], off nt
	global_load_dwordx2 v[46:47], v[10:11], off offset:-4096 nt
	global_load_dwordx2 v[36:37], v[10:11], off nt
	v_add_co_u32_e32 v8, vcc, s35, v14
	v_cvt_f32_f16_sdwa v177, v25 dst_sel:DWORD dst_unused:UNUSED_PAD src0_sel:WORD_1
	s_nop 0
	v_addc_co_u32_e32 v9, vcc, 0, v15, vcc
	v_add_co_u32_e32 v22, vcc, s30, v14
	v_cvt_f32_f16_e32 v176, v24
	s_nop 0
	v_addc_co_u32_e32 v23, vcc, 0, v15, vcc
	global_load_dwordx2 v[26:27], v[8:9], off offset:-4096 nt
	global_load_dwordx2 v[20:21], v[8:9], off nt
	global_load_dwordx2 v[10:11], v[22:23], off offset:-4096 nt
	s_nop 0
	global_load_dwordx2 v[8:9], v[22:23], off nt
	v_add_co_u32_e32 v22, vcc, s31, v14
	s_waitcnt vmcnt(10)
	v_cvt_f32_f16_sdwa v164, v12 dst_sel:DWORD dst_unused:UNUSED_PAD src0_sel:WORD_1
	v_addc_co_u32_e32 v23, vcc, 0, v15, vcc
	global_load_dwordx2 v[30:31], v[2:3], off offset:-4096 nt
	global_load_dwordx2 v[28:29], v[2:3], off nt
	s_nop 0
	global_load_dwordx2 v[2:3], v[22:23], off nt
	global_load_dwordx2 v[32:33], v[14:15], off nt
	v_mov_b32_e32 v14, v210
	v_cvt_f32_f16_e32 v165, v13
	v_ashrrev_i32_e32 v15, 31, v14
	v_lshrrev_b32_e32 v15, 23, v15
	v_add_u32_e32 v15, v14, v15
	v_ashrrev_i32_e32 v15, 9, v15
	v_mul_i32_i24_e32 v18, 0x200, v15
	v_sub_u32_e32 v18, v14, v18
	v_lshlrev_b32_e32 v14, 14, v15
	v_lshlrev_b32_e32 v15, 1, v18
	v_bfrev_b32_e32 v15, v15
	v_lshrrev_b32_e32 v15, 22, v15
	v_sub_u32_e32 v15, 0x400, v15
	v_bfrev_b32_e32 v15, v15
	v_lshrrev_b32_e32 v15, 18, v15
	v_and_b32_e32 v15, 0x3ff0, v15
	v_cmp_eq_u32_e64 s[0:1], 0, v18
	v_lshl_add_u32 v22, v18, 5, v14
	v_lshl_add_u32 v23, v22, 3, 0
	v_cndmask_b32_e64 v15, v15, 16, s[0:1]
	v_or_b32_e32 v14, v15, v14
	v_ashrrev_i32_e32 v22, 2, v22
	v_ashrrev_i32_e32 v15, 5, v14
	v_add_u32_e32 v211, v23, v22
	v_lshlrev_b32_e32 v14, 3, v14
	v_lshlrev_b32_e32 v15, 3, v15
	v_add3_u32 v212, 0, v14, v15
	ds_read2_b64 v[38:41], v211 offset1:1
	ds_read2_b64 v[42:45], v211 offset0:2 offset1:3
	ds_read2_b64 v[48:51], v212 offset1:1
	ds_read2_b64 v[52:55], v212 offset0:2 offset1:3
	ds_read2_b64 v[56:59], v211 offset0:4 offset1:5
	ds_read2_b64 v[60:63], v211 offset0:6 offset1:7
	ds_read2_b64 v[68:71], v212 offset0:4 offset1:5
	ds_read2_b64 v[72:75], v212 offset0:6 offset1:7
	ds_read2_b64 v[64:67], v211 offset0:8 offset1:9
	ds_read2_b64 v[76:79], v211 offset0:10 offset1:11
	ds_read2_b64 v[80:83], v212 offset0:8 offset1:9
	ds_read2_b64 v[98:101], v212 offset0:10 offset1:11
	ds_read2_b64 v[84:87], v211 offset0:12 offset1:13
	ds_read2_b64 v[88:91], v211 offset0:14 offset1:15
	ds_read2_b64 v[102:105], v212 offset0:12 offset1:13
	ds_read2_b64 v[106:109], v212 offset0:14 offset1:15
	s_waitcnt lgkmcnt(7)
	v_pk_add_f32 v[14:15], v[38:39], v[64:65]
	v_pk_add_f32 v[22:23], v[38:39], v[64:65] neg_lo:[0,1] neg_hi:[0,1]
	v_pk_add_f32 v[38:39], v[40:41], v[66:67] neg_lo:[0,1] neg_hi:[0,1]
	v_pk_add_f32 v[34:35], v[40:41], v[66:67]
	v_pk_mul_f32 v[40:41], v[38:39], s[18:19]
	v_cmp_ne_u32_e32 vcc, 0, v18
	v_pk_fma_f32 v[38:39], v[38:39], s[16:17], v[40:41] op_sel:[0,0,1] op_sel_hi:[1,0,0]
	s_waitcnt lgkmcnt(6)
	v_pk_add_f32 v[40:41], v[42:43], v[76:77]
	v_pk_add_f32 v[42:43], v[42:43], v[76:77] neg_lo:[0,1] neg_hi:[0,1]
	v_bfrev_b32_e32 v18, v18
	v_pk_mul_f32 v[64:65], v[42:43], s[36:37]
	v_lshrrev_b32_e32 v18, 23, v18
	v_pk_fma_f32 v[42:43], v[42:43], s[78:79], v[64:65] op_sel:[0,0,1] op_sel_hi:[1,0,0]
	v_pk_add_f32 v[64:65], v[44:45], v[78:79]
	v_pk_add_f32 v[44:45], v[44:45], v[78:79] neg_lo:[0,1] neg_hi:[0,1]
	s_waitcnt lgkmcnt(3)
	v_pk_add_f32 v[78:79], v[58:59], v[86:87]
	v_pk_mul_f32 v[66:67], v[44:45], s[40:41]
	v_pk_add_f32 v[58:59], v[58:59], v[86:87] neg_lo:[0,1] neg_hi:[0,1]
	v_pk_fma_f32 v[44:45], v[44:45], s[80:81], v[66:67] op_sel:[0,0,1] op_sel_hi:[1,0,0]
	v_pk_add_f32 v[66:67], v[56:57], v[84:85]
	v_pk_add_f32 v[76:77], v[56:57], v[84:85] neg_lo:[0,1] neg_hi:[0,1]
	v_pk_mul_f32 v[84:85], v[58:59], s[40:41]
	s_nop 0
	v_pk_fma_f32 v[58:59], v[58:59], s[80:81], v[84:85] op_sel:[0,0,1] op_sel_hi:[1,0,0] neg_lo:[1,0,0] neg_hi:[1,0,0]
	s_waitcnt lgkmcnt(2)
	v_pk_add_f32 v[84:85], v[60:61], v[88:89]
	v_pk_add_f32 v[60:61], v[60:61], v[88:89] neg_lo:[0,1] neg_hi:[0,1]
	s_nop 0
	v_pk_mul_f32 v[86:87], v[60:61], s[36:37]
	v_pk_add_f32 v[56:57], v[22:23], v[76:77] op_sel:[0,1] op_sel_hi:[1,0] neg_hi:[0,1]
	v_pk_fma_f32 v[60:61], v[60:61], s[78:79], v[86:87] op_sel:[0,0,1] op_sel_hi:[1,0,0] neg_lo:[1,0,0] neg_hi:[1,0,0]
	v_pk_add_f32 v[86:87], v[62:63], v[90:91]
	v_pk_add_f32 v[62:63], v[62:63], v[90:91] neg_lo:[0,1] neg_hi:[0,1]
	v_pk_add_f32 v[90:91], v[64:65], v[86:87]
	v_pk_mul_f32 v[88:89], v[62:63], s[18:19]
	v_pk_add_f32 v[64:65], v[64:65], v[86:87] neg_lo:[0,1] neg_hi:[0,1]
	v_pk_fma_f32 v[62:63], v[62:63], s[16:17], v[88:89] op_sel:[0,0,1] op_sel_hi:[1,0,0] neg_lo:[1,0,0] neg_hi:[1,0,0]
	v_pk_add_f32 v[88:89], v[14:15], v[66:67]
	v_pk_add_f32 v[14:15], v[14:15], v[66:67] neg_lo:[0,1] neg_hi:[0,1]
	v_pk_add_f32 v[66:67], v[34:35], v[78:79]
	v_pk_add_f32 v[34:35], v[34:35], v[78:79] neg_lo:[0,1] neg_hi:[0,1]
	v_pk_add_f32 v[22:23], v[22:23], v[76:77] op_sel:[0,1] op_sel_hi:[1,0] neg_lo:[0,1]
	v_pk_mul_f32 v[78:79], v[34:35], s[36:37]
	v_pk_add_f32 v[76:77], v[38:39], v[58:59]
	v_pk_add_f32 v[38:39], v[38:39], v[58:59] neg_lo:[0,1] neg_hi:[0,1]
	v_pk_fma_f32 v[34:35], v[34:35], s[78:79], v[78:79] op_sel:[0,0,1] op_sel_hi:[1,0,0]
	v_pk_add_f32 v[78:79], v[40:41], v[84:85]
	v_pk_add_f32 v[84:85], v[40:41], v[84:85] neg_lo:[0,1] neg_hi:[0,1]
	v_pk_mul_f32 v[86:87], v[64:65], s[36:37]
	v_pk_mul_f32 v[58:59], v[38:39], s[36:37]
	v_pk_fma_f32 v[64:65], v[64:65], s[78:79], v[86:87] op_sel:[0,0,1] op_sel_hi:[1,0,0] neg_lo:[1,0,0] neg_hi:[1,0,0]
	v_pk_fma_f32 v[38:39], v[38:39], s[78:79], v[58:59] op_sel:[0,0,1] op_sel_hi:[1,0,0]
	v_pk_add_f32 v[58:59], v[42:43], v[60:61]
	v_pk_add_f32 v[86:87], v[44:45], v[62:63]
	v_pk_add_f32 v[44:45], v[44:45], v[62:63] neg_lo:[0,1] neg_hi:[0,1]
	s_nop 0
	v_pk_mul_f32 v[62:63], v[44:45], s[36:37]
	v_pk_add_f32 v[40:41], v[14:15], v[84:85] op_sel:[0,1] op_sel_hi:[1,0] neg_hi:[0,1]
	v_pk_add_f32 v[14:15], v[14:15], v[84:85] op_sel:[0,1] op_sel_hi:[1,0] neg_lo:[0,1]
	v_pk_add_f32 v[84:85], v[34:35], v[64:65]
	v_pk_add_f32 v[64:65], v[34:35], v[64:65] neg_lo:[0,1] neg_hi:[0,1]
	v_pk_add_f32 v[94:95], v[56:57], v[58:59]
	v_pk_add_f32 v[56:57], v[56:57], v[58:59] neg_lo:[0,1] neg_hi:[0,1]
	v_pk_add_f32 v[58:59], v[76:77], v[86:87]
	v_pk_fma_f32 v[44:45], v[44:45], s[78:79], v[62:63] op_sel:[0,0,1] op_sel_hi:[1,0,0] neg_lo:[1,0,0] neg_hi:[1,0,0]
	v_pk_add_f32 v[62:63], v[88:89], v[78:79]
	v_pk_add_f32 v[78:79], v[88:89], v[78:79] neg_lo:[0,1] neg_hi:[0,1]
	v_pk_add_f32 v[88:89], v[66:67], v[90:91]
	v_pk_add_f32 v[110:111], v[76:77], v[86:87] neg_lo:[0,1] neg_hi:[0,1]
	v_pk_add_f32 v[86:87], v[94:95], v[58:59]
	v_pk_add_f32 v[34:35], v[94:95], v[58:59] neg_lo:[0,1] neg_hi:[0,1]
	v_pk_add_f32 v[58:59], v[50:51], v[82:83]
	v_pk_add_f32 v[50:51], v[50:51], v[82:83] neg_lo:[0,1] neg_hi:[0,1]
	v_pk_add_f32 v[60:61], v[42:43], v[60:61] neg_lo:[0,1] neg_hi:[0,1]
	v_pk_add_f32 v[148:149], v[62:63], v[88:89]
	v_pk_add_f32 v[138:139], v[62:63], v[88:89] neg_lo:[0,1] neg_hi:[0,1]
	v_pk_mul_f32 v[62:63], v[50:51], s[18:19]
	v_pk_add_f32 v[90:91], v[66:67], v[90:91] neg_lo:[0,1] neg_hi:[0,1]
	v_pk_fma_f32 v[50:51], v[50:51], s[16:17], v[62:63] op_sel:[0,0,1] op_sel_hi:[1,0,0]
	v_pk_add_f32 v[62:63], v[52:53], v[98:99]
	v_pk_add_f32 v[52:53], v[52:53], v[98:99] neg_lo:[0,1] neg_hi:[0,1]
	v_pk_add_f32 v[112:113], v[22:23], v[60:61] op_sel:[0,1] op_sel_hi:[1,0] neg_hi:[0,1]
	v_pk_add_f32 v[114:115], v[22:23], v[60:61] op_sel:[0,1] op_sel_hi:[1,0] neg_lo:[0,1]
	v_pk_add_f32 v[96:97], v[40:41], v[84:85]
	v_pk_add_f32 v[66:67], v[40:41], v[84:85] neg_lo:[0,1] neg_hi:[0,1]
	v_pk_add_f32 v[60:61], v[14:15], v[64:65] op_sel:[0,1] op_sel_hi:[1,0] neg_hi:[0,1]
	v_pk_add_f32 v[84:85], v[14:15], v[64:65] op_sel:[0,1] op_sel_hi:[1,0] neg_lo:[0,1]
	v_pk_mul_f32 v[64:65], v[52:53], s[36:37]
	s_nop 0
	v_pk_fma_f32 v[52:53], v[52:53], s[78:79], v[64:65] op_sel:[0,0,1] op_sel_hi:[1,0,0]
	v_pk_add_f32 v[64:65], v[54:55], v[100:101]
	v_pk_add_f32 v[54:55], v[54:55], v[100:101] neg_lo:[0,1] neg_hi:[0,1]
	s_nop 0
	v_pk_mul_f32 v[76:77], v[54:55], s[40:41]
	v_pk_add_f32 v[92:93], v[78:79], v[90:91] op_sel:[0,1] op_sel_hi:[1,0] neg_hi:[0,1]
	v_pk_fma_f32 v[54:55], v[54:55], s[80:81], v[76:77] op_sel:[0,0,1] op_sel_hi:[1,0,0]
	s_waitcnt lgkmcnt(1)
	v_pk_add_f32 v[76:77], v[68:69], v[102:103]
	v_pk_add_f32 v[88:89], v[78:79], v[90:91] op_sel:[0,1] op_sel_hi:[1,0] neg_lo:[0,1]
	v_pk_add_f32 v[78:79], v[68:69], v[102:103] neg_lo:[0,1] neg_hi:[0,1]
	v_pk_add_f32 v[68:69], v[70:71], v[104:105]
	v_pk_add_f32 v[70:71], v[70:71], v[104:105] neg_lo:[0,1] neg_hi:[0,1]
	v_pk_add_f32 v[22:23], v[38:39], v[44:45]
	v_pk_add_f32 v[116:117], v[38:39], v[44:45] neg_lo:[0,1] neg_hi:[0,1]
	v_pk_add_f32 v[40:41], v[56:57], v[110:111] op_sel:[0,1] op_sel_hi:[1,0] neg_hi:[0,1]
	v_pk_add_f32 v[44:45], v[56:57], v[110:111] op_sel:[0,1] op_sel_hi:[1,0] neg_lo:[0,1]
	v_pk_add_f32 v[56:57], v[48:49], v[80:81]
	v_pk_add_f32 v[48:49], v[48:49], v[80:81] neg_lo:[0,1] neg_hi:[0,1]
	v_pk_mul_f32 v[80:81], v[70:71], s[40:41]
	v_cvt_f32_u32_e32 v18, v18
	v_pk_fma_f32 v[70:71], v[70:71], s[80:81], v[80:81] op_sel:[0,0,1] op_sel_hi:[1,0,0] neg_lo:[1,0,0] neg_hi:[1,0,0]
	s_waitcnt lgkmcnt(0)
	v_pk_add_f32 v[80:81], v[72:73], v[106:107]
	v_pk_add_f32 v[72:73], v[72:73], v[106:107] neg_lo:[0,1] neg_hi:[0,1]
	v_mul_f32_e32 v18, 0x38000000, v18
	v_pk_mul_f32 v[82:83], v[72:73], s[36:37]
	v_cndmask_b32_e64 v18, v18, v208, s[0:1]
	v_pk_fma_f32 v[72:73], v[72:73], s[78:79], v[82:83] op_sel:[0,0,1] op_sel_hi:[1,0,0] neg_lo:[1,0,0] neg_hi:[1,0,0]
	v_pk_add_f32 v[82:83], v[74:75], v[108:109]
	v_pk_add_f32 v[74:75], v[74:75], v[108:109] neg_lo:[0,1] neg_hi:[0,1]
	s_nop 0
	v_pk_mul_f32 v[90:91], v[74:75], s[18:19]
	s_nop 0
	v_pk_fma_f32 v[74:75], v[74:75], s[16:17], v[90:91] op_sel:[0,0,1] op_sel_hi:[1,0,0] neg_lo:[1,0,0] neg_hi:[1,0,0]
	v_pk_add_f32 v[90:91], v[56:57], v[76:77]
	v_pk_add_f32 v[56:57], v[56:57], v[76:77] neg_lo:[0,1] neg_hi:[0,1]
	v_pk_add_f32 v[76:77], v[58:59], v[68:69]
	v_pk_add_f32 v[58:59], v[58:59], v[68:69] neg_lo:[0,1] neg_hi:[0,1]
	v_pk_add_f32 v[14:15], v[114:115], v[116:117] op_sel:[0,1] op_sel_hi:[1,0] neg_hi:[0,1]
	v_pk_mul_f32 v[68:69], v[58:59], s[36:37]
	v_pk_add_f32 v[38:39], v[114:115], v[116:117] op_sel:[0,1] op_sel_hi:[1,0] neg_lo:[0,1]
	v_pk_fma_f32 v[58:59], v[58:59], s[78:79], v[68:69] op_sel:[0,0,1] op_sel_hi:[1,0,0]
	v_pk_add_f32 v[68:69], v[62:63], v[80:81]
	v_pk_add_f32 v[80:81], v[62:63], v[80:81] neg_lo:[0,1] neg_hi:[0,1]
	s_waitcnt vmcnt(0)
	v_cvt_f32_f16_e32 v193, v33
	s_nop 0
	s_nop 0
	v_pk_add_f32 v[62:63], v[64:65], v[82:83]
	v_pk_add_f32 v[64:65], v[64:65], v[82:83] neg_lo:[0,1] neg_hi:[0,1]
	v_cvt_f32_f16_sdwa v192, v32 dst_sel:DWORD dst_unused:UNUSED_PAD src0_sel:WORD_1
	v_pk_mul_f32 v[82:83], v[64:65], s[36:37]
	v_cvt_f32_f16_e32 v194, v32
	v_pk_fma_f32 v[64:65], v[64:65], s[78:79], v[82:83] op_sel:[0,0,1] op_sel_hi:[1,0,0] neg_lo:[1,0,0] neg_hi:[1,0,0]
	v_pk_add_f32 v[82:83], v[48:49], v[78:79] op_sel:[0,1] op_sel_hi:[1,0] neg_hi:[0,1]
	v_pk_add_f32 v[48:49], v[48:49], v[78:79] op_sel:[0,1] op_sel_hi:[1,0] neg_lo:[0,1]
	v_pk_add_f32 v[78:79], v[50:51], v[70:71]
	v_pk_add_f32 v[50:51], v[50:51], v[70:71] neg_lo:[0,1] neg_hi:[0,1]
	v_cvt_f32_f16_sdwa v195, v33 dst_sel:DWORD dst_unused:UNUSED_PAD src0_sel:WORD_1
	v_pk_mul_f32 v[70:71], v[50:51], s[36:37]
	v_cvt_f32_f16_sdwa v170, v30 dst_sel:DWORD dst_unused:UNUSED_PAD src0_sel:WORD_1
	v_pk_fma_f32 v[50:51], v[50:51], s[78:79], v[70:71] op_sel:[0,0,1] op_sel_hi:[1,0,0]
	v_pk_add_f32 v[70:71], v[52:53], v[72:73]
	v_pk_add_f32 v[72:73], v[52:53], v[72:73] neg_lo:[0,1] neg_hi:[0,1]
	v_cvt_f32_f16_e32 v171, v31
	s_nop 0
	s_nop 0
	v_pk_add_f32 v[52:53], v[54:55], v[74:75]
	v_pk_add_f32 v[54:55], v[54:55], v[74:75] neg_lo:[0,1] neg_hi:[0,1]
	v_cvt_f32_f16_sdwa v185, v31 dst_sel:DWORD dst_unused:UNUSED_PAD src0_sel:WORD_1
	v_pk_mul_f32 v[74:75], v[54:55], s[36:37]
	v_cvt_f32_f16_e32 v184, v30
	v_pk_fma_f32 v[54:55], v[54:55], s[78:79], v[74:75] op_sel:[0,0,1] op_sel_hi:[1,0,0] neg_lo:[1,0,0] neg_hi:[1,0,0]
	v_pk_add_f32 v[74:75], v[90:91], v[68:69]
	v_pk_add_f32 v[68:69], v[90:91], v[68:69] neg_lo:[0,1] neg_hi:[0,1]
	v_pk_add_f32 v[90:91], v[76:77], v[62:63]
	v_pk_add_f32 v[62:63], v[76:77], v[62:63] neg_lo:[0,1] neg_hi:[0,1]
	v_cvt_f32_f16_sdwa v172, v28 dst_sel:DWORD dst_unused:UNUSED_PAD src0_sel:WORD_1
	v_xor_b32_e32 v77, 0x80000000, v62
	v_mov_b32_e32 v76, v63
	v_pk_add_f32 v[62:63], v[56:57], v[80:81] op_sel:[0,1] op_sel_hi:[1,0] neg_hi:[0,1]
	v_pk_add_f32 v[56:57], v[56:57], v[80:81] op_sel:[0,1] op_sel_hi:[1,0] neg_lo:[0,1]
	v_pk_add_f32 v[80:81], v[58:59], v[64:65]
	v_pk_add_f32 v[58:59], v[58:59], v[64:65] neg_lo:[0,1] neg_hi:[0,1]
	v_cvt_f32_f16_e32 v173, v29
	v_xor_b32_e32 v65, 0x80000000, v58
	v_mov_b32_e32 v64, v59
	v_pk_add_f32 v[58:59], v[82:83], v[70:71]
	v_pk_add_f32 v[70:71], v[82:83], v[70:71] neg_lo:[0,1] neg_hi:[0,1]
	v_pk_add_f32 v[82:83], v[78:79], v[52:53]
	v_pk_add_f32 v[52:53], v[78:79], v[52:53] neg_lo:[0,1] neg_hi:[0,1]
	v_pk_add_f32 v[118:119], v[58:59], v[82:83]
	v_pk_add_f32 v[134:135], v[58:59], v[82:83] neg_lo:[0,1] neg_hi:[0,1]
	v_cos_f32_e32 v83, v18
	v_sin_f32_e32 v82, v18
	v_cvt_f32_f16_sdwa v181, v29 dst_sel:DWORD dst_unused:UNUSED_PAD src0_sel:WORD_1
	v_cvt_f32_f16_e32 v180, v28
	v_cvt_f32_f16_sdwa v167, v13 dst_sel:DWORD dst_unused:UNUSED_PAD src0_sel:WORD_1
	v_cvt_f32_f16_e32 v166, v12
	v_cvt_f32_f16_e32 v154, v6
	v_cvt_f32_f16_e32 v155, v7
	v_cvt_f32_f16_sdwa v157, v7 dst_sel:DWORD dst_unused:UNUSED_PAD src0_sel:WORD_1
	v_cvt_f32_f16_sdwa v156, v6 dst_sel:DWORD dst_unused:UNUSED_PAD src0_sel:WORD_1
	v_cvt_f32_f16_sdwa v140, v4 dst_sel:DWORD dst_unused:UNUSED_PAD src0_sel:WORD_1
	v_cvt_f32_f16_e32 v141, v5
	v_cvt_f32_f16_sdwa v143, v5 dst_sel:DWORD dst_unused:UNUSED_PAD src0_sel:WORD_1
	v_cvt_f32_f16_e32 v142, v4
	v_cvt_f32_f16_e32 v124, v16
	v_cvt_f32_f16_e32 v125, v17
	v_cvt_f32_f16_sdwa v127, v17 dst_sel:DWORD dst_unused:UNUSED_PAD src0_sel:WORD_1
	v_cvt_f32_f16_sdwa v126, v16 dst_sel:DWORD dst_unused:UNUSED_PAD src0_sel:WORD_1
	v_cvt_f32_f16_sdwa v114, v122 dst_sel:DWORD dst_unused:UNUSED_PAD src0_sel:WORD_1
	v_cvt_f32_f16_e32 v115, v123
	v_cvt_f32_f16_sdwa v117, v123 dst_sel:DWORD dst_unused:UNUSED_PAD src0_sel:WORD_1
	v_cvt_f32_f16_e32 v116, v122
	v_xor_b32_e32 v79, 0x80000000, v52
	v_mov_b32_e32 v78, v53
	v_pk_add_f32 v[52:53], v[48:49], v[72:73] op_sel:[0,1] op_sel_hi:[1,0] neg_hi:[0,1]
	v_pk_add_f32 v[48:49], v[48:49], v[72:73] op_sel:[0,1] op_sel_hi:[1,0] neg_lo:[0,1]
	v_pk_add_f32 v[72:73], v[50:51], v[54:55]
	v_pk_add_f32 v[50:51], v[50:51], v[54:55] neg_lo:[0,1] neg_hi:[0,1]
	v_pk_fma_f32 v[160:161], v[82:83], 0, v[82:83] op_sel:[0,0,1] op_sel_hi:[1,0,0] neg_lo:[1,0,0] neg_hi:[1,0,0]
	v_xor_b32_e32 v55, 0x80000000, v50
	v_mov_b32_e32 v54, v51
	v_pk_fma_f32 v[198:199], v[82:83], 0, v[82:83] op_sel:[0,0,1] op_sel_hi:[1,0,0]
	v_pk_add_f32 v[42:43], v[112:113], v[22:23]
	v_pk_add_f32 v[22:23], v[112:113], v[22:23] neg_lo:[0,1] neg_hi:[0,1]
	v_pk_add_f32 v[98:99], v[74:75], v[90:91]
	v_pk_add_f32 v[100:101], v[74:75], v[90:91] neg_lo:[0,1] neg_hi:[0,1]
	v_pk_add_f32 v[102:103], v[68:69], v[76:77]
	v_pk_add_f32 v[106:107], v[68:69], v[76:77] neg_lo:[0,1] neg_hi:[0,1]
	v_pk_add_f32 v[104:105], v[62:63], v[80:81]
	v_pk_add_f32 v[108:109], v[62:63], v[80:81] neg_lo:[0,1] neg_hi:[0,1]
	v_pk_add_f32 v[110:111], v[56:57], v[64:65]
	v_pk_add_f32 v[112:113], v[56:57], v[64:65] neg_lo:[0,1] neg_hi:[0,1]
	v_pk_add_f32 v[152:153], v[70:71], v[78:79]
	v_pk_add_f32 v[162:163], v[70:71], v[78:79] neg_lo:[0,1] neg_hi:[0,1]
	v_pk_add_f32 v[178:179], v[52:53], v[72:73]
	v_pk_add_f32 v[182:183], v[52:53], v[72:73] neg_lo:[0,1] neg_hi:[0,1]
	v_pk_add_f32 v[188:189], v[48:49], v[54:55]
	v_pk_add_f32 v[196:197], v[48:49], v[54:55] neg_lo:[0,1] neg_hi:[0,1]
	v_pk_mul_f32 v[186:187], v[82:83], 0 op_sel_hi:[1,0]
	v_mov_b32_e32 v190, v160
	v_mov_b32_e32 v191, v199
	v_mul_f32_e32 v18, 0x3f3504f3, v83
	v_mul_f32_e32 v158, 0xbec3ef15, v83
	v_mul_f32_e32 v132, 0xbf6c835e, v83
	s_and_saveexec_b64 s[0:1], vcc
	s_xor_b64 s[0:1], exec, s[0:1]
	s_cbranch_execz .LBB0_501
	v_pk_add_f32 v[4:5], v[148:149], v[196:197]
	v_pk_add_f32 v[6:7], v[148:149], v[196:197] neg_lo:[0,1] neg_hi:[0,1]
	v_mul_f32_e32 v4, 0.5, v4
	v_mul_f32_e32 v12, 0.5, v7
	v_mov_b32_e32 v7, v5
	v_pk_mul_f32 v[6:7], v[6:7], s[44:45]
	v_pk_mov_b32 v[16:17], v[198:199], v[160:161] op_sel:[1,0]
	v_pk_mul_f32 v[24:25], v[190:191], v[6:7] op_sel:[0,1] op_sel_hi:[1,0]
	v_pk_mul_f32 v[6:7], v[190:191], v[6:7]
	v_pk_add_f32 v[24:25], v[24:25], v[24:25] op_sel:[0,1] op_sel_hi:[0,1]
	v_pk_add_f32 v[28:29], v[4:5], v[24:25] op_sel_hi:[0,1] neg_hi:[0,1]
	v_pk_add_f32 v[4:5], v[6:7], v[6:7] op_sel:[0,1] op_sel_hi:[0,1] neg_lo:[0,1] neg_hi:[0,1]
	v_pk_add_f32 v[6:7], v[12:13], v[4:5] op_sel_hi:[0,1] neg_hi:[0,1]
	v_pk_mul_f32 v[4:5], v[6:7], v[194:195]
	v_pk_mul_f32 v[6:7], v[6:7], v[192:193]
	v_pk_fma_f32 v[4:5], v[28:29], v[192:193], v[4:5]
	v_pk_fma_f32 v[6:7], v[28:29], v[194:195], v[6:7] neg_lo:[0,0,1] neg_hi:[0,0,1]
	s_mov_b32 s78, s19
	v_pk_add_f32 v[12:13], v[6:7], v[4:5] op_sel:[0,1] op_sel_hi:[1,0] neg_lo:[0,1]
	v_pk_add_f32 v[28:29], v[6:7], v[4:5] op_sel:[0,1] op_sel_hi:[1,0]
	v_pk_add_f32 v[4:5], v[4:5], v[6:7] op_sel:[1,0] op_sel_hi:[0,1] neg_lo:[0,1] neg_hi:[0,1]
	s_nop 0
	v_pk_mul_f32 v[12:13], v[12:13], 0.5 op_sel_hi:[1,0]
	v_mov_b32_e32 v29, v5
	v_mul_f32_e32 v24, v190, v12
	v_pk_fma_f32 v[30:31], v[190:191], v[12:13], v[24:25] op_sel_hi:[1,1,0] neg_lo:[1,0,0] neg_hi:[1,0,0]
	v_mul_f32_e32 v24, v160, v13
	v_pk_fma_f32 v[12:13], v[16:17], v[12:13], v[24:25] op_sel_hi:[1,1,0]
	v_mov_b32_e32 v16, v83
	v_mov_b32_e32 v30, v12
	v_pk_fma_f32 v[4:5], v[28:29], 0.5, v[12:13] op_sel_hi:[1,0,1] neg_lo:[0,0,1] neg_hi:[0,0,1]
	v_pk_fma_f32 v[122:123], v[28:29], 0.5, v[30:31] op_sel_hi:[1,0,1]
	v_pk_fma_f32 v[6:7], v[28:29], 0.5, v[30:31] op_sel_hi:[1,0,1] neg_lo:[1,0,0] neg_hi:[1,0,0]
	v_mov_b32_e32 v5, v123
	v_pk_mul_f32 v[24:25], v[4:5], s[6:7] op_sel_hi:[1,0]
	v_pk_add_f32 v[4:5], v[138:139], v[188:189]
	v_pk_add_f32 v[12:13], v[138:139], v[188:189] neg_lo:[0,1] neg_hi:[0,1]
	v_mov_b32_e32 v17, v82
	v_mul_f32_e32 v6, 0.5, v13
	v_pk_add_f32 v[28:29], v[186:187], v[16:17] neg_lo:[0,1] neg_hi:[0,1]
	v_pk_add_f32 v[30:31], v[186:187], v[16:17]
	v_mov_b32_e32 v13, v5
	v_pk_mov_b32 v[32:33], v[28:29], v[30:31] op_sel:[1,0]
	v_pk_mul_f32 v[12:13], v[12:13], s[44:45]
	v_mul_f32_e32 v4, 0.5, v4
	v_pk_mul_f32 v[48:49], v[32:33], v[12:13] op_sel:[0,1] op_sel_hi:[1,0]
	v_pk_mul_f32 v[12:13], v[32:33], v[12:13]
	v_pk_add_f32 v[48:49], v[48:49], v[48:49] op_sel:[0,1] op_sel_hi:[0,1]
	v_pk_add_f32 v[50:51], v[4:5], v[48:49] op_sel_hi:[0,1] neg_hi:[0,1]
	v_pk_add_f32 v[4:5], v[12:13], v[12:13] op_sel:[0,1] op_sel_hi:[0,1] neg_lo:[0,1] neg_hi:[0,1]
	v_pk_add_f32 v[12:13], v[6:7], v[4:5] op_sel_hi:[0,1] neg_hi:[0,1]
	v_pk_mul_f32 v[4:5], v[12:13], v[184:185]
	v_pk_mul_f32 v[12:13], v[12:13], v[170:171]
	v_pk_fma_f32 v[4:5], v[50:51], v[170:171], v[4:5]
	v_pk_fma_f32 v[12:13], v[50:51], v[184:185], v[12:13] neg_lo:[0,0,1] neg_hi:[0,0,1]
	v_mov_b32_e32 v31, v29
	v_pk_add_f32 v[48:49], v[12:13], v[4:5] op_sel:[0,1] op_sel_hi:[1,0] neg_lo:[0,1]
	v_pk_add_f32 v[50:51], v[12:13], v[4:5] op_sel:[0,1] op_sel_hi:[1,0]
	v_pk_add_f32 v[4:5], v[4:5], v[12:13] op_sel:[1,0] op_sel_hi:[0,1] neg_lo:[0,1] neg_hi:[0,1]
	v_pk_mul_f32 v[48:49], v[48:49], 0.5 op_sel_hi:[1,0]
	v_mov_b32_e32 v51, v5
	v_mul_f32_e32 v6, v29, v48
	v_pk_fma_f32 v[32:33], v[32:33], v[48:49], v[6:7] op_sel_hi:[1,1,0] neg_lo:[1,0,0] neg_hi:[1,0,0]
	v_mul_f32_e32 v6, v29, v49
	v_pk_fma_f32 v[28:29], v[30:31], v[48:49], v[6:7] op_sel_hi:[1,1,0]
	v_pk_mul_f32 v[12:13], v[16:17], s[36:37]
	v_mov_b32_e32 v32, v28
	v_pk_fma_f32 v[4:5], v[50:51], 0.5, v[28:29] op_sel_hi:[1,0,1] neg_lo:[0,0,1] neg_hi:[0,0,1]
	v_pk_fma_f32 v[138:139], v[50:51], 0.5, v[32:33] op_sel_hi:[1,0,1]
	v_pk_add_f32 v[16:17], v[92:93], v[182:183]
	v_mov_b32_e32 v5, v139
	v_pk_add_f32 v[28:29], v[92:93], v[182:183] neg_lo:[0,1] neg_hi:[0,1]
	v_pk_mul_f32 v[30:31], v[4:5], s[6:7] op_sel_hi:[1,0]
	v_pk_fma_f32 v[4:5], v[50:51], 0.5, v[32:33] op_sel_hi:[1,0,1] neg_lo:[1,0,0] neg_hi:[1,0,0]
	v_mul_f32_e32 v6, 0.5, v29
	v_pk_add_f32 v[32:33], v[18:19], v[12:13] op_sel:[0,1] op_sel_hi:[0,1] neg_lo:[0,1] neg_hi:[0,1]
	v_pk_add_f32 v[48:49], v[18:19], v[12:13] op_sel:[0,1] op_sel_hi:[0,1]
	v_mov_b32_e32 v29, v17
	v_mul_f32_e32 v4, 0.5, v16
	v_mov_b32_e32 v50, v32
	v_mov_b32_e32 v51, v49
	v_pk_mul_f32 v[16:17], v[28:29], s[44:45]
	v_pk_mov_b32 v[48:49], v[48:49], v[32:33] op_sel:[1,0]
	v_pk_mul_f32 v[28:29], v[50:51], v[16:17] op_sel:[0,1] op_sel_hi:[1,0]
	v_pk_mul_f32 v[16:17], v[50:51], v[16:17]
	v_pk_add_f32 v[28:29], v[28:29], v[28:29] op_sel:[0,1] op_sel_hi:[0,1]
	v_pk_add_f32 v[52:53], v[4:5], v[28:29] op_sel_hi:[0,1] neg_hi:[0,1]
	v_pk_add_f32 v[16:17], v[16:17], v[16:17] op_sel:[0,1] op_sel_hi:[0,1] neg_lo:[0,1] neg_hi:[0,1]
	v_pk_add_f32 v[28:29], v[6:7], v[16:17] op_sel_hi:[0,1] neg_hi:[0,1]
	v_pk_mul_f32 v[16:17], v[28:29], v[180:181]
	v_pk_mul_f32 v[28:29], v[28:29], v[172:173]
	v_pk_fma_f32 v[16:17], v[52:53], v[172:173], v[16:17]
	v_pk_fma_f32 v[28:29], v[52:53], v[180:181], v[28:29] neg_lo:[0,0,1] neg_hi:[0,0,1]
	v_sub_f32_e32 v6, v89, v179
	v_pk_add_f32 v[52:53], v[28:29], v[16:17] op_sel:[0,1] op_sel_hi:[1,0] neg_lo:[0,1]
	v_pk_add_f32 v[54:55], v[28:29], v[16:17] op_sel:[0,1] op_sel_hi:[1,0]
	v_pk_add_f32 v[16:17], v[16:17], v[28:29] op_sel:[1,0] op_sel_hi:[0,1] neg_lo:[0,1] neg_hi:[0,1]
	v_pk_mul_f32 v[52:53], v[52:53], 0.5 op_sel_hi:[1,0]
	v_mov_b32_e32 v55, v17
	v_mul_f32_e32 v4, v32, v52
	v_pk_fma_f32 v[56:57], v[50:51], v[52:53], v[4:5] op_sel_hi:[1,1,0] neg_lo:[1,0,0] neg_hi:[1,0,0]
	v_mul_f32_e32 v4, v32, v53
	v_pk_fma_f32 v[48:49], v[48:49], v[52:53], v[4:5] op_sel_hi:[1,1,0]
	v_pk_add_f32 v[28:29], v[88:89], v[178:179]
	v_mov_b32_e32 v56, v48
	v_pk_fma_f32 v[16:17], v[54:55], 0.5, v[48:49] op_sel_hi:[1,0,1] neg_lo:[0,0,1] neg_hi:[0,0,1]
	v_mov_b32_e32 v48, v12
	v_mov_b32_e32 v49, v88
	v_pk_mov_b32 v[12:13], v[12:13], v[178:179] op_sel:[1,0]
	v_mul_f32_e32 v18, 0.5, v29
	v_pk_add_f32 v[12:13], v[48:49], v[12:13] neg_lo:[0,1] neg_hi:[0,1]
	v_mul_f32_e32 v4, 0.5, v28
	v_pk_mul_f32 v[48:49], v[12:13], v[18:19]
	v_mov_b32_e32 v13, v32
	v_pk_fma_f32 v[50:51], v[50:51], v[48:49], v[48:49] op_sel:[0,1,0] op_sel_hi:[1,0,1]
	v_mov_b32_e32 v48, v49
	v_mov_b32_e32 v49, v18
	v_pk_mul_f32 v[48:49], v[12:13], v[48:49]
	v_pk_add_f32 v[52:53], v[4:5], v[50:51]
	v_mul_f32_e32 v6, 0.5, v6
	v_fma_f32 v53, v28, 0.5, -v50
	v_pk_add_f32 v[28:29], v[48:49], v[48:49] op_sel:[0,1] op_sel_hi:[0,1] neg_lo:[0,1] neg_hi:[0,1]
	v_pk_add_f32 v[48:49], v[6:7], v[28:29] op_sel_hi:[0,1] neg_hi:[0,1]
	v_pk_mul_f32 v[28:29], v[48:49], v[176:177]
	v_pk_mul_f32 v[48:49], v[48:49], v[174:175]
	v_pk_fma_f32 v[28:29], v[52:53], v[174:175], v[28:29]
	v_pk_fma_f32 v[48:49], v[52:53], v[176:177], v[48:49] neg_lo:[0,0,1] neg_hi:[0,0,1]
	v_pk_fma_f32 v[92:93], v[54:55], 0.5, v[56:57] op_sel_hi:[1,0,1]
	v_pk_add_f32 v[50:51], v[48:49], v[28:29] op_sel:[0,1] op_sel_hi:[1,0] neg_lo:[0,1]
	v_pk_add_f32 v[52:53], v[48:49], v[28:29] op_sel:[0,1] op_sel_hi:[1,0]
	v_mov_b32_e32 v17, v93
	v_pk_mul_f32 v[50:51], v[50:51], 0.5 op_sel_hi:[1,0]
	v_pk_mul_f32 v[64:65], v[16:17], s[6:7] op_sel_hi:[1,0]
	v_mul_f32_e32 v4, v12, v50
	v_pk_fma_f32 v[16:17], v[54:55], 0.5, v[56:57] op_sel_hi:[1,0,1] neg_lo:[1,0,0] neg_hi:[1,0,0]
	v_pk_fma_f32 v[54:55], v[12:13], v[50:51], v[4:5] op_sel_hi:[1,1,0] neg_lo:[1,0,0] neg_hi:[1,0,0]
	v_mov_b32_e32 v33, v12
	v_mul_f32_e32 v4, v12, v51
	v_pk_fma_f32 v[12:13], v[32:33], v[50:51], v[4:5] op_sel_hi:[1,1,0]
	v_pk_add_f32 v[28:29], v[28:29], v[48:49] op_sel:[1,0] op_sel_hi:[0,1] neg_lo:[0,1] neg_hi:[0,1]
	v_mov_b32_e32 v53, v29
	v_mov_b32_e32 v54, v12
	v_pk_fma_f32 v[12:13], v[52:53], 0.5, v[12:13] op_sel_hi:[1,0,1] neg_lo:[0,0,1] neg_hi:[0,0,1]
	v_pk_fma_f32 v[88:89], v[52:53], 0.5, v[54:55] op_sel_hi:[1,0,1]
	s_mov_b32 s79, s16
	v_mov_b32_e32 v13, v89
	v_pk_mul_f32 v[68:69], v[12:13], s[6:7] op_sel_hi:[1,0]
	v_pk_fma_f32 v[12:13], v[52:53], 0.5, v[54:55] op_sel_hi:[1,0,1] neg_lo:[1,0,0] neg_hi:[1,0,0]
	v_mov_b32_e32 v4, v83
	s_mov_b32 s17, s19
	v_pk_mul_f32 v[48:49], v[82:83], s[78:79] op_sel_hi:[0,1]
	v_pk_add_f32 v[28:29], v[96:97], v[162:163]
	v_pk_add_f32 v[32:33], v[96:97], v[162:163] neg_lo:[0,1] neg_hi:[0,1]
	v_pk_fma_f32 v[52:53], v[4:5], s[16:17], v[48:49] op_sel_hi:[0,1,1] neg_lo:[0,0,1] neg_hi:[0,0,1]
	v_mul_f32_e32 v12, 0.5, v33
	v_pk_fma_f32 v[50:51], v[4:5], s[16:17], v[48:49] op_sel_hi:[0,1,1]
	v_mov_b32_e32 v33, v29
	v_mul_f32_e32 v6, 0.5, v28
	v_mov_b32_e32 v54, v52
	v_mov_b32_e32 v55, v51
	v_pk_mul_f32 v[28:29], v[32:33], s[44:45]
	v_pk_mov_b32 v[56:57], v[50:51], v[52:53] op_sel:[1,0]
	v_pk_mul_f32 v[32:33], v[54:55], v[28:29] op_sel:[0,1] op_sel_hi:[1,0]
	v_pk_mul_f32 v[28:29], v[54:55], v[28:29]
	v_pk_add_f32 v[32:33], v[32:33], v[32:33] op_sel:[0,1] op_sel_hi:[0,1]
	v_pk_add_f32 v[58:59], v[6:7], v[32:33] op_sel_hi:[0,1] neg_hi:[0,1]
	v_pk_add_f32 v[28:29], v[28:29], v[28:29] op_sel:[0,1] op_sel_hi:[0,1] neg_lo:[0,1] neg_hi:[0,1]
	v_pk_add_f32 v[32:33], v[12:13], v[28:29] op_sel_hi:[0,1] neg_hi:[0,1]
	v_pk_mul_f32 v[28:29], v[32:33], v[166:167]
	v_pk_mul_f32 v[32:33], v[32:33], v[164:165]
	v_pk_fma_f32 v[28:29], v[58:59], v[164:165], v[28:29]
	v_pk_fma_f32 v[32:33], v[58:59], v[166:167], v[32:33] neg_lo:[0,0,1] neg_hi:[0,0,1]
	v_mov_b32_e32 v159, v66
	v_pk_add_f32 v[58:59], v[32:33], v[28:29] op_sel:[0,1] op_sel_hi:[1,0] neg_lo:[0,1]
	v_pk_add_f32 v[70:71], v[32:33], v[28:29] op_sel:[0,1] op_sel_hi:[1,0]
	v_pk_add_f32 v[28:29], v[28:29], v[32:33] op_sel:[1,0] op_sel_hi:[0,1] neg_lo:[0,1] neg_hi:[0,1]
	v_pk_mul_f32 v[58:59], v[58:59], 0.5 op_sel_hi:[1,0]
	v_mov_b32_e32 v71, v29
	v_mul_f32_e32 v6, v52, v58
	v_pk_fma_f32 v[72:73], v[54:55], v[58:59], v[6:7] op_sel_hi:[1,1,0] neg_lo:[1,0,0] neg_hi:[1,0,0]
	v_mul_f32_e32 v6, v52, v59
	v_pk_fma_f32 v[56:57], v[56:57], v[58:59], v[6:7] op_sel_hi:[1,1,0]
	v_sub_f32_e32 v12, v67, v153
	v_mov_b32_e32 v72, v56
	v_pk_fma_f32 v[28:29], v[70:71], 0.5, v[56:57] op_sel_hi:[1,0,1] neg_lo:[0,0,1] neg_hi:[0,0,1]
	v_pk_fma_f32 v[96:97], v[70:71], 0.5, v[72:73] op_sel_hi:[1,0,1]
	v_pk_mov_b32 v[56:57], v[48:49], v[152:153] op_sel:[1,0]
	v_mov_b32_e32 v29, v97
	v_pk_mul_f32 v[62:63], v[28:29], s[6:7] op_sel_hi:[1,0]
	v_pk_add_f32 v[28:29], v[66:67], v[152:153]
	v_pk_add_f32 v[56:57], v[158:159], v[56:57] neg_lo:[0,1] neg_hi:[0,1]
	v_mul_f32_e32 v18, 0.5, v29
	v_pk_mul_f32 v[58:59], v[56:57], v[18:19]
	v_mul_f32_e32 v6, 0.5, v28
	v_pk_fma_f32 v[54:55], v[54:55], v[58:59], v[58:59] op_sel:[0,1,0] op_sel_hi:[1,0,1]
	v_mov_b32_e32 v66, v56
	v_mov_b32_e32 v67, v52
	v_mov_b32_e32 v58, v59
	v_mov_b32_e32 v59, v18
	v_pk_mul_f32 v[58:59], v[66:67], v[58:59]
	v_pk_add_f32 v[66:67], v[6:7], v[54:55]
	v_mul_f32_e32 v12, 0.5, v12
	v_fma_f32 v67, v28, 0.5, -v54
	v_pk_add_f32 v[28:29], v[58:59], v[58:59] op_sel:[0,1] op_sel_hi:[0,1] neg_lo:[0,1] neg_hi:[0,1]
	v_pk_add_f32 v[54:55], v[12:13], v[28:29] op_sel_hi:[0,1] neg_hi:[0,1]
	v_pk_mul_f32 v[28:29], v[54:55], v[156:157]
	v_pk_mul_f32 v[54:55], v[54:55], v[154:155]
	v_pk_fma_f32 v[32:33], v[70:71], 0.5, v[72:73] op_sel_hi:[1,0,1] neg_lo:[1,0,0] neg_hi:[1,0,0]
	v_pk_fma_f32 v[58:59], v[66:67], v[154:155], v[28:29] neg_lo:[0,0,1] neg_hi:[0,0,1]
	v_pk_fma_f32 v[28:29], v[66:67], v[154:155], v[28:29]
	v_pk_fma_f32 v[70:71], v[66:67], v[156:157], v[54:55]
	v_pk_fma_f32 v[54:55], v[66:67], v[156:157], v[54:55] neg_lo:[0,0,1] neg_hi:[0,0,1]
	v_pk_add_f32 v[72:73], v[58:59], v[28:29] op_sel:[0,1] op_sel_hi:[1,0]
	v_pk_add_f32 v[66:67], v[70:71], v[54:55] op_sel_hi:[0,1] neg_lo:[0,1] neg_hi:[0,1]
	v_pk_add_f32 v[28:29], v[58:59], v[28:29] op_sel_hi:[0,1] neg_lo:[0,1] neg_hi:[0,1]
	v_pk_add_f32 v[54:55], v[70:71], v[54:55] op_sel:[0,1] op_sel_hi:[1,0]
	v_mov_b32_e32 v73, v67
	v_mov_b32_e32 v55, v29
	v_pk_mul_f32 v[28:29], v[54:55], 0.5 op_sel_hi:[1,0]
	v_mov_b32_e32 v133, v84
	v_pk_mul_f32 v[54:55], v[52:53], v[28:29] op_sel:[0,1] op_sel_hi:[0,0]
	v_pk_fma_f32 v[58:59], v[56:57], v[28:29], v[54:55] op_sel_hi:[0,1,1]
	v_pk_fma_f32 v[28:29], v[56:57], v[28:29], v[54:55] op_sel_hi:[0,1,1] neg_hi:[0,0,1]
	v_pk_fma_f32 v[54:55], v[72:73], 0.5, v[58:59] op_sel_hi:[1,0,1] neg_lo:[0,0,1] neg_hi:[0,0,1]
	v_pk_fma_f32 v[66:67], v[72:73], 0.5, v[28:29] op_sel_hi:[1,0,1]
	v_pk_add_f32 v[56:57], v[60:61], v[134:135] neg_lo:[0,1] neg_hi:[0,1]
	v_mov_b32_e32 v55, v67
	v_pk_mul_f32 v[90:91], v[54:55], s[6:7] op_sel_hi:[1,0]
	v_pk_add_f32 v[54:55], v[134:135], v[60:61]
	v_mul_f32_e32 v12, 0.5, v57
	v_mov_b32_e32 v57, v55
	v_mul_f32_e32 v6, 0.5, v54
	v_pk_mov_b32 v[58:59], v[52:53], v[50:51] op_sel:[1,0]
	v_pk_mul_f32 v[54:55], v[56:57], s[44:45]
	v_pk_fma_f32 v[28:29], v[72:73], 0.5, v[28:29] op_sel_hi:[1,0,1] neg_lo:[1,0,0] neg_hi:[1,0,0]
	v_pk_mul_f32 v[56:57], v[58:59], v[54:55] op_sel:[0,1] op_sel_hi:[1,0]
	v_pk_mul_f32 v[54:55], v[58:59], v[54:55]
	v_pk_add_f32 v[56:57], v[56:57], v[56:57] op_sel:[0,1] op_sel_hi:[0,1]
	v_pk_add_f32 v[60:61], v[6:7], v[56:57] op_sel_hi:[0,1] neg_hi:[0,1]
	v_pk_add_f32 v[54:55], v[54:55], v[54:55] op_sel:[0,1] op_sel_hi:[0,1] neg_lo:[0,1] neg_hi:[0,1]
	v_pk_add_f32 v[56:57], v[12:13], v[54:55] op_sel_hi:[0,1] neg_hi:[0,1]
	v_pk_mul_f32 v[54:55], v[56:57], v[142:143]
	v_pk_mul_f32 v[56:57], v[56:57], v[140:141]
	v_pk_fma_f32 v[54:55], v[60:61], v[140:141], v[54:55]
	v_pk_fma_f32 v[56:57], v[60:61], v[142:143], v[56:57] neg_lo:[0,0,1] neg_hi:[0,0,1]
	v_mov_b32_e32 v51, v53
	v_pk_add_f32 v[60:61], v[56:57], v[54:55] op_sel:[0,1] op_sel_hi:[1,0] neg_lo:[0,1]
	v_pk_add_f32 v[70:71], v[56:57], v[54:55] op_sel:[0,1] op_sel_hi:[1,0]
	v_pk_add_f32 v[54:55], v[54:55], v[56:57] op_sel:[1,0] op_sel_hi:[0,1] neg_lo:[0,1] neg_hi:[0,1]
	v_pk_mul_f32 v[60:61], v[60:61], 0.5 op_sel_hi:[1,0]
	v_mov_b32_e32 v71, v55
	v_mul_f32_e32 v6, v53, v60
	v_pk_fma_f32 v[72:73], v[58:59], v[60:61], v[6:7] op_sel_hi:[1,1,0] neg_lo:[1,0,0] neg_hi:[1,0,0]
	v_mul_f32_e32 v6, v53, v61
	v_pk_fma_f32 v[50:51], v[50:51], v[60:61], v[6:7] op_sel_hi:[1,1,0]
	v_pk_add_f32 v[54:55], v[118:119], v[84:85]
	v_mov_b32_e32 v72, v50
	v_mov_b32_e32 v49, v118
	v_pk_fma_f32 v[50:51], v[70:71], 0.5, v[50:51] op_sel_hi:[1,0,1] neg_lo:[0,0,1] neg_hi:[0,0,1]
	v_pk_fma_f32 v[60:61], v[70:71], 0.5, v[72:73] op_sel_hi:[1,0,1]
	v_mul_f32_e32 v18, 0.5, v55
	v_pk_add_f32 v[48:49], v[132:133], v[48:49] neg_lo:[0,1] neg_hi:[0,1]
	v_mov_b32_e32 v51, v61
	v_pk_mul_f32 v[56:57], v[48:49], v[18:19]
	v_pk_mul_f32 v[94:95], v[50:51], s[6:7] op_sel_hi:[1,0]
	v_pk_fma_f32 v[50:51], v[70:71], 0.5, v[72:73] op_sel_hi:[1,0,1] neg_lo:[1,0,0] neg_hi:[1,0,0]
	v_mul_f32_e32 v6, 0.5, v54
	v_pk_fma_f32 v[58:59], v[58:59], v[56:57], v[56:57] op_sel:[0,1,0] op_sel_hi:[1,0,1]
	v_mov_b32_e32 v70, v48
	v_mov_b32_e32 v71, v53
	v_mov_b32_e32 v56, v57
	v_mov_b32_e32 v57, v18
	v_sub_f32_e32 v12, v85, v119
	v_pk_mul_f32 v[56:57], v[70:71], v[56:57]
	v_pk_add_f32 v[70:71], v[6:7], v[58:59]
	v_mul_f32_e32 v12, 0.5, v12
	v_fma_f32 v71, v54, 0.5, -v58
	v_pk_add_f32 v[54:55], v[56:57], v[56:57] op_sel:[0,1] op_sel_hi:[0,1] neg_lo:[0,1] neg_hi:[0,1]
	v_pk_add_f32 v[56:57], v[12:13], v[54:55] op_sel_hi:[0,1] neg_hi:[0,1]
	v_pk_mul_f32 v[54:55], v[56:57], v[126:127]
	v_pk_mul_f32 v[56:57], v[56:57], v[124:125]
	v_pk_fma_f32 v[58:59], v[70:71], v[124:125], v[54:55] neg_lo:[0,0,1] neg_hi:[0,0,1]
	v_pk_fma_f32 v[54:55], v[70:71], v[124:125], v[54:55]
	v_pk_fma_f32 v[72:73], v[70:71], v[126:127], v[56:57]
	v_pk_fma_f32 v[56:57], v[70:71], v[126:127], v[56:57] neg_lo:[0,0,1] neg_hi:[0,0,1]
	v_pk_add_f32 v[70:71], v[58:59], v[54:55] op_sel:[0,1] op_sel_hi:[1,0]
	v_pk_add_f32 v[74:75], v[72:73], v[56:57] op_sel_hi:[0,1] neg_lo:[0,1] neg_hi:[0,1]
	v_pk_add_f32 v[54:55], v[58:59], v[54:55] op_sel_hi:[0,1] neg_lo:[0,1] neg_hi:[0,1]
	v_pk_add_f32 v[56:57], v[72:73], v[56:57] op_sel:[0,1] op_sel_hi:[1,0]
	v_mov_b32_e32 v71, v75
	v_mov_b32_e32 v57, v55
	v_pk_mul_f32 v[54:55], v[56:57], 0.5 op_sel_hi:[1,0]
	s_mov_b32 s78, s11
	v_pk_mul_f32 v[52:53], v[52:53], v[54:55] op_sel:[1,1] op_sel_hi:[1,0]
	s_mov_b32 s79, s8
	v_pk_fma_f32 v[56:57], v[48:49], v[54:55], v[52:53] op_sel_hi:[0,1,1]
	v_pk_fma_f32 v[48:49], v[48:49], v[54:55], v[52:53] op_sel_hi:[0,1,1] neg_hi:[0,0,1]
	s_nop 0
	v_pk_fma_f32 v[52:53], v[70:71], 0.5, v[56:57] op_sel_hi:[1,0,1] neg_lo:[0,0,1] neg_hi:[0,0,1]
	v_pk_fma_f32 v[84:85], v[70:71], 0.5, v[48:49] op_sel_hi:[1,0,1]
	s_mov_b32 s9, s11
	v_mov_b32_e32 v53, v85
	v_pk_mul_f32 v[80:81], v[52:53], s[6:7] op_sel_hi:[1,0]
	v_pk_mul_f32 v[118:119], v[82:83], s[78:79] op_sel_hi:[0,1]
	v_pk_add_f32 v[52:53], v[86:87], v[112:113]
	v_pk_add_f32 v[54:55], v[86:87], v[112:113] neg_lo:[0,1] neg_hi:[0,1]
	v_pk_fma_f32 v[58:59], v[4:5], s[8:9], v[118:119] op_sel_hi:[0,1,1] neg_lo:[0,0,1] neg_hi:[0,0,1]
	v_mul_f32_e32 v12, 0.5, v55
	v_pk_fma_f32 v[72:73], v[4:5], s[8:9], v[118:119] op_sel_hi:[0,1,1]
	v_mov_b32_e32 v55, v53
	v_mul_f32_e32 v6, 0.5, v52
	v_mov_b32_e32 v56, v58
	v_mov_b32_e32 v57, v73
	v_pk_mul_f32 v[52:53], v[54:55], s[44:45]
	v_pk_fma_f32 v[48:49], v[70:71], 0.5, v[48:49] op_sel_hi:[1,0,1] neg_lo:[1,0,0] neg_hi:[1,0,0]
	v_pk_mul_f32 v[54:55], v[56:57], v[52:53] op_sel:[0,1] op_sel_hi:[1,0]
	v_pk_mul_f32 v[52:53], v[56:57], v[52:53]
	v_pk_add_f32 v[54:55], v[54:55], v[54:55] op_sel:[0,1] op_sel_hi:[0,1]
	v_pk_add_f32 v[74:75], v[6:7], v[54:55] op_sel_hi:[0,1] neg_hi:[0,1]
	v_pk_add_f32 v[52:53], v[52:53], v[52:53] op_sel:[0,1] op_sel_hi:[0,1] neg_lo:[0,1] neg_hi:[0,1]
	v_pk_add_f32 v[54:55], v[12:13], v[52:53] op_sel_hi:[0,1] neg_hi:[0,1]
	v_pk_mul_f32 v[52:53], v[54:55], v[116:117]
	v_pk_mul_f32 v[54:55], v[54:55], v[114:115]
	v_pk_fma_f32 v[52:53], v[74:75], v[114:115], v[52:53]
	v_pk_fma_f32 v[54:55], v[74:75], v[116:117], v[54:55] neg_lo:[0,0,1] neg_hi:[0,0,1]
	v_pk_mov_b32 v[70:71], v[72:73], v[58:59] op_sel:[1,0]
	v_pk_add_f32 v[74:75], v[54:55], v[52:53] op_sel:[0,1] op_sel_hi:[1,0] neg_lo:[0,1]
	v_pk_add_f32 v[76:77], v[54:55], v[52:53] op_sel:[0,1] op_sel_hi:[1,0]
	v_pk_add_f32 v[52:53], v[52:53], v[54:55] op_sel:[1,0] op_sel_hi:[0,1] neg_lo:[0,1] neg_hi:[0,1]
	v_pk_mul_f32 v[74:75], v[74:75], 0.5 op_sel_hi:[1,0]
	v_mov_b32_e32 v77, v53
	v_mul_f32_e32 v6, v58, v74
	v_pk_fma_f32 v[112:113], v[56:57], v[74:75], v[6:7] op_sel_hi:[1,1,0] neg_lo:[1,0,0] neg_hi:[1,0,0]
	v_mul_f32_e32 v6, v58, v75
	v_pk_fma_f32 v[70:71], v[70:71], v[74:75], v[6:7] op_sel_hi:[1,1,0]
	v_pk_add_f32 v[54:55], v[34:35], v[110:111]
	v_mov_b32_e32 v112, v70
	v_pk_fma_f32 v[52:53], v[76:77], 0.5, v[70:71] op_sel_hi:[1,0,1] neg_lo:[0,0,1] neg_hi:[0,0,1]
	v_pk_fma_f32 v[86:87], v[76:77], 0.5, v[112:113] op_sel_hi:[1,0,1]
	v_sub_f32_e32 v12, v35, v111
	v_mov_b32_e32 v53, v87
	v_pk_mul_f32 v[78:79], v[52:53], s[6:7] op_sel_hi:[1,0]
	v_mul_f32_e32 v52, 0xbe47c5c2, v83
	v_mov_b32_e32 v53, v34
	v_pk_mov_b32 v[34:35], v[118:119], v[110:111] op_sel:[1,0]
	v_mul_f32_e32 v18, 0.5, v55
	v_pk_add_f32 v[34:35], v[52:53], v[34:35] neg_lo:[0,1] neg_hi:[0,1]
	v_mov_b32_e32 v71, v58
	v_pk_mul_f32 v[52:53], v[34:35], v[18:19]
	v_mov_b32_e32 v70, v34
	v_pk_fma_f32 v[56:57], v[56:57], v[52:53], v[52:53] op_sel:[0,1,0] op_sel_hi:[1,0,1]
	v_mov_b32_e32 v52, v53
	v_mov_b32_e32 v53, v18
	v_mul_f32_e32 v6, 0.5, v54
	v_pk_mul_f32 v[52:53], v[70:71], v[52:53]
	v_cvt_f32_f16_e32 v70, v46
	v_cvt_f32_f16_e32 v71, v47
	v_cvt_f32_f16_sdwa v47, v47 dst_sel:DWORD dst_unused:UNUSED_PAD src0_sel:WORD_1
	v_cvt_f32_f16_sdwa v46, v46 dst_sel:DWORD dst_unused:UNUSED_PAD src0_sel:WORD_1
	v_pk_fma_f32 v[74:75], v[76:77], 0.5, v[112:113] op_sel_hi:[1,0,1] neg_lo:[1,0,0] neg_hi:[1,0,0]
	v_mul_f32_e32 v12, 0.5, v12
	v_pk_add_f32 v[76:77], v[6:7], v[56:57]
	v_pk_add_f32 v[52:53], v[52:53], v[52:53] op_sel:[0,1] op_sel_hi:[0,1] neg_lo:[0,1] neg_hi:[0,1]
	v_fma_f32 v77, v54, 0.5, -v56
	v_pk_add_f32 v[54:55], v[12:13], v[52:53] op_sel_hi:[0,1] neg_hi:[0,1]
	v_pk_mul_f32 v[52:53], v[54:55], v[46:47]
	v_pk_mul_f32 v[54:55], v[54:55], v[70:71]
	v_pk_fma_f32 v[56:57], v[76:77], v[70:71], v[52:53] neg_lo:[0,0,1] neg_hi:[0,0,1]
	v_pk_fma_f32 v[52:53], v[76:77], v[70:71], v[52:53]
	v_pk_fma_f32 v[70:71], v[76:77], v[46:47], v[54:55]
	v_pk_fma_f32 v[46:47], v[76:77], v[46:47], v[54:55] neg_lo:[0,0,1] neg_hi:[0,0,1]
	v_pk_add_f32 v[54:55], v[56:57], v[52:53] op_sel:[0,1] op_sel_hi:[1,0]
	v_pk_add_f32 v[76:77], v[70:71], v[46:47] op_sel_hi:[0,1] neg_lo:[0,1] neg_hi:[0,1]
	v_pk_add_f32 v[52:53], v[56:57], v[52:53] op_sel_hi:[0,1] neg_lo:[0,1] neg_hi:[0,1]
	v_pk_add_f32 v[46:47], v[70:71], v[46:47] op_sel:[0,1] op_sel_hi:[1,0]
	v_mov_b32_e32 v55, v77
	v_mov_b32_e32 v47, v53
	v_pk_mul_f32 v[46:47], v[46:47], 0.5 op_sel_hi:[1,0]
	s_mov_b32 s25, s27
	v_pk_mul_f32 v[52:53], v[58:59], v[46:47] op_sel:[0,1] op_sel_hi:[0,0]
	v_pk_fma_f32 v[56:57], v[34:35], v[46:47], v[52:53] op_sel_hi:[0,1,1]
	v_pk_fma_f32 v[46:47], v[34:35], v[46:47], v[52:53] op_sel_hi:[0,1,1] neg_hi:[0,0,1]
	s_nop 0
	v_pk_fma_f32 v[52:53], v[54:55], 0.5, v[56:57] op_sel_hi:[1,0,1] neg_lo:[0,0,1] neg_hi:[0,0,1]
	v_pk_fma_f32 v[34:35], v[54:55], 0.5, v[46:47] op_sel_hi:[1,0,1]
	s_mov_b32 s78, s27
	v_mov_b32_e32 v53, v35
	v_pk_mul_f32 v[136:137], v[52:53], s[6:7] op_sel_hi:[1,0]
	v_pk_fma_f32 v[52:53], v[54:55], 0.5, v[46:47] op_sel_hi:[1,0,1] neg_lo:[1,0,0] neg_hi:[1,0,0]
	s_mov_b32 s79, s24
	v_pk_mul_f32 v[46:47], v[82:83], s[24:25] op_sel_hi:[0,1]
	v_pk_add_f32 v[54:55], v[108:109], v[40:41]
	v_pk_add_f32 v[40:41], v[40:41], v[108:109] neg_lo:[0,1] neg_hi:[0,1]
	v_pk_fma_f32 v[108:109], v[4:5], s[78:79], v[46:47] op_sel_hi:[0,1,1] neg_lo:[0,0,1] neg_hi:[0,0,1]
	v_mul_f32_e32 v12, 0.5, v41
	v_pk_fma_f32 v[70:71], v[4:5], s[78:79], v[46:47] op_sel_hi:[0,1,1]
	v_mov_b32_e32 v41, v55
	v_mov_b32_e32 v56, v108
	v_mov_b32_e32 v57, v71
	v_pk_mul_f32 v[40:41], v[40:41], s[44:45]
	v_mul_f32_e32 v6, 0.5, v54
	v_pk_mul_f32 v[54:55], v[56:57], v[40:41] op_sel:[0,1] op_sel_hi:[1,0]
	v_cvt_f32_f16_sdwa v76, v36 dst_sel:DWORD dst_unused:UNUSED_PAD src0_sel:WORD_1
	v_cvt_f32_f16_e32 v77, v37
	v_cvt_f32_f16_sdwa v37, v37 dst_sel:DWORD dst_unused:UNUSED_PAD src0_sel:WORD_1
	v_cvt_f32_f16_e32 v36, v36
	v_pk_mul_f32 v[40:41], v[56:57], v[40:41]
	v_pk_add_f32 v[54:55], v[54:55], v[54:55] op_sel:[0,1] op_sel_hi:[0,1]
	v_pk_add_f32 v[112:113], v[6:7], v[54:55] op_sel_hi:[0,1] neg_hi:[0,1]
	s_nop 0
	v_pk_add_f32 v[40:41], v[40:41], v[40:41] op_sel:[0,1] op_sel_hi:[0,1] neg_lo:[0,1] neg_hi:[0,1]
	v_pk_add_f32 v[54:55], v[12:13], v[40:41] op_sel_hi:[0,1] neg_hi:[0,1]
	v_pk_mul_f32 v[40:41], v[54:55], v[36:37]
	v_pk_mul_f32 v[54:55], v[54:55], v[76:77]
	v_pk_fma_f32 v[40:41], v[112:113], v[76:77], v[40:41]
	v_pk_fma_f32 v[36:37], v[112:113], v[36:37], v[54:55] neg_lo:[0,0,1] neg_hi:[0,0,1]
	v_pk_mov_b32 v[110:111], v[70:71], v[108:109] op_sel:[1,0]
	v_pk_add_f32 v[54:55], v[36:37], v[40:41] op_sel:[0,1] op_sel_hi:[1,0] neg_lo:[0,1]
	v_pk_add_f32 v[76:77], v[36:37], v[40:41] op_sel:[0,1] op_sel_hi:[1,0]
	v_pk_add_f32 v[36:37], v[40:41], v[36:37] op_sel:[1,0] op_sel_hi:[0,1] neg_lo:[0,1] neg_hi:[0,1]
	v_pk_mul_f32 v[54:55], v[54:55], 0.5 op_sel_hi:[1,0]
	v_mov_b32_e32 v77, v37
	v_mul_f32_e32 v4, v108, v54
	v_pk_fma_f32 v[112:113], v[56:57], v[54:55], v[4:5] op_sel_hi:[1,1,0] neg_lo:[1,0,0] neg_hi:[1,0,0]
	v_mul_f32_e32 v4, v108, v55
	v_pk_fma_f32 v[54:55], v[110:111], v[54:55], v[4:5] op_sel_hi:[1,1,0]
	v_sub_f32_e32 v6, v45, v105
	v_mov_b32_e32 v112, v54
	v_pk_fma_f32 v[40:41], v[76:77], 0.5, v[54:55] op_sel_hi:[1,0,1] neg_lo:[0,0,1] neg_hi:[0,0,1]
	v_pk_fma_f32 v[36:37], v[76:77], 0.5, v[112:113] op_sel_hi:[1,0,1]
	v_pk_add_f32 v[54:55], v[104:105], v[44:45]
	v_mov_b32_e32 v41, v37
	v_pk_mul_f32 v[130:131], v[40:41], s[6:7] op_sel_hi:[1,0]
	v_mul_f32_e32 v40, 0xbf54db31, v83
	v_mov_b32_e32 v41, v44
	v_pk_mov_b32 v[44:45], v[46:47], v[104:105] op_sel:[1,0]
	v_mul_f32_e32 v18, 0.5, v55
	v_pk_add_f32 v[40:41], v[40:41], v[44:45] neg_lo:[0,1] neg_hi:[0,1]
	v_mov_b32_e32 v105, v108
	v_pk_mul_f32 v[44:45], v[40:41], v[18:19]
	v_mov_b32_e32 v104, v40
	v_pk_fma_f32 v[56:57], v[56:57], v[44:45], v[44:45] op_sel:[0,1,0] op_sel_hi:[1,0,1]
	v_mov_b32_e32 v44, v45
	v_mov_b32_e32 v45, v18
	v_mul_f32_e32 v4, 0.5, v54
	v_pk_mul_f32 v[44:45], v[104:105], v[44:45]
	v_cvt_f32_f16_e32 v104, v26
	v_cvt_f32_f16_e32 v105, v27
	v_cvt_f32_f16_sdwa v27, v27 dst_sel:DWORD dst_unused:UNUSED_PAD src0_sel:WORD_1
	v_cvt_f32_f16_sdwa v26, v26 dst_sel:DWORD dst_unused:UNUSED_PAD src0_sel:WORD_1
	v_mul_f32_e32 v6, 0.5, v6
	v_pk_add_f32 v[110:111], v[4:5], v[56:57]
	v_pk_add_f32 v[44:45], v[44:45], v[44:45] op_sel:[0,1] op_sel_hi:[0,1] neg_lo:[0,1] neg_hi:[0,1]
	v_fma_f32 v111, v54, 0.5, -v56
	v_pk_add_f32 v[54:55], v[6:7], v[44:45] op_sel_hi:[0,1] neg_hi:[0,1]
	v_pk_mul_f32 v[44:45], v[54:55], v[26:27]
	v_pk_mul_f32 v[54:55], v[54:55], v[104:105]
	v_pk_fma_f32 v[56:57], v[110:111], v[104:105], v[44:45] neg_lo:[0,0,1] neg_hi:[0,0,1]
	v_pk_fma_f32 v[44:45], v[110:111], v[104:105], v[44:45]
	v_pk_fma_f32 v[104:105], v[110:111], v[26:27], v[54:55]
	v_pk_fma_f32 v[26:27], v[110:111], v[26:27], v[54:55] neg_lo:[0,0,1] neg_hi:[0,0,1]
	v_pk_add_f32 v[54:55], v[56:57], v[44:45] op_sel:[0,1] op_sel_hi:[1,0]
	v_pk_add_f32 v[110:111], v[104:105], v[26:27] op_sel_hi:[0,1] neg_lo:[0,1] neg_hi:[0,1]
	v_pk_add_f32 v[44:45], v[56:57], v[44:45] op_sel_hi:[0,1] neg_lo:[0,1] neg_hi:[0,1]
	v_pk_add_f32 v[26:27], v[104:105], v[26:27] op_sel:[0,1] op_sel_hi:[1,0]
	v_mov_b32_e32 v55, v111
	v_mov_b32_e32 v27, v45
	v_pk_mul_f32 v[26:27], v[26:27], 0.5 op_sel_hi:[1,0]
	v_mov_b32_e32 v47, v102
	v_pk_mul_f32 v[44:45], v[108:109], v[26:27] op_sel:[0,1] op_sel_hi:[0,0]
	v_pk_fma_f32 v[56:57], v[40:41], v[26:27], v[44:45] op_sel_hi:[0,1,1]
	v_pk_fma_f32 v[40:41], v[40:41], v[26:27], v[44:45] op_sel_hi:[0,1,1] neg_hi:[0,0,1]
	v_pk_fma_f32 v[44:45], v[54:55], 0.5, v[56:57] op_sel_hi:[1,0,1] neg_lo:[0,0,1] neg_hi:[0,0,1]
	v_pk_fma_f32 v[26:27], v[54:55], 0.5, v[40:41] op_sel_hi:[1,0,1]
	v_pk_fma_f32 v[56:57], v[54:55], 0.5, v[40:41] op_sel_hi:[1,0,1] neg_lo:[1,0,0] neg_hi:[1,0,0]
	v_pk_add_f32 v[40:41], v[106:107], v[42:43]
	v_pk_add_f32 v[42:43], v[42:43], v[106:107] neg_lo:[0,1] neg_hi:[0,1]
	v_mov_b32_e32 v45, v27
	v_mul_f32_e32 v6, 0.5, v43
	v_mov_b32_e32 v43, v41
	v_pk_mul_f32 v[120:121], v[44:45], s[6:7] op_sel_hi:[1,0]
	v_mul_f32_e32 v4, 0.5, v40
	v_pk_mov_b32 v[44:45], v[108:109], v[70:71] op_sel:[1,0]
	v_pk_mul_f32 v[40:41], v[42:43], s[44:45]
	v_cvt_f32_f16_sdwa v54, v20 dst_sel:DWORD dst_unused:UNUSED_PAD src0_sel:WORD_1
	v_pk_mul_f32 v[42:43], v[44:45], v[40:41] op_sel:[0,1] op_sel_hi:[1,0]
	v_cvt_f32_f16_e32 v55, v21
	v_cvt_f32_f16_sdwa v21, v21 dst_sel:DWORD dst_unused:UNUSED_PAD src0_sel:WORD_1
	v_cvt_f32_f16_e32 v20, v20
	v_pk_mul_f32 v[40:41], v[44:45], v[40:41]
	v_pk_add_f32 v[42:43], v[42:43], v[42:43] op_sel:[0,1] op_sel_hi:[0,1]
	v_pk_add_f32 v[104:105], v[4:5], v[42:43] op_sel_hi:[0,1] neg_hi:[0,1]
	s_nop 0
	v_pk_add_f32 v[40:41], v[40:41], v[40:41] op_sel:[0,1] op_sel_hi:[0,1] neg_lo:[0,1] neg_hi:[0,1]
	v_pk_add_f32 v[42:43], v[6:7], v[40:41] op_sel_hi:[0,1] neg_hi:[0,1]
	v_pk_mul_f32 v[40:41], v[42:43], v[20:21]
	v_pk_mul_f32 v[42:43], v[42:43], v[54:55]
	v_pk_fma_f32 v[40:41], v[104:105], v[54:55], v[40:41]
	v_pk_fma_f32 v[20:21], v[104:105], v[20:21], v[42:43] neg_lo:[0,0,1] neg_hi:[0,0,1]
	v_mov_b32_e32 v71, v109
	v_pk_add_f32 v[42:43], v[20:21], v[40:41] op_sel:[0,1] op_sel_hi:[1,0] neg_lo:[0,1]
	v_pk_add_f32 v[54:55], v[20:21], v[40:41] op_sel:[0,1] op_sel_hi:[1,0]
	v_pk_add_f32 v[20:21], v[40:41], v[20:21] op_sel:[1,0] op_sel_hi:[0,1] neg_lo:[0,1] neg_hi:[0,1]
	v_pk_mul_f32 v[42:43], v[42:43], 0.5 op_sel_hi:[1,0]
	v_mov_b32_e32 v55, v21
	v_mul_f32_e32 v4, v109, v42
	v_pk_fma_f32 v[104:105], v[44:45], v[42:43], v[4:5] op_sel_hi:[1,1,0] neg_lo:[1,0,0] neg_hi:[1,0,0]
	v_mul_f32_e32 v4, v109, v43
	v_pk_fma_f32 v[42:43], v[70:71], v[42:43], v[4:5] op_sel_hi:[1,1,0]
	v_sub_f32_e32 v6, v23, v103
	v_mov_b32_e32 v104, v42
	v_pk_fma_f32 v[40:41], v[54:55], 0.5, v[42:43] op_sel_hi:[1,0,1] neg_lo:[0,0,1] neg_hi:[0,0,1]
	v_pk_fma_f32 v[20:21], v[54:55], 0.5, v[104:105] op_sel_hi:[1,0,1]
	v_pk_add_f32 v[42:43], v[102:103], v[22:23]
	v_mov_b32_e32 v41, v21
	v_pk_mul_f32 v[128:129], v[40:41], s[6:7] op_sel_hi:[1,0]
	v_mul_f32_e32 v40, 0xbf0e39da, v83
	v_mov_b32_e32 v41, v22
	v_mul_f32_e32 v18, 0.5, v43
	v_pk_add_f32 v[22:23], v[40:41], v[46:47] neg_lo:[0,1] neg_hi:[0,1]
	v_mov_b32_e32 v47, v109
	v_pk_mul_f32 v[40:41], v[22:23], v[18:19]
	v_mov_b32_e32 v46, v22
	v_pk_fma_f32 v[44:45], v[44:45], v[40:41], v[40:41] op_sel:[0,1,0] op_sel_hi:[1,0,1]
	v_mov_b32_e32 v40, v41
	v_mov_b32_e32 v41, v18
	v_mul_f32_e32 v4, 0.5, v42
	v_pk_mul_f32 v[40:41], v[46:47], v[40:41]
	v_cvt_f32_f16_e32 v46, v10
	v_cvt_f32_f16_e32 v47, v11
	v_cvt_f32_f16_sdwa v11, v11 dst_sel:DWORD dst_unused:UNUSED_PAD src0_sel:WORD_1
	v_cvt_f32_f16_sdwa v10, v10 dst_sel:DWORD dst_unused:UNUSED_PAD src0_sel:WORD_1
	v_pk_fma_f32 v[70:71], v[54:55], 0.5, v[104:105] op_sel_hi:[1,0,1] neg_lo:[1,0,0] neg_hi:[1,0,0]
	v_mul_f32_e32 v6, 0.5, v6
	v_pk_add_f32 v[54:55], v[4:5], v[44:45]
	v_pk_add_f32 v[40:41], v[40:41], v[40:41] op_sel:[0,1] op_sel_hi:[0,1] neg_lo:[0,1] neg_hi:[0,1]
	v_fma_f32 v55, v42, 0.5, -v44
	v_pk_add_f32 v[42:43], v[6:7], v[40:41] op_sel_hi:[0,1] neg_hi:[0,1]
	v_pk_mul_f32 v[40:41], v[42:43], v[10:11]
	v_pk_mul_f32 v[42:43], v[42:43], v[46:47]
	v_pk_fma_f32 v[44:45], v[54:55], v[46:47], v[40:41] neg_lo:[0,0,1] neg_hi:[0,0,1]
	v_pk_fma_f32 v[40:41], v[54:55], v[46:47], v[40:41]
	v_pk_fma_f32 v[46:47], v[54:55], v[10:11], v[42:43]
	v_pk_fma_f32 v[10:11], v[54:55], v[10:11], v[42:43] neg_lo:[0,0,1] neg_hi:[0,0,1]
	v_pk_add_f32 v[42:43], v[44:45], v[40:41] op_sel:[0,1] op_sel_hi:[1,0]
	v_pk_add_f32 v[54:55], v[46:47], v[10:11] op_sel_hi:[0,1] neg_lo:[0,1] neg_hi:[0,1]
	v_pk_add_f32 v[40:41], v[44:45], v[40:41] op_sel_hi:[0,1] neg_lo:[0,1] neg_hi:[0,1]
	v_pk_add_f32 v[10:11], v[46:47], v[10:11] op_sel:[0,1] op_sel_hi:[1,0]
	v_mov_b32_e32 v43, v55
	v_mov_b32_e32 v11, v41
	v_pk_mul_f32 v[10:11], v[10:11], 0.5 op_sel_hi:[1,0]
	v_mov_b32_e32 v119, v98
	v_pk_mul_f32 v[40:41], v[108:109], v[10:11] op_sel:[1,1] op_sel_hi:[1,0]
	v_pk_fma_f32 v[76:77], v[76:77], 0.5, v[112:113] op_sel_hi:[1,0,1] neg_lo:[1,0,0] neg_hi:[1,0,0]
	v_pk_fma_f32 v[44:45], v[22:23], v[10:11], v[40:41] op_sel_hi:[0,1,1]
	v_pk_fma_f32 v[10:11], v[22:23], v[10:11], v[40:41] op_sel_hi:[0,1,1] neg_hi:[0,0,1]
	v_pk_fma_f32 v[22:23], v[42:43], 0.5, v[44:45] op_sel_hi:[1,0,1] neg_lo:[0,0,1] neg_hi:[0,0,1]
	v_pk_fma_f32 v[40:41], v[42:43], 0.5, v[10:11] op_sel_hi:[1,0,1]
	v_pk_fma_f32 v[54:55], v[42:43], 0.5, v[10:11] op_sel_hi:[1,0,1] neg_lo:[1,0,0] neg_hi:[1,0,0]
	v_pk_add_f32 v[10:11], v[100:101], v[14:15]
	v_pk_add_f32 v[14:15], v[14:15], v[100:101] neg_lo:[0,1] neg_hi:[0,1]
	v_mov_b32_e32 v23, v41
	v_mul_f32_e32 v6, 0.5, v15
	v_mov_b32_e32 v15, v11
	v_pk_mul_f32 v[150:151], v[22:23], s[6:7] op_sel_hi:[1,0]
	v_mul_f32_e32 v4, 0.5, v10
	v_pk_mov_b32 v[22:23], v[58:59], v[72:73] op_sel:[1,0]
	v_pk_mul_f32 v[10:11], v[14:15], s[44:45]
	v_cvt_f32_f16_sdwa v42, v8 dst_sel:DWORD dst_unused:UNUSED_PAD src0_sel:WORD_1
	v_pk_mul_f32 v[14:15], v[22:23], v[10:11] op_sel:[0,1] op_sel_hi:[1,0]
	v_cvt_f32_f16_e32 v43, v9
	v_cvt_f32_f16_sdwa v9, v9 dst_sel:DWORD dst_unused:UNUSED_PAD src0_sel:WORD_1
	v_cvt_f32_f16_e32 v8, v8
	v_pk_mul_f32 v[10:11], v[22:23], v[10:11]
	v_pk_add_f32 v[14:15], v[14:15], v[14:15] op_sel:[0,1] op_sel_hi:[0,1]
	v_pk_add_f32 v[44:45], v[4:5], v[14:15] op_sel_hi:[0,1] neg_hi:[0,1]
	s_nop 0
	v_pk_add_f32 v[10:11], v[10:11], v[10:11] op_sel:[0,1] op_sel_hi:[0,1] neg_lo:[0,1] neg_hi:[0,1]
	v_pk_add_f32 v[14:15], v[6:7], v[10:11] op_sel_hi:[0,1] neg_hi:[0,1]
	v_pk_mul_f32 v[10:11], v[14:15], v[8:9]
	v_pk_mul_f32 v[14:15], v[14:15], v[42:43]
	v_pk_fma_f32 v[10:11], v[44:45], v[42:43], v[10:11]
	v_pk_fma_f32 v[8:9], v[44:45], v[8:9], v[14:15] neg_lo:[0,0,1] neg_hi:[0,0,1]
	v_mov_b32_e32 v73, v59
	v_pk_add_f32 v[14:15], v[8:9], v[10:11] op_sel:[0,1] op_sel_hi:[1,0] neg_lo:[0,1]
	v_pk_add_f32 v[42:43], v[8:9], v[10:11] op_sel:[0,1] op_sel_hi:[1,0]
	v_pk_add_f32 v[8:9], v[10:11], v[8:9] op_sel:[1,0] op_sel_hi:[0,1] neg_lo:[0,1] neg_hi:[0,1]
	v_pk_mul_f32 v[14:15], v[14:15], 0.5 op_sel_hi:[1,0]
	v_mov_b32_e32 v43, v9
	v_mul_f32_e32 v4, v59, v14
	v_pk_fma_f32 v[44:45], v[22:23], v[14:15], v[4:5] op_sel_hi:[1,1,0] neg_lo:[1,0,0] neg_hi:[1,0,0]
	v_mul_f32_e32 v4, v59, v15
	v_pk_fma_f32 v[14:15], v[72:73], v[14:15], v[4:5] op_sel_hi:[1,1,0]
	v_sub_f32_e32 v6, v39, v99
	v_mov_b32_e32 v44, v14
	v_pk_fma_f32 v[8:9], v[42:43], 0.5, v[14:15] op_sel_hi:[1,0,1] neg_lo:[0,0,1] neg_hi:[0,0,1]
	v_pk_fma_f32 v[10:11], v[42:43], 0.5, v[44:45] op_sel_hi:[1,0,1]
	v_pk_add_f32 v[14:15], v[98:99], v[38:39]
	v_mov_b32_e32 v9, v11
	v_pk_mul_f32 v[168:169], v[8:9], s[6:7] op_sel_hi:[1,0]
	v_mul_f32_e32 v8, 0xbf7b14be, v83
	v_mov_b32_e32 v9, v38
	v_mul_f32_e32 v18, 0.5, v15
	v_pk_add_f32 v[8:9], v[8:9], v[118:119] neg_lo:[0,1] neg_hi:[0,1]
	v_pk_fma_f32 v[72:73], v[42:43], 0.5, v[44:45] op_sel_hi:[1,0,1] neg_lo:[1,0,0] neg_hi:[1,0,0]
	v_pk_mul_f32 v[38:39], v[8:9], v[18:19]
	v_mov_b32_e32 v42, v8
	v_pk_fma_f32 v[22:23], v[22:23], v[38:39], v[38:39] op_sel:[0,1,0] op_sel_hi:[1,0,1]
	v_mov_b32_e32 v43, v59
	v_mov_b32_e32 v38, v39
	v_mov_b32_e32 v39, v18
	v_mul_f32_e32 v4, 0.5, v14
	v_pk_mul_f32 v[38:39], v[42:43], v[38:39]
	v_cvt_f32_f16_e32 v44, v2
	v_cvt_f32_f16_e32 v45, v3
	v_cvt_f32_f16_sdwa v3, v3 dst_sel:DWORD dst_unused:UNUSED_PAD src0_sel:WORD_1
	v_cvt_f32_f16_sdwa v2, v2 dst_sel:DWORD dst_unused:UNUSED_PAD src0_sel:WORD_1
	v_mul_f32_e32 v6, 0.5, v6
	v_pk_add_f32 v[46:47], v[4:5], v[22:23]
	v_fma_f32 v4, v14, 0.5, -v22
	v_pk_add_f32 v[22:23], v[38:39], v[38:39] op_sel:[0,1] op_sel_hi:[0,1] neg_lo:[0,1] neg_hi:[0,1]
	v_pk_add_f32 v[38:39], v[6:7], v[22:23] op_sel_hi:[0,1] neg_hi:[0,1]
	v_mov_b32_e32 v14, v46
	v_mov_b32_e32 v15, v4
	v_pk_mul_f32 v[22:23], v[4:5], v[44:45] op_sel_hi:[0,1]
	v_pk_mul_f32 v[82:83], v[38:39], v[2:3]
	v_pk_mul_f32 v[46:47], v[46:47], v[2:3]
	v_pk_mul_f32 v[38:39], v[38:39], v[44:45]
	v_pk_fma_f32 v[98:99], v[14:15], v[44:45], v[82:83] neg_lo:[0,0,1] neg_hi:[0,0,1]
	v_pk_fma_f32 v[2:3], v[14:15], v[2:3], v[38:39] neg_lo:[0,0,1] neg_hi:[0,0,1]
	v_add_f32_e32 v4, v23, v83
	v_add_f32_e32 v6, v46, v38
	v_pk_add_f32 v[22:23], v[6:7], v[2:3] op_sel_hi:[0,1] neg_lo:[0,1] neg_hi:[0,1]
	v_pk_add_f32 v[38:39], v[98:99], v[4:5] op_sel_hi:[1,0] neg_lo:[0,1] neg_hi:[0,1]
	v_pk_add_f32 v[2:3], v[6:7], v[2:3] op_sel_hi:[0,1]
	v_mov_b32_e32 v39, v3
	v_pk_mul_f32 v[2:3], v[38:39], 0.5 op_sel_hi:[1,0]
	v_pk_add_f32 v[14:15], v[98:99], v[4:5] op_sel_hi:[1,0]
	v_mul_f32_e32 v4, v59, v3
	v_pk_fma_f32 v[38:39], v[42:43], v[2:3], v[4:5] op_sel_hi:[1,1,0] neg_lo:[0,0,1] neg_hi:[0,0,1]
	v_pk_mov_b32 v[42:43], v[58:59], v[8:9] op_sel:[1,0]
	v_mul_f32_e32 v4, v8, v3
	v_pk_fma_f32 v[2:3], v[42:43], v[2:3], v[4:5] op_sel_hi:[1,1,0]
	v_mov_b32_e32 v15, v23
	v_pk_fma_f32 v[8:9], v[14:15], 0.5, v[2:3] op_sel_hi:[1,0,1] neg_lo:[0,0,1] neg_hi:[0,0,1]
	v_pk_fma_f32 v[42:43], v[14:15], 0.5, v[38:39] op_sel_hi:[1,0,0]
	v_pk_fma_f32 v[2:3], v[14:15], 0.5, v[2:3] op_sel_hi:[1,0,1]
	v_mov_b32_e32 v9, v43
	v_pk_fma_f32 v[58:59], v[22:23], 0.5, v[38:39] op_sel_hi:[1,0,0] neg_lo:[1,0,0] neg_hi:[1,0,0]
	v_pk_mul_f32 v[144:145], v[8:9], s[6:7] op_sel_hi:[1,0]
	v_mov_b32_e32 v58, v2
	v_mov_b32_e32 v72, v10
	v_mov_b32_e32 v54, v40
	v_mov_b32_e32 v70, v20
	v_mov_b32_e32 v56, v26
	v_mov_b32_e32 v76, v36
	v_mov_b32_e32 v52, v34
	v_mov_b32_e32 v74, v86
	v_mov_b32_e32 v48, v84
	v_mov_b32_e32 v50, v60
	v_mov_b32_e32 v28, v66
	v_mov_b32_e32 v32, v96
	v_mov_b32_e32 v12, v88
	v_mov_b32_e32 v16, v92
	v_mov_b32_e32 v4, v138
	v_mov_b32_e32 v6, v122

.LBB0_503:
	s_or_b64 exec, exec, s[0:1]
	v_pk_mul_f32 v[22:23], v[32:33], s[6:7] op_sel_hi:[1,0]
	v_pk_add_f32 v[26:27], v[24:25], v[30:31]
	v_pk_add_f32 v[24:25], v[24:25], v[30:31] neg_lo:[0,1] neg_hi:[0,1]
	v_pk_add_f32 v[30:31], v[64:65], v[68:69]
	v_pk_add_f32 v[32:33], v[64:65], v[68:69] neg_lo:[0,1] neg_hi:[0,1]
	v_pk_add_f32 v[34:35], v[62:63], v[90:91]
	v_pk_add_f32 v[38:39], v[94:95], v[80:81]
	v_pk_add_f32 v[68:69], v[26:27], v[30:31]
	v_pk_add_f32 v[26:27], v[26:27], v[30:31] neg_lo:[0,1] neg_hi:[0,1]
	v_xor_b32_e32 v30, 0x80000000, v33
	v_mov_b32_e32 v31, v32
	v_pk_mul_f32 v[20:21], v[50:51], s[6:7] op_sel_hi:[1,0]
	v_pk_add_f32 v[36:37], v[62:63], v[90:91] neg_lo:[0,1] neg_hi:[0,1]
	v_pk_add_f32 v[42:43], v[78:79], v[136:137]
	v_pk_add_f32 v[46:47], v[130:131], v[120:121]
	v_pk_add_f32 v[32:33], v[24:25], v[30:31]
	v_pk_add_f32 v[24:25], v[24:25], v[30:31] neg_lo:[0,1] neg_hi:[0,1]
	v_pk_add_f32 v[30:31], v[34:35], v[38:39]
	v_pk_add_f32 v[34:35], v[34:35], v[38:39] neg_lo:[0,1] neg_hi:[0,1]
	v_pk_add_f32 v[38:39], v[94:95], v[80:81] neg_lo:[0,1] neg_hi:[0,1]
	v_pk_add_f32 v[44:45], v[78:79], v[136:137] neg_lo:[0,1] neg_hi:[0,1]
	v_pk_add_f32 v[60:61], v[128:129], v[150:151]
	v_pk_add_f32 v[64:65], v[168:169], v[144:145]
	v_pk_add_f32 v[40:41], v[36:37], v[38:39] op_sel:[0,1] op_sel_hi:[1,0] neg_lo:[0,1]
	v_pk_add_f32 v[36:37], v[36:37], v[38:39] op_sel:[0,1] op_sel_hi:[1,0] neg_hi:[0,1]
	v_pk_add_f32 v[38:39], v[42:43], v[46:47]
	v_pk_add_f32 v[42:43], v[42:43], v[46:47] neg_lo:[0,1] neg_hi:[0,1]
	v_pk_add_f32 v[46:47], v[130:131], v[120:121] neg_lo:[0,1] neg_hi:[0,1]
	v_pk_add_f32 v[62:63], v[128:129], v[150:151] neg_lo:[0,1] neg_hi:[0,1]
	v_pk_add_f32 v[50:51], v[44:45], v[46:47] op_sel:[0,1] op_sel_hi:[1,0] neg_lo:[0,1]
	v_pk_add_f32 v[44:45], v[44:45], v[46:47] op_sel:[0,1] op_sel_hi:[1,0] neg_hi:[0,1]
	v_pk_add_f32 v[46:47], v[60:61], v[64:65]
	v_pk_add_f32 v[60:61], v[60:61], v[64:65] neg_lo:[0,1] neg_hi:[0,1]
	v_pk_add_f32 v[64:65], v[168:169], v[144:145] neg_lo:[0,1] neg_hi:[0,1]
	s_mov_b32 s78, s37
	s_mov_b32 s79, s36
	v_pk_add_f32 v[66:67], v[62:63], v[64:65] op_sel:[0,1] op_sel_hi:[1,0] neg_lo:[0,1]
	v_pk_add_f32 v[62:63], v[62:63], v[64:65] op_sel:[0,1] op_sel_hi:[1,0] neg_hi:[0,1]
	v_pk_add_f32 v[64:65], v[68:69], v[30:31]
	v_pk_add_f32 v[30:31], v[68:69], v[30:31] neg_lo:[0,1] neg_hi:[0,1]
	s_mov_b32 s0, s37
	v_pk_mul_f32 v[68:69], v[40:41], s[78:79]
	s_mov_b32 s80, s19
	v_pk_fma_f32 v[40:41], v[40:41], s[0:1], v[68:69] op_sel:[0,0,1] op_sel_hi:[1,0,0]
	s_mov_b32 s81, s18
	v_pk_add_f32 v[68:69], v[32:33], v[40:41]
	v_pk_add_f32 v[32:33], v[32:33], v[40:41] neg_lo:[0,1] neg_hi:[0,1]
	v_xor_b32_e32 v40, 0x80000000, v35
	v_mov_b32_e32 v41, v34
	v_pk_add_f32 v[34:35], v[26:27], v[40:41]
	v_pk_add_f32 v[26:27], v[26:27], v[40:41] neg_lo:[0,1] neg_hi:[0,1]
	v_pk_mul_f32 v[40:41], v[36:37], s[78:79]
	s_mov_b32 s82, s19
	v_pk_fma_f32 v[36:37], v[36:37], s[0:1], v[40:41] op_sel:[0,0,1] op_sel_hi:[1,0,0] neg_lo:[1,0,0] neg_hi:[1,0,0]
	v_pk_mul_f32 v[2:3], v[72:73], s[6:7] op_sel_hi:[1,0]
	v_pk_add_f32 v[40:41], v[24:25], v[36:37]
	v_pk_add_f32 v[24:25], v[24:25], v[36:37] neg_lo:[0,1] neg_hi:[0,1]
	v_pk_add_f32 v[36:37], v[38:39], v[46:47]
	v_pk_add_f32 v[38:39], v[38:39], v[46:47] neg_lo:[0,1] neg_hi:[0,1]
	v_pk_mul_f32 v[46:47], v[66:67], s[78:79]
	v_pk_mul_f32 v[8:9], v[70:71], s[6:7] op_sel_hi:[1,0]
	v_pk_fma_f32 v[46:47], v[66:67], s[0:1], v[46:47] op_sel:[0,0,1] op_sel_hi:[1,0,0]
	v_pk_mul_f32 v[10:11], v[76:77], s[6:7] op_sel_hi:[1,0]
	v_pk_add_f32 v[66:67], v[50:51], v[46:47]
	v_pk_add_f32 v[46:47], v[50:51], v[46:47] neg_lo:[0,1] neg_hi:[0,1]
	v_xor_b32_e32 v50, 0x80000000, v61
	v_mov_b32_e32 v51, v60
	v_pk_add_f32 v[60:61], v[42:43], v[50:51]
	v_pk_add_f32 v[42:43], v[42:43], v[50:51] neg_lo:[0,1] neg_hi:[0,1]
	v_pk_mul_f32 v[50:51], v[62:63], s[78:79]
	v_pk_mul_f32 v[14:15], v[74:75], s[6:7] op_sel_hi:[1,0]
	v_pk_fma_f32 v[50:51], v[62:63], s[0:1], v[50:51] op_sel:[0,0,1] op_sel_hi:[1,0,0] neg_lo:[1,0,0] neg_hi:[1,0,0]
	v_pk_mul_f32 v[16:17], v[16:17], s[6:7] op_sel_hi:[1,0]
	v_pk_add_f32 v[62:63], v[44:45], v[50:51]
	v_pk_add_f32 v[44:45], v[44:45], v[50:51] neg_lo:[0,1] neg_hi:[0,1]
	v_pk_add_f32 v[50:51], v[64:65], v[36:37]
	v_pk_add_f32 v[36:37], v[64:65], v[36:37] neg_lo:[0,1] neg_hi:[0,1]
	v_pk_mul_f32 v[64:65], v[66:67], s[80:81]
	v_pk_mul_f32 v[6:7], v[6:7], s[6:7] op_sel_hi:[1,0]
	v_pk_fma_f32 v[64:65], v[66:67], s[16:17], v[64:65] op_sel:[0,0,1] op_sel_hi:[1,0,0]
	s_mov_b32 s17, s40
	v_pk_add_f32 v[66:67], v[68:69], v[64:65]
	v_pk_add_f32 v[64:65], v[68:69], v[64:65] neg_lo:[0,1] neg_hi:[0,1]
	v_pk_mul_f32 v[68:69], v[60:61], s[78:79]
	s_mov_b32 s88, s11
	v_pk_fma_f32 v[60:61], v[60:61], s[0:1], v[68:69] op_sel:[0,0,1] op_sel_hi:[1,0,0]
	s_mov_b32 s89, s10
	v_pk_add_f32 v[68:69], v[34:35], v[60:61]
	v_pk_add_f32 v[34:35], v[34:35], v[60:61] neg_lo:[0,1] neg_hi:[0,1]
	v_pk_mul_f32 v[60:61], v[62:63], s[16:17]
	s_mov_b32 s62, s27
	v_pk_fma_f32 v[60:61], v[62:63], s[82:83], v[60:61] op_sel:[0,0,1] op_sel_hi:[1,0,0]
	s_mov_b32 s63, s26
	v_pk_add_f32 v[62:63], v[40:41], v[60:61]
	v_pk_add_f32 v[40:41], v[40:41], v[60:61] neg_lo:[0,1] neg_hi:[0,1]
	v_xor_b32_e32 v60, 0x80000000, v39
	v_mov_b32_e32 v61, v38
	v_pk_add_f32 v[38:39], v[30:31], v[60:61]
	v_pk_add_f32 v[30:31], v[30:31], v[60:61] neg_lo:[0,1] neg_hi:[0,1]
	v_pk_mul_f32 v[60:61], v[46:47], s[16:17]
	s_mov_b32 s84, s27
	v_pk_fma_f32 v[46:47], v[46:47], s[82:83], v[60:61] op_sel:[0,0,1] op_sel_hi:[1,0,0] neg_lo:[1,0,0] neg_hi:[1,0,0]
	s_mov_b32 s86, s11
	v_pk_add_f32 v[60:61], v[32:33], v[46:47]
	v_pk_add_f32 v[32:33], v[32:33], v[46:47] neg_lo:[0,1] neg_hi:[0,1]
	v_pk_mul_f32 v[46:47], v[42:43], s[78:79]
	s_ashr_i32 s73, s72, 31
	v_pk_fma_f32 v[42:43], s[0:1], v[42:43], v[46:47] op_sel:[0,0,1] op_sel_hi:[0,1,0] neg_lo:[0,1,0] neg_hi:[0,1,0]
	v_pk_add_f32 v[46:47], v[26:27], v[42:43]
	v_pk_add_f32 v[26:27], v[26:27], v[42:43] neg_lo:[0,1] neg_hi:[0,1]
	v_pk_mul_f32 v[42:43], v[44:45], s[80:81]
	s_nop 0
	v_pk_fma_f32 v[42:43], s[16:17], v[44:45], v[42:43] op_sel:[0,0,1] op_sel_hi:[0,1,0] neg_lo:[0,1,0] neg_hi:[0,1,0]
	v_pk_add_f32 v[44:45], v[24:25], v[42:43]
	v_pk_add_f32 v[24:25], v[24:25], v[42:43] neg_lo:[0,1] neg_hi:[0,1]
	v_pk_fma_f32 v[42:43], v[58:59], s[6:7], v[2:3] op_sel_hi:[1,0,1]
	v_pk_fma_f32 v[2:3], v[58:59], s[6:7], v[2:3] op_sel_hi:[1,0,1] neg_lo:[0,0,1] neg_hi:[0,0,1]
	v_pk_fma_f32 v[58:59], v[54:55], s[6:7], v[8:9] op_sel_hi:[1,0,1]
	v_pk_fma_f32 v[8:9], v[54:55], s[6:7], v[8:9] op_sel_hi:[1,0,1] neg_lo:[0,0,1] neg_hi:[0,0,1]
	v_pk_fma_f32 v[54:55], v[56:57], s[6:7], v[10:11] op_sel_hi:[1,0,1]
	v_pk_fma_f32 v[10:11], v[56:57], s[6:7], v[10:11] op_sel_hi:[1,0,1] neg_lo:[0,0,1] neg_hi:[0,0,1]
	v_pk_fma_f32 v[56:57], v[52:53], s[6:7], v[14:15] op_sel_hi:[1,0,1]
	v_pk_fma_f32 v[14:15], v[52:53], s[6:7], v[14:15] op_sel_hi:[1,0,1] neg_lo:[0,0,1] neg_hi:[0,0,1]
	v_pk_fma_f32 v[52:53], v[48:49], s[6:7], v[20:21] op_sel_hi:[1,0,1]
	v_pk_fma_f32 v[20:21], v[48:49], s[6:7], v[20:21] op_sel_hi:[1,0,1] neg_lo:[0,0,1] neg_hi:[0,0,1]
	v_pk_fma_f32 v[48:49], v[28:29], s[6:7], v[22:23] op_sel_hi:[1,0,1]
	v_pk_fma_f32 v[22:23], v[28:29], s[6:7], v[22:23] op_sel_hi:[1,0,1] neg_lo:[0,0,1] neg_hi:[0,0,1]
	v_pk_fma_f32 v[28:29], v[12:13], s[6:7], v[16:17] op_sel_hi:[1,0,1]
	v_pk_fma_f32 v[12:13], v[12:13], s[6:7], v[16:17] op_sel_hi:[1,0,1] neg_lo:[0,0,1] neg_hi:[0,0,1]
	v_pk_fma_f32 v[16:17], v[4:5], s[6:7], v[6:7] op_sel_hi:[1,0,1]
	v_pk_fma_f32 v[4:5], v[4:5], s[6:7], v[6:7] op_sel_hi:[1,0,1] neg_lo:[0,0,1] neg_hi:[0,0,1]
	v_pk_add_f32 v[6:7], v[58:59], v[42:43]
	v_pk_add_f32 v[42:43], v[42:43], v[58:59] neg_lo:[0,1] neg_hi:[0,1]
	v_xor_b32_e32 v58, 0x80000000, v9
	v_mov_b32_e32 v59, v8
	v_pk_add_f32 v[8:9], v[2:3], v[58:59]
	v_pk_add_f32 v[2:3], v[2:3], v[58:59] neg_lo:[0,1] neg_hi:[0,1]
	v_pk_add_f32 v[58:59], v[56:57], v[54:55]
	v_pk_add_f32 v[54:55], v[54:55], v[56:57] neg_lo:[0,1] neg_hi:[0,1]
	v_xor_b32_e32 v56, 0x80000000, v15
	v_mov_b32_e32 v57, v14
	v_pk_add_f32 v[14:15], v[10:11], v[56:57]
	v_pk_add_f32 v[10:11], v[10:11], v[56:57] neg_lo:[0,1] neg_hi:[0,1]
	v_pk_add_f32 v[56:57], v[48:49], v[52:53]
	v_pk_add_f32 v[48:49], v[52:53], v[48:49] neg_lo:[0,1] neg_hi:[0,1]
	v_xor_b32_e32 v52, 0x80000000, v23
	v_mov_b32_e32 v53, v22
	v_pk_add_f32 v[22:23], v[20:21], v[52:53]
	v_pk_add_f32 v[20:21], v[20:21], v[52:53] neg_lo:[0,1] neg_hi:[0,1]
	v_pk_add_f32 v[52:53], v[16:17], v[28:29]
	v_pk_add_f32 v[16:17], v[28:29], v[16:17] neg_lo:[0,1] neg_hi:[0,1]
	v_xor_b32_e32 v28, 0x80000000, v5
	v_mov_b32_e32 v29, v4
	v_pk_add_f32 v[4:5], v[12:13], v[28:29]
	v_pk_add_f32 v[12:13], v[12:13], v[28:29] neg_lo:[0,1] neg_hi:[0,1]
	v_pk_add_f32 v[28:29], v[58:59], v[6:7]
	v_pk_add_f32 v[6:7], v[6:7], v[58:59] neg_lo:[0,1] neg_hi:[0,1]
	v_pk_mul_f32 v[58:59], v[14:15], s[78:79]
	s_nop 0
	v_pk_fma_f32 v[14:15], s[0:1], v[14:15], v[58:59] op_sel:[0,0,1] op_sel_hi:[0,1,0]
	v_pk_add_f32 v[58:59], v[14:15], v[8:9]
	v_pk_add_f32 v[8:9], v[8:9], v[14:15] neg_lo:[0,1] neg_hi:[0,1]
	v_xor_b32_e32 v14, 0x80000000, v55
	v_mov_b32_e32 v15, v54
	v_pk_add_f32 v[54:55], v[14:15], v[42:43]
	v_pk_add_f32 v[14:15], v[42:43], v[14:15] neg_lo:[0,1] neg_hi:[0,1]
	v_pk_mul_f32 v[42:43], v[10:11], s[78:79]
	s_nop 0
	v_pk_fma_f32 v[10:11], s[0:1], v[10:11], v[42:43] op_sel:[0,0,1] op_sel_hi:[0,1,0] neg_lo:[0,1,0] neg_hi:[0,1,0]
	v_pk_add_f32 v[42:43], v[10:11], v[2:3]
	v_pk_add_f32 v[2:3], v[2:3], v[10:11] neg_lo:[0,1] neg_hi:[0,1]
	v_pk_add_f32 v[10:11], v[52:53], v[56:57]
	v_pk_add_f32 v[52:53], v[56:57], v[52:53] neg_lo:[0,1] neg_hi:[0,1]
	v_pk_mul_f32 v[56:57], v[4:5], s[78:79]
	s_nop 0
	v_pk_fma_f32 v[4:5], s[0:1], v[4:5], v[56:57] op_sel:[0,0,1] op_sel_hi:[0,1,0]
	v_pk_add_f32 v[56:57], v[4:5], v[22:23]
	v_pk_add_f32 v[4:5], v[22:23], v[4:5] neg_lo:[0,1] neg_hi:[0,1]
	v_xor_b32_e32 v22, 0x80000000, v17
	v_mov_b32_e32 v23, v16
	v_pk_add_f32 v[16:17], v[22:23], v[48:49]
	v_pk_add_f32 v[22:23], v[48:49], v[22:23] neg_lo:[0,1] neg_hi:[0,1]
	v_pk_mul_f32 v[48:49], v[12:13], s[78:79]
	s_nop 0
	v_pk_fma_f32 v[12:13], s[0:1], v[12:13], v[48:49] op_sel:[0,0,1] op_sel_hi:[0,1,0] neg_lo:[0,1,0] neg_hi:[0,1,0]
	v_pk_add_f32 v[48:49], v[12:13], v[20:21]
	v_pk_add_f32 v[12:13], v[20:21], v[12:13] neg_lo:[0,1] neg_hi:[0,1]
	v_pk_add_f32 v[20:21], v[10:11], v[28:29]
	v_pk_add_f32 v[10:11], v[28:29], v[10:11] neg_lo:[0,1] neg_hi:[0,1]
	v_pk_mul_f32 v[28:29], v[56:57], s[80:81]
	s_nop 0
	v_pk_fma_f32 v[28:29], s[16:17], v[56:57], v[28:29] op_sel:[0,0,1] op_sel_hi:[0,1,0]
	v_pk_add_f32 v[56:57], v[28:29], v[58:59]
	v_pk_add_f32 v[28:29], v[58:59], v[28:29] neg_lo:[0,1] neg_hi:[0,1]
	v_pk_mul_f32 v[58:59], v[16:17], s[78:79]
	s_nop 0
	v_pk_fma_f32 v[16:17], s[0:1], v[16:17], v[58:59] op_sel:[0,0,1] op_sel_hi:[0,1,0]
	v_pk_add_f32 v[58:59], v[16:17], v[54:55]
	v_pk_add_f32 v[16:17], v[54:55], v[16:17] neg_lo:[0,1] neg_hi:[0,1]
	v_pk_mul_f32 v[54:55], v[48:49], s[16:17]
	s_nop 0
	v_pk_fma_f32 v[48:49], s[82:83], v[48:49], v[54:55] op_sel:[0,0,1] op_sel_hi:[0,1,0]
	v_pk_add_f32 v[54:55], v[48:49], v[42:43]
	v_pk_add_f32 v[42:43], v[42:43], v[48:49] neg_lo:[0,1] neg_hi:[0,1]
	v_xor_b32_e32 v48, 0x80000000, v53
	v_mov_b32_e32 v49, v52
	v_pk_add_f32 v[52:53], v[48:49], v[6:7]
	v_pk_add_f32 v[6:7], v[6:7], v[48:49] neg_lo:[0,1] neg_hi:[0,1]
	v_pk_mul_f32 v[48:49], v[4:5], s[16:17]
	s_nop 0
	v_pk_fma_f32 v[4:5], s[82:83], v[4:5], v[48:49] op_sel:[0,0,1] op_sel_hi:[0,1,0] neg_lo:[0,1,0] neg_hi:[0,1,0]
	v_pk_add_f32 v[48:49], v[4:5], v[8:9]
	v_pk_add_f32 v[4:5], v[8:9], v[4:5] neg_lo:[0,1] neg_hi:[0,1]
	v_pk_mul_f32 v[8:9], v[22:23], s[78:79]
	s_nop 0
	v_pk_fma_f32 v[8:9], s[0:1], v[22:23], v[8:9] op_sel:[0,0,1] op_sel_hi:[0,1,0] neg_lo:[0,1,0] neg_hi:[0,1,0]
	v_pk_add_f32 v[22:23], v[8:9], v[14:15]
	v_pk_add_f32 v[8:9], v[14:15], v[8:9] neg_lo:[0,1] neg_hi:[0,1]
	v_pk_mul_f32 v[14:15], v[12:13], s[80:81]
	s_nop 0
	v_pk_fma_f32 v[12:13], s[16:17], v[12:13], v[14:15] op_sel:[0,0,1] op_sel_hi:[0,1,0] neg_lo:[0,1,0] neg_hi:[0,1,0]
	v_pk_add_f32 v[14:15], v[12:13], v[2:3]
	v_pk_add_f32 v[2:3], v[2:3], v[12:13] neg_lo:[0,1] neg_hi:[0,1]
	ds_write_b64 v211, v[50:51]
	ds_write_b64 v212, v[20:21]
	ds_write_b64 v211, v[66:67] offset:8
	ds_write_b64 v212, v[56:57] offset:8
	ds_write_b64 v211, v[68:69] offset:16
	ds_write_b64 v212, v[58:59] offset:16
	ds_write_b64 v211, v[62:63] offset:24
	ds_write_b64 v212, v[54:55] offset:24
	ds_write_b64 v211, v[38:39] offset:32
	ds_write_b64 v212, v[52:53] offset:32
	ds_write_b64 v211, v[60:61] offset:40
	ds_write_b64 v212, v[48:49] offset:40
	ds_write_b64 v211, v[46:47] offset:48
	ds_write_b64 v212, v[22:23] offset:48
	ds_write_b64 v211, v[44:45] offset:56
	ds_write_b64 v212, v[14:15] offset:56
	ds_write_b64 v211, v[36:37] offset:64
	ds_write_b64 v212, v[10:11] offset:64
	ds_write_b64 v211, v[64:65] offset:72
	ds_write_b64 v212, v[28:29] offset:72
	ds_write_b64 v211, v[34:35] offset:80
	ds_write_b64 v212, v[16:17] offset:80
	ds_write_b64 v211, v[40:41] offset:88
	ds_write_b64 v212, v[42:43] offset:88
	ds_write_b64 v211, v[30:31] offset:96
	ds_write_b64 v212, v[6:7] offset:96
	ds_write_b64 v211, v[32:33] offset:104
	ds_write_b64 v212, v[4:5] offset:104
	ds_write_b64 v211, v[26:27] offset:112
	ds_write_b64 v212, v[8:9] offset:112
	ds_write_b64 v211, v[24:25] offset:120
	ds_write_b64 v212, v[2:3] offset:120
	v_mov_b32_e32 v2, v210
	s_waitcnt lgkmcnt(0)
	s_barrier
	s_nop 0
	v_and_b32_e32 v3, 15, v2
	v_lshlrev_b32_e32 v5, 3, v3
	v_cvt_f32_ubyte0_e32 v3, v3
	v_mul_f32_e32 v3, 0x3b000000, v3
	v_sin_f32_e32 v17, v3
	v_cos_f32_e32 v16, v3
	v_lshlrev_b32_e32 v2, 5, v2
	v_and_b32_e32 v2, 0xfffffe00, v2
	v_lshl_add_u32 v4, v2, 3, 0
	v_ashrrev_i32_e32 v2, 2, v2
	v_xor_b32_e32 v72, 0x80000000, v17
	v_mov_b32_e32 v73, v17
	v_add3_u32 v2, v4, v5, v2
	v_pk_mul_f32 v[4:5], v[16:17], v[72:73] op_sel:[1,0] op_sel_hi:[0,1]
	v_pk_fma_f32 v[74:75], v[16:17], v[16:17], v[4:5] op_sel_hi:[1,0,1]
	v_add_u32_e32 v3, 0x800, v2
	v_pk_mul_f32 v[4:5], v[72:73], v[74:75] op_sel:[0,1] op_sel_hi:[1,0]
	v_xor_b32_e32 v78, 0x80000000, v75
	v_mov_b32_e32 v79, v75
	v_pk_fma_f32 v[76:77], v[16:17], v[74:75], v[4:5] op_sel_hi:[0,1,1]
	v_pk_mul_f32 v[4:5], v[74:75], v[78:79] op_sel:[1,0] op_sel_hi:[0,1]
	v_pk_fma_f32 v[80:81], v[74:75], v[74:75], v[4:5] op_sel_hi:[1,0,1]
	v_xor_b32_e32 v84, 0x80000000, v77
	v_pk_mul_f32 v[4:5], v[72:73], v[80:81] op_sel:[0,1] op_sel_hi:[1,0]
	v_mov_b32_e32 v85, v77
	v_pk_fma_f32 v[86:87], v[16:17], v[80:81], v[4:5] op_sel_hi:[0,1,1]
	v_pk_mul_f32 v[4:5], v[78:79], v[80:81] op_sel:[0,1] op_sel_hi:[1,0]
	v_xor_b32_e32 v82, 0x80000000, v81
	v_mov_b32_e32 v83, v81
	v_pk_fma_f32 v[90:91], v[74:75], v[80:81], v[4:5] op_sel_hi:[0,1,1]
	v_pk_mul_f32 v[4:5], v[80:81], v[84:85] op_sel:[1,0] op_sel_hi:[0,1]
	v_pk_fma_f32 v[94:95], v[80:81], v[76:77], v[4:5] op_sel_hi:[1,0,1]
	v_pk_mul_f32 v[4:5], v[80:81], v[82:83] op_sel:[1,0] op_sel_hi:[0,1]
	v_pk_fma_f32 v[98:99], v[80:81], v[80:81], v[4:5] op_sel_hi:[1,0,1]
	v_xor_b32_e32 v88, 0x80000000, v87
	v_pk_mul_f32 v[4:5], v[72:73], v[98:99] op_sel:[0,1] op_sel_hi:[1,0]
	v_mov_b32_e32 v89, v87
	v_pk_fma_f32 v[102:103], v[16:17], v[98:99], v[4:5] op_sel_hi:[0,1,1]
	v_pk_mul_f32 v[4:5], v[78:79], v[98:99] op_sel:[0,1] op_sel_hi:[1,0]
	v_xor_b32_e32 v92, 0x80000000, v91
	v_pk_fma_f32 v[106:107], v[74:75], v[98:99], v[4:5] op_sel_hi:[0,1,1]
	v_pk_mul_f32 v[4:5], v[84:85], v[98:99] op_sel:[0,1] op_sel_hi:[1,0]
	v_mov_b32_e32 v93, v91
	v_pk_fma_f32 v[110:111], v[76:77], v[98:99], v[4:5] op_sel_hi:[0,1,1]
	v_pk_mul_f32 v[4:5], v[82:83], v[98:99] op_sel:[0,1] op_sel_hi:[1,0]
	v_xor_b32_e32 v96, 0x80000000, v95
	v_pk_fma_f32 v[114:115], v[80:81], v[98:99], v[4:5] op_sel_hi:[0,1,1]
	v_pk_mul_f32 v[4:5], v[72:73], v[114:115] op_sel:[0,1] op_sel_hi:[1,0]
	v_mov_b32_e32 v97, v95
	v_pk_fma_f32 v[118:119], v[16:17], v[114:115], v[4:5] op_sel_hi:[0,1,1]
	v_pk_mul_f32 v[4:5], v[78:79], v[114:115] op_sel:[0,1] op_sel_hi:[1,0]
	v_xor_b32_e32 v100, 0x80000000, v99
	v_pk_fma_f32 v[122:123], v[74:75], v[114:115], v[4:5] op_sel_hi:[0,1,1]
	v_pk_mul_f32 v[4:5], v[84:85], v[114:115] op_sel:[0,1] op_sel_hi:[1,0]
	v_mov_b32_e32 v101, v99
	v_pk_fma_f32 v[126:127], v[76:77], v[114:115], v[4:5] op_sel_hi:[0,1,1]
	v_pk_mul_f32 v[4:5], v[82:83], v[114:115] op_sel:[0,1] op_sel_hi:[1,0]
	v_xor_b32_e32 v104, 0x80000000, v103
	v_pk_fma_f32 v[130:131], v[80:81], v[114:115], v[4:5] op_sel_hi:[0,1,1]
	v_pk_mul_f32 v[4:5], v[72:73], v[130:131] op_sel:[0,1] op_sel_hi:[1,0]
	v_mov_b32_e32 v105, v103
	v_pk_fma_f32 v[134:135], v[16:17], v[130:131], v[4:5] op_sel_hi:[0,1,1]
	v_pk_mul_f32 v[4:5], v[78:79], v[130:131] op_sel:[0,1] op_sel_hi:[1,0]
	v_xor_b32_e32 v108, 0x80000000, v107
	v_pk_fma_f32 v[138:139], v[74:75], v[130:131], v[4:5] op_sel_hi:[0,1,1]
	v_pk_mul_f32 v[4:5], v[84:85], v[130:131] op_sel:[0,1] op_sel_hi:[1,0]
	v_mov_b32_e32 v109, v107
	v_pk_fma_f32 v[142:143], v[76:77], v[130:131], v[4:5] op_sel_hi:[0,1,1]
	v_pk_mul_f32 v[4:5], v[82:83], v[130:131] op_sel:[0,1] op_sel_hi:[1,0]
	v_xor_b32_e32 v112, 0x80000000, v111
	v_pk_fma_f32 v[148:149], v[80:81], v[130:131], v[4:5] op_sel_hi:[0,1,1]
	v_pk_mul_f32 v[4:5], v[72:73], v[148:149] op_sel:[0,1] op_sel_hi:[1,0]
	v_mov_b32_e32 v113, v111
	v_pk_fma_f32 v[152:153], v[16:17], v[148:149], v[4:5] op_sel_hi:[0,1,1]
	v_pk_mul_f32 v[4:5], v[78:79], v[148:149] op_sel:[0,1] op_sel_hi:[1,0]
	v_xor_b32_e32 v116, 0x80000000, v115
	v_pk_fma_f32 v[156:157], v[74:75], v[148:149], v[4:5] op_sel_hi:[0,1,1]
	v_pk_mul_f32 v[4:5], v[84:85], v[148:149] op_sel:[0,1] op_sel_hi:[1,0]
	v_mov_b32_e32 v117, v115
	v_pk_fma_f32 v[160:161], v[76:77], v[148:149], v[4:5] op_sel_hi:[0,1,1]
	v_pk_mul_f32 v[4:5], v[82:83], v[148:149] op_sel:[0,1] op_sel_hi:[1,0]
	v_xor_b32_e32 v120, 0x80000000, v119
	v_pk_fma_f32 v[164:165], v[80:81], v[148:149], v[4:5] op_sel_hi:[0,1,1]
	v_pk_mul_f32 v[4:5], v[72:73], v[164:165] op_sel:[0,1] op_sel_hi:[1,0]
	v_mov_b32_e32 v121, v119
	v_pk_fma_f32 v[168:169], v[16:17], v[164:165], v[4:5] op_sel_hi:[0,1,1]
	v_pk_mul_f32 v[4:5], v[78:79], v[164:165] op_sel:[0,1] op_sel_hi:[1,0]
	v_xor_b32_e32 v124, 0x80000000, v123
	v_pk_fma_f32 v[172:173], v[74:75], v[164:165], v[4:5] op_sel_hi:[0,1,1]
	v_pk_mul_f32 v[4:5], v[84:85], v[164:165] op_sel:[0,1] op_sel_hi:[1,0]
	v_mov_b32_e32 v125, v123
	v_pk_fma_f32 v[176:177], v[76:77], v[164:165], v[4:5] op_sel_hi:[0,1,1]
	v_pk_mul_f32 v[4:5], v[82:83], v[164:165] op_sel:[0,1] op_sel_hi:[1,0]
	v_xor_b32_e32 v128, 0x80000000, v127
	v_pk_fma_f32 v[180:181], v[80:81], v[164:165], v[4:5] op_sel_hi:[0,1,1]
	v_pk_mul_f32 v[4:5], v[72:73], v[180:181] op_sel:[0,1] op_sel_hi:[1,0]
	v_mov_b32_e32 v129, v127
	v_pk_fma_f32 v[184:185], v[16:17], v[180:181], v[4:5] op_sel_hi:[0,1,1]
	v_pk_mul_f32 v[4:5], v[78:79], v[180:181] op_sel:[0,1] op_sel_hi:[1,0]
	v_xor_b32_e32 v132, 0x80000000, v131
	v_pk_fma_f32 v[188:189], v[74:75], v[180:181], v[4:5] op_sel_hi:[0,1,1]
	v_pk_mul_f32 v[4:5], v[84:85], v[180:181] op_sel:[0,1] op_sel_hi:[1,0]
	v_mov_b32_e32 v133, v131
	v_pk_fma_f32 v[192:193], v[76:77], v[180:181], v[4:5] op_sel_hi:[0,1,1]
	ds_read2_b64 v[4:7], v2 offset1:16
	ds_read2_b64 v[8:11], v2 offset0:33 offset1:49
	ds_read2_b64 v[12:15], v2 offset0:66 offset1:82
	ds_read2_b64 v[20:23], v2 offset0:99 offset1:115
	ds_read2_b64 v[24:27], v2 offset0:132 offset1:148
	ds_read2_b64 v[28:31], v2 offset0:165 offset1:181
	ds_read2_b64 v[32:35], v2 offset0:198 offset1:214
	ds_read2_b64 v[36:39], v2 offset0:231 offset1:247
	ds_read2_b64 v[40:43], v3 offset0:8 offset1:24
	ds_read2_b64 v[44:47], v3 offset0:41 offset1:57
	ds_read2_b64 v[48:51], v3 offset0:74 offset1:90
	ds_read2_b64 v[52:55], v3 offset0:107 offset1:123
	ds_read2_b64 v[56:59], v3 offset0:140 offset1:156
	ds_read2_b64 v[60:63], v3 offset0:173 offset1:189
	ds_read2_b64 v[64:67], v3 offset0:206 offset1:222
	ds_read2_b64 v[68:71], v3 offset0:239 offset1:255
	s_waitcnt lgkmcnt(7)
	v_pk_mul_f32 v[72:73], v[72:73], v[40:41] op_sel:[0,1] op_sel_hi:[1,0]
	v_xor_b32_e32 v136, 0x80000000, v135
	v_pk_fma_f32 v[16:17], v[16:17], v[40:41], v[72:73] op_sel_hi:[0,1,1]
	v_pk_mul_f32 v[40:41], v[24:25], v[78:79] op_sel:[1,0] op_sel_hi:[0,1]
	v_pk_fma_f32 v[24:25], v[24:25], v[74:75], v[40:41] op_sel_hi:[1,0,1]
	s_waitcnt lgkmcnt(3)
	v_pk_mul_f32 v[40:41], v[84:85], v[56:57] op_sel:[0,1] op_sel_hi:[1,0]
	v_mov_b32_e32 v137, v135
	v_pk_fma_f32 v[40:41], v[76:77], v[56:57], v[40:41] op_sel_hi:[0,1,1]
	v_pk_mul_f32 v[56:57], v[12:13], v[82:83] op_sel:[1,0] op_sel_hi:[0,1]
	v_pk_fma_f32 v[12:13], v[12:13], v[80:81], v[56:57] op_sel_hi:[1,0,1]
	v_pk_mul_f32 v[56:57], v[88:89], v[48:49] op_sel:[0,1] op_sel_hi:[1,0]
	v_xor_b32_e32 v140, 0x80000000, v139
	v_pk_fma_f32 v[48:49], v[86:87], v[48:49], v[56:57] op_sel_hi:[0,1,1]
	v_pk_mul_f32 v[56:57], v[32:33], v[92:93] op_sel:[1,0] op_sel_hi:[0,1]
	v_pk_fma_f32 v[32:33], v[32:33], v[90:91], v[56:57] op_sel_hi:[1,0,1]
	s_waitcnt lgkmcnt(1)
	v_pk_mul_f32 v[56:57], v[96:97], v[64:65] op_sel:[0,1] op_sel_hi:[1,0]
	v_mov_b32_e32 v141, v139
	v_pk_fma_f32 v[56:57], v[94:95], v[64:65], v[56:57] op_sel_hi:[0,1,1]
	v_pk_mul_f32 v[64:65], v[8:9], v[100:101] op_sel:[1,0] op_sel_hi:[0,1]
	v_pk_fma_f32 v[8:9], v[8:9], v[98:99], v[64:65] op_sel_hi:[1,0,1]
	v_pk_mul_f32 v[64:65], v[44:45], v[104:105] op_sel:[1,0] op_sel_hi:[0,1]
	v_pk_fma_f32 v[44:45], v[44:45], v[102:103], v[64:65] op_sel_hi:[1,0,1]
	v_pk_mul_f32 v[64:65], v[28:29], v[108:109] op_sel:[1,0] op_sel_hi:[0,1]
	v_pk_fma_f32 v[28:29], v[28:29], v[106:107], v[64:65] op_sel_hi:[1,0,1]
	v_pk_mul_f32 v[64:65], v[112:113], v[60:61] op_sel:[0,1] op_sel_hi:[1,0]
	v_xor_b32_e32 v144, 0x80000000, v143
	v_pk_fma_f32 v[60:61], v[110:111], v[60:61], v[64:65] op_sel_hi:[0,1,1]
	v_pk_mul_f32 v[64:65], v[20:21], v[116:117] op_sel:[1,0] op_sel_hi:[0,1]
	v_pk_fma_f32 v[20:21], v[20:21], v[114:115], v[64:65] op_sel_hi:[1,0,1]
	v_pk_mul_f32 v[64:65], v[52:53], v[120:121] op_sel:[1,0] op_sel_hi:[0,1]
	v_pk_fma_f32 v[52:53], v[52:53], v[118:119], v[64:65] op_sel_hi:[1,0,1]
	v_pk_mul_f32 v[64:65], v[36:37], v[124:125] op_sel:[1,0] op_sel_hi:[0,1]
	v_pk_fma_f32 v[36:37], v[36:37], v[122:123], v[64:65] op_sel_hi:[1,0,1]
	s_waitcnt lgkmcnt(0)
	v_pk_mul_f32 v[64:65], v[128:129], v[68:69] op_sel:[0,1] op_sel_hi:[1,0]
	v_mov_b32_e32 v145, v143
	v_pk_fma_f32 v[64:65], v[126:127], v[68:69], v[64:65] op_sel_hi:[0,1,1]
	v_pk_mul_f32 v[68:69], v[6:7], v[132:133] op_sel:[1,0] op_sel_hi:[0,1]
	v_pk_fma_f32 v[6:7], v[6:7], v[130:131], v[68:69] op_sel_hi:[1,0,1]
	v_pk_mul_f32 v[68:69], v[42:43], v[136:137] op_sel:[1,0] op_sel_hi:[0,1]
	v_pk_fma_f32 v[42:43], v[42:43], v[134:135], v[68:69] op_sel_hi:[1,0,1]
	v_pk_mul_f32 v[68:69], v[26:27], v[140:141] op_sel:[1,0] op_sel_hi:[0,1]
	v_xor_b32_e32 v150, 0x80000000, v149
	v_mov_b32_e32 v151, v149
	v_pk_fma_f32 v[26:27], v[26:27], v[138:139], v[68:69] op_sel_hi:[1,0,1]
	v_pk_mul_f32 v[68:69], v[58:59], v[144:145] op_sel:[1,0] op_sel_hi:[0,1]
	v_xor_b32_e32 v154, 0x80000000, v153
	v_mov_b32_e32 v155, v153
	v_pk_fma_f32 v[58:59], v[58:59], v[142:143], v[68:69] op_sel_hi:[1,0,1]
	v_pk_mul_f32 v[68:69], v[14:15], v[150:151] op_sel:[1,0] op_sel_hi:[0,1]
	v_xor_b32_e32 v158, 0x80000000, v157
	v_mov_b32_e32 v159, v157
	v_pk_fma_f32 v[14:15], v[14:15], v[148:149], v[68:69] op_sel_hi:[1,0,1]
	v_pk_mul_f32 v[68:69], v[50:51], v[154:155] op_sel:[1,0] op_sel_hi:[0,1]
	v_xor_b32_e32 v162, 0x80000000, v161
	v_mov_b32_e32 v163, v161
	v_pk_fma_f32 v[50:51], v[50:51], v[152:153], v[68:69] op_sel_hi:[1,0,1]
	v_pk_mul_f32 v[68:69], v[34:35], v[158:159] op_sel:[1,0] op_sel_hi:[0,1]
	v_xor_b32_e32 v166, 0x80000000, v165
	v_mov_b32_e32 v167, v165
	v_pk_fma_f32 v[34:35], v[34:35], v[156:157], v[68:69] op_sel_hi:[1,0,1]
	v_pk_mul_f32 v[68:69], v[162:163], v[66:67] op_sel:[0,1] op_sel_hi:[1,0]
	v_xor_b32_e32 v170, 0x80000000, v169
	v_mov_b32_e32 v171, v169
	v_pk_fma_f32 v[66:67], v[160:161], v[66:67], v[68:69] op_sel_hi:[0,1,1]
	v_pk_mul_f32 v[68:69], v[10:11], v[166:167] op_sel:[1,0] op_sel_hi:[0,1]
	v_xor_b32_e32 v174, 0x80000000, v173
	v_mov_b32_e32 v175, v173
	v_pk_fma_f32 v[10:11], v[10:11], v[164:165], v[68:69] op_sel_hi:[1,0,1]
	v_pk_mul_f32 v[68:69], v[46:47], v[170:171] op_sel:[1,0] op_sel_hi:[0,1]
	v_xor_b32_e32 v178, 0x80000000, v177
	v_mov_b32_e32 v179, v177
	v_pk_fma_f32 v[46:47], v[46:47], v[168:169], v[68:69] op_sel_hi:[1,0,1]
	v_pk_mul_f32 v[68:69], v[30:31], v[174:175] op_sel:[1,0] op_sel_hi:[0,1]
	v_xor_b32_e32 v182, 0x80000000, v181
	v_mov_b32_e32 v183, v181
	v_pk_fma_f32 v[30:31], v[30:31], v[172:173], v[68:69] op_sel_hi:[1,0,1]
	v_pk_mul_f32 v[68:69], v[62:63], v[178:179] op_sel:[1,0] op_sel_hi:[0,1]
	v_xor_b32_e32 v186, 0x80000000, v185
	v_mov_b32_e32 v187, v185
	v_pk_fma_f32 v[62:63], v[62:63], v[176:177], v[68:69] op_sel_hi:[1,0,1]
	v_pk_mul_f32 v[68:69], v[22:23], v[182:183] op_sel:[1,0] op_sel_hi:[0,1]
	v_xor_b32_e32 v190, 0x80000000, v189
	v_mov_b32_e32 v191, v189
	v_pk_fma_f32 v[22:23], v[22:23], v[180:181], v[68:69] op_sel_hi:[1,0,1]
	v_pk_mul_f32 v[68:69], v[54:55], v[186:187] op_sel:[1,0] op_sel_hi:[0,1]
	v_xor_b32_e32 v194, 0x80000000, v193
	v_mov_b32_e32 v195, v193
	v_pk_fma_f32 v[54:55], v[54:55], v[184:185], v[68:69] op_sel_hi:[1,0,1]
	v_pk_mul_f32 v[68:69], v[38:39], v[190:191] op_sel:[1,0] op_sel_hi:[0,1]
	v_pk_fma_f32 v[38:39], v[38:39], v[188:189], v[68:69] op_sel_hi:[1,0,1]
	v_pk_mul_f32 v[68:69], v[70:71], v[194:195] op_sel:[1,0] op_sel_hi:[0,1]
	v_pk_fma_f32 v[68:69], v[70:71], v[192:193], v[68:69] op_sel_hi:[1,0,1]
	v_pk_add_f32 v[70:71], v[4:5], v[6:7]
	v_pk_add_f32 v[4:5], v[4:5], v[6:7] neg_lo:[0,1] neg_hi:[0,1]
	v_pk_add_f32 v[6:7], v[8:9], v[10:11]
	v_pk_add_f32 v[8:9], v[8:9], v[10:11] neg_lo:[0,1] neg_hi:[0,1]
	v_pk_add_f32 v[10:11], v[12:13], v[14:15]
	v_pk_add_f32 v[12:13], v[12:13], v[14:15] neg_lo:[0,1] neg_hi:[0,1]
	v_pk_add_f32 v[14:15], v[20:21], v[22:23]
	v_pk_add_f32 v[20:21], v[20:21], v[22:23] neg_lo:[0,1] neg_hi:[0,1]
	v_pk_add_f32 v[22:23], v[24:25], v[26:27]
	v_pk_add_f32 v[24:25], v[24:25], v[26:27] neg_lo:[0,1] neg_hi:[0,1]
	v_pk_add_f32 v[26:27], v[28:29], v[30:31]
	v_pk_add_f32 v[28:29], v[28:29], v[30:31] neg_lo:[0,1] neg_hi:[0,1]
	v_pk_add_f32 v[30:31], v[32:33], v[34:35]
	v_pk_add_f32 v[32:33], v[32:33], v[34:35] neg_lo:[0,1] neg_hi:[0,1]
	v_pk_add_f32 v[34:35], v[36:37], v[38:39]
	v_pk_add_f32 v[36:37], v[36:37], v[38:39] neg_lo:[0,1] neg_hi:[0,1]
	v_pk_add_f32 v[38:39], v[16:17], v[42:43]
	v_pk_add_f32 v[16:17], v[16:17], v[42:43] neg_lo:[0,1] neg_hi:[0,1]
	v_pk_add_f32 v[42:43], v[44:45], v[46:47]
	v_pk_add_f32 v[44:45], v[44:45], v[46:47] neg_lo:[0,1] neg_hi:[0,1]
	v_pk_add_f32 v[46:47], v[48:49], v[50:51]
	v_pk_add_f32 v[48:49], v[48:49], v[50:51] neg_lo:[0,1] neg_hi:[0,1]
	v_pk_add_f32 v[50:51], v[52:53], v[54:55]
	v_pk_add_f32 v[52:53], v[52:53], v[54:55] neg_lo:[0,1] neg_hi:[0,1]
	v_pk_add_f32 v[54:55], v[40:41], v[58:59]
	v_pk_add_f32 v[40:41], v[40:41], v[58:59] neg_lo:[0,1] neg_hi:[0,1]
	v_pk_add_f32 v[58:59], v[60:61], v[62:63]
	v_pk_add_f32 v[60:61], v[60:61], v[62:63] neg_lo:[0,1] neg_hi:[0,1]
	v_pk_add_f32 v[62:63], v[56:57], v[66:67]
	v_pk_add_f32 v[56:57], v[56:57], v[66:67] neg_lo:[0,1] neg_hi:[0,1]
	v_pk_add_f32 v[66:67], v[64:65], v[68:69]
	v_pk_add_f32 v[64:65], v[64:65], v[68:69] neg_lo:[0,1] neg_hi:[0,1]
	v_pk_add_f32 v[68:69], v[70:71], v[6:7]
	v_pk_add_f32 v[6:7], v[70:71], v[6:7] neg_lo:[0,1] neg_hi:[0,1]
	v_xor_b32_e32 v70, 0x80000000, v9
	v_mov_b32_e32 v71, v8
	v_pk_add_f32 v[8:9], v[4:5], v[70:71]
	v_pk_add_f32 v[4:5], v[4:5], v[70:71] neg_lo:[0,1] neg_hi:[0,1]
	v_pk_add_f32 v[70:71], v[10:11], v[14:15]
	v_pk_add_f32 v[10:11], v[10:11], v[14:15] neg_lo:[0,1] neg_hi:[0,1]
	v_xor_b32_e32 v14, 0x80000000, v21
	v_mov_b32_e32 v15, v20
	v_pk_add_f32 v[20:21], v[12:13], v[14:15]
	v_pk_add_f32 v[12:13], v[12:13], v[14:15] neg_lo:[0,1] neg_hi:[0,1]
	v_pk_add_f32 v[14:15], v[22:23], v[26:27]
	v_pk_add_f32 v[22:23], v[22:23], v[26:27] neg_lo:[0,1] neg_hi:[0,1]
	v_xor_b32_e32 v26, 0x80000000, v29
	v_mov_b32_e32 v27, v28
	v_pk_add_f32 v[28:29], v[24:25], v[26:27]
	v_pk_add_f32 v[24:25], v[24:25], v[26:27] neg_lo:[0,1] neg_hi:[0,1]
	v_pk_add_f32 v[26:27], v[30:31], v[34:35]
	v_pk_add_f32 v[30:31], v[30:31], v[34:35] neg_lo:[0,1] neg_hi:[0,1]
	v_xor_b32_e32 v34, 0x80000000, v37
	v_mov_b32_e32 v35, v36
	v_pk_add_f32 v[36:37], v[32:33], v[34:35]
	v_pk_add_f32 v[32:33], v[32:33], v[34:35] neg_lo:[0,1] neg_hi:[0,1]
	v_pk_add_f32 v[34:35], v[38:39], v[42:43]
	v_pk_add_f32 v[38:39], v[38:39], v[42:43] neg_lo:[0,1] neg_hi:[0,1]
	v_xor_b32_e32 v42, 0x80000000, v45
	v_mov_b32_e32 v43, v44
	v_pk_add_f32 v[44:45], v[16:17], v[42:43]
	v_pk_add_f32 v[16:17], v[16:17], v[42:43] neg_lo:[0,1] neg_hi:[0,1]
	v_pk_add_f32 v[42:43], v[46:47], v[50:51]
	v_pk_add_f32 v[46:47], v[46:47], v[50:51] neg_lo:[0,1] neg_hi:[0,1]
	v_xor_b32_e32 v50, 0x80000000, v53
	v_mov_b32_e32 v51, v52
	v_pk_add_f32 v[52:53], v[48:49], v[50:51]
	v_pk_add_f32 v[48:49], v[48:49], v[50:51] neg_lo:[0,1] neg_hi:[0,1]
	v_pk_add_f32 v[50:51], v[54:55], v[58:59]
	v_pk_add_f32 v[54:55], v[54:55], v[58:59] neg_lo:[0,1] neg_hi:[0,1]
	v_xor_b32_e32 v58, 0x80000000, v61
	v_mov_b32_e32 v59, v60
	v_pk_add_f32 v[60:61], v[40:41], v[58:59]
	v_pk_add_f32 v[40:41], v[40:41], v[58:59] neg_lo:[0,1] neg_hi:[0,1]
	v_pk_add_f32 v[58:59], v[62:63], v[66:67]
	v_pk_add_f32 v[62:63], v[62:63], v[66:67] neg_lo:[0,1] neg_hi:[0,1]
	v_xor_b32_e32 v66, 0x80000000, v65
	v_mov_b32_e32 v67, v64
	v_pk_add_f32 v[64:65], v[56:57], v[66:67]
	v_pk_add_f32 v[56:57], v[56:57], v[66:67] neg_lo:[0,1] neg_hi:[0,1]
	v_pk_add_f32 v[66:67], v[68:69], v[70:71]
	v_pk_add_f32 v[68:69], v[68:69], v[70:71] neg_lo:[0,1] neg_hi:[0,1]
	v_pk_mul_f32 v[70:71], v[20:21], s[78:79]
	s_nop 0
	v_pk_fma_f32 v[20:21], s[0:1], v[20:21], v[70:71] op_sel:[0,0,1] op_sel_hi:[0,1,0]
	v_pk_add_f32 v[70:71], v[8:9], v[20:21]
	v_pk_add_f32 v[8:9], v[8:9], v[20:21] neg_lo:[0,1] neg_hi:[0,1]
	v_xor_b32_e32 v20, 0x80000000, v11
	v_mov_b32_e32 v21, v10
	v_pk_add_f32 v[10:11], v[6:7], v[20:21]
	v_pk_add_f32 v[6:7], v[6:7], v[20:21] neg_lo:[0,1] neg_hi:[0,1]
	v_pk_mul_f32 v[20:21], v[12:13], s[78:79]
	s_nop 0
	v_pk_fma_f32 v[12:13], s[0:1], v[12:13], v[20:21] op_sel:[0,0,1] op_sel_hi:[0,1,0] neg_lo:[0,1,0] neg_hi:[0,1,0]
	v_pk_add_f32 v[20:21], v[4:5], v[12:13]
	v_pk_add_f32 v[4:5], v[4:5], v[12:13] neg_lo:[0,1] neg_hi:[0,1]
	v_pk_add_f32 v[12:13], v[14:15], v[26:27]
	v_pk_add_f32 v[14:15], v[14:15], v[26:27] neg_lo:[0,1] neg_hi:[0,1]
	v_pk_mul_f32 v[26:27], v[36:37], s[78:79]
	s_nop 0
	v_pk_fma_f32 v[26:27], s[0:1], v[36:37], v[26:27] op_sel:[0,0,1] op_sel_hi:[0,1,0]
	v_pk_add_f32 v[36:37], v[28:29], v[26:27]
	v_pk_add_f32 v[26:27], v[28:29], v[26:27] neg_lo:[0,1] neg_hi:[0,1]
	v_xor_b32_e32 v28, 0x80000000, v31
	v_mov_b32_e32 v29, v30
	v_pk_add_f32 v[30:31], v[22:23], v[28:29]
	v_pk_add_f32 v[22:23], v[22:23], v[28:29] neg_lo:[0,1] neg_hi:[0,1]
	v_pk_mul_f32 v[28:29], v[32:33], s[78:79]
	s_nop 0
	v_pk_fma_f32 v[28:29], s[0:1], v[32:33], v[28:29] op_sel:[0,0,1] op_sel_hi:[0,1,0] neg_lo:[0,1,0] neg_hi:[0,1,0]
	v_pk_add_f32 v[32:33], v[24:25], v[28:29]
	v_pk_add_f32 v[24:25], v[24:25], v[28:29] neg_lo:[0,1] neg_hi:[0,1]
	v_pk_add_f32 v[28:29], v[34:35], v[42:43]
	v_pk_add_f32 v[34:35], v[34:35], v[42:43] neg_lo:[0,1] neg_hi:[0,1]
	v_pk_mul_f32 v[42:43], v[52:53], s[78:79]
	s_nop 0
	v_pk_fma_f32 v[42:43], s[0:1], v[52:53], v[42:43] op_sel:[0,0,1] op_sel_hi:[0,1,0]
	v_pk_add_f32 v[52:53], v[44:45], v[42:43]
	v_pk_add_f32 v[42:43], v[44:45], v[42:43] neg_lo:[0,1] neg_hi:[0,1]
	v_xor_b32_e32 v44, 0x80000000, v47
	v_mov_b32_e32 v45, v46
	v_pk_add_f32 v[46:47], v[38:39], v[44:45]
	v_pk_add_f32 v[38:39], v[38:39], v[44:45] neg_lo:[0,1] neg_hi:[0,1]
	v_pk_mul_f32 v[44:45], v[48:49], s[78:79]
	s_nop 0
	v_pk_fma_f32 v[44:45], s[0:1], v[48:49], v[44:45] op_sel:[0,0,1] op_sel_hi:[0,1,0] neg_lo:[0,1,0] neg_hi:[0,1,0]
	v_pk_add_f32 v[48:49], v[16:17], v[44:45]
	v_pk_add_f32 v[16:17], v[16:17], v[44:45] neg_lo:[0,1] neg_hi:[0,1]
	v_pk_add_f32 v[44:45], v[50:51], v[58:59]
	v_pk_add_f32 v[50:51], v[50:51], v[58:59] neg_lo:[0,1] neg_hi:[0,1]
	v_pk_mul_f32 v[58:59], v[64:65], s[78:79]
	s_nop 0
	v_pk_fma_f32 v[58:59], s[0:1], v[64:65], v[58:59] op_sel:[0,0,1] op_sel_hi:[0,1,0]
	v_pk_add_f32 v[64:65], v[60:61], v[58:59]
	v_pk_add_f32 v[58:59], v[60:61], v[58:59] neg_lo:[0,1] neg_hi:[0,1]
	v_xor_b32_e32 v60, 0x80000000, v63
	v_mov_b32_e32 v61, v62
	v_pk_add_f32 v[62:63], v[54:55], v[60:61]
	v_pk_add_f32 v[54:55], v[54:55], v[60:61] neg_lo:[0,1] neg_hi:[0,1]
	v_pk_mul_f32 v[60:61], v[56:57], s[78:79]
	s_nop 0
	v_pk_fma_f32 v[56:57], s[0:1], v[56:57], v[60:61] op_sel:[0,0,1] op_sel_hi:[0,1,0] neg_lo:[0,1,0] neg_hi:[0,1,0]
	v_pk_add_f32 v[60:61], v[40:41], v[56:57]
	v_pk_add_f32 v[40:41], v[40:41], v[56:57] neg_lo:[0,1] neg_hi:[0,1]
	v_pk_add_f32 v[56:57], v[66:67], v[12:13]
	v_pk_add_f32 v[12:13], v[66:67], v[12:13] neg_lo:[0,1] neg_hi:[0,1]
	v_pk_mul_f32 v[66:67], v[36:37], s[80:81]
	s_nop 0
	v_pk_fma_f32 v[36:37], s[16:17], v[36:37], v[66:67] op_sel:[0,0,1] op_sel_hi:[0,1,0]
	v_pk_add_f32 v[66:67], v[70:71], v[36:37]
	v_pk_add_f32 v[36:37], v[70:71], v[36:37] neg_lo:[0,1] neg_hi:[0,1]
	v_pk_mul_f32 v[70:71], v[30:31], s[78:79]
	s_nop 0
	v_pk_fma_f32 v[30:31], s[0:1], v[30:31], v[70:71] op_sel:[0,0,1] op_sel_hi:[0,1,0]
	v_pk_add_f32 v[70:71], v[10:11], v[30:31]
	v_pk_add_f32 v[10:11], v[10:11], v[30:31] neg_lo:[0,1] neg_hi:[0,1]
	v_pk_mul_f32 v[30:31], v[32:33], s[16:17]
	s_nop 0
	v_pk_fma_f32 v[30:31], s[82:83], v[32:33], v[30:31] op_sel:[0,0,1] op_sel_hi:[0,1,0]
	v_pk_add_f32 v[32:33], v[20:21], v[30:31]
	v_pk_add_f32 v[20:21], v[20:21], v[30:31] neg_lo:[0,1] neg_hi:[0,1]
	v_xor_b32_e32 v30, 0x80000000, v15
	v_mov_b32_e32 v31, v14
	v_pk_add_f32 v[14:15], v[68:69], v[30:31]
	v_pk_add_f32 v[30:31], v[68:69], v[30:31] neg_lo:[0,1] neg_hi:[0,1]
	v_pk_mul_f32 v[68:69], v[26:27], s[16:17]
	s_nop 0
	v_pk_fma_f32 v[26:27], s[82:83], v[26:27], v[68:69] op_sel:[0,0,1] op_sel_hi:[0,1,0] neg_lo:[0,1,0] neg_hi:[0,1,0]
	v_pk_add_f32 v[68:69], v[8:9], v[26:27]
	v_pk_add_f32 v[8:9], v[8:9], v[26:27] neg_lo:[0,1] neg_hi:[0,1]
	v_pk_mul_f32 v[26:27], v[22:23], s[78:79]
	s_nop 0
	v_pk_fma_f32 v[22:23], s[0:1], v[22:23], v[26:27] op_sel:[0,0,1] op_sel_hi:[0,1,0] neg_lo:[0,1,0] neg_hi:[0,1,0]
	v_pk_add_f32 v[26:27], v[6:7], v[22:23]
	v_pk_add_f32 v[6:7], v[6:7], v[22:23] neg_lo:[0,1] neg_hi:[0,1]
	v_pk_mul_f32 v[22:23], v[24:25], s[80:81]
	s_nop 0
	v_pk_fma_f32 v[22:23], s[16:17], v[24:25], v[22:23] op_sel:[0,0,1] op_sel_hi:[0,1,0] neg_lo:[0,1,0] neg_hi:[0,1,0]
	v_pk_add_f32 v[24:25], v[4:5], v[22:23]
	v_pk_add_f32 v[4:5], v[4:5], v[22:23] neg_lo:[0,1] neg_hi:[0,1]
	v_pk_add_f32 v[22:23], v[28:29], v[44:45]
	v_pk_add_f32 v[28:29], v[28:29], v[44:45] neg_lo:[0,1] neg_hi:[0,1]
	v_pk_mul_f32 v[44:45], v[64:65], s[80:81]
	s_nop 0
	v_pk_fma_f32 v[44:45], s[16:17], v[64:65], v[44:45] op_sel:[0,0,1] op_sel_hi:[0,1,0]
	v_pk_add_f32 v[64:65], v[52:53], v[44:45]
	v_pk_add_f32 v[44:45], v[52:53], v[44:45] neg_lo:[0,1] neg_hi:[0,1]
	v_pk_mul_f32 v[52:53], v[62:63], s[78:79]
	s_nop 0
	v_pk_fma_f32 v[52:53], s[0:1], v[62:63], v[52:53] op_sel:[0,0,1] op_sel_hi:[0,1,0]
	v_pk_add_f32 v[62:63], v[46:47], v[52:53]
	v_pk_add_f32 v[46:47], v[46:47], v[52:53] neg_lo:[0,1] neg_hi:[0,1]
	v_pk_mul_f32 v[52:53], v[60:61], s[16:17]
	s_nop 0
	v_pk_fma_f32 v[52:53], s[82:83], v[60:61], v[52:53] op_sel:[0,0,1] op_sel_hi:[0,1,0]
	v_pk_add_f32 v[60:61], v[48:49], v[52:53]
	v_pk_add_f32 v[48:49], v[48:49], v[52:53] neg_lo:[0,1] neg_hi:[0,1]
	v_xor_b32_e32 v52, 0x80000000, v51
	v_mov_b32_e32 v53, v50
	v_pk_add_f32 v[50:51], v[34:35], v[52:53]
	v_pk_add_f32 v[34:35], v[34:35], v[52:53] neg_lo:[0,1] neg_hi:[0,1]
	v_pk_mul_f32 v[52:53], v[58:59], s[16:17]
	s_nop 0
	v_pk_fma_f32 v[52:53], s[82:83], v[58:59], v[52:53] op_sel:[0,0,1] op_sel_hi:[0,1,0] neg_lo:[0,1,0] neg_hi:[0,1,0]
	v_pk_add_f32 v[58:59], v[42:43], v[52:53]
	v_pk_add_f32 v[42:43], v[42:43], v[52:53] neg_lo:[0,1] neg_hi:[0,1]
	v_pk_mul_f32 v[52:53], v[54:55], s[78:79]
	s_nop 0
	v_pk_fma_f32 v[52:53], s[0:1], v[54:55], v[52:53] op_sel:[0,0,1] op_sel_hi:[0,1,0] neg_lo:[0,1,0] neg_hi:[0,1,0]
	v_pk_add_f32 v[54:55], v[38:39], v[52:53]
	v_pk_add_f32 v[38:39], v[38:39], v[52:53] neg_lo:[0,1] neg_hi:[0,1]
	v_pk_mul_f32 v[52:53], v[40:41], s[80:81]
	s_nop 0
	v_pk_fma_f32 v[40:41], s[16:17], v[40:41], v[52:53] op_sel:[0,0,1] op_sel_hi:[0,1,0] neg_lo:[0,1,0] neg_hi:[0,1,0]
	v_pk_add_f32 v[52:53], v[16:17], v[40:41]
	v_pk_add_f32 v[16:17], v[16:17], v[40:41] neg_lo:[0,1] neg_hi:[0,1]
	v_pk_add_f32 v[40:41], v[56:57], v[22:23]
	v_pk_add_f32 v[22:23], v[56:57], v[22:23] neg_lo:[0,1] neg_hi:[0,1]
	v_pk_mul_f32 v[56:57], v[64:65], s[88:89]
	s_nop 0
	v_pk_fma_f32 v[56:57], v[64:65], s[8:9], v[56:57] op_sel:[0,0,1] op_sel_hi:[1,0,0]
	s_mov_b32 s9, s42
	v_pk_add_f32 v[64:65], v[66:67], v[56:57]
	v_pk_add_f32 v[56:57], v[66:67], v[56:57] neg_lo:[0,1] neg_hi:[0,1]
	v_pk_mul_f32 v[66:67], v[62:63], s[80:81]
	s_nop 0
	v_pk_fma_f32 v[62:63], s[16:17], v[62:63], v[66:67] op_sel:[0,0,1] op_sel_hi:[0,1,0]
	v_pk_add_f32 v[66:67], v[70:71], v[62:63]
	v_pk_add_f32 v[62:63], v[70:71], v[62:63] neg_lo:[0,1] neg_hi:[0,1]
	v_pk_mul_f32 v[70:71], v[60:61], s[62:63]
	s_nop 0
	v_pk_fma_f32 v[60:61], v[60:61], s[24:25], v[70:71] op_sel:[0,0,1] op_sel_hi:[1,0,0]
	s_mov_b32 s25, s38
	v_pk_add_f32 v[70:71], v[32:33], v[60:61]
	v_pk_add_f32 v[32:33], v[32:33], v[60:61] neg_lo:[0,1] neg_hi:[0,1]
	v_pk_mul_f32 v[60:61], v[50:51], s[78:79]
	s_nop 0
	v_pk_fma_f32 v[50:51], s[0:1], v[50:51], v[60:61] op_sel:[0,0,1] op_sel_hi:[0,1,0]
	v_pk_add_f32 v[60:61], v[14:15], v[50:51]
	v_pk_add_f32 v[14:15], v[14:15], v[50:51] neg_lo:[0,1] neg_hi:[0,1]
	v_pk_mul_f32 v[50:51], v[58:59], s[24:25]
	s_nop 0
	v_pk_fma_f32 v[50:51], s[84:85], v[58:59], v[50:51] op_sel:[0,0,1] op_sel_hi:[0,1,0]
	v_pk_add_f32 v[58:59], v[68:69], v[50:51]
	v_pk_add_f32 v[50:51], v[68:69], v[50:51] neg_lo:[0,1] neg_hi:[0,1]
	v_pk_mul_f32 v[68:69], v[54:55], s[16:17]
	s_nop 0
	v_pk_fma_f32 v[54:55], s[82:83], v[54:55], v[68:69] op_sel:[0,0,1] op_sel_hi:[0,1,0]
	v_pk_add_f32 v[68:69], v[26:27], v[54:55]
	v_pk_add_f32 v[26:27], v[26:27], v[54:55] neg_lo:[0,1] neg_hi:[0,1]
	v_pk_mul_f32 v[54:55], v[52:53], s[8:9]
	s_nop 0
	v_pk_fma_f32 v[52:53], s[86:87], v[52:53], v[54:55] op_sel:[0,0,1] op_sel_hi:[0,1,0]
	v_pk_add_f32 v[54:55], v[24:25], v[52:53]
	v_pk_add_f32 v[24:25], v[24:25], v[52:53] neg_lo:[0,1] neg_hi:[0,1]
	v_xor_b32_e32 v52, 0x80000000, v29
	v_mov_b32_e32 v53, v28
	v_pk_add_f32 v[28:29], v[12:13], v[52:53]
	v_pk_add_f32 v[12:13], v[12:13], v[52:53] neg_lo:[0,1] neg_hi:[0,1]
	v_pk_mul_f32 v[52:53], v[44:45], s[8:9]
	s_nop 0
	v_pk_fma_f32 v[44:45], s[86:87], v[44:45], v[52:53] op_sel:[0,0,1] op_sel_hi:[0,1,0] neg_lo:[0,1,0] neg_hi:[0,1,0]
	v_pk_add_f32 v[52:53], v[36:37], v[44:45]
	v_pk_add_f32 v[36:37], v[36:37], v[44:45] neg_lo:[0,1] neg_hi:[0,1]
	v_pk_mul_f32 v[44:45], v[46:47], s[16:17]
	s_nop 0
	v_pk_fma_f32 v[44:45], s[82:83], v[46:47], v[44:45] op_sel:[0,0,1] op_sel_hi:[0,1,0] neg_lo:[0,1,0] neg_hi:[0,1,0]
	v_pk_add_f32 v[46:47], v[10:11], v[44:45]
	v_pk_add_f32 v[10:11], v[10:11], v[44:45] neg_lo:[0,1] neg_hi:[0,1]
	v_pk_mul_f32 v[44:45], v[48:49], s[24:25]
	s_nop 0
	v_pk_fma_f32 v[44:45], s[84:85], v[48:49], v[44:45] op_sel:[0,0,1] op_sel_hi:[0,1,0] neg_lo:[0,1,0] neg_hi:[0,1,0]
	v_pk_add_f32 v[48:49], v[20:21], v[44:45]
	v_pk_add_f32 v[20:21], v[20:21], v[44:45] neg_lo:[0,1] neg_hi:[0,1]
	v_pk_mul_f32 v[44:45], v[34:35], s[78:79]
	s_nop 0
	v_pk_fma_f32 v[34:35], v[34:35], s[0:1], v[44:45] op_sel:[0,0,1] op_sel_hi:[1,0,0] neg_lo:[1,0,0] neg_hi:[1,0,0]
	s_lshl_b64 s[0:1], s[72:73], 2
	v_pk_add_f32 v[44:45], v[30:31], v[34:35]
	v_pk_add_f32 v[30:31], v[30:31], v[34:35] neg_lo:[0,1] neg_hi:[0,1]
	v_pk_mul_f32 v[34:35], v[42:43], s[62:63]
	s_add_u32 s0, s49, s0
	v_pk_fma_f32 v[34:35], v[42:43], s[24:25], v[34:35] op_sel:[0,0,1] op_sel_hi:[1,0,0] neg_lo:[1,0,0] neg_hi:[1,0,0]
	s_addc_u32 s1, s60, s1
	v_pk_add_f32 v[42:43], v[8:9], v[34:35]
	v_pk_add_f32 v[8:9], v[8:9], v[34:35] neg_lo:[0,1] neg_hi:[0,1]
	v_pk_mul_f32 v[34:35], v[38:39], s[80:81]
	s_lshl_b64 s[62:63], s[76:77], 2
	v_pk_fma_f32 v[34:35], v[38:39], s[16:17], v[34:35] op_sel:[0,0,1] op_sel_hi:[1,0,0] neg_lo:[1,0,0] neg_hi:[1,0,0]
	s_add_u32 s62, s22, s62
	v_pk_add_f32 v[38:39], v[6:7], v[34:35]
	v_pk_add_f32 v[6:7], v[6:7], v[34:35] neg_lo:[0,1] neg_hi:[0,1]
	v_pk_mul_f32 v[34:35], v[16:17], s[88:89]
	s_addc_u32 s63, s23, s63
	v_pk_fma_f32 v[16:17], s[8:9], v[16:17], v[34:35] op_sel:[0,0,1] op_sel_hi:[0,1,0] neg_lo:[0,1,0] neg_hi:[0,1,0]
	v_pk_add_f32 v[34:35], v[4:5], v[16:17]
	v_pk_add_f32 v[4:5], v[4:5], v[16:17] neg_lo:[0,1] neg_hi:[0,1]
	ds_write2_b64 v2, v[40:41], v[64:65] offset1:16
	ds_write2_b64 v2, v[66:67], v[70:71] offset0:33 offset1:49
	ds_write2_b64 v2, v[60:61], v[58:59] offset0:66 offset1:82
	ds_write2_b64 v2, v[68:69], v[54:55] offset0:99 offset1:115
	ds_write2_b64 v2, v[28:29], v[52:53] offset0:132 offset1:148
	ds_write2_b64 v2, v[46:47], v[48:49] offset0:165 offset1:181
	ds_write2_b64 v2, v[44:45], v[42:43] offset0:198 offset1:214
	ds_write2_b64 v2, v[38:39], v[34:35] offset0:231 offset1:247
	ds_write2_b64 v3, v[22:23], v[56:57] offset0:8 offset1:24
	ds_write2_b64 v3, v[62:63], v[32:33] offset0:41 offset1:57
	ds_write2_b64 v3, v[14:15], v[50:51] offset0:74 offset1:90
	ds_write2_b64 v3, v[26:27], v[24:25] offset0:107 offset1:123
	ds_write2_b64 v3, v[12:13], v[36:37] offset0:140 offset1:156
	ds_write2_b64 v3, v[10:11], v[20:21] offset0:173 offset1:189
	ds_write2_b64 v3, v[30:31], v[8:9] offset0:206 offset1:222
	ds_write2_b64 v3, v[6:7], v[4:5] offset0:239 offset1:255
	s_waitcnt lgkmcnt(0)
	s_barrier
	global_load_dword v30, v206, s[0:1]
	global_load_dword v20, v207, s[0:1]
	v_ashrrev_i32_e32 v2, 31, v210
	v_lshrrev_b32_e32 v2, 22, v2
	v_add_u32_e32 v2, v210, v2
	v_ashrrev_i32_e32 v2, 10, v2
	v_mul_i32_i24_e32 v3, 0x400, v2
	global_load_dword v31, v205, s[0:1]
	global_load_dword v24, v205, s[62:63]
	s_add_u32 s0, s87, s74
	v_sub_u32_e32 v21, v210, v3
	v_lshlrev_b32_e32 v36, 14, v2
	s_addc_u32 s1, s90, s75
	v_ashrrev_i32_e32 v37, 31, v36
	v_lshlrev_b32_e32 v32, 4, v21
	v_lshl_add_u64 v[2:3], v[36:37], 1, s[0:1]
	v_ashrrev_i32_e32 v33, 31, v32
	v_lshl_add_u64 v[2:3], v[32:33], 1, v[2:3]
	global_load_dwordx4 v[10:13], v[2:3], off offset:16 nt
	global_load_dwordx4 v[14:17], v[2:3], off nt
	v_cmp_lt_i32_e32 vcc, 0, v21
	v_mov_b32_e32 v39, 0
	v_mov_b32_e32 v41, 0
	s_and_saveexec_b64 s[72:73], vcc
	s_cbranch_execz .LBB0_505
	global_load_ushort v41, v[2:3], off offset:-2

.LBB0_511:
	s_or_b64 exec, exec, s[0:1]
	v_mov_b32_e32 v25, v210
	s_mov_b32 s72, s37
	v_and_b32_e32 v28, 0x1ff, v25
	v_cvt_f32_u32_e32 v34, v28
	v_lshlrev_b32_e32 v25, 5, v25
	v_and_or_b32 v25, v25, s94, v28
	v_ashrrev_i32_e32 v28, 5, v25
	v_mul_f32_e32 v34, 0x38800000, v34
	v_sin_f32_e32 v43, v34
	v_cos_f32_e32 v42, v34
	v_lshlrev_b32_e32 v25, 3, v25
	v_lshlrev_b32_e32 v28, 3, v28
	v_xor_b32_e32 v44, 0x80000000, v43
	v_mov_b32_e32 v45, v43
	v_pk_mul_f32 v[46:47], v[42:43], v[44:45] op_sel:[1,0] op_sel_hi:[0,1]
	v_pk_fma_f32 v[46:47], v[42:43], v[42:43], v[46:47] op_sel_hi:[1,0,1]
	v_add3_u32 v25, 0, v25, v28
	v_xor_b32_e32 v50, 0x80000000, v47
	v_mov_b32_e32 v51, v47
	v_pk_mul_f32 v[52:53], v[46:47], v[50:51] op_sel:[1,0] op_sel_hi:[0,1]
	v_pk_fma_f32 v[52:53], v[46:47], v[46:47], v[52:53] op_sel_hi:[1,0,1]
	v_add_u32_e32 v28, 0x10800, v25
	v_xor_b32_e32 v54, 0x80000000, v53
	v_mov_b32_e32 v55, v53
	v_pk_mul_f32 v[70:71], v[52:53], v[54:55] op_sel:[1,0] op_sel_hi:[0,1]
	v_pk_fma_f32 v[70:71], v[52:53], v[52:53], v[70:71] op_sel_hi:[1,0,1]
	v_pk_mul_f32 v[48:49], v[44:45], v[46:47] op_sel:[0,1] op_sel_hi:[1,0]
	v_pk_mul_f32 v[86:87], v[54:55], v[70:71] op_sel:[0,1] op_sel_hi:[1,0]
	ds_read_b64 v[168:169], v25
	ds_read_b64 v[170:171], v25 offset:4224
	ds_read_b64 v[172:173], v25 offset:8448
	ds_read_b64 v[174:175], v25 offset:12672
	ds_read_b64 v[176:177], v25 offset:16896
	ds_read_b64 v[178:179], v25 offset:21120
	ds_read_b64 v[180:181], v25 offset:25344
	ds_read_b64 v[182:183], v25 offset:29568
	ds_read_b64 v[184:185], v25 offset:33792
	ds_read_b64 v[186:187], v25 offset:38016
	ds_read_b64 v[188:189], v25 offset:42240
	ds_read_b64 v[190:191], v25 offset:46464
	ds_read_b64 v[192:193], v25 offset:50688
	ds_read_b64 v[194:195], v25 offset:54912
	ds_read_b64 v[196:197], v25 offset:59136
	ds_read_b64 v[198:199], v25 offset:63360
	v_pk_fma_f32 v[86:87], v[52:53], v[70:71], v[86:87] op_sel_hi:[0,1,1]
	v_pk_mul_f32 v[102:103], v[54:55], v[86:87] op_sel:[0,1] op_sel_hi:[1,0]
	v_add_u32_e32 v34, 0x11880, v25
	v_pk_fma_f32 v[102:103], v[52:53], v[86:87], v[102:103] op_sel_hi:[0,1,1]
	v_pk_mul_f32 v[118:119], v[54:55], v[102:103] op_sel:[0,1] op_sel_hi:[1,0]
	v_add_u32_e32 v38, 0x12900, v25
	v_pk_fma_f32 v[118:119], v[52:53], v[102:103], v[118:119] op_sel_hi:[0,1,1]
	v_pk_mul_f32 v[134:135], v[54:55], v[118:119] op_sel:[0,1] op_sel_hi:[1,0]
	v_add_u32_e32 v40, 0x13980, v25
	v_pk_fma_f32 v[134:135], v[52:53], v[118:119], v[134:135] op_sel_hi:[0,1,1]
	v_pk_mul_f32 v[152:153], v[54:55], v[134:135] op_sel:[0,1] op_sel_hi:[1,0]
	ds_read_b64 v[212:213], v28
	ds_read_b64 v[214:215], v34
	ds_read_b64 v[216:217], v38
	ds_read_b64 v[218:219], v40
	v_add_u32_e32 v28, 0x14a00, v25
	v_pk_fma_f32 v[48:49], v[42:43], v[46:47], v[48:49] op_sel_hi:[0,1,1]
	v_pk_fma_f32 v[152:153], v[52:53], v[134:135], v[152:153] op_sel_hi:[0,1,1]
	v_add_u32_e32 v34, 0x15a80, v25
	v_add_u32_e32 v38, 0x16b00, v25
	v_add_u32_e32 v40, 0x17b80, v25
	ds_read_b64 v[220:221], v28
	ds_read_b64 v[222:223], v34
	ds_read_b64 v[224:225], v38
	ds_read_b64 v[226:227], v40
	v_add_u32_e32 v28, 0x18c00, v25
	v_xor_b32_e32 v56, 0x80000000, v49
	v_mov_b32_e32 v57, v49
	v_pk_mul_f32 v[58:59], v[44:45], v[52:53] op_sel:[0,1] op_sel_hi:[1,0]
	v_pk_mul_f32 v[74:75], v[44:45], v[70:71] op_sel:[0,1] op_sel_hi:[1,0]
	v_pk_mul_f32 v[90:91], v[44:45], v[86:87] op_sel:[0,1] op_sel_hi:[1,0]
	v_pk_mul_f32 v[106:107], v[44:45], v[102:103] op_sel:[0,1] op_sel_hi:[1,0]
	v_pk_mul_f32 v[122:123], v[44:45], v[118:119] op_sel:[0,1] op_sel_hi:[1,0]
	v_pk_mul_f32 v[138:139], v[44:45], v[134:135] op_sel:[0,1] op_sel_hi:[1,0]
	v_pk_mul_f32 v[156:157], v[44:45], v[152:153] op_sel:[0,1] op_sel_hi:[1,0]
	v_add_u32_e32 v34, 0x19c80, v25
	v_add_u32_e32 v38, 0x1ad00, v25
	v_add_u32_e32 v40, 0x1bd80, v25
	ds_read_b64 v[228:229], v28
	ds_read_b64 v[230:231], v34
	ds_read_b64 v[232:233], v38
	ds_read_b64 v[234:235], v40
	v_add_u32_e32 v28, 0x1ce00, v25
	s_waitcnt lgkmcnt(11)
	v_pk_mul_f32 v[44:45], v[44:45], v[212:213] op_sel:[0,1] op_sel_hi:[1,0]
	v_pk_fma_f32 v[58:59], v[42:43], v[52:53], v[58:59] op_sel_hi:[0,1,1]
	v_pk_mul_f32 v[62:63], v[50:51], v[52:53] op_sel:[0,1] op_sel_hi:[1,0]
	v_pk_mul_f32 v[66:67], v[52:53], v[56:57] op_sel:[1,0] op_sel_hi:[0,1]
	v_pk_fma_f32 v[74:75], v[42:43], v[70:71], v[74:75] op_sel_hi:[0,1,1]
	v_pk_mul_f32 v[78:79], v[50:51], v[70:71] op_sel:[0,1] op_sel_hi:[1,0]
	v_pk_fma_f32 v[90:91], v[42:43], v[86:87], v[90:91] op_sel_hi:[0,1,1]
	v_pk_mul_f32 v[94:95], v[50:51], v[86:87] op_sel:[0,1] op_sel_hi:[1,0]
	v_pk_fma_f32 v[106:107], v[42:43], v[102:103], v[106:107] op_sel_hi:[0,1,1]
	v_pk_mul_f32 v[110:111], v[50:51], v[102:103] op_sel:[0,1] op_sel_hi:[1,0]
	v_pk_fma_f32 v[122:123], v[42:43], v[118:119], v[122:123] op_sel_hi:[0,1,1]
	v_pk_mul_f32 v[126:127], v[50:51], v[118:119] op_sel:[0,1] op_sel_hi:[1,0]
	v_pk_fma_f32 v[138:139], v[42:43], v[134:135], v[138:139] op_sel_hi:[0,1,1]
	v_pk_mul_f32 v[142:143], v[50:51], v[134:135] op_sel:[0,1] op_sel_hi:[1,0]
	v_pk_fma_f32 v[156:157], v[42:43], v[152:153], v[156:157] op_sel_hi:[0,1,1]
	v_pk_mul_f32 v[160:161], v[50:51], v[152:153] op_sel:[0,1] op_sel_hi:[1,0]
	v_add_u32_e32 v34, 0x1de80, v25
	v_add_u32_e32 v38, 0x1ef00, v25
	v_add_u32_e32 v40, 0x1ff80, v25
	ds_read_b64 v[236:237], v28
	ds_read_b64 v[238:239], v34
	ds_read_b64 v[240:241], v38
	ds_read_b64 v[242:243], v40
	v_pk_fma_f32 v[42:43], v[42:43], v[212:213], v[44:45] op_sel_hi:[0,1,1]
	v_pk_mul_f32 v[44:45], v[184:185], v[50:51] op_sel:[1,0] op_sel_hi:[0,1]
	v_pk_fma_f32 v[62:63], v[46:47], v[52:53], v[62:63] op_sel_hi:[0,1,1]
	v_pk_fma_f32 v[66:67], v[52:53], v[48:49], v[66:67] op_sel_hi:[1,0,1]
	v_pk_fma_f32 v[78:79], v[46:47], v[70:71], v[78:79] op_sel_hi:[0,1,1]
	v_pk_mul_f32 v[82:83], v[56:57], v[70:71] op_sel:[0,1] op_sel_hi:[1,0]
	v_pk_fma_f32 v[94:95], v[46:47], v[86:87], v[94:95] op_sel_hi:[0,1,1]
	v_pk_mul_f32 v[98:99], v[56:57], v[86:87] op_sel:[0,1] op_sel_hi:[1,0]
	v_pk_fma_f32 v[110:111], v[46:47], v[102:103], v[110:111] op_sel_hi:[0,1,1]
	v_pk_mul_f32 v[114:115], v[56:57], v[102:103] op_sel:[0,1] op_sel_hi:[1,0]
	v_pk_fma_f32 v[126:127], v[46:47], v[118:119], v[126:127] op_sel_hi:[0,1,1]
	v_pk_mul_f32 v[130:131], v[56:57], v[118:119] op_sel:[0,1] op_sel_hi:[1,0]
	v_pk_fma_f32 v[142:143], v[46:47], v[134:135], v[142:143] op_sel_hi:[0,1,1]
	v_pk_mul_f32 v[148:149], v[56:57], v[134:135] op_sel:[0,1] op_sel_hi:[1,0]
	v_pk_fma_f32 v[160:161], v[46:47], v[152:153], v[160:161] op_sel_hi:[0,1,1]
	v_pk_mul_f32 v[164:165], v[56:57], v[152:153] op_sel:[0,1] op_sel_hi:[1,0]
	v_pk_fma_f32 v[44:45], v[184:185], v[46:47], v[44:45] op_sel_hi:[1,0,1]
	s_waitcnt lgkmcnt(7)
	v_pk_mul_f32 v[46:47], v[56:57], v[228:229] op_sel:[0,1] op_sel_hi:[1,0]
	v_xor_b32_e32 v60, 0x80000000, v59
	v_xor_b32_e32 v64, 0x80000000, v63
	v_xor_b32_e32 v68, 0x80000000, v67
	v_xor_b32_e32 v72, 0x80000000, v71
	v_pk_fma_f32 v[82:83], v[48:49], v[70:71], v[82:83] op_sel_hi:[0,1,1]
	v_pk_fma_f32 v[98:99], v[48:49], v[86:87], v[98:99] op_sel_hi:[0,1,1]
	v_pk_fma_f32 v[114:115], v[48:49], v[102:103], v[114:115] op_sel_hi:[0,1,1]
	v_pk_fma_f32 v[130:131], v[48:49], v[118:119], v[130:131] op_sel_hi:[0,1,1]
	v_pk_fma_f32 v[148:149], v[48:49], v[134:135], v[148:149] op_sel_hi:[0,1,1]
	v_pk_fma_f32 v[164:165], v[48:49], v[152:153], v[164:165] op_sel_hi:[0,1,1]
	v_mov_b32_e32 v61, v59
	v_mov_b32_e32 v65, v63
	v_mov_b32_e32 v69, v67
	v_mov_b32_e32 v73, v71
	v_pk_fma_f32 v[46:47], v[48:49], v[228:229], v[46:47] op_sel_hi:[0,1,1]
	v_pk_mul_f32 v[48:49], v[176:177], v[54:55] op_sel:[1,0] op_sel_hi:[0,1]
	v_xor_b32_e32 v76, 0x80000000, v75
	v_xor_b32_e32 v80, 0x80000000, v79
	v_xor_b32_e32 v84, 0x80000000, v83
	v_xor_b32_e32 v88, 0x80000000, v87
	v_xor_b32_e32 v92, 0x80000000, v91
	v_xor_b32_e32 v96, 0x80000000, v95
	v_xor_b32_e32 v100, 0x80000000, v99
	v_xor_b32_e32 v104, 0x80000000, v103
	v_xor_b32_e32 v136, 0x80000000, v135
	v_mov_b32_e32 v77, v75
	v_mov_b32_e32 v81, v79
	v_mov_b32_e32 v85, v83
	v_mov_b32_e32 v89, v87
	v_mov_b32_e32 v93, v91
	v_mov_b32_e32 v97, v95
	v_mov_b32_e32 v101, v99
	v_mov_b32_e32 v105, v103
	v_mov_b32_e32 v137, v135
	v_pk_fma_f32 v[48:49], v[176:177], v[52:53], v[48:49] op_sel_hi:[1,0,1]
	v_pk_mul_f32 v[50:51], v[60:61], v[220:221] op_sel:[0,1] op_sel_hi:[1,0]
	v_pk_mul_f32 v[52:53], v[192:193], v[64:65] op_sel:[1,0] op_sel_hi:[0,1]
	s_waitcnt lgkmcnt(3)
	v_pk_mul_f32 v[54:55], v[68:69], v[236:237] op_sel:[0,1] op_sel_hi:[1,0]
	v_pk_mul_f32 v[56:57], v[172:173], v[72:73] op_sel:[1,0] op_sel_hi:[0,1]
	v_xor_b32_e32 v108, 0x80000000, v107
	v_xor_b32_e32 v112, 0x80000000, v111
	v_xor_b32_e32 v116, 0x80000000, v115
	v_xor_b32_e32 v120, 0x80000000, v119
	v_xor_b32_e32 v124, 0x80000000, v123
	v_xor_b32_e32 v128, 0x80000000, v127
	v_xor_b32_e32 v132, 0x80000000, v131
	v_xor_b32_e32 v140, 0x80000000, v139
	v_xor_b32_e32 v144, 0x80000000, v143
	v_xor_b32_e32 v150, 0x80000000, v149
	v_xor_b32_e32 v154, 0x80000000, v153
	v_xor_b32_e32 v158, 0x80000000, v157
	v_xor_b32_e32 v162, 0x80000000, v161
	v_xor_b32_e32 v166, 0x80000000, v165
	v_mov_b32_e32 v109, v107
	v_mov_b32_e32 v113, v111
	v_mov_b32_e32 v117, v115
	v_mov_b32_e32 v121, v119
	v_mov_b32_e32 v125, v123
	v_mov_b32_e32 v129, v127
	v_mov_b32_e32 v133, v131
	v_mov_b32_e32 v141, v139
	v_mov_b32_e32 v145, v143
	v_mov_b32_e32 v151, v149
	v_mov_b32_e32 v155, v153
	v_mov_b32_e32 v159, v157
	v_mov_b32_e32 v163, v161
	v_mov_b32_e32 v167, v165
	v_pk_fma_f32 v[50:51], v[58:59], v[220:221], v[50:51] op_sel_hi:[0,1,1]
	v_pk_fma_f32 v[52:53], v[192:193], v[62:63], v[52:53] op_sel_hi:[1,0,1]
	v_pk_fma_f32 v[54:55], v[66:67], v[236:237], v[54:55] op_sel_hi:[0,1,1]
	v_pk_fma_f32 v[56:57], v[172:173], v[70:71], v[56:57] op_sel_hi:[1,0,1]
	v_pk_mul_f32 v[58:59], v[216:217], v[76:77] op_sel:[1,0] op_sel_hi:[0,1]
	v_pk_mul_f32 v[60:61], v[188:189], v[80:81] op_sel:[1,0] op_sel_hi:[0,1]
	v_pk_mul_f32 v[62:63], v[84:85], v[232:233] op_sel:[0,1] op_sel_hi:[1,0]
	v_pk_mul_f32 v[64:65], v[180:181], v[88:89] op_sel:[1,0] op_sel_hi:[0,1]
	v_pk_mul_f32 v[66:67], v[224:225], v[92:93] op_sel:[1,0] op_sel_hi:[0,1]
	v_pk_mul_f32 v[68:69], v[196:197], v[96:97] op_sel:[1,0] op_sel_hi:[0,1]
	s_waitcnt lgkmcnt(1)
	v_pk_mul_f32 v[70:71], v[100:101], v[240:241] op_sel:[0,1] op_sel_hi:[1,0]
	v_pk_mul_f32 v[72:73], v[170:171], v[104:105] op_sel:[1,0] op_sel_hi:[0,1]
	v_pk_mul_f32 v[88:89], v[174:175], v[136:137] op_sel:[1,0] op_sel_hi:[0,1]
	v_pk_fma_f32 v[58:59], v[216:217], v[74:75], v[58:59] op_sel_hi:[1,0,1]
	v_pk_fma_f32 v[60:61], v[188:189], v[78:79], v[60:61] op_sel_hi:[1,0,1]
	v_pk_fma_f32 v[62:63], v[82:83], v[232:233], v[62:63] op_sel_hi:[0,1,1]
	v_pk_fma_f32 v[64:65], v[180:181], v[86:87], v[64:65] op_sel_hi:[1,0,1]
	v_pk_fma_f32 v[66:67], v[224:225], v[90:91], v[66:67] op_sel_hi:[1,0,1]
	v_pk_fma_f32 v[68:69], v[196:197], v[94:95], v[68:69] op_sel_hi:[1,0,1]
	v_pk_fma_f32 v[70:71], v[98:99], v[240:241], v[70:71] op_sel_hi:[0,1,1]
	v_pk_fma_f32 v[72:73], v[170:171], v[102:103], v[72:73] op_sel_hi:[1,0,1]
	v_pk_mul_f32 v[74:75], v[214:215], v[108:109] op_sel:[1,0] op_sel_hi:[0,1]
	v_pk_mul_f32 v[76:77], v[186:187], v[112:113] op_sel:[1,0] op_sel_hi:[0,1]
	v_pk_mul_f32 v[78:79], v[230:231], v[116:117] op_sel:[1,0] op_sel_hi:[0,1]
	v_pk_mul_f32 v[80:81], v[178:179], v[120:121] op_sel:[1,0] op_sel_hi:[0,1]
	v_pk_mul_f32 v[82:83], v[222:223], v[124:125] op_sel:[1,0] op_sel_hi:[0,1]
	v_pk_mul_f32 v[84:85], v[194:195], v[128:129] op_sel:[1,0] op_sel_hi:[0,1]
	v_pk_mul_f32 v[86:87], v[132:133], v[238:239] op_sel:[0,1] op_sel_hi:[1,0]
	v_pk_fma_f32 v[88:89], v[174:175], v[134:135], v[88:89] op_sel_hi:[1,0,1]
	v_pk_mul_f32 v[90:91], v[218:219], v[140:141] op_sel:[1,0] op_sel_hi:[0,1]
	v_pk_mul_f32 v[92:93], v[190:191], v[144:145] op_sel:[1,0] op_sel_hi:[0,1]
	v_pk_mul_f32 v[94:95], v[234:235], v[150:151] op_sel:[1,0] op_sel_hi:[0,1]
	v_pk_mul_f32 v[96:97], v[182:183], v[154:155] op_sel:[1,0] op_sel_hi:[0,1]
	v_pk_mul_f32 v[98:99], v[226:227], v[158:159] op_sel:[1,0] op_sel_hi:[0,1]
	v_pk_mul_f32 v[100:101], v[198:199], v[162:163] op_sel:[1,0] op_sel_hi:[0,1]
	s_waitcnt lgkmcnt(0)
	v_pk_mul_f32 v[102:103], v[242:243], v[166:167] op_sel:[1,0] op_sel_hi:[0,1]
	v_pk_fma_f32 v[74:75], v[214:215], v[106:107], v[74:75] op_sel_hi:[1,0,1]
	v_pk_fma_f32 v[76:77], v[186:187], v[110:111], v[76:77] op_sel_hi:[1,0,1]
	v_pk_fma_f32 v[78:79], v[230:231], v[114:115], v[78:79] op_sel_hi:[1,0,1]
	v_pk_fma_f32 v[80:81], v[178:179], v[118:119], v[80:81] op_sel_hi:[1,0,1]
	v_pk_fma_f32 v[82:83], v[222:223], v[122:123], v[82:83] op_sel_hi:[1,0,1]
	v_pk_fma_f32 v[84:85], v[194:195], v[126:127], v[84:85] op_sel_hi:[1,0,1]
	v_pk_fma_f32 v[86:87], v[130:131], v[238:239], v[86:87] op_sel_hi:[0,1,1]
	v_pk_fma_f32 v[90:91], v[218:219], v[138:139], v[90:91] op_sel_hi:[1,0,1]
	v_pk_fma_f32 v[92:93], v[190:191], v[142:143], v[92:93] op_sel_hi:[1,0,1]
	v_pk_fma_f32 v[94:95], v[234:235], v[148:149], v[94:95] op_sel_hi:[1,0,1]
	v_pk_fma_f32 v[96:97], v[182:183], v[152:153], v[96:97] op_sel_hi:[1,0,1]
	v_pk_fma_f32 v[98:99], v[226:227], v[156:157], v[98:99] op_sel_hi:[1,0,1]
	v_pk_fma_f32 v[100:101], v[198:199], v[160:161], v[100:101] op_sel_hi:[1,0,1]
	v_pk_fma_f32 v[102:103], v[242:243], v[164:165], v[102:103] op_sel_hi:[1,0,1]
	v_pk_add_f32 v[104:105], v[168:169], v[72:73]
	v_pk_add_f32 v[106:107], v[56:57], v[88:89]
	v_pk_add_f32 v[56:57], v[56:57], v[88:89] neg_lo:[0,1] neg_hi:[0,1]
	v_pk_add_f32 v[72:73], v[168:169], v[72:73] neg_lo:[0,1] neg_hi:[0,1]
	v_pk_add_f32 v[88:89], v[48:49], v[80:81]
	v_pk_add_f32 v[48:49], v[48:49], v[80:81] neg_lo:[0,1] neg_hi:[0,1]
	v_pk_add_f32 v[80:81], v[64:65], v[96:97]
	v_pk_add_f32 v[64:65], v[64:65], v[96:97] neg_lo:[0,1] neg_hi:[0,1]
	v_pk_add_f32 v[96:97], v[44:45], v[76:77]
	v_pk_add_f32 v[44:45], v[44:45], v[76:77] neg_lo:[0,1] neg_hi:[0,1]
	v_pk_add_f32 v[76:77], v[60:61], v[92:93]
	v_pk_add_f32 v[60:61], v[60:61], v[92:93] neg_lo:[0,1] neg_hi:[0,1]
	v_pk_add_f32 v[92:93], v[52:53], v[84:85]
	v_pk_add_f32 v[52:53], v[52:53], v[84:85] neg_lo:[0,1] neg_hi:[0,1]
	v_pk_add_f32 v[84:85], v[68:69], v[100:101]
	v_pk_add_f32 v[68:69], v[68:69], v[100:101] neg_lo:[0,1] neg_hi:[0,1]
	v_pk_add_f32 v[100:101], v[42:43], v[74:75]
	v_pk_add_f32 v[42:43], v[42:43], v[74:75] neg_lo:[0,1] neg_hi:[0,1]
	v_pk_add_f32 v[74:75], v[58:59], v[90:91]
	v_pk_add_f32 v[58:59], v[58:59], v[90:91] neg_lo:[0,1] neg_hi:[0,1]
	v_pk_add_f32 v[90:91], v[50:51], v[82:83]
	v_pk_add_f32 v[50:51], v[50:51], v[82:83] neg_lo:[0,1] neg_hi:[0,1]
	v_pk_add_f32 v[82:83], v[66:67], v[98:99]
	v_pk_add_f32 v[66:67], v[66:67], v[98:99] neg_lo:[0,1] neg_hi:[0,1]
	v_pk_add_f32 v[98:99], v[46:47], v[78:79]
	v_pk_add_f32 v[46:47], v[46:47], v[78:79] neg_lo:[0,1] neg_hi:[0,1]
	v_pk_add_f32 v[78:79], v[62:63], v[94:95]
	v_pk_add_f32 v[62:63], v[62:63], v[94:95] neg_lo:[0,1] neg_hi:[0,1]
	v_pk_add_f32 v[94:95], v[54:55], v[86:87]
	v_pk_add_f32 v[54:55], v[54:55], v[86:87] neg_lo:[0,1] neg_hi:[0,1]
	v_pk_add_f32 v[86:87], v[70:71], v[102:103]
	v_pk_add_f32 v[70:71], v[70:71], v[102:103] neg_lo:[0,1] neg_hi:[0,1]
	v_pk_add_f32 v[102:103], v[104:105], v[106:107]
	v_pk_add_f32 v[104:105], v[104:105], v[106:107] neg_lo:[0,1] neg_hi:[0,1]
	v_xor_b32_e32 v106, 0x80000000, v57
	v_mov_b32_e32 v107, v56
	v_pk_add_f32 v[56:57], v[72:73], v[106:107]
	v_pk_add_f32 v[72:73], v[72:73], v[106:107] neg_lo:[0,1] neg_hi:[0,1]
	v_pk_add_f32 v[106:107], v[88:89], v[80:81]
	v_pk_add_f32 v[80:81], v[88:89], v[80:81] neg_lo:[0,1] neg_hi:[0,1]
	v_xor_b32_e32 v88, 0x80000000, v65
	v_mov_b32_e32 v89, v64
	v_pk_add_f32 v[64:65], v[48:49], v[88:89]
	v_pk_add_f32 v[48:49], v[48:49], v[88:89] neg_lo:[0,1] neg_hi:[0,1]
	v_pk_add_f32 v[88:89], v[96:97], v[76:77]
	v_pk_add_f32 v[76:77], v[96:97], v[76:77] neg_lo:[0,1] neg_hi:[0,1]
	v_xor_b32_e32 v96, 0x80000000, v61
	v_mov_b32_e32 v97, v60
	v_pk_add_f32 v[60:61], v[44:45], v[96:97]
	v_pk_add_f32 v[44:45], v[44:45], v[96:97] neg_lo:[0,1] neg_hi:[0,1]
	v_pk_add_f32 v[96:97], v[92:93], v[84:85]
	v_pk_add_f32 v[84:85], v[92:93], v[84:85] neg_lo:[0,1] neg_hi:[0,1]
	v_xor_b32_e32 v92, 0x80000000, v69
	v_mov_b32_e32 v93, v68
	v_pk_add_f32 v[68:69], v[52:53], v[92:93]
	v_pk_add_f32 v[52:53], v[52:53], v[92:93] neg_lo:[0,1] neg_hi:[0,1]
	v_pk_add_f32 v[92:93], v[100:101], v[74:75]
	v_pk_add_f32 v[74:75], v[100:101], v[74:75] neg_lo:[0,1] neg_hi:[0,1]
	v_xor_b32_e32 v100, 0x80000000, v59
	v_mov_b32_e32 v101, v58
	v_pk_add_f32 v[58:59], v[42:43], v[100:101]
	v_pk_add_f32 v[42:43], v[42:43], v[100:101] neg_lo:[0,1] neg_hi:[0,1]
	v_pk_add_f32 v[100:101], v[90:91], v[82:83]
	v_pk_add_f32 v[82:83], v[90:91], v[82:83] neg_lo:[0,1] neg_hi:[0,1]
	v_xor_b32_e32 v90, 0x80000000, v67
	v_mov_b32_e32 v91, v66
	v_pk_add_f32 v[66:67], v[50:51], v[90:91]
	v_pk_add_f32 v[50:51], v[50:51], v[90:91] neg_lo:[0,1] neg_hi:[0,1]
	v_pk_add_f32 v[90:91], v[98:99], v[78:79]
	v_pk_add_f32 v[78:79], v[98:99], v[78:79] neg_lo:[0,1] neg_hi:[0,1]
	v_xor_b32_e32 v98, 0x80000000, v63
	v_mov_b32_e32 v99, v62
	v_pk_add_f32 v[62:63], v[46:47], v[98:99]
	v_pk_add_f32 v[46:47], v[46:47], v[98:99] neg_lo:[0,1] neg_hi:[0,1]
	v_pk_add_f32 v[98:99], v[94:95], v[86:87]
	v_pk_add_f32 v[86:87], v[94:95], v[86:87] neg_lo:[0,1] neg_hi:[0,1]
	v_xor_b32_e32 v94, 0x80000000, v71
	v_mov_b32_e32 v95, v70
	s_mov_b32 s73, s36
	v_pk_add_f32 v[70:71], v[54:55], v[94:95]
	v_pk_add_f32 v[54:55], v[54:55], v[94:95] neg_lo:[0,1] neg_hi:[0,1]
	v_pk_add_f32 v[94:95], v[102:103], v[106:107]
	v_pk_add_f32 v[102:103], v[102:103], v[106:107] neg_lo:[0,1] neg_hi:[0,1]
	s_mov_b32 s0, s37
	v_pk_mul_f32 v[106:107], v[64:65], s[72:73]
	s_mov_b32 s74, s19
	v_pk_fma_f32 v[64:65], v[64:65], s[0:1], v[106:107] op_sel:[0,0,1] op_sel_hi:[1,0,0]
	s_mov_b32 s75, s18
	v_pk_add_f32 v[106:107], v[56:57], v[64:65]
	v_pk_add_f32 v[56:57], v[56:57], v[64:65] neg_lo:[0,1] neg_hi:[0,1]
	v_xor_b32_e32 v64, 0x80000000, v81
	v_mov_b32_e32 v65, v80
	v_pk_add_f32 v[80:81], v[104:105], v[64:65]
	v_pk_add_f32 v[64:65], v[104:105], v[64:65] neg_lo:[0,1] neg_hi:[0,1]
	v_pk_mul_f32 v[104:105], v[48:49], s[72:73]
	s_mov_b32 s76, s19
	v_pk_fma_f32 v[48:49], v[48:49], s[0:1], v[104:105] op_sel:[0,0,1] op_sel_hi:[1,0,0] neg_lo:[1,0,0] neg_hi:[1,0,0]
	s_mov_b32 s62, s11
	v_pk_add_f32 v[104:105], v[72:73], v[48:49]
	v_pk_add_f32 v[48:49], v[72:73], v[48:49] neg_lo:[0,1] neg_hi:[0,1]
	v_pk_add_f32 v[72:73], v[88:89], v[96:97]
	v_pk_add_f32 v[88:89], v[88:89], v[96:97] neg_lo:[0,1] neg_hi:[0,1]
	v_pk_mul_f32 v[96:97], v[68:69], s[72:73]
	s_mov_b32 s63, s10
	v_pk_fma_f32 v[68:69], v[68:69], s[0:1], v[96:97] op_sel:[0,0,1] op_sel_hi:[1,0,0]
	s_mov_b32 s78, s27
	v_pk_add_f32 v[96:97], v[60:61], v[68:69]
	v_pk_add_f32 v[60:61], v[60:61], v[68:69] neg_lo:[0,1] neg_hi:[0,1]
	v_xor_b32_e32 v68, 0x80000000, v85
	v_mov_b32_e32 v69, v84
	v_pk_add_f32 v[84:85], v[76:77], v[68:69]
	v_pk_add_f32 v[68:69], v[76:77], v[68:69] neg_lo:[0,1] neg_hi:[0,1]
	v_pk_mul_f32 v[76:77], v[52:53], s[72:73]
	v_pk_mul_f32 v[108:109], v[96:97], s[74:75]
	v_pk_fma_f32 v[52:53], v[52:53], s[0:1], v[76:77] op_sel:[0,0,1] op_sel_hi:[1,0,0] neg_lo:[1,0,0] neg_hi:[1,0,0]
	v_pk_fma_f32 v[96:97], v[96:97], s[16:17], v[108:109] op_sel:[0,0,1] op_sel_hi:[1,0,0]
	v_pk_add_f32 v[76:77], v[44:45], v[52:53]
	v_pk_add_f32 v[44:45], v[44:45], v[52:53] neg_lo:[0,1] neg_hi:[0,1]
	v_pk_add_f32 v[52:53], v[92:93], v[100:101]
	v_pk_add_f32 v[92:93], v[92:93], v[100:101] neg_lo:[0,1] neg_hi:[0,1]
	v_pk_mul_f32 v[100:101], v[66:67], s[72:73]
	s_mov_b32 s17, s40
	v_pk_fma_f32 v[66:67], v[66:67], s[0:1], v[100:101] op_sel:[0,0,1] op_sel_hi:[1,0,0]
	v_pk_add_f32 v[108:109], v[106:107], v[96:97]
	v_pk_add_f32 v[100:101], v[58:59], v[66:67]
	v_pk_add_f32 v[58:59], v[58:59], v[66:67] neg_lo:[0,1] neg_hi:[0,1]
	v_xor_b32_e32 v66, 0x80000000, v83
	v_mov_b32_e32 v67, v82
	v_pk_add_f32 v[82:83], v[74:75], v[66:67]
	v_pk_add_f32 v[66:67], v[74:75], v[66:67] neg_lo:[0,1] neg_hi:[0,1]
	v_pk_mul_f32 v[74:75], v[50:51], s[72:73]
	v_pk_add_f32 v[96:97], v[106:107], v[96:97] neg_lo:[0,1] neg_hi:[0,1]
	v_pk_fma_f32 v[50:51], v[50:51], s[0:1], v[74:75] op_sel:[0,0,1] op_sel_hi:[1,0,0] neg_lo:[1,0,0] neg_hi:[1,0,0]
	v_pk_mul_f32 v[106:107], v[84:85], s[72:73]
	v_pk_add_f32 v[74:75], v[42:43], v[50:51]
	v_pk_add_f32 v[42:43], v[42:43], v[50:51] neg_lo:[0,1] neg_hi:[0,1]
	v_pk_add_f32 v[50:51], v[90:91], v[98:99]
	v_pk_add_f32 v[90:91], v[90:91], v[98:99] neg_lo:[0,1] neg_hi:[0,1]
	v_pk_mul_f32 v[98:99], v[70:71], s[72:73]
	v_pk_fma_f32 v[84:85], v[84:85], s[0:1], v[106:107] op_sel:[0,0,1] op_sel_hi:[1,0,0]
	v_pk_fma_f32 v[70:71], v[70:71], s[0:1], v[98:99] op_sel:[0,0,1] op_sel_hi:[1,0,0]
	v_pk_add_f32 v[106:107], v[80:81], v[84:85]
	v_pk_add_f32 v[98:99], v[62:63], v[70:71]
	v_pk_add_f32 v[62:63], v[62:63], v[70:71] neg_lo:[0,1] neg_hi:[0,1]
	v_xor_b32_e32 v70, 0x80000000, v87
	v_mov_b32_e32 v71, v86
	v_pk_mul_f32 v[110:111], v[98:99], s[74:75]
	v_pk_add_f32 v[86:87], v[78:79], v[70:71]
	v_pk_add_f32 v[70:71], v[78:79], v[70:71] neg_lo:[0,1] neg_hi:[0,1]
	v_pk_mul_f32 v[78:79], v[54:55], s[72:73]
	v_pk_fma_f32 v[98:99], v[98:99], s[16:17], v[110:111] op_sel:[0,0,1] op_sel_hi:[1,0,0]
	v_pk_fma_f32 v[54:55], v[54:55], s[0:1], v[78:79] op_sel:[0,0,1] op_sel_hi:[1,0,0] neg_lo:[1,0,0] neg_hi:[1,0,0]
	v_pk_add_f32 v[110:111], v[100:101], v[98:99]
	v_pk_add_f32 v[98:99], v[100:101], v[98:99] neg_lo:[0,1] neg_hi:[0,1]
	v_pk_mul_f32 v[100:101], v[86:87], s[72:73]
	v_pk_add_f32 v[78:79], v[46:47], v[54:55]
	v_pk_fma_f32 v[86:87], v[86:87], s[0:1], v[100:101] op_sel:[0,0,1] op_sel_hi:[1,0,0]
	v_pk_add_f32 v[46:47], v[46:47], v[54:55] neg_lo:[0,1] neg_hi:[0,1]
	v_pk_add_f32 v[100:101], v[82:83], v[86:87]
	v_pk_add_f32 v[82:83], v[82:83], v[86:87] neg_lo:[0,1] neg_hi:[0,1]
	v_pk_mul_f32 v[86:87], v[78:79], s[16:17]
	v_pk_add_f32 v[80:81], v[80:81], v[84:85] neg_lo:[0,1] neg_hi:[0,1]
	v_pk_fma_f32 v[78:79], v[78:79], s[76:77], v[86:87] op_sel:[0,0,1] op_sel_hi:[1,0,0]
	v_pk_mul_f32 v[84:85], v[76:77], s[16:17]
	v_pk_add_f32 v[86:87], v[74:75], v[78:79]
	v_pk_add_f32 v[74:75], v[74:75], v[78:79] neg_lo:[0,1] neg_hi:[0,1]
	v_xor_b32_e32 v78, 0x80000000, v91
	v_mov_b32_e32 v79, v90
	v_pk_add_f32 v[90:91], v[92:93], v[78:79]
	v_pk_add_f32 v[78:79], v[92:93], v[78:79] neg_lo:[0,1] neg_hi:[0,1]
	v_pk_mul_f32 v[92:93], v[62:63], s[16:17]
	v_pk_fma_f32 v[76:77], v[76:77], s[76:77], v[84:85] op_sel:[0,0,1] op_sel_hi:[1,0,0]
	v_pk_fma_f32 v[62:63], v[62:63], s[76:77], v[92:93] op_sel:[0,0,1] op_sel_hi:[1,0,0] neg_lo:[1,0,0] neg_hi:[1,0,0]
	v_pk_add_f32 v[84:85], v[104:105], v[76:77]
	v_pk_add_f32 v[92:93], v[58:59], v[62:63]
	v_pk_add_f32 v[58:59], v[58:59], v[62:63] neg_lo:[0,1] neg_hi:[0,1]
	v_pk_mul_f32 v[62:63], v[70:71], s[72:73]
	v_pk_add_f32 v[76:77], v[104:105], v[76:77] neg_lo:[0,1] neg_hi:[0,1]
	v_pk_fma_f32 v[62:63], v[70:71], s[0:1], v[62:63] op_sel:[0,0,1] op_sel_hi:[1,0,0] neg_lo:[1,0,0] neg_hi:[1,0,0]
	v_xor_b32_e32 v104, 0x80000000, v89
	v_pk_add_f32 v[70:71], v[66:67], v[62:63]
	v_pk_add_f32 v[62:63], v[66:67], v[62:63] neg_lo:[0,1] neg_hi:[0,1]
	v_pk_mul_f32 v[66:67], v[46:47], s[74:75]
	v_mov_b32_e32 v105, v88
	v_pk_fma_f32 v[46:47], v[46:47], s[16:17], v[66:67] op_sel:[0,0,1] op_sel_hi:[1,0,0] neg_lo:[1,0,0] neg_hi:[1,0,0]
	s_mov_b32 s79, s26
	v_pk_add_f32 v[66:67], v[42:43], v[46:47]
	v_pk_add_f32 v[42:43], v[42:43], v[46:47] neg_lo:[0,1] neg_hi:[0,1]
	v_pk_mul_f32 v[46:47], v[110:111], s[62:63]
	v_pk_add_f32 v[88:89], v[102:103], v[104:105]
	v_pk_fma_f32 v[46:47], v[110:111], s[8:9], v[46:47] op_sel:[0,0,1] op_sel_hi:[1,0,0]
	v_pk_add_f32 v[102:103], v[102:103], v[104:105] neg_lo:[0,1] neg_hi:[0,1]
	v_pk_add_f32 v[46:47], v[108:109], v[46:47]
	v_pk_mul_f32 v[108:109], v[100:101], s[74:75]
	v_pk_mul_f32 v[104:105], v[60:61], s[16:17]
	v_pk_fma_f32 v[100:101], v[100:101], s[16:17], v[108:109] op_sel:[0,0,1] op_sel_hi:[1,0,0]
	v_pk_fma_f32 v[60:61], v[60:61], s[76:77], v[104:105] op_sel:[0,0,1] op_sel_hi:[1,0,0] neg_lo:[1,0,0] neg_hi:[1,0,0]
	v_pk_add_f32 v[100:101], v[106:107], v[100:101]
	v_pk_mul_f32 v[106:107], v[86:87], s[78:79]
	v_pk_add_f32 v[104:105], v[56:57], v[60:61]
	v_pk_fma_f32 v[86:87], v[86:87], s[24:25], v[106:107] op_sel:[0,0,1] op_sel_hi:[1,0,0]
	v_pk_add_f32 v[56:57], v[56:57], v[60:61] neg_lo:[0,1] neg_hi:[0,1]
	v_pk_mul_f32 v[60:61], v[68:69], s[72:73]
	v_pk_add_f32 v[84:85], v[84:85], v[86:87]
	v_pk_mul_f32 v[86:87], v[90:91], s[72:73]
	v_pk_fma_f32 v[60:61], v[68:69], s[0:1], v[60:61] op_sel:[0,0,1] op_sel_hi:[1,0,0] neg_lo:[1,0,0] neg_hi:[1,0,0]
	v_pk_fma_f32 v[86:87], v[90:91], s[0:1], v[86:87] op_sel:[0,0,1] op_sel_hi:[1,0,0]
	v_pk_mul_f32 v[90:91], v[70:71], s[16:17]
	v_pk_add_f32 v[68:69], v[64:65], v[60:61]
	v_pk_fma_f32 v[70:71], v[70:71], s[76:77], v[90:91] op_sel:[0,0,1] op_sel_hi:[1,0,0]
	s_mov_b32 s9, s42
	s_mov_b32 s25, s38
	v_pk_add_f32 v[68:69], v[68:69], v[70:71]
	s_mov_b32 s82, s11
	v_pk_mul_f32 v[70:71], v[66:67], s[8:9]
	s_mov_b32 s80, s27
	v_pk_fma_f32 v[66:67], v[66:67], s[82:83], v[70:71] op_sel:[0,0,1] op_sel_hi:[1,0,0]
	v_pk_mul_f32 v[70:71], v[74:75], s[24:25]
	v_pk_add_f32 v[60:61], v[64:65], v[60:61] neg_lo:[0,1] neg_hi:[0,1]
	v_pk_fma_f32 v[70:71], v[74:75], s[80:81], v[70:71] op_sel:[0,0,1] op_sel_hi:[1,0,0] neg_lo:[1,0,0] neg_hi:[1,0,0]
	v_pk_mul_f32 v[64:65], v[44:45], s[74:75]
	v_pk_add_f32 v[70:71], v[76:77], v[70:71]
	v_pk_mul_f32 v[76:77], v[58:59], s[78:79]
	v_pk_fma_f32 v[44:45], v[44:45], s[16:17], v[64:65] op_sel:[0,0,1] op_sel_hi:[1,0,0] neg_lo:[1,0,0] neg_hi:[1,0,0]
	v_pk_fma_f32 v[58:59], v[58:59], s[24:25], v[76:77] op_sel:[0,0,1] op_sel_hi:[1,0,0] neg_lo:[1,0,0] neg_hi:[1,0,0]
	v_pk_add_f32 v[64:65], v[48:49], v[44:45]
	v_pk_add_f32 v[56:57], v[56:57], v[58:59]
	v_pk_mul_f32 v[58:59], v[62:63], s[74:75]
	v_pk_add_f32 v[44:45], v[48:49], v[44:45] neg_lo:[0,1] neg_hi:[0,1]
	v_pk_fma_f32 v[58:59], s[16:17], v[62:63], v[58:59] op_sel:[0,0,1] op_sel_hi:[0,1,0] neg_lo:[0,1,0] neg_hi:[0,1,0]
	v_pk_add_f32 v[58:59], v[60:61], v[58:59]
	v_pk_mul_f32 v[60:61], v[42:43], s[62:63]
	v_pk_add_f32 v[54:55], v[94:95], v[72:73] neg_lo:[0,1] neg_hi:[0,1]
	v_pk_add_f32 v[64:65], v[64:65], v[66:67]
	v_pk_add_f32 v[66:67], v[52:53], v[50:51] neg_lo:[0,1] neg_hi:[0,1]
	v_pk_fma_f32 v[42:43], v[42:43], s[8:9], v[60:61] op_sel:[0,0,1] op_sel_hi:[1,0,0] neg_lo:[1,0,0] neg_hi:[1,0,0]
	v_pk_add_f32 v[86:87], v[88:89], v[86:87]
	v_pk_mul_f32 v[88:89], v[92:93], s[24:25]
	v_pk_add_f32 v[48:49], v[54:55], v[66:67] op_sel:[0,1] op_sel_hi:[1,0] neg_lo:[0,1]
	v_pk_mul_f32 v[54:55], v[98:99], s[8:9]
	v_pk_mul_f32 v[66:67], v[82:83], s[16:17]
	v_pk_mul_f32 v[74:75], v[78:79], s[72:73]
	v_pk_add_f32 v[42:43], v[44:45], v[42:43]
	v_pk_add_f32 v[44:45], v[94:95], v[72:73]
	v_pk_add_f32 v[50:51], v[52:53], v[50:51]
	v_pk_fma_f32 v[88:89], v[92:93], s[80:81], v[88:89] op_sel:[0,0,1] op_sel_hi:[1,0,0]
	v_pk_fma_f32 v[54:55], v[98:99], s[82:83], v[54:55] op_sel:[0,0,1] op_sel_hi:[1,0,0] neg_lo:[1,0,0] neg_hi:[1,0,0]
	v_pk_fma_f32 v[66:67], v[82:83], s[76:77], v[66:67] op_sel:[0,0,1] op_sel_hi:[1,0,0] neg_lo:[1,0,0] neg_hi:[1,0,0]
	v_pk_fma_f32 v[74:75], v[78:79], s[0:1], v[74:75] op_sel:[0,0,1] op_sel_hi:[1,0,0] neg_lo:[1,0,0] neg_hi:[1,0,0]
	v_pk_add_f32 v[44:45], v[44:45], v[50:51]
	v_lshl_add_u32 v21, v21, 3, v36
	v_pk_add_f32 v[88:89], v[104:105], v[88:89]
	v_pk_add_f32 v[54:55], v[96:97], v[54:55]
	v_pk_add_f32 v[66:67], v[80:81], v[66:67]
	v_pk_add_f32 v[74:75], v[102:103], v[74:75]
	ds_write_b64 v25, v[44:45]
	ds_write_b64 v25, v[46:47] offset:4224
	ds_write_b64 v25, v[100:101] offset:8448
	ds_write_b64 v25, v[84:85] offset:12672
	ds_write_b64 v25, v[86:87] offset:16896
	ds_write_b64 v25, v[88:89] offset:21120
	ds_write_b64 v25, v[68:69] offset:25344
	ds_write_b64 v25, v[64:65] offset:29568
	ds_write_b64 v25, v[48:49] offset:33792
	ds_write_b64 v25, v[54:55] offset:38016
	ds_write_b64 v25, v[66:67] offset:42240
	ds_write_b64 v25, v[70:71] offset:46464
	ds_write_b64 v25, v[74:75] offset:50688
	ds_write_b64 v25, v[56:57] offset:54912
	ds_write_b64 v25, v[58:59] offset:59136
	ds_write_b64 v25, v[42:43] offset:63360
	v_ashrrev_i32_e32 v25, 5, v21
	v_lshlrev_b32_e32 v21, 3, v21
	v_lshlrev_b32_e32 v25, 3, v25
	s_waitcnt vmcnt(0)
	v_lshlrev_b32_e32 v41, 16, v41
	v_lshlrev_b32_e32 v39, 16, v39
	v_lshlrev_b32_e32 v35, 16, v35
	v_lshlrev_b32_e32 v29, 16, v29
	v_and_b32_e32 v48, 0xffff0000, v14
	v_add3_u32 v21, 0, v21, v25
	v_mov_b32_e32 v40, v48
	s_waitcnt lgkmcnt(0)
	s_barrier
	v_pk_mul_f32 v[44:45], v[30:31], v[40:41]
	ds_read2_b64 v[40:43], v21 offset1:1
	v_lshlrev_b32_e32 v28, 16, v14
	v_lshlrev_b32_e32 v49, 16, v15
	v_pk_fma_f32 v[44:45], v[30:31], v[28:29], v[44:45] op_sel:[0,0,1] op_sel_hi:[1,0,0]
	v_mov_b32_e32 v28, v31
	v_pk_fma_f32 v[44:45], v[20:21], v[48:49], v[44:45] op_sel_hi:[0,1,1]
	v_pk_add_f32 v[50:51], v[24:25], v[44:45] op_sel_hi:[0,1]
	ds_read2_b64 v[44:47], v21 offset0:2 offset1:3
	s_waitcnt lgkmcnt(1)
	v_pk_mul_f32 v[40:41], v[50:51], v[40:41]
	v_and_b32_e32 v51, 16, v16
	v_and_b32_e32 v50, 0xffff0000, v15
	v_pk_mov_b32 v[14:15], v[48:49], v[50:51] op_sel:[1,0]
	v_lshlrev_b32_e32 v53, 16, v16
	v_pk_mul_f32 v[14:15], v[30:31], v[14:15] op_sel_hi:[0,1]
	v_mov_b32_e32 v52, v50
	v_pk_fma_f32 v[14:15], v[28:29], v[48:49], v[14:15] op_sel_hi:[0,1,1]
	v_pk_fma_f32 v[14:15], v[20:21], v[52:53], v[14:15] op_sel_hi:[0,1,1]
	v_pk_add_f32 v[14:15], v[24:25], v[14:15] op_sel_hi:[0,1]
	v_pk_mul_f32 v[14:15], v[14:15], v[42:43]
	v_and_b32_e32 v43, 16, v17
	v_and_b32_e32 v42, 0xffff0000, v16
	v_lshlrev_b32_e32 v49, 16, v17
	v_mov_b32_e32 v48, v42
	v_pk_mov_b32 v[42:43], v[52:53], v[42:43] op_sel:[1,0]
	v_pk_mov_b32 v[16:17], v[16:17], v[10:11] op_sel:[1,0]
	v_pk_mul_f32 v[42:43], v[30:31], v[42:43] op_sel_hi:[0,1]
	v_and_b32_e32 v17, 16, v17
	v_and_b32_e32 v16, 0xffff0000, v16
	v_pk_fma_f32 v[42:43], v[28:29], v[52:53], v[42:43] op_sel_hi:[0,1,1]
	v_mov_b32_e32 v50, v16
	v_pk_mov_b32 v[16:17], v[48:49], v[16:17] op_sel:[1,0]
	v_pk_fma_f32 v[42:43], v[20:21], v[48:49], v[42:43] op_sel_hi:[0,1,1]
	v_pk_mul_f32 v[16:17], v[30:31], v[16:17] op_sel_hi:[0,1]
	v_pk_add_f32 v[42:43], v[24:25], v[42:43] op_sel_hi:[0,1]
	v_lshlrev_b32_e32 v51, 16, v10
	v_pk_fma_f32 v[16:17], v[28:29], v[48:49], v[16:17] op_sel_hi:[0,1,1]
	s_waitcnt lgkmcnt(0)
	v_pk_mul_f32 v[42:43], v[42:43], v[44:45]
	v_pk_fma_f32 v[16:17], v[20:21], v[50:51], v[16:17] op_sel_hi:[0,1,1]
	v_and_b32_e32 v45, 16, v11
	v_and_b32_e32 v44, 0xffff0000, v10
	v_pk_add_f32 v[16:17], v[24:25], v[16:17] op_sel_hi:[0,1]
	v_mov_b32_e32 v52, v44
	v_pk_mov_b32 v[44:45], v[50:51], v[44:45] op_sel:[1,0]
	v_pk_mul_f32 v[16:17], v[16:17], v[46:47]
	v_pk_mul_f32 v[48:49], v[30:31], v[44:45] op_sel_hi:[0,1]
	ds_read2_b64 v[44:47], v21 offset0:4 offset1:5
	v_lshlrev_b32_e32 v53, 16, v11
	v_pk_fma_f32 v[48:49], v[28:29], v[50:51], v[48:49] op_sel_hi:[0,1,1]
	v_pk_fma_f32 v[48:49], v[20:21], v[52:53], v[48:49] op_sel_hi:[0,1,1]
	v_pk_add_f32 v[54:55], v[24:25], v[48:49] op_sel_hi:[0,1]
	ds_read2_b64 v[48:51], v21 offset0:6 offset1:7
	s_waitcnt lgkmcnt(1)
	v_pk_mul_f32 v[44:45], v[54:55], v[44:45]
	v_and_b32_e32 v55, 16, v12
	v_and_b32_e32 v54, 0xffff0000, v11
	v_pk_mov_b32 v[10:11], v[52:53], v[54:55] op_sel:[1,0]
	v_lshlrev_b32_e32 v57, 16, v12
	v_pk_mul_f32 v[10:11], v[30:31], v[10:11] op_sel_hi:[0,1]
	v_mov_b32_e32 v56, v54
	v_pk_fma_f32 v[10:11], v[28:29], v[52:53], v[10:11] op_sel_hi:[0,1,1]
	v_pk_fma_f32 v[10:11], v[20:21], v[56:57], v[10:11] op_sel_hi:[0,1,1]
	v_pk_add_f32 v[10:11], v[24:25], v[10:11] op_sel_hi:[0,1]
	v_and_b32_e32 v38, 0xffff0000, v13
	v_pk_mul_f32 v[10:11], v[10:11], v[46:47]
	v_and_b32_e32 v47, 16, v13
	v_and_b32_e32 v46, 0xffff0000, v12
	v_lshlrev_b32_e32 v53, 16, v13
	v_mov_b32_e32 v52, v46
	v_pk_mov_b32 v[12:13], v[56:57], v[46:47] op_sel:[1,0]
	v_mov_b32_e32 v46, v53
	v_mov_b32_e32 v47, v38
	v_pk_mul_f32 v[12:13], v[30:31], v[12:13] op_sel_hi:[0,1]
	v_pk_mul_f32 v[46:47], v[30:31], v[46:47] op_sel_hi:[0,1]
	v_pk_fma_f32 v[12:13], v[28:29], v[56:57], v[12:13] op_sel_hi:[0,1,1]
	v_pk_fma_f32 v[46:47], v[28:29], v[52:53], v[46:47] op_sel_hi:[0,1,1]
	v_pk_fma_f32 v[12:13], v[20:21], v[52:53], v[12:13] op_sel_hi:[0,1,1]
	v_pk_fma_f32 v[38:39], v[20:21], v[38:39], v[46:47] op_sel_hi:[0,1,1]
	s_xor_b64 s[70:71], s[70:71], -1
	v_pk_add_f32 v[12:13], v[24:25], v[12:13] op_sel_hi:[0,1]
	v_pk_add_f32 v[38:39], v[24:25], v[38:39] op_sel_hi:[0,1]
	s_waitcnt lgkmcnt(0)
	v_pk_mul_f32 v[12:13], v[12:13], v[48:49]
	v_pk_mul_f32 v[38:39], v[38:39], v[50:51]
	s_mov_b64 s[0:1], -1
	s_and_b64 vcc, exec, s[70:71]
	s_cbranch_vccz .LBB0_513
	v_bfe_u32 v46, v15, 16, 1
	v_add3_u32 v47, v15, v46, s4
	v_bfe_u32 v46, v14, 16, 1
	v_bfe_u32 v48, v16, 16, 1
	v_bfe_u32 v50, v42, 16, 1
	v_bfe_u32 v34, v17, 16, 1
	v_bfe_u32 v49, v40, 16, 1
	v_add3_u32 v50, v42, v50, s4
	v_add3_u32 v48, v16, v48, s4
	v_add3_u32 v46, v14, v46, s4
	v_bfe_u32 v25, v43, 16, 1
	v_bfe_u32 v28, v41, 16, 1
	v_add3_u32 v34, v17, v34, s4
	v_add3_u32 v49, v40, v49, s4
	v_lshrrev_b32_e32 v51, 16, v46
	v_lshrrev_b32_e32 v52, 16, v48
	v_lshrrev_b32_e32 v48, 16, v50
	v_bfe_u32 v50, v11, 16, 1
	v_add3_u32 v28, v41, v28, s4
	v_add3_u32 v25, v43, v25, s4
	v_lshrrev_b32_e32 v46, 16, v49
	v_and_or_b32 v49, v34, s91, v52
	v_and_or_b32 v47, v47, s91, v51
	v_add3_u32 v51, v11, v50, s4
	v_bfe_u32 v50, v10, 16, 1
	v_bfe_u32 v52, v38, 16, 1
	v_bfe_u32 v53, v44, 16, 1
	v_bfe_u32 v54, v12, 16, 1
	v_lshl_add_u64 v[36:37], v[36:37], 1, s[50:51]
	v_and_or_b32 v48, v25, s91, v48
	v_and_or_b32 v46, v28, s91, v46
	v_bfe_u32 v25, v13, 16, 1
	v_bfe_u32 v28, v45, 16, 1
	v_bfe_u32 v34, v39, 16, 1
	v_add3_u32 v54, v12, v54, s4
	v_add3_u32 v53, v44, v53, s4
	v_add3_u32 v52, v38, v52, s4
	v_add3_u32 v50, v10, v50, s4
	v_add3_u32 v34, v39, v34, s4
	v_add3_u32 v28, v45, v28, s4
	v_add3_u32 v25, v13, v25, s4
	v_lshrrev_b32_e32 v55, 16, v50
	v_lshrrev_b32_e32 v56, 16, v52
	v_lshrrev_b32_e32 v50, 16, v53
	v_lshrrev_b32_e32 v52, 16, v54
	v_lshl_add_u64 v[32:33], v[32:33], 1, v[36:37]
	v_and_or_b32 v52, v25, s91, v52
	v_and_or_b32 v50, v28, s91, v50
	v_and_or_b32 v53, v34, s91, v56
	v_and_or_b32 v51, v51, s91, v55
	global_store_dwordx4 v[32:33], v[46:49], off
	global_store_dwordx4 v[32:33], v[50:53], off offset:16
	s_mov_b64 s[0:1], 0

.LBB0_534:
	v_mov_b32_e32 v2, v210
	s_mov_b32 s43, s8
	v_and_b32_e32 v3, 0xff, v2
	v_lshlrev_b32_e32 v4, 5, v2
	v_and_or_b32 v3, v4, s33, v3
	v_ashrrev_i32_e32 v4, 5, v3
	v_lshlrev_b32_e32 v3, 3, v3
	v_lshlrev_b32_e32 v4, 3, v4
	v_add3_u32 v18, 0, v3, v4
	ds_read_b64 v[128:129], v18
	ds_read_b64 v[132:133], v18 offset:2112
	ds_read_b64 v[134:135], v18 offset:4224
	ds_read_b64 v[136:137], v18 offset:6336
	ds_read_b64 v[138:139], v18 offset:8448
	ds_read_b64 v[140:141], v18 offset:10560
	ds_read_b64 v[142:143], v18 offset:12672
	ds_read_b64 v[130:131], v18 offset:14784
	ds_read_b64 v[144:145], v18 offset:16896
	ds_read_b64 v[148:149], v18 offset:19008
	ds_read_b64 v[150:151], v18 offset:21120
	ds_read_b64 v[152:153], v18 offset:23232
	s_waitcnt lgkmcnt(10)
	v_pk_mul_f32 v[162:163], v[132:133], s[10:11]
	s_mov_b32 s64, s11
	v_pk_fma_f32 v[162:163], v[132:133], s[8:9], v[162:163] op_sel:[0,0,1] op_sel_hi:[1,0,0]
	s_waitcnt lgkmcnt(2)
	v_pk_mul_f32 v[178:179], v[148:149], s[42:43]
	v_pk_add_f32 v[194:195], v[132:133], v[148:149]
	v_pk_add_f32 v[132:133], v[132:133], v[148:149] neg_lo:[0,1] neg_hi:[0,1]
	v_pk_mul_f32 v[164:165], v[134:135], s[18:19]
	s_mov_b32 s41, s16
	v_pk_fma_f32 v[178:179], v[148:149], s[64:65], v[178:179] op_sel:[0,0,1] op_sel_hi:[1,0,0] neg_lo:[1,0,0] neg_hi:[1,0,0]
	v_pk_mul_f32 v[148:149], v[132:133], s[18:19]
	v_pk_fma_f32 v[164:165], v[134:135], s[16:17], v[164:165] op_sel:[0,0,1] op_sel_hi:[1,0,0]
	s_mov_b32 s68, s19
	s_waitcnt lgkmcnt(1)
	v_pk_mul_f32 v[180:181], v[150:151], s[40:41]
	v_pk_fma_f32 v[132:133], v[132:133], s[16:17], v[148:149] op_sel:[0,0,1] op_sel_hi:[1,0,0]
	v_pk_add_f32 v[148:149], v[134:135], v[150:151]
	v_pk_add_f32 v[134:135], v[134:135], v[150:151] neg_lo:[0,1] neg_hi:[0,1]
	v_pk_mul_f32 v[166:167], v[136:137], s[26:27]
	s_mov_b32 s66, s37
	s_mov_b32 s39, s24
	v_pk_fma_f32 v[180:181], v[150:151], s[68:69], v[180:181] op_sel:[0,0,1] op_sel_hi:[1,0,0] neg_lo:[1,0,0] neg_hi:[1,0,0]
	v_pk_mul_f32 v[150:151], v[134:135], s[36:37]
	ds_read_b64 v[154:155], v18 offset:25344
	ds_read_b64 v[156:157], v18 offset:27456
	ds_read_b64 v[158:159], v18 offset:29568
	ds_read_b64 v[160:161], v18 offset:31680
	v_pk_fma_f32 v[166:167], v[136:137], s[24:25], v[166:167] op_sel:[0,0,1] op_sel_hi:[1,0,0]
	s_mov_b32 s0, s27
	s_waitcnt lgkmcnt(4)
	v_pk_mul_f32 v[182:183], v[152:153], s[38:39]
	v_pk_fma_f32 v[134:135], v[134:135], s[66:67], v[150:151] op_sel:[0,0,1] op_sel_hi:[1,0,0]
	v_pk_add_f32 v[150:151], v[136:137], v[152:153]
	v_pk_add_f32 v[136:137], v[136:137], v[152:153] neg_lo:[0,1] neg_hi:[0,1]
	v_pk_mul_f32 v[168:169], v[138:139], s[36:37]
	v_pk_fma_f32 v[182:183], v[152:153], s[0:1], v[182:183] op_sel:[0,0,1] op_sel_hi:[1,0,0] neg_lo:[1,0,0] neg_hi:[1,0,0]
	v_pk_mul_f32 v[152:153], v[136:137], s[40:41]
	v_pk_fma_f32 v[168:169], v[138:139], s[66:67], v[168:169] op_sel:[0,0,1] op_sel_hi:[1,0,0]
	v_pk_mul_f32 v[170:171], v[140:141], s[38:39]
	s_waitcnt lgkmcnt(3)
	v_pk_mul_f32 v[184:185], v[154:155], s[36:37]
	v_pk_fma_f32 v[136:137], v[136:137], s[68:69], v[152:153] op_sel:[0,0,1] op_sel_hi:[1,0,0]
	v_pk_add_f32 v[152:153], v[138:139], v[154:155]
	v_pk_add_f32 v[138:139], v[138:139], v[154:155] neg_lo:[0,1] neg_hi:[0,1]
	v_pk_fma_f32 v[170:171], v[140:141], s[0:1], v[170:171] op_sel:[0,0,1] op_sel_hi:[1,0,0]
	v_pk_fma_f32 v[184:185], v[154:155], s[66:67], v[184:185] op_sel:[0,0,1] op_sel_hi:[1,0,0] neg_lo:[1,0,0] neg_hi:[1,0,0]
	s_waitcnt lgkmcnt(2)
	v_pk_mul_f32 v[186:187], v[156:157], s[26:27]
	v_xor_b32_e32 v155, 0x80000000, v138
	v_mov_b32_e32 v154, v139
	v_pk_add_f32 v[138:139], v[140:141], v[156:157]
	v_pk_add_f32 v[140:141], v[140:141], v[156:157] neg_lo:[0,1] neg_hi:[0,1]
	v_pk_mul_f32 v[172:173], v[142:143], s[40:41]
	v_pk_fma_f32 v[186:187], v[156:157], s[24:25], v[186:187] op_sel:[0,0,1] op_sel_hi:[1,0,0] neg_lo:[1,0,0] neg_hi:[1,0,0]
	v_pk_mul_f32 v[156:157], v[140:141], s[40:41]
	v_pk_fma_f32 v[172:173], v[142:143], s[68:69], v[172:173] op_sel:[0,0,1] op_sel_hi:[1,0,0]
	s_waitcnt lgkmcnt(1)
	v_pk_mul_f32 v[188:189], v[158:159], s[18:19]
	v_pk_fma_f32 v[140:141], v[140:141], s[68:69], v[156:157] op_sel:[0,0,1] op_sel_hi:[1,0,0] neg_lo:[1,0,0] neg_hi:[1,0,0]
	v_pk_add_f32 v[156:157], v[142:143], v[158:159]
	v_pk_add_f32 v[142:143], v[142:143], v[158:159] neg_lo:[0,1] neg_hi:[0,1]
	v_pk_mul_f32 v[174:175], v[130:131], s[42:43]
	v_pk_fma_f32 v[188:189], v[158:159], s[16:17], v[188:189] op_sel:[0,0,1] op_sel_hi:[1,0,0] neg_lo:[1,0,0] neg_hi:[1,0,0]
	v_pk_mul_f32 v[158:159], v[142:143], s[36:37]
	v_pk_fma_f32 v[174:175], v[130:131], s[64:65], v[174:175] op_sel:[0,0,1] op_sel_hi:[1,0,0]
	s_waitcnt lgkmcnt(0)
	v_pk_mul_f32 v[190:191], v[160:161], s[10:11]
	v_pk_fma_f32 v[142:143], v[142:143], s[66:67], v[158:159] op_sel:[0,0,1] op_sel_hi:[1,0,0] neg_lo:[1,0,0] neg_hi:[1,0,0]
	v_pk_add_f32 v[158:159], v[130:131], v[160:161]
	v_pk_add_f32 v[130:131], v[130:131], v[160:161] neg_lo:[0,1] neg_hi:[0,1]
	v_xor_b32_e32 v177, 0x80000000, v144
	v_mov_b32_e32 v176, v145
	v_pk_fma_f32 v[190:191], v[160:161], s[8:9], v[190:191] op_sel:[0,0,1] op_sel_hi:[1,0,0] neg_lo:[1,0,0] neg_hi:[1,0,0]
	v_pk_mul_f32 v[160:161], v[130:131], s[18:19]
	v_pk_add_f32 v[192:193], v[128:129], v[144:145]
	v_pk_add_f32 v[144:145], v[128:129], v[144:145] neg_lo:[0,1] neg_hi:[0,1]
	v_pk_fma_f32 v[130:131], v[130:131], s[16:17], v[160:161] op_sel:[0,0,1] op_sel_hi:[1,0,0] neg_lo:[1,0,0] neg_hi:[1,0,0]
	v_pk_add_f32 v[160:161], v[128:129], v[176:177]
	v_pk_add_f32 v[128:129], v[128:129], v[176:177] neg_lo:[0,1] neg_hi:[0,1]
	v_pk_add_f32 v[176:177], v[162:163], v[178:179]
	v_pk_add_f32 v[162:163], v[162:163], v[178:179] neg_lo:[0,1] neg_hi:[0,1]
	v_cvt_f32_ubyte0_e32 v2, v2
	v_pk_mul_f32 v[178:179], v[162:163], s[18:19]
	v_mul_f32_e32 v2, 0x39000000, v2
	v_pk_fma_f32 v[162:163], v[162:163], s[16:17], v[178:179] op_sel:[0,0,1] op_sel_hi:[1,0,0]
	v_pk_add_f32 v[178:179], v[164:165], v[180:181]
	v_pk_add_f32 v[164:165], v[164:165], v[180:181] neg_lo:[0,1] neg_hi:[0,1]
	v_sin_f32_e32 v34, v2
	v_pk_mul_f32 v[180:181], v[164:165], s[36:37]
	v_cos_f32_e32 v30, v2
	v_pk_fma_f32 v[164:165], v[164:165], s[66:67], v[180:181] op_sel:[0,0,1] op_sel_hi:[1,0,0]
	v_pk_add_f32 v[180:181], v[166:167], v[182:183]
	v_pk_add_f32 v[166:167], v[166:167], v[182:183] neg_lo:[0,1] neg_hi:[0,1]
	v_xor_b32_e32 v31, 0x80000000, v34
	v_pk_mul_f32 v[182:183], v[166:167], s[40:41]
	v_mov_b32_e32 v35, v31
	v_pk_fma_f32 v[166:167], v[166:167], s[68:69], v[182:183] op_sel:[0,0,1] op_sel_hi:[1,0,0]
	v_pk_add_f32 v[182:183], v[168:169], v[184:185]
	v_pk_add_f32 v[184:185], v[168:169], v[184:185] neg_lo:[0,1] neg_hi:[0,1]
	v_pk_mul_f32 v[2:3], v[30:31], v[34:35] op_sel:[1,0] op_sel_hi:[0,1]
	v_pk_add_f32 v[168:169], v[170:171], v[186:187]
	v_pk_add_f32 v[170:171], v[170:171], v[186:187] neg_lo:[0,1] neg_hi:[0,1]
	v_pk_fma_f32 v[44:45], v[30:31], v[30:31], v[2:3] op_sel_hi:[1,0,1]
	v_pk_mul_f32 v[186:187], v[170:171], s[40:41]
	v_pk_mul_f32 v[2:3], v[34:35], v[44:45] op_sel:[0,1] op_sel_hi:[1,0]
	v_pk_fma_f32 v[170:171], v[170:171], s[68:69], v[186:187] op_sel:[0,0,1] op_sel_hi:[1,0,0] neg_lo:[1,0,0] neg_hi:[1,0,0]
	v_pk_add_f32 v[186:187], v[172:173], v[188:189]
	v_pk_add_f32 v[172:173], v[172:173], v[188:189] neg_lo:[0,1] neg_hi:[0,1]
	v_xor_b32_e32 v54, 0x80000000, v45
	v_pk_mul_f32 v[188:189], v[172:173], s[36:37]
	v_mov_b32_e32 v55, v45
	v_pk_fma_f32 v[172:173], v[172:173], s[66:67], v[188:189] op_sel:[0,0,1] op_sel_hi:[1,0,0] neg_lo:[1,0,0] neg_hi:[1,0,0]
	v_pk_add_f32 v[188:189], v[174:175], v[190:191]
	v_pk_add_f32 v[174:175], v[174:175], v[190:191] neg_lo:[0,1] neg_hi:[0,1]
	v_pk_fma_f32 v[46:47], v[30:31], v[44:45], v[2:3] op_sel_hi:[0,1,1]
	v_pk_mul_f32 v[190:191], v[174:175], s[18:19]
	v_pk_mul_f32 v[2:3], v[44:45], v[54:55] op_sel:[1,0] op_sel_hi:[0,1]
	v_pk_fma_f32 v[174:175], v[174:175], s[16:17], v[190:191] op_sel:[0,0,1] op_sel_hi:[1,0,0] neg_lo:[1,0,0] neg_hi:[1,0,0]
	v_pk_add_f32 v[190:191], v[192:193], v[152:153]
	v_pk_add_f32 v[152:153], v[192:193], v[152:153] neg_lo:[0,1] neg_hi:[0,1]
	v_pk_add_f32 v[192:193], v[194:195], v[138:139]
	v_pk_add_f32 v[138:139], v[194:195], v[138:139] neg_lo:[0,1] neg_hi:[0,1]
	v_pk_fma_f32 v[52:53], v[44:45], v[44:45], v[2:3] op_sel_hi:[1,0,1]
	v_pk_mul_f32 v[194:195], v[138:139], s[36:37]
	v_xor_b32_e32 v58, 0x80000000, v53
	v_pk_fma_f32 v[138:139], v[138:139], s[66:67], v[194:195] op_sel:[0,0,1] op_sel_hi:[1,0,0]
	v_pk_add_f32 v[194:195], v[148:149], v[156:157]
	v_pk_add_f32 v[156:157], v[148:149], v[156:157] neg_lo:[0,1] neg_hi:[0,1]
	v_mov_b32_e32 v59, v53
	v_pk_add_f32 v[148:149], v[150:151], v[158:159]
	v_pk_add_f32 v[150:151], v[150:151], v[158:159] neg_lo:[0,1] neg_hi:[0,1]
	v_pk_mul_f32 v[2:3], v[52:53], v[58:59] op_sel:[1,0] op_sel_hi:[0,1]
	v_pk_mul_f32 v[158:159], v[150:151], s[36:37]
	v_pk_fma_f32 v[48:49], v[52:53], v[52:53], v[2:3] op_sel_hi:[1,0,1]
	v_pk_fma_f32 v[150:151], v[150:151], s[66:67], v[158:159] op_sel:[0,0,1] op_sel_hi:[1,0,0] neg_lo:[1,0,0] neg_hi:[1,0,0]
	v_pk_add_f32 v[158:159], v[144:145], v[154:155]
	v_pk_add_f32 v[144:145], v[144:145], v[154:155] neg_lo:[0,1] neg_hi:[0,1]
	v_pk_add_f32 v[154:155], v[132:133], v[140:141]
	v_pk_add_f32 v[132:133], v[132:133], v[140:141] neg_lo:[0,1] neg_hi:[0,1]
	v_pk_mul_f32 v[2:3], v[58:59], v[48:49] op_sel:[0,1] op_sel_hi:[1,0]
	v_pk_mul_f32 v[140:141], v[132:133], s[36:37]
	v_pk_fma_f32 v[36:37], v[52:53], v[48:49], v[2:3] op_sel_hi:[0,1,1]
	v_pk_fma_f32 v[132:133], v[132:133], s[66:67], v[140:141] op_sel:[0,0,1] op_sel_hi:[1,0,0]
	v_pk_add_f32 v[140:141], v[134:135], v[142:143]
	v_pk_add_f32 v[142:143], v[134:135], v[142:143] neg_lo:[0,1] neg_hi:[0,1]
	v_pk_mul_f32 v[2:3], v[58:59], v[36:37] op_sel:[0,1] op_sel_hi:[1,0]
	v_pk_add_f32 v[134:135], v[136:137], v[130:131]
	v_pk_add_f32 v[130:131], v[136:137], v[130:131] neg_lo:[0,1] neg_hi:[0,1]
	v_pk_fma_f32 v[26:27], v[52:53], v[36:37], v[2:3] op_sel_hi:[0,1,1]
	v_pk_mul_f32 v[136:137], v[130:131], s[36:37]
	v_pk_mul_f32 v[2:3], v[58:59], v[26:27] op_sel:[0,1] op_sel_hi:[1,0]
	v_pk_fma_f32 v[130:131], v[130:131], s[66:67], v[136:137] op_sel:[0,0,1] op_sel_hi:[1,0,0] neg_lo:[1,0,0] neg_hi:[1,0,0]
	v_pk_add_f32 v[136:137], v[160:161], v[182:183]
	v_pk_add_f32 v[160:161], v[160:161], v[182:183] neg_lo:[0,1] neg_hi:[0,1]
	v_pk_add_f32 v[182:183], v[176:177], v[168:169]
	v_pk_add_f32 v[168:169], v[176:177], v[168:169] neg_lo:[0,1] neg_hi:[0,1]
	v_pk_fma_f32 v[20:21], v[52:53], v[26:27], v[2:3] op_sel_hi:[0,1,1]
	v_pk_mul_f32 v[176:177], v[168:169], s[36:37]
	v_pk_mul_f32 v[2:3], v[58:59], v[20:21] op_sel:[0,1] op_sel_hi:[1,0]
	v_pk_fma_f32 v[168:169], v[168:169], s[66:67], v[176:177] op_sel:[0,0,1] op_sel_hi:[1,0,0]
	v_pk_add_f32 v[176:177], v[178:179], v[186:187]
	v_pk_add_f32 v[186:187], v[178:179], v[186:187] neg_lo:[0,1] neg_hi:[0,1]
	v_pk_fma_f32 v[10:11], v[52:53], v[20:21], v[2:3] op_sel_hi:[0,1,1]
	v_pk_add_f32 v[178:179], v[180:181], v[188:189]
	v_pk_add_f32 v[180:181], v[180:181], v[188:189] neg_lo:[0,1] neg_hi:[0,1]
	v_pk_mul_f32 v[2:3], v[58:59], v[10:11] op_sel:[0,1] op_sel_hi:[1,0]
	v_pk_mul_f32 v[188:189], v[180:181], s[36:37]
	v_pk_fma_f32 v[4:5], v[52:53], v[10:11], v[2:3] op_sel_hi:[0,1,1]
	v_pk_fma_f32 v[180:181], v[180:181], s[66:67], v[188:189] op_sel:[0,0,1] op_sel_hi:[1,0,0] neg_lo:[1,0,0] neg_hi:[1,0,0]
	v_pk_add_f32 v[188:189], v[128:129], v[184:185] op_sel:[0,1] op_sel_hi:[1,0] neg_hi:[0,1]
	v_pk_add_f32 v[128:129], v[128:129], v[184:185] op_sel:[0,1] op_sel_hi:[1,0] neg_lo:[0,1]
	v_pk_add_f32 v[184:185], v[162:163], v[170:171]
	v_pk_add_f32 v[162:163], v[162:163], v[170:171] neg_lo:[0,1] neg_hi:[0,1]
	v_xor_b32_e32 v72, 0x80000000, v47
	v_pk_mul_f32 v[170:171], v[162:163], s[36:37]
	v_mov_b32_e32 v73, v47
	v_pk_fma_f32 v[162:163], v[162:163], s[66:67], v[170:171] op_sel:[0,0,1] op_sel_hi:[1,0,0]
	v_pk_add_f32 v[170:171], v[164:165], v[172:173]
	v_pk_add_f32 v[172:173], v[164:165], v[172:173] neg_lo:[0,1] neg_hi:[0,1]
	v_pk_mul_f32 v[2:3], v[72:73], v[4:5] op_sel:[0,1] op_sel_hi:[1,0]
	v_pk_add_f32 v[164:165], v[166:167], v[174:175]
	v_pk_add_f32 v[166:167], v[166:167], v[174:175] neg_lo:[0,1] neg_hi:[0,1]
	v_pk_mul_f32 v[14:15], v[34:35], v[4:5] op_sel:[0,1] op_sel_hi:[1,0]
	v_pk_mul_f32 v[174:175], v[166:167], s[36:37]
	v_pk_mul_f32 v[40:41], v[34:35], v[10:11] op_sel:[0,1] op_sel_hi:[1,0]
	v_pk_fma_f32 v[166:167], v[166:167], s[66:67], v[174:175] op_sel:[0,0,1] op_sel_hi:[1,0,0] neg_lo:[1,0,0] neg_hi:[1,0,0]
	v_pk_add_f32 v[174:175], v[190:191], v[194:195]
	v_pk_add_f32 v[190:191], v[190:191], v[194:195] neg_lo:[0,1] neg_hi:[0,1]
	v_pk_add_f32 v[194:195], v[192:193], v[148:149]
	v_pk_add_f32 v[192:193], v[192:193], v[148:149] neg_lo:[0,1] neg_hi:[0,1]
	v_pk_mul_f32 v[66:67], v[34:35], v[20:21] op_sel:[0,1] op_sel_hi:[1,0]
	v_pk_add_f32 v[148:149], v[152:153], v[156:157] op_sel:[0,1] op_sel_hi:[1,0] neg_hi:[0,1]
	v_pk_add_f32 v[152:153], v[152:153], v[156:157] op_sel:[0,1] op_sel_hi:[1,0] neg_lo:[0,1]
	v_pk_add_f32 v[156:157], v[138:139], v[150:151]
	v_pk_add_f32 v[150:151], v[138:139], v[150:151] neg_lo:[0,1] neg_hi:[0,1]
	v_pk_mul_f32 v[82:83], v[34:35], v[26:27] op_sel:[0,1] op_sel_hi:[1,0]
	v_pk_add_f32 v[138:139], v[158:159], v[140:141]
	v_pk_add_f32 v[140:141], v[158:159], v[140:141] neg_lo:[0,1] neg_hi:[0,1]
	v_pk_add_f32 v[158:159], v[154:155], v[134:135]
	v_pk_add_f32 v[154:155], v[154:155], v[134:135] neg_lo:[0,1] neg_hi:[0,1]
	v_pk_mul_f32 v[96:97], v[34:35], v[36:37] op_sel:[0,1] op_sel_hi:[1,0]
	v_pk_add_f32 v[134:135], v[144:145], v[142:143] op_sel:[0,1] op_sel_hi:[1,0] neg_hi:[0,1]
	v_pk_add_f32 v[142:143], v[144:145], v[142:143] op_sel:[0,1] op_sel_hi:[1,0] neg_lo:[0,1]
	v_pk_add_f32 v[144:145], v[132:133], v[130:131]
	v_pk_add_f32 v[132:133], v[132:133], v[130:131] neg_lo:[0,1] neg_hi:[0,1]
	v_pk_mul_f32 v[110:111], v[34:35], v[48:49] op_sel:[0,1] op_sel_hi:[1,0]
	v_pk_add_f32 v[130:131], v[136:137], v[176:177]
	v_pk_add_f32 v[136:137], v[136:137], v[176:177] neg_lo:[0,1] neg_hi:[0,1]
	v_pk_add_f32 v[176:177], v[182:183], v[178:179]
	v_pk_add_f32 v[182:183], v[182:183], v[178:179] neg_lo:[0,1] neg_hi:[0,1]
	v_pk_mul_f32 v[124:125], v[34:35], v[52:53] op_sel:[0,1] op_sel_hi:[1,0]
	v_pk_add_f32 v[178:179], v[160:161], v[186:187] op_sel:[0,1] op_sel_hi:[1,0] neg_hi:[0,1]
	v_pk_add_f32 v[160:161], v[160:161], v[186:187] op_sel:[0,1] op_sel_hi:[1,0] neg_lo:[0,1]
	v_pk_add_f32 v[186:187], v[168:169], v[180:181]
	v_pk_add_f32 v[180:181], v[168:169], v[180:181] neg_lo:[0,1] neg_hi:[0,1]
	v_pk_fma_f32 v[2:3], v[46:47], v[4:5], v[2:3] op_sel_hi:[0,1,1]
	v_pk_add_f32 v[168:169], v[188:189], v[170:171]
	v_pk_add_f32 v[170:171], v[188:189], v[170:171] neg_lo:[0,1] neg_hi:[0,1]
	v_pk_add_f32 v[188:189], v[184:185], v[164:165]
	v_pk_add_f32 v[184:185], v[184:185], v[164:165] neg_lo:[0,1] neg_hi:[0,1]
	v_pk_mul_f32 v[8:9], v[54:55], v[4:5] op_sel:[0,1] op_sel_hi:[1,0]
	v_pk_add_f32 v[164:165], v[128:129], v[172:173] op_sel:[0,1] op_sel_hi:[1,0] neg_hi:[0,1]
	v_pk_add_f32 v[128:129], v[128:129], v[172:173] op_sel:[0,1] op_sel_hi:[1,0] neg_lo:[0,1]
	v_pk_add_f32 v[172:173], v[162:163], v[166:167]
	v_pk_add_f32 v[166:167], v[162:163], v[166:167] neg_lo:[0,1] neg_hi:[0,1]
	v_pk_fma_f32 v[14:15], v[30:31], v[4:5], v[14:15] op_sel_hi:[0,1,1]
	v_pk_add_f32 v[162:163], v[174:175], v[194:195]
	v_pk_add_f32 v[174:175], v[174:175], v[194:195] neg_lo:[0,1] neg_hi:[0,1]
	v_pk_add_f32 v[194:195], v[190:191], v[192:193] op_sel:[0,1] op_sel_hi:[1,0] neg_hi:[0,1]
	v_pk_add_f32 v[190:191], v[190:191], v[192:193] op_sel:[0,1] op_sel_hi:[1,0] neg_lo:[0,1]
	v_pk_add_f32 v[192:193], v[148:149], v[156:157]
	v_pk_add_f32 v[148:149], v[148:149], v[156:157] neg_lo:[0,1] neg_hi:[0,1]
	v_pk_add_f32 v[156:157], v[152:153], v[150:151] op_sel:[0,1] op_sel_hi:[1,0] neg_hi:[0,1]
	v_pk_add_f32 v[150:151], v[152:153], v[150:151] op_sel:[0,1] op_sel_hi:[1,0] neg_lo:[0,1]
	v_pk_add_f32 v[152:153], v[138:139], v[158:159]
	v_pk_add_f32 v[138:139], v[138:139], v[158:159] neg_lo:[0,1] neg_hi:[0,1]
	v_pk_add_f32 v[158:159], v[140:141], v[154:155] op_sel:[0,1] op_sel_hi:[1,0] neg_hi:[0,1]
	v_pk_add_f32 v[140:141], v[140:141], v[154:155] op_sel:[0,1] op_sel_hi:[1,0] neg_lo:[0,1]
	v_pk_add_f32 v[154:155], v[134:135], v[144:145]
	v_pk_add_f32 v[134:135], v[134:135], v[144:145] neg_lo:[0,1] neg_hi:[0,1]
	v_pk_add_f32 v[144:145], v[142:143], v[132:133] op_sel:[0,1] op_sel_hi:[1,0] neg_hi:[0,1]
	v_pk_add_f32 v[132:133], v[142:143], v[132:133] op_sel:[0,1] op_sel_hi:[1,0] neg_lo:[0,1]
	v_pk_add_f32 v[142:143], v[130:131], v[176:177]
	v_pk_mul_f32 v[24:25], v[72:73], v[10:11] op_sel:[0,1] op_sel_hi:[1,0]
	v_pk_mul_f32 v[34:35], v[34:35], v[142:143] op_sel:[0,1] op_sel_hi:[1,0]
	v_pk_mul_f32 v[32:33], v[54:55], v[10:11] op_sel:[0,1] op_sel_hi:[1,0]
	v_pk_fma_f32 v[40:41], v[30:31], v[10:11], v[40:41] op_sel_hi:[0,1,1]
	v_pk_mul_f32 v[56:57], v[72:73], v[20:21] op_sel:[0,1] op_sel_hi:[1,0]
	v_pk_mul_f32 v[62:63], v[54:55], v[20:21] op_sel:[0,1] op_sel_hi:[1,0]
	v_pk_fma_f32 v[66:67], v[30:31], v[20:21], v[66:67] op_sel_hi:[0,1,1]
	v_pk_mul_f32 v[74:75], v[72:73], v[26:27] op_sel:[0,1] op_sel_hi:[1,0]
	v_pk_mul_f32 v[78:79], v[54:55], v[26:27] op_sel:[0,1] op_sel_hi:[1,0]
	v_pk_fma_f32 v[82:83], v[30:31], v[26:27], v[82:83] op_sel_hi:[0,1,1]
	v_pk_mul_f32 v[88:89], v[72:73], v[36:37] op_sel:[0,1] op_sel_hi:[1,0]
	v_pk_mul_f32 v[92:93], v[54:55], v[36:37] op_sel:[0,1] op_sel_hi:[1,0]
	v_pk_fma_f32 v[96:97], v[30:31], v[36:37], v[96:97] op_sel_hi:[0,1,1]
	v_pk_mul_f32 v[102:103], v[72:73], v[48:49] op_sel:[0,1] op_sel_hi:[1,0]
	v_pk_mul_f32 v[106:107], v[54:55], v[48:49] op_sel:[0,1] op_sel_hi:[1,0]
	v_pk_fma_f32 v[110:111], v[30:31], v[48:49], v[110:111] op_sel_hi:[0,1,1]
	v_pk_mul_f32 v[116:117], v[52:53], v[72:73] op_sel:[1,0] op_sel_hi:[0,1]
	v_pk_mul_f32 v[120:121], v[54:55], v[52:53] op_sel:[0,1] op_sel_hi:[1,0]
	v_pk_fma_f32 v[124:125], v[30:31], v[52:53], v[124:125] op_sel_hi:[0,1,1]
	v_pk_add_f32 v[130:131], v[130:131], v[176:177] neg_lo:[0,1] neg_hi:[0,1]
	v_pk_add_f32 v[176:177], v[136:137], v[182:183] op_sel:[0,1] op_sel_hi:[1,0] neg_hi:[0,1]
	v_pk_add_f32 v[136:137], v[136:137], v[182:183] op_sel:[0,1] op_sel_hi:[1,0] neg_lo:[0,1]
	v_pk_add_f32 v[182:183], v[178:179], v[186:187]
	v_pk_add_f32 v[178:179], v[178:179], v[186:187] neg_lo:[0,1] neg_hi:[0,1]
	v_pk_add_f32 v[186:187], v[160:161], v[180:181] op_sel:[0,1] op_sel_hi:[1,0] neg_hi:[0,1]
	v_pk_add_f32 v[160:161], v[160:161], v[180:181] op_sel:[0,1] op_sel_hi:[1,0] neg_lo:[0,1]
	v_pk_add_f32 v[180:181], v[168:169], v[188:189]
	v_pk_fma_f32 v[30:31], v[30:31], v[142:143], v[34:35] op_sel_hi:[0,1,1]
	v_pk_mul_f32 v[34:35], v[54:55], v[152:153] op_sel:[0,1] op_sel_hi:[1,0]
	v_xor_b32_e32 v6, 0x80000000, v3
	v_pk_fma_f32 v[8:9], v[44:45], v[4:5], v[8:9] op_sel_hi:[0,1,1]
	v_pk_fma_f32 v[24:25], v[46:47], v[10:11], v[24:25] op_sel_hi:[0,1,1]
	v_pk_fma_f32 v[32:33], v[44:45], v[10:11], v[32:33] op_sel_hi:[0,1,1]
	v_pk_fma_f32 v[56:57], v[46:47], v[20:21], v[56:57] op_sel_hi:[0,1,1]
	v_pk_fma_f32 v[62:63], v[44:45], v[20:21], v[62:63] op_sel_hi:[0,1,1]
	v_pk_fma_f32 v[74:75], v[46:47], v[26:27], v[74:75] op_sel_hi:[0,1,1]
	v_pk_fma_f32 v[78:79], v[44:45], v[26:27], v[78:79] op_sel_hi:[0,1,1]
	v_pk_fma_f32 v[88:89], v[46:47], v[36:37], v[88:89] op_sel_hi:[0,1,1]
	v_pk_fma_f32 v[92:93], v[44:45], v[36:37], v[92:93] op_sel_hi:[0,1,1]
	v_pk_fma_f32 v[102:103], v[46:47], v[48:49], v[102:103] op_sel_hi:[0,1,1]
	v_pk_fma_f32 v[106:107], v[44:45], v[48:49], v[106:107] op_sel_hi:[0,1,1]
	v_xor_b32_e32 v114, 0x80000000, v49
	v_pk_fma_f32 v[116:117], v[52:53], v[46:47], v[116:117] op_sel_hi:[1,0,1]
	v_pk_fma_f32 v[120:121], v[44:45], v[52:53], v[120:121] op_sel_hi:[0,1,1]
	v_mov_b32_e32 v115, v49
	v_mov_b32_e32 v7, v3
	v_pk_add_f32 v[168:169], v[168:169], v[188:189] neg_lo:[0,1] neg_hi:[0,1]
	v_pk_add_f32 v[188:189], v[170:171], v[184:185] op_sel:[0,1] op_sel_hi:[1,0] neg_hi:[0,1]
	v_pk_add_f32 v[170:171], v[170:171], v[184:185] op_sel:[0,1] op_sel_hi:[1,0] neg_lo:[0,1]
	v_pk_add_f32 v[184:185], v[164:165], v[172:173]
	v_pk_add_f32 v[164:165], v[164:165], v[172:173] neg_lo:[0,1] neg_hi:[0,1]
	v_pk_add_f32 v[172:173], v[128:129], v[166:167] op_sel:[0,1] op_sel_hi:[1,0] neg_hi:[0,1]
	v_pk_add_f32 v[128:129], v[128:129], v[166:167] op_sel:[0,1] op_sel_hi:[1,0] neg_lo:[0,1]
	v_pk_fma_f32 v[34:35], v[44:45], v[152:153], v[34:35] op_sel_hi:[0,1,1]
	v_pk_mul_f32 v[44:45], v[72:73], v[180:181] op_sel:[0,1] op_sel_hi:[1,0]
	v_xor_b32_e32 v12, 0x80000000, v9
	v_xor_b32_e32 v16, 0x80000000, v15
	v_xor_b32_e32 v22, 0x80000000, v5
	v_xor_b32_e32 v28, 0x80000000, v25
	v_xor_b32_e32 v38, 0x80000000, v33
	v_xor_b32_e32 v42, 0x80000000, v41
	v_xor_b32_e32 v50, 0x80000000, v11
	v_xor_b32_e32 v60, 0x80000000, v57
	v_xor_b32_e32 v64, 0x80000000, v63
	v_xor_b32_e32 v68, 0x80000000, v67
	v_xor_b32_e32 v70, 0x80000000, v21
	v_xor_b32_e32 v76, 0x80000000, v75
	v_xor_b32_e32 v80, 0x80000000, v79
	v_xor_b32_e32 v84, 0x80000000, v83
	v_xor_b32_e32 v86, 0x80000000, v27
	v_xor_b32_e32 v90, 0x80000000, v89
	v_xor_b32_e32 v94, 0x80000000, v93
	v_xor_b32_e32 v98, 0x80000000, v97
	v_xor_b32_e32 v100, 0x80000000, v37
	v_xor_b32_e32 v104, 0x80000000, v103
	v_xor_b32_e32 v108, 0x80000000, v107
	v_xor_b32_e32 v112, 0x80000000, v111
	v_xor_b32_e32 v118, 0x80000000, v117
	v_xor_b32_e32 v122, 0x80000000, v121
	v_xor_b32_e32 v126, 0x80000000, v125
	v_mov_b32_e32 v127, v125
	v_mov_b32_e32 v123, v121
	v_mov_b32_e32 v119, v117
	v_mov_b32_e32 v113, v111
	v_mov_b32_e32 v109, v107
	v_mov_b32_e32 v105, v103
	v_mov_b32_e32 v101, v37
	v_mov_b32_e32 v99, v97
	v_mov_b32_e32 v95, v93
	v_mov_b32_e32 v91, v89
	v_mov_b32_e32 v87, v27
	v_mov_b32_e32 v85, v83
	v_mov_b32_e32 v81, v79
	v_mov_b32_e32 v77, v75
	v_mov_b32_e32 v71, v21
	v_mov_b32_e32 v69, v67
	v_mov_b32_e32 v65, v63
	v_mov_b32_e32 v61, v57
	v_mov_b32_e32 v51, v11
	v_mov_b32_e32 v43, v41
	v_mov_b32_e32 v39, v33
	v_mov_b32_e32 v29, v25
	v_mov_b32_e32 v23, v5
	v_mov_b32_e32 v17, v15
	v_mov_b32_e32 v13, v9
	v_pk_fma_f32 v[44:45], v[46:47], v[180:181], v[44:45] op_sel_hi:[0,1,1]
	v_pk_mul_f32 v[46:47], v[58:59], v[192:193] op_sel:[0,1] op_sel_hi:[1,0]
	v_pk_mul_f32 v[72:73], v[114:115], v[194:195] op_sel:[0,1] op_sel_hi:[1,0]
	v_pk_mul_f32 v[6:7], v[128:129], v[6:7] op_sel:[1,0] op_sel_hi:[0,1]
	v_pk_fma_f32 v[46:47], v[52:53], v[192:193], v[46:47] op_sel_hi:[0,1,1]
	v_pk_mul_f32 v[52:53], v[126:127], v[182:183] op_sel:[0,1] op_sel_hi:[1,0]
	v_pk_mul_f32 v[54:55], v[122:123], v[154:155] op_sel:[0,1] op_sel_hi:[1,0]
	v_pk_mul_f32 v[58:59], v[118:119], v[184:185] op_sel:[0,1] op_sel_hi:[1,0]
	v_pk_fma_f32 v[48:49], v[48:49], v[194:195], v[72:73] op_sel_hi:[0,1,1]
	v_pk_mul_f32 v[72:73], v[112:113], v[176:177] op_sel:[0,1] op_sel_hi:[1,0]
	v_pk_mul_f32 v[108:109], v[108:109], v[158:159] op_sel:[0,1] op_sel_hi:[1,0]
	v_pk_mul_f32 v[104:105], v[104:105], v[188:189] op_sel:[0,1] op_sel_hi:[1,0]
	v_pk_mul_f32 v[100:101], v[100:101], v[156:157] op_sel:[0,1] op_sel_hi:[1,0]
	v_pk_mul_f32 v[98:99], v[98:99], v[186:187] op_sel:[0,1] op_sel_hi:[1,0]
	v_pk_mul_f32 v[94:95], v[94:95], v[144:145] op_sel:[0,1] op_sel_hi:[1,0]
	v_pk_mul_f32 v[90:91], v[90:91], v[172:173] op_sel:[0,1] op_sel_hi:[1,0]
	v_pk_mul_f32 v[86:87], v[174:175], v[86:87] op_sel:[1,0] op_sel_hi:[0,1]
	v_pk_mul_f32 v[84:85], v[130:131], v[84:85] op_sel:[1,0] op_sel_hi:[0,1]
	v_pk_mul_f32 v[80:81], v[138:139], v[80:81] op_sel:[1,0] op_sel_hi:[0,1]
	v_pk_mul_f32 v[76:77], v[168:169], v[76:77] op_sel:[1,0] op_sel_hi:[0,1]
	v_pk_mul_f32 v[70:71], v[148:149], v[70:71] op_sel:[1,0] op_sel_hi:[0,1]
	v_pk_mul_f32 v[68:69], v[178:179], v[68:69] op_sel:[1,0] op_sel_hi:[0,1]
	v_pk_mul_f32 v[64:65], v[134:135], v[64:65] op_sel:[1,0] op_sel_hi:[0,1]
	v_pk_mul_f32 v[60:61], v[164:165], v[60:61] op_sel:[1,0] op_sel_hi:[0,1]
	v_pk_mul_f32 v[50:51], v[190:191], v[50:51] op_sel:[1,0] op_sel_hi:[0,1]
	v_pk_mul_f32 v[42:43], v[136:137], v[42:43] op_sel:[1,0] op_sel_hi:[0,1]
	v_pk_mul_f32 v[38:39], v[140:141], v[38:39] op_sel:[1,0] op_sel_hi:[0,1]
	v_pk_mul_f32 v[28:29], v[170:171], v[28:29] op_sel:[1,0] op_sel_hi:[0,1]
	v_pk_mul_f32 v[22:23], v[150:151], v[22:23] op_sel:[1,0] op_sel_hi:[0,1]
	v_pk_mul_f32 v[16:17], v[160:161], v[16:17] op_sel:[1,0] op_sel_hi:[0,1]
	v_pk_mul_f32 v[12:13], v[132:133], v[12:13] op_sel:[1,0] op_sel_hi:[0,1]
	v_pk_fma_f32 v[2:3], v[128:129], v[2:3], v[6:7] op_sel_hi:[1,0,1]
	v_pk_fma_f32 v[52:53], v[124:125], v[182:183], v[52:53] op_sel_hi:[0,1,1]
	v_pk_fma_f32 v[54:55], v[120:121], v[154:155], v[54:55] op_sel_hi:[0,1,1]
	v_pk_fma_f32 v[58:59], v[116:117], v[184:185], v[58:59] op_sel_hi:[0,1,1]
	v_pk_fma_f32 v[72:73], v[110:111], v[176:177], v[72:73] op_sel_hi:[0,1,1]
	v_pk_fma_f32 v[106:107], v[106:107], v[158:159], v[108:109] op_sel_hi:[0,1,1]
	v_pk_fma_f32 v[102:103], v[102:103], v[188:189], v[104:105] op_sel_hi:[0,1,1]
	v_pk_fma_f32 v[36:37], v[36:37], v[156:157], v[100:101] op_sel_hi:[0,1,1]
	v_pk_fma_f32 v[96:97], v[96:97], v[186:187], v[98:99] op_sel_hi:[0,1,1]
	v_pk_fma_f32 v[92:93], v[92:93], v[144:145], v[94:95] op_sel_hi:[0,1,1]
	v_pk_fma_f32 v[88:89], v[88:89], v[172:173], v[90:91] op_sel_hi:[0,1,1]
	v_pk_fma_f32 v[26:27], v[174:175], v[26:27], v[86:87] op_sel_hi:[1,0,1]
	v_pk_fma_f32 v[82:83], v[130:131], v[82:83], v[84:85] op_sel_hi:[1,0,1]
	v_pk_fma_f32 v[78:79], v[138:139], v[78:79], v[80:81] op_sel_hi:[1,0,1]
	v_pk_fma_f32 v[74:75], v[168:169], v[74:75], v[76:77] op_sel_hi:[1,0,1]
	v_pk_fma_f32 v[20:21], v[148:149], v[20:21], v[70:71] op_sel_hi:[1,0,1]
	v_pk_fma_f32 v[66:67], v[178:179], v[66:67], v[68:69] op_sel_hi:[1,0,1]
	v_pk_fma_f32 v[62:63], v[134:135], v[62:63], v[64:65] op_sel_hi:[1,0,1]
	v_pk_fma_f32 v[56:57], v[164:165], v[56:57], v[60:61] op_sel_hi:[1,0,1]
	v_pk_fma_f32 v[10:11], v[190:191], v[10:11], v[50:51] op_sel_hi:[1,0,1]
	v_pk_fma_f32 v[40:41], v[136:137], v[40:41], v[42:43] op_sel_hi:[1,0,1]
	v_pk_fma_f32 v[32:33], v[140:141], v[32:33], v[38:39] op_sel_hi:[1,0,1]
	v_pk_fma_f32 v[24:25], v[170:171], v[24:25], v[28:29] op_sel_hi:[1,0,1]
	v_pk_fma_f32 v[4:5], v[150:151], v[4:5], v[22:23] op_sel_hi:[1,0,1]
	v_pk_fma_f32 v[14:15], v[160:161], v[14:15], v[16:17] op_sel_hi:[1,0,1]
	v_pk_fma_f32 v[8:9], v[132:133], v[8:9], v[12:13] op_sel_hi:[1,0,1]
	ds_write_b64 v18, v[162:163]
	ds_write_b64 v18, v[26:27] offset:2112
	ds_write_b64 v18, v[48:49] offset:4224
	ds_write_b64 v18, v[10:11] offset:6336
	ds_write_b64 v18, v[46:47] offset:8448
	ds_write_b64 v18, v[20:21] offset:10560
	ds_write_b64 v18, v[36:37] offset:12672
	ds_write_b64 v18, v[4:5] offset:14784
	ds_write_b64 v18, v[34:35] offset:16896
	ds_write_b64 v18, v[78:79] offset:19008
	ds_write_b64 v18, v[106:107] offset:21120
	ds_write_b64 v18, v[32:33] offset:23232
	ds_write_b64 v18, v[54:55] offset:25344
	ds_write_b64 v18, v[62:63] offset:27456
	ds_write_b64 v18, v[92:93] offset:29568
	ds_write_b64 v18, v[8:9] offset:31680
	ds_write_b64 v18, v[30:31] offset:33792
	ds_write_b64 v18, v[82:83] offset:35904
	ds_write_b64 v18, v[72:73] offset:38016
	ds_write_b64 v18, v[40:41] offset:40128
	ds_write_b64 v18, v[52:53] offset:42240
	ds_write_b64 v18, v[66:67] offset:44352
	ds_write_b64 v18, v[96:97] offset:46464
	ds_write_b64 v18, v[14:15] offset:48576
	ds_write_b64 v18, v[44:45] offset:50688
	ds_write_b64 v18, v[74:75] offset:52800
	ds_write_b64 v18, v[102:103] offset:54912
	ds_write_b64 v18, v[24:25] offset:57024
	ds_write_b64 v18, v[58:59] offset:59136
	ds_write_b64 v18, v[56:57] offset:61248
	ds_write_b64 v18, v[88:89] offset:63360
	ds_write_b64 v18, v[2:3] offset:65472
	v_mov_b32_e32 v3, v210
	s_waitcnt lgkmcnt(0)
	s_barrier
	s_add_i32 s64, s62, s48
	v_and_b32_e32 v5, 15, v3
	v_cvt_f32_ubyte0_e32 v2, v5
	v_mul_f32_e32 v4, 0x3b800000, v2
	v_sin_f32_e32 v2, v4
	v_cos_f32_e32 v4, v4
	v_lshlrev_b32_e32 v64, 3, v5
	v_lshlrev_b32_e32 v18, 4, v3
	v_xor_b32_e32 v5, 0x80000000, v2
	v_mov_b32_e32 v3, v5
	v_pk_mul_f32 v[6:7], v[4:5], v[2:3] op_sel:[1,0] op_sel_hi:[0,1]
	v_pk_fma_f32 v[6:7], v[4:5], v[4:5], v[6:7] op_sel_hi:[1,0,1]
	s_ashr_i32 s65, s64, 31
	v_xor_b32_e32 v12, 0x80000000, v7
	v_mov_b32_e32 v13, v7
	v_pk_mul_f32 v[10:11], v[6:7], v[12:13] op_sel:[1,0] op_sel_hi:[0,1]
	v_pk_fma_f32 v[10:11], v[6:7], v[6:7], v[10:11] op_sel_hi:[1,0,1]
	v_pk_mul_f32 v[8:9], v[2:3], v[6:7] op_sel:[0,1] op_sel_hi:[1,0]
	v_xor_b32_e32 v14, 0x80000000, v11
	v_mov_b32_e32 v15, v11
	v_pk_mul_f32 v[32:33], v[10:11], v[14:15] op_sel:[1,0] op_sel_hi:[0,1]
	v_pk_fma_f32 v[32:33], v[10:11], v[10:11], v[32:33] op_sel_hi:[1,0,1]
	v_pk_mul_f32 v[16:17], v[2:3], v[10:11] op_sel:[0,1] op_sel_hi:[1,0]
	v_pk_mul_f32 v[48:49], v[14:15], v[32:33] op_sel:[0,1] op_sel_hi:[1,0]
	v_pk_mul_f32 v[36:37], v[2:3], v[32:33] op_sel:[0,1] op_sel_hi:[1,0]
	v_pk_fma_f32 v[48:49], v[10:11], v[32:33], v[48:49] op_sel_hi:[0,1,1]
	v_pk_mul_f32 v[52:53], v[2:3], v[48:49] op_sel:[0,1] op_sel_hi:[1,0]
	v_pk_fma_f32 v[8:9], v[4:5], v[6:7], v[8:9] op_sel_hi:[0,1,1]
	v_pk_fma_f32 v[16:17], v[4:5], v[10:11], v[16:17] op_sel_hi:[0,1,1]
	v_pk_fma_f32 v[36:37], v[4:5], v[32:33], v[36:37] op_sel_hi:[0,1,1]
	v_pk_fma_f32 v[52:53], v[4:5], v[48:49], v[52:53] op_sel_hi:[0,1,1]
	v_and_b32_e32 v5, 0xffffff00, v18
	v_lshlrev_b32_e32 v18, 3, v5
	v_add3_u32 v18, 0, v64, v18
	v_ashrrev_i32_e32 v64, 2, v5
	v_add_u32_e32 v106, v18, v64
	ds_read2_b64 v[64:67], v106 offset1:16
	ds_read2_b64 v[68:71], v106 offset0:33 offset1:49
	ds_read2_b64 v[72:75], v106 offset0:66 offset1:82
	ds_read2_b64 v[76:79], v106 offset0:132 offset1:148
	ds_read2_b64 v[80:83], v106 offset0:99 offset1:115
	ds_read2_b64 v[84:87], v106 offset0:165 offset1:181
	ds_read2_b64 v[88:91], v106 offset0:198 offset1:214
	ds_read2_b64 v[92:95], v106 offset0:231 offset1:247
	s_waitcnt lgkmcnt(4)
	v_pk_add_f32 v[96:97], v[64:65], v[76:77]
	v_pk_add_f32 v[64:65], v[64:65], v[76:77] neg_lo:[0,1] neg_hi:[0,1]
	v_pk_add_f32 v[76:77], v[66:67], v[78:79]
	v_pk_add_f32 v[66:67], v[66:67], v[78:79] neg_lo:[0,1] neg_hi:[0,1]
	s_waitcnt lgkmcnt(1)
	v_pk_add_f32 v[98:99], v[74:75], v[90:91]
	v_pk_mul_f32 v[78:79], v[66:67], s[18:19]
	v_pk_add_f32 v[74:75], v[74:75], v[90:91] neg_lo:[0,1] neg_hi:[0,1]
	v_pk_fma_f32 v[66:67], v[66:67], s[16:17], v[78:79] op_sel:[0,0,1] op_sel_hi:[1,0,0]
	v_pk_add_f32 v[78:79], v[68:69], v[84:85]
	v_pk_add_f32 v[68:69], v[68:69], v[84:85] neg_lo:[0,1] neg_hi:[0,1]
	v_pk_mul_f32 v[90:91], v[74:75], s[40:41]
	v_pk_mul_f32 v[84:85], v[68:69], s[36:37]
	v_pk_fma_f32 v[74:75], v[74:75], s[68:69], v[90:91] op_sel:[0,0,1] op_sel_hi:[1,0,0] neg_lo:[1,0,0] neg_hi:[1,0,0]
	v_pk_fma_f32 v[68:69], v[68:69], s[66:67], v[84:85] op_sel:[0,0,1] op_sel_hi:[1,0,0]
	v_pk_add_f32 v[84:85], v[70:71], v[86:87]
	v_pk_add_f32 v[70:71], v[70:71], v[86:87] neg_lo:[0,1] neg_hi:[0,1]
	s_waitcnt lgkmcnt(0)
	v_pk_add_f32 v[90:91], v[80:81], v[92:93]
	v_pk_add_f32 v[80:81], v[80:81], v[92:93] neg_lo:[0,1] neg_hi:[0,1]
	v_pk_mul_f32 v[86:87], v[70:71], s[40:41]
	v_pk_mul_f32 v[92:93], v[80:81], s[36:37]
	v_pk_fma_f32 v[70:71], v[70:71], s[68:69], v[86:87] op_sel:[0,0,1] op_sel_hi:[1,0,0]
	v_pk_add_f32 v[86:87], v[72:73], v[88:89]
	v_pk_add_f32 v[88:89], v[72:73], v[88:89] neg_lo:[0,1] neg_hi:[0,1]
	v_pk_fma_f32 v[80:81], v[80:81], s[66:67], v[92:93] op_sel:[0,0,1] op_sel_hi:[1,0,0] neg_lo:[1,0,0] neg_hi:[1,0,0]
	v_pk_add_f32 v[92:93], v[82:83], v[94:95]
	v_pk_add_f32 v[82:83], v[82:83], v[94:95] neg_lo:[0,1] neg_hi:[0,1]
	s_nop 0
	v_pk_mul_f32 v[94:95], v[82:83], s[18:19]
	s_nop 0
	v_pk_fma_f32 v[82:83], v[82:83], s[16:17], v[94:95] op_sel:[0,0,1] op_sel_hi:[1,0,0] neg_lo:[1,0,0] neg_hi:[1,0,0]
	v_pk_add_f32 v[94:95], v[96:97], v[86:87]
	v_pk_add_f32 v[86:87], v[96:97], v[86:87] neg_lo:[0,1] neg_hi:[0,1]
	v_pk_add_f32 v[96:97], v[76:77], v[98:99]
	v_pk_add_f32 v[76:77], v[76:77], v[98:99] neg_lo:[0,1] neg_hi:[0,1]
	v_pk_add_f32 v[100:101], v[84:85], v[92:93]
	v_pk_add_f32 v[84:85], v[84:85], v[92:93] neg_lo:[0,1] neg_hi:[0,1]
	v_pk_add_f32 v[72:73], v[64:65], v[88:89] op_sel:[0,1] op_sel_hi:[1,0] neg_hi:[0,1]
	v_pk_add_f32 v[64:65], v[64:65], v[88:89] op_sel:[0,1] op_sel_hi:[1,0] neg_lo:[0,1]
	v_pk_add_f32 v[88:89], v[66:67], v[74:75]
	v_pk_add_f32 v[66:67], v[66:67], v[74:75] neg_lo:[0,1] neg_hi:[0,1]
	v_pk_mul_f32 v[98:99], v[76:77], s[36:37]
	v_pk_mul_f32 v[92:93], v[84:85], s[36:37]
	v_pk_mul_f32 v[74:75], v[66:67], s[36:37]
	v_pk_fma_f32 v[76:77], v[76:77], s[66:67], v[98:99] op_sel:[0,0,1] op_sel_hi:[1,0,0]
	v_pk_add_f32 v[98:99], v[78:79], v[90:91]
	v_pk_add_f32 v[90:91], v[78:79], v[90:91] neg_lo:[0,1] neg_hi:[0,1]
	v_pk_fma_f32 v[84:85], v[84:85], s[66:67], v[92:93] op_sel:[0,0,1] op_sel_hi:[1,0,0] neg_lo:[1,0,0] neg_hi:[1,0,0]
	v_pk_fma_f32 v[66:67], v[66:67], s[66:67], v[74:75] op_sel:[0,0,1] op_sel_hi:[1,0,0]
	v_pk_add_f32 v[74:75], v[68:69], v[80:81]
	v_pk_add_f32 v[92:93], v[70:71], v[82:83]
	v_pk_add_f32 v[70:71], v[70:71], v[82:83] neg_lo:[0,1] neg_hi:[0,1]
	v_pk_add_f32 v[80:81], v[68:69], v[80:81] neg_lo:[0,1] neg_hi:[0,1]
	v_pk_mul_f32 v[82:83], v[70:71], s[36:37]
	v_pk_add_f32 v[102:103], v[72:73], v[74:75]
	v_pk_add_f32 v[72:73], v[72:73], v[74:75] neg_lo:[0,1] neg_hi:[0,1]
	v_pk_add_f32 v[74:75], v[88:89], v[92:93]
	v_pk_add_f32 v[92:93], v[88:89], v[92:93] neg_lo:[0,1] neg_hi:[0,1]
	v_xor_b32_e32 v20, 0x80000000, v9
	v_mov_b32_e32 v21, v9
	v_pk_mul_f32 v[24:25], v[12:13], v[10:11] op_sel:[0,1] op_sel_hi:[1,0]
	v_pk_fma_f32 v[70:71], v[70:71], s[66:67], v[82:83] op_sel:[0,0,1] op_sel_hi:[1,0,0] neg_lo:[1,0,0] neg_hi:[1,0,0]
	v_pk_add_f32 v[78:79], v[86:87], v[90:91] op_sel:[0,1] op_sel_hi:[1,0] neg_hi:[0,1]
	v_pk_add_f32 v[86:87], v[86:87], v[90:91] op_sel:[0,1] op_sel_hi:[1,0] neg_lo:[0,1]
	v_pk_add_f32 v[90:91], v[76:77], v[84:85]
	v_pk_add_f32 v[84:85], v[76:77], v[84:85] neg_lo:[0,1] neg_hi:[0,1]
	v_xor_b32_e32 v22, 0x80000000, v17
	v_mov_b32_e32 v23, v17
	v_pk_fma_f32 v[24:25], v[6:7], v[10:11], v[24:25] op_sel_hi:[0,1,1]
	v_pk_mul_f32 v[28:29], v[10:11], v[20:21] op_sel:[1,0] op_sel_hi:[0,1]
	v_pk_add_f32 v[68:69], v[64:65], v[80:81] op_sel:[0,1] op_sel_hi:[1,0] neg_hi:[0,1]
	v_pk_add_f32 v[64:65], v[64:65], v[80:81] op_sel:[0,1] op_sel_hi:[1,0] neg_lo:[0,1]
	v_pk_add_f32 v[80:81], v[66:67], v[70:71]
	v_pk_add_f32 v[70:71], v[66:67], v[70:71] neg_lo:[0,1] neg_hi:[0,1]
	v_pk_add_f32 v[88:89], v[72:73], v[92:93] op_sel:[0,1] op_sel_hi:[1,0] neg_hi:[0,1]
	v_xor_b32_e32 v26, 0x80000000, v25
	v_mov_b32_e32 v27, v25
	v_pk_fma_f32 v[28:29], v[10:11], v[8:9], v[28:29] op_sel_hi:[1,0,1]
	v_pk_add_f32 v[76:77], v[86:87], v[84:85] op_sel:[0,1] op_sel_hi:[1,0] neg_hi:[0,1]
	v_pk_add_f32 v[72:73], v[72:73], v[92:93] op_sel:[0,1] op_sel_hi:[1,0] neg_lo:[0,1]
	v_pk_mul_f32 v[92:93], v[22:23], v[88:89] op_sel:[0,1] op_sel_hi:[1,0]
	v_xor_b32_e32 v30, 0x80000000, v29
	v_mov_b32_e32 v31, v29
	v_pk_add_f32 v[82:83], v[94:95], v[98:99]
	v_pk_add_f32 v[94:95], v[94:95], v[98:99] neg_lo:[0,1] neg_hi:[0,1]
	v_pk_add_f32 v[98:99], v[96:97], v[100:101]
	v_pk_add_f32 v[66:67], v[64:65], v[70:71] op_sel:[0,1] op_sel_hi:[1,0] neg_hi:[0,1]
	v_pk_fma_f32 v[88:89], v[16:17], v[88:89], v[92:93] op_sel_hi:[0,1,1]
	v_pk_mul_f32 v[92:93], v[26:27], v[76:77] op_sel:[0,1] op_sel_hi:[1,0]
	v_xor_b32_e32 v34, 0x80000000, v33
	v_mov_b32_e32 v35, v33
	v_pk_mul_f32 v[40:41], v[12:13], v[32:33] op_sel:[0,1] op_sel_hi:[1,0]
	v_pk_add_f32 v[104:105], v[82:83], v[98:99]
	v_pk_add_f32 v[82:83], v[82:83], v[98:99] neg_lo:[0,1] neg_hi:[0,1]
	v_pk_fma_f32 v[76:77], v[24:25], v[76:77], v[92:93] op_sel_hi:[0,1,1]
	v_pk_mul_f32 v[92:93], v[30:31], v[66:67] op_sel:[0,1] op_sel_hi:[1,0]
	v_xor_b32_e32 v38, 0x80000000, v37
	v_mov_b32_e32 v39, v37
	v_pk_fma_f32 v[40:41], v[6:7], v[32:33], v[40:41] op_sel_hi:[0,1,1]
	v_pk_mul_f32 v[44:45], v[20:21], v[32:33] op_sel:[0,1] op_sel_hi:[1,0]
	v_pk_add_f32 v[84:85], v[86:87], v[84:85] op_sel:[0,1] op_sel_hi:[1,0] neg_lo:[0,1]
	v_pk_add_f32 v[86:87], v[102:103], v[74:75]
	v_pk_add_f32 v[74:75], v[102:103], v[74:75] neg_lo:[0,1] neg_hi:[0,1]
	v_pk_fma_f32 v[66:67], v[28:29], v[66:67], v[92:93] op_sel_hi:[0,1,1]
	v_pk_mul_f32 v[92:93], v[34:35], v[82:83] op_sel:[0,1] op_sel_hi:[1,0]
	v_xor_b32_e32 v42, 0x80000000, v41
	v_mov_b32_e32 v43, v41
	v_pk_fma_f32 v[44:45], v[8:9], v[32:33], v[44:45] op_sel_hi:[0,1,1]
	v_pk_add_f32 v[100:101], v[96:97], v[100:101] neg_lo:[0,1] neg_hi:[0,1]
	v_pk_add_f32 v[98:99], v[78:79], v[90:91]
	v_pk_add_f32 v[78:79], v[78:79], v[90:91] neg_lo:[0,1] neg_hi:[0,1]
	v_pk_fma_f32 v[82:83], v[32:33], v[82:83], v[92:93] op_sel_hi:[0,1,1]
	v_pk_mul_f32 v[92:93], v[38:39], v[74:75] op_sel:[0,1] op_sel_hi:[1,0]
	v_xor_b32_e32 v46, 0x80000000, v45
	v_mov_b32_e32 v47, v45
	v_pk_add_f32 v[90:91], v[68:69], v[80:81]
	v_pk_add_f32 v[68:69], v[68:69], v[80:81] neg_lo:[0,1] neg_hi:[0,1]
	v_pk_fma_f32 v[74:75], v[36:37], v[74:75], v[92:93] op_sel_hi:[0,1,1]
	v_pk_mul_f32 v[92:93], v[42:43], v[78:79] op_sel:[0,1] op_sel_hi:[1,0]
	v_xor_b32_e32 v50, 0x80000000, v49
	v_mov_b32_e32 v51, v49
	v_pk_mul_f32 v[56:57], v[12:13], v[48:49] op_sel:[0,1] op_sel_hi:[1,0]
	v_pk_add_f32 v[96:97], v[94:95], v[100:101] op_sel:[0,1] op_sel_hi:[1,0] neg_hi:[0,1]
	v_pk_add_f32 v[94:95], v[94:95], v[100:101] op_sel:[0,1] op_sel_hi:[1,0] neg_lo:[0,1]
	v_pk_fma_f32 v[78:79], v[40:41], v[78:79], v[92:93] op_sel_hi:[0,1,1]
	v_pk_mul_f32 v[92:93], v[46:47], v[68:69] op_sel:[0,1] op_sel_hi:[1,0]
	v_xor_b32_e32 v54, 0x80000000, v53
	v_mov_b32_e32 v55, v53
	v_pk_fma_f32 v[56:57], v[6:7], v[48:49], v[56:57] op_sel_hi:[0,1,1]
	v_pk_mul_f32 v[60:61], v[20:21], v[48:49] op_sel:[0,1] op_sel_hi:[1,0]
	v_pk_fma_f32 v[68:69], v[44:45], v[68:69], v[92:93] op_sel_hi:[0,1,1]
	v_pk_mul_f32 v[92:93], v[50:51], v[94:95] op_sel:[0,1] op_sel_hi:[1,0]
	v_xor_b32_e32 v58, 0x80000000, v57
	v_mov_b32_e32 v59, v57
	v_pk_fma_f32 v[60:61], v[8:9], v[48:49], v[60:61] op_sel_hi:[0,1,1]
	v_pk_add_f32 v[64:65], v[64:65], v[70:71] op_sel:[0,1] op_sel_hi:[1,0] neg_lo:[0,1]
	v_pk_mul_f32 v[70:71], v[2:3], v[86:87] op_sel:[0,1] op_sel_hi:[1,0]
	v_pk_fma_f32 v[92:93], v[48:49], v[94:95], v[92:93] op_sel_hi:[0,1,1]
	v_pk_mul_f32 v[94:95], v[54:55], v[72:73] op_sel:[0,1] op_sel_hi:[1,0]
	v_xor_b32_e32 v62, 0x80000000, v61
	v_mov_b32_e32 v63, v61
	v_pk_fma_f32 v[70:71], v[4:5], v[86:87], v[70:71] op_sel_hi:[0,1,1]
	v_pk_mul_f32 v[86:87], v[20:21], v[90:91] op_sel:[0,1] op_sel_hi:[1,0]
	v_pk_fma_f32 v[72:73], v[52:53], v[72:73], v[94:95] op_sel_hi:[0,1,1]
	v_pk_mul_f32 v[94:95], v[58:59], v[84:85] op_sel:[0,1] op_sel_hi:[1,0]
	v_add_u32_e32 v5, 0x2000, v5
	v_pk_mul_f32 v[80:81], v[12:13], v[98:99] op_sel:[0,1] op_sel_hi:[1,0]
	v_pk_fma_f32 v[86:87], v[8:9], v[90:91], v[86:87] op_sel_hi:[0,1,1]
	v_pk_mul_f32 v[90:91], v[14:15], v[96:97] op_sel:[0,1] op_sel_hi:[1,0]
	v_pk_fma_f32 v[84:85], v[56:57], v[84:85], v[94:95] op_sel_hi:[0,1,1]
	v_pk_mul_f32 v[94:95], v[62:63], v[64:65] op_sel:[0,1] op_sel_hi:[1,0]
	v_ashrrev_i32_e32 v5, 2, v5
	v_pk_fma_f32 v[80:81], v[6:7], v[98:99], v[80:81] op_sel_hi:[0,1,1]
	v_pk_fma_f32 v[90:91], v[10:11], v[96:97], v[90:91] op_sel_hi:[0,1,1]
	v_pk_fma_f32 v[64:65], v[60:61], v[64:65], v[94:95] op_sel_hi:[0,1,1]
	ds_write2_b64 v106, v[104:105], v[82:83] offset1:16
	ds_write2_b64 v106, v[90:91], v[92:93] offset0:33 offset1:49
	ds_write2_b64 v106, v[80:81], v[78:79] offset0:66 offset1:82
	ds_write2_b64 v106, v[76:77], v[84:85] offset0:99 offset1:115
	ds_write2_b64 v106, v[70:71], v[74:75] offset0:132 offset1:148
	ds_write2_b64 v106, v[88:89], v[72:73] offset0:165 offset1:181
	ds_write2_b64 v106, v[86:87], v[68:69] offset0:198 offset1:214
	ds_write2_b64 v106, v[66:67], v[64:65] offset0:231 offset1:247
	v_add3_u32 v18, v18, v5, s5
	ds_read2_b64 v[64:67], v18 offset1:16
	ds_read2_b64 v[68:71], v18 offset0:33 offset1:49
	ds_read2_b64 v[72:75], v18 offset0:66 offset1:82
	ds_read2_b64 v[76:79], v18 offset0:132 offset1:148
	ds_read2_b64 v[80:83], v18 offset0:99 offset1:115
	ds_read2_b64 v[84:87], v18 offset0:165 offset1:181
	ds_read2_b64 v[88:91], v18 offset0:198 offset1:214
	ds_read2_b64 v[92:95], v18 offset0:231 offset1:247
	s_waitcnt lgkmcnt(4)
	v_pk_add_f32 v[96:97], v[64:65], v[76:77]
	v_pk_add_f32 v[64:65], v[64:65], v[76:77] neg_lo:[0,1] neg_hi:[0,1]
	v_pk_add_f32 v[76:77], v[66:67], v[78:79]
	v_pk_add_f32 v[66:67], v[66:67], v[78:79] neg_lo:[0,1] neg_hi:[0,1]
	s_waitcnt lgkmcnt(1)
	v_pk_add_f32 v[98:99], v[74:75], v[90:91]
	v_pk_mul_f32 v[78:79], v[66:67], s[18:19]
	v_pk_add_f32 v[74:75], v[74:75], v[90:91] neg_lo:[0,1] neg_hi:[0,1]
	v_pk_fma_f32 v[66:67], v[66:67], s[16:17], v[78:79] op_sel:[0,0,1] op_sel_hi:[1,0,0]
	v_pk_add_f32 v[78:79], v[68:69], v[84:85]
	v_pk_add_f32 v[68:69], v[68:69], v[84:85] neg_lo:[0,1] neg_hi:[0,1]
	v_pk_mul_f32 v[90:91], v[74:75], s[40:41]
	v_pk_mul_f32 v[84:85], v[68:69], s[36:37]
	v_pk_fma_f32 v[74:75], v[74:75], s[68:69], v[90:91] op_sel:[0,0,1] op_sel_hi:[1,0,0] neg_lo:[1,0,0] neg_hi:[1,0,0]
	s_waitcnt lgkmcnt(0)
	v_pk_add_f32 v[90:91], v[80:81], v[92:93]
	v_pk_add_f32 v[80:81], v[80:81], v[92:93] neg_lo:[0,1] neg_hi:[0,1]
	v_pk_fma_f32 v[68:69], v[68:69], s[66:67], v[84:85] op_sel:[0,0,1] op_sel_hi:[1,0,0]
	v_pk_add_f32 v[84:85], v[70:71], v[86:87]
	v_pk_add_f32 v[70:71], v[70:71], v[86:87] neg_lo:[0,1] neg_hi:[0,1]
	v_pk_mul_f32 v[92:93], v[80:81], s[36:37]
	v_pk_mul_f32 v[86:87], v[70:71], s[40:41]
	v_pk_fma_f32 v[80:81], v[80:81], s[66:67], v[92:93] op_sel:[0,0,1] op_sel_hi:[1,0,0] neg_lo:[1,0,0] neg_hi:[1,0,0]
	v_pk_add_f32 v[92:93], v[82:83], v[94:95]
	v_pk_add_f32 v[82:83], v[82:83], v[94:95] neg_lo:[0,1] neg_hi:[0,1]
	v_pk_fma_f32 v[70:71], v[70:71], s[68:69], v[86:87] op_sel:[0,0,1] op_sel_hi:[1,0,0]
	v_pk_add_f32 v[86:87], v[72:73], v[88:89]
	v_pk_mul_f32 v[94:95], v[82:83], s[18:19]
	v_pk_add_f32 v[88:89], v[72:73], v[88:89] neg_lo:[0,1] neg_hi:[0,1]
	v_pk_fma_f32 v[82:83], v[82:83], s[16:17], v[94:95] op_sel:[0,0,1] op_sel_hi:[1,0,0] neg_lo:[1,0,0] neg_hi:[1,0,0]
	v_pk_add_f32 v[94:95], v[96:97], v[86:87]
	v_pk_add_f32 v[86:87], v[96:97], v[86:87] neg_lo:[0,1] neg_hi:[0,1]
	v_pk_add_f32 v[96:97], v[76:77], v[98:99]
	v_pk_add_f32 v[76:77], v[76:77], v[98:99] neg_lo:[0,1] neg_hi:[0,1]
	s_nop 0
	v_pk_mul_f32 v[98:99], v[76:77], s[36:37]
	v_pk_add_f32 v[100:101], v[84:85], v[92:93]
	v_pk_add_f32 v[84:85], v[84:85], v[92:93] neg_lo:[0,1] neg_hi:[0,1]
	v_pk_fma_f32 v[76:77], v[76:77], s[66:67], v[98:99] op_sel:[0,0,1] op_sel_hi:[1,0,0]
	v_pk_add_f32 v[98:99], v[78:79], v[90:91]
	v_pk_add_f32 v[90:91], v[78:79], v[90:91] neg_lo:[0,1] neg_hi:[0,1]
	v_pk_mul_f32 v[92:93], v[84:85], s[36:37]
	v_pk_add_f32 v[72:73], v[64:65], v[88:89] op_sel:[0,1] op_sel_hi:[1,0] neg_hi:[0,1]
	v_pk_add_f32 v[64:65], v[64:65], v[88:89] op_sel:[0,1] op_sel_hi:[1,0] neg_lo:[0,1]
	v_pk_add_f32 v[88:89], v[66:67], v[74:75]
	v_pk_add_f32 v[66:67], v[66:67], v[74:75] neg_lo:[0,1] neg_hi:[0,1]
	v_pk_fma_f32 v[84:85], v[84:85], s[66:67], v[92:93] op_sel:[0,0,1] op_sel_hi:[1,0,0] neg_lo:[1,0,0] neg_hi:[1,0,0]
	v_pk_mul_f32 v[74:75], v[66:67], s[36:37]
	s_nop 0
	v_pk_fma_f32 v[66:67], v[66:67], s[66:67], v[74:75] op_sel:[0,0,1] op_sel_hi:[1,0,0]
	v_pk_add_f32 v[74:75], v[68:69], v[80:81]
	v_pk_add_f32 v[92:93], v[70:71], v[82:83]
	v_pk_add_f32 v[70:71], v[70:71], v[82:83] neg_lo:[0,1] neg_hi:[0,1]
	v_pk_add_f32 v[78:79], v[86:87], v[90:91] op_sel:[0,1] op_sel_hi:[1,0] neg_hi:[0,1]
	v_pk_add_f32 v[86:87], v[86:87], v[90:91] op_sel:[0,1] op_sel_hi:[1,0] neg_lo:[0,1]
	v_pk_add_f32 v[90:91], v[76:77], v[84:85]
	v_pk_add_f32 v[84:85], v[76:77], v[84:85] neg_lo:[0,1] neg_hi:[0,1]
	v_pk_add_f32 v[80:81], v[68:69], v[80:81] neg_lo:[0,1] neg_hi:[0,1]
	v_pk_mul_f32 v[82:83], v[70:71], s[36:37]
	v_pk_add_f32 v[102:103], v[72:73], v[74:75]
	v_pk_add_f32 v[72:73], v[72:73], v[74:75] neg_lo:[0,1] neg_hi:[0,1]
	v_pk_add_f32 v[74:75], v[88:89], v[92:93]
	v_pk_fma_f32 v[70:71], v[70:71], s[66:67], v[82:83] op_sel:[0,0,1] op_sel_hi:[1,0,0] neg_lo:[1,0,0] neg_hi:[1,0,0]
	v_pk_add_f32 v[82:83], v[94:95], v[98:99]
	v_pk_add_f32 v[94:95], v[94:95], v[98:99] neg_lo:[0,1] neg_hi:[0,1]
	v_pk_add_f32 v[98:99], v[96:97], v[100:101]
	v_pk_add_f32 v[76:77], v[86:87], v[84:85] op_sel:[0,1] op_sel_hi:[1,0] neg_hi:[0,1]
	v_pk_add_f32 v[84:85], v[86:87], v[84:85] op_sel:[0,1] op_sel_hi:[1,0] neg_lo:[0,1]
	v_pk_add_f32 v[86:87], v[102:103], v[74:75]
	v_pk_add_f32 v[100:101], v[96:97], v[100:101] neg_lo:[0,1] neg_hi:[0,1]
	v_pk_add_f32 v[68:69], v[64:65], v[80:81] op_sel:[0,1] op_sel_hi:[1,0] neg_hi:[0,1]
	v_pk_add_f32 v[64:65], v[64:65], v[80:81] op_sel:[0,1] op_sel_hi:[1,0] neg_lo:[0,1]
	v_pk_add_f32 v[80:81], v[66:67], v[70:71]
	v_pk_add_f32 v[104:105], v[82:83], v[98:99]
	v_pk_add_f32 v[82:83], v[82:83], v[98:99] neg_lo:[0,1] neg_hi:[0,1]
	v_pk_add_f32 v[98:99], v[78:79], v[90:91]
	v_pk_mul_f32 v[2:3], v[2:3], v[86:87] op_sel:[0,1] op_sel_hi:[1,0]
	v_pk_add_f32 v[92:93], v[88:89], v[92:93] neg_lo:[0,1] neg_hi:[0,1]
	v_pk_add_f32 v[78:79], v[78:79], v[90:91] neg_lo:[0,1] neg_hi:[0,1]
	v_pk_add_f32 v[90:91], v[68:69], v[80:81]
	v_pk_fma_f32 v[2:3], v[4:5], v[86:87], v[2:3] op_sel_hi:[0,1,1]
	v_pk_mul_f32 v[4:5], v[12:13], v[98:99] op_sel:[0,1] op_sel_hi:[1,0]
	v_pk_add_f32 v[70:71], v[66:67], v[70:71] neg_lo:[0,1] neg_hi:[0,1]
	v_pk_add_f32 v[96:97], v[94:95], v[100:101] op_sel:[0,1] op_sel_hi:[1,0] neg_hi:[0,1]
	v_pk_fma_f32 v[4:5], v[6:7], v[98:99], v[4:5] op_sel_hi:[0,1,1]
	v_pk_mul_f32 v[6:7], v[20:21], v[90:91] op_sel:[0,1] op_sel_hi:[1,0]
	v_pk_add_f32 v[88:89], v[72:73], v[92:93] op_sel:[0,1] op_sel_hi:[1,0] neg_hi:[0,1]
	v_pk_fma_f32 v[6:7], v[8:9], v[90:91], v[6:7] op_sel_hi:[0,1,1]
	v_pk_mul_f32 v[8:9], v[14:15], v[96:97] op_sel:[0,1] op_sel_hi:[1,0]
	v_pk_add_f32 v[66:67], v[64:65], v[70:71] op_sel:[0,1] op_sel_hi:[1,0] neg_hi:[0,1]
	v_pk_fma_f32 v[8:9], v[10:11], v[96:97], v[8:9] op_sel_hi:[0,1,1]
	v_pk_mul_f32 v[10:11], v[22:23], v[88:89] op_sel:[0,1] op_sel_hi:[1,0]
	v_pk_add_f32 v[94:95], v[94:95], v[100:101] op_sel:[0,1] op_sel_hi:[1,0] neg_lo:[0,1]
	v_pk_add_f32 v[74:75], v[102:103], v[74:75] neg_lo:[0,1] neg_hi:[0,1]
	v_pk_add_f32 v[72:73], v[72:73], v[92:93] op_sel:[0,1] op_sel_hi:[1,0] neg_lo:[0,1]
	v_pk_add_f32 v[68:69], v[68:69], v[80:81] neg_lo:[0,1] neg_hi:[0,1]
	v_pk_add_f32 v[64:65], v[64:65], v[70:71] op_sel:[0,1] op_sel_hi:[1,0] neg_lo:[0,1]
	v_pk_fma_f32 v[10:11], v[16:17], v[88:89], v[10:11] op_sel_hi:[0,1,1]
	v_pk_mul_f32 v[12:13], v[26:27], v[76:77] op_sel:[0,1] op_sel_hi:[1,0]
	v_pk_mul_f32 v[14:15], v[30:31], v[66:67] op_sel:[0,1] op_sel_hi:[1,0]
	v_pk_mul_f32 v[16:17], v[34:35], v[82:83] op_sel:[0,1] op_sel_hi:[1,0]
	v_pk_fma_f32 v[12:13], v[24:25], v[76:77], v[12:13] op_sel_hi:[0,1,1]
	v_pk_fma_f32 v[14:15], v[28:29], v[66:67], v[14:15] op_sel_hi:[0,1,1]
	v_pk_fma_f32 v[16:17], v[32:33], v[82:83], v[16:17] op_sel_hi:[0,1,1]
	v_pk_mul_f32 v[20:21], v[38:39], v[74:75] op_sel:[0,1] op_sel_hi:[1,0]
	v_pk_mul_f32 v[22:23], v[42:43], v[78:79] op_sel:[0,1] op_sel_hi:[1,0]
	v_pk_mul_f32 v[24:25], v[46:47], v[68:69] op_sel:[0,1] op_sel_hi:[1,0]
	v_pk_mul_f32 v[26:27], v[50:51], v[94:95] op_sel:[0,1] op_sel_hi:[1,0]
	v_pk_mul_f32 v[28:29], v[54:55], v[72:73] op_sel:[0,1] op_sel_hi:[1,0]
	v_pk_mul_f32 v[30:31], v[58:59], v[84:85] op_sel:[0,1] op_sel_hi:[1,0]
	v_pk_mul_f32 v[32:33], v[62:63], v[64:65] op_sel:[0,1] op_sel_hi:[1,0]
	v_pk_fma_f32 v[20:21], v[36:37], v[74:75], v[20:21] op_sel_hi:[0,1,1]
	v_pk_fma_f32 v[22:23], v[40:41], v[78:79], v[22:23] op_sel_hi:[0,1,1]
	v_pk_fma_f32 v[24:25], v[44:45], v[68:69], v[24:25] op_sel_hi:[0,1,1]
	v_pk_fma_f32 v[26:27], v[48:49], v[94:95], v[26:27] op_sel_hi:[0,1,1]
	v_pk_fma_f32 v[28:29], v[52:53], v[72:73], v[28:29] op_sel_hi:[0,1,1]
	v_pk_fma_f32 v[30:31], v[56:57], v[84:85], v[30:31] op_sel_hi:[0,1,1]
	v_pk_fma_f32 v[32:33], v[60:61], v[64:65], v[32:33] op_sel_hi:[0,1,1]
	ds_write2_b64 v18, v[104:105], v[16:17] offset1:16
	ds_write2_b64 v18, v[8:9], v[26:27] offset0:33 offset1:49
	ds_write2_b64 v18, v[4:5], v[22:23] offset0:66 offset1:82
	ds_write2_b64 v18, v[12:13], v[30:31] offset0:99 offset1:115
	ds_write2_b64 v18, v[2:3], v[20:21] offset0:132 offset1:148
	ds_write2_b64 v18, v[10:11], v[28:29] offset0:165 offset1:181
	ds_write2_b64 v18, v[6:7], v[24:25] offset0:198 offset1:214
	ds_write2_b64 v18, v[14:15], v[32:33] offset0:231 offset1:247
	v_ashrrev_i32_e32 v2, 31, v210
	v_add_u32_sdwa v2, v210, v2 dst_sel:DWORD dst_unused:UNUSED_PAD src0_sel:DWORD src1_sel:BYTE_3
	s_lshl_b64 s[0:1], s[64:65], 15
	v_and_b32_e32 v2, 0xffffff00, v2
	s_add_u32 s0, s29, s0
	v_sub_u32_e32 v2, v210, v2
	s_addc_u32 s1, s85, s1
	v_ashrrev_i32_e32 v3, 31, v2
	v_lshl_add_u64 v[14:15], v[2:3], 3, s[0:1]
	s_movk_i32 s0, 0x1000
	v_add_co_u32_e32 v16, vcc, s0, v14
	s_movk_i32 s0, 0x3000
	s_nop 0
	v_addc_co_u32_e32 v17, vcc, 0, v15, vcc
	v_add_co_u32_e32 v2, vcc, s92, v14
	s_waitcnt lgkmcnt(0)
	s_nop 0
	v_addc_co_u32_e32 v3, vcc, 0, v15, vcc
	v_add_co_u32_e32 v22, vcc, s0, v14
	s_movk_i32 s0, 0x5000
	s_nop 0
	v_addc_co_u32_e32 v23, vcc, 0, v15, vcc
	v_add_co_u32_e32 v8, vcc, s95, v14
	s_barrier
	s_nop 0
	v_addc_co_u32_e32 v9, vcc, 0, v15, vcc
	v_add_co_u32_e32 v26, vcc, s0, v14
	s_nop 1
	v_addc_co_u32_e32 v27, vcc, 0, v15, vcc
	v_add_co_u32_e32 v10, vcc, s96, v14
	global_load_dwordx2 v[12:13], v[2:3], off nt
	global_load_dwordx2 v[6:7], v[2:3], off offset:2048 nt
	global_load_dwordx2 v[4:5], v[8:9], off offset:-4096 nt
	global_load_dwordx2 v[122:123], v[8:9], off nt
	v_addc_co_u32_e32 v11, vcc, 0, v15, vcc
	v_add_co_u32_e32 v28, vcc, s97, v14
	global_load_dwordx2 v[46:47], v[8:9], off offset:2048 nt
	global_load_dwordx2 v[38:39], v[10:11], off offset:-4096 nt
	global_load_dwordx2 v[20:21], v[10:11], off nt
	s_nop 0
	global_load_dwordx2 v[10:11], v[10:11], off offset:2048 nt
	v_addc_co_u32_e32 v29, vcc, 0, v15, vcc
	global_load_dwordx2 v[24:25], v[2:3], off offset:-4096 nt
	s_nop 0
	global_load_dwordx2 v[26:27], v[26:27], off offset:2048 nt
	s_nop 0
	global_load_dwordx2 v[8:9], v[28:29], off nt
	global_load_dwordx2 v[2:3], v[28:29], off offset:2048 nt
	global_load_dwordx2 v[30:31], v[14:15], off offset:2048 nt
	s_nop 0
	global_load_dwordx2 v[28:29], v[16:17], off offset:2048 nt
	s_nop 0
	global_load_dwordx2 v[16:17], v[22:23], off offset:2048 nt
	global_load_dwordx2 v[32:33], v[14:15], off nt
	v_mov_b32_e32 v14, v210
	s_waitcnt vmcnt(15)
	v_cvt_f32_f16_sdwa v164, v12 dst_sel:DWORD dst_unused:UNUSED_PAD src0_sel:WORD_1
	v_ashrrev_i32_e32 v15, 31, v14
	v_add_u32_sdwa v15, v14, v15 dst_sel:DWORD dst_unused:UNUSED_PAD src0_sel:DWORD src1_sel:BYTE_3
	v_ashrrev_i32_e32 v15, 8, v15
	v_mul_i32_i24_e32 v18, 0x100, v15
	v_sub_u32_e32 v18, v14, v18
	v_lshlrev_b32_e32 v14, 13, v15
	v_lshlrev_b32_e32 v15, 1, v18
	v_bfrev_b32_e32 v15, v15
	v_lshrrev_b32_e32 v15, 23, v15
	v_sub_u32_e32 v15, 0x200, v15
	v_bfrev_b32_e32 v15, v15
	v_lshrrev_b32_e32 v15, 19, v15
	v_and_b32_e32 v15, 0x1ff0, v15
	v_cmp_eq_u32_e64 s[0:1], 0, v18
	v_lshl_add_u32 v22, v18, 5, v14
	v_lshl_add_u32 v23, v22, 3, 0
	v_cndmask_b32_e64 v15, v15, 16, s[0:1]
	v_or_b32_e32 v14, v15, v14
	v_ashrrev_i32_e32 v22, 2, v22
	v_ashrrev_i32_e32 v15, 5, v14
	v_add_u32_e32 v211, v23, v22
	v_lshlrev_b32_e32 v14, 3, v14
	v_lshlrev_b32_e32 v15, 3, v15
	v_add3_u32 v212, 0, v14, v15
	ds_read2_b64 v[34:37], v211 offset1:1
	ds_read2_b64 v[40:43], v211 offset0:2 offset1:3
	ds_read2_b64 v[48:51], v212 offset1:1
	ds_read2_b64 v[52:55], v212 offset0:2 offset1:3
	ds_read2_b64 v[56:59], v211 offset0:4 offset1:5
	ds_read2_b64 v[60:63], v211 offset0:6 offset1:7
	ds_read2_b64 v[68:71], v212 offset0:4 offset1:5
	ds_read2_b64 v[72:75], v212 offset0:6 offset1:7
	ds_read2_b64 v[64:67], v211 offset0:8 offset1:9
	ds_read2_b64 v[76:79], v211 offset0:10 offset1:11
	ds_read2_b64 v[80:83], v212 offset0:8 offset1:9
	ds_read2_b64 v[98:101], v212 offset0:10 offset1:11
	ds_read2_b64 v[84:87], v211 offset0:12 offset1:13
	ds_read2_b64 v[88:91], v211 offset0:14 offset1:15
	ds_read2_b64 v[102:105], v212 offset0:12 offset1:13
	ds_read2_b64 v[106:109], v212 offset0:14 offset1:15
	s_waitcnt lgkmcnt(7)
	v_pk_add_f32 v[14:15], v[34:35], v[64:65]
	v_pk_add_f32 v[22:23], v[34:35], v[64:65] neg_lo:[0,1] neg_hi:[0,1]
	v_pk_add_f32 v[34:35], v[36:37], v[66:67]
	v_pk_add_f32 v[36:37], v[36:37], v[66:67] neg_lo:[0,1] neg_hi:[0,1]
	v_cmp_ne_u32_e32 vcc, 0, v18
	v_pk_mul_f32 v[44:45], v[36:37], s[18:19]
	v_bfrev_b32_e32 v18, v18
	v_pk_fma_f32 v[36:37], v[36:37], s[16:17], v[44:45] op_sel:[0,0,1] op_sel_hi:[1,0,0]
	s_waitcnt lgkmcnt(6)
	v_pk_add_f32 v[44:45], v[40:41], v[76:77]
	v_pk_add_f32 v[40:41], v[40:41], v[76:77] neg_lo:[0,1] neg_hi:[0,1]
	v_cvt_f32_ubyte3_e32 v18, v18
	v_pk_mul_f32 v[64:65], v[40:41], s[36:37]
	v_mul_f32_e32 v18, 0x38800000, v18
	v_pk_fma_f32 v[40:41], v[40:41], s[66:67], v[64:65] op_sel:[0,0,1] op_sel_hi:[1,0,0]
	v_pk_add_f32 v[64:65], v[42:43], v[78:79]
	v_pk_add_f32 v[42:43], v[42:43], v[78:79] neg_lo:[0,1] neg_hi:[0,1]
	s_waitcnt lgkmcnt(3)
	v_pk_add_f32 v[78:79], v[58:59], v[86:87]
	v_pk_mul_f32 v[66:67], v[42:43], s[40:41]
	v_pk_add_f32 v[58:59], v[58:59], v[86:87] neg_lo:[0,1] neg_hi:[0,1]
	v_pk_fma_f32 v[42:43], v[42:43], s[68:69], v[66:67] op_sel:[0,0,1] op_sel_hi:[1,0,0]
	v_pk_add_f32 v[66:67], v[56:57], v[84:85]
	v_pk_add_f32 v[76:77], v[56:57], v[84:85] neg_lo:[0,1] neg_hi:[0,1]
	v_pk_mul_f32 v[84:85], v[58:59], s[40:41]
	s_nop 0
	v_pk_fma_f32 v[58:59], v[58:59], s[68:69], v[84:85] op_sel:[0,0,1] op_sel_hi:[1,0,0] neg_lo:[1,0,0] neg_hi:[1,0,0]
	s_waitcnt lgkmcnt(2)
	v_pk_add_f32 v[84:85], v[60:61], v[88:89]
	v_pk_add_f32 v[60:61], v[60:61], v[88:89] neg_lo:[0,1] neg_hi:[0,1]
	s_nop 0
	v_pk_mul_f32 v[86:87], v[60:61], s[36:37]
	v_pk_add_f32 v[56:57], v[22:23], v[76:77] op_sel:[0,1] op_sel_hi:[1,0] neg_hi:[0,1]
	v_pk_fma_f32 v[60:61], v[60:61], s[66:67], v[86:87] op_sel:[0,0,1] op_sel_hi:[1,0,0] neg_lo:[1,0,0] neg_hi:[1,0,0]
	v_pk_add_f32 v[86:87], v[62:63], v[90:91]
	v_pk_add_f32 v[62:63], v[62:63], v[90:91] neg_lo:[0,1] neg_hi:[0,1]
	v_pk_add_f32 v[90:91], v[64:65], v[86:87]
	v_pk_mul_f32 v[88:89], v[62:63], s[18:19]
	v_pk_add_f32 v[64:65], v[64:65], v[86:87] neg_lo:[0,1] neg_hi:[0,1]
	v_pk_fma_f32 v[62:63], v[62:63], s[16:17], v[88:89] op_sel:[0,0,1] op_sel_hi:[1,0,0] neg_lo:[1,0,0] neg_hi:[1,0,0]
	v_pk_add_f32 v[88:89], v[14:15], v[66:67]
	v_pk_add_f32 v[14:15], v[14:15], v[66:67] neg_lo:[0,1] neg_hi:[0,1]
	v_pk_add_f32 v[66:67], v[34:35], v[78:79]
	v_pk_add_f32 v[34:35], v[34:35], v[78:79] neg_lo:[0,1] neg_hi:[0,1]
	v_pk_add_f32 v[22:23], v[22:23], v[76:77] op_sel:[0,1] op_sel_hi:[1,0] neg_lo:[0,1]
	v_pk_mul_f32 v[78:79], v[34:35], s[36:37]
	v_pk_add_f32 v[76:77], v[36:37], v[58:59]
	v_pk_add_f32 v[36:37], v[36:37], v[58:59] neg_lo:[0,1] neg_hi:[0,1]
	v_pk_fma_f32 v[34:35], v[34:35], s[66:67], v[78:79] op_sel:[0,0,1] op_sel_hi:[1,0,0]
	v_pk_add_f32 v[78:79], v[44:45], v[84:85]
	v_pk_add_f32 v[84:85], v[44:45], v[84:85] neg_lo:[0,1] neg_hi:[0,1]
	v_pk_mul_f32 v[86:87], v[64:65], s[36:37]
	v_pk_mul_f32 v[58:59], v[36:37], s[36:37]
	v_pk_fma_f32 v[64:65], v[64:65], s[66:67], v[86:87] op_sel:[0,0,1] op_sel_hi:[1,0,0] neg_lo:[1,0,0] neg_hi:[1,0,0]
	v_pk_fma_f32 v[36:37], v[36:37], s[66:67], v[58:59] op_sel:[0,0,1] op_sel_hi:[1,0,0]
	v_pk_add_f32 v[58:59], v[40:41], v[60:61]
	v_pk_add_f32 v[86:87], v[42:43], v[62:63]
	v_pk_add_f32 v[42:43], v[42:43], v[62:63] neg_lo:[0,1] neg_hi:[0,1]
	s_nop 0
	v_pk_mul_f32 v[62:63], v[42:43], s[36:37]
	v_pk_add_f32 v[44:45], v[14:15], v[84:85] op_sel:[0,1] op_sel_hi:[1,0] neg_hi:[0,1]
	v_pk_add_f32 v[14:15], v[14:15], v[84:85] op_sel:[0,1] op_sel_hi:[1,0] neg_lo:[0,1]
	v_pk_add_f32 v[84:85], v[34:35], v[64:65]
	v_pk_add_f32 v[64:65], v[34:35], v[64:65] neg_lo:[0,1] neg_hi:[0,1]
	v_pk_add_f32 v[94:95], v[56:57], v[58:59]
	v_pk_add_f32 v[56:57], v[56:57], v[58:59] neg_lo:[0,1] neg_hi:[0,1]
	v_pk_add_f32 v[58:59], v[76:77], v[86:87]
	v_pk_fma_f32 v[42:43], v[42:43], s[66:67], v[62:63] op_sel:[0,0,1] op_sel_hi:[1,0,0] neg_lo:[1,0,0] neg_hi:[1,0,0]
	v_pk_add_f32 v[62:63], v[88:89], v[78:79]
	v_pk_add_f32 v[78:79], v[88:89], v[78:79] neg_lo:[0,1] neg_hi:[0,1]
	v_pk_add_f32 v[88:89], v[66:67], v[90:91]
	v_pk_add_f32 v[110:111], v[76:77], v[86:87] neg_lo:[0,1] neg_hi:[0,1]
	v_pk_add_f32 v[86:87], v[94:95], v[58:59]
	v_pk_add_f32 v[34:35], v[94:95], v[58:59] neg_lo:[0,1] neg_hi:[0,1]
	v_pk_add_f32 v[58:59], v[50:51], v[82:83]
	v_pk_add_f32 v[50:51], v[50:51], v[82:83] neg_lo:[0,1] neg_hi:[0,1]
	v_pk_add_f32 v[60:61], v[40:41], v[60:61] neg_lo:[0,1] neg_hi:[0,1]
	v_pk_add_f32 v[148:149], v[62:63], v[88:89]
	v_pk_add_f32 v[138:139], v[62:63], v[88:89] neg_lo:[0,1] neg_hi:[0,1]
	v_pk_mul_f32 v[62:63], v[50:51], s[18:19]
	v_pk_add_f32 v[90:91], v[66:67], v[90:91] neg_lo:[0,1] neg_hi:[0,1]
	v_pk_fma_f32 v[50:51], v[50:51], s[16:17], v[62:63] op_sel:[0,0,1] op_sel_hi:[1,0,0]
	v_pk_add_f32 v[62:63], v[52:53], v[98:99]
	v_pk_add_f32 v[52:53], v[52:53], v[98:99] neg_lo:[0,1] neg_hi:[0,1]
	v_pk_add_f32 v[112:113], v[22:23], v[60:61] op_sel:[0,1] op_sel_hi:[1,0] neg_hi:[0,1]
	v_pk_add_f32 v[114:115], v[22:23], v[60:61] op_sel:[0,1] op_sel_hi:[1,0] neg_lo:[0,1]
	v_pk_add_f32 v[96:97], v[44:45], v[84:85]
	v_pk_add_f32 v[66:67], v[44:45], v[84:85] neg_lo:[0,1] neg_hi:[0,1]
	v_pk_add_f32 v[60:61], v[14:15], v[64:65] op_sel:[0,1] op_sel_hi:[1,0] neg_hi:[0,1]
	v_pk_add_f32 v[84:85], v[14:15], v[64:65] op_sel:[0,1] op_sel_hi:[1,0] neg_lo:[0,1]
	v_pk_mul_f32 v[64:65], v[52:53], s[36:37]
	s_nop 0
	v_pk_fma_f32 v[52:53], v[52:53], s[66:67], v[64:65] op_sel:[0,0,1] op_sel_hi:[1,0,0]
	v_pk_add_f32 v[64:65], v[54:55], v[100:101]
	v_pk_add_f32 v[54:55], v[54:55], v[100:101] neg_lo:[0,1] neg_hi:[0,1]
	s_nop 0
	v_pk_mul_f32 v[76:77], v[54:55], s[40:41]
	v_pk_add_f32 v[92:93], v[78:79], v[90:91] op_sel:[0,1] op_sel_hi:[1,0] neg_hi:[0,1]
	v_pk_fma_f32 v[54:55], v[54:55], s[68:69], v[76:77] op_sel:[0,0,1] op_sel_hi:[1,0,0]
	s_waitcnt lgkmcnt(1)
	v_pk_add_f32 v[76:77], v[68:69], v[102:103]
	v_pk_add_f32 v[88:89], v[78:79], v[90:91] op_sel:[0,1] op_sel_hi:[1,0] neg_lo:[0,1]
	v_pk_add_f32 v[78:79], v[68:69], v[102:103] neg_lo:[0,1] neg_hi:[0,1]
	v_pk_add_f32 v[68:69], v[70:71], v[104:105]
	v_pk_add_f32 v[70:71], v[70:71], v[104:105] neg_lo:[0,1] neg_hi:[0,1]
	v_pk_add_f32 v[40:41], v[56:57], v[110:111] op_sel:[0,1] op_sel_hi:[1,0] neg_hi:[0,1]
	v_pk_add_f32 v[44:45], v[56:57], v[110:111] op_sel:[0,1] op_sel_hi:[1,0] neg_lo:[0,1]
	v_pk_add_f32 v[56:57], v[48:49], v[80:81]
	v_pk_add_f32 v[48:49], v[48:49], v[80:81] neg_lo:[0,1] neg_hi:[0,1]
	v_pk_mul_f32 v[80:81], v[70:71], s[40:41]
	v_cndmask_b32_e64 v18, v18, v208, s[0:1]
	v_pk_fma_f32 v[70:71], v[70:71], s[68:69], v[80:81] op_sel:[0,0,1] op_sel_hi:[1,0,0] neg_lo:[1,0,0] neg_hi:[1,0,0]
	s_waitcnt lgkmcnt(0)
	v_pk_add_f32 v[80:81], v[72:73], v[106:107]
	v_pk_add_f32 v[72:73], v[72:73], v[106:107] neg_lo:[0,1] neg_hi:[0,1]
	v_pk_add_f32 v[22:23], v[36:37], v[42:43]
	v_pk_mul_f32 v[82:83], v[72:73], s[36:37]
	v_pk_add_f32 v[116:117], v[36:37], v[42:43] neg_lo:[0,1] neg_hi:[0,1]
	v_pk_fma_f32 v[72:73], v[72:73], s[66:67], v[82:83] op_sel:[0,0,1] op_sel_hi:[1,0,0] neg_lo:[1,0,0] neg_hi:[1,0,0]
	v_pk_add_f32 v[82:83], v[74:75], v[108:109]
	v_pk_add_f32 v[74:75], v[74:75], v[108:109] neg_lo:[0,1] neg_hi:[0,1]
	s_nop 0
	v_pk_mul_f32 v[90:91], v[74:75], s[18:19]
	s_nop 0
	v_pk_fma_f32 v[74:75], v[74:75], s[16:17], v[90:91] op_sel:[0,0,1] op_sel_hi:[1,0,0] neg_lo:[1,0,0] neg_hi:[1,0,0]
	v_pk_add_f32 v[90:91], v[56:57], v[76:77]
	v_pk_add_f32 v[56:57], v[56:57], v[76:77] neg_lo:[0,1] neg_hi:[0,1]
	v_pk_add_f32 v[76:77], v[58:59], v[68:69]
	v_pk_add_f32 v[58:59], v[58:59], v[68:69] neg_lo:[0,1] neg_hi:[0,1]
	v_pk_add_f32 v[14:15], v[114:115], v[116:117] op_sel:[0,1] op_sel_hi:[1,0] neg_hi:[0,1]
	v_pk_mul_f32 v[68:69], v[58:59], s[36:37]
	v_pk_add_f32 v[36:37], v[114:115], v[116:117] op_sel:[0,1] op_sel_hi:[1,0] neg_lo:[0,1]
	v_pk_fma_f32 v[58:59], v[58:59], s[66:67], v[68:69] op_sel:[0,0,1] op_sel_hi:[1,0,0]
	v_pk_add_f32 v[68:69], v[62:63], v[80:81]
	v_pk_add_f32 v[80:81], v[62:63], v[80:81] neg_lo:[0,1] neg_hi:[0,1]
	s_waitcnt vmcnt(0)
	v_cvt_f32_f16_e32 v193, v33
	s_nop 0
	s_nop 0
	v_pk_add_f32 v[62:63], v[64:65], v[82:83]
	v_pk_add_f32 v[64:65], v[64:65], v[82:83] neg_lo:[0,1] neg_hi:[0,1]
	v_cvt_f32_f16_sdwa v192, v32 dst_sel:DWORD dst_unused:UNUSED_PAD src0_sel:WORD_1
	v_pk_mul_f32 v[82:83], v[64:65], s[36:37]
	v_cvt_f32_f16_e32 v194, v32
	v_pk_fma_f32 v[64:65], v[64:65], s[66:67], v[82:83] op_sel:[0,0,1] op_sel_hi:[1,0,0] neg_lo:[1,0,0] neg_hi:[1,0,0]
	v_pk_add_f32 v[82:83], v[48:49], v[78:79] op_sel:[0,1] op_sel_hi:[1,0] neg_hi:[0,1]
	v_pk_add_f32 v[48:49], v[48:49], v[78:79] op_sel:[0,1] op_sel_hi:[1,0] neg_lo:[0,1]
	v_pk_add_f32 v[78:79], v[50:51], v[70:71]
	v_pk_add_f32 v[50:51], v[50:51], v[70:71] neg_lo:[0,1] neg_hi:[0,1]
	v_cvt_f32_f16_sdwa v195, v33 dst_sel:DWORD dst_unused:UNUSED_PAD src0_sel:WORD_1
	v_pk_mul_f32 v[70:71], v[50:51], s[36:37]
	v_cvt_f32_f16_sdwa v170, v30 dst_sel:DWORD dst_unused:UNUSED_PAD src0_sel:WORD_1
	v_pk_fma_f32 v[50:51], v[50:51], s[66:67], v[70:71] op_sel:[0,0,1] op_sel_hi:[1,0,0]
	v_pk_add_f32 v[70:71], v[52:53], v[72:73]
	v_pk_add_f32 v[72:73], v[52:53], v[72:73] neg_lo:[0,1] neg_hi:[0,1]
	v_cvt_f32_f16_e32 v171, v31
	s_nop 0
	s_nop 0
	v_pk_add_f32 v[52:53], v[54:55], v[74:75]
	v_pk_add_f32 v[54:55], v[54:55], v[74:75] neg_lo:[0,1] neg_hi:[0,1]
	v_cvt_f32_f16_sdwa v185, v31 dst_sel:DWORD dst_unused:UNUSED_PAD src0_sel:WORD_1
	v_pk_mul_f32 v[74:75], v[54:55], s[36:37]
	v_cvt_f32_f16_e32 v184, v30
	v_pk_fma_f32 v[54:55], v[54:55], s[66:67], v[74:75] op_sel:[0,0,1] op_sel_hi:[1,0,0] neg_lo:[1,0,0] neg_hi:[1,0,0]
	v_pk_add_f32 v[74:75], v[90:91], v[68:69]
	v_pk_add_f32 v[68:69], v[90:91], v[68:69] neg_lo:[0,1] neg_hi:[0,1]
	v_pk_add_f32 v[90:91], v[76:77], v[62:63]
	v_pk_add_f32 v[62:63], v[76:77], v[62:63] neg_lo:[0,1] neg_hi:[0,1]
	v_cvt_f32_f16_sdwa v172, v24 dst_sel:DWORD dst_unused:UNUSED_PAD src0_sel:WORD_1
	v_xor_b32_e32 v77, 0x80000000, v62
	v_mov_b32_e32 v76, v63
	v_pk_add_f32 v[62:63], v[56:57], v[80:81] op_sel:[0,1] op_sel_hi:[1,0] neg_hi:[0,1]
	v_pk_add_f32 v[56:57], v[56:57], v[80:81] op_sel:[0,1] op_sel_hi:[1,0] neg_lo:[0,1]
	v_pk_add_f32 v[80:81], v[58:59], v[64:65]
	v_pk_add_f32 v[58:59], v[58:59], v[64:65] neg_lo:[0,1] neg_hi:[0,1]
	v_cvt_f32_f16_e32 v173, v25
	v_xor_b32_e32 v65, 0x80000000, v58
	v_mov_b32_e32 v64, v59
	v_pk_add_f32 v[58:59], v[82:83], v[70:71]
	v_pk_add_f32 v[70:71], v[82:83], v[70:71] neg_lo:[0,1] neg_hi:[0,1]
	v_pk_add_f32 v[82:83], v[78:79], v[52:53]
	v_pk_add_f32 v[52:53], v[78:79], v[52:53] neg_lo:[0,1] neg_hi:[0,1]
	v_pk_add_f32 v[118:119], v[58:59], v[82:83]
	v_pk_add_f32 v[134:135], v[58:59], v[82:83] neg_lo:[0,1] neg_hi:[0,1]
	v_cos_f32_e32 v83, v18
	v_sin_f32_e32 v82, v18
	v_cvt_f32_f16_sdwa v181, v25 dst_sel:DWORD dst_unused:UNUSED_PAD src0_sel:WORD_1
	v_cvt_f32_f16_e32 v180, v24
	v_cvt_f32_f16_sdwa v174, v28 dst_sel:DWORD dst_unused:UNUSED_PAD src0_sel:WORD_1
	v_cvt_f32_f16_e32 v175, v29
	v_cvt_f32_f16_sdwa v179, v29 dst_sel:DWORD dst_unused:UNUSED_PAD src0_sel:WORD_1
	v_cvt_f32_f16_e32 v178, v28
	v_cvt_f32_f16_e32 v165, v13
	v_cvt_f32_f16_sdwa v167, v13 dst_sel:DWORD dst_unused:UNUSED_PAD src0_sel:WORD_1
	v_cvt_f32_f16_e32 v166, v12
	v_cvt_f32_f16_e32 v154, v6
	v_cvt_f32_f16_e32 v155, v7
	v_cvt_f32_f16_sdwa v157, v7 dst_sel:DWORD dst_unused:UNUSED_PAD src0_sel:WORD_1
	v_cvt_f32_f16_sdwa v156, v6 dst_sel:DWORD dst_unused:UNUSED_PAD src0_sel:WORD_1
	v_cvt_f32_f16_sdwa v140, v4 dst_sel:DWORD dst_unused:UNUSED_PAD src0_sel:WORD_1
	v_cvt_f32_f16_e32 v141, v5
	v_cvt_f32_f16_sdwa v143, v5 dst_sel:DWORD dst_unused:UNUSED_PAD src0_sel:WORD_1
	v_cvt_f32_f16_e32 v142, v4
	v_cvt_f32_f16_e32 v124, v16
	v_cvt_f32_f16_e32 v125, v17
	v_cvt_f32_f16_sdwa v127, v17 dst_sel:DWORD dst_unused:UNUSED_PAD src0_sel:WORD_1
	v_cvt_f32_f16_sdwa v126, v16 dst_sel:DWORD dst_unused:UNUSED_PAD src0_sel:WORD_1
	v_cvt_f32_f16_sdwa v114, v122 dst_sel:DWORD dst_unused:UNUSED_PAD src0_sel:WORD_1
	v_cvt_f32_f16_e32 v115, v123
	v_cvt_f32_f16_sdwa v117, v123 dst_sel:DWORD dst_unused:UNUSED_PAD src0_sel:WORD_1
	v_cvt_f32_f16_e32 v116, v122
	v_xor_b32_e32 v79, 0x80000000, v52
	v_mov_b32_e32 v78, v53
	v_pk_add_f32 v[52:53], v[48:49], v[72:73] op_sel:[0,1] op_sel_hi:[1,0] neg_hi:[0,1]
	v_pk_add_f32 v[48:49], v[48:49], v[72:73] op_sel:[0,1] op_sel_hi:[1,0] neg_lo:[0,1]
	v_pk_add_f32 v[72:73], v[50:51], v[54:55]
	v_pk_add_f32 v[50:51], v[50:51], v[54:55] neg_lo:[0,1] neg_hi:[0,1]
	v_pk_fma_f32 v[160:161], v[82:83], 0, v[82:83] op_sel:[0,0,1] op_sel_hi:[1,0,0] neg_lo:[1,0,0] neg_hi:[1,0,0]
	v_xor_b32_e32 v55, 0x80000000, v50
	v_mov_b32_e32 v54, v51
	v_pk_fma_f32 v[198:199], v[82:83], 0, v[82:83] op_sel:[0,0,1] op_sel_hi:[1,0,0]
	v_pk_add_f32 v[42:43], v[112:113], v[22:23]
	v_pk_add_f32 v[22:23], v[112:113], v[22:23] neg_lo:[0,1] neg_hi:[0,1]
	v_pk_add_f32 v[98:99], v[74:75], v[90:91]
	v_pk_add_f32 v[100:101], v[74:75], v[90:91] neg_lo:[0,1] neg_hi:[0,1]
	v_pk_add_f32 v[102:103], v[68:69], v[76:77]
	v_pk_add_f32 v[106:107], v[68:69], v[76:77] neg_lo:[0,1] neg_hi:[0,1]
	v_pk_add_f32 v[104:105], v[62:63], v[80:81]
	v_pk_add_f32 v[108:109], v[62:63], v[80:81] neg_lo:[0,1] neg_hi:[0,1]
	v_pk_add_f32 v[110:111], v[56:57], v[64:65]
	v_pk_add_f32 v[112:113], v[56:57], v[64:65] neg_lo:[0,1] neg_hi:[0,1]
	v_pk_add_f32 v[152:153], v[70:71], v[78:79]
	v_pk_add_f32 v[162:163], v[70:71], v[78:79] neg_lo:[0,1] neg_hi:[0,1]
	v_pk_add_f32 v[176:177], v[52:53], v[72:73]
	v_pk_add_f32 v[182:183], v[52:53], v[72:73] neg_lo:[0,1] neg_hi:[0,1]
	v_pk_add_f32 v[188:189], v[48:49], v[54:55]
	v_pk_add_f32 v[196:197], v[48:49], v[54:55] neg_lo:[0,1] neg_hi:[0,1]
	v_pk_mul_f32 v[186:187], v[82:83], 0 op_sel_hi:[1,0]
	v_mov_b32_e32 v190, v160
	v_mov_b32_e32 v191, v199
	v_mul_f32_e32 v18, 0x3f3504f3, v83
	v_mul_f32_e32 v158, 0xbec3ef15, v83
	v_mul_f32_e32 v132, 0xbf6c835e, v83
	s_and_saveexec_b64 s[0:1], vcc
	s_xor_b64 s[0:1], exec, s[0:1]
	s_cbranch_execz .LBB0_536
	v_pk_add_f32 v[4:5], v[148:149], v[196:197]
	v_pk_add_f32 v[6:7], v[148:149], v[196:197] neg_lo:[0,1] neg_hi:[0,1]
	v_mul_f32_e32 v4, 0.5, v4
	v_mul_f32_e32 v12, 0.5, v7
	v_mov_b32_e32 v7, v5
	v_pk_mul_f32 v[6:7], v[6:7], s[44:45]
	v_pk_mov_b32 v[16:17], v[198:199], v[160:161] op_sel:[1,0]
	v_pk_mul_f32 v[24:25], v[190:191], v[6:7] op_sel:[0,1] op_sel_hi:[1,0]
	v_pk_mul_f32 v[6:7], v[190:191], v[6:7]
	v_pk_add_f32 v[24:25], v[24:25], v[24:25] op_sel:[0,1] op_sel_hi:[0,1]
	v_pk_add_f32 v[28:29], v[4:5], v[24:25] op_sel_hi:[0,1] neg_hi:[0,1]
	v_pk_add_f32 v[4:5], v[6:7], v[6:7] op_sel:[0,1] op_sel_hi:[0,1] neg_lo:[0,1] neg_hi:[0,1]
	v_pk_add_f32 v[6:7], v[12:13], v[4:5] op_sel_hi:[0,1] neg_hi:[0,1]
	v_pk_mul_f32 v[4:5], v[6:7], v[194:195]
	v_pk_mul_f32 v[6:7], v[6:7], v[192:193]
	v_pk_fma_f32 v[4:5], v[28:29], v[192:193], v[4:5]
	v_pk_fma_f32 v[6:7], v[28:29], v[194:195], v[6:7] neg_lo:[0,0,1] neg_hi:[0,0,1]
	s_mov_b32 s66, s19
	v_pk_add_f32 v[12:13], v[6:7], v[4:5] op_sel:[0,1] op_sel_hi:[1,0] neg_lo:[0,1]
	v_pk_add_f32 v[28:29], v[6:7], v[4:5] op_sel:[0,1] op_sel_hi:[1,0]
	v_pk_add_f32 v[4:5], v[4:5], v[6:7] op_sel:[1,0] op_sel_hi:[0,1] neg_lo:[0,1] neg_hi:[0,1]
	s_nop 0
	v_pk_mul_f32 v[12:13], v[12:13], 0.5 op_sel_hi:[1,0]
	v_mov_b32_e32 v29, v5
	v_mul_f32_e32 v24, v190, v12
	v_pk_fma_f32 v[30:31], v[190:191], v[12:13], v[24:25] op_sel_hi:[1,1,0] neg_lo:[1,0,0] neg_hi:[1,0,0]
	v_mul_f32_e32 v24, v160, v13
	v_pk_fma_f32 v[12:13], v[16:17], v[12:13], v[24:25] op_sel_hi:[1,1,0]
	v_mov_b32_e32 v16, v83
	v_mov_b32_e32 v30, v12
	v_pk_fma_f32 v[4:5], v[28:29], 0.5, v[12:13] op_sel_hi:[1,0,1] neg_lo:[0,0,1] neg_hi:[0,0,1]
	v_pk_fma_f32 v[122:123], v[28:29], 0.5, v[30:31] op_sel_hi:[1,0,1]
	v_pk_fma_f32 v[6:7], v[28:29], 0.5, v[30:31] op_sel_hi:[1,0,1] neg_lo:[1,0,0] neg_hi:[1,0,0]
	v_mov_b32_e32 v5, v123
	v_pk_mul_f32 v[24:25], v[4:5], s[46:47] op_sel_hi:[1,0]
	v_pk_add_f32 v[4:5], v[138:139], v[188:189]
	v_pk_add_f32 v[12:13], v[138:139], v[188:189] neg_lo:[0,1] neg_hi:[0,1]
	v_mov_b32_e32 v17, v82
	v_mul_f32_e32 v6, 0.5, v13
	v_pk_add_f32 v[28:29], v[186:187], v[16:17] neg_lo:[0,1] neg_hi:[0,1]
	v_pk_add_f32 v[30:31], v[186:187], v[16:17]
	v_mov_b32_e32 v13, v5
	v_pk_mov_b32 v[32:33], v[28:29], v[30:31] op_sel:[1,0]
	v_pk_mul_f32 v[12:13], v[12:13], s[44:45]
	v_mul_f32_e32 v4, 0.5, v4
	v_pk_mul_f32 v[48:49], v[32:33], v[12:13] op_sel:[0,1] op_sel_hi:[1,0]
	v_pk_mul_f32 v[12:13], v[32:33], v[12:13]
	v_pk_add_f32 v[48:49], v[48:49], v[48:49] op_sel:[0,1] op_sel_hi:[0,1]
	v_pk_add_f32 v[50:51], v[4:5], v[48:49] op_sel_hi:[0,1] neg_hi:[0,1]
	v_pk_add_f32 v[4:5], v[12:13], v[12:13] op_sel:[0,1] op_sel_hi:[0,1] neg_lo:[0,1] neg_hi:[0,1]
	v_pk_add_f32 v[12:13], v[6:7], v[4:5] op_sel_hi:[0,1] neg_hi:[0,1]
	v_pk_mul_f32 v[4:5], v[12:13], v[184:185]
	v_pk_mul_f32 v[12:13], v[12:13], v[170:171]
	v_pk_fma_f32 v[4:5], v[50:51], v[170:171], v[4:5]
	v_pk_fma_f32 v[12:13], v[50:51], v[184:185], v[12:13] neg_lo:[0,0,1] neg_hi:[0,0,1]
	v_mov_b32_e32 v31, v29
	v_pk_add_f32 v[48:49], v[12:13], v[4:5] op_sel:[0,1] op_sel_hi:[1,0] neg_lo:[0,1]
	v_pk_add_f32 v[50:51], v[12:13], v[4:5] op_sel:[0,1] op_sel_hi:[1,0]
	v_pk_add_f32 v[4:5], v[4:5], v[12:13] op_sel:[1,0] op_sel_hi:[0,1] neg_lo:[0,1] neg_hi:[0,1]
	v_pk_mul_f32 v[48:49], v[48:49], 0.5 op_sel_hi:[1,0]
	v_mov_b32_e32 v51, v5
	v_mul_f32_e32 v6, v29, v48
	v_pk_fma_f32 v[32:33], v[32:33], v[48:49], v[6:7] op_sel_hi:[1,1,0] neg_lo:[1,0,0] neg_hi:[1,0,0]
	v_mul_f32_e32 v6, v29, v49
	v_pk_fma_f32 v[28:29], v[30:31], v[48:49], v[6:7] op_sel_hi:[1,1,0]
	v_pk_mul_f32 v[12:13], v[16:17], s[36:37]
	v_mov_b32_e32 v32, v28
	v_pk_fma_f32 v[4:5], v[50:51], 0.5, v[28:29] op_sel_hi:[1,0,1] neg_lo:[0,0,1] neg_hi:[0,0,1]
	v_pk_fma_f32 v[138:139], v[50:51], 0.5, v[32:33] op_sel_hi:[1,0,1]
	v_pk_add_f32 v[16:17], v[92:93], v[182:183]
	v_mov_b32_e32 v5, v139
	v_pk_add_f32 v[28:29], v[92:93], v[182:183] neg_lo:[0,1] neg_hi:[0,1]
	v_pk_mul_f32 v[30:31], v[4:5], s[46:47] op_sel_hi:[1,0]
	v_pk_fma_f32 v[4:5], v[50:51], 0.5, v[32:33] op_sel_hi:[1,0,1] neg_lo:[1,0,0] neg_hi:[1,0,0]
	v_mul_f32_e32 v6, 0.5, v29
	v_pk_add_f32 v[32:33], v[18:19], v[12:13] op_sel:[0,1] op_sel_hi:[0,1] neg_lo:[0,1] neg_hi:[0,1]
	v_pk_add_f32 v[48:49], v[18:19], v[12:13] op_sel:[0,1] op_sel_hi:[0,1]
	v_mov_b32_e32 v29, v17
	v_mul_f32_e32 v4, 0.5, v16
	v_mov_b32_e32 v50, v32
	v_mov_b32_e32 v51, v49
	v_pk_mul_f32 v[16:17], v[28:29], s[44:45]
	v_pk_mov_b32 v[48:49], v[48:49], v[32:33] op_sel:[1,0]
	v_pk_mul_f32 v[28:29], v[50:51], v[16:17] op_sel:[0,1] op_sel_hi:[1,0]
	v_pk_mul_f32 v[16:17], v[50:51], v[16:17]
	v_pk_add_f32 v[28:29], v[28:29], v[28:29] op_sel:[0,1] op_sel_hi:[0,1]
	v_pk_add_f32 v[52:53], v[4:5], v[28:29] op_sel_hi:[0,1] neg_hi:[0,1]
	v_pk_add_f32 v[16:17], v[16:17], v[16:17] op_sel:[0,1] op_sel_hi:[0,1] neg_lo:[0,1] neg_hi:[0,1]
	v_pk_add_f32 v[28:29], v[6:7], v[16:17] op_sel_hi:[0,1] neg_hi:[0,1]
	v_pk_mul_f32 v[16:17], v[28:29], v[180:181]
	v_pk_mul_f32 v[28:29], v[28:29], v[172:173]
	v_pk_fma_f32 v[16:17], v[52:53], v[172:173], v[16:17]
	v_pk_fma_f32 v[28:29], v[52:53], v[180:181], v[28:29] neg_lo:[0,0,1] neg_hi:[0,0,1]
	v_sub_f32_e32 v6, v89, v177
	v_pk_add_f32 v[52:53], v[28:29], v[16:17] op_sel:[0,1] op_sel_hi:[1,0] neg_lo:[0,1]
	v_pk_add_f32 v[54:55], v[28:29], v[16:17] op_sel:[0,1] op_sel_hi:[1,0]
	v_pk_add_f32 v[16:17], v[16:17], v[28:29] op_sel:[1,0] op_sel_hi:[0,1] neg_lo:[0,1] neg_hi:[0,1]
	v_pk_mul_f32 v[52:53], v[52:53], 0.5 op_sel_hi:[1,0]
	v_mov_b32_e32 v55, v17
	v_mul_f32_e32 v4, v32, v52
	v_pk_fma_f32 v[56:57], v[50:51], v[52:53], v[4:5] op_sel_hi:[1,1,0] neg_lo:[1,0,0] neg_hi:[1,0,0]
	v_mul_f32_e32 v4, v32, v53
	v_pk_fma_f32 v[48:49], v[48:49], v[52:53], v[4:5] op_sel_hi:[1,1,0]
	v_pk_add_f32 v[28:29], v[88:89], v[176:177]
	v_mov_b32_e32 v56, v48
	v_pk_fma_f32 v[16:17], v[54:55], 0.5, v[48:49] op_sel_hi:[1,0,1] neg_lo:[0,0,1] neg_hi:[0,0,1]
	v_mov_b32_e32 v48, v12
	v_mov_b32_e32 v49, v88
	v_pk_mov_b32 v[12:13], v[12:13], v[176:177] op_sel:[1,0]
	v_mul_f32_e32 v18, 0.5, v29
	v_pk_add_f32 v[12:13], v[48:49], v[12:13] neg_lo:[0,1] neg_hi:[0,1]
	v_mul_f32_e32 v4, 0.5, v28
	v_pk_mul_f32 v[48:49], v[12:13], v[18:19]
	v_mov_b32_e32 v13, v32
	v_pk_fma_f32 v[50:51], v[50:51], v[48:49], v[48:49] op_sel:[0,1,0] op_sel_hi:[1,0,1]
	v_mov_b32_e32 v48, v49
	v_mov_b32_e32 v49, v18
	v_pk_mul_f32 v[48:49], v[12:13], v[48:49]
	v_pk_add_f32 v[52:53], v[4:5], v[50:51]
	v_mul_f32_e32 v6, 0.5, v6
	v_fma_f32 v53, v28, 0.5, -v50
	v_pk_add_f32 v[28:29], v[48:49], v[48:49] op_sel:[0,1] op_sel_hi:[0,1] neg_lo:[0,1] neg_hi:[0,1]
	v_pk_add_f32 v[48:49], v[6:7], v[28:29] op_sel_hi:[0,1] neg_hi:[0,1]
	v_pk_mul_f32 v[28:29], v[48:49], v[178:179]
	v_pk_mul_f32 v[48:49], v[48:49], v[174:175]
	v_pk_fma_f32 v[28:29], v[52:53], v[174:175], v[28:29]
	v_pk_fma_f32 v[48:49], v[52:53], v[178:179], v[48:49] neg_lo:[0,0,1] neg_hi:[0,0,1]
	v_pk_fma_f32 v[92:93], v[54:55], 0.5, v[56:57] op_sel_hi:[1,0,1]
	v_pk_add_f32 v[50:51], v[48:49], v[28:29] op_sel:[0,1] op_sel_hi:[1,0] neg_lo:[0,1]
	v_pk_add_f32 v[52:53], v[48:49], v[28:29] op_sel:[0,1] op_sel_hi:[1,0]
	v_mov_b32_e32 v17, v93
	v_pk_mul_f32 v[50:51], v[50:51], 0.5 op_sel_hi:[1,0]
	v_pk_mul_f32 v[64:65], v[16:17], s[46:47] op_sel_hi:[1,0]
	v_mul_f32_e32 v4, v12, v50
	v_pk_fma_f32 v[16:17], v[54:55], 0.5, v[56:57] op_sel_hi:[1,0,1] neg_lo:[1,0,0] neg_hi:[1,0,0]
	v_pk_fma_f32 v[54:55], v[12:13], v[50:51], v[4:5] op_sel_hi:[1,1,0] neg_lo:[1,0,0] neg_hi:[1,0,0]
	v_mov_b32_e32 v33, v12
	v_mul_f32_e32 v4, v12, v51
	v_pk_fma_f32 v[12:13], v[32:33], v[50:51], v[4:5] op_sel_hi:[1,1,0]
	v_pk_add_f32 v[28:29], v[28:29], v[48:49] op_sel:[1,0] op_sel_hi:[0,1] neg_lo:[0,1] neg_hi:[0,1]
	v_mov_b32_e32 v53, v29
	v_mov_b32_e32 v54, v12
	v_pk_fma_f32 v[12:13], v[52:53], 0.5, v[12:13] op_sel_hi:[1,0,1] neg_lo:[0,0,1] neg_hi:[0,0,1]
	v_pk_fma_f32 v[88:89], v[52:53], 0.5, v[54:55] op_sel_hi:[1,0,1]
	s_mov_b32 s67, s16
	v_mov_b32_e32 v13, v89
	v_pk_mul_f32 v[68:69], v[12:13], s[46:47] op_sel_hi:[1,0]
	v_pk_fma_f32 v[12:13], v[52:53], 0.5, v[54:55] op_sel_hi:[1,0,1] neg_lo:[1,0,0] neg_hi:[1,0,0]
	v_mov_b32_e32 v4, v83
	s_mov_b32 s17, s19
	v_pk_mul_f32 v[48:49], v[82:83], s[66:67] op_sel_hi:[0,1]
	v_pk_add_f32 v[28:29], v[96:97], v[162:163]
	v_pk_add_f32 v[32:33], v[96:97], v[162:163] neg_lo:[0,1] neg_hi:[0,1]
	v_pk_fma_f32 v[52:53], v[4:5], s[16:17], v[48:49] op_sel_hi:[0,1,1] neg_lo:[0,0,1] neg_hi:[0,0,1]
	v_mul_f32_e32 v12, 0.5, v33
	v_pk_fma_f32 v[50:51], v[4:5], s[16:17], v[48:49] op_sel_hi:[0,1,1]
	v_mov_b32_e32 v33, v29
	v_mul_f32_e32 v6, 0.5, v28
	v_mov_b32_e32 v54, v52
	v_mov_b32_e32 v55, v51
	v_pk_mul_f32 v[28:29], v[32:33], s[44:45]
	v_pk_mov_b32 v[56:57], v[50:51], v[52:53] op_sel:[1,0]
	v_pk_mul_f32 v[32:33], v[54:55], v[28:29] op_sel:[0,1] op_sel_hi:[1,0]
	v_pk_mul_f32 v[28:29], v[54:55], v[28:29]
	v_pk_add_f32 v[32:33], v[32:33], v[32:33] op_sel:[0,1] op_sel_hi:[0,1]
	v_pk_add_f32 v[58:59], v[6:7], v[32:33] op_sel_hi:[0,1] neg_hi:[0,1]
	v_pk_add_f32 v[28:29], v[28:29], v[28:29] op_sel:[0,1] op_sel_hi:[0,1] neg_lo:[0,1] neg_hi:[0,1]
	v_pk_add_f32 v[32:33], v[12:13], v[28:29] op_sel_hi:[0,1] neg_hi:[0,1]
	v_pk_mul_f32 v[28:29], v[32:33], v[166:167]
	v_pk_mul_f32 v[32:33], v[32:33], v[164:165]
	v_pk_fma_f32 v[28:29], v[58:59], v[164:165], v[28:29]
	v_pk_fma_f32 v[32:33], v[58:59], v[166:167], v[32:33] neg_lo:[0,0,1] neg_hi:[0,0,1]
	v_mov_b32_e32 v159, v66
	v_pk_add_f32 v[58:59], v[32:33], v[28:29] op_sel:[0,1] op_sel_hi:[1,0] neg_lo:[0,1]
	v_pk_add_f32 v[70:71], v[32:33], v[28:29] op_sel:[0,1] op_sel_hi:[1,0]
	v_pk_add_f32 v[28:29], v[28:29], v[32:33] op_sel:[1,0] op_sel_hi:[0,1] neg_lo:[0,1] neg_hi:[0,1]
	v_pk_mul_f32 v[58:59], v[58:59], 0.5 op_sel_hi:[1,0]
	v_mov_b32_e32 v71, v29
	v_mul_f32_e32 v6, v52, v58
	v_pk_fma_f32 v[72:73], v[54:55], v[58:59], v[6:7] op_sel_hi:[1,1,0] neg_lo:[1,0,0] neg_hi:[1,0,0]
	v_mul_f32_e32 v6, v52, v59
	v_pk_fma_f32 v[56:57], v[56:57], v[58:59], v[6:7] op_sel_hi:[1,1,0]
	v_sub_f32_e32 v12, v67, v153
	v_mov_b32_e32 v72, v56
	v_pk_fma_f32 v[28:29], v[70:71], 0.5, v[56:57] op_sel_hi:[1,0,1] neg_lo:[0,0,1] neg_hi:[0,0,1]
	v_pk_fma_f32 v[96:97], v[70:71], 0.5, v[72:73] op_sel_hi:[1,0,1]
	v_pk_mov_b32 v[56:57], v[48:49], v[152:153] op_sel:[1,0]
	v_mov_b32_e32 v29, v97
	v_pk_mul_f32 v[62:63], v[28:29], s[46:47] op_sel_hi:[1,0]
	v_pk_add_f32 v[28:29], v[66:67], v[152:153]
	v_pk_add_f32 v[56:57], v[158:159], v[56:57] neg_lo:[0,1] neg_hi:[0,1]
	v_mul_f32_e32 v18, 0.5, v29
	v_pk_mul_f32 v[58:59], v[56:57], v[18:19]
	v_mul_f32_e32 v6, 0.5, v28
	v_pk_fma_f32 v[54:55], v[54:55], v[58:59], v[58:59] op_sel:[0,1,0] op_sel_hi:[1,0,1]
	v_mov_b32_e32 v66, v56
	v_mov_b32_e32 v67, v52
	v_mov_b32_e32 v58, v59
	v_mov_b32_e32 v59, v18
	v_pk_mul_f32 v[58:59], v[66:67], v[58:59]
	v_pk_add_f32 v[66:67], v[6:7], v[54:55]
	v_mul_f32_e32 v12, 0.5, v12
	v_fma_f32 v67, v28, 0.5, -v54
	v_pk_add_f32 v[28:29], v[58:59], v[58:59] op_sel:[0,1] op_sel_hi:[0,1] neg_lo:[0,1] neg_hi:[0,1]
	v_pk_add_f32 v[54:55], v[12:13], v[28:29] op_sel_hi:[0,1] neg_hi:[0,1]
	v_pk_mul_f32 v[28:29], v[54:55], v[156:157]
	v_pk_mul_f32 v[54:55], v[54:55], v[154:155]
	v_pk_fma_f32 v[32:33], v[70:71], 0.5, v[72:73] op_sel_hi:[1,0,1] neg_lo:[1,0,0] neg_hi:[1,0,0]
	v_pk_fma_f32 v[58:59], v[66:67], v[154:155], v[28:29] neg_lo:[0,0,1] neg_hi:[0,0,1]
	v_pk_fma_f32 v[28:29], v[66:67], v[154:155], v[28:29]
	v_pk_fma_f32 v[70:71], v[66:67], v[156:157], v[54:55]
	v_pk_fma_f32 v[54:55], v[66:67], v[156:157], v[54:55] neg_lo:[0,0,1] neg_hi:[0,0,1]
	v_pk_add_f32 v[72:73], v[58:59], v[28:29] op_sel:[0,1] op_sel_hi:[1,0]
	v_pk_add_f32 v[66:67], v[70:71], v[54:55] op_sel_hi:[0,1] neg_lo:[0,1] neg_hi:[0,1]
	v_pk_add_f32 v[28:29], v[58:59], v[28:29] op_sel_hi:[0,1] neg_lo:[0,1] neg_hi:[0,1]
	v_pk_add_f32 v[54:55], v[70:71], v[54:55] op_sel:[0,1] op_sel_hi:[1,0]
	v_mov_b32_e32 v73, v67
	v_mov_b32_e32 v55, v29
	v_pk_mul_f32 v[28:29], v[54:55], 0.5 op_sel_hi:[1,0]
	v_mov_b32_e32 v133, v84
	v_pk_mul_f32 v[54:55], v[52:53], v[28:29] op_sel:[0,1] op_sel_hi:[0,0]
	v_pk_fma_f32 v[58:59], v[56:57], v[28:29], v[54:55] op_sel_hi:[0,1,1]
	v_pk_fma_f32 v[28:29], v[56:57], v[28:29], v[54:55] op_sel_hi:[0,1,1] neg_hi:[0,0,1]
	v_pk_fma_f32 v[54:55], v[72:73], 0.5, v[58:59] op_sel_hi:[1,0,1] neg_lo:[0,0,1] neg_hi:[0,0,1]
	v_pk_fma_f32 v[66:67], v[72:73], 0.5, v[28:29] op_sel_hi:[1,0,1]
	v_pk_add_f32 v[56:57], v[60:61], v[134:135] neg_lo:[0,1] neg_hi:[0,1]
	v_mov_b32_e32 v55, v67
	v_pk_mul_f32 v[90:91], v[54:55], s[46:47] op_sel_hi:[1,0]
	v_pk_add_f32 v[54:55], v[134:135], v[60:61]
	v_mul_f32_e32 v12, 0.5, v57
	v_mov_b32_e32 v57, v55
	v_mul_f32_e32 v6, 0.5, v54
	v_pk_mov_b32 v[58:59], v[52:53], v[50:51] op_sel:[1,0]
	v_pk_mul_f32 v[54:55], v[56:57], s[44:45]
	v_pk_fma_f32 v[28:29], v[72:73], 0.5, v[28:29] op_sel_hi:[1,0,1] neg_lo:[1,0,0] neg_hi:[1,0,0]
	v_pk_mul_f32 v[56:57], v[58:59], v[54:55] op_sel:[0,1] op_sel_hi:[1,0]
	v_pk_mul_f32 v[54:55], v[58:59], v[54:55]
	v_pk_add_f32 v[56:57], v[56:57], v[56:57] op_sel:[0,1] op_sel_hi:[0,1]
	v_pk_add_f32 v[60:61], v[6:7], v[56:57] op_sel_hi:[0,1] neg_hi:[0,1]
	v_pk_add_f32 v[54:55], v[54:55], v[54:55] op_sel:[0,1] op_sel_hi:[0,1] neg_lo:[0,1] neg_hi:[0,1]
	v_pk_add_f32 v[56:57], v[12:13], v[54:55] op_sel_hi:[0,1] neg_hi:[0,1]
	v_pk_mul_f32 v[54:55], v[56:57], v[142:143]
	v_pk_mul_f32 v[56:57], v[56:57], v[140:141]
	v_pk_fma_f32 v[54:55], v[60:61], v[140:141], v[54:55]
	v_pk_fma_f32 v[56:57], v[60:61], v[142:143], v[56:57] neg_lo:[0,0,1] neg_hi:[0,0,1]
	v_mov_b32_e32 v51, v53
	v_pk_add_f32 v[60:61], v[56:57], v[54:55] op_sel:[0,1] op_sel_hi:[1,0] neg_lo:[0,1]
	v_pk_add_f32 v[70:71], v[56:57], v[54:55] op_sel:[0,1] op_sel_hi:[1,0]
	v_pk_add_f32 v[54:55], v[54:55], v[56:57] op_sel:[1,0] op_sel_hi:[0,1] neg_lo:[0,1] neg_hi:[0,1]
	v_pk_mul_f32 v[60:61], v[60:61], 0.5 op_sel_hi:[1,0]
	v_mov_b32_e32 v71, v55
	v_mul_f32_e32 v6, v53, v60
	v_pk_fma_f32 v[72:73], v[58:59], v[60:61], v[6:7] op_sel_hi:[1,1,0] neg_lo:[1,0,0] neg_hi:[1,0,0]
	v_mul_f32_e32 v6, v53, v61
	v_pk_fma_f32 v[50:51], v[50:51], v[60:61], v[6:7] op_sel_hi:[1,1,0]
	v_pk_add_f32 v[54:55], v[118:119], v[84:85]
	v_mov_b32_e32 v72, v50
	v_mov_b32_e32 v49, v118
	v_pk_fma_f32 v[50:51], v[70:71], 0.5, v[50:51] op_sel_hi:[1,0,1] neg_lo:[0,0,1] neg_hi:[0,0,1]
	v_pk_fma_f32 v[60:61], v[70:71], 0.5, v[72:73] op_sel_hi:[1,0,1]
	v_mul_f32_e32 v18, 0.5, v55
	v_pk_add_f32 v[48:49], v[132:133], v[48:49] neg_lo:[0,1] neg_hi:[0,1]
	v_mov_b32_e32 v51, v61
	v_pk_mul_f32 v[56:57], v[48:49], v[18:19]
	v_pk_mul_f32 v[94:95], v[50:51], s[46:47] op_sel_hi:[1,0]
	v_pk_fma_f32 v[50:51], v[70:71], 0.5, v[72:73] op_sel_hi:[1,0,1] neg_lo:[1,0,0] neg_hi:[1,0,0]
	v_mul_f32_e32 v6, 0.5, v54
	v_pk_fma_f32 v[58:59], v[58:59], v[56:57], v[56:57] op_sel:[0,1,0] op_sel_hi:[1,0,1]
	v_mov_b32_e32 v70, v48
	v_mov_b32_e32 v71, v53
	v_mov_b32_e32 v56, v57
	v_mov_b32_e32 v57, v18
	v_sub_f32_e32 v12, v85, v119
	v_pk_mul_f32 v[56:57], v[70:71], v[56:57]
	v_pk_add_f32 v[70:71], v[6:7], v[58:59]
	v_mul_f32_e32 v12, 0.5, v12
	v_fma_f32 v71, v54, 0.5, -v58
	v_pk_add_f32 v[54:55], v[56:57], v[56:57] op_sel:[0,1] op_sel_hi:[0,1] neg_lo:[0,1] neg_hi:[0,1]
	v_pk_add_f32 v[56:57], v[12:13], v[54:55] op_sel_hi:[0,1] neg_hi:[0,1]
	v_pk_mul_f32 v[54:55], v[56:57], v[126:127]
	v_pk_mul_f32 v[56:57], v[56:57], v[124:125]
	v_pk_fma_f32 v[58:59], v[70:71], v[124:125], v[54:55] neg_lo:[0,0,1] neg_hi:[0,0,1]
	v_pk_fma_f32 v[54:55], v[70:71], v[124:125], v[54:55]
	v_pk_fma_f32 v[72:73], v[70:71], v[126:127], v[56:57]
	v_pk_fma_f32 v[56:57], v[70:71], v[126:127], v[56:57] neg_lo:[0,0,1] neg_hi:[0,0,1]
	v_pk_add_f32 v[70:71], v[58:59], v[54:55] op_sel:[0,1] op_sel_hi:[1,0]
	v_pk_add_f32 v[74:75], v[72:73], v[56:57] op_sel_hi:[0,1] neg_lo:[0,1] neg_hi:[0,1]
	v_pk_add_f32 v[54:55], v[58:59], v[54:55] op_sel_hi:[0,1] neg_lo:[0,1] neg_hi:[0,1]
	v_pk_add_f32 v[56:57], v[72:73], v[56:57] op_sel:[0,1] op_sel_hi:[1,0]
	v_mov_b32_e32 v71, v75
	v_mov_b32_e32 v57, v55
	v_pk_mul_f32 v[54:55], v[56:57], 0.5 op_sel_hi:[1,0]
	s_mov_b32 s66, s11
	v_pk_mul_f32 v[52:53], v[52:53], v[54:55] op_sel:[1,1] op_sel_hi:[1,0]
	s_mov_b32 s67, s8
	v_pk_fma_f32 v[56:57], v[48:49], v[54:55], v[52:53] op_sel_hi:[0,1,1]
	v_pk_fma_f32 v[48:49], v[48:49], v[54:55], v[52:53] op_sel_hi:[0,1,1] neg_hi:[0,0,1]
	s_nop 0
	v_pk_fma_f32 v[52:53], v[70:71], 0.5, v[56:57] op_sel_hi:[1,0,1] neg_lo:[0,0,1] neg_hi:[0,0,1]
	v_pk_fma_f32 v[84:85], v[70:71], 0.5, v[48:49] op_sel_hi:[1,0,1]
	s_mov_b32 s9, s11
	v_mov_b32_e32 v53, v85
	v_pk_mul_f32 v[80:81], v[52:53], s[46:47] op_sel_hi:[1,0]
	v_pk_mul_f32 v[118:119], v[82:83], s[66:67] op_sel_hi:[0,1]
	v_pk_add_f32 v[52:53], v[86:87], v[112:113]
	v_pk_add_f32 v[54:55], v[86:87], v[112:113] neg_lo:[0,1] neg_hi:[0,1]
	v_pk_fma_f32 v[58:59], v[4:5], s[8:9], v[118:119] op_sel_hi:[0,1,1] neg_lo:[0,0,1] neg_hi:[0,0,1]
	v_mul_f32_e32 v12, 0.5, v55
	v_pk_fma_f32 v[72:73], v[4:5], s[8:9], v[118:119] op_sel_hi:[0,1,1]
	v_mov_b32_e32 v55, v53
	v_mul_f32_e32 v6, 0.5, v52
	v_mov_b32_e32 v56, v58
	v_mov_b32_e32 v57, v73
	v_pk_mul_f32 v[52:53], v[54:55], s[44:45]
	v_pk_fma_f32 v[48:49], v[70:71], 0.5, v[48:49] op_sel_hi:[1,0,1] neg_lo:[1,0,0] neg_hi:[1,0,0]
	v_pk_mul_f32 v[54:55], v[56:57], v[52:53] op_sel:[0,1] op_sel_hi:[1,0]
	v_pk_mul_f32 v[52:53], v[56:57], v[52:53]
	v_pk_add_f32 v[54:55], v[54:55], v[54:55] op_sel:[0,1] op_sel_hi:[0,1]
	v_pk_add_f32 v[74:75], v[6:7], v[54:55] op_sel_hi:[0,1] neg_hi:[0,1]
	v_pk_add_f32 v[52:53], v[52:53], v[52:53] op_sel:[0,1] op_sel_hi:[0,1] neg_lo:[0,1] neg_hi:[0,1]
	v_pk_add_f32 v[54:55], v[12:13], v[52:53] op_sel_hi:[0,1] neg_hi:[0,1]
	v_pk_mul_f32 v[52:53], v[54:55], v[116:117]
	v_pk_mul_f32 v[54:55], v[54:55], v[114:115]
	v_pk_fma_f32 v[52:53], v[74:75], v[114:115], v[52:53]
	v_pk_fma_f32 v[54:55], v[74:75], v[116:117], v[54:55] neg_lo:[0,0,1] neg_hi:[0,0,1]
	v_pk_mov_b32 v[70:71], v[72:73], v[58:59] op_sel:[1,0]
	v_pk_add_f32 v[74:75], v[54:55], v[52:53] op_sel:[0,1] op_sel_hi:[1,0] neg_lo:[0,1]
	v_pk_add_f32 v[76:77], v[54:55], v[52:53] op_sel:[0,1] op_sel_hi:[1,0]
	v_pk_add_f32 v[52:53], v[52:53], v[54:55] op_sel:[1,0] op_sel_hi:[0,1] neg_lo:[0,1] neg_hi:[0,1]
	v_pk_mul_f32 v[74:75], v[74:75], 0.5 op_sel_hi:[1,0]
	v_mov_b32_e32 v77, v53
	v_mul_f32_e32 v6, v58, v74
	v_pk_fma_f32 v[112:113], v[56:57], v[74:75], v[6:7] op_sel_hi:[1,1,0] neg_lo:[1,0,0] neg_hi:[1,0,0]
	v_mul_f32_e32 v6, v58, v75
	v_pk_fma_f32 v[70:71], v[70:71], v[74:75], v[6:7] op_sel_hi:[1,1,0]
	v_pk_add_f32 v[54:55], v[34:35], v[110:111]
	v_mov_b32_e32 v112, v70
	v_pk_fma_f32 v[52:53], v[76:77], 0.5, v[70:71] op_sel_hi:[1,0,1] neg_lo:[0,0,1] neg_hi:[0,0,1]
	v_pk_fma_f32 v[86:87], v[76:77], 0.5, v[112:113] op_sel_hi:[1,0,1]
	v_sub_f32_e32 v12, v35, v111
	v_mov_b32_e32 v53, v87
	v_pk_mul_f32 v[78:79], v[52:53], s[46:47] op_sel_hi:[1,0]
	v_mul_f32_e32 v52, 0xbe47c5c2, v83
	v_mov_b32_e32 v53, v34
	v_pk_mov_b32 v[34:35], v[118:119], v[110:111] op_sel:[1,0]
	v_mul_f32_e32 v18, 0.5, v55
	v_pk_add_f32 v[34:35], v[52:53], v[34:35] neg_lo:[0,1] neg_hi:[0,1]
	v_mov_b32_e32 v71, v58
	v_pk_mul_f32 v[52:53], v[34:35], v[18:19]
	v_mov_b32_e32 v70, v34
	v_pk_fma_f32 v[56:57], v[56:57], v[52:53], v[52:53] op_sel:[0,1,0] op_sel_hi:[1,0,1]
	v_mov_b32_e32 v52, v53
	v_mov_b32_e32 v53, v18
	v_mul_f32_e32 v6, 0.5, v54
	v_pk_mul_f32 v[52:53], v[70:71], v[52:53]
	v_cvt_f32_f16_e32 v70, v46
	v_cvt_f32_f16_e32 v71, v47
	v_cvt_f32_f16_sdwa v47, v47 dst_sel:DWORD dst_unused:UNUSED_PAD src0_sel:WORD_1
	v_cvt_f32_f16_sdwa v46, v46 dst_sel:DWORD dst_unused:UNUSED_PAD src0_sel:WORD_1
	v_pk_fma_f32 v[74:75], v[76:77], 0.5, v[112:113] op_sel_hi:[1,0,1] neg_lo:[1,0,0] neg_hi:[1,0,0]
	v_mul_f32_e32 v12, 0.5, v12
	v_pk_add_f32 v[76:77], v[6:7], v[56:57]
	v_pk_add_f32 v[52:53], v[52:53], v[52:53] op_sel:[0,1] op_sel_hi:[0,1] neg_lo:[0,1] neg_hi:[0,1]
	v_fma_f32 v77, v54, 0.5, -v56
	v_pk_add_f32 v[54:55], v[12:13], v[52:53] op_sel_hi:[0,1] neg_hi:[0,1]
	v_pk_mul_f32 v[52:53], v[54:55], v[46:47]
	v_pk_mul_f32 v[54:55], v[54:55], v[70:71]
	v_pk_fma_f32 v[56:57], v[76:77], v[70:71], v[52:53] neg_lo:[0,0,1] neg_hi:[0,0,1]
	v_pk_fma_f32 v[52:53], v[76:77], v[70:71], v[52:53]
	v_pk_fma_f32 v[70:71], v[76:77], v[46:47], v[54:55]
	v_pk_fma_f32 v[46:47], v[76:77], v[46:47], v[54:55] neg_lo:[0,0,1] neg_hi:[0,0,1]
	v_pk_add_f32 v[54:55], v[56:57], v[52:53] op_sel:[0,1] op_sel_hi:[1,0]
	v_pk_add_f32 v[76:77], v[70:71], v[46:47] op_sel_hi:[0,1] neg_lo:[0,1] neg_hi:[0,1]
	v_pk_add_f32 v[52:53], v[56:57], v[52:53] op_sel_hi:[0,1] neg_lo:[0,1] neg_hi:[0,1]
	v_pk_add_f32 v[46:47], v[70:71], v[46:47] op_sel:[0,1] op_sel_hi:[1,0]
	v_mov_b32_e32 v55, v77
	v_mov_b32_e32 v47, v53
	v_pk_mul_f32 v[46:47], v[46:47], 0.5 op_sel_hi:[1,0]
	s_mov_b32 s25, s27
	v_pk_mul_f32 v[52:53], v[58:59], v[46:47] op_sel:[0,1] op_sel_hi:[0,0]
	v_pk_fma_f32 v[56:57], v[34:35], v[46:47], v[52:53] op_sel_hi:[0,1,1]
	v_pk_fma_f32 v[46:47], v[34:35], v[46:47], v[52:53] op_sel_hi:[0,1,1] neg_hi:[0,0,1]
	s_nop 0
	v_pk_fma_f32 v[52:53], v[54:55], 0.5, v[56:57] op_sel_hi:[1,0,1] neg_lo:[0,0,1] neg_hi:[0,0,1]
	v_pk_fma_f32 v[34:35], v[54:55], 0.5, v[46:47] op_sel_hi:[1,0,1]
	s_mov_b32 s66, s27
	v_mov_b32_e32 v53, v35
	v_pk_mul_f32 v[136:137], v[52:53], s[46:47] op_sel_hi:[1,0]
	v_pk_fma_f32 v[52:53], v[54:55], 0.5, v[46:47] op_sel_hi:[1,0,1] neg_lo:[1,0,0] neg_hi:[1,0,0]
	s_mov_b32 s67, s24
	v_pk_mul_f32 v[46:47], v[82:83], s[24:25] op_sel_hi:[0,1]
	v_pk_add_f32 v[54:55], v[108:109], v[40:41]
	v_pk_add_f32 v[40:41], v[40:41], v[108:109] neg_lo:[0,1] neg_hi:[0,1]
	v_pk_fma_f32 v[108:109], v[4:5], s[66:67], v[46:47] op_sel_hi:[0,1,1] neg_lo:[0,0,1] neg_hi:[0,0,1]
	v_mul_f32_e32 v12, 0.5, v41
	v_pk_fma_f32 v[70:71], v[4:5], s[66:67], v[46:47] op_sel_hi:[0,1,1]
	v_mov_b32_e32 v41, v55
	v_mov_b32_e32 v56, v108
	v_mov_b32_e32 v57, v71
	v_pk_mul_f32 v[40:41], v[40:41], s[44:45]
	v_mul_f32_e32 v6, 0.5, v54
	v_pk_mul_f32 v[54:55], v[56:57], v[40:41] op_sel:[0,1] op_sel_hi:[1,0]
	v_cvt_f32_f16_sdwa v76, v38 dst_sel:DWORD dst_unused:UNUSED_PAD src0_sel:WORD_1
	v_cvt_f32_f16_e32 v77, v39
	v_cvt_f32_f16_sdwa v39, v39 dst_sel:DWORD dst_unused:UNUSED_PAD src0_sel:WORD_1
	v_cvt_f32_f16_e32 v38, v38
	v_pk_mul_f32 v[40:41], v[56:57], v[40:41]
	v_pk_add_f32 v[54:55], v[54:55], v[54:55] op_sel:[0,1] op_sel_hi:[0,1]
	v_pk_add_f32 v[112:113], v[6:7], v[54:55] op_sel_hi:[0,1] neg_hi:[0,1]
	s_nop 0
	v_pk_add_f32 v[40:41], v[40:41], v[40:41] op_sel:[0,1] op_sel_hi:[0,1] neg_lo:[0,1] neg_hi:[0,1]
	v_pk_add_f32 v[54:55], v[12:13], v[40:41] op_sel_hi:[0,1] neg_hi:[0,1]
	v_pk_mul_f32 v[40:41], v[54:55], v[38:39]
	v_pk_mul_f32 v[54:55], v[54:55], v[76:77]
	v_pk_fma_f32 v[40:41], v[112:113], v[76:77], v[40:41]
	v_pk_fma_f32 v[38:39], v[112:113], v[38:39], v[54:55] neg_lo:[0,0,1] neg_hi:[0,0,1]
	v_pk_mov_b32 v[110:111], v[70:71], v[108:109] op_sel:[1,0]
	v_pk_add_f32 v[54:55], v[38:39], v[40:41] op_sel:[0,1] op_sel_hi:[1,0] neg_lo:[0,1]
	v_pk_add_f32 v[76:77], v[38:39], v[40:41] op_sel:[0,1] op_sel_hi:[1,0]
	v_pk_add_f32 v[38:39], v[40:41], v[38:39] op_sel:[1,0] op_sel_hi:[0,1] neg_lo:[0,1] neg_hi:[0,1]
	v_pk_mul_f32 v[54:55], v[54:55], 0.5 op_sel_hi:[1,0]
	v_mov_b32_e32 v77, v39
	v_mul_f32_e32 v4, v108, v54
	v_pk_fma_f32 v[112:113], v[56:57], v[54:55], v[4:5] op_sel_hi:[1,1,0] neg_lo:[1,0,0] neg_hi:[1,0,0]
	v_mul_f32_e32 v4, v108, v55
	v_pk_fma_f32 v[54:55], v[110:111], v[54:55], v[4:5] op_sel_hi:[1,1,0]
	v_sub_f32_e32 v6, v45, v105
	v_mov_b32_e32 v112, v54
	v_pk_fma_f32 v[40:41], v[76:77], 0.5, v[54:55] op_sel_hi:[1,0,1] neg_lo:[0,0,1] neg_hi:[0,0,1]
	v_pk_fma_f32 v[38:39], v[76:77], 0.5, v[112:113] op_sel_hi:[1,0,1]
	v_pk_add_f32 v[54:55], v[104:105], v[44:45]
	v_mov_b32_e32 v41, v39
	v_pk_mul_f32 v[130:131], v[40:41], s[46:47] op_sel_hi:[1,0]
	v_mul_f32_e32 v40, 0xbf54db31, v83
	v_mov_b32_e32 v41, v44
	v_pk_mov_b32 v[44:45], v[46:47], v[104:105] op_sel:[1,0]
	v_mul_f32_e32 v18, 0.5, v55
	v_pk_add_f32 v[40:41], v[40:41], v[44:45] neg_lo:[0,1] neg_hi:[0,1]
	v_mov_b32_e32 v105, v108
	v_pk_mul_f32 v[44:45], v[40:41], v[18:19]
	v_mov_b32_e32 v104, v40
	v_pk_fma_f32 v[56:57], v[56:57], v[44:45], v[44:45] op_sel:[0,1,0] op_sel_hi:[1,0,1]
	v_mov_b32_e32 v44, v45
	v_mov_b32_e32 v45, v18
	v_mul_f32_e32 v4, 0.5, v54
	v_pk_mul_f32 v[44:45], v[104:105], v[44:45]
	v_cvt_f32_f16_e32 v104, v26
	v_cvt_f32_f16_e32 v105, v27
	v_cvt_f32_f16_sdwa v27, v27 dst_sel:DWORD dst_unused:UNUSED_PAD src0_sel:WORD_1
	v_cvt_f32_f16_sdwa v26, v26 dst_sel:DWORD dst_unused:UNUSED_PAD src0_sel:WORD_1
	v_mul_f32_e32 v6, 0.5, v6
	v_pk_add_f32 v[110:111], v[4:5], v[56:57]
	v_pk_add_f32 v[44:45], v[44:45], v[44:45] op_sel:[0,1] op_sel_hi:[0,1] neg_lo:[0,1] neg_hi:[0,1]
	v_fma_f32 v111, v54, 0.5, -v56
	v_pk_add_f32 v[54:55], v[6:7], v[44:45] op_sel_hi:[0,1] neg_hi:[0,1]
	v_pk_mul_f32 v[44:45], v[54:55], v[26:27]
	v_pk_mul_f32 v[54:55], v[54:55], v[104:105]
	v_pk_fma_f32 v[56:57], v[110:111], v[104:105], v[44:45] neg_lo:[0,0,1] neg_hi:[0,0,1]
	v_pk_fma_f32 v[44:45], v[110:111], v[104:105], v[44:45]
	v_pk_fma_f32 v[104:105], v[110:111], v[26:27], v[54:55]
	v_pk_fma_f32 v[26:27], v[110:111], v[26:27], v[54:55] neg_lo:[0,0,1] neg_hi:[0,0,1]
	v_pk_add_f32 v[54:55], v[56:57], v[44:45] op_sel:[0,1] op_sel_hi:[1,0]
	v_pk_add_f32 v[110:111], v[104:105], v[26:27] op_sel_hi:[0,1] neg_lo:[0,1] neg_hi:[0,1]
	v_pk_add_f32 v[44:45], v[56:57], v[44:45] op_sel_hi:[0,1] neg_lo:[0,1] neg_hi:[0,1]
	v_pk_add_f32 v[26:27], v[104:105], v[26:27] op_sel:[0,1] op_sel_hi:[1,0]
	v_mov_b32_e32 v55, v111
	v_mov_b32_e32 v27, v45
	v_pk_mul_f32 v[26:27], v[26:27], 0.5 op_sel_hi:[1,0]
	v_mov_b32_e32 v47, v102
	v_pk_mul_f32 v[44:45], v[108:109], v[26:27] op_sel:[0,1] op_sel_hi:[0,0]
	v_pk_fma_f32 v[56:57], v[40:41], v[26:27], v[44:45] op_sel_hi:[0,1,1]
	v_pk_fma_f32 v[40:41], v[40:41], v[26:27], v[44:45] op_sel_hi:[0,1,1] neg_hi:[0,0,1]
	v_pk_fma_f32 v[44:45], v[54:55], 0.5, v[56:57] op_sel_hi:[1,0,1] neg_lo:[0,0,1] neg_hi:[0,0,1]
	v_pk_fma_f32 v[26:27], v[54:55], 0.5, v[40:41] op_sel_hi:[1,0,1]
	v_pk_fma_f32 v[56:57], v[54:55], 0.5, v[40:41] op_sel_hi:[1,0,1] neg_lo:[1,0,0] neg_hi:[1,0,0]
	v_pk_add_f32 v[40:41], v[106:107], v[42:43]
	v_pk_add_f32 v[42:43], v[42:43], v[106:107] neg_lo:[0,1] neg_hi:[0,1]
	v_mov_b32_e32 v45, v27
	v_mul_f32_e32 v6, 0.5, v43
	v_mov_b32_e32 v43, v41
	v_pk_mul_f32 v[120:121], v[44:45], s[46:47] op_sel_hi:[1,0]
	v_mul_f32_e32 v4, 0.5, v40
	v_pk_mov_b32 v[44:45], v[108:109], v[70:71] op_sel:[1,0]
	v_pk_mul_f32 v[40:41], v[42:43], s[44:45]
	v_cvt_f32_f16_sdwa v54, v20 dst_sel:DWORD dst_unused:UNUSED_PAD src0_sel:WORD_1
	v_pk_mul_f32 v[42:43], v[44:45], v[40:41] op_sel:[0,1] op_sel_hi:[1,0]
	v_cvt_f32_f16_e32 v55, v21
	v_cvt_f32_f16_sdwa v21, v21 dst_sel:DWORD dst_unused:UNUSED_PAD src0_sel:WORD_1
	v_cvt_f32_f16_e32 v20, v20
	v_pk_mul_f32 v[40:41], v[44:45], v[40:41]
	v_pk_add_f32 v[42:43], v[42:43], v[42:43] op_sel:[0,1] op_sel_hi:[0,1]
	v_pk_add_f32 v[104:105], v[4:5], v[42:43] op_sel_hi:[0,1] neg_hi:[0,1]
	s_nop 0
	v_pk_add_f32 v[40:41], v[40:41], v[40:41] op_sel:[0,1] op_sel_hi:[0,1] neg_lo:[0,1] neg_hi:[0,1]
	v_pk_add_f32 v[42:43], v[6:7], v[40:41] op_sel_hi:[0,1] neg_hi:[0,1]
	v_pk_mul_f32 v[40:41], v[42:43], v[20:21]
	v_pk_mul_f32 v[42:43], v[42:43], v[54:55]
	v_pk_fma_f32 v[40:41], v[104:105], v[54:55], v[40:41]
	v_pk_fma_f32 v[20:21], v[104:105], v[20:21], v[42:43] neg_lo:[0,0,1] neg_hi:[0,0,1]
	v_mov_b32_e32 v71, v109
	v_pk_add_f32 v[42:43], v[20:21], v[40:41] op_sel:[0,1] op_sel_hi:[1,0] neg_lo:[0,1]
	v_pk_add_f32 v[54:55], v[20:21], v[40:41] op_sel:[0,1] op_sel_hi:[1,0]
	v_pk_add_f32 v[20:21], v[40:41], v[20:21] op_sel:[1,0] op_sel_hi:[0,1] neg_lo:[0,1] neg_hi:[0,1]
	v_pk_mul_f32 v[42:43], v[42:43], 0.5 op_sel_hi:[1,0]
	v_mov_b32_e32 v55, v21
	v_mul_f32_e32 v4, v109, v42
	v_pk_fma_f32 v[104:105], v[44:45], v[42:43], v[4:5] op_sel_hi:[1,1,0] neg_lo:[1,0,0] neg_hi:[1,0,0]
	v_mul_f32_e32 v4, v109, v43
	v_pk_fma_f32 v[42:43], v[70:71], v[42:43], v[4:5] op_sel_hi:[1,1,0]
	v_sub_f32_e32 v6, v23, v103
	v_mov_b32_e32 v104, v42
	v_pk_fma_f32 v[40:41], v[54:55], 0.5, v[42:43] op_sel_hi:[1,0,1] neg_lo:[0,0,1] neg_hi:[0,0,1]
	v_pk_fma_f32 v[20:21], v[54:55], 0.5, v[104:105] op_sel_hi:[1,0,1]
	v_pk_add_f32 v[42:43], v[102:103], v[22:23]
	v_mov_b32_e32 v41, v21
	v_pk_mul_f32 v[128:129], v[40:41], s[46:47] op_sel_hi:[1,0]
	v_mul_f32_e32 v40, 0xbf0e39da, v83
	v_mov_b32_e32 v41, v22
	v_mul_f32_e32 v18, 0.5, v43
	v_pk_add_f32 v[22:23], v[40:41], v[46:47] neg_lo:[0,1] neg_hi:[0,1]
	v_mov_b32_e32 v47, v109
	v_pk_mul_f32 v[40:41], v[22:23], v[18:19]
	v_mov_b32_e32 v46, v22
	v_pk_fma_f32 v[44:45], v[44:45], v[40:41], v[40:41] op_sel:[0,1,0] op_sel_hi:[1,0,1]
	v_mov_b32_e32 v40, v41
	v_mov_b32_e32 v41, v18
	v_mul_f32_e32 v4, 0.5, v42
	v_pk_mul_f32 v[40:41], v[46:47], v[40:41]
	v_cvt_f32_f16_e32 v46, v10
	v_cvt_f32_f16_e32 v47, v11
	v_cvt_f32_f16_sdwa v11, v11 dst_sel:DWORD dst_unused:UNUSED_PAD src0_sel:WORD_1
	v_cvt_f32_f16_sdwa v10, v10 dst_sel:DWORD dst_unused:UNUSED_PAD src0_sel:WORD_1
	v_pk_fma_f32 v[70:71], v[54:55], 0.5, v[104:105] op_sel_hi:[1,0,1] neg_lo:[1,0,0] neg_hi:[1,0,0]
	v_mul_f32_e32 v6, 0.5, v6
	v_pk_add_f32 v[54:55], v[4:5], v[44:45]
	v_pk_add_f32 v[40:41], v[40:41], v[40:41] op_sel:[0,1] op_sel_hi:[0,1] neg_lo:[0,1] neg_hi:[0,1]
	v_fma_f32 v55, v42, 0.5, -v44
	v_pk_add_f32 v[42:43], v[6:7], v[40:41] op_sel_hi:[0,1] neg_hi:[0,1]
	v_pk_mul_f32 v[40:41], v[42:43], v[10:11]
	v_pk_mul_f32 v[42:43], v[42:43], v[46:47]
	v_pk_fma_f32 v[44:45], v[54:55], v[46:47], v[40:41] neg_lo:[0,0,1] neg_hi:[0,0,1]
	v_pk_fma_f32 v[40:41], v[54:55], v[46:47], v[40:41]
	v_pk_fma_f32 v[46:47], v[54:55], v[10:11], v[42:43]
	v_pk_fma_f32 v[10:11], v[54:55], v[10:11], v[42:43] neg_lo:[0,0,1] neg_hi:[0,0,1]
	v_pk_add_f32 v[42:43], v[44:45], v[40:41] op_sel:[0,1] op_sel_hi:[1,0]
	v_pk_add_f32 v[54:55], v[46:47], v[10:11] op_sel_hi:[0,1] neg_lo:[0,1] neg_hi:[0,1]
	v_pk_add_f32 v[40:41], v[44:45], v[40:41] op_sel_hi:[0,1] neg_lo:[0,1] neg_hi:[0,1]
	v_pk_add_f32 v[10:11], v[46:47], v[10:11] op_sel:[0,1] op_sel_hi:[1,0]
	v_mov_b32_e32 v43, v55
	v_mov_b32_e32 v11, v41
	v_pk_mul_f32 v[10:11], v[10:11], 0.5 op_sel_hi:[1,0]
	v_mov_b32_e32 v119, v98
	v_pk_mul_f32 v[40:41], v[108:109], v[10:11] op_sel:[1,1] op_sel_hi:[1,0]
	v_pk_fma_f32 v[76:77], v[76:77], 0.5, v[112:113] op_sel_hi:[1,0,1] neg_lo:[1,0,0] neg_hi:[1,0,0]
	v_pk_fma_f32 v[44:45], v[22:23], v[10:11], v[40:41] op_sel_hi:[0,1,1]
	v_pk_fma_f32 v[10:11], v[22:23], v[10:11], v[40:41] op_sel_hi:[0,1,1] neg_hi:[0,0,1]
	v_pk_fma_f32 v[22:23], v[42:43], 0.5, v[44:45] op_sel_hi:[1,0,1] neg_lo:[0,0,1] neg_hi:[0,0,1]
	v_pk_fma_f32 v[40:41], v[42:43], 0.5, v[10:11] op_sel_hi:[1,0,1]
	v_pk_fma_f32 v[54:55], v[42:43], 0.5, v[10:11] op_sel_hi:[1,0,1] neg_lo:[1,0,0] neg_hi:[1,0,0]
	v_pk_add_f32 v[10:11], v[100:101], v[14:15]
	v_pk_add_f32 v[14:15], v[14:15], v[100:101] neg_lo:[0,1] neg_hi:[0,1]
	v_mov_b32_e32 v23, v41
	v_mul_f32_e32 v6, 0.5, v15
	v_mov_b32_e32 v15, v11
	v_pk_mul_f32 v[150:151], v[22:23], s[46:47] op_sel_hi:[1,0]
	v_mul_f32_e32 v4, 0.5, v10
	v_pk_mov_b32 v[22:23], v[58:59], v[72:73] op_sel:[1,0]
	v_pk_mul_f32 v[10:11], v[14:15], s[44:45]
	v_cvt_f32_f16_sdwa v42, v8 dst_sel:DWORD dst_unused:UNUSED_PAD src0_sel:WORD_1
	v_pk_mul_f32 v[14:15], v[22:23], v[10:11] op_sel:[0,1] op_sel_hi:[1,0]
	v_cvt_f32_f16_e32 v43, v9
	v_cvt_f32_f16_sdwa v9, v9 dst_sel:DWORD dst_unused:UNUSED_PAD src0_sel:WORD_1
	v_cvt_f32_f16_e32 v8, v8
	v_pk_mul_f32 v[10:11], v[22:23], v[10:11]
	v_pk_add_f32 v[14:15], v[14:15], v[14:15] op_sel:[0,1] op_sel_hi:[0,1]
	v_pk_add_f32 v[44:45], v[4:5], v[14:15] op_sel_hi:[0,1] neg_hi:[0,1]
	s_nop 0
	v_pk_add_f32 v[10:11], v[10:11], v[10:11] op_sel:[0,1] op_sel_hi:[0,1] neg_lo:[0,1] neg_hi:[0,1]
	v_pk_add_f32 v[14:15], v[6:7], v[10:11] op_sel_hi:[0,1] neg_hi:[0,1]
	v_pk_mul_f32 v[10:11], v[14:15], v[8:9]
	v_pk_mul_f32 v[14:15], v[14:15], v[42:43]
	v_pk_fma_f32 v[10:11], v[44:45], v[42:43], v[10:11]
	v_pk_fma_f32 v[8:9], v[44:45], v[8:9], v[14:15] neg_lo:[0,0,1] neg_hi:[0,0,1]
	v_mov_b32_e32 v73, v59
	v_pk_add_f32 v[14:15], v[8:9], v[10:11] op_sel:[0,1] op_sel_hi:[1,0] neg_lo:[0,1]
	v_pk_add_f32 v[42:43], v[8:9], v[10:11] op_sel:[0,1] op_sel_hi:[1,0]
	v_pk_add_f32 v[8:9], v[10:11], v[8:9] op_sel:[1,0] op_sel_hi:[0,1] neg_lo:[0,1] neg_hi:[0,1]
	v_pk_mul_f32 v[14:15], v[14:15], 0.5 op_sel_hi:[1,0]
	v_mov_b32_e32 v43, v9
	v_mul_f32_e32 v4, v59, v14
	v_pk_fma_f32 v[44:45], v[22:23], v[14:15], v[4:5] op_sel_hi:[1,1,0] neg_lo:[1,0,0] neg_hi:[1,0,0]
	v_mul_f32_e32 v4, v59, v15
	v_pk_fma_f32 v[14:15], v[72:73], v[14:15], v[4:5] op_sel_hi:[1,1,0]
	v_sub_f32_e32 v6, v37, v99
	v_mov_b32_e32 v44, v14
	v_pk_fma_f32 v[8:9], v[42:43], 0.5, v[14:15] op_sel_hi:[1,0,1] neg_lo:[0,0,1] neg_hi:[0,0,1]
	v_pk_fma_f32 v[10:11], v[42:43], 0.5, v[44:45] op_sel_hi:[1,0,1]
	v_pk_add_f32 v[14:15], v[98:99], v[36:37]
	v_mov_b32_e32 v9, v11
	v_pk_mul_f32 v[168:169], v[8:9], s[46:47] op_sel_hi:[1,0]
	v_mul_f32_e32 v8, 0xbf7b14be, v83
	v_mov_b32_e32 v9, v36
	v_mul_f32_e32 v18, 0.5, v15
	v_pk_add_f32 v[8:9], v[8:9], v[118:119] neg_lo:[0,1] neg_hi:[0,1]
	v_pk_fma_f32 v[72:73], v[42:43], 0.5, v[44:45] op_sel_hi:[1,0,1] neg_lo:[1,0,0] neg_hi:[1,0,0]
	v_pk_mul_f32 v[36:37], v[8:9], v[18:19]
	v_mov_b32_e32 v42, v8
	v_pk_fma_f32 v[22:23], v[22:23], v[36:37], v[36:37] op_sel:[0,1,0] op_sel_hi:[1,0,1]
	v_mov_b32_e32 v43, v59
	v_mov_b32_e32 v36, v37
	v_mov_b32_e32 v37, v18
	v_mul_f32_e32 v4, 0.5, v14
	v_pk_mul_f32 v[36:37], v[42:43], v[36:37]
	v_cvt_f32_f16_e32 v44, v2
	v_cvt_f32_f16_e32 v45, v3
	v_cvt_f32_f16_sdwa v3, v3 dst_sel:DWORD dst_unused:UNUSED_PAD src0_sel:WORD_1
	v_cvt_f32_f16_sdwa v2, v2 dst_sel:DWORD dst_unused:UNUSED_PAD src0_sel:WORD_1
	v_mul_f32_e32 v6, 0.5, v6
	v_pk_add_f32 v[46:47], v[4:5], v[22:23]
	v_fma_f32 v4, v14, 0.5, -v22
	v_pk_add_f32 v[22:23], v[36:37], v[36:37] op_sel:[0,1] op_sel_hi:[0,1] neg_lo:[0,1] neg_hi:[0,1]
	v_pk_add_f32 v[36:37], v[6:7], v[22:23] op_sel_hi:[0,1] neg_hi:[0,1]
	v_mov_b32_e32 v14, v46
	v_mov_b32_e32 v15, v4
	v_pk_mul_f32 v[22:23], v[4:5], v[44:45] op_sel_hi:[0,1]
	v_pk_mul_f32 v[82:83], v[36:37], v[2:3]
	v_pk_mul_f32 v[46:47], v[46:47], v[2:3]
	v_pk_mul_f32 v[36:37], v[36:37], v[44:45]
	v_pk_fma_f32 v[98:99], v[14:15], v[44:45], v[82:83] neg_lo:[0,0,1] neg_hi:[0,0,1]
	v_pk_fma_f32 v[2:3], v[14:15], v[2:3], v[36:37] neg_lo:[0,0,1] neg_hi:[0,0,1]
	v_add_f32_e32 v4, v23, v83
	v_add_f32_e32 v6, v46, v36
	v_pk_add_f32 v[22:23], v[6:7], v[2:3] op_sel_hi:[0,1] neg_lo:[0,1] neg_hi:[0,1]
	v_pk_add_f32 v[36:37], v[98:99], v[4:5] op_sel_hi:[1,0] neg_lo:[0,1] neg_hi:[0,1]
	v_pk_add_f32 v[2:3], v[6:7], v[2:3] op_sel_hi:[0,1]
	v_mov_b32_e32 v37, v3
	v_pk_mul_f32 v[2:3], v[36:37], 0.5 op_sel_hi:[1,0]
	v_pk_add_f32 v[14:15], v[98:99], v[4:5] op_sel_hi:[1,0]
	v_mul_f32_e32 v4, v59, v3
	v_pk_fma_f32 v[36:37], v[42:43], v[2:3], v[4:5] op_sel_hi:[1,1,0] neg_lo:[0,0,1] neg_hi:[0,0,1]
	v_pk_mov_b32 v[42:43], v[58:59], v[8:9] op_sel:[1,0]
	v_mul_f32_e32 v4, v8, v3
	v_pk_fma_f32 v[2:3], v[42:43], v[2:3], v[4:5] op_sel_hi:[1,1,0]
	v_mov_b32_e32 v15, v23
	v_pk_fma_f32 v[8:9], v[14:15], 0.5, v[2:3] op_sel_hi:[1,0,1] neg_lo:[0,0,1] neg_hi:[0,0,1]
	v_pk_fma_f32 v[42:43], v[14:15], 0.5, v[36:37] op_sel_hi:[1,0,0]
	v_pk_fma_f32 v[2:3], v[14:15], 0.5, v[2:3] op_sel_hi:[1,0,1]
	v_mov_b32_e32 v9, v43
	v_pk_fma_f32 v[58:59], v[22:23], 0.5, v[36:37] op_sel_hi:[1,0,0] neg_lo:[1,0,0] neg_hi:[1,0,0]
	v_pk_mul_f32 v[144:145], v[8:9], s[46:47] op_sel_hi:[1,0]
	v_mov_b32_e32 v58, v2
	v_mov_b32_e32 v72, v10
	v_mov_b32_e32 v54, v40
	v_mov_b32_e32 v70, v20
	v_mov_b32_e32 v56, v26
	v_mov_b32_e32 v76, v38
	v_mov_b32_e32 v52, v34
	v_mov_b32_e32 v74, v86
	v_mov_b32_e32 v48, v84
	v_mov_b32_e32 v50, v60
	v_mov_b32_e32 v28, v66
	v_mov_b32_e32 v32, v96
	v_mov_b32_e32 v12, v88
	v_mov_b32_e32 v16, v92
	v_mov_b32_e32 v4, v138
	v_mov_b32_e32 v6, v122

.LBB0_538:
	s_or_b64 exec, exec, s[0:1]
	v_pk_mul_f32 v[22:23], v[32:33], s[46:47] op_sel_hi:[1,0]
	v_pk_add_f32 v[26:27], v[24:25], v[30:31]
	v_pk_add_f32 v[24:25], v[24:25], v[30:31] neg_lo:[0,1] neg_hi:[0,1]
	v_pk_add_f32 v[30:31], v[64:65], v[68:69]
	v_pk_add_f32 v[32:33], v[64:65], v[68:69] neg_lo:[0,1] neg_hi:[0,1]
	v_pk_add_f32 v[34:35], v[62:63], v[90:91]
	v_pk_add_f32 v[38:39], v[94:95], v[80:81]
	v_pk_add_f32 v[68:69], v[26:27], v[30:31]
	v_pk_add_f32 v[26:27], v[26:27], v[30:31] neg_lo:[0,1] neg_hi:[0,1]
	v_xor_b32_e32 v30, 0x80000000, v33
	v_mov_b32_e32 v31, v32
	v_pk_mul_f32 v[20:21], v[50:51], s[46:47] op_sel_hi:[1,0]
	v_pk_add_f32 v[36:37], v[62:63], v[90:91] neg_lo:[0,1] neg_hi:[0,1]
	v_pk_add_f32 v[42:43], v[78:79], v[136:137]
	v_pk_add_f32 v[46:47], v[130:131], v[120:121]
	v_pk_add_f32 v[32:33], v[24:25], v[30:31]
	v_pk_add_f32 v[24:25], v[24:25], v[30:31] neg_lo:[0,1] neg_hi:[0,1]
	v_pk_add_f32 v[30:31], v[34:35], v[38:39]
	v_pk_add_f32 v[34:35], v[34:35], v[38:39] neg_lo:[0,1] neg_hi:[0,1]
	v_pk_add_f32 v[38:39], v[94:95], v[80:81] neg_lo:[0,1] neg_hi:[0,1]
	v_pk_add_f32 v[44:45], v[78:79], v[136:137] neg_lo:[0,1] neg_hi:[0,1]
	v_pk_add_f32 v[60:61], v[128:129], v[150:151]
	v_pk_add_f32 v[64:65], v[168:169], v[144:145]
	v_pk_add_f32 v[40:41], v[36:37], v[38:39] op_sel:[0,1] op_sel_hi:[1,0] neg_lo:[0,1]
	v_pk_add_f32 v[36:37], v[36:37], v[38:39] op_sel:[0,1] op_sel_hi:[1,0] neg_hi:[0,1]
	v_pk_add_f32 v[38:39], v[42:43], v[46:47]
	v_pk_add_f32 v[42:43], v[42:43], v[46:47] neg_lo:[0,1] neg_hi:[0,1]
	v_pk_add_f32 v[46:47], v[130:131], v[120:121] neg_lo:[0,1] neg_hi:[0,1]
	v_pk_add_f32 v[62:63], v[128:129], v[150:151] neg_lo:[0,1] neg_hi:[0,1]
	v_pk_add_f32 v[50:51], v[44:45], v[46:47] op_sel:[0,1] op_sel_hi:[1,0] neg_lo:[0,1]
	v_pk_add_f32 v[44:45], v[44:45], v[46:47] op_sel:[0,1] op_sel_hi:[1,0] neg_hi:[0,1]
	v_pk_add_f32 v[46:47], v[60:61], v[64:65]
	v_pk_add_f32 v[60:61], v[60:61], v[64:65] neg_lo:[0,1] neg_hi:[0,1]
	v_pk_add_f32 v[64:65], v[168:169], v[144:145] neg_lo:[0,1] neg_hi:[0,1]
	s_mov_b32 s66, s37
	s_mov_b32 s67, s36
	v_pk_add_f32 v[66:67], v[62:63], v[64:65] op_sel:[0,1] op_sel_hi:[1,0] neg_lo:[0,1]
	v_pk_add_f32 v[62:63], v[62:63], v[64:65] op_sel:[0,1] op_sel_hi:[1,0] neg_hi:[0,1]
	v_pk_add_f32 v[64:65], v[68:69], v[30:31]
	v_pk_add_f32 v[30:31], v[68:69], v[30:31] neg_lo:[0,1] neg_hi:[0,1]
	s_mov_b32 s0, s37
	v_pk_mul_f32 v[68:69], v[40:41], s[66:67]
	s_mov_b32 s68, s19
	v_pk_fma_f32 v[40:41], v[40:41], s[0:1], v[68:69] op_sel:[0,0,1] op_sel_hi:[1,0,0]
	s_mov_b32 s69, s18
	v_pk_add_f32 v[68:69], v[32:33], v[40:41]
	v_pk_add_f32 v[32:33], v[32:33], v[40:41] neg_lo:[0,1] neg_hi:[0,1]
	v_xor_b32_e32 v40, 0x80000000, v35
	v_mov_b32_e32 v41, v34
	v_pk_add_f32 v[34:35], v[26:27], v[40:41]
	v_pk_add_f32 v[26:27], v[26:27], v[40:41] neg_lo:[0,1] neg_hi:[0,1]
	v_pk_mul_f32 v[40:41], v[36:37], s[66:67]
	s_mov_b32 s72, s19
	v_pk_fma_f32 v[36:37], v[36:37], s[0:1], v[40:41] op_sel:[0,0,1] op_sel_hi:[1,0,0] neg_lo:[1,0,0] neg_hi:[1,0,0]
	v_pk_mul_f32 v[2:3], v[72:73], s[46:47] op_sel_hi:[1,0]
	v_pk_add_f32 v[40:41], v[24:25], v[36:37]
	v_pk_add_f32 v[24:25], v[24:25], v[36:37] neg_lo:[0,1] neg_hi:[0,1]
	v_pk_add_f32 v[36:37], v[38:39], v[46:47]
	v_pk_add_f32 v[38:39], v[38:39], v[46:47] neg_lo:[0,1] neg_hi:[0,1]
	v_pk_mul_f32 v[46:47], v[66:67], s[66:67]
	v_pk_mul_f32 v[8:9], v[70:71], s[46:47] op_sel_hi:[1,0]
	v_pk_fma_f32 v[46:47], v[66:67], s[0:1], v[46:47] op_sel:[0,0,1] op_sel_hi:[1,0,0]
	v_pk_mul_f32 v[10:11], v[76:77], s[46:47] op_sel_hi:[1,0]
	v_pk_add_f32 v[66:67], v[50:51], v[46:47]
	v_pk_add_f32 v[46:47], v[50:51], v[46:47] neg_lo:[0,1] neg_hi:[0,1]
	v_xor_b32_e32 v50, 0x80000000, v61
	v_mov_b32_e32 v51, v60
	v_pk_add_f32 v[60:61], v[42:43], v[50:51]
	v_pk_add_f32 v[42:43], v[42:43], v[50:51] neg_lo:[0,1] neg_hi:[0,1]
	v_pk_mul_f32 v[50:51], v[62:63], s[66:67]
	v_pk_mul_f32 v[14:15], v[74:75], s[46:47] op_sel_hi:[1,0]
	v_pk_fma_f32 v[50:51], v[62:63], s[0:1], v[50:51] op_sel:[0,0,1] op_sel_hi:[1,0,0] neg_lo:[1,0,0] neg_hi:[1,0,0]
	v_pk_mul_f32 v[16:17], v[16:17], s[46:47] op_sel_hi:[1,0]
	v_pk_add_f32 v[62:63], v[44:45], v[50:51]
	v_pk_add_f32 v[44:45], v[44:45], v[50:51] neg_lo:[0,1] neg_hi:[0,1]
	v_pk_add_f32 v[50:51], v[64:65], v[36:37]
	v_pk_add_f32 v[36:37], v[64:65], v[36:37] neg_lo:[0,1] neg_hi:[0,1]
	v_pk_mul_f32 v[64:65], v[66:67], s[68:69]
	v_pk_mul_f32 v[6:7], v[6:7], s[46:47] op_sel_hi:[1,0]
	v_pk_fma_f32 v[64:65], v[66:67], s[16:17], v[64:65] op_sel:[0,0,1] op_sel_hi:[1,0,0]
	s_mov_b32 s17, s40
	v_pk_add_f32 v[66:67], v[68:69], v[64:65]
	v_pk_add_f32 v[64:65], v[68:69], v[64:65] neg_lo:[0,1] neg_hi:[0,1]
	v_pk_mul_f32 v[68:69], v[60:61], s[66:67]
	s_ashr_i32 s63, s62, 31
	v_pk_fma_f32 v[60:61], s[0:1], v[60:61], v[68:69] op_sel:[0,0,1] op_sel_hi:[0,1,0]
	v_pk_add_f32 v[68:69], v[34:35], v[60:61]
	v_pk_add_f32 v[34:35], v[34:35], v[60:61] neg_lo:[0,1] neg_hi:[0,1]
	v_pk_mul_f32 v[60:61], v[62:63], s[16:17]
	s_nop 0
	v_pk_fma_f32 v[60:61], s[72:73], v[62:63], v[60:61] op_sel:[0,0,1] op_sel_hi:[0,1,0]
	v_pk_add_f32 v[62:63], v[40:41], v[60:61]
	v_pk_add_f32 v[40:41], v[40:41], v[60:61] neg_lo:[0,1] neg_hi:[0,1]
	v_xor_b32_e32 v60, 0x80000000, v39
	v_mov_b32_e32 v61, v38
	v_pk_add_f32 v[38:39], v[30:31], v[60:61]
	v_pk_add_f32 v[30:31], v[30:31], v[60:61] neg_lo:[0,1] neg_hi:[0,1]
	v_pk_mul_f32 v[60:61], v[46:47], s[16:17]
	s_nop 0
	v_pk_fma_f32 v[46:47], s[72:73], v[46:47], v[60:61] op_sel:[0,0,1] op_sel_hi:[0,1,0] neg_lo:[0,1,0] neg_hi:[0,1,0]
	v_pk_add_f32 v[60:61], v[32:33], v[46:47]
	v_pk_add_f32 v[32:33], v[32:33], v[46:47] neg_lo:[0,1] neg_hi:[0,1]
	v_pk_mul_f32 v[46:47], v[42:43], s[66:67]
	s_nop 0
	v_pk_fma_f32 v[42:43], s[0:1], v[42:43], v[46:47] op_sel:[0,0,1] op_sel_hi:[0,1,0] neg_lo:[0,1,0] neg_hi:[0,1,0]
	v_pk_add_f32 v[46:47], v[26:27], v[42:43]
	v_pk_add_f32 v[26:27], v[26:27], v[42:43] neg_lo:[0,1] neg_hi:[0,1]
	v_pk_mul_f32 v[42:43], v[44:45], s[68:69]
	s_nop 0
	v_pk_fma_f32 v[42:43], s[16:17], v[44:45], v[42:43] op_sel:[0,0,1] op_sel_hi:[0,1,0] neg_lo:[0,1,0] neg_hi:[0,1,0]
	v_pk_add_f32 v[44:45], v[24:25], v[42:43]
	v_pk_add_f32 v[24:25], v[24:25], v[42:43] neg_lo:[0,1] neg_hi:[0,1]
	v_pk_fma_f32 v[42:43], v[58:59], s[46:47], v[2:3] op_sel_hi:[1,0,1]
	v_pk_fma_f32 v[2:3], v[58:59], s[46:47], v[2:3] op_sel_hi:[1,0,1] neg_lo:[0,0,1] neg_hi:[0,0,1]
	v_pk_fma_f32 v[58:59], v[54:55], s[46:47], v[8:9] op_sel_hi:[1,0,1]
	v_pk_fma_f32 v[8:9], v[54:55], s[46:47], v[8:9] op_sel_hi:[1,0,1] neg_lo:[0,0,1] neg_hi:[0,0,1]
	v_pk_fma_f32 v[54:55], v[56:57], s[46:47], v[10:11] op_sel_hi:[1,0,1]
	v_pk_fma_f32 v[10:11], v[56:57], s[46:47], v[10:11] op_sel_hi:[1,0,1] neg_lo:[0,0,1] neg_hi:[0,0,1]
	v_pk_fma_f32 v[56:57], v[52:53], s[46:47], v[14:15] op_sel_hi:[1,0,1]
	v_pk_fma_f32 v[14:15], v[52:53], s[46:47], v[14:15] op_sel_hi:[1,0,1] neg_lo:[0,0,1] neg_hi:[0,0,1]
	v_pk_fma_f32 v[52:53], v[48:49], s[46:47], v[20:21] op_sel_hi:[1,0,1]
	v_pk_fma_f32 v[20:21], v[48:49], s[46:47], v[20:21] op_sel_hi:[1,0,1] neg_lo:[0,0,1] neg_hi:[0,0,1]
	v_pk_fma_f32 v[48:49], v[28:29], s[46:47], v[22:23] op_sel_hi:[1,0,1]
	v_pk_fma_f32 v[22:23], v[28:29], s[46:47], v[22:23] op_sel_hi:[1,0,1] neg_lo:[0,0,1] neg_hi:[0,0,1]
	v_pk_fma_f32 v[28:29], v[12:13], s[46:47], v[16:17] op_sel_hi:[1,0,1]
	v_pk_fma_f32 v[12:13], v[12:13], s[46:47], v[16:17] op_sel_hi:[1,0,1] neg_lo:[0,0,1] neg_hi:[0,0,1]
	v_pk_fma_f32 v[16:17], v[4:5], s[46:47], v[6:7] op_sel_hi:[1,0,1]
	v_pk_fma_f32 v[4:5], v[4:5], s[46:47], v[6:7] op_sel_hi:[1,0,1] neg_lo:[0,0,1] neg_hi:[0,0,1]
	v_pk_add_f32 v[6:7], v[58:59], v[42:43]
	v_pk_add_f32 v[42:43], v[42:43], v[58:59] neg_lo:[0,1] neg_hi:[0,1]
	v_xor_b32_e32 v58, 0x80000000, v9
	v_mov_b32_e32 v59, v8
	v_pk_add_f32 v[8:9], v[2:3], v[58:59]
	v_pk_add_f32 v[2:3], v[2:3], v[58:59] neg_lo:[0,1] neg_hi:[0,1]
	v_pk_add_f32 v[58:59], v[56:57], v[54:55]
	v_pk_add_f32 v[54:55], v[54:55], v[56:57] neg_lo:[0,1] neg_hi:[0,1]
	v_xor_b32_e32 v56, 0x80000000, v15
	v_mov_b32_e32 v57, v14
	v_pk_add_f32 v[14:15], v[10:11], v[56:57]
	v_pk_add_f32 v[10:11], v[10:11], v[56:57] neg_lo:[0,1] neg_hi:[0,1]
	v_pk_add_f32 v[56:57], v[48:49], v[52:53]
	v_pk_add_f32 v[48:49], v[52:53], v[48:49] neg_lo:[0,1] neg_hi:[0,1]
	v_xor_b32_e32 v52, 0x80000000, v23
	v_mov_b32_e32 v53, v22
	v_pk_add_f32 v[22:23], v[20:21], v[52:53]
	v_pk_add_f32 v[20:21], v[20:21], v[52:53] neg_lo:[0,1] neg_hi:[0,1]
	v_pk_add_f32 v[52:53], v[16:17], v[28:29]
	v_pk_add_f32 v[16:17], v[28:29], v[16:17] neg_lo:[0,1] neg_hi:[0,1]
	v_xor_b32_e32 v28, 0x80000000, v5
	v_mov_b32_e32 v29, v4
	v_pk_add_f32 v[4:5], v[12:13], v[28:29]
	v_pk_add_f32 v[12:13], v[12:13], v[28:29] neg_lo:[0,1] neg_hi:[0,1]
	v_pk_add_f32 v[28:29], v[58:59], v[6:7]
	v_pk_add_f32 v[6:7], v[6:7], v[58:59] neg_lo:[0,1] neg_hi:[0,1]
	v_pk_mul_f32 v[58:59], v[14:15], s[66:67]
	s_nop 0
	v_pk_fma_f32 v[14:15], s[0:1], v[14:15], v[58:59] op_sel:[0,0,1] op_sel_hi:[0,1,0]
	v_pk_add_f32 v[58:59], v[14:15], v[8:9]
	v_pk_add_f32 v[8:9], v[8:9], v[14:15] neg_lo:[0,1] neg_hi:[0,1]
	v_xor_b32_e32 v14, 0x80000000, v55
	v_mov_b32_e32 v15, v54
	v_pk_add_f32 v[54:55], v[14:15], v[42:43]
	v_pk_add_f32 v[14:15], v[42:43], v[14:15] neg_lo:[0,1] neg_hi:[0,1]
	v_pk_mul_f32 v[42:43], v[10:11], s[66:67]
	s_nop 0
	v_pk_fma_f32 v[10:11], s[0:1], v[10:11], v[42:43] op_sel:[0,0,1] op_sel_hi:[0,1,0] neg_lo:[0,1,0] neg_hi:[0,1,0]
	v_pk_add_f32 v[42:43], v[10:11], v[2:3]
	v_pk_add_f32 v[2:3], v[2:3], v[10:11] neg_lo:[0,1] neg_hi:[0,1]
	v_pk_add_f32 v[10:11], v[52:53], v[56:57]
	v_pk_add_f32 v[52:53], v[56:57], v[52:53] neg_lo:[0,1] neg_hi:[0,1]
	v_pk_mul_f32 v[56:57], v[4:5], s[66:67]
	s_nop 0
	v_pk_fma_f32 v[4:5], s[0:1], v[4:5], v[56:57] op_sel:[0,0,1] op_sel_hi:[0,1,0]
	v_pk_add_f32 v[56:57], v[4:5], v[22:23]
	v_pk_add_f32 v[4:5], v[22:23], v[4:5] neg_lo:[0,1] neg_hi:[0,1]
	v_xor_b32_e32 v22, 0x80000000, v17
	v_mov_b32_e32 v23, v16
	v_pk_add_f32 v[16:17], v[22:23], v[48:49]
	v_pk_add_f32 v[22:23], v[48:49], v[22:23] neg_lo:[0,1] neg_hi:[0,1]
	v_pk_mul_f32 v[48:49], v[12:13], s[66:67]
	s_nop 0
	v_pk_fma_f32 v[12:13], s[0:1], v[12:13], v[48:49] op_sel:[0,0,1] op_sel_hi:[0,1,0] neg_lo:[0,1,0] neg_hi:[0,1,0]
	v_pk_add_f32 v[48:49], v[12:13], v[20:21]
	v_pk_add_f32 v[12:13], v[20:21], v[12:13] neg_lo:[0,1] neg_hi:[0,1]
	v_pk_add_f32 v[20:21], v[10:11], v[28:29]
	v_pk_add_f32 v[10:11], v[28:29], v[10:11] neg_lo:[0,1] neg_hi:[0,1]
	v_pk_mul_f32 v[28:29], v[56:57], s[68:69]
	s_nop 0
	v_pk_fma_f32 v[28:29], s[16:17], v[56:57], v[28:29] op_sel:[0,0,1] op_sel_hi:[0,1,0]
	v_pk_add_f32 v[56:57], v[28:29], v[58:59]
	v_pk_add_f32 v[28:29], v[58:59], v[28:29] neg_lo:[0,1] neg_hi:[0,1]
	v_pk_mul_f32 v[58:59], v[16:17], s[66:67]
	s_nop 0
	v_pk_fma_f32 v[16:17], s[0:1], v[16:17], v[58:59] op_sel:[0,0,1] op_sel_hi:[0,1,0]
	v_pk_add_f32 v[58:59], v[16:17], v[54:55]
	v_pk_add_f32 v[16:17], v[54:55], v[16:17] neg_lo:[0,1] neg_hi:[0,1]
	v_pk_mul_f32 v[54:55], v[48:49], s[16:17]
	s_nop 0
	v_pk_fma_f32 v[48:49], s[72:73], v[48:49], v[54:55] op_sel:[0,0,1] op_sel_hi:[0,1,0]
	v_pk_add_f32 v[54:55], v[48:49], v[42:43]
	v_pk_add_f32 v[42:43], v[42:43], v[48:49] neg_lo:[0,1] neg_hi:[0,1]
	v_xor_b32_e32 v48, 0x80000000, v53
	v_mov_b32_e32 v49, v52
	v_pk_add_f32 v[52:53], v[48:49], v[6:7]
	v_pk_add_f32 v[6:7], v[6:7], v[48:49] neg_lo:[0,1] neg_hi:[0,1]
	v_pk_mul_f32 v[48:49], v[4:5], s[16:17]
	s_nop 0
	v_pk_fma_f32 v[4:5], s[72:73], v[4:5], v[48:49] op_sel:[0,0,1] op_sel_hi:[0,1,0] neg_lo:[0,1,0] neg_hi:[0,1,0]
	v_pk_add_f32 v[48:49], v[4:5], v[8:9]
	v_pk_add_f32 v[4:5], v[8:9], v[4:5] neg_lo:[0,1] neg_hi:[0,1]
	v_pk_mul_f32 v[8:9], v[22:23], s[66:67]
	s_nop 0
	v_pk_fma_f32 v[8:9], s[0:1], v[22:23], v[8:9] op_sel:[0,0,1] op_sel_hi:[0,1,0] neg_lo:[0,1,0] neg_hi:[0,1,0]
	v_pk_add_f32 v[22:23], v[8:9], v[14:15]
	v_pk_add_f32 v[8:9], v[14:15], v[8:9] neg_lo:[0,1] neg_hi:[0,1]
	v_pk_mul_f32 v[14:15], v[12:13], s[68:69]
	s_nop 0
	v_pk_fma_f32 v[12:13], s[16:17], v[12:13], v[14:15] op_sel:[0,0,1] op_sel_hi:[0,1,0] neg_lo:[0,1,0] neg_hi:[0,1,0]
	v_pk_add_f32 v[14:15], v[12:13], v[2:3]
	v_pk_add_f32 v[2:3], v[2:3], v[12:13] neg_lo:[0,1] neg_hi:[0,1]
	ds_write_b64 v211, v[50:51]
	ds_write_b64 v212, v[20:21]
	ds_write_b64 v211, v[66:67] offset:8
	ds_write_b64 v212, v[56:57] offset:8
	ds_write_b64 v211, v[68:69] offset:16
	ds_write_b64 v212, v[58:59] offset:16
	ds_write_b64 v211, v[62:63] offset:24
	ds_write_b64 v212, v[54:55] offset:24
	ds_write_b64 v211, v[38:39] offset:32
	ds_write_b64 v212, v[52:53] offset:32
	ds_write_b64 v211, v[60:61] offset:40
	ds_write_b64 v212, v[48:49] offset:40
	ds_write_b64 v211, v[46:47] offset:48
	ds_write_b64 v212, v[22:23] offset:48
	ds_write_b64 v211, v[44:45] offset:56
	ds_write_b64 v212, v[14:15] offset:56
	ds_write_b64 v211, v[36:37] offset:64
	ds_write_b64 v212, v[10:11] offset:64
	ds_write_b64 v211, v[64:65] offset:72
	ds_write_b64 v212, v[28:29] offset:72
	ds_write_b64 v211, v[34:35] offset:80
	ds_write_b64 v212, v[16:17] offset:80
	ds_write_b64 v211, v[40:41] offset:88
	ds_write_b64 v212, v[42:43] offset:88
	ds_write_b64 v211, v[30:31] offset:96
	ds_write_b64 v212, v[6:7] offset:96
	ds_write_b64 v211, v[32:33] offset:104
	ds_write_b64 v212, v[4:5] offset:104
	ds_write_b64 v211, v[26:27] offset:112
	ds_write_b64 v212, v[8:9] offset:112
	ds_write_b64 v211, v[24:25] offset:120
	ds_write_b64 v212, v[2:3] offset:120
	v_mov_b32_e32 v2, v210
	s_waitcnt lgkmcnt(0)
	s_barrier
	s_nop 0
	v_and_b32_e32 v4, 15, v2
	v_cvt_f32_ubyte0_e32 v3, v4
	v_mul_f32_e32 v5, 0x3b800000, v3
	v_sin_f32_e32 v3, v5
	v_lshlrev_b32_e32 v6, 4, v2
	v_cos_f32_e32 v2, v5
	v_lshlrev_b32_e32 v7, 3, v4
	v_xor_b32_e32 v16, 0x80000000, v3
	v_mov_b32_e32 v17, v3
	v_pk_mul_f32 v[4:5], v[2:3], v[16:17] op_sel:[1,0] op_sel_hi:[0,1]
	v_pk_fma_f32 v[40:41], v[2:3], v[2:3], v[4:5] op_sel_hi:[0,1,1]
	v_pk_mul_f32 v[4:5], v[16:17], v[40:41] op_sel:[0,1] op_sel_hi:[1,0]
	v_xor_b32_e32 v44, 0x80000000, v41
	v_mov_b32_e32 v45, v41
	v_pk_fma_f32 v[42:43], v[2:3], v[40:41], v[4:5] op_sel_hi:[0,1,1]
	v_pk_mul_f32 v[4:5], v[40:41], v[44:45] op_sel:[1,0] op_sel_hi:[0,1]
	v_pk_fma_f32 v[46:47], v[40:41], v[40:41], v[4:5] op_sel_hi:[1,0,1]
	v_xor_b32_e32 v50, 0x80000000, v43
	v_pk_mul_f32 v[4:5], v[16:17], v[46:47] op_sel:[0,1] op_sel_hi:[1,0]
	v_mov_b32_e32 v51, v43
	v_pk_fma_f32 v[52:53], v[2:3], v[46:47], v[4:5] op_sel_hi:[0,1,1]
	v_pk_mul_f32 v[4:5], v[44:45], v[46:47] op_sel:[0,1] op_sel_hi:[1,0]
	v_xor_b32_e32 v48, 0x80000000, v47
	v_mov_b32_e32 v49, v47
	v_pk_fma_f32 v[56:57], v[40:41], v[46:47], v[4:5] op_sel_hi:[0,1,1]
	v_pk_mul_f32 v[4:5], v[46:47], v[50:51] op_sel:[1,0] op_sel_hi:[0,1]
	v_pk_fma_f32 v[60:61], v[46:47], v[42:43], v[4:5] op_sel_hi:[1,0,1]
	v_pk_mul_f32 v[4:5], v[46:47], v[48:49] op_sel:[1,0] op_sel_hi:[0,1]
	v_pk_fma_f32 v[64:65], v[46:47], v[46:47], v[4:5] op_sel_hi:[1,0,1]
	v_xor_b32_e32 v54, 0x80000000, v53
	v_pk_mul_f32 v[4:5], v[16:17], v[64:65] op_sel:[0,1] op_sel_hi:[1,0]
	v_mov_b32_e32 v55, v53
	v_pk_fma_f32 v[68:69], v[2:3], v[64:65], v[4:5] op_sel_hi:[0,1,1]
	v_pk_mul_f32 v[4:5], v[44:45], v[64:65] op_sel:[0,1] op_sel_hi:[1,0]
	v_xor_b32_e32 v58, 0x80000000, v57
	v_pk_fma_f32 v[72:73], v[40:41], v[64:65], v[4:5] op_sel_hi:[0,1,1]
	v_pk_mul_f32 v[4:5], v[50:51], v[64:65] op_sel:[0,1] op_sel_hi:[1,0]
	v_mov_b32_e32 v59, v57
	v_pk_fma_f32 v[76:77], v[42:43], v[64:65], v[4:5] op_sel_hi:[0,1,1]
	v_pk_mul_f32 v[4:5], v[48:49], v[64:65] op_sel:[0,1] op_sel_hi:[1,0]
	v_xor_b32_e32 v62, 0x80000000, v61
	v_pk_fma_f32 v[80:81], v[46:47], v[64:65], v[4:5] op_sel_hi:[0,1,1]
	v_pk_mul_f32 v[4:5], v[16:17], v[80:81] op_sel:[0,1] op_sel_hi:[1,0]
	v_mov_b32_e32 v63, v61
	v_pk_fma_f32 v[84:85], v[2:3], v[80:81], v[4:5] op_sel_hi:[0,1,1]
	v_pk_mul_f32 v[4:5], v[44:45], v[80:81] op_sel:[0,1] op_sel_hi:[1,0]
	v_and_b32_e32 v3, 0xffffff00, v6
	v_pk_fma_f32 v[88:89], v[40:41], v[80:81], v[4:5] op_sel_hi:[0,1,1]
	v_pk_mul_f32 v[4:5], v[50:51], v[80:81] op_sel:[0,1] op_sel_hi:[1,0]
	v_xor_b32_e32 v66, 0x80000000, v65
	v_pk_fma_f32 v[92:93], v[42:43], v[80:81], v[4:5] op_sel_hi:[0,1,1]
	v_lshlrev_b32_e32 v4, 3, v3
	v_add3_u32 v18, 0, v7, v4
	v_ashrrev_i32_e32 v4, 2, v3
	v_add_u32_e32 v98, v18, v4
	ds_read2_b64 v[4:7], v98 offset1:16
	ds_read2_b64 v[8:11], v98 offset0:33 offset1:49
	ds_read2_b64 v[12:15], v98 offset0:66 offset1:82
	ds_read2_b64 v[20:23], v98 offset0:132 offset1:148
	ds_read2_b64 v[24:27], v98 offset0:99 offset1:115
	ds_read2_b64 v[28:31], v98 offset0:165 offset1:181
	ds_read2_b64 v[32:35], v98 offset0:198 offset1:214
	ds_read2_b64 v[36:39], v98 offset0:231 offset1:247
	s_waitcnt lgkmcnt(4)
	v_pk_mul_f32 v[96:97], v[16:17], v[20:21] op_sel:[0,1] op_sel_hi:[1,0]
	v_mov_b32_e32 v67, v65
	v_pk_fma_f32 v[20:21], v[2:3], v[20:21], v[96:97] op_sel_hi:[0,1,1]
	v_pk_mul_f32 v[96:97], v[12:13], v[44:45] op_sel:[1,0] op_sel_hi:[0,1]
	v_pk_fma_f32 v[12:13], v[12:13], v[40:41], v[96:97] op_sel_hi:[1,0,1]
	s_waitcnt lgkmcnt(1)
	v_pk_mul_f32 v[96:97], v[50:51], v[32:33] op_sel:[0,1] op_sel_hi:[1,0]
	v_xor_b32_e32 v70, 0x80000000, v69
	v_pk_fma_f32 v[32:33], v[42:43], v[32:33], v[96:97] op_sel_hi:[0,1,1]
	v_pk_mul_f32 v[96:97], v[8:9], v[48:49] op_sel:[1,0] op_sel_hi:[0,1]
	v_pk_fma_f32 v[8:9], v[8:9], v[46:47], v[96:97] op_sel_hi:[1,0,1]
	v_pk_mul_f32 v[96:97], v[28:29], v[54:55] op_sel:[1,0] op_sel_hi:[0,1]
	v_pk_fma_f32 v[28:29], v[28:29], v[52:53], v[96:97] op_sel_hi:[1,0,1]
	v_pk_mul_f32 v[96:97], v[24:25], v[58:59] op_sel:[1,0] op_sel_hi:[0,1]
	v_pk_fma_f32 v[24:25], v[24:25], v[56:57], v[96:97] op_sel_hi:[1,0,1]
	s_waitcnt lgkmcnt(0)
	v_pk_mul_f32 v[96:97], v[36:37], v[62:63] op_sel:[1,0] op_sel_hi:[0,1]
	v_mov_b32_e32 v71, v69
	v_pk_fma_f32 v[36:37], v[36:37], v[60:61], v[96:97] op_sel_hi:[1,0,1]
	v_pk_mul_f32 v[96:97], v[6:7], v[66:67] op_sel:[1,0] op_sel_hi:[0,1]
	v_xor_b32_e32 v74, 0x80000000, v73
	v_mov_b32_e32 v75, v73
	v_pk_fma_f32 v[6:7], v[6:7], v[64:65], v[96:97] op_sel_hi:[1,0,1]
	v_pk_mul_f32 v[96:97], v[22:23], v[70:71] op_sel:[1,0] op_sel_hi:[0,1]
	v_xor_b32_e32 v78, 0x80000000, v77
	v_mov_b32_e32 v79, v77
	v_pk_fma_f32 v[22:23], v[22:23], v[68:69], v[96:97] op_sel_hi:[1,0,1]
	v_pk_mul_f32 v[96:97], v[14:15], v[74:75] op_sel:[1,0] op_sel_hi:[0,1]
	v_xor_b32_e32 v82, 0x80000000, v81
	v_mov_b32_e32 v83, v81
	v_pk_fma_f32 v[14:15], v[14:15], v[72:73], v[96:97] op_sel_hi:[1,0,1]
	v_pk_mul_f32 v[96:97], v[34:35], v[78:79] op_sel:[1,0] op_sel_hi:[0,1]
	v_xor_b32_e32 v86, 0x80000000, v85
	v_mov_b32_e32 v87, v85
	v_pk_fma_f32 v[34:35], v[34:35], v[76:77], v[96:97] op_sel_hi:[1,0,1]
	v_pk_mul_f32 v[96:97], v[10:11], v[82:83] op_sel:[1,0] op_sel_hi:[0,1]
	v_xor_b32_e32 v90, 0x80000000, v89
	v_mov_b32_e32 v91, v89
	v_pk_fma_f32 v[10:11], v[10:11], v[80:81], v[96:97] op_sel_hi:[1,0,1]
	v_pk_mul_f32 v[96:97], v[30:31], v[86:87] op_sel:[1,0] op_sel_hi:[0,1]
	v_xor_b32_e32 v94, 0x80000000, v93
	v_mov_b32_e32 v95, v93
	v_pk_fma_f32 v[30:31], v[30:31], v[84:85], v[96:97] op_sel_hi:[1,0,1]
	v_pk_mul_f32 v[96:97], v[26:27], v[90:91] op_sel:[1,0] op_sel_hi:[0,1]
	v_pk_fma_f32 v[26:27], v[26:27], v[88:89], v[96:97] op_sel_hi:[1,0,1]
	v_pk_mul_f32 v[96:97], v[38:39], v[94:95] op_sel:[1,0] op_sel_hi:[0,1]
	v_pk_fma_f32 v[38:39], v[38:39], v[92:93], v[96:97] op_sel_hi:[1,0,1]
	v_pk_add_f32 v[96:97], v[4:5], v[6:7]
	v_pk_add_f32 v[4:5], v[4:5], v[6:7] neg_lo:[0,1] neg_hi:[0,1]
	v_pk_add_f32 v[6:7], v[8:9], v[10:11]
	v_pk_add_f32 v[8:9], v[8:9], v[10:11] neg_lo:[0,1] neg_hi:[0,1]
	v_pk_add_f32 v[10:11], v[12:13], v[14:15]
	v_pk_add_f32 v[12:13], v[12:13], v[14:15] neg_lo:[0,1] neg_hi:[0,1]
	v_pk_add_f32 v[14:15], v[24:25], v[26:27]
	v_pk_add_f32 v[24:25], v[24:25], v[26:27] neg_lo:[0,1] neg_hi:[0,1]
	v_pk_add_f32 v[26:27], v[20:21], v[22:23]
	v_pk_add_f32 v[20:21], v[20:21], v[22:23] neg_lo:[0,1] neg_hi:[0,1]
	v_pk_add_f32 v[22:23], v[28:29], v[30:31]
	v_pk_add_f32 v[28:29], v[28:29], v[30:31] neg_lo:[0,1] neg_hi:[0,1]
	v_pk_add_f32 v[30:31], v[32:33], v[34:35]
	v_pk_add_f32 v[32:33], v[32:33], v[34:35] neg_lo:[0,1] neg_hi:[0,1]
	v_pk_add_f32 v[34:35], v[36:37], v[38:39]
	v_pk_add_f32 v[36:37], v[36:37], v[38:39] neg_lo:[0,1] neg_hi:[0,1]
	v_pk_add_f32 v[38:39], v[96:97], v[6:7]
	v_pk_add_f32 v[6:7], v[96:97], v[6:7] neg_lo:[0,1] neg_hi:[0,1]
	v_xor_b32_e32 v96, 0x80000000, v9
	v_mov_b32_e32 v97, v8
	v_pk_add_f32 v[8:9], v[4:5], v[96:97]
	v_pk_add_f32 v[4:5], v[4:5], v[96:97] neg_lo:[0,1] neg_hi:[0,1]
	v_pk_add_f32 v[96:97], v[10:11], v[14:15]
	v_pk_add_f32 v[10:11], v[10:11], v[14:15] neg_lo:[0,1] neg_hi:[0,1]
	v_xor_b32_e32 v14, 0x80000000, v25
	v_mov_b32_e32 v15, v24
	v_pk_add_f32 v[24:25], v[12:13], v[14:15]
	v_pk_add_f32 v[12:13], v[12:13], v[14:15] neg_lo:[0,1] neg_hi:[0,1]
	v_pk_add_f32 v[14:15], v[26:27], v[22:23]
	v_pk_add_f32 v[22:23], v[26:27], v[22:23] neg_lo:[0,1] neg_hi:[0,1]
	v_xor_b32_e32 v26, 0x80000000, v29
	v_mov_b32_e32 v27, v28
	v_pk_add_f32 v[28:29], v[20:21], v[26:27]
	v_pk_add_f32 v[20:21], v[20:21], v[26:27] neg_lo:[0,1] neg_hi:[0,1]
	v_pk_add_f32 v[26:27], v[30:31], v[34:35]
	v_pk_add_f32 v[30:31], v[30:31], v[34:35] neg_lo:[0,1] neg_hi:[0,1]
	v_xor_b32_e32 v34, 0x80000000, v37
	v_mov_b32_e32 v35, v36
	v_pk_add_f32 v[36:37], v[32:33], v[34:35]
	v_pk_add_f32 v[32:33], v[32:33], v[34:35] neg_lo:[0,1] neg_hi:[0,1]
	v_pk_add_f32 v[34:35], v[38:39], v[96:97]
	v_pk_add_f32 v[38:39], v[38:39], v[96:97] neg_lo:[0,1] neg_hi:[0,1]
	v_pk_mul_f32 v[96:97], v[24:25], s[66:67]
	v_add_u32_e32 v3, 0x2000, v3
	v_pk_fma_f32 v[24:25], v[24:25], s[0:1], v[96:97] op_sel:[0,0,1] op_sel_hi:[1,0,0]
	v_ashrrev_i32_e32 v3, 2, v3
	v_pk_add_f32 v[96:97], v[8:9], v[24:25]
	v_pk_add_f32 v[8:9], v[8:9], v[24:25] neg_lo:[0,1] neg_hi:[0,1]
	v_xor_b32_e32 v24, 0x80000000, v11
	v_mov_b32_e32 v25, v10
	v_pk_add_f32 v[10:11], v[6:7], v[24:25]
	v_pk_add_f32 v[6:7], v[6:7], v[24:25] neg_lo:[0,1] neg_hi:[0,1]
	v_pk_mul_f32 v[24:25], v[12:13], s[66:67]
	v_add3_u32 v18, v18, v3, s5
	v_pk_fma_f32 v[12:13], s[0:1], v[12:13], v[24:25] op_sel:[0,0,1] op_sel_hi:[0,1,0] neg_lo:[0,1,0] neg_hi:[0,1,0]
	v_pk_add_f32 v[24:25], v[4:5], v[12:13]
	v_pk_add_f32 v[4:5], v[4:5], v[12:13] neg_lo:[0,1] neg_hi:[0,1]
	v_pk_add_f32 v[12:13], v[14:15], v[26:27]
	v_pk_add_f32 v[14:15], v[14:15], v[26:27] neg_lo:[0,1] neg_hi:[0,1]
	v_pk_mul_f32 v[26:27], v[36:37], s[66:67]
	s_nop 0
	v_pk_fma_f32 v[26:27], s[0:1], v[36:37], v[26:27] op_sel:[0,0,1] op_sel_hi:[0,1,0]
	v_pk_add_f32 v[36:37], v[28:29], v[26:27]
	v_pk_add_f32 v[26:27], v[28:29], v[26:27] neg_lo:[0,1] neg_hi:[0,1]
	v_xor_b32_e32 v28, 0x80000000, v31
	v_mov_b32_e32 v29, v30
	v_pk_add_f32 v[30:31], v[22:23], v[28:29]
	v_pk_add_f32 v[22:23], v[22:23], v[28:29] neg_lo:[0,1] neg_hi:[0,1]
	v_pk_mul_f32 v[28:29], v[32:33], s[66:67]
	s_nop 0
	v_pk_fma_f32 v[28:29], s[0:1], v[32:33], v[28:29] op_sel:[0,0,1] op_sel_hi:[0,1,0] neg_lo:[0,1,0] neg_hi:[0,1,0]
	v_pk_add_f32 v[32:33], v[20:21], v[28:29]
	v_pk_add_f32 v[20:21], v[20:21], v[28:29] neg_lo:[0,1] neg_hi:[0,1]
	v_pk_add_f32 v[28:29], v[34:35], v[12:13]
	v_pk_add_f32 v[12:13], v[34:35], v[12:13] neg_lo:[0,1] neg_hi:[0,1]
	v_pk_mul_f32 v[34:35], v[36:37], s[68:69]
	s_nop 0
	v_pk_fma_f32 v[34:35], s[16:17], v[36:37], v[34:35] op_sel:[0,0,1] op_sel_hi:[0,1,0]
	v_pk_add_f32 v[36:37], v[96:97], v[34:35]
	v_pk_add_f32 v[34:35], v[96:97], v[34:35] neg_lo:[0,1] neg_hi:[0,1]
	v_pk_mul_f32 v[96:97], v[30:31], s[66:67]
	s_nop 0
	v_pk_fma_f32 v[30:31], s[0:1], v[30:31], v[96:97] op_sel:[0,0,1] op_sel_hi:[0,1,0]
	v_pk_add_f32 v[96:97], v[10:11], v[30:31]
	v_pk_add_f32 v[10:11], v[10:11], v[30:31] neg_lo:[0,1] neg_hi:[0,1]
	v_pk_mul_f32 v[30:31], v[32:33], s[16:17]
	s_nop 0
	v_pk_fma_f32 v[30:31], s[72:73], v[32:33], v[30:31] op_sel:[0,0,1] op_sel_hi:[0,1,0]
	v_pk_add_f32 v[32:33], v[24:25], v[30:31]
	v_pk_add_f32 v[24:25], v[24:25], v[30:31] neg_lo:[0,1] neg_hi:[0,1]
	v_xor_b32_e32 v30, 0x80000000, v15
	v_mov_b32_e32 v31, v14
	v_pk_add_f32 v[14:15], v[38:39], v[30:31]
	v_pk_add_f32 v[30:31], v[38:39], v[30:31] neg_lo:[0,1] neg_hi:[0,1]
	v_pk_mul_f32 v[38:39], v[26:27], s[16:17]
	s_nop 0
	v_pk_fma_f32 v[26:27], s[72:73], v[26:27], v[38:39] op_sel:[0,0,1] op_sel_hi:[0,1,0] neg_lo:[0,1,0] neg_hi:[0,1,0]
	v_pk_add_f32 v[38:39], v[8:9], v[26:27]
	v_pk_add_f32 v[8:9], v[8:9], v[26:27] neg_lo:[0,1] neg_hi:[0,1]
	v_pk_mul_f32 v[26:27], v[22:23], s[66:67]
	s_nop 0
	v_pk_fma_f32 v[22:23], s[0:1], v[22:23], v[26:27] op_sel:[0,0,1] op_sel_hi:[0,1,0] neg_lo:[0,1,0] neg_hi:[0,1,0]
	v_pk_add_f32 v[26:27], v[6:7], v[22:23]
	v_pk_add_f32 v[6:7], v[6:7], v[22:23] neg_lo:[0,1] neg_hi:[0,1]
	v_pk_mul_f32 v[22:23], v[20:21], s[68:69]
	s_nop 0
	v_pk_fma_f32 v[20:21], s[16:17], v[20:21], v[22:23] op_sel:[0,0,1] op_sel_hi:[0,1,0] neg_lo:[0,1,0] neg_hi:[0,1,0]
	v_pk_add_f32 v[22:23], v[4:5], v[20:21]
	v_pk_add_f32 v[4:5], v[4:5], v[20:21] neg_lo:[0,1] neg_hi:[0,1]
	ds_write2_b64 v98, v[28:29], v[36:37] offset1:16
	ds_write2_b64 v98, v[96:97], v[32:33] offset0:33 offset1:49
	ds_write2_b64 v98, v[14:15], v[38:39] offset0:66 offset1:82
	ds_write2_b64 v98, v[26:27], v[22:23] offset0:99 offset1:115
	ds_write2_b64 v98, v[12:13], v[34:35] offset0:132 offset1:148
	ds_write2_b64 v98, v[10:11], v[24:25] offset0:165 offset1:181
	ds_write2_b64 v98, v[30:31], v[8:9] offset0:198 offset1:214
	ds_write2_b64 v98, v[6:7], v[4:5] offset0:231 offset1:247
	ds_read2_b64 v[4:7], v18 offset1:16
	ds_read2_b64 v[8:11], v18 offset0:33 offset1:49
	ds_read2_b64 v[12:15], v18 offset0:66 offset1:82
	ds_read2_b64 v[20:23], v18 offset0:132 offset1:148
	ds_read2_b64 v[24:27], v18 offset0:99 offset1:115
	ds_read2_b64 v[28:31], v18 offset0:165 offset1:181
	ds_read2_b64 v[32:35], v18 offset0:198 offset1:214
	ds_read2_b64 v[36:39], v18 offset0:231 offset1:247
	s_waitcnt lgkmcnt(4)
	v_pk_mul_f32 v[16:17], v[20:21], v[16:17] op_sel:[1,0] op_sel_hi:[0,1]
	v_pk_fma_f32 v[2:3], v[2:3], v[20:21], v[16:17] op_sel_hi:[0,1,1]
	v_pk_mul_f32 v[16:17], v[44:45], v[12:13] op_sel:[0,1] op_sel_hi:[1,0]
	v_pk_mul_f32 v[20:21], v[48:49], v[8:9] op_sel:[0,1] op_sel_hi:[1,0]
	v_pk_fma_f32 v[12:13], v[40:41], v[12:13], v[16:17] op_sel_hi:[0,1,1]
	s_waitcnt lgkmcnt(1)
	v_pk_mul_f32 v[16:17], v[50:51], v[32:33] op_sel:[0,1] op_sel_hi:[1,0]
	v_pk_fma_f32 v[8:9], v[46:47], v[8:9], v[20:21] op_sel_hi:[0,1,1]
	v_pk_fma_f32 v[16:17], v[42:43], v[32:33], v[16:17] op_sel_hi:[0,1,1]
	v_pk_mul_f32 v[32:33], v[66:67], v[6:7] op_sel:[0,1] op_sel_hi:[1,0]
	v_pk_mul_f32 v[20:21], v[54:55], v[28:29] op_sel:[0,1] op_sel_hi:[1,0]
	v_pk_fma_f32 v[6:7], v[64:65], v[6:7], v[32:33] op_sel_hi:[0,1,1]
	v_pk_mul_f32 v[32:33], v[70:71], v[22:23] op_sel:[0,1] op_sel_hi:[1,0]
	v_pk_fma_f32 v[20:21], v[52:53], v[28:29], v[20:21] op_sel_hi:[0,1,1]
	v_pk_fma_f32 v[22:23], v[68:69], v[22:23], v[32:33] op_sel_hi:[0,1,1]
	v_pk_mul_f32 v[32:33], v[74:75], v[14:15] op_sel:[0,1] op_sel_hi:[1,0]
	v_pk_mul_f32 v[28:29], v[58:59], v[24:25] op_sel:[0,1] op_sel_hi:[1,0]
	v_pk_fma_f32 v[14:15], v[72:73], v[14:15], v[32:33] op_sel_hi:[0,1,1]
	v_pk_mul_f32 v[32:33], v[78:79], v[34:35] op_sel:[0,1] op_sel_hi:[1,0]
	v_pk_fma_f32 v[24:25], v[56:57], v[24:25], v[28:29] op_sel_hi:[0,1,1]
	v_pk_fma_f32 v[32:33], v[76:77], v[34:35], v[32:33] op_sel_hi:[0,1,1]
	v_pk_mul_f32 v[34:35], v[82:83], v[10:11] op_sel:[0,1] op_sel_hi:[1,0]
	s_waitcnt lgkmcnt(0)
	v_pk_mul_f32 v[28:29], v[62:63], v[36:37] op_sel:[0,1] op_sel_hi:[1,0]
	v_pk_fma_f32 v[10:11], v[80:81], v[10:11], v[34:35] op_sel_hi:[0,1,1]
	v_pk_mul_f32 v[34:35], v[86:87], v[30:31] op_sel:[0,1] op_sel_hi:[1,0]
	v_pk_fma_f32 v[28:29], v[60:61], v[36:37], v[28:29] op_sel_hi:[0,1,1]
	v_pk_fma_f32 v[30:31], v[84:85], v[30:31], v[34:35] op_sel_hi:[0,1,1]
	v_pk_mul_f32 v[34:35], v[90:91], v[26:27] op_sel:[0,1] op_sel_hi:[1,0]
	v_pk_add_f32 v[36:37], v[4:5], v[6:7]
	v_pk_fma_f32 v[26:27], v[88:89], v[26:27], v[34:35] op_sel_hi:[0,1,1]
	v_pk_mul_f32 v[34:35], v[94:95], v[38:39] op_sel:[0,1] op_sel_hi:[1,0]
	v_pk_add_f32 v[4:5], v[4:5], v[6:7] neg_lo:[0,1] neg_hi:[0,1]
	v_pk_fma_f32 v[34:35], v[92:93], v[38:39], v[34:35] op_sel_hi:[0,1,1]
	v_pk_add_f32 v[6:7], v[8:9], v[10:11]
	v_pk_add_f32 v[8:9], v[8:9], v[10:11] neg_lo:[0,1] neg_hi:[0,1]
	v_pk_add_f32 v[10:11], v[12:13], v[14:15]
	v_pk_add_f32 v[12:13], v[12:13], v[14:15] neg_lo:[0,1] neg_hi:[0,1]
	v_pk_add_f32 v[14:15], v[24:25], v[26:27]
	v_pk_add_f32 v[24:25], v[24:25], v[26:27] neg_lo:[0,1] neg_hi:[0,1]
	v_pk_add_f32 v[26:27], v[2:3], v[22:23]
	v_pk_add_f32 v[2:3], v[2:3], v[22:23] neg_lo:[0,1] neg_hi:[0,1]
	v_pk_add_f32 v[22:23], v[20:21], v[30:31]
	v_pk_add_f32 v[20:21], v[20:21], v[30:31] neg_lo:[0,1] neg_hi:[0,1]
	v_pk_add_f32 v[30:31], v[16:17], v[32:33]
	v_pk_add_f32 v[16:17], v[16:17], v[32:33] neg_lo:[0,1] neg_hi:[0,1]
	v_pk_add_f32 v[32:33], v[28:29], v[34:35]
	v_pk_add_f32 v[28:29], v[28:29], v[34:35] neg_lo:[0,1] neg_hi:[0,1]
	v_pk_add_f32 v[34:35], v[36:37], v[6:7]
	v_pk_add_f32 v[6:7], v[36:37], v[6:7] neg_lo:[0,1] neg_hi:[0,1]
	v_xor_b32_e32 v36, 0x80000000, v9
	v_mov_b32_e32 v37, v8
	v_pk_add_f32 v[8:9], v[4:5], v[36:37]
	v_pk_add_f32 v[4:5], v[4:5], v[36:37] neg_lo:[0,1] neg_hi:[0,1]
	v_pk_add_f32 v[36:37], v[10:11], v[14:15]
	v_pk_add_f32 v[10:11], v[10:11], v[14:15] neg_lo:[0,1] neg_hi:[0,1]
	v_xor_b32_e32 v14, 0x80000000, v25
	v_mov_b32_e32 v15, v24
	v_pk_add_f32 v[24:25], v[12:13], v[14:15]
	v_pk_add_f32 v[12:13], v[12:13], v[14:15] neg_lo:[0,1] neg_hi:[0,1]
	v_pk_add_f32 v[14:15], v[26:27], v[22:23]
	v_pk_add_f32 v[22:23], v[26:27], v[22:23] neg_lo:[0,1] neg_hi:[0,1]
	v_xor_b32_e32 v26, 0x80000000, v21
	v_mov_b32_e32 v27, v20
	v_pk_add_f32 v[20:21], v[2:3], v[26:27]
	v_pk_add_f32 v[2:3], v[2:3], v[26:27] neg_lo:[0,1] neg_hi:[0,1]
	v_pk_add_f32 v[26:27], v[30:31], v[32:33]
	v_pk_add_f32 v[30:31], v[30:31], v[32:33] neg_lo:[0,1] neg_hi:[0,1]
	v_xor_b32_e32 v32, 0x80000000, v29
	v_mov_b32_e32 v33, v28
	v_pk_add_f32 v[28:29], v[16:17], v[32:33]
	v_pk_add_f32 v[16:17], v[16:17], v[32:33] neg_lo:[0,1] neg_hi:[0,1]
	v_pk_add_f32 v[32:33], v[34:35], v[36:37]
	v_pk_add_f32 v[34:35], v[34:35], v[36:37] neg_lo:[0,1] neg_hi:[0,1]
	v_pk_mul_f32 v[36:37], v[24:25], s[66:67]
	v_mov_b32_e32 v39, 0
	v_pk_fma_f32 v[24:25], v[24:25], s[0:1], v[36:37] op_sel:[0,0,1] op_sel_hi:[1,0,0]
	v_mov_b32_e32 v41, 0
	v_pk_add_f32 v[36:37], v[8:9], v[24:25]
	v_pk_add_f32 v[8:9], v[8:9], v[24:25] neg_lo:[0,1] neg_hi:[0,1]
	v_xor_b32_e32 v24, 0x80000000, v11
	v_mov_b32_e32 v25, v10
	v_pk_add_f32 v[10:11], v[6:7], v[24:25]
	v_pk_add_f32 v[6:7], v[6:7], v[24:25] neg_lo:[0,1] neg_hi:[0,1]
	v_pk_mul_f32 v[24:25], v[12:13], s[66:67]
	s_nop 0
	v_pk_fma_f32 v[12:13], s[0:1], v[12:13], v[24:25] op_sel:[0,0,1] op_sel_hi:[0,1,0] neg_lo:[0,1,0] neg_hi:[0,1,0]
	v_pk_add_f32 v[24:25], v[4:5], v[12:13]
	v_pk_add_f32 v[4:5], v[4:5], v[12:13] neg_lo:[0,1] neg_hi:[0,1]
	v_pk_add_f32 v[12:13], v[14:15], v[26:27]
	v_pk_add_f32 v[14:15], v[14:15], v[26:27] neg_lo:[0,1] neg_hi:[0,1]
	v_pk_mul_f32 v[26:27], v[28:29], s[66:67]
	s_nop 0
	v_pk_fma_f32 v[26:27], s[0:1], v[28:29], v[26:27] op_sel:[0,0,1] op_sel_hi:[0,1,0]
	v_pk_add_f32 v[28:29], v[20:21], v[26:27]
	v_pk_add_f32 v[20:21], v[20:21], v[26:27] neg_lo:[0,1] neg_hi:[0,1]
	v_xor_b32_e32 v26, 0x80000000, v31
	v_mov_b32_e32 v27, v30
	v_pk_add_f32 v[30:31], v[22:23], v[26:27]
	v_pk_add_f32 v[22:23], v[22:23], v[26:27] neg_lo:[0,1] neg_hi:[0,1]
	v_pk_mul_f32 v[26:27], v[16:17], s[66:67]
	s_nop 0
	v_pk_fma_f32 v[16:17], s[0:1], v[16:17], v[26:27] op_sel:[0,0,1] op_sel_hi:[0,1,0] neg_lo:[0,1,0] neg_hi:[0,1,0]
	v_pk_add_f32 v[26:27], v[2:3], v[16:17]
	v_pk_add_f32 v[2:3], v[2:3], v[16:17] neg_lo:[0,1] neg_hi:[0,1]
	v_pk_add_f32 v[16:17], v[32:33], v[12:13]
	v_pk_add_f32 v[12:13], v[32:33], v[12:13] neg_lo:[0,1] neg_hi:[0,1]
	v_pk_mul_f32 v[32:33], v[28:29], s[68:69]
	s_nop 0
	v_pk_fma_f32 v[28:29], s[16:17], v[28:29], v[32:33] op_sel:[0,0,1] op_sel_hi:[0,1,0]
	v_pk_add_f32 v[32:33], v[36:37], v[28:29]
	v_pk_add_f32 v[28:29], v[36:37], v[28:29] neg_lo:[0,1] neg_hi:[0,1]
	v_pk_mul_f32 v[36:37], v[30:31], s[66:67]
	s_nop 0
	v_pk_fma_f32 v[30:31], s[0:1], v[30:31], v[36:37] op_sel:[0,0,1] op_sel_hi:[0,1,0]
	v_pk_add_f32 v[36:37], v[10:11], v[30:31]
	v_pk_add_f32 v[10:11], v[10:11], v[30:31] neg_lo:[0,1] neg_hi:[0,1]
	v_pk_mul_f32 v[30:31], v[26:27], s[16:17]
	s_nop 0
	v_pk_fma_f32 v[26:27], s[72:73], v[26:27], v[30:31] op_sel:[0,0,1] op_sel_hi:[0,1,0]
	v_pk_add_f32 v[30:31], v[24:25], v[26:27]
	v_pk_add_f32 v[24:25], v[24:25], v[26:27] neg_lo:[0,1] neg_hi:[0,1]
	v_xor_b32_e32 v26, 0x80000000, v15
	v_mov_b32_e32 v27, v14
	v_pk_add_f32 v[14:15], v[34:35], v[26:27]
	v_pk_add_f32 v[26:27], v[34:35], v[26:27] neg_lo:[0,1] neg_hi:[0,1]
	v_pk_mul_f32 v[34:35], v[20:21], s[16:17]
	s_nop 0
	v_pk_fma_f32 v[20:21], s[72:73], v[20:21], v[34:35] op_sel:[0,0,1] op_sel_hi:[0,1,0] neg_lo:[0,1,0] neg_hi:[0,1,0]
	v_pk_add_f32 v[34:35], v[8:9], v[20:21]
	v_pk_add_f32 v[8:9], v[8:9], v[20:21] neg_lo:[0,1] neg_hi:[0,1]
	v_pk_mul_f32 v[20:21], v[22:23], s[66:67]
	s_nop 0
	v_pk_fma_f32 v[20:21], v[22:23], s[0:1], v[20:21] op_sel:[0,0,1] op_sel_hi:[1,0,0] neg_lo:[1,0,0] neg_hi:[1,0,0]
	s_lshl_b64 s[0:1], s[62:63], 2
	v_pk_add_f32 v[22:23], v[6:7], v[20:21]
	v_pk_add_f32 v[6:7], v[6:7], v[20:21] neg_lo:[0,1] neg_hi:[0,1]
	v_pk_mul_f32 v[20:21], v[2:3], s[68:69]
	s_add_u32 s0, s49, s0
	v_pk_fma_f32 v[2:3], v[2:3], s[16:17], v[20:21] op_sel:[0,0,1] op_sel_hi:[1,0,0] neg_lo:[1,0,0] neg_hi:[1,0,0]
	s_addc_u32 s1, s60, s1
	v_pk_add_f32 v[20:21], v[4:5], v[2:3]
	v_pk_add_f32 v[2:3], v[4:5], v[2:3] neg_lo:[0,1] neg_hi:[0,1]
	ds_write2_b64 v18, v[16:17], v[32:33] offset1:16
	ds_write2_b64 v18, v[36:37], v[30:31] offset0:33 offset1:49
	ds_write2_b64 v18, v[14:15], v[34:35] offset0:66 offset1:82
	ds_write2_b64 v18, v[22:23], v[20:21] offset0:99 offset1:115
	ds_write2_b64 v18, v[12:13], v[28:29] offset0:132 offset1:148
	ds_write2_b64 v18, v[10:11], v[24:25] offset0:165 offset1:181
	ds_write2_b64 v18, v[26:27], v[8:9] offset0:198 offset1:214
	ds_write2_b64 v18, v[6:7], v[2:3] offset0:231 offset1:247
	s_waitcnt lgkmcnt(0)
	s_barrier
	s_lshl_b64 s[62:63], s[64:65], 2
	v_ashrrev_i32_e32 v2, 31, v210
	s_add_u32 s62, s22, s62
	v_lshrrev_b32_e32 v2, 23, v2
	global_load_dword v30, v206, s[0:1]
	global_load_dword v20, v207, s[0:1]
	s_addc_u32 s63, s23, s63
	global_load_dword v31, v205, s[0:1]
	global_load_dword v24, v205, s[62:63]
	s_lshl_b64 s[0:1], s[64:65], 16
	v_add_u32_e32 v2, v210, v2
	s_add_u32 s0, s87, s0
	v_ashrrev_i32_e32 v2, 9, v2
	s_addc_u32 s1, s90, s1
	v_mul_i32_i24_e32 v3, 0x200, v2
	s_add_u32 s0, s0, 0x8000
	v_sub_u32_e32 v21, v210, v3
	v_lshlrev_b32_e32 v36, 13, v2
	s_addc_u32 s1, s1, 0
	v_ashrrev_i32_e32 v37, 31, v36
	v_lshlrev_b32_e32 v32, 4, v21
	v_lshl_add_u64 v[2:3], v[36:37], 1, s[0:1]
	v_ashrrev_i32_e32 v33, 31, v32
	v_lshl_add_u64 v[2:3], v[32:33], 1, v[2:3]
	global_load_dwordx4 v[10:13], v[2:3], off offset:16 nt
	global_load_dwordx4 v[14:17], v[2:3], off nt
	v_cmp_lt_i32_e32 vcc, 0, v21
	s_and_saveexec_b64 s[62:63], vcc
	s_cbranch_execz .LBB0_540
	global_load_ushort v41, v[2:3], off offset:-2

.LBB0_546:
	s_or_b64 exec, exec, s[0:1]
	v_mov_b32_e32 v25, v210
	s_mov_b32 s62, s37
	v_and_b32_e32 v28, 0xff, v25
	v_lshlrev_b32_e32 v34, 5, v25
	v_cvt_f32_ubyte0_e32 v25, v25
	v_mul_f32_e32 v25, 0x39000000, v25
	v_sin_f32_e32 v43, v25
	v_cos_f32_e32 v42, v25
	v_and_or_b32 v28, v34, s33, v28
	v_ashrrev_i32_e32 v34, 5, v28
	v_xor_b32_e32 v44, 0x80000000, v43
	v_mov_b32_e32 v45, v43
	v_pk_mul_f32 v[46:47], v[42:43], v[44:45] op_sel:[1,0] op_sel_hi:[0,1]
	v_pk_fma_f32 v[46:47], v[42:43], v[42:43], v[46:47] op_sel_hi:[1,0,1]
	v_lshlrev_b32_e32 v28, 3, v28
	v_xor_b32_e32 v50, 0x80000000, v47
	v_mov_b32_e32 v51, v47
	v_pk_mul_f32 v[52:53], v[46:47], v[50:51] op_sel:[1,0] op_sel_hi:[0,1]
	v_pk_fma_f32 v[52:53], v[46:47], v[46:47], v[52:53] op_sel_hi:[1,0,1]
	v_lshlrev_b32_e32 v34, 3, v34
	v_xor_b32_e32 v54, 0x80000000, v53
	v_mov_b32_e32 v55, v53
	v_pk_mul_f32 v[70:71], v[52:53], v[54:55] op_sel:[1,0] op_sel_hi:[0,1]
	v_pk_fma_f32 v[70:71], v[52:53], v[52:53], v[70:71] op_sel_hi:[1,0,1]
	v_pk_mul_f32 v[48:49], v[44:45], v[46:47] op_sel:[0,1] op_sel_hi:[1,0]
	v_pk_mul_f32 v[86:87], v[54:55], v[70:71] op_sel:[0,1] op_sel_hi:[1,0]
	v_add3_u32 v25, 0, v28, v34
	v_pk_fma_f32 v[86:87], v[52:53], v[70:71], v[86:87] op_sel_hi:[0,1,1]
	v_pk_mul_f32 v[102:103], v[54:55], v[86:87] op_sel:[0,1] op_sel_hi:[1,0]
	v_pk_fma_f32 v[48:49], v[42:43], v[46:47], v[48:49] op_sel_hi:[0,1,1]
	v_pk_fma_f32 v[102:103], v[52:53], v[86:87], v[102:103] op_sel_hi:[0,1,1]
	v_pk_mul_f32 v[118:119], v[54:55], v[102:103] op_sel:[0,1] op_sel_hi:[1,0]
	v_xor_b32_e32 v56, 0x80000000, v49
	v_pk_fma_f32 v[118:119], v[52:53], v[102:103], v[118:119] op_sel_hi:[0,1,1]
	v_pk_mul_f32 v[134:135], v[54:55], v[118:119] op_sel:[0,1] op_sel_hi:[1,0]
	v_mov_b32_e32 v57, v49
	v_pk_fma_f32 v[134:135], v[52:53], v[118:119], v[134:135] op_sel_hi:[0,1,1]
	v_pk_mul_f32 v[152:153], v[54:55], v[134:135] op_sel:[0,1] op_sel_hi:[1,0]
	v_pk_mul_f32 v[58:59], v[44:45], v[52:53] op_sel:[0,1] op_sel_hi:[1,0]
	v_pk_fma_f32 v[152:153], v[52:53], v[134:135], v[152:153] op_sel_hi:[0,1,1]
	v_pk_mul_f32 v[74:75], v[44:45], v[70:71] op_sel:[0,1] op_sel_hi:[1,0]
	v_pk_mul_f32 v[90:91], v[44:45], v[86:87] op_sel:[0,1] op_sel_hi:[1,0]
	v_pk_mul_f32 v[106:107], v[44:45], v[102:103] op_sel:[0,1] op_sel_hi:[1,0]
	v_pk_mul_f32 v[122:123], v[44:45], v[118:119] op_sel:[0,1] op_sel_hi:[1,0]
	v_pk_mul_f32 v[138:139], v[44:45], v[134:135] op_sel:[0,1] op_sel_hi:[1,0]
	v_pk_mul_f32 v[156:157], v[44:45], v[152:153] op_sel:[0,1] op_sel_hi:[1,0]
	ds_read_b64 v[168:169], v25
	ds_read_b64 v[170:171], v25 offset:2112
	ds_read_b64 v[172:173], v25 offset:4224
	ds_read_b64 v[174:175], v25 offset:6336
	ds_read_b64 v[176:177], v25 offset:8448
	ds_read_b64 v[178:179], v25 offset:10560
	ds_read_b64 v[180:181], v25 offset:12672
	ds_read_b64 v[182:183], v25 offset:14784
	ds_read_b64 v[184:185], v25 offset:16896
	ds_read_b64 v[186:187], v25 offset:19008
	ds_read_b64 v[188:189], v25 offset:21120
	ds_read_b64 v[190:191], v25 offset:23232
	ds_read_b64 v[192:193], v25 offset:25344
	ds_read_b64 v[194:195], v25 offset:27456
	ds_read_b64 v[196:197], v25 offset:29568
	ds_read_b64 v[198:199], v25 offset:31680
	ds_read_b64 v[212:213], v25 offset:33792
	ds_read_b64 v[214:215], v25 offset:35904
	ds_read_b64 v[216:217], v25 offset:38016
	ds_read_b64 v[218:219], v25 offset:40128
	ds_read_b64 v[220:221], v25 offset:42240
	ds_read_b64 v[222:223], v25 offset:44352
	ds_read_b64 v[224:225], v25 offset:46464
	ds_read_b64 v[226:227], v25 offset:48576
	ds_read_b64 v[228:229], v25 offset:50688
	ds_read_b64 v[230:231], v25 offset:52800
	ds_read_b64 v[232:233], v25 offset:54912
	ds_read_b64 v[234:235], v25 offset:57024
	ds_read_b64 v[236:237], v25 offset:59136
	ds_read_b64 v[238:239], v25 offset:61248
	ds_read_b64 v[240:241], v25 offset:63360
	ds_read_b64 v[242:243], v25 offset:65472
	s_waitcnt lgkmcnt(14)
	v_pk_mul_f32 v[44:45], v[44:45], v[212:213] op_sel:[0,1] op_sel_hi:[1,0]
	v_pk_fma_f32 v[58:59], v[42:43], v[52:53], v[58:59] op_sel_hi:[0,1,1]
	v_pk_mul_f32 v[62:63], v[50:51], v[52:53] op_sel:[0,1] op_sel_hi:[1,0]
	v_pk_mul_f32 v[66:67], v[52:53], v[56:57] op_sel:[1,0] op_sel_hi:[0,1]
	v_pk_fma_f32 v[74:75], v[42:43], v[70:71], v[74:75] op_sel_hi:[0,1,1]
	v_pk_mul_f32 v[78:79], v[50:51], v[70:71] op_sel:[0,1] op_sel_hi:[1,0]
	v_pk_fma_f32 v[90:91], v[42:43], v[86:87], v[90:91] op_sel_hi:[0,1,1]
	v_pk_mul_f32 v[94:95], v[50:51], v[86:87] op_sel:[0,1] op_sel_hi:[1,0]
	v_pk_fma_f32 v[106:107], v[42:43], v[102:103], v[106:107] op_sel_hi:[0,1,1]
	v_pk_mul_f32 v[110:111], v[50:51], v[102:103] op_sel:[0,1] op_sel_hi:[1,0]
	v_pk_fma_f32 v[122:123], v[42:43], v[118:119], v[122:123] op_sel_hi:[0,1,1]
	v_pk_mul_f32 v[126:127], v[50:51], v[118:119] op_sel:[0,1] op_sel_hi:[1,0]
	v_pk_fma_f32 v[138:139], v[42:43], v[134:135], v[138:139] op_sel_hi:[0,1,1]
	v_pk_mul_f32 v[142:143], v[50:51], v[134:135] op_sel:[0,1] op_sel_hi:[1,0]
	v_pk_fma_f32 v[156:157], v[42:43], v[152:153], v[156:157] op_sel_hi:[0,1,1]
	v_pk_mul_f32 v[160:161], v[50:51], v[152:153] op_sel:[0,1] op_sel_hi:[1,0]
	v_pk_fma_f32 v[42:43], v[42:43], v[212:213], v[44:45] op_sel_hi:[0,1,1]
	v_pk_mul_f32 v[44:45], v[184:185], v[50:51] op_sel:[1,0] op_sel_hi:[0,1]
	v_pk_fma_f32 v[62:63], v[46:47], v[52:53], v[62:63] op_sel_hi:[0,1,1]
	v_pk_fma_f32 v[66:67], v[52:53], v[48:49], v[66:67] op_sel_hi:[1,0,1]
	v_pk_fma_f32 v[78:79], v[46:47], v[70:71], v[78:79] op_sel_hi:[0,1,1]
	v_pk_mul_f32 v[82:83], v[56:57], v[70:71] op_sel:[0,1] op_sel_hi:[1,0]
	v_pk_fma_f32 v[94:95], v[46:47], v[86:87], v[94:95] op_sel_hi:[0,1,1]
	v_pk_mul_f32 v[98:99], v[56:57], v[86:87] op_sel:[0,1] op_sel_hi:[1,0]
	v_pk_fma_f32 v[110:111], v[46:47], v[102:103], v[110:111] op_sel_hi:[0,1,1]
	v_pk_mul_f32 v[114:115], v[56:57], v[102:103] op_sel:[0,1] op_sel_hi:[1,0]
	v_pk_fma_f32 v[126:127], v[46:47], v[118:119], v[126:127] op_sel_hi:[0,1,1]
	v_pk_mul_f32 v[130:131], v[56:57], v[118:119] op_sel:[0,1] op_sel_hi:[1,0]
	v_pk_fma_f32 v[142:143], v[46:47], v[134:135], v[142:143] op_sel_hi:[0,1,1]
	v_pk_mul_f32 v[148:149], v[56:57], v[134:135] op_sel:[0,1] op_sel_hi:[1,0]
	v_pk_fma_f32 v[160:161], v[46:47], v[152:153], v[160:161] op_sel_hi:[0,1,1]
	v_pk_mul_f32 v[164:165], v[56:57], v[152:153] op_sel:[0,1] op_sel_hi:[1,0]
	v_pk_fma_f32 v[44:45], v[184:185], v[46:47], v[44:45] op_sel_hi:[1,0,1]
	s_waitcnt lgkmcnt(7)
	v_pk_mul_f32 v[46:47], v[56:57], v[228:229] op_sel:[0,1] op_sel_hi:[1,0]
	v_xor_b32_e32 v60, 0x80000000, v59
	v_xor_b32_e32 v64, 0x80000000, v63
	v_xor_b32_e32 v68, 0x80000000, v67
	v_xor_b32_e32 v72, 0x80000000, v71
	v_pk_fma_f32 v[82:83], v[48:49], v[70:71], v[82:83] op_sel_hi:[0,1,1]
	v_pk_fma_f32 v[98:99], v[48:49], v[86:87], v[98:99] op_sel_hi:[0,1,1]
	v_pk_fma_f32 v[114:115], v[48:49], v[102:103], v[114:115] op_sel_hi:[0,1,1]
	v_pk_fma_f32 v[130:131], v[48:49], v[118:119], v[130:131] op_sel_hi:[0,1,1]
	v_pk_fma_f32 v[148:149], v[48:49], v[134:135], v[148:149] op_sel_hi:[0,1,1]
	v_pk_fma_f32 v[164:165], v[48:49], v[152:153], v[164:165] op_sel_hi:[0,1,1]
	v_mov_b32_e32 v61, v59
	v_mov_b32_e32 v65, v63
	v_mov_b32_e32 v69, v67
	v_mov_b32_e32 v73, v71
	v_pk_fma_f32 v[46:47], v[48:49], v[228:229], v[46:47] op_sel_hi:[0,1,1]
	v_pk_mul_f32 v[48:49], v[176:177], v[54:55] op_sel:[1,0] op_sel_hi:[0,1]
	v_xor_b32_e32 v76, 0x80000000, v75
	v_xor_b32_e32 v80, 0x80000000, v79
	v_xor_b32_e32 v84, 0x80000000, v83
	v_xor_b32_e32 v88, 0x80000000, v87
	v_xor_b32_e32 v92, 0x80000000, v91
	v_xor_b32_e32 v96, 0x80000000, v95
	v_xor_b32_e32 v100, 0x80000000, v99
	v_xor_b32_e32 v104, 0x80000000, v103
	v_xor_b32_e32 v136, 0x80000000, v135
	v_mov_b32_e32 v77, v75
	v_mov_b32_e32 v81, v79
	v_mov_b32_e32 v85, v83
	v_mov_b32_e32 v89, v87
	v_mov_b32_e32 v93, v91
	v_mov_b32_e32 v97, v95
	v_mov_b32_e32 v101, v99
	v_mov_b32_e32 v105, v103
	v_mov_b32_e32 v137, v135
	v_pk_fma_f32 v[48:49], v[176:177], v[52:53], v[48:49] op_sel_hi:[1,0,1]
	v_pk_mul_f32 v[50:51], v[60:61], v[220:221] op_sel:[0,1] op_sel_hi:[1,0]
	v_pk_mul_f32 v[52:53], v[192:193], v[64:65] op_sel:[1,0] op_sel_hi:[0,1]
	s_waitcnt lgkmcnt(3)
	v_pk_mul_f32 v[54:55], v[68:69], v[236:237] op_sel:[0,1] op_sel_hi:[1,0]
	v_pk_mul_f32 v[56:57], v[172:173], v[72:73] op_sel:[1,0] op_sel_hi:[0,1]
	v_xor_b32_e32 v108, 0x80000000, v107
	v_xor_b32_e32 v112, 0x80000000, v111
	v_xor_b32_e32 v116, 0x80000000, v115
	v_xor_b32_e32 v120, 0x80000000, v119
	v_xor_b32_e32 v124, 0x80000000, v123
	v_xor_b32_e32 v128, 0x80000000, v127
	v_xor_b32_e32 v132, 0x80000000, v131
	v_xor_b32_e32 v140, 0x80000000, v139
	v_xor_b32_e32 v144, 0x80000000, v143
	v_xor_b32_e32 v150, 0x80000000, v149
	v_xor_b32_e32 v154, 0x80000000, v153
	v_xor_b32_e32 v158, 0x80000000, v157
	v_xor_b32_e32 v162, 0x80000000, v161
	v_xor_b32_e32 v166, 0x80000000, v165
	v_mov_b32_e32 v109, v107
	v_mov_b32_e32 v113, v111
	v_mov_b32_e32 v117, v115
	v_mov_b32_e32 v121, v119
	v_mov_b32_e32 v125, v123
	v_mov_b32_e32 v129, v127
	v_mov_b32_e32 v133, v131
	v_mov_b32_e32 v141, v139
	v_mov_b32_e32 v145, v143
	v_mov_b32_e32 v151, v149
	v_mov_b32_e32 v155, v153
	v_mov_b32_e32 v159, v157
	v_mov_b32_e32 v163, v161
	v_mov_b32_e32 v167, v165
	v_pk_fma_f32 v[50:51], v[58:59], v[220:221], v[50:51] op_sel_hi:[0,1,1]
	v_pk_fma_f32 v[52:53], v[192:193], v[62:63], v[52:53] op_sel_hi:[1,0,1]
	v_pk_fma_f32 v[54:55], v[66:67], v[236:237], v[54:55] op_sel_hi:[0,1,1]
	v_pk_fma_f32 v[56:57], v[172:173], v[70:71], v[56:57] op_sel_hi:[1,0,1]
	v_pk_mul_f32 v[58:59], v[216:217], v[76:77] op_sel:[1,0] op_sel_hi:[0,1]
	v_pk_mul_f32 v[60:61], v[188:189], v[80:81] op_sel:[1,0] op_sel_hi:[0,1]
	v_pk_mul_f32 v[62:63], v[84:85], v[232:233] op_sel:[0,1] op_sel_hi:[1,0]
	v_pk_mul_f32 v[64:65], v[180:181], v[88:89] op_sel:[1,0] op_sel_hi:[0,1]
	v_pk_mul_f32 v[66:67], v[224:225], v[92:93] op_sel:[1,0] op_sel_hi:[0,1]
	v_pk_mul_f32 v[68:69], v[196:197], v[96:97] op_sel:[1,0] op_sel_hi:[0,1]
	s_waitcnt lgkmcnt(1)
	v_pk_mul_f32 v[70:71], v[100:101], v[240:241] op_sel:[0,1] op_sel_hi:[1,0]
	v_pk_mul_f32 v[72:73], v[170:171], v[104:105] op_sel:[1,0] op_sel_hi:[0,1]
	v_pk_mul_f32 v[88:89], v[174:175], v[136:137] op_sel:[1,0] op_sel_hi:[0,1]
	v_pk_fma_f32 v[58:59], v[216:217], v[74:75], v[58:59] op_sel_hi:[1,0,1]
	v_pk_fma_f32 v[60:61], v[188:189], v[78:79], v[60:61] op_sel_hi:[1,0,1]
	v_pk_fma_f32 v[62:63], v[82:83], v[232:233], v[62:63] op_sel_hi:[0,1,1]
	v_pk_fma_f32 v[64:65], v[180:181], v[86:87], v[64:65] op_sel_hi:[1,0,1]
	v_pk_fma_f32 v[66:67], v[224:225], v[90:91], v[66:67] op_sel_hi:[1,0,1]
	v_pk_fma_f32 v[68:69], v[196:197], v[94:95], v[68:69] op_sel_hi:[1,0,1]
	v_pk_fma_f32 v[70:71], v[98:99], v[240:241], v[70:71] op_sel_hi:[0,1,1]
	v_pk_fma_f32 v[72:73], v[170:171], v[102:103], v[72:73] op_sel_hi:[1,0,1]
	v_pk_mul_f32 v[74:75], v[214:215], v[108:109] op_sel:[1,0] op_sel_hi:[0,1]
	v_pk_mul_f32 v[76:77], v[186:187], v[112:113] op_sel:[1,0] op_sel_hi:[0,1]
	v_pk_mul_f32 v[78:79], v[230:231], v[116:117] op_sel:[1,0] op_sel_hi:[0,1]
	v_pk_mul_f32 v[80:81], v[178:179], v[120:121] op_sel:[1,0] op_sel_hi:[0,1]
	v_pk_mul_f32 v[82:83], v[222:223], v[124:125] op_sel:[1,0] op_sel_hi:[0,1]
	v_pk_mul_f32 v[84:85], v[194:195], v[128:129] op_sel:[1,0] op_sel_hi:[0,1]
	v_pk_mul_f32 v[86:87], v[132:133], v[238:239] op_sel:[0,1] op_sel_hi:[1,0]
	v_pk_fma_f32 v[88:89], v[174:175], v[134:135], v[88:89] op_sel_hi:[1,0,1]
	v_pk_mul_f32 v[90:91], v[218:219], v[140:141] op_sel:[1,0] op_sel_hi:[0,1]
	v_pk_mul_f32 v[92:93], v[190:191], v[144:145] op_sel:[1,0] op_sel_hi:[0,1]
	v_pk_mul_f32 v[94:95], v[234:235], v[150:151] op_sel:[1,0] op_sel_hi:[0,1]
	v_pk_mul_f32 v[96:97], v[182:183], v[154:155] op_sel:[1,0] op_sel_hi:[0,1]
	v_pk_mul_f32 v[98:99], v[226:227], v[158:159] op_sel:[1,0] op_sel_hi:[0,1]
	v_pk_mul_f32 v[100:101], v[198:199], v[162:163] op_sel:[1,0] op_sel_hi:[0,1]
	s_waitcnt lgkmcnt(0)
	v_pk_mul_f32 v[102:103], v[242:243], v[166:167] op_sel:[1,0] op_sel_hi:[0,1]
	v_pk_fma_f32 v[74:75], v[214:215], v[106:107], v[74:75] op_sel_hi:[1,0,1]
	v_pk_fma_f32 v[76:77], v[186:187], v[110:111], v[76:77] op_sel_hi:[1,0,1]
	v_pk_fma_f32 v[78:79], v[230:231], v[114:115], v[78:79] op_sel_hi:[1,0,1]
	v_pk_fma_f32 v[80:81], v[178:179], v[118:119], v[80:81] op_sel_hi:[1,0,1]
	v_pk_fma_f32 v[82:83], v[222:223], v[122:123], v[82:83] op_sel_hi:[1,0,1]
	v_pk_fma_f32 v[84:85], v[194:195], v[126:127], v[84:85] op_sel_hi:[1,0,1]
	v_pk_fma_f32 v[86:87], v[130:131], v[238:239], v[86:87] op_sel_hi:[0,1,1]
	v_pk_fma_f32 v[90:91], v[218:219], v[138:139], v[90:91] op_sel_hi:[1,0,1]
	v_pk_fma_f32 v[92:93], v[190:191], v[142:143], v[92:93] op_sel_hi:[1,0,1]
	v_pk_fma_f32 v[94:95], v[234:235], v[148:149], v[94:95] op_sel_hi:[1,0,1]
	v_pk_fma_f32 v[96:97], v[182:183], v[152:153], v[96:97] op_sel_hi:[1,0,1]
	v_pk_fma_f32 v[98:99], v[226:227], v[156:157], v[98:99] op_sel_hi:[1,0,1]
	v_pk_fma_f32 v[100:101], v[198:199], v[160:161], v[100:101] op_sel_hi:[1,0,1]
	v_pk_fma_f32 v[102:103], v[242:243], v[164:165], v[102:103] op_sel_hi:[1,0,1]
	v_pk_add_f32 v[104:105], v[168:169], v[72:73]
	v_pk_add_f32 v[106:107], v[56:57], v[88:89]
	v_pk_add_f32 v[56:57], v[56:57], v[88:89] neg_lo:[0,1] neg_hi:[0,1]
	v_pk_add_f32 v[72:73], v[168:169], v[72:73] neg_lo:[0,1] neg_hi:[0,1]
	v_pk_add_f32 v[88:89], v[48:49], v[80:81]
	v_pk_add_f32 v[48:49], v[48:49], v[80:81] neg_lo:[0,1] neg_hi:[0,1]
	v_pk_add_f32 v[80:81], v[64:65], v[96:97]
	v_pk_add_f32 v[64:65], v[64:65], v[96:97] neg_lo:[0,1] neg_hi:[0,1]
	v_pk_add_f32 v[96:97], v[44:45], v[76:77]
	v_pk_add_f32 v[44:45], v[44:45], v[76:77] neg_lo:[0,1] neg_hi:[0,1]
	v_pk_add_f32 v[76:77], v[60:61], v[92:93]
	v_pk_add_f32 v[60:61], v[60:61], v[92:93] neg_lo:[0,1] neg_hi:[0,1]
	v_pk_add_f32 v[92:93], v[52:53], v[84:85]
	v_pk_add_f32 v[52:53], v[52:53], v[84:85] neg_lo:[0,1] neg_hi:[0,1]
	v_pk_add_f32 v[84:85], v[68:69], v[100:101]
	v_pk_add_f32 v[68:69], v[68:69], v[100:101] neg_lo:[0,1] neg_hi:[0,1]
	v_pk_add_f32 v[100:101], v[42:43], v[74:75]
	v_pk_add_f32 v[42:43], v[42:43], v[74:75] neg_lo:[0,1] neg_hi:[0,1]
	v_pk_add_f32 v[74:75], v[58:59], v[90:91]
	v_pk_add_f32 v[58:59], v[58:59], v[90:91] neg_lo:[0,1] neg_hi:[0,1]
	v_pk_add_f32 v[90:91], v[50:51], v[82:83]
	v_pk_add_f32 v[50:51], v[50:51], v[82:83] neg_lo:[0,1] neg_hi:[0,1]
	v_pk_add_f32 v[82:83], v[66:67], v[98:99]
	v_pk_add_f32 v[66:67], v[66:67], v[98:99] neg_lo:[0,1] neg_hi:[0,1]
	v_pk_add_f32 v[98:99], v[46:47], v[78:79]
	v_pk_add_f32 v[46:47], v[46:47], v[78:79] neg_lo:[0,1] neg_hi:[0,1]
	v_pk_add_f32 v[78:79], v[62:63], v[94:95]
	v_pk_add_f32 v[62:63], v[62:63], v[94:95] neg_lo:[0,1] neg_hi:[0,1]
	v_pk_add_f32 v[94:95], v[54:55], v[86:87]
	v_pk_add_f32 v[54:55], v[54:55], v[86:87] neg_lo:[0,1] neg_hi:[0,1]
	v_pk_add_f32 v[86:87], v[70:71], v[102:103]
	v_pk_add_f32 v[70:71], v[70:71], v[102:103] neg_lo:[0,1] neg_hi:[0,1]
	v_pk_add_f32 v[102:103], v[104:105], v[106:107]
	v_pk_add_f32 v[104:105], v[104:105], v[106:107] neg_lo:[0,1] neg_hi:[0,1]
	v_xor_b32_e32 v106, 0x80000000, v57
	v_mov_b32_e32 v107, v56
	v_pk_add_f32 v[56:57], v[72:73], v[106:107]
	v_pk_add_f32 v[72:73], v[72:73], v[106:107] neg_lo:[0,1] neg_hi:[0,1]
	v_pk_add_f32 v[106:107], v[88:89], v[80:81]
	v_pk_add_f32 v[80:81], v[88:89], v[80:81] neg_lo:[0,1] neg_hi:[0,1]
	v_xor_b32_e32 v88, 0x80000000, v65
	v_mov_b32_e32 v89, v64
	v_pk_add_f32 v[64:65], v[48:49], v[88:89]
	v_pk_add_f32 v[48:49], v[48:49], v[88:89] neg_lo:[0,1] neg_hi:[0,1]
	v_pk_add_f32 v[88:89], v[96:97], v[76:77]
	v_pk_add_f32 v[76:77], v[96:97], v[76:77] neg_lo:[0,1] neg_hi:[0,1]
	v_xor_b32_e32 v96, 0x80000000, v61
	v_mov_b32_e32 v97, v60
	v_pk_add_f32 v[60:61], v[44:45], v[96:97]
	v_pk_add_f32 v[44:45], v[44:45], v[96:97] neg_lo:[0,1] neg_hi:[0,1]
	v_pk_add_f32 v[96:97], v[92:93], v[84:85]
	v_pk_add_f32 v[84:85], v[92:93], v[84:85] neg_lo:[0,1] neg_hi:[0,1]
	v_xor_b32_e32 v92, 0x80000000, v69
	v_mov_b32_e32 v93, v68
	v_pk_add_f32 v[68:69], v[52:53], v[92:93]
	v_pk_add_f32 v[52:53], v[52:53], v[92:93] neg_lo:[0,1] neg_hi:[0,1]
	v_pk_add_f32 v[92:93], v[100:101], v[74:75]
	v_pk_add_f32 v[74:75], v[100:101], v[74:75] neg_lo:[0,1] neg_hi:[0,1]
	v_xor_b32_e32 v100, 0x80000000, v59
	v_mov_b32_e32 v101, v58
	v_pk_add_f32 v[58:59], v[42:43], v[100:101]
	v_pk_add_f32 v[42:43], v[42:43], v[100:101] neg_lo:[0,1] neg_hi:[0,1]
	v_pk_add_f32 v[100:101], v[90:91], v[82:83]
	v_pk_add_f32 v[82:83], v[90:91], v[82:83] neg_lo:[0,1] neg_hi:[0,1]
	v_xor_b32_e32 v90, 0x80000000, v67
	v_mov_b32_e32 v91, v66
	v_pk_add_f32 v[66:67], v[50:51], v[90:91]
	v_pk_add_f32 v[50:51], v[50:51], v[90:91] neg_lo:[0,1] neg_hi:[0,1]
	v_pk_add_f32 v[90:91], v[98:99], v[78:79]
	v_pk_add_f32 v[78:79], v[98:99], v[78:79] neg_lo:[0,1] neg_hi:[0,1]
	v_xor_b32_e32 v98, 0x80000000, v63
	v_mov_b32_e32 v99, v62
	v_pk_add_f32 v[62:63], v[46:47], v[98:99]
	v_pk_add_f32 v[46:47], v[46:47], v[98:99] neg_lo:[0,1] neg_hi:[0,1]
	v_pk_add_f32 v[98:99], v[94:95], v[86:87]
	v_pk_add_f32 v[86:87], v[94:95], v[86:87] neg_lo:[0,1] neg_hi:[0,1]
	v_xor_b32_e32 v94, 0x80000000, v71
	v_mov_b32_e32 v95, v70
	s_mov_b32 s63, s36
	v_pk_add_f32 v[70:71], v[54:55], v[94:95]
	v_pk_add_f32 v[54:55], v[54:55], v[94:95] neg_lo:[0,1] neg_hi:[0,1]
	v_pk_add_f32 v[94:95], v[102:103], v[106:107]
	v_pk_add_f32 v[102:103], v[102:103], v[106:107] neg_lo:[0,1] neg_hi:[0,1]
	s_mov_b32 s0, s37
	v_pk_mul_f32 v[106:107], v[64:65], s[62:63]
	s_mov_b32 s64, s19
	v_pk_fma_f32 v[64:65], v[64:65], s[0:1], v[106:107] op_sel:[0,0,1] op_sel_hi:[1,0,0]
	s_mov_b32 s65, s18
	v_pk_add_f32 v[106:107], v[56:57], v[64:65]
	v_pk_add_f32 v[56:57], v[56:57], v[64:65] neg_lo:[0,1] neg_hi:[0,1]
	v_xor_b32_e32 v64, 0x80000000, v81
	v_mov_b32_e32 v65, v80
	v_pk_add_f32 v[80:81], v[104:105], v[64:65]
	v_pk_add_f32 v[64:65], v[104:105], v[64:65] neg_lo:[0,1] neg_hi:[0,1]
	v_pk_mul_f32 v[104:105], v[48:49], s[62:63]
	s_mov_b32 s66, s19
	v_pk_fma_f32 v[48:49], v[48:49], s[0:1], v[104:105] op_sel:[0,0,1] op_sel_hi:[1,0,0] neg_lo:[1,0,0] neg_hi:[1,0,0]
	s_mov_b32 s68, s11
	v_pk_add_f32 v[104:105], v[72:73], v[48:49]
	v_pk_add_f32 v[48:49], v[72:73], v[48:49] neg_lo:[0,1] neg_hi:[0,1]
	v_pk_add_f32 v[72:73], v[88:89], v[96:97]
	v_pk_add_f32 v[88:89], v[88:89], v[96:97] neg_lo:[0,1] neg_hi:[0,1]
	v_pk_mul_f32 v[96:97], v[68:69], s[62:63]
	s_mov_b32 s69, s10
	v_pk_fma_f32 v[68:69], v[68:69], s[0:1], v[96:97] op_sel:[0,0,1] op_sel_hi:[1,0,0]
	s_mov_b32 s72, s27
	v_pk_add_f32 v[96:97], v[60:61], v[68:69]
	v_pk_add_f32 v[60:61], v[60:61], v[68:69] neg_lo:[0,1] neg_hi:[0,1]
	v_xor_b32_e32 v68, 0x80000000, v85
	v_mov_b32_e32 v69, v84
	v_pk_add_f32 v[84:85], v[76:77], v[68:69]
	v_pk_add_f32 v[68:69], v[76:77], v[68:69] neg_lo:[0,1] neg_hi:[0,1]
	v_pk_mul_f32 v[76:77], v[52:53], s[62:63]
	v_pk_mul_f32 v[108:109], v[96:97], s[64:65]
	v_pk_fma_f32 v[52:53], v[52:53], s[0:1], v[76:77] op_sel:[0,0,1] op_sel_hi:[1,0,0] neg_lo:[1,0,0] neg_hi:[1,0,0]
	v_pk_fma_f32 v[96:97], v[96:97], s[16:17], v[108:109] op_sel:[0,0,1] op_sel_hi:[1,0,0]
	v_pk_add_f32 v[76:77], v[44:45], v[52:53]
	v_pk_add_f32 v[44:45], v[44:45], v[52:53] neg_lo:[0,1] neg_hi:[0,1]
	v_pk_add_f32 v[52:53], v[92:93], v[100:101]
	v_pk_add_f32 v[92:93], v[92:93], v[100:101] neg_lo:[0,1] neg_hi:[0,1]
	v_pk_mul_f32 v[100:101], v[66:67], s[62:63]
	s_mov_b32 s17, s40
	v_pk_fma_f32 v[66:67], v[66:67], s[0:1], v[100:101] op_sel:[0,0,1] op_sel_hi:[1,0,0]
	v_pk_add_f32 v[108:109], v[106:107], v[96:97]
	v_pk_add_f32 v[100:101], v[58:59], v[66:67]
	v_pk_add_f32 v[58:59], v[58:59], v[66:67] neg_lo:[0,1] neg_hi:[0,1]
	v_xor_b32_e32 v66, 0x80000000, v83
	v_mov_b32_e32 v67, v82
	v_pk_add_f32 v[82:83], v[74:75], v[66:67]
	v_pk_add_f32 v[66:67], v[74:75], v[66:67] neg_lo:[0,1] neg_hi:[0,1]
	v_pk_mul_f32 v[74:75], v[50:51], s[62:63]
	v_pk_add_f32 v[96:97], v[106:107], v[96:97] neg_lo:[0,1] neg_hi:[0,1]
	v_pk_fma_f32 v[50:51], v[50:51], s[0:1], v[74:75] op_sel:[0,0,1] op_sel_hi:[1,0,0] neg_lo:[1,0,0] neg_hi:[1,0,0]
	v_pk_mul_f32 v[106:107], v[84:85], s[62:63]
	v_pk_add_f32 v[74:75], v[42:43], v[50:51]
	v_pk_add_f32 v[42:43], v[42:43], v[50:51] neg_lo:[0,1] neg_hi:[0,1]
	v_pk_add_f32 v[50:51], v[90:91], v[98:99]
	v_pk_add_f32 v[90:91], v[90:91], v[98:99] neg_lo:[0,1] neg_hi:[0,1]
	v_pk_mul_f32 v[98:99], v[70:71], s[62:63]
	v_pk_fma_f32 v[84:85], v[84:85], s[0:1], v[106:107] op_sel:[0,0,1] op_sel_hi:[1,0,0]
	v_pk_fma_f32 v[70:71], v[70:71], s[0:1], v[98:99] op_sel:[0,0,1] op_sel_hi:[1,0,0]
	v_pk_add_f32 v[106:107], v[80:81], v[84:85]
	v_pk_add_f32 v[98:99], v[62:63], v[70:71]
	v_pk_add_f32 v[62:63], v[62:63], v[70:71] neg_lo:[0,1] neg_hi:[0,1]
	v_xor_b32_e32 v70, 0x80000000, v87
	v_mov_b32_e32 v71, v86
	v_pk_mul_f32 v[110:111], v[98:99], s[64:65]
	v_pk_add_f32 v[86:87], v[78:79], v[70:71]
	v_pk_add_f32 v[70:71], v[78:79], v[70:71] neg_lo:[0,1] neg_hi:[0,1]
	v_pk_mul_f32 v[78:79], v[54:55], s[62:63]
	v_pk_fma_f32 v[98:99], v[98:99], s[16:17], v[110:111] op_sel:[0,0,1] op_sel_hi:[1,0,0]
	v_pk_fma_f32 v[54:55], v[54:55], s[0:1], v[78:79] op_sel:[0,0,1] op_sel_hi:[1,0,0] neg_lo:[1,0,0] neg_hi:[1,0,0]
	v_pk_add_f32 v[110:111], v[100:101], v[98:99]
	v_pk_add_f32 v[98:99], v[100:101], v[98:99] neg_lo:[0,1] neg_hi:[0,1]
	v_pk_mul_f32 v[100:101], v[86:87], s[62:63]
	v_pk_add_f32 v[78:79], v[46:47], v[54:55]
	v_pk_fma_f32 v[86:87], v[86:87], s[0:1], v[100:101] op_sel:[0,0,1] op_sel_hi:[1,0,0]
	v_pk_add_f32 v[46:47], v[46:47], v[54:55] neg_lo:[0,1] neg_hi:[0,1]
	v_pk_add_f32 v[100:101], v[82:83], v[86:87]
	v_pk_add_f32 v[82:83], v[82:83], v[86:87] neg_lo:[0,1] neg_hi:[0,1]
	v_pk_mul_f32 v[86:87], v[78:79], s[16:17]
	v_pk_add_f32 v[80:81], v[80:81], v[84:85] neg_lo:[0,1] neg_hi:[0,1]
	v_pk_fma_f32 v[78:79], v[78:79], s[66:67], v[86:87] op_sel:[0,0,1] op_sel_hi:[1,0,0]
	v_pk_mul_f32 v[84:85], v[76:77], s[16:17]
	v_pk_add_f32 v[86:87], v[74:75], v[78:79]
	v_pk_add_f32 v[74:75], v[74:75], v[78:79] neg_lo:[0,1] neg_hi:[0,1]
	v_xor_b32_e32 v78, 0x80000000, v91
	v_mov_b32_e32 v79, v90
	v_pk_add_f32 v[90:91], v[92:93], v[78:79]
	v_pk_add_f32 v[78:79], v[92:93], v[78:79] neg_lo:[0,1] neg_hi:[0,1]
	v_pk_mul_f32 v[92:93], v[62:63], s[16:17]
	v_pk_fma_f32 v[76:77], v[76:77], s[66:67], v[84:85] op_sel:[0,0,1] op_sel_hi:[1,0,0]
	v_pk_fma_f32 v[62:63], v[62:63], s[66:67], v[92:93] op_sel:[0,0,1] op_sel_hi:[1,0,0] neg_lo:[1,0,0] neg_hi:[1,0,0]
	v_pk_add_f32 v[84:85], v[104:105], v[76:77]
	v_pk_add_f32 v[92:93], v[58:59], v[62:63]
	v_pk_add_f32 v[58:59], v[58:59], v[62:63] neg_lo:[0,1] neg_hi:[0,1]
	v_pk_mul_f32 v[62:63], v[70:71], s[62:63]
	v_pk_add_f32 v[76:77], v[104:105], v[76:77] neg_lo:[0,1] neg_hi:[0,1]
	v_pk_fma_f32 v[62:63], v[70:71], s[0:1], v[62:63] op_sel:[0,0,1] op_sel_hi:[1,0,0] neg_lo:[1,0,0] neg_hi:[1,0,0]
	v_xor_b32_e32 v104, 0x80000000, v89
	v_pk_add_f32 v[70:71], v[66:67], v[62:63]
	v_pk_add_f32 v[62:63], v[66:67], v[62:63] neg_lo:[0,1] neg_hi:[0,1]
	v_pk_mul_f32 v[66:67], v[46:47], s[64:65]
	v_mov_b32_e32 v105, v88
	v_pk_fma_f32 v[46:47], v[46:47], s[16:17], v[66:67] op_sel:[0,0,1] op_sel_hi:[1,0,0] neg_lo:[1,0,0] neg_hi:[1,0,0]
	s_mov_b32 s73, s26
	v_pk_add_f32 v[66:67], v[42:43], v[46:47]
	v_pk_add_f32 v[42:43], v[42:43], v[46:47] neg_lo:[0,1] neg_hi:[0,1]
	v_pk_mul_f32 v[46:47], v[110:111], s[68:69]
	v_pk_add_f32 v[88:89], v[102:103], v[104:105]
	v_pk_fma_f32 v[46:47], v[110:111], s[8:9], v[46:47] op_sel:[0,0,1] op_sel_hi:[1,0,0]
	v_pk_add_f32 v[102:103], v[102:103], v[104:105] neg_lo:[0,1] neg_hi:[0,1]
	v_pk_add_f32 v[46:47], v[108:109], v[46:47]
	v_pk_mul_f32 v[108:109], v[100:101], s[64:65]
	v_pk_mul_f32 v[104:105], v[60:61], s[16:17]
	v_pk_fma_f32 v[100:101], v[100:101], s[16:17], v[108:109] op_sel:[0,0,1] op_sel_hi:[1,0,0]
	v_pk_fma_f32 v[60:61], v[60:61], s[66:67], v[104:105] op_sel:[0,0,1] op_sel_hi:[1,0,0] neg_lo:[1,0,0] neg_hi:[1,0,0]
	v_pk_add_f32 v[100:101], v[106:107], v[100:101]
	v_pk_mul_f32 v[106:107], v[86:87], s[72:73]
	v_pk_add_f32 v[104:105], v[56:57], v[60:61]
	v_pk_fma_f32 v[86:87], v[86:87], s[24:25], v[106:107] op_sel:[0,0,1] op_sel_hi:[1,0,0]
	v_pk_add_f32 v[56:57], v[56:57], v[60:61] neg_lo:[0,1] neg_hi:[0,1]
	v_pk_mul_f32 v[60:61], v[68:69], s[62:63]
	v_pk_add_f32 v[84:85], v[84:85], v[86:87]
	v_pk_mul_f32 v[86:87], v[90:91], s[62:63]
	v_pk_fma_f32 v[60:61], v[68:69], s[0:1], v[60:61] op_sel:[0,0,1] op_sel_hi:[1,0,0] neg_lo:[1,0,0] neg_hi:[1,0,0]
	v_pk_fma_f32 v[86:87], v[90:91], s[0:1], v[86:87] op_sel:[0,0,1] op_sel_hi:[1,0,0]
	v_pk_mul_f32 v[90:91], v[70:71], s[16:17]
	v_pk_add_f32 v[68:69], v[64:65], v[60:61]
	v_pk_fma_f32 v[70:71], v[70:71], s[66:67], v[90:91] op_sel:[0,0,1] op_sel_hi:[1,0,0]
	s_mov_b32 s9, s42
	s_mov_b32 s25, s38
	v_pk_add_f32 v[68:69], v[68:69], v[70:71]
	s_mov_b32 s76, s11
	v_pk_mul_f32 v[70:71], v[66:67], s[8:9]
	s_mov_b32 s74, s27
	v_pk_fma_f32 v[66:67], v[66:67], s[76:77], v[70:71] op_sel:[0,0,1] op_sel_hi:[1,0,0]
	v_pk_mul_f32 v[70:71], v[74:75], s[24:25]
	v_pk_add_f32 v[60:61], v[64:65], v[60:61] neg_lo:[0,1] neg_hi:[0,1]
	v_pk_fma_f32 v[70:71], v[74:75], s[74:75], v[70:71] op_sel:[0,0,1] op_sel_hi:[1,0,0] neg_lo:[1,0,0] neg_hi:[1,0,0]
	v_pk_mul_f32 v[64:65], v[44:45], s[64:65]
	v_pk_add_f32 v[70:71], v[76:77], v[70:71]
	v_pk_mul_f32 v[76:77], v[58:59], s[72:73]
	v_pk_fma_f32 v[44:45], v[44:45], s[16:17], v[64:65] op_sel:[0,0,1] op_sel_hi:[1,0,0] neg_lo:[1,0,0] neg_hi:[1,0,0]
	v_pk_fma_f32 v[58:59], v[58:59], s[24:25], v[76:77] op_sel:[0,0,1] op_sel_hi:[1,0,0] neg_lo:[1,0,0] neg_hi:[1,0,0]
	v_pk_add_f32 v[64:65], v[48:49], v[44:45]
	v_pk_add_f32 v[56:57], v[56:57], v[58:59]
	v_pk_mul_f32 v[58:59], v[62:63], s[64:65]
	v_pk_add_f32 v[44:45], v[48:49], v[44:45] neg_lo:[0,1] neg_hi:[0,1]
	v_pk_fma_f32 v[58:59], s[16:17], v[62:63], v[58:59] op_sel:[0,0,1] op_sel_hi:[0,1,0] neg_lo:[0,1,0] neg_hi:[0,1,0]
	v_pk_add_f32 v[58:59], v[60:61], v[58:59]
	v_pk_mul_f32 v[60:61], v[42:43], s[68:69]
	v_pk_add_f32 v[54:55], v[94:95], v[72:73] neg_lo:[0,1] neg_hi:[0,1]
	v_pk_add_f32 v[64:65], v[64:65], v[66:67]
	v_pk_add_f32 v[66:67], v[52:53], v[50:51] neg_lo:[0,1] neg_hi:[0,1]
	v_pk_fma_f32 v[42:43], v[42:43], s[8:9], v[60:61] op_sel:[0,0,1] op_sel_hi:[1,0,0] neg_lo:[1,0,0] neg_hi:[1,0,0]
	v_pk_add_f32 v[86:87], v[88:89], v[86:87]
	v_pk_mul_f32 v[88:89], v[92:93], s[24:25]
	v_pk_add_f32 v[48:49], v[54:55], v[66:67] op_sel:[0,1] op_sel_hi:[1,0] neg_lo:[0,1]
	v_pk_mul_f32 v[54:55], v[98:99], s[8:9]
	v_pk_mul_f32 v[66:67], v[82:83], s[16:17]
	v_pk_mul_f32 v[74:75], v[78:79], s[62:63]
	v_pk_add_f32 v[42:43], v[44:45], v[42:43]
	v_pk_add_f32 v[44:45], v[94:95], v[72:73]
	v_pk_add_f32 v[50:51], v[52:53], v[50:51]
	v_pk_fma_f32 v[88:89], v[92:93], s[74:75], v[88:89] op_sel:[0,0,1] op_sel_hi:[1,0,0]
	v_pk_fma_f32 v[54:55], v[98:99], s[76:77], v[54:55] op_sel:[0,0,1] op_sel_hi:[1,0,0] neg_lo:[1,0,0] neg_hi:[1,0,0]
	v_pk_fma_f32 v[66:67], v[82:83], s[66:67], v[66:67] op_sel:[0,0,1] op_sel_hi:[1,0,0] neg_lo:[1,0,0] neg_hi:[1,0,0]
	v_pk_fma_f32 v[74:75], v[78:79], s[0:1], v[74:75] op_sel:[0,0,1] op_sel_hi:[1,0,0] neg_lo:[1,0,0] neg_hi:[1,0,0]
	v_pk_add_f32 v[44:45], v[44:45], v[50:51]
	v_lshl_add_u32 v21, v21, 3, v36
	v_pk_add_f32 v[88:89], v[104:105], v[88:89]
	v_pk_add_f32 v[54:55], v[96:97], v[54:55]
	v_pk_add_f32 v[66:67], v[80:81], v[66:67]
	v_pk_add_f32 v[74:75], v[102:103], v[74:75]
	ds_write_b64 v25, v[44:45]
	ds_write_b64 v25, v[46:47] offset:2112
	ds_write_b64 v25, v[100:101] offset:4224
	ds_write_b64 v25, v[84:85] offset:6336
	ds_write_b64 v25, v[86:87] offset:8448
	ds_write_b64 v25, v[88:89] offset:10560
	ds_write_b64 v25, v[68:69] offset:12672
	ds_write_b64 v25, v[64:65] offset:14784
	ds_write_b64 v25, v[48:49] offset:16896
	ds_write_b64 v25, v[54:55] offset:19008
	ds_write_b64 v25, v[66:67] offset:21120
	ds_write_b64 v25, v[70:71] offset:23232
	ds_write_b64 v25, v[74:75] offset:25344
	ds_write_b64 v25, v[56:57] offset:27456
	ds_write_b64 v25, v[58:59] offset:29568
	ds_write_b64 v25, v[42:43] offset:31680
	v_ashrrev_i32_e32 v25, 5, v21
	v_lshlrev_b32_e32 v21, 3, v21
	v_lshlrev_b32_e32 v25, 3, v25
	s_waitcnt vmcnt(0)
	v_lshlrev_b32_e32 v41, 16, v41
	v_lshlrev_b32_e32 v39, 16, v39
	v_lshlrev_b32_e32 v35, 16, v35
	v_lshlrev_b32_e32 v29, 16, v29
	v_and_b32_e32 v48, 0xffff0000, v14
	v_add3_u32 v21, 0, v21, v25
	v_mov_b32_e32 v40, v48
	s_waitcnt lgkmcnt(0)
	s_barrier
	v_pk_mul_f32 v[44:45], v[30:31], v[40:41]
	ds_read2_b64 v[40:43], v21 offset1:1
	v_lshlrev_b32_e32 v28, 16, v14
	v_lshlrev_b32_e32 v49, 16, v15
	v_pk_fma_f32 v[44:45], v[30:31], v[28:29], v[44:45] op_sel:[0,0,1] op_sel_hi:[1,0,0]
	v_mov_b32_e32 v28, v31
	v_pk_fma_f32 v[44:45], v[20:21], v[48:49], v[44:45] op_sel_hi:[0,1,1]
	v_pk_add_f32 v[50:51], v[24:25], v[44:45] op_sel_hi:[0,1]
	ds_read2_b64 v[44:47], v21 offset0:2 offset1:3
	s_waitcnt lgkmcnt(1)
	v_pk_mul_f32 v[40:41], v[50:51], v[40:41]
	v_and_b32_e32 v51, 16, v16
	v_and_b32_e32 v50, 0xffff0000, v15
	v_pk_mov_b32 v[14:15], v[48:49], v[50:51] op_sel:[1,0]
	v_lshlrev_b32_e32 v53, 16, v16
	v_pk_mul_f32 v[14:15], v[30:31], v[14:15] op_sel_hi:[0,1]
	v_mov_b32_e32 v52, v50
	v_pk_fma_f32 v[14:15], v[28:29], v[48:49], v[14:15] op_sel_hi:[0,1,1]
	v_pk_fma_f32 v[14:15], v[20:21], v[52:53], v[14:15] op_sel_hi:[0,1,1]
	v_pk_add_f32 v[14:15], v[24:25], v[14:15] op_sel_hi:[0,1]
	v_pk_mul_f32 v[14:15], v[14:15], v[42:43]
	v_and_b32_e32 v43, 16, v17
	v_and_b32_e32 v42, 0xffff0000, v16
	v_lshlrev_b32_e32 v49, 16, v17
	v_mov_b32_e32 v48, v42
	v_pk_mov_b32 v[42:43], v[52:53], v[42:43] op_sel:[1,0]
	v_pk_mov_b32 v[16:17], v[16:17], v[10:11] op_sel:[1,0]
	v_pk_mul_f32 v[42:43], v[30:31], v[42:43] op_sel_hi:[0,1]
	v_and_b32_e32 v17, 16, v17
	v_and_b32_e32 v16, 0xffff0000, v16
	v_pk_fma_f32 v[42:43], v[28:29], v[52:53], v[42:43] op_sel_hi:[0,1,1]
	v_mov_b32_e32 v50, v16
	v_pk_mov_b32 v[16:17], v[48:49], v[16:17] op_sel:[1,0]
	v_pk_fma_f32 v[42:43], v[20:21], v[48:49], v[42:43] op_sel_hi:[0,1,1]
	v_pk_mul_f32 v[16:17], v[30:31], v[16:17] op_sel_hi:[0,1]
	v_pk_add_f32 v[42:43], v[24:25], v[42:43] op_sel_hi:[0,1]
	v_lshlrev_b32_e32 v51, 16, v10
	v_pk_fma_f32 v[16:17], v[28:29], v[48:49], v[16:17] op_sel_hi:[0,1,1]
	s_waitcnt lgkmcnt(0)
	v_pk_mul_f32 v[42:43], v[42:43], v[44:45]
	v_pk_fma_f32 v[16:17], v[20:21], v[50:51], v[16:17] op_sel_hi:[0,1,1]
	v_and_b32_e32 v45, 16, v11
	v_and_b32_e32 v44, 0xffff0000, v10
	v_pk_add_f32 v[16:17], v[24:25], v[16:17] op_sel_hi:[0,1]
	v_mov_b32_e32 v52, v44
	v_pk_mov_b32 v[44:45], v[50:51], v[44:45] op_sel:[1,0]
	v_pk_mul_f32 v[16:17], v[16:17], v[46:47]
	v_pk_mul_f32 v[48:49], v[30:31], v[44:45] op_sel_hi:[0,1]
	ds_read2_b64 v[44:47], v21 offset0:4 offset1:5
	v_lshlrev_b32_e32 v53, 16, v11
	v_pk_fma_f32 v[48:49], v[28:29], v[50:51], v[48:49] op_sel_hi:[0,1,1]
	v_pk_fma_f32 v[48:49], v[20:21], v[52:53], v[48:49] op_sel_hi:[0,1,1]
	v_pk_add_f32 v[54:55], v[24:25], v[48:49] op_sel_hi:[0,1]
	ds_read2_b64 v[48:51], v21 offset0:6 offset1:7
	s_waitcnt lgkmcnt(1)
	v_pk_mul_f32 v[44:45], v[54:55], v[44:45]
	v_and_b32_e32 v55, 16, v12
	v_and_b32_e32 v54, 0xffff0000, v11
	v_pk_mov_b32 v[10:11], v[52:53], v[54:55] op_sel:[1,0]
	v_lshlrev_b32_e32 v57, 16, v12
	v_pk_mul_f32 v[10:11], v[30:31], v[10:11] op_sel_hi:[0,1]
	v_mov_b32_e32 v56, v54
	v_pk_fma_f32 v[10:11], v[28:29], v[52:53], v[10:11] op_sel_hi:[0,1,1]
	v_pk_fma_f32 v[10:11], v[20:21], v[56:57], v[10:11] op_sel_hi:[0,1,1]
	v_pk_add_f32 v[10:11], v[24:25], v[10:11] op_sel_hi:[0,1]
	v_and_b32_e32 v38, 0xffff0000, v13
	v_pk_mul_f32 v[10:11], v[10:11], v[46:47]
	v_and_b32_e32 v47, 16, v13
	v_and_b32_e32 v46, 0xffff0000, v12
	v_lshlrev_b32_e32 v53, 16, v13
	v_mov_b32_e32 v52, v46
	v_pk_mov_b32 v[12:13], v[56:57], v[46:47] op_sel:[1,0]
	v_mov_b32_e32 v46, v53
	v_mov_b32_e32 v47, v38
	v_pk_mul_f32 v[12:13], v[30:31], v[12:13] op_sel_hi:[0,1]
	v_pk_mul_f32 v[46:47], v[30:31], v[46:47] op_sel_hi:[0,1]
	v_pk_fma_f32 v[12:13], v[28:29], v[56:57], v[12:13] op_sel_hi:[0,1,1]
	v_pk_fma_f32 v[46:47], v[28:29], v[52:53], v[46:47] op_sel_hi:[0,1,1]
	v_pk_fma_f32 v[12:13], v[20:21], v[52:53], v[12:13] op_sel_hi:[0,1,1]
	v_pk_fma_f32 v[38:39], v[20:21], v[38:39], v[46:47] op_sel_hi:[0,1,1]
	s_xor_b64 s[50:51], s[50:51], -1
	v_pk_add_f32 v[12:13], v[24:25], v[12:13] op_sel_hi:[0,1]
	v_pk_add_f32 v[38:39], v[24:25], v[38:39] op_sel_hi:[0,1]
	s_waitcnt lgkmcnt(0)
	v_pk_mul_f32 v[12:13], v[12:13], v[48:49]
	v_pk_mul_f32 v[38:39], v[38:39], v[50:51]
	s_mov_b64 s[0:1], -1
	s_and_b64 vcc, exec, s[50:51]
	s_cbranch_vccz .LBB0_548
	v_bfe_u32 v46, v15, 16, 1
	v_add3_u32 v47, v15, v46, s4
	v_bfe_u32 v46, v14, 16, 1
	v_bfe_u32 v48, v16, 16, 1
	v_bfe_u32 v50, v42, 16, 1
	v_bfe_u32 v34, v17, 16, 1
	v_bfe_u32 v49, v40, 16, 1
	v_add3_u32 v50, v42, v50, s4
	v_add3_u32 v48, v16, v48, s4
	v_add3_u32 v46, v14, v46, s4
	v_bfe_u32 v25, v43, 16, 1
	v_bfe_u32 v28, v41, 16, 1
	v_add3_u32 v34, v17, v34, s4
	v_add3_u32 v49, v40, v49, s4
	v_lshrrev_b32_e32 v51, 16, v46
	v_lshrrev_b32_e32 v52, 16, v48
	v_lshrrev_b32_e32 v48, 16, v50
	v_bfe_u32 v50, v11, 16, 1
	v_add3_u32 v28, v41, v28, s4
	v_add3_u32 v25, v43, v25, s4
	v_lshrrev_b32_e32 v46, 16, v49
	v_and_or_b32 v49, v34, s91, v52
	v_and_or_b32 v47, v47, s91, v51
	v_add3_u32 v51, v11, v50, s4
	v_bfe_u32 v50, v10, 16, 1
	v_bfe_u32 v52, v38, 16, 1
	v_bfe_u32 v53, v44, 16, 1
	v_bfe_u32 v54, v12, 16, 1
	v_lshl_add_u64 v[36:37], v[36:37], 1, s[70:71]
	v_and_or_b32 v48, v25, s91, v48
	v_and_or_b32 v46, v28, s91, v46
	v_bfe_u32 v25, v13, 16, 1
	v_bfe_u32 v28, v45, 16, 1
	v_bfe_u32 v34, v39, 16, 1
	v_add3_u32 v54, v12, v54, s4
	v_add3_u32 v53, v44, v53, s4
	v_add3_u32 v52, v38, v52, s4
	v_add3_u32 v50, v10, v50, s4
	v_add3_u32 v34, v39, v34, s4
	v_add3_u32 v28, v45, v28, s4
	v_add3_u32 v25, v13, v25, s4
	v_lshrrev_b32_e32 v55, 16, v50
	v_lshrrev_b32_e32 v56, 16, v52
	v_lshrrev_b32_e32 v50, 16, v53
	v_lshrrev_b32_e32 v52, 16, v54
	v_lshl_add_u64 v[32:33], v[32:33], 1, v[36:37]
	v_and_or_b32 v52, v25, s91, v52
	v_and_or_b32 v50, v28, s91, v50
	v_and_or_b32 v53, v34, s91, v56
	v_and_or_b32 v51, v51, s91, v55
	global_store_dwordx4 v[32:33], v[46:49], off
	global_store_dwordx4 v[32:33], v[50:53], off offset:16
	s_mov_b64 s[0:1], 0

.LBB0_574:
	s_or_b64 exec, exec, s[0:1]
	v_mov_b32_e32 v2, v142
	s_waitcnt lgkmcnt(0)
	s_barrier
	s_mov_b32 s19, s16
	v_and_b32_e32 v4, 0xff, v2
	v_lshlrev_b32_e32 v5, 5, v2
	v_and_or_b32 v4, v5, s68, v4
	v_ashrrev_i32_e32 v5, 5, v4
	v_cvt_f32_ubyte0_e32 v2, v2
	v_lshlrev_b32_e32 v7, 3, v4
	v_mul_f32_e32 v2, 0x39000000, v2
	v_lshlrev_b32_e32 v5, 3, v5
	v_sin_f32_e32 v4, v2
	v_cos_f32_e32 v6, v2
	v_add3_u32 v2, 0, v7, v5
	ds_read_b64 v[128:129], v2
	ds_read_b64 v[130:131], v2 offset:2112
	ds_read_b64 v[144:145], v2 offset:4224
	ds_read_b64 v[148:149], v2 offset:6336
	ds_read_b64 v[150:151], v2 offset:8448
	ds_read_b64 v[152:153], v2 offset:10560
	ds_read_b64 v[154:155], v2 offset:12672
	ds_read_b64 v[156:157], v2 offset:14784
	ds_read_b64 v[158:159], v2 offset:16896
	ds_read_b64 v[160:161], v2 offset:19008
	ds_read_b64 v[162:163], v2 offset:21120
	ds_read_b64 v[164:165], v2 offset:23232
	ds_read_b64 v[166:167], v2 offset:25344
	ds_read_b64 v[168:169], v2 offset:27456
	ds_read_b64 v[170:171], v2 offset:29568
	ds_read_b64 v[172:173], v2 offset:31680
	ds_read_b64 v[174:175], v2 offset:33792
	ds_read_b64 v[176:177], v2 offset:35904
	ds_read_b64 v[178:179], v2 offset:38016
	ds_read_b64 v[180:181], v2 offset:40128
	ds_read_b64 v[182:183], v2 offset:42240
	ds_read_b64 v[184:185], v2 offset:44352
	ds_read_b64 v[186:187], v2 offset:46464
	ds_read_b64 v[188:189], v2 offset:48576
	ds_read_b64 v[190:191], v2 offset:50688
	ds_read_b64 v[192:193], v2 offset:52800
	ds_read_b64 v[194:195], v2 offset:54912
	ds_read_b64 v[196:197], v2 offset:57024
	ds_read_b64 v[198:199], v2 offset:59136
	ds_read_b64 v[204:205], v2 offset:61248
	ds_read_b64 v[206:207], v2 offset:63360
	ds_read_b64 v[208:209], v2 offset:65472
	s_waitcnt lgkmcnt(14)
	v_pk_add_f32 v[210:211], v[128:129], v[174:175]
	v_pk_add_f32 v[128:129], v[128:129], v[174:175] neg_lo:[0,1] neg_hi:[0,1]
	v_pk_add_f32 v[174:175], v[130:131], v[176:177]
	v_pk_add_f32 v[130:131], v[130:131], v[176:177] neg_lo:[0,1] neg_hi:[0,1]
	s_mov_b32 s0, s9
	v_pk_mul_f32 v[176:177], v[130:131], s[18:19]
	s_mov_b32 s41, s38
	v_pk_fma_f32 v[130:131], v[130:131], s[0:1], v[176:177] op_sel:[0,0,1] op_sel_hi:[1,0,0]
	s_waitcnt lgkmcnt(13)
	v_pk_add_f32 v[176:177], v[144:145], v[178:179]
	v_pk_add_f32 v[144:145], v[144:145], v[178:179] neg_lo:[0,1] neg_hi:[0,1]
	s_mov_b32 s43, s26
	v_pk_mul_f32 v[178:179], v[144:145], s[24:25]
	s_mov_b32 s62, s37
	v_pk_fma_f32 v[144:145], v[144:145], s[22:23], v[178:179] op_sel:[0,0,1] op_sel_hi:[1,0,0]
	s_waitcnt lgkmcnt(12)
	v_pk_add_f32 v[178:179], v[148:149], v[180:181]
	v_pk_add_f32 v[148:149], v[148:149], v[180:181] neg_lo:[0,1] neg_hi:[0,1]
	s_mov_b32 s45, s22
	v_pk_mul_f32 v[180:181], v[148:149], s[36:37]
	s_mov_b32 s50, s25
	v_pk_fma_f32 v[148:149], v[148:149], s[26:27], v[180:181] op_sel:[0,0,1] op_sel_hi:[1,0,0]
	s_waitcnt lgkmcnt(11)
	v_pk_add_f32 v[180:181], v[150:151], v[182:183]
	v_pk_add_f32 v[150:151], v[150:151], v[182:183] neg_lo:[0,1] neg_hi:[0,1]
	v_xor_b32_e32 v7, 0x80000000, v4
	v_pk_mul_f32 v[182:183], v[150:151], s[40:41]
	v_mov_b32_e32 v5, v7
	v_pk_fma_f32 v[150:151], v[150:151], s[38:39], v[182:183] op_sel:[0,0,1] op_sel_hi:[1,0,0]
	s_waitcnt lgkmcnt(10)
	v_pk_add_f32 v[182:183], v[152:153], v[184:185]
	v_pk_add_f32 v[152:153], v[152:153], v[184:185] neg_lo:[0,1] neg_hi:[0,1]
	v_pk_mul_f32 v[8:9], v[6:7], v[4:5] op_sel:[1,0] op_sel_hi:[0,1]
	v_pk_mul_f32 v[184:185], v[152:153], s[42:43]
	v_pk_fma_f32 v[8:9], v[6:7], v[6:7], v[8:9] op_sel_hi:[1,0,1]
	v_pk_fma_f32 v[152:153], v[152:153], s[62:63], v[184:185] op_sel:[0,0,1] op_sel_hi:[1,0,0]
	s_waitcnt lgkmcnt(9)
	v_pk_add_f32 v[184:185], v[154:155], v[186:187]
	v_pk_add_f32 v[154:155], v[154:155], v[186:187] neg_lo:[0,1] neg_hi:[0,1]
	v_xor_b32_e32 v14, 0x80000000, v9
	v_pk_mul_f32 v[186:187], v[154:155], s[44:45]
	v_mov_b32_e32 v15, v9
	v_pk_fma_f32 v[154:155], v[154:155], s[50:51], v[186:187] op_sel:[0,0,1] op_sel_hi:[1,0,0]
	s_waitcnt lgkmcnt(8)
	v_pk_add_f32 v[186:187], v[156:157], v[188:189]
	v_pk_add_f32 v[156:157], v[156:157], v[188:189] neg_lo:[0,1] neg_hi:[0,1]
	v_pk_mul_f32 v[12:13], v[8:9], v[14:15] op_sel:[1,0] op_sel_hi:[0,1]
	v_pk_mul_f32 v[188:189], v[156:157], s[8:9]
	v_pk_fma_f32 v[12:13], v[8:9], v[8:9], v[12:13] op_sel_hi:[1,0,1]
	v_pk_fma_f32 v[156:157], v[156:157], s[16:17], v[188:189] op_sel:[0,0,1] op_sel_hi:[1,0,0]
	s_waitcnt lgkmcnt(7)
	v_pk_add_f32 v[188:189], v[158:159], v[190:191]
	v_pk_add_f32 v[190:191], v[158:159], v[190:191] neg_lo:[0,1] neg_hi:[0,1]
	v_xor_b32_e32 v16, 0x80000000, v13
	s_waitcnt lgkmcnt(6)
	v_pk_add_f32 v[158:159], v[160:161], v[192:193]
	v_pk_add_f32 v[160:161], v[160:161], v[192:193] neg_lo:[0,1] neg_hi:[0,1]
	v_mov_b32_e32 v17, v13
	v_pk_mul_f32 v[192:193], v[160:161], s[8:9]
	v_pk_mul_f32 v[28:29], v[12:13], v[16:17] op_sel:[1,0] op_sel_hi:[0,1]
	v_pk_fma_f32 v[160:161], v[160:161], s[16:17], v[192:193] op_sel:[0,0,1] op_sel_hi:[1,0,0] neg_lo:[1,0,0] neg_hi:[1,0,0]
	s_waitcnt lgkmcnt(5)
	v_pk_add_f32 v[192:193], v[162:163], v[194:195]
	v_pk_add_f32 v[162:163], v[162:163], v[194:195] neg_lo:[0,1] neg_hi:[0,1]
	v_pk_fma_f32 v[28:29], v[12:13], v[12:13], v[28:29] op_sel_hi:[1,0,1]
	v_pk_mul_f32 v[194:195], v[162:163], s[44:45]
	v_pk_mul_f32 v[44:45], v[16:17], v[28:29] op_sel:[0,1] op_sel_hi:[1,0]
	v_pk_fma_f32 v[162:163], v[162:163], s[50:51], v[194:195] op_sel:[0,0,1] op_sel_hi:[1,0,0] neg_lo:[1,0,0] neg_hi:[1,0,0]
	s_waitcnt lgkmcnt(4)
	v_pk_add_f32 v[194:195], v[164:165], v[196:197]
	v_pk_add_f32 v[164:165], v[164:165], v[196:197] neg_lo:[0,1] neg_hi:[0,1]
	v_pk_fma_f32 v[44:45], v[12:13], v[28:29], v[44:45] op_sel_hi:[0,1,1]
	v_pk_mul_f32 v[196:197], v[164:165], s[42:43]
	v_pk_mul_f32 v[60:61], v[16:17], v[44:45] op_sel:[0,1] op_sel_hi:[1,0]
	v_pk_fma_f32 v[164:165], v[164:165], s[62:63], v[196:197] op_sel:[0,0,1] op_sel_hi:[1,0,0] neg_lo:[1,0,0] neg_hi:[1,0,0]
	s_waitcnt lgkmcnt(3)
	v_pk_add_f32 v[196:197], v[166:167], v[198:199]
	v_pk_add_f32 v[166:167], v[166:167], v[198:199] neg_lo:[0,1] neg_hi:[0,1]
	v_pk_fma_f32 v[60:61], v[12:13], v[44:45], v[60:61] op_sel_hi:[0,1,1]
	v_pk_mul_f32 v[198:199], v[166:167], s[40:41]
	v_pk_mul_f32 v[76:77], v[16:17], v[60:61] op_sel:[0,1] op_sel_hi:[1,0]
	v_pk_fma_f32 v[166:167], v[166:167], s[38:39], v[198:199] op_sel:[0,0,1] op_sel_hi:[1,0,0] neg_lo:[1,0,0] neg_hi:[1,0,0]
	s_waitcnt lgkmcnt(2)
	v_pk_add_f32 v[198:199], v[168:169], v[204:205]
	v_pk_add_f32 v[168:169], v[168:169], v[204:205] neg_lo:[0,1] neg_hi:[0,1]
	v_pk_fma_f32 v[76:77], v[12:13], v[60:61], v[76:77] op_sel_hi:[0,1,1]
	v_pk_mul_f32 v[204:205], v[168:169], s[36:37]
	v_pk_mul_f32 v[92:93], v[16:17], v[76:77] op_sel:[0,1] op_sel_hi:[1,0]
	v_pk_fma_f32 v[168:169], v[168:169], s[26:27], v[204:205] op_sel:[0,0,1] op_sel_hi:[1,0,0] neg_lo:[1,0,0] neg_hi:[1,0,0]
	s_waitcnt lgkmcnt(1)
	v_pk_add_f32 v[204:205], v[170:171], v[206:207]
	v_pk_add_f32 v[170:171], v[170:171], v[206:207] neg_lo:[0,1] neg_hi:[0,1]
	v_pk_fma_f32 v[92:93], v[12:13], v[76:77], v[92:93] op_sel_hi:[0,1,1]
	v_pk_mul_f32 v[206:207], v[170:171], s[24:25]
	v_pk_mul_f32 v[108:109], v[16:17], v[92:93] op_sel:[0,1] op_sel_hi:[1,0]
	v_pk_fma_f32 v[170:171], v[170:171], s[22:23], v[206:207] op_sel:[0,0,1] op_sel_hi:[1,0,0] neg_lo:[1,0,0] neg_hi:[1,0,0]
	s_waitcnt lgkmcnt(0)
	v_pk_add_f32 v[206:207], v[172:173], v[208:209]
	v_pk_add_f32 v[172:173], v[172:173], v[208:209] neg_lo:[0,1] neg_hi:[0,1]
	v_pk_mul_f32 v[10:11], v[4:5], v[8:9] op_sel:[0,1] op_sel_hi:[1,0]
	v_pk_mul_f32 v[208:209], v[172:173], s[18:19]
	v_pk_fma_f32 v[108:109], v[12:13], v[92:93], v[108:109] op_sel_hi:[0,1,1]
	v_pk_fma_f32 v[172:173], v[172:173], s[0:1], v[208:209] op_sel:[0,0,1] op_sel_hi:[1,0,0] neg_lo:[1,0,0] neg_hi:[1,0,0]
	v_pk_add_f32 v[208:209], v[210:211], v[188:189]
	v_pk_add_f32 v[188:189], v[210:211], v[188:189] neg_lo:[0,1] neg_hi:[0,1]
	v_pk_add_f32 v[210:211], v[174:175], v[158:159]
	v_pk_add_f32 v[158:159], v[174:175], v[158:159] neg_lo:[0,1] neg_hi:[0,1]
	v_pk_fma_f32 v[10:11], v[6:7], v[8:9], v[10:11] op_sel_hi:[0,1,1]
	v_pk_mul_f32 v[174:175], v[158:159], s[24:25]
	v_pk_mul_f32 v[18:19], v[4:5], v[12:13] op_sel:[0,1] op_sel_hi:[1,0]
	v_pk_fma_f32 v[158:159], v[158:159], s[22:23], v[174:175] op_sel:[0,0,1] op_sel_hi:[1,0,0]
	v_pk_add_f32 v[174:175], v[176:177], v[192:193]
	v_pk_add_f32 v[176:177], v[176:177], v[192:193] neg_lo:[0,1] neg_hi:[0,1]
	v_pk_mul_f32 v[32:33], v[4:5], v[28:29] op_sel:[0,1] op_sel_hi:[1,0]
	v_pk_mul_f32 v[192:193], v[176:177], s[40:41]
	v_pk_mul_f32 v[48:49], v[4:5], v[44:45] op_sel:[0,1] op_sel_hi:[1,0]
	v_pk_fma_f32 v[176:177], v[176:177], s[38:39], v[192:193] op_sel:[0,0,1] op_sel_hi:[1,0,0]
	v_pk_add_f32 v[192:193], v[178:179], v[194:195]
	v_pk_add_f32 v[178:179], v[178:179], v[194:195] neg_lo:[0,1] neg_hi:[0,1]
	v_pk_mul_f32 v[64:65], v[4:5], v[60:61] op_sel:[0,1] op_sel_hi:[1,0]
	v_pk_mul_f32 v[194:195], v[178:179], s[44:45]
	v_pk_mul_f32 v[80:81], v[4:5], v[76:77] op_sel:[0,1] op_sel_hi:[1,0]
	v_pk_fma_f32 v[178:179], v[178:179], s[50:51], v[194:195] op_sel:[0,0,1] op_sel_hi:[1,0,0]
	v_pk_add_f32 v[194:195], v[180:181], v[196:197]
	v_pk_add_f32 v[196:197], v[180:181], v[196:197] neg_lo:[0,1] neg_hi:[0,1]
	v_pk_mul_f32 v[96:97], v[4:5], v[92:93] op_sel:[0,1] op_sel_hi:[1,0]
	v_pk_add_f32 v[180:181], v[182:183], v[198:199]
	v_pk_add_f32 v[182:183], v[182:183], v[198:199] neg_lo:[0,1] neg_hi:[0,1]
	v_pk_mul_f32 v[112:113], v[4:5], v[108:109] op_sel:[0,1] op_sel_hi:[1,0]
	v_pk_mul_f32 v[198:199], v[182:183], s[44:45]
	v_xor_b32_e32 v22, 0x80000000, v11
	v_pk_fma_f32 v[182:183], v[182:183], s[50:51], v[198:199] op_sel:[0,0,1] op_sel_hi:[1,0,0] neg_lo:[1,0,0] neg_hi:[1,0,0]
	v_pk_add_f32 v[198:199], v[184:185], v[204:205]
	v_pk_add_f32 v[184:185], v[184:185], v[204:205] neg_lo:[0,1] neg_hi:[0,1]
	v_mov_b32_e32 v23, v11
	v_pk_mul_f32 v[204:205], v[184:185], s[40:41]
	v_pk_fma_f32 v[18:19], v[6:7], v[12:13], v[18:19] op_sel_hi:[0,1,1]
	v_pk_fma_f32 v[184:185], v[184:185], s[38:39], v[204:205] op_sel:[0,0,1] op_sel_hi:[1,0,0] neg_lo:[1,0,0] neg_hi:[1,0,0]
	v_pk_add_f32 v[204:205], v[186:187], v[206:207]
	v_pk_add_f32 v[186:187], v[186:187], v[206:207] neg_lo:[0,1] neg_hi:[0,1]
	v_pk_mul_f32 v[20:21], v[14:15], v[12:13] op_sel:[0,1] op_sel_hi:[1,0]
	v_pk_mul_f32 v[206:207], v[186:187], s[24:25]
	v_pk_fma_f32 v[32:33], v[6:7], v[28:29], v[32:33] op_sel_hi:[0,1,1]
	v_pk_fma_f32 v[186:187], v[186:187], s[22:23], v[206:207] op_sel:[0,0,1] op_sel_hi:[1,0,0] neg_lo:[1,0,0] neg_hi:[1,0,0]
	v_pk_add_f32 v[206:207], v[128:129], v[190:191] op_sel:[0,1] op_sel_hi:[1,0] neg_hi:[0,1]
	v_pk_add_f32 v[128:129], v[128:129], v[190:191] op_sel:[0,1] op_sel_hi:[1,0] neg_lo:[0,1]
	v_pk_add_f32 v[190:191], v[130:131], v[160:161]
	v_pk_add_f32 v[130:131], v[130:131], v[160:161] neg_lo:[0,1] neg_hi:[0,1]
	v_pk_mul_f32 v[36:37], v[14:15], v[28:29] op_sel:[0,1] op_sel_hi:[1,0]
	v_pk_mul_f32 v[160:161], v[130:131], s[24:25]
	v_pk_fma_f32 v[48:49], v[6:7], v[44:45], v[48:49] op_sel_hi:[0,1,1]
	v_pk_fma_f32 v[130:131], v[130:131], s[22:23], v[160:161] op_sel:[0,0,1] op_sel_hi:[1,0,0]
	v_pk_add_f32 v[160:161], v[144:145], v[162:163]
	v_pk_add_f32 v[144:145], v[144:145], v[162:163] neg_lo:[0,1] neg_hi:[0,1]
	v_pk_mul_f32 v[52:53], v[14:15], v[44:45] op_sel:[0,1] op_sel_hi:[1,0]
	v_pk_mul_f32 v[162:163], v[144:145], s[40:41]
	v_pk_fma_f32 v[64:65], v[6:7], v[60:61], v[64:65] op_sel_hi:[0,1,1]
	v_pk_fma_f32 v[144:145], v[144:145], s[38:39], v[162:163] op_sel:[0,0,1] op_sel_hi:[1,0,0]
	v_pk_add_f32 v[162:163], v[148:149], v[164:165]
	v_pk_add_f32 v[148:149], v[148:149], v[164:165] neg_lo:[0,1] neg_hi:[0,1]
	v_pk_mul_f32 v[68:69], v[14:15], v[60:61] op_sel:[0,1] op_sel_hi:[1,0]
	v_pk_mul_f32 v[164:165], v[148:149], s[44:45]
	v_pk_fma_f32 v[80:81], v[6:7], v[76:77], v[80:81] op_sel_hi:[0,1,1]
	v_pk_fma_f32 v[148:149], v[148:149], s[50:51], v[164:165] op_sel:[0,0,1] op_sel_hi:[1,0,0]
	v_pk_add_f32 v[164:165], v[150:151], v[166:167]
	v_pk_add_f32 v[166:167], v[150:151], v[166:167] neg_lo:[0,1] neg_hi:[0,1]
	v_pk_mul_f32 v[84:85], v[14:15], v[76:77] op_sel:[0,1] op_sel_hi:[1,0]
	v_pk_add_f32 v[150:151], v[152:153], v[168:169]
	v_pk_add_f32 v[152:153], v[152:153], v[168:169] neg_lo:[0,1] neg_hi:[0,1]
	v_pk_fma_f32 v[96:97], v[6:7], v[92:93], v[96:97] op_sel_hi:[0,1,1]
	v_pk_mul_f32 v[168:169], v[152:153], s[44:45]
	v_pk_mul_f32 v[100:101], v[14:15], v[92:93] op_sel:[0,1] op_sel_hi:[1,0]
	v_pk_fma_f32 v[152:153], v[152:153], s[50:51], v[168:169] op_sel:[0,0,1] op_sel_hi:[1,0,0] neg_lo:[1,0,0] neg_hi:[1,0,0]
	v_pk_add_f32 v[168:169], v[154:155], v[170:171]
	v_pk_add_f32 v[154:155], v[154:155], v[170:171] neg_lo:[0,1] neg_hi:[0,1]
	v_pk_fma_f32 v[112:113], v[6:7], v[108:109], v[112:113] op_sel_hi:[0,1,1]
	v_pk_mul_f32 v[170:171], v[154:155], s[40:41]
	v_pk_mul_f32 v[116:117], v[14:15], v[108:109] op_sel:[0,1] op_sel_hi:[1,0]
	v_pk_fma_f32 v[154:155], v[154:155], s[38:39], v[170:171] op_sel:[0,0,1] op_sel_hi:[1,0,0] neg_lo:[1,0,0] neg_hi:[1,0,0]
	v_pk_add_f32 v[170:171], v[156:157], v[172:173]
	v_pk_add_f32 v[156:157], v[156:157], v[172:173] neg_lo:[0,1] neg_hi:[0,1]
	v_pk_fma_f32 v[20:21], v[8:9], v[12:13], v[20:21] op_sel_hi:[0,1,1]
	v_pk_mul_f32 v[172:173], v[156:157], s[24:25]
	v_pk_mul_f32 v[24:25], v[12:13], v[22:23] op_sel:[1,0] op_sel_hi:[0,1]
	v_pk_fma_f32 v[156:157], v[156:157], s[22:23], v[172:173] op_sel:[0,0,1] op_sel_hi:[1,0,0] neg_lo:[1,0,0] neg_hi:[1,0,0]
	v_pk_add_f32 v[172:173], v[208:209], v[194:195]
	v_pk_add_f32 v[194:195], v[208:209], v[194:195] neg_lo:[0,1] neg_hi:[0,1]
	v_pk_add_f32 v[208:209], v[210:211], v[180:181]
	v_pk_add_f32 v[180:181], v[210:211], v[180:181] neg_lo:[0,1] neg_hi:[0,1]
	v_pk_fma_f32 v[36:37], v[8:9], v[28:29], v[36:37] op_sel_hi:[0,1,1]
	v_pk_mul_f32 v[210:211], v[180:181], s[40:41]
	v_pk_mul_f32 v[40:41], v[22:23], v[28:29] op_sel:[0,1] op_sel_hi:[1,0]
	v_pk_fma_f32 v[180:181], v[180:181], s[38:39], v[210:211] op_sel:[0,0,1] op_sel_hi:[1,0,0]
	v_pk_add_f32 v[210:211], v[174:175], v[198:199]
	v_pk_add_f32 v[198:199], v[174:175], v[198:199] neg_lo:[0,1] neg_hi:[0,1]
	v_pk_fma_f32 v[52:53], v[8:9], v[44:45], v[52:53] op_sel_hi:[0,1,1]
	v_pk_add_f32 v[174:175], v[192:193], v[204:205]
	v_pk_add_f32 v[192:193], v[192:193], v[204:205] neg_lo:[0,1] neg_hi:[0,1]
	v_pk_mul_f32 v[56:57], v[22:23], v[44:45] op_sel:[0,1] op_sel_hi:[1,0]
	v_pk_mul_f32 v[204:205], v[192:193], s[40:41]
	v_pk_fma_f32 v[68:69], v[8:9], v[60:61], v[68:69] op_sel_hi:[0,1,1]
	v_pk_fma_f32 v[192:193], v[192:193], s[38:39], v[204:205] op_sel:[0,0,1] op_sel_hi:[1,0,0] neg_lo:[1,0,0] neg_hi:[1,0,0]
	v_pk_add_f32 v[204:205], v[188:189], v[196:197] op_sel:[0,1] op_sel_hi:[1,0] neg_hi:[0,1]
	v_pk_add_f32 v[188:189], v[188:189], v[196:197] op_sel:[0,1] op_sel_hi:[1,0] neg_lo:[0,1]
	v_pk_add_f32 v[196:197], v[158:159], v[182:183]
	v_pk_add_f32 v[158:159], v[158:159], v[182:183] neg_lo:[0,1] neg_hi:[0,1]
	v_pk_mul_f32 v[72:73], v[22:23], v[60:61] op_sel:[0,1] op_sel_hi:[1,0]
	v_pk_mul_f32 v[182:183], v[158:159], s[40:41]
	v_pk_fma_f32 v[84:85], v[8:9], v[76:77], v[84:85] op_sel_hi:[0,1,1]
	v_pk_fma_f32 v[158:159], v[158:159], s[38:39], v[182:183] op_sel:[0,0,1] op_sel_hi:[1,0,0]
	v_pk_add_f32 v[182:183], v[176:177], v[184:185]
	v_pk_add_f32 v[184:185], v[176:177], v[184:185] neg_lo:[0,1] neg_hi:[0,1]
	v_pk_mul_f32 v[88:89], v[22:23], v[76:77] op_sel:[0,1] op_sel_hi:[1,0]
	v_pk_add_f32 v[176:177], v[178:179], v[186:187]
	v_pk_add_f32 v[178:179], v[178:179], v[186:187] neg_lo:[0,1] neg_hi:[0,1]
	v_pk_fma_f32 v[100:101], v[8:9], v[92:93], v[100:101] op_sel_hi:[0,1,1]
	v_pk_mul_f32 v[186:187], v[178:179], s[40:41]
	v_pk_mul_f32 v[104:105], v[22:23], v[92:93] op_sel:[0,1] op_sel_hi:[1,0]
	v_pk_fma_f32 v[178:179], v[178:179], s[38:39], v[186:187] op_sel:[0,0,1] op_sel_hi:[1,0,0] neg_lo:[1,0,0] neg_hi:[1,0,0]
	v_pk_add_f32 v[186:187], v[206:207], v[164:165]
	v_pk_add_f32 v[164:165], v[206:207], v[164:165] neg_lo:[0,1] neg_hi:[0,1]
	v_pk_add_f32 v[206:207], v[190:191], v[150:151]
	v_pk_add_f32 v[150:151], v[190:191], v[150:151] neg_lo:[0,1] neg_hi:[0,1]
	v_pk_fma_f32 v[116:117], v[8:9], v[108:109], v[116:117] op_sel_hi:[0,1,1]
	v_pk_mul_f32 v[190:191], v[150:151], s[40:41]
	v_pk_mul_f32 v[120:121], v[22:23], v[108:109] op_sel:[0,1] op_sel_hi:[1,0]
	v_pk_fma_f32 v[150:151], v[150:151], s[38:39], v[190:191] op_sel:[0,0,1] op_sel_hi:[1,0,0]
	v_pk_add_f32 v[190:191], v[160:161], v[168:169]
	v_pk_add_f32 v[168:169], v[160:161], v[168:169] neg_lo:[0,1] neg_hi:[0,1]
	v_xor_b32_e32 v26, 0x80000000, v19
	v_pk_add_f32 v[160:161], v[162:163], v[170:171]
	v_pk_add_f32 v[162:163], v[162:163], v[170:171] neg_lo:[0,1] neg_hi:[0,1]
	v_xor_b32_e32 v30, 0x80000000, v21
	v_pk_mul_f32 v[170:171], v[162:163], s[40:41]
	v_pk_fma_f32 v[24:25], v[12:13], v[10:11], v[24:25] op_sel_hi:[1,0,1]
	v_pk_fma_f32 v[162:163], v[162:163], s[38:39], v[170:171] op_sel:[0,0,1] op_sel_hi:[1,0,0] neg_lo:[1,0,0] neg_hi:[1,0,0]
	v_pk_add_f32 v[170:171], v[128:129], v[166:167] op_sel:[0,1] op_sel_hi:[1,0] neg_hi:[0,1]
	v_pk_add_f32 v[128:129], v[128:129], v[166:167] op_sel:[0,1] op_sel_hi:[1,0] neg_lo:[0,1]
	v_pk_add_f32 v[166:167], v[130:131], v[152:153]
	v_pk_add_f32 v[130:131], v[130:131], v[152:153] neg_lo:[0,1] neg_hi:[0,1]
	v_pk_fma_f32 v[40:41], v[10:11], v[28:29], v[40:41] op_sel_hi:[0,1,1]
	v_pk_mul_f32 v[152:153], v[130:131], s[40:41]
	v_pk_fma_f32 v[56:57], v[10:11], v[44:45], v[56:57] op_sel_hi:[0,1,1]
	v_pk_fma_f32 v[130:131], v[130:131], s[38:39], v[152:153] op_sel:[0,0,1] op_sel_hi:[1,0,0]
	v_pk_add_f32 v[152:153], v[144:145], v[154:155]
	v_pk_add_f32 v[154:155], v[144:145], v[154:155] neg_lo:[0,1] neg_hi:[0,1]
	v_pk_fma_f32 v[72:73], v[10:11], v[60:61], v[72:73] op_sel_hi:[0,1,1]
	v_pk_add_f32 v[144:145], v[148:149], v[156:157]
	v_pk_add_f32 v[148:149], v[148:149], v[156:157] neg_lo:[0,1] neg_hi:[0,1]
	v_pk_fma_f32 v[88:89], v[10:11], v[76:77], v[88:89] op_sel_hi:[0,1,1]
	v_pk_mul_f32 v[156:157], v[148:149], s[40:41]
	v_pk_fma_f32 v[104:105], v[10:11], v[92:93], v[104:105] op_sel_hi:[0,1,1]
	v_pk_fma_f32 v[148:149], v[148:149], s[38:39], v[156:157] op_sel:[0,0,1] op_sel_hi:[1,0,0] neg_lo:[1,0,0] neg_hi:[1,0,0]
	v_pk_add_f32 v[156:157], v[172:173], v[210:211]
	v_pk_add_f32 v[172:173], v[172:173], v[210:211] neg_lo:[0,1] neg_hi:[0,1]
	v_pk_add_f32 v[210:211], v[208:209], v[174:175]
	v_pk_add_f32 v[208:209], v[208:209], v[174:175] neg_lo:[0,1] neg_hi:[0,1]
	v_pk_fma_f32 v[120:121], v[10:11], v[108:109], v[120:121] op_sel_hi:[0,1,1]
	v_pk_add_f32 v[174:175], v[194:195], v[198:199] op_sel:[0,1] op_sel_hi:[1,0] neg_hi:[0,1]
	v_pk_add_f32 v[194:195], v[194:195], v[198:199] op_sel:[0,1] op_sel_hi:[1,0] neg_lo:[0,1]
	v_pk_add_f32 v[198:199], v[180:181], v[192:193]
	v_pk_add_f32 v[192:193], v[180:181], v[192:193] neg_lo:[0,1] neg_hi:[0,1]
	v_mov_b32_e32 v27, v19
	v_pk_add_f32 v[180:181], v[204:205], v[182:183]
	v_pk_add_f32 v[182:183], v[204:205], v[182:183] neg_lo:[0,1] neg_hi:[0,1]
	v_pk_add_f32 v[204:205], v[196:197], v[176:177]
	v_pk_add_f32 v[196:197], v[196:197], v[176:177] neg_lo:[0,1] neg_hi:[0,1]
	v_mov_b32_e32 v31, v21
	v_pk_add_f32 v[176:177], v[188:189], v[184:185] op_sel:[0,1] op_sel_hi:[1,0] neg_hi:[0,1]
	v_pk_add_f32 v[184:185], v[188:189], v[184:185] op_sel:[0,1] op_sel_hi:[1,0] neg_lo:[0,1]
	v_pk_add_f32 v[188:189], v[158:159], v[178:179]
	v_pk_add_f32 v[178:179], v[158:159], v[178:179] neg_lo:[0,1] neg_hi:[0,1]
	v_xor_b32_e32 v34, 0x80000000, v25
	v_pk_add_f32 v[158:159], v[186:187], v[190:191]
	v_pk_add_f32 v[186:187], v[186:187], v[190:191] neg_lo:[0,1] neg_hi:[0,1]
	v_pk_add_f32 v[190:191], v[206:207], v[160:161]
	v_pk_add_f32 v[206:207], v[206:207], v[160:161] neg_lo:[0,1] neg_hi:[0,1]
	v_xor_b32_e32 v38, 0x80000000, v29
	v_pk_add_f32 v[160:161], v[164:165], v[168:169] op_sel:[0,1] op_sel_hi:[1,0] neg_hi:[0,1]
	v_pk_add_f32 v[164:165], v[164:165], v[168:169] op_sel:[0,1] op_sel_hi:[1,0] neg_lo:[0,1]
	v_pk_add_f32 v[168:169], v[150:151], v[162:163]
	v_pk_add_f32 v[162:163], v[150:151], v[162:163] neg_lo:[0,1] neg_hi:[0,1]
	v_xor_b32_e32 v42, 0x80000000, v33
	v_pk_add_f32 v[150:151], v[170:171], v[152:153]
	v_pk_add_f32 v[152:153], v[170:171], v[152:153] neg_lo:[0,1] neg_hi:[0,1]
	v_pk_add_f32 v[170:171], v[166:167], v[144:145]
	v_pk_add_f32 v[166:167], v[166:167], v[144:145] neg_lo:[0,1] neg_hi:[0,1]
	v_xor_b32_e32 v46, 0x80000000, v37
	v_pk_add_f32 v[144:145], v[128:129], v[154:155] op_sel:[0,1] op_sel_hi:[1,0] neg_hi:[0,1]
	v_pk_add_f32 v[128:129], v[128:129], v[154:155] op_sel:[0,1] op_sel_hi:[1,0] neg_lo:[0,1]
	v_pk_add_f32 v[154:155], v[130:131], v[148:149]
	v_pk_add_f32 v[130:131], v[130:131], v[148:149] neg_lo:[0,1] neg_hi:[0,1]
	v_mov_b32_e32 v35, v25
	v_xor_b32_e32 v149, 0x80000000, v130
	v_mov_b32_e32 v148, v131
	v_pk_add_f32 v[130:131], v[156:157], v[210:211]
	v_pk_add_f32 v[156:157], v[156:157], v[210:211] neg_lo:[0,1] neg_hi:[0,1]
	v_pk_add_f32 v[210:211], v[172:173], v[208:209] op_sel:[0,1] op_sel_hi:[1,0] neg_hi:[0,1]
	v_pk_add_f32 v[172:173], v[172:173], v[208:209] op_sel:[0,1] op_sel_hi:[1,0] neg_lo:[0,1]
	v_pk_add_f32 v[208:209], v[174:175], v[198:199]
	v_pk_add_f32 v[174:175], v[174:175], v[198:199] neg_lo:[0,1] neg_hi:[0,1]
	v_pk_add_f32 v[198:199], v[194:195], v[192:193] op_sel:[0,1] op_sel_hi:[1,0] neg_hi:[0,1]
	v_pk_add_f32 v[192:193], v[194:195], v[192:193] op_sel:[0,1] op_sel_hi:[1,0] neg_lo:[0,1]
	v_pk_add_f32 v[194:195], v[180:181], v[204:205]
	v_pk_add_f32 v[180:181], v[180:181], v[204:205] neg_lo:[0,1] neg_hi:[0,1]
	v_pk_add_f32 v[204:205], v[182:183], v[196:197] op_sel:[0,1] op_sel_hi:[1,0] neg_hi:[0,1]
	v_pk_add_f32 v[182:183], v[182:183], v[196:197] op_sel:[0,1] op_sel_hi:[1,0] neg_lo:[0,1]
	v_pk_add_f32 v[196:197], v[176:177], v[188:189]
	v_pk_add_f32 v[176:177], v[176:177], v[188:189] neg_lo:[0,1] neg_hi:[0,1]
	v_pk_add_f32 v[188:189], v[184:185], v[178:179] op_sel:[0,1] op_sel_hi:[1,0] neg_hi:[0,1]
	v_pk_add_f32 v[178:179], v[184:185], v[178:179] op_sel:[0,1] op_sel_hi:[1,0] neg_lo:[0,1]
	v_pk_add_f32 v[184:185], v[158:159], v[190:191]
	v_pk_add_f32 v[158:159], v[158:159], v[190:191] neg_lo:[0,1] neg_hi:[0,1]
	v_pk_mul_f32 v[4:5], v[4:5], v[184:185] op_sel:[0,1] op_sel_hi:[1,0]
	v_pk_add_f32 v[190:191], v[186:187], v[206:207] op_sel:[0,1] op_sel_hi:[1,0] neg_hi:[0,1]
	v_pk_add_f32 v[186:187], v[186:187], v[206:207] op_sel:[0,1] op_sel_hi:[1,0] neg_lo:[0,1]
	v_pk_add_f32 v[206:207], v[160:161], v[168:169]
	v_pk_add_f32 v[160:161], v[160:161], v[168:169] neg_lo:[0,1] neg_hi:[0,1]
	v_pk_add_f32 v[168:169], v[164:165], v[162:163] op_sel:[0,1] op_sel_hi:[1,0] neg_hi:[0,1]
	v_pk_add_f32 v[162:163], v[164:165], v[162:163] op_sel:[0,1] op_sel_hi:[1,0] neg_lo:[0,1]
	v_pk_add_f32 v[164:165], v[150:151], v[170:171]
	v_pk_fma_f32 v[4:5], v[6:7], v[184:185], v[4:5] op_sel_hi:[0,1,1]
	v_pk_mul_f32 v[6:7], v[14:15], v[194:195] op_sel:[0,1] op_sel_hi:[1,0]
	v_mov_b32_e32 v39, v29
	v_pk_fma_f32 v[6:7], v[8:9], v[194:195], v[6:7] op_sel_hi:[0,1,1]
	v_pk_mul_f32 v[8:9], v[22:23], v[164:165] op_sel:[0,1] op_sel_hi:[1,0]
	v_mov_b32_e32 v43, v33
	v_pk_fma_f32 v[8:9], v[10:11], v[164:165], v[8:9] op_sel_hi:[0,1,1]
	v_pk_mul_f32 v[10:11], v[16:17], v[208:209] op_sel:[0,1] op_sel_hi:[1,0]
	v_mov_b32_e32 v47, v37
	v_pk_add_f32 v[150:151], v[150:151], v[170:171] neg_lo:[0,1] neg_hi:[0,1]
	v_pk_add_f32 v[170:171], v[152:153], v[166:167] op_sel:[0,1] op_sel_hi:[1,0] neg_hi:[0,1]
	v_pk_add_f32 v[152:153], v[152:153], v[166:167] op_sel:[0,1] op_sel_hi:[1,0] neg_lo:[0,1]
	v_pk_add_f32 v[166:167], v[144:145], v[154:155]
	v_pk_fma_f32 v[10:11], v[12:13], v[208:209], v[10:11] op_sel_hi:[0,1,1]
	v_pk_mul_f32 v[12:13], v[26:27], v[206:207] op_sel:[0,1] op_sel_hi:[1,0]
	v_pk_mul_f32 v[14:15], v[30:31], v[196:197] op_sel:[0,1] op_sel_hi:[1,0]
	v_xor_b32_e32 v50, 0x80000000, v41
	v_xor_b32_e32 v54, 0x80000000, v45
	v_xor_b32_e32 v58, 0x80000000, v49
	v_xor_b32_e32 v62, 0x80000000, v53
	v_xor_b32_e32 v66, 0x80000000, v57
	v_xor_b32_e32 v70, 0x80000000, v61
	v_xor_b32_e32 v74, 0x80000000, v65
	v_mov_b32_e32 v51, v41
	v_mov_b32_e32 v55, v45
	v_mov_b32_e32 v59, v49
	v_mov_b32_e32 v63, v53
	v_mov_b32_e32 v67, v57
	v_mov_b32_e32 v71, v61
	v_mov_b32_e32 v75, v65
	v_pk_add_f32 v[144:145], v[144:145], v[154:155] neg_lo:[0,1] neg_hi:[0,1]
	v_pk_add_f32 v[154:155], v[128:129], v[148:149]
	v_pk_fma_f32 v[12:13], v[18:19], v[206:207], v[12:13] op_sel_hi:[0,1,1]
	v_pk_fma_f32 v[14:15], v[20:21], v[196:197], v[14:15] op_sel_hi:[0,1,1]
	v_pk_mul_f32 v[16:17], v[34:35], v[166:167] op_sel:[0,1] op_sel_hi:[1,0]
	v_pk_mul_f32 v[18:19], v[38:39], v[210:211] op_sel:[0,1] op_sel_hi:[1,0]
	v_pk_mul_f32 v[20:21], v[42:43], v[190:191] op_sel:[0,1] op_sel_hi:[1,0]
	v_pk_mul_f32 v[22:23], v[46:47], v[204:205] op_sel:[0,1] op_sel_hi:[1,0]
	v_xor_b32_e32 v78, 0x80000000, v69
	v_xor_b32_e32 v82, 0x80000000, v73
	v_xor_b32_e32 v86, 0x80000000, v77
	v_xor_b32_e32 v90, 0x80000000, v81
	v_xor_b32_e32 v94, 0x80000000, v85
	v_xor_b32_e32 v98, 0x80000000, v89
	v_xor_b32_e32 v102, 0x80000000, v93
	v_xor_b32_e32 v106, 0x80000000, v97
	v_xor_b32_e32 v110, 0x80000000, v101
	v_xor_b32_e32 v114, 0x80000000, v105
	v_xor_b32_e32 v118, 0x80000000, v109
	v_xor_b32_e32 v122, 0x80000000, v113
	v_xor_b32_e32 v124, 0x80000000, v117
	v_xor_b32_e32 v126, 0x80000000, v121
	v_mov_b32_e32 v79, v69
	v_mov_b32_e32 v83, v73
	v_mov_b32_e32 v87, v77
	v_mov_b32_e32 v91, v81
	v_mov_b32_e32 v95, v85
	v_mov_b32_e32 v99, v89
	v_mov_b32_e32 v103, v93
	v_mov_b32_e32 v107, v97
	v_mov_b32_e32 v111, v101
	v_mov_b32_e32 v115, v105
	v_mov_b32_e32 v119, v109
	v_mov_b32_e32 v123, v113
	v_mov_b32_e32 v125, v117
	v_mov_b32_e32 v127, v121
	v_pk_add_f32 v[128:129], v[128:129], v[148:149] neg_lo:[0,1] neg_hi:[0,1]
	v_pk_fma_f32 v[16:17], v[24:25], v[166:167], v[16:17] op_sel_hi:[0,1,1]
	v_pk_fma_f32 v[18:19], v[28:29], v[210:211], v[18:19] op_sel_hi:[0,1,1]
	v_pk_fma_f32 v[20:21], v[32:33], v[190:191], v[20:21] op_sel_hi:[0,1,1]
	v_pk_fma_f32 v[22:23], v[36:37], v[204:205], v[22:23] op_sel_hi:[0,1,1]
	v_pk_mul_f32 v[24:25], v[50:51], v[170:171] op_sel:[0,1] op_sel_hi:[1,0]
	v_pk_mul_f32 v[26:27], v[54:55], v[198:199] op_sel:[0,1] op_sel_hi:[1,0]
	v_pk_mul_f32 v[28:29], v[58:59], v[168:169] op_sel:[0,1] op_sel_hi:[1,0]
	v_pk_mul_f32 v[30:31], v[62:63], v[188:189] op_sel:[0,1] op_sel_hi:[1,0]
	v_pk_mul_f32 v[32:33], v[66:67], v[154:155] op_sel:[0,1] op_sel_hi:[1,0]
	v_pk_mul_f32 v[34:35], v[70:71], v[156:157] op_sel:[0,1] op_sel_hi:[1,0]
	v_pk_mul_f32 v[36:37], v[74:75], v[158:159] op_sel:[0,1] op_sel_hi:[1,0]
	v_pk_fma_f32 v[24:25], v[40:41], v[170:171], v[24:25] op_sel_hi:[0,1,1]
	v_pk_fma_f32 v[26:27], v[44:45], v[198:199], v[26:27] op_sel_hi:[0,1,1]
	v_pk_fma_f32 v[28:29], v[48:49], v[168:169], v[28:29] op_sel_hi:[0,1,1]
	v_pk_fma_f32 v[30:31], v[52:53], v[188:189], v[30:31] op_sel_hi:[0,1,1]
	v_pk_fma_f32 v[32:33], v[56:57], v[154:155], v[32:33] op_sel_hi:[0,1,1]
	v_pk_fma_f32 v[34:35], v[60:61], v[156:157], v[34:35] op_sel_hi:[0,1,1]
	v_pk_fma_f32 v[36:37], v[64:65], v[158:159], v[36:37] op_sel_hi:[0,1,1]
	v_pk_mul_f32 v[38:39], v[78:79], v[180:181] op_sel:[0,1] op_sel_hi:[1,0]
	v_pk_mul_f32 v[40:41], v[82:83], v[150:151] op_sel:[0,1] op_sel_hi:[1,0]
	v_pk_mul_f32 v[42:43], v[86:87], v[174:175] op_sel:[0,1] op_sel_hi:[1,0]
	v_pk_mul_f32 v[44:45], v[90:91], v[160:161] op_sel:[0,1] op_sel_hi:[1,0]
	v_pk_mul_f32 v[46:47], v[94:95], v[176:177] op_sel:[0,1] op_sel_hi:[1,0]
	v_pk_mul_f32 v[48:49], v[98:99], v[144:145] op_sel:[0,1] op_sel_hi:[1,0]
	v_pk_mul_f32 v[50:51], v[102:103], v[172:173] op_sel:[0,1] op_sel_hi:[1,0]
	v_pk_mul_f32 v[52:53], v[106:107], v[186:187] op_sel:[0,1] op_sel_hi:[1,0]
	v_pk_mul_f32 v[54:55], v[110:111], v[182:183] op_sel:[0,1] op_sel_hi:[1,0]
	v_pk_mul_f32 v[56:57], v[114:115], v[152:153] op_sel:[0,1] op_sel_hi:[1,0]
	v_pk_mul_f32 v[58:59], v[118:119], v[192:193] op_sel:[0,1] op_sel_hi:[1,0]
	v_pk_mul_f32 v[60:61], v[122:123], v[162:163] op_sel:[0,1] op_sel_hi:[1,0]
	v_pk_mul_f32 v[62:63], v[124:125], v[178:179] op_sel:[0,1] op_sel_hi:[1,0]
	v_pk_mul_f32 v[64:65], v[126:127], v[128:129] op_sel:[0,1] op_sel_hi:[1,0]
	v_pk_fma_f32 v[38:39], v[68:69], v[180:181], v[38:39] op_sel_hi:[0,1,1]
	v_pk_fma_f32 v[40:41], v[72:73], v[150:151], v[40:41] op_sel_hi:[0,1,1]
	v_pk_fma_f32 v[42:43], v[76:77], v[174:175], v[42:43] op_sel_hi:[0,1,1]
	v_pk_fma_f32 v[44:45], v[80:81], v[160:161], v[44:45] op_sel_hi:[0,1,1]
	v_pk_fma_f32 v[46:47], v[84:85], v[176:177], v[46:47] op_sel_hi:[0,1,1]
	v_pk_fma_f32 v[48:49], v[88:89], v[144:145], v[48:49] op_sel_hi:[0,1,1]
	v_pk_fma_f32 v[50:51], v[92:93], v[172:173], v[50:51] op_sel_hi:[0,1,1]
	v_pk_fma_f32 v[52:53], v[96:97], v[186:187], v[52:53] op_sel_hi:[0,1,1]
	v_pk_fma_f32 v[54:55], v[100:101], v[182:183], v[54:55] op_sel_hi:[0,1,1]
	v_pk_fma_f32 v[56:57], v[104:105], v[152:153], v[56:57] op_sel_hi:[0,1,1]
	v_pk_fma_f32 v[58:59], v[108:109], v[192:193], v[58:59] op_sel_hi:[0,1,1]
	v_pk_fma_f32 v[60:61], v[112:113], v[162:163], v[60:61] op_sel_hi:[0,1,1]
	v_pk_fma_f32 v[62:63], v[116:117], v[178:179], v[62:63] op_sel_hi:[0,1,1]
	v_pk_fma_f32 v[64:65], v[120:121], v[128:129], v[64:65] op_sel_hi:[0,1,1]
	ds_write_b64 v2, v[130:131]
	ds_write_b64 v2, v[34:35] offset:2112
	ds_write_b64 v2, v[18:19] offset:4224
	ds_write_b64 v2, v[50:51] offset:6336
	ds_write_b64 v2, v[10:11] offset:8448
	ds_write_b64 v2, v[42:43] offset:10560
	ds_write_b64 v2, v[26:27] offset:12672
	ds_write_b64 v2, v[58:59] offset:14784
	ds_write_b64 v2, v[6:7] offset:16896
	ds_write_b64 v2, v[38:39] offset:19008
	ds_write_b64 v2, v[22:23] offset:21120
	ds_write_b64 v2, v[54:55] offset:23232
	ds_write_b64 v2, v[14:15] offset:25344
	ds_write_b64 v2, v[46:47] offset:27456
	ds_write_b64 v2, v[30:31] offset:29568
	ds_write_b64 v2, v[62:63] offset:31680
	ds_write_b64 v2, v[4:5] offset:33792
	ds_write_b64 v2, v[36:37] offset:35904
	ds_write_b64 v2, v[20:21] offset:38016
	ds_write_b64 v2, v[52:53] offset:40128
	ds_write_b64 v2, v[12:13] offset:42240
	ds_write_b64 v2, v[44:45] offset:44352
	ds_write_b64 v2, v[28:29] offset:46464
	ds_write_b64 v2, v[60:61] offset:48576
	ds_write_b64 v2, v[8:9] offset:50688
	ds_write_b64 v2, v[40:41] offset:52800
	ds_write_b64 v2, v[24:25] offset:54912
	ds_write_b64 v2, v[56:57] offset:57024
	ds_write_b64 v2, v[16:17] offset:59136
	ds_write_b64 v2, v[48:49] offset:61248
	ds_write_b64 v2, v[32:33] offset:63360
	ds_write_b64 v2, v[64:65] offset:65472
	v_mov_b32_e32 v2, v142
	s_waitcnt lgkmcnt(0)
	s_barrier
	s_nop 0
	v_and_b32_e32 v5, 15, v2
	v_cvt_f32_ubyte0_e32 v4, v5
	v_mul_f32_e32 v6, 0x3b800000, v4
	v_sin_f32_e32 v4, v6
	v_cos_f32_e32 v6, v6
	v_lshlrev_b32_e32 v64, 3, v5
	v_lshlrev_b32_e32 v2, 4, v2
	v_xor_b32_e32 v7, 0x80000000, v4
	v_mov_b32_e32 v5, v7
	v_pk_mul_f32 v[8:9], v[6:7], v[4:5] op_sel:[1,0] op_sel_hi:[0,1]
	v_pk_fma_f32 v[8:9], v[6:7], v[6:7], v[8:9] op_sel_hi:[1,0,1]
	v_and_b32_e32 v2, 0xffffff00, v2
	v_xor_b32_e32 v14, 0x80000000, v9
	v_mov_b32_e32 v15, v9
	v_pk_mul_f32 v[12:13], v[8:9], v[14:15] op_sel:[1,0] op_sel_hi:[0,1]
	v_pk_fma_f32 v[12:13], v[8:9], v[8:9], v[12:13] op_sel_hi:[1,0,1]
	v_pk_mul_f32 v[10:11], v[4:5], v[8:9] op_sel:[0,1] op_sel_hi:[1,0]
	v_xor_b32_e32 v16, 0x80000000, v13
	v_mov_b32_e32 v17, v13
	v_pk_mul_f32 v[32:33], v[12:13], v[16:17] op_sel:[1,0] op_sel_hi:[0,1]
	v_pk_fma_f32 v[32:33], v[12:13], v[12:13], v[32:33] op_sel_hi:[1,0,1]
	v_pk_mul_f32 v[18:19], v[4:5], v[12:13] op_sel:[0,1] op_sel_hi:[1,0]
	v_pk_mul_f32 v[48:49], v[16:17], v[32:33] op_sel:[0,1] op_sel_hi:[1,0]
	v_pk_mul_f32 v[36:37], v[4:5], v[32:33] op_sel:[0,1] op_sel_hi:[1,0]
	v_pk_fma_f32 v[48:49], v[12:13], v[32:33], v[48:49] op_sel_hi:[0,1,1]
	v_pk_mul_f32 v[52:53], v[4:5], v[48:49] op_sel:[0,1] op_sel_hi:[1,0]
	v_pk_fma_f32 v[10:11], v[6:7], v[8:9], v[10:11] op_sel_hi:[0,1,1]
	v_pk_fma_f32 v[18:19], v[6:7], v[12:13], v[18:19] op_sel_hi:[0,1,1]
	v_pk_fma_f32 v[36:37], v[6:7], v[32:33], v[36:37] op_sel_hi:[0,1,1]
	v_pk_fma_f32 v[52:53], v[6:7], v[48:49], v[52:53] op_sel_hi:[0,1,1]
	v_lshlrev_b32_e32 v7, 3, v2
	v_add3_u32 v7, 0, v64, v7
	v_ashrrev_i32_e32 v64, 2, v2
	v_add_u32_e32 v106, v7, v64
	ds_read2_b64 v[64:67], v106 offset1:16
	ds_read2_b64 v[68:71], v106 offset0:33 offset1:49
	ds_read2_b64 v[72:75], v106 offset0:66 offset1:82
	ds_read2_b64 v[76:79], v106 offset0:132 offset1:148
	ds_read2_b64 v[80:83], v106 offset0:99 offset1:115
	ds_read2_b64 v[84:87], v106 offset0:165 offset1:181
	ds_read2_b64 v[88:91], v106 offset0:198 offset1:214
	ds_read2_b64 v[92:95], v106 offset0:231 offset1:247
	s_waitcnt lgkmcnt(4)
	v_pk_add_f32 v[96:97], v[64:65], v[76:77]
	v_pk_add_f32 v[64:65], v[64:65], v[76:77] neg_lo:[0,1] neg_hi:[0,1]
	v_pk_add_f32 v[76:77], v[66:67], v[78:79]
	v_pk_add_f32 v[66:67], v[66:67], v[78:79] neg_lo:[0,1] neg_hi:[0,1]
	s_waitcnt lgkmcnt(1)
	v_pk_add_f32 v[98:99], v[74:75], v[90:91]
	v_pk_mul_f32 v[78:79], v[66:67], s[24:25]
	v_pk_add_f32 v[74:75], v[74:75], v[90:91] neg_lo:[0,1] neg_hi:[0,1]
	v_pk_fma_f32 v[66:67], v[66:67], s[22:23], v[78:79] op_sel:[0,0,1] op_sel_hi:[1,0,0]
	v_pk_add_f32 v[78:79], v[68:69], v[84:85]
	v_pk_add_f32 v[68:69], v[68:69], v[84:85] neg_lo:[0,1] neg_hi:[0,1]
	v_pk_mul_f32 v[90:91], v[74:75], s[44:45]
	v_pk_mul_f32 v[84:85], v[68:69], s[40:41]
	v_pk_fma_f32 v[74:75], v[74:75], s[50:51], v[90:91] op_sel:[0,0,1] op_sel_hi:[1,0,0] neg_lo:[1,0,0] neg_hi:[1,0,0]
	v_pk_fma_f32 v[68:69], v[68:69], s[38:39], v[84:85] op_sel:[0,0,1] op_sel_hi:[1,0,0]
	v_pk_add_f32 v[84:85], v[70:71], v[86:87]
	v_pk_add_f32 v[70:71], v[70:71], v[86:87] neg_lo:[0,1] neg_hi:[0,1]
	s_waitcnt lgkmcnt(0)
	v_pk_add_f32 v[90:91], v[80:81], v[92:93]
	v_pk_add_f32 v[80:81], v[80:81], v[92:93] neg_lo:[0,1] neg_hi:[0,1]
	v_pk_mul_f32 v[86:87], v[70:71], s[44:45]
	v_pk_mul_f32 v[92:93], v[80:81], s[40:41]
	v_pk_fma_f32 v[70:71], v[70:71], s[50:51], v[86:87] op_sel:[0,0,1] op_sel_hi:[1,0,0]
	v_pk_add_f32 v[86:87], v[72:73], v[88:89]
	v_pk_add_f32 v[88:89], v[72:73], v[88:89] neg_lo:[0,1] neg_hi:[0,1]
	v_pk_fma_f32 v[80:81], v[80:81], s[38:39], v[92:93] op_sel:[0,0,1] op_sel_hi:[1,0,0] neg_lo:[1,0,0] neg_hi:[1,0,0]
	v_pk_add_f32 v[92:93], v[82:83], v[94:95]
	v_pk_add_f32 v[82:83], v[82:83], v[94:95] neg_lo:[0,1] neg_hi:[0,1]
	s_nop 0
	v_pk_mul_f32 v[94:95], v[82:83], s[24:25]
	s_nop 0
	v_pk_fma_f32 v[82:83], v[82:83], s[22:23], v[94:95] op_sel:[0,0,1] op_sel_hi:[1,0,0] neg_lo:[1,0,0] neg_hi:[1,0,0]
	v_pk_add_f32 v[94:95], v[96:97], v[86:87]
	v_pk_add_f32 v[86:87], v[96:97], v[86:87] neg_lo:[0,1] neg_hi:[0,1]
	v_pk_add_f32 v[96:97], v[76:77], v[98:99]
	v_pk_add_f32 v[76:77], v[76:77], v[98:99] neg_lo:[0,1] neg_hi:[0,1]
	v_pk_add_f32 v[100:101], v[84:85], v[92:93]
	v_pk_add_f32 v[84:85], v[84:85], v[92:93] neg_lo:[0,1] neg_hi:[0,1]
	v_pk_add_f32 v[72:73], v[64:65], v[88:89] op_sel:[0,1] op_sel_hi:[1,0] neg_hi:[0,1]
	v_pk_add_f32 v[64:65], v[64:65], v[88:89] op_sel:[0,1] op_sel_hi:[1,0] neg_lo:[0,1]
	v_pk_add_f32 v[88:89], v[66:67], v[74:75]
	v_pk_add_f32 v[66:67], v[66:67], v[74:75] neg_lo:[0,1] neg_hi:[0,1]
	v_pk_mul_f32 v[98:99], v[76:77], s[40:41]
	v_pk_mul_f32 v[92:93], v[84:85], s[40:41]
	v_pk_mul_f32 v[74:75], v[66:67], s[40:41]
	v_pk_fma_f32 v[76:77], v[76:77], s[38:39], v[98:99] op_sel:[0,0,1] op_sel_hi:[1,0,0]
	v_pk_add_f32 v[98:99], v[78:79], v[90:91]
	v_pk_add_f32 v[90:91], v[78:79], v[90:91] neg_lo:[0,1] neg_hi:[0,1]
	v_pk_fma_f32 v[84:85], v[84:85], s[38:39], v[92:93] op_sel:[0,0,1] op_sel_hi:[1,0,0] neg_lo:[1,0,0] neg_hi:[1,0,0]
	v_pk_fma_f32 v[66:67], v[66:67], s[38:39], v[74:75] op_sel:[0,0,1] op_sel_hi:[1,0,0]
	v_pk_add_f32 v[74:75], v[68:69], v[80:81]
	v_pk_add_f32 v[92:93], v[70:71], v[82:83]
	v_pk_add_f32 v[70:71], v[70:71], v[82:83] neg_lo:[0,1] neg_hi:[0,1]
	v_pk_add_f32 v[80:81], v[68:69], v[80:81] neg_lo:[0,1] neg_hi:[0,1]
	v_pk_mul_f32 v[82:83], v[70:71], s[40:41]
	v_pk_add_f32 v[102:103], v[72:73], v[74:75]
	v_pk_add_f32 v[72:73], v[72:73], v[74:75] neg_lo:[0,1] neg_hi:[0,1]
	v_pk_add_f32 v[74:75], v[88:89], v[92:93]
	v_pk_add_f32 v[92:93], v[88:89], v[92:93] neg_lo:[0,1] neg_hi:[0,1]
	v_xor_b32_e32 v20, 0x80000000, v11
	v_mov_b32_e32 v21, v11
	v_pk_mul_f32 v[24:25], v[14:15], v[12:13] op_sel:[0,1] op_sel_hi:[1,0]
	v_pk_fma_f32 v[70:71], v[70:71], s[38:39], v[82:83] op_sel:[0,0,1] op_sel_hi:[1,0,0] neg_lo:[1,0,0] neg_hi:[1,0,0]
	v_pk_add_f32 v[78:79], v[86:87], v[90:91] op_sel:[0,1] op_sel_hi:[1,0] neg_hi:[0,1]
	v_pk_add_f32 v[86:87], v[86:87], v[90:91] op_sel:[0,1] op_sel_hi:[1,0] neg_lo:[0,1]
	v_pk_add_f32 v[90:91], v[76:77], v[84:85]
	v_pk_add_f32 v[84:85], v[76:77], v[84:85] neg_lo:[0,1] neg_hi:[0,1]
	v_xor_b32_e32 v22, 0x80000000, v19
	v_mov_b32_e32 v23, v19
	v_pk_fma_f32 v[24:25], v[8:9], v[12:13], v[24:25] op_sel_hi:[0,1,1]
	v_pk_mul_f32 v[28:29], v[12:13], v[20:21] op_sel:[1,0] op_sel_hi:[0,1]
	v_pk_add_f32 v[68:69], v[64:65], v[80:81] op_sel:[0,1] op_sel_hi:[1,0] neg_hi:[0,1]
	v_pk_add_f32 v[64:65], v[64:65], v[80:81] op_sel:[0,1] op_sel_hi:[1,0] neg_lo:[0,1]
	v_pk_add_f32 v[80:81], v[66:67], v[70:71]
	v_pk_add_f32 v[70:71], v[66:67], v[70:71] neg_lo:[0,1] neg_hi:[0,1]
	v_pk_add_f32 v[88:89], v[72:73], v[92:93] op_sel:[0,1] op_sel_hi:[1,0] neg_hi:[0,1]
	v_xor_b32_e32 v26, 0x80000000, v25
	v_mov_b32_e32 v27, v25
	v_pk_fma_f32 v[28:29], v[12:13], v[10:11], v[28:29] op_sel_hi:[1,0,1]
	v_pk_add_f32 v[76:77], v[86:87], v[84:85] op_sel:[0,1] op_sel_hi:[1,0] neg_hi:[0,1]
	v_pk_add_f32 v[72:73], v[72:73], v[92:93] op_sel:[0,1] op_sel_hi:[1,0] neg_lo:[0,1]
	v_pk_mul_f32 v[92:93], v[22:23], v[88:89] op_sel:[0,1] op_sel_hi:[1,0]
	v_xor_b32_e32 v30, 0x80000000, v29
	v_mov_b32_e32 v31, v29
	v_pk_add_f32 v[82:83], v[94:95], v[98:99]
	v_pk_add_f32 v[94:95], v[94:95], v[98:99] neg_lo:[0,1] neg_hi:[0,1]
	v_pk_add_f32 v[98:99], v[96:97], v[100:101]
	v_pk_add_f32 v[66:67], v[64:65], v[70:71] op_sel:[0,1] op_sel_hi:[1,0] neg_hi:[0,1]
	v_pk_fma_f32 v[88:89], v[18:19], v[88:89], v[92:93] op_sel_hi:[0,1,1]
	v_pk_mul_f32 v[92:93], v[26:27], v[76:77] op_sel:[0,1] op_sel_hi:[1,0]
	v_xor_b32_e32 v34, 0x80000000, v33
	v_mov_b32_e32 v35, v33
	v_pk_mul_f32 v[40:41], v[14:15], v[32:33] op_sel:[0,1] op_sel_hi:[1,0]
	v_pk_add_f32 v[104:105], v[82:83], v[98:99]
	v_pk_add_f32 v[82:83], v[82:83], v[98:99] neg_lo:[0,1] neg_hi:[0,1]
	v_pk_fma_f32 v[76:77], v[24:25], v[76:77], v[92:93] op_sel_hi:[0,1,1]
	v_pk_mul_f32 v[92:93], v[30:31], v[66:67] op_sel:[0,1] op_sel_hi:[1,0]
	v_xor_b32_e32 v38, 0x80000000, v37
	v_mov_b32_e32 v39, v37
	v_pk_fma_f32 v[40:41], v[8:9], v[32:33], v[40:41] op_sel_hi:[0,1,1]
	v_pk_mul_f32 v[44:45], v[20:21], v[32:33] op_sel:[0,1] op_sel_hi:[1,0]
	v_pk_add_f32 v[84:85], v[86:87], v[84:85] op_sel:[0,1] op_sel_hi:[1,0] neg_lo:[0,1]
	v_pk_add_f32 v[86:87], v[102:103], v[74:75]
	v_pk_add_f32 v[74:75], v[102:103], v[74:75] neg_lo:[0,1] neg_hi:[0,1]
	v_pk_fma_f32 v[66:67], v[28:29], v[66:67], v[92:93] op_sel_hi:[0,1,1]
	v_pk_mul_f32 v[92:93], v[34:35], v[82:83] op_sel:[0,1] op_sel_hi:[1,0]
	v_xor_b32_e32 v42, 0x80000000, v41
	v_mov_b32_e32 v43, v41
	v_pk_fma_f32 v[44:45], v[10:11], v[32:33], v[44:45] op_sel_hi:[0,1,1]
	v_pk_add_f32 v[100:101], v[96:97], v[100:101] neg_lo:[0,1] neg_hi:[0,1]
	v_pk_add_f32 v[98:99], v[78:79], v[90:91]
	v_pk_add_f32 v[78:79], v[78:79], v[90:91] neg_lo:[0,1] neg_hi:[0,1]
	v_pk_fma_f32 v[82:83], v[32:33], v[82:83], v[92:93] op_sel_hi:[0,1,1]
	v_pk_mul_f32 v[92:93], v[38:39], v[74:75] op_sel:[0,1] op_sel_hi:[1,0]
	v_xor_b32_e32 v46, 0x80000000, v45
	v_mov_b32_e32 v47, v45
	v_pk_add_f32 v[90:91], v[68:69], v[80:81]
	v_pk_add_f32 v[68:69], v[68:69], v[80:81] neg_lo:[0,1] neg_hi:[0,1]
	v_pk_fma_f32 v[74:75], v[36:37], v[74:75], v[92:93] op_sel_hi:[0,1,1]
	v_pk_mul_f32 v[92:93], v[42:43], v[78:79] op_sel:[0,1] op_sel_hi:[1,0]
	v_xor_b32_e32 v50, 0x80000000, v49
	v_mov_b32_e32 v51, v49
	v_pk_mul_f32 v[56:57], v[14:15], v[48:49] op_sel:[0,1] op_sel_hi:[1,0]
	v_pk_add_f32 v[96:97], v[94:95], v[100:101] op_sel:[0,1] op_sel_hi:[1,0] neg_hi:[0,1]
	v_pk_add_f32 v[94:95], v[94:95], v[100:101] op_sel:[0,1] op_sel_hi:[1,0] neg_lo:[0,1]
	v_pk_fma_f32 v[78:79], v[40:41], v[78:79], v[92:93] op_sel_hi:[0,1,1]
	v_pk_mul_f32 v[92:93], v[46:47], v[68:69] op_sel:[0,1] op_sel_hi:[1,0]
	v_xor_b32_e32 v54, 0x80000000, v53
	v_mov_b32_e32 v55, v53
	v_pk_fma_f32 v[56:57], v[8:9], v[48:49], v[56:57] op_sel_hi:[0,1,1]
	v_pk_mul_f32 v[60:61], v[20:21], v[48:49] op_sel:[0,1] op_sel_hi:[1,0]
	v_pk_fma_f32 v[68:69], v[44:45], v[68:69], v[92:93] op_sel_hi:[0,1,1]
	v_pk_mul_f32 v[92:93], v[50:51], v[94:95] op_sel:[0,1] op_sel_hi:[1,0]
	v_xor_b32_e32 v58, 0x80000000, v57
	v_mov_b32_e32 v59, v57
	v_pk_fma_f32 v[60:61], v[10:11], v[48:49], v[60:61] op_sel_hi:[0,1,1]
	v_pk_add_f32 v[64:65], v[64:65], v[70:71] op_sel:[0,1] op_sel_hi:[1,0] neg_lo:[0,1]
	v_pk_mul_f32 v[70:71], v[4:5], v[86:87] op_sel:[0,1] op_sel_hi:[1,0]
	v_pk_fma_f32 v[92:93], v[48:49], v[94:95], v[92:93] op_sel_hi:[0,1,1]
	v_pk_mul_f32 v[94:95], v[54:55], v[72:73] op_sel:[0,1] op_sel_hi:[1,0]
	v_xor_b32_e32 v62, 0x80000000, v61
	v_mov_b32_e32 v63, v61
	v_pk_fma_f32 v[70:71], v[6:7], v[86:87], v[70:71] op_sel_hi:[0,1,1]
	v_pk_mul_f32 v[86:87], v[20:21], v[90:91] op_sel:[0,1] op_sel_hi:[1,0]
	v_pk_fma_f32 v[72:73], v[52:53], v[72:73], v[94:95] op_sel_hi:[0,1,1]
	v_pk_mul_f32 v[94:95], v[58:59], v[84:85] op_sel:[0,1] op_sel_hi:[1,0]
	v_add_u32_e32 v2, 0x2000, v2
	v_pk_mul_f32 v[80:81], v[14:15], v[98:99] op_sel:[0,1] op_sel_hi:[1,0]
	v_pk_fma_f32 v[86:87], v[10:11], v[90:91], v[86:87] op_sel_hi:[0,1,1]
	v_pk_mul_f32 v[90:91], v[16:17], v[96:97] op_sel:[0,1] op_sel_hi:[1,0]
	v_pk_fma_f32 v[84:85], v[56:57], v[84:85], v[94:95] op_sel_hi:[0,1,1]
	v_pk_mul_f32 v[94:95], v[62:63], v[64:65] op_sel:[0,1] op_sel_hi:[1,0]
	v_ashrrev_i32_e32 v2, 2, v2
	v_pk_fma_f32 v[80:81], v[8:9], v[98:99], v[80:81] op_sel_hi:[0,1,1]
	v_pk_fma_f32 v[90:91], v[12:13], v[96:97], v[90:91] op_sel_hi:[0,1,1]
	v_pk_fma_f32 v[64:65], v[60:61], v[64:65], v[94:95] op_sel_hi:[0,1,1]
	ds_write2_b64 v106, v[104:105], v[82:83] offset1:16
	ds_write2_b64 v106, v[90:91], v[92:93] offset0:33 offset1:49
	ds_write2_b64 v106, v[80:81], v[78:79] offset0:66 offset1:82
	ds_write2_b64 v106, v[76:77], v[84:85] offset0:99 offset1:115
	ds_write2_b64 v106, v[70:71], v[74:75] offset0:132 offset1:148
	ds_write2_b64 v106, v[88:89], v[72:73] offset0:165 offset1:181
	ds_write2_b64 v106, v[86:87], v[68:69] offset0:198 offset1:214
	ds_write2_b64 v106, v[66:67], v[64:65] offset0:231 offset1:247
	v_add3_u32 v2, v7, v2, s60
	ds_read2_b64 v[64:67], v2 offset1:16
	ds_read2_b64 v[68:71], v2 offset0:33 offset1:49
	ds_read2_b64 v[72:75], v2 offset0:66 offset1:82
	ds_read2_b64 v[76:79], v2 offset0:132 offset1:148
	ds_read2_b64 v[80:83], v2 offset0:99 offset1:115
	ds_read2_b64 v[84:87], v2 offset0:165 offset1:181
	ds_read2_b64 v[88:91], v2 offset0:198 offset1:214
	ds_read2_b64 v[92:95], v2 offset0:231 offset1:247
	s_waitcnt lgkmcnt(4)
	v_pk_add_f32 v[96:97], v[64:65], v[76:77]
	v_pk_add_f32 v[64:65], v[64:65], v[76:77] neg_lo:[0,1] neg_hi:[0,1]
	v_pk_add_f32 v[76:77], v[66:67], v[78:79]
	v_pk_add_f32 v[66:67], v[66:67], v[78:79] neg_lo:[0,1] neg_hi:[0,1]
	s_waitcnt lgkmcnt(1)
	v_pk_add_f32 v[98:99], v[74:75], v[90:91]
	v_pk_mul_f32 v[78:79], v[66:67], s[24:25]
	v_pk_add_f32 v[74:75], v[74:75], v[90:91] neg_lo:[0,1] neg_hi:[0,1]
	v_pk_fma_f32 v[66:67], v[66:67], s[22:23], v[78:79] op_sel:[0,0,1] op_sel_hi:[1,0,0]
	v_pk_add_f32 v[78:79], v[68:69], v[84:85]
	v_pk_add_f32 v[68:69], v[68:69], v[84:85] neg_lo:[0,1] neg_hi:[0,1]
	v_pk_mul_f32 v[90:91], v[74:75], s[44:45]
	v_pk_mul_f32 v[84:85], v[68:69], s[40:41]
	v_pk_fma_f32 v[74:75], v[74:75], s[50:51], v[90:91] op_sel:[0,0,1] op_sel_hi:[1,0,0] neg_lo:[1,0,0] neg_hi:[1,0,0]
	s_waitcnt lgkmcnt(0)
	v_pk_add_f32 v[90:91], v[80:81], v[92:93]
	v_pk_add_f32 v[80:81], v[80:81], v[92:93] neg_lo:[0,1] neg_hi:[0,1]
	v_pk_fma_f32 v[68:69], v[68:69], s[38:39], v[84:85] op_sel:[0,0,1] op_sel_hi:[1,0,0]
	v_pk_add_f32 v[84:85], v[70:71], v[86:87]
	v_pk_add_f32 v[70:71], v[70:71], v[86:87] neg_lo:[0,1] neg_hi:[0,1]
	v_pk_mul_f32 v[92:93], v[80:81], s[40:41]
	v_pk_mul_f32 v[86:87], v[70:71], s[44:45]
	v_pk_fma_f32 v[80:81], v[80:81], s[38:39], v[92:93] op_sel:[0,0,1] op_sel_hi:[1,0,0] neg_lo:[1,0,0] neg_hi:[1,0,0]
	v_pk_add_f32 v[92:93], v[82:83], v[94:95]
	v_pk_add_f32 v[82:83], v[82:83], v[94:95] neg_lo:[0,1] neg_hi:[0,1]
	v_pk_fma_f32 v[70:71], v[70:71], s[50:51], v[86:87] op_sel:[0,0,1] op_sel_hi:[1,0,0]
	v_pk_add_f32 v[86:87], v[72:73], v[88:89]
	v_pk_mul_f32 v[94:95], v[82:83], s[24:25]
	v_pk_add_f32 v[88:89], v[72:73], v[88:89] neg_lo:[0,1] neg_hi:[0,1]
	v_pk_fma_f32 v[82:83], v[82:83], s[22:23], v[94:95] op_sel:[0,0,1] op_sel_hi:[1,0,0] neg_lo:[1,0,0] neg_hi:[1,0,0]
	v_pk_add_f32 v[94:95], v[96:97], v[86:87]
	v_pk_add_f32 v[86:87], v[96:97], v[86:87] neg_lo:[0,1] neg_hi:[0,1]
	v_pk_add_f32 v[96:97], v[76:77], v[98:99]
	v_pk_add_f32 v[76:77], v[76:77], v[98:99] neg_lo:[0,1] neg_hi:[0,1]
	s_nop 0
	v_pk_mul_f32 v[98:99], v[76:77], s[40:41]
	v_pk_add_f32 v[100:101], v[84:85], v[92:93]
	v_pk_add_f32 v[84:85], v[84:85], v[92:93] neg_lo:[0,1] neg_hi:[0,1]
	v_pk_fma_f32 v[76:77], v[76:77], s[38:39], v[98:99] op_sel:[0,0,1] op_sel_hi:[1,0,0]
	v_pk_add_f32 v[98:99], v[78:79], v[90:91]
	v_pk_add_f32 v[90:91], v[78:79], v[90:91] neg_lo:[0,1] neg_hi:[0,1]
	v_pk_mul_f32 v[92:93], v[84:85], s[40:41]
	v_pk_add_f32 v[72:73], v[64:65], v[88:89] op_sel:[0,1] op_sel_hi:[1,0] neg_hi:[0,1]
	v_pk_add_f32 v[64:65], v[64:65], v[88:89] op_sel:[0,1] op_sel_hi:[1,0] neg_lo:[0,1]
	v_pk_add_f32 v[88:89], v[66:67], v[74:75]
	v_pk_add_f32 v[66:67], v[66:67], v[74:75] neg_lo:[0,1] neg_hi:[0,1]
	v_pk_fma_f32 v[84:85], v[84:85], s[38:39], v[92:93] op_sel:[0,0,1] op_sel_hi:[1,0,0] neg_lo:[1,0,0] neg_hi:[1,0,0]
	v_pk_mul_f32 v[74:75], v[66:67], s[40:41]
	s_nop 0
	v_pk_fma_f32 v[66:67], v[66:67], s[38:39], v[74:75] op_sel:[0,0,1] op_sel_hi:[1,0,0]
	v_pk_add_f32 v[74:75], v[68:69], v[80:81]
	v_pk_add_f32 v[92:93], v[70:71], v[82:83]
	v_pk_add_f32 v[70:71], v[70:71], v[82:83] neg_lo:[0,1] neg_hi:[0,1]
	v_pk_add_f32 v[78:79], v[86:87], v[90:91] op_sel:[0,1] op_sel_hi:[1,0] neg_hi:[0,1]
	v_pk_add_f32 v[86:87], v[86:87], v[90:91] op_sel:[0,1] op_sel_hi:[1,0] neg_lo:[0,1]
	v_pk_add_f32 v[90:91], v[76:77], v[84:85]
	v_pk_add_f32 v[84:85], v[76:77], v[84:85] neg_lo:[0,1] neg_hi:[0,1]
	v_pk_add_f32 v[80:81], v[68:69], v[80:81] neg_lo:[0,1] neg_hi:[0,1]
	v_pk_mul_f32 v[82:83], v[70:71], s[40:41]
	v_pk_add_f32 v[102:103], v[72:73], v[74:75]
	v_pk_add_f32 v[72:73], v[72:73], v[74:75] neg_lo:[0,1] neg_hi:[0,1]
	v_pk_add_f32 v[74:75], v[88:89], v[92:93]
	v_pk_fma_f32 v[70:71], v[70:71], s[38:39], v[82:83] op_sel:[0,0,1] op_sel_hi:[1,0,0] neg_lo:[1,0,0] neg_hi:[1,0,0]
	v_pk_add_f32 v[82:83], v[94:95], v[98:99]
	v_pk_add_f32 v[94:95], v[94:95], v[98:99] neg_lo:[0,1] neg_hi:[0,1]
	v_pk_add_f32 v[98:99], v[96:97], v[100:101]
	v_pk_add_f32 v[76:77], v[86:87], v[84:85] op_sel:[0,1] op_sel_hi:[1,0] neg_hi:[0,1]
	v_pk_add_f32 v[84:85], v[86:87], v[84:85] op_sel:[0,1] op_sel_hi:[1,0] neg_lo:[0,1]
	v_pk_add_f32 v[86:87], v[102:103], v[74:75]
	v_pk_add_f32 v[100:101], v[96:97], v[100:101] neg_lo:[0,1] neg_hi:[0,1]
	v_pk_add_f32 v[68:69], v[64:65], v[80:81] op_sel:[0,1] op_sel_hi:[1,0] neg_hi:[0,1]
	v_pk_add_f32 v[64:65], v[64:65], v[80:81] op_sel:[0,1] op_sel_hi:[1,0] neg_lo:[0,1]
	v_pk_add_f32 v[80:81], v[66:67], v[70:71]
	v_pk_add_f32 v[104:105], v[82:83], v[98:99]
	v_pk_add_f32 v[82:83], v[82:83], v[98:99] neg_lo:[0,1] neg_hi:[0,1]
	v_pk_add_f32 v[98:99], v[78:79], v[90:91]
	v_pk_mul_f32 v[4:5], v[4:5], v[86:87] op_sel:[0,1] op_sel_hi:[1,0]
	v_pk_add_f32 v[92:93], v[88:89], v[92:93] neg_lo:[0,1] neg_hi:[0,1]
	v_pk_add_f32 v[78:79], v[78:79], v[90:91] neg_lo:[0,1] neg_hi:[0,1]
	v_pk_add_f32 v[90:91], v[68:69], v[80:81]
	v_pk_fma_f32 v[4:5], v[6:7], v[86:87], v[4:5] op_sel_hi:[0,1,1]
	v_pk_mul_f32 v[6:7], v[14:15], v[98:99] op_sel:[0,1] op_sel_hi:[1,0]
	v_pk_add_f32 v[70:71], v[66:67], v[70:71] neg_lo:[0,1] neg_hi:[0,1]
	v_pk_add_f32 v[96:97], v[94:95], v[100:101] op_sel:[0,1] op_sel_hi:[1,0] neg_hi:[0,1]
	v_pk_fma_f32 v[6:7], v[8:9], v[98:99], v[6:7] op_sel_hi:[0,1,1]
	v_pk_mul_f32 v[8:9], v[20:21], v[90:91] op_sel:[0,1] op_sel_hi:[1,0]
	v_pk_add_f32 v[88:89], v[72:73], v[92:93] op_sel:[0,1] op_sel_hi:[1,0] neg_hi:[0,1]
	v_pk_fma_f32 v[8:9], v[10:11], v[90:91], v[8:9] op_sel_hi:[0,1,1]
	v_pk_mul_f32 v[10:11], v[16:17], v[96:97] op_sel:[0,1] op_sel_hi:[1,0]
	v_pk_add_f32 v[66:67], v[64:65], v[70:71] op_sel:[0,1] op_sel_hi:[1,0] neg_hi:[0,1]
	v_pk_fma_f32 v[10:11], v[12:13], v[96:97], v[10:11] op_sel_hi:[0,1,1]
	v_pk_mul_f32 v[12:13], v[22:23], v[88:89] op_sel:[0,1] op_sel_hi:[1,0]
	v_pk_add_f32 v[94:95], v[94:95], v[100:101] op_sel:[0,1] op_sel_hi:[1,0] neg_lo:[0,1]
	v_pk_add_f32 v[74:75], v[102:103], v[74:75] neg_lo:[0,1] neg_hi:[0,1]
	v_pk_add_f32 v[72:73], v[72:73], v[92:93] op_sel:[0,1] op_sel_hi:[1,0] neg_lo:[0,1]
	v_pk_add_f32 v[68:69], v[68:69], v[80:81] neg_lo:[0,1] neg_hi:[0,1]
	v_pk_add_f32 v[64:65], v[64:65], v[70:71] op_sel:[0,1] op_sel_hi:[1,0] neg_lo:[0,1]
	v_pk_fma_f32 v[12:13], v[18:19], v[88:89], v[12:13] op_sel_hi:[0,1,1]
	v_pk_mul_f32 v[14:15], v[26:27], v[76:77] op_sel:[0,1] op_sel_hi:[1,0]
	v_pk_mul_f32 v[16:17], v[30:31], v[66:67] op_sel:[0,1] op_sel_hi:[1,0]
	v_pk_mul_f32 v[18:19], v[34:35], v[82:83] op_sel:[0,1] op_sel_hi:[1,0]
	v_pk_fma_f32 v[14:15], v[24:25], v[76:77], v[14:15] op_sel_hi:[0,1,1]
	v_pk_fma_f32 v[16:17], v[28:29], v[66:67], v[16:17] op_sel_hi:[0,1,1]
	v_pk_fma_f32 v[18:19], v[32:33], v[82:83], v[18:19] op_sel_hi:[0,1,1]
	v_pk_mul_f32 v[20:21], v[38:39], v[74:75] op_sel:[0,1] op_sel_hi:[1,0]
	v_pk_mul_f32 v[22:23], v[42:43], v[78:79] op_sel:[0,1] op_sel_hi:[1,0]
	v_pk_mul_f32 v[24:25], v[46:47], v[68:69] op_sel:[0,1] op_sel_hi:[1,0]
	v_pk_mul_f32 v[26:27], v[50:51], v[94:95] op_sel:[0,1] op_sel_hi:[1,0]
	v_pk_mul_f32 v[28:29], v[54:55], v[72:73] op_sel:[0,1] op_sel_hi:[1,0]
	v_pk_mul_f32 v[30:31], v[58:59], v[84:85] op_sel:[0,1] op_sel_hi:[1,0]
	v_pk_mul_f32 v[32:33], v[62:63], v[64:65] op_sel:[0,1] op_sel_hi:[1,0]
	v_pk_fma_f32 v[20:21], v[36:37], v[74:75], v[20:21] op_sel_hi:[0,1,1]
	v_pk_fma_f32 v[22:23], v[40:41], v[78:79], v[22:23] op_sel_hi:[0,1,1]
	v_pk_fma_f32 v[24:25], v[44:45], v[68:69], v[24:25] op_sel_hi:[0,1,1]
	v_pk_fma_f32 v[26:27], v[48:49], v[94:95], v[26:27] op_sel_hi:[0,1,1]
	v_pk_fma_f32 v[28:29], v[52:53], v[72:73], v[28:29] op_sel_hi:[0,1,1]
	v_pk_fma_f32 v[30:31], v[56:57], v[84:85], v[30:31] op_sel_hi:[0,1,1]
	v_pk_fma_f32 v[32:33], v[60:61], v[64:65], v[32:33] op_sel_hi:[0,1,1]
	ds_write2_b64 v2, v[104:105], v[18:19] offset1:16
	ds_write2_b64 v2, v[10:11], v[26:27] offset0:33 offset1:49
	ds_write2_b64 v2, v[6:7], v[22:23] offset0:66 offset1:82
	ds_write2_b64 v2, v[14:15], v[30:31] offset0:99 offset1:115
	ds_write2_b64 v2, v[4:5], v[20:21] offset0:132 offset1:148
	ds_write2_b64 v2, v[12:13], v[28:29] offset0:165 offset1:181
	ds_write2_b64 v2, v[8:9], v[24:25] offset0:198 offset1:214
	ds_write2_b64 v2, v[16:17], v[32:33] offset0:231 offset1:247
	s_waitcnt lgkmcnt(0)
	s_barrier
	s_nop 0
	v_ashrrev_i32_e32 v2, 31, v142
	v_add_u32_sdwa v2, v142, v2 dst_sel:DWORD dst_unused:UNUSED_PAD src0_sel:DWORD src1_sel:BYTE_3
	v_ashrrev_i32_e32 v145, 8, v2
	v_mul_i32_i24_e32 v2, 0x100, v145
	v_sub_u32_e32 v144, v142, v2
	v_lshlrev_b32_e32 v2, 1, v144
	v_bfrev_b32_e32 v2, v2
	v_lshrrev_b32_e32 v2, 23, v2
	v_sub_u32_e32 v2, 0x200, v2
	v_bfrev_b32_e32 v2, v2
	v_lshrrev_b32_e32 v2, 19, v2
	v_lshlrev_b32_e32 v143, 13, v145
	v_and_b32_e32 v2, 0x1ff0, v2
	v_cmp_eq_u32_e32 vcc, 0, v144
	v_lshl_add_u32 v4, v144, 5, v143
	v_lshlrev_b32_e32 v5, 3, v4
	v_cndmask_b32_e64 v2, v2, 16, vcc
	v_ashrrev_i32_e32 v4, 2, v4
	v_or_b32_e32 v2, v2, v143
	v_add3_u32 v56, 0, v5, v4
	v_ashrrev_i32_e32 v4, 5, v2
	v_lshlrev_b32_e32 v2, 3, v2
	v_lshlrev_b32_e32 v4, 3, v4
	v_add3_u32 v2, 0, v2, v4
	ds_read2_b64 v[4:7], v56 offset1:1
	ds_read2_b64 v[8:11], v56 offset0:2 offset1:3
	ds_read2_b64 v[12:15], v2 offset1:1
	ds_read2_b64 v[16:19], v2 offset0:2 offset1:3
	ds_read2_b64 v[20:23], v56 offset0:4 offset1:5
	ds_read2_b64 v[24:27], v56 offset0:6 offset1:7
	ds_read2_b64 v[28:31], v2 offset0:4 offset1:5
	ds_read2_b64 v[32:35], v2 offset0:6 offset1:7
	ds_read2_b64 v[36:39], v56 offset0:8 offset1:9
	ds_read2_b64 v[40:43], v56 offset0:10 offset1:11
	ds_read2_b64 v[44:47], v2 offset0:8 offset1:9
	ds_read2_b64 v[52:55], v2 offset0:10 offset1:11
	ds_read2_b64 v[48:51], v56 offset0:12 offset1:13
	ds_read2_b64 v[56:59], v56 offset0:14 offset1:15
	ds_read2_b64 v[62:65], v2 offset0:12 offset1:13
	ds_read2_b64 v[74:77], v2 offset0:14 offset1:15
	s_waitcnt lgkmcnt(7)
	v_pk_add_f32 v[60:61], v[4:5], v[36:37]
	v_pk_add_f32 v[4:5], v[4:5], v[36:37] neg_lo:[0,1] neg_hi:[0,1]
	v_pk_add_f32 v[36:37], v[6:7], v[38:39]
	v_pk_add_f32 v[6:7], v[6:7], v[38:39] neg_lo:[0,1] neg_hi:[0,1]
	s_waitcnt lgkmcnt(3)
	v_pk_add_f32 v[66:67], v[22:23], v[50:51]
	v_pk_mul_f32 v[38:39], v[6:7], s[24:25]
	v_pk_add_f32 v[22:23], v[22:23], v[50:51] neg_lo:[0,1] neg_hi:[0,1]
	v_pk_fma_f32 v[6:7], v[6:7], s[22:23], v[38:39] op_sel:[0,0,1] op_sel_hi:[1,0,0]
	v_pk_add_f32 v[38:39], v[8:9], v[40:41]
	v_pk_add_f32 v[8:9], v[8:9], v[40:41] neg_lo:[0,1] neg_hi:[0,1]
	v_pk_mul_f32 v[50:51], v[22:23], s[44:45]
	v_pk_mul_f32 v[40:41], v[8:9], s[40:41]
	v_pk_fma_f32 v[22:23], v[22:23], s[50:51], v[50:51] op_sel:[0,0,1] op_sel_hi:[1,0,0] neg_lo:[1,0,0] neg_hi:[1,0,0]
	v_pk_fma_f32 v[8:9], v[8:9], s[38:39], v[40:41] op_sel:[0,0,1] op_sel_hi:[1,0,0]
	v_pk_add_f32 v[40:41], v[10:11], v[42:43]
	v_pk_add_f32 v[10:11], v[10:11], v[42:43] neg_lo:[0,1] neg_hi:[0,1]
	s_waitcnt lgkmcnt(2)
	v_pk_add_f32 v[50:51], v[24:25], v[56:57]
	v_pk_add_f32 v[24:25], v[24:25], v[56:57] neg_lo:[0,1] neg_hi:[0,1]
	v_pk_mul_f32 v[42:43], v[10:11], s[44:45]
	v_pk_mul_f32 v[56:57], v[24:25], s[40:41]
	v_pk_fma_f32 v[10:11], v[10:11], s[50:51], v[42:43] op_sel:[0,0,1] op_sel_hi:[1,0,0]
	v_pk_add_f32 v[42:43], v[20:21], v[48:49]
	v_pk_add_f32 v[48:49], v[20:21], v[48:49] neg_lo:[0,1] neg_hi:[0,1]
	v_pk_fma_f32 v[24:25], v[24:25], s[38:39], v[56:57] op_sel:[0,0,1] op_sel_hi:[1,0,0] neg_lo:[1,0,0] neg_hi:[1,0,0]
	v_pk_add_f32 v[56:57], v[26:27], v[58:59]
	v_pk_add_f32 v[26:27], v[26:27], v[58:59] neg_lo:[0,1] neg_hi:[0,1]
	s_nop 0
	v_pk_mul_f32 v[58:59], v[26:27], s[24:25]
	v_pk_add_f32 v[68:69], v[40:41], v[56:57]
	v_pk_add_f32 v[40:41], v[40:41], v[56:57] neg_lo:[0,1] neg_hi:[0,1]
	v_pk_fma_f32 v[26:27], v[26:27], s[22:23], v[58:59] op_sel:[0,0,1] op_sel_hi:[1,0,0] neg_lo:[1,0,0] neg_hi:[1,0,0]
	v_pk_mul_f32 v[56:57], v[40:41], s[40:41]
	v_pk_add_f32 v[20:21], v[4:5], v[48:49] op_sel:[0,1] op_sel_hi:[1,0] neg_hi:[0,1]
	v_pk_add_f32 v[4:5], v[4:5], v[48:49] op_sel:[0,1] op_sel_hi:[1,0] neg_lo:[0,1]
	v_pk_add_f32 v[48:49], v[6:7], v[22:23]
	v_pk_add_f32 v[6:7], v[6:7], v[22:23] neg_lo:[0,1] neg_hi:[0,1]
	v_pk_fma_f32 v[40:41], v[40:41], s[38:39], v[56:57] op_sel:[0,0,1] op_sel_hi:[1,0,0] neg_lo:[1,0,0] neg_hi:[1,0,0]
	v_pk_mul_f32 v[22:23], v[6:7], s[40:41]
	v_pk_add_f32 v[56:57], v[10:11], v[26:27]
	v_pk_add_f32 v[10:11], v[10:11], v[26:27] neg_lo:[0,1] neg_hi:[0,1]
	v_pk_add_f32 v[58:59], v[60:61], v[42:43]
	v_pk_add_f32 v[42:43], v[60:61], v[42:43] neg_lo:[0,1] neg_hi:[0,1]
	v_pk_add_f32 v[60:61], v[36:37], v[66:67]
	v_pk_add_f32 v[36:37], v[36:37], v[66:67] neg_lo:[0,1] neg_hi:[0,1]
	v_pk_fma_f32 v[6:7], v[6:7], s[38:39], v[22:23] op_sel:[0,0,1] op_sel_hi:[1,0,0]
	v_pk_add_f32 v[22:23], v[8:9], v[24:25]
	v_pk_add_f32 v[24:25], v[8:9], v[24:25] neg_lo:[0,1] neg_hi:[0,1]
	v_pk_mul_f32 v[26:27], v[10:11], s[40:41]
	v_pk_mul_f32 v[66:67], v[36:37], s[40:41]
	v_pk_fma_f32 v[10:11], v[10:11], s[38:39], v[26:27] op_sel:[0,0,1] op_sel_hi:[1,0,0] neg_lo:[1,0,0] neg_hi:[1,0,0]
	v_pk_fma_f32 v[36:37], v[36:37], s[38:39], v[66:67] op_sel:[0,0,1] op_sel_hi:[1,0,0]
	v_pk_add_f32 v[66:67], v[38:39], v[50:51]
	v_pk_add_f32 v[8:9], v[4:5], v[24:25] op_sel:[0,1] op_sel_hi:[1,0] neg_hi:[0,1]
	v_pk_add_f32 v[4:5], v[4:5], v[24:25] op_sel:[0,1] op_sel_hi:[1,0] neg_lo:[0,1]
	v_pk_add_f32 v[24:25], v[6:7], v[10:11]
	v_pk_add_f32 v[10:11], v[6:7], v[10:11] neg_lo:[0,1] neg_hi:[0,1]
	v_pk_add_f32 v[26:27], v[58:59], v[66:67]
	v_pk_add_f32 v[58:59], v[58:59], v[66:67] neg_lo:[0,1] neg_hi:[0,1]
	v_pk_add_f32 v[66:67], v[60:61], v[68:69]
	v_pk_add_f32 v[68:69], v[60:61], v[68:69] neg_lo:[0,1] neg_hi:[0,1]
	v_pk_add_f32 v[60:61], v[4:5], v[10:11] op_sel:[0,1] op_sel_hi:[1,0] neg_hi:[0,1]
	v_pk_add_f32 v[90:91], v[4:5], v[10:11] op_sel:[0,1] op_sel_hi:[1,0] neg_lo:[0,1]
	v_pk_add_f32 v[10:11], v[14:15], v[46:47] neg_lo:[0,1] neg_hi:[0,1]
	v_pk_add_f32 v[50:51], v[38:39], v[50:51] neg_lo:[0,1] neg_hi:[0,1]
	v_pk_add_f32 v[84:85], v[58:59], v[68:69] op_sel:[0,1] op_sel_hi:[1,0] neg_hi:[0,1]
	v_pk_add_f32 v[86:87], v[58:59], v[68:69] op_sel:[0,1] op_sel_hi:[1,0] neg_lo:[0,1]
	v_pk_add_f32 v[82:83], v[8:9], v[24:25]
	v_pk_add_f32 v[68:69], v[8:9], v[24:25] neg_lo:[0,1] neg_hi:[0,1]
	v_pk_add_f32 v[4:5], v[12:13], v[44:45]
	v_pk_add_f32 v[6:7], v[12:13], v[44:45] neg_lo:[0,1] neg_hi:[0,1]
	v_pk_add_f32 v[8:9], v[14:15], v[46:47]
	v_pk_mul_f32 v[12:13], v[10:11], s[24:25]
	v_pk_add_f32 v[14:15], v[16:17], v[52:53] neg_lo:[0,1] neg_hi:[0,1]
	v_pk_add_f32 v[70:71], v[20:21], v[22:23]
	v_pk_add_f32 v[20:21], v[20:21], v[22:23] neg_lo:[0,1] neg_hi:[0,1]
	v_pk_add_f32 v[22:23], v[48:49], v[56:57]
	v_pk_add_f32 v[48:49], v[48:49], v[56:57] neg_lo:[0,1] neg_hi:[0,1]
	v_pk_fma_f32 v[10:11], v[10:11], s[22:23], v[12:13] op_sel:[0,0,1] op_sel_hi:[1,0,0]
	v_pk_add_f32 v[12:13], v[16:17], v[52:53]
	v_pk_mul_f32 v[16:17], v[14:15], s[40:41]
	v_pk_add_f32 v[38:39], v[42:43], v[50:51] op_sel:[0,1] op_sel_hi:[1,0] neg_hi:[0,1]
	v_pk_add_f32 v[42:43], v[42:43], v[50:51] op_sel:[0,1] op_sel_hi:[1,0] neg_lo:[0,1]
	v_pk_add_f32 v[50:51], v[36:37], v[40:41]
	v_xor_b32_e32 v57, 0x80000000, v48
	v_mov_b32_e32 v56, v49
	v_pk_fma_f32 v[14:15], v[14:15], s[38:39], v[16:17] op_sel:[0,0,1] op_sel_hi:[1,0,0]
	v_pk_add_f32 v[16:17], v[18:19], v[54:55]
	v_pk_add_f32 v[18:19], v[18:19], v[54:55] neg_lo:[0,1] neg_hi:[0,1]
	v_pk_add_f32 v[130:131], v[26:27], v[66:67]
	v_pk_add_f32 v[92:93], v[26:27], v[66:67] neg_lo:[0,1] neg_hi:[0,1]
	v_pk_add_f32 v[88:89], v[38:39], v[50:51]
	v_pk_add_f32 v[72:73], v[38:39], v[50:51] neg_lo:[0,1] neg_hi:[0,1]
	v_pk_add_f32 v[96:97], v[70:71], v[22:23]
	v_pk_add_f32 v[50:51], v[70:71], v[22:23] neg_lo:[0,1] neg_hi:[0,1]
	v_pk_add_f32 v[66:67], v[20:21], v[56:57]
	v_pk_add_f32 v[80:81], v[20:21], v[56:57] neg_lo:[0,1] neg_hi:[0,1]
	v_pk_mul_f32 v[20:21], v[18:19], s[44:45]
	s_waitcnt lgkmcnt(1)
	v_pk_add_f32 v[24:25], v[28:29], v[62:63] neg_lo:[0,1] neg_hi:[0,1]
	v_pk_add_f32 v[26:27], v[30:31], v[64:65] neg_lo:[0,1] neg_hi:[0,1]
	v_pk_fma_f32 v[18:19], v[18:19], s[50:51], v[20:21] op_sel:[0,0,1] op_sel_hi:[1,0,0]
	v_pk_add_f32 v[20:21], v[28:29], v[62:63]
	v_pk_add_f32 v[22:23], v[30:31], v[64:65]
	v_pk_mul_f32 v[28:29], v[26:27], s[44:45]
	s_waitcnt lgkmcnt(0)
	v_pk_add_f32 v[30:31], v[32:33], v[74:75] neg_lo:[0,1] neg_hi:[0,1]
	v_pk_fma_f32 v[26:27], v[26:27], s[50:51], v[28:29] op_sel:[0,0,1] op_sel_hi:[1,0,0] neg_lo:[1,0,0] neg_hi:[1,0,0]
	v_pk_add_f32 v[28:29], v[32:33], v[74:75]
	v_pk_mul_f32 v[32:33], v[30:31], s[40:41]
	v_pk_add_f32 v[36:37], v[36:37], v[40:41] neg_lo:[0,1] neg_hi:[0,1]
	v_pk_fma_f32 v[30:31], v[30:31], s[38:39], v[32:33] op_sel:[0,0,1] op_sel_hi:[1,0,0] neg_lo:[1,0,0] neg_hi:[1,0,0]
	v_pk_add_f32 v[32:33], v[34:35], v[76:77]
	v_pk_add_f32 v[34:35], v[34:35], v[76:77] neg_lo:[0,1] neg_hi:[0,1]
	v_xor_b32_e32 v41, 0x80000000, v36
	v_mov_b32_e32 v40, v37
	v_pk_mul_f32 v[36:37], v[34:35], s[24:25]
	v_mov_b32_e32 v2, v130
	v_pk_fma_f32 v[34:35], v[34:35], s[22:23], v[36:37] op_sel:[0,0,1] op_sel_hi:[1,0,0] neg_lo:[1,0,0] neg_hi:[1,0,0]
	v_pk_add_f32 v[36:37], v[4:5], v[20:21]
	v_pk_add_f32 v[4:5], v[4:5], v[20:21] neg_lo:[0,1] neg_hi:[0,1]
	v_pk_add_f32 v[20:21], v[8:9], v[22:23]
	v_pk_add_f32 v[8:9], v[8:9], v[22:23] neg_lo:[0,1] neg_hi:[0,1]
	v_cmp_ne_u32_e64 s[0:1], 0, v144
	v_pk_mul_f32 v[22:23], v[8:9], s[40:41]
	v_pk_add_f32 v[78:79], v[42:43], v[40:41]
	v_pk_fma_f32 v[8:9], v[8:9], s[38:39], v[22:23] op_sel:[0,0,1] op_sel_hi:[1,0,0]
	v_pk_add_f32 v[22:23], v[12:13], v[28:29]
	v_pk_add_f32 v[28:29], v[12:13], v[28:29] neg_lo:[0,1] neg_hi:[0,1]
	v_pk_add_f32 v[94:95], v[42:43], v[40:41] neg_lo:[0,1] neg_hi:[0,1]
	v_pk_add_f32 v[12:13], v[16:17], v[32:33]
	v_pk_add_f32 v[16:17], v[16:17], v[32:33] neg_lo:[0,1] neg_hi:[0,1]
	s_nop 0
	v_pk_mul_f32 v[32:33], v[16:17], s[40:41]
	s_nop 0
	v_pk_fma_f32 v[16:17], v[16:17], s[38:39], v[32:33] op_sel:[0,0,1] op_sel_hi:[1,0,0] neg_lo:[1,0,0] neg_hi:[1,0,0]
	v_pk_add_f32 v[32:33], v[6:7], v[24:25] op_sel:[0,1] op_sel_hi:[1,0] neg_hi:[0,1]
	v_pk_add_f32 v[6:7], v[6:7], v[24:25] op_sel:[0,1] op_sel_hi:[1,0] neg_lo:[0,1]
	v_pk_add_f32 v[24:25], v[10:11], v[26:27]
	v_pk_add_f32 v[10:11], v[10:11], v[26:27] neg_lo:[0,1] neg_hi:[0,1]
	s_nop 0
	v_pk_mul_f32 v[26:27], v[10:11], s[40:41]
	s_nop 0
	v_pk_fma_f32 v[10:11], v[10:11], s[38:39], v[26:27] op_sel:[0,0,1] op_sel_hi:[1,0,0]
	v_pk_add_f32 v[26:27], v[14:15], v[30:31]
	v_pk_add_f32 v[30:31], v[14:15], v[30:31] neg_lo:[0,1] neg_hi:[0,1]
	s_nop 0
	v_pk_add_f32 v[14:15], v[18:19], v[34:35]
	v_pk_add_f32 v[18:19], v[18:19], v[34:35] neg_lo:[0,1] neg_hi:[0,1]
	s_nop 0
	v_pk_mul_f32 v[34:35], v[18:19], s[40:41]
	s_nop 0
	v_pk_fma_f32 v[18:19], v[18:19], s[38:39], v[34:35] op_sel:[0,0,1] op_sel_hi:[1,0,0] neg_lo:[1,0,0] neg_hi:[1,0,0]
	v_pk_add_f32 v[34:35], v[36:37], v[22:23]
	v_pk_add_f32 v[22:23], v[36:37], v[22:23] neg_lo:[0,1] neg_hi:[0,1]
	v_pk_add_f32 v[36:37], v[20:21], v[12:13]
	v_pk_add_f32 v[12:13], v[20:21], v[12:13] neg_lo:[0,1] neg_hi:[0,1]
	v_pk_add_f32 v[98:99], v[34:35], v[36:37]
	v_xor_b32_e32 v21, 0x80000000, v12
	v_mov_b32_e32 v20, v13
	v_pk_add_f32 v[12:13], v[4:5], v[28:29] op_sel:[0,1] op_sel_hi:[1,0] neg_hi:[0,1]
	v_pk_add_f32 v[4:5], v[4:5], v[28:29] op_sel:[0,1] op_sel_hi:[1,0] neg_lo:[0,1]
	v_pk_add_f32 v[28:29], v[8:9], v[16:17]
	v_pk_add_f32 v[8:9], v[8:9], v[16:17] neg_lo:[0,1] neg_hi:[0,1]
	v_pk_add_f32 v[100:101], v[34:35], v[36:37] neg_lo:[0,1] neg_hi:[0,1]
	v_xor_b32_e32 v17, 0x80000000, v8
	v_mov_b32_e32 v16, v9
	v_pk_add_f32 v[8:9], v[32:33], v[26:27]
	v_pk_add_f32 v[26:27], v[32:33], v[26:27] neg_lo:[0,1] neg_hi:[0,1]
	v_pk_add_f32 v[32:33], v[24:25], v[14:15]
	v_pk_add_f32 v[14:15], v[24:25], v[14:15] neg_lo:[0,1] neg_hi:[0,1]
	v_pk_add_f32 v[102:103], v[22:23], v[20:21]
	v_xor_b32_e32 v25, 0x80000000, v14
	v_mov_b32_e32 v24, v15
	v_pk_add_f32 v[14:15], v[6:7], v[30:31] op_sel:[0,1] op_sel_hi:[1,0] neg_hi:[0,1]
	v_pk_add_f32 v[6:7], v[6:7], v[30:31] op_sel:[0,1] op_sel_hi:[1,0] neg_lo:[0,1]
	v_pk_add_f32 v[30:31], v[10:11], v[18:19]
	v_pk_add_f32 v[10:11], v[10:11], v[18:19] neg_lo:[0,1] neg_hi:[0,1]
	v_pk_add_f32 v[104:105], v[22:23], v[20:21] neg_lo:[0,1] neg_hi:[0,1]
	v_xor_b32_e32 v19, 0x80000000, v10
	v_mov_b32_e32 v18, v11
	v_pk_add_f32 v[106:107], v[12:13], v[28:29]
	v_pk_add_f32 v[108:109], v[12:13], v[28:29] neg_lo:[0,1] neg_hi:[0,1]
	v_pk_add_f32 v[110:111], v[4:5], v[16:17]
	v_pk_add_f32 v[112:113], v[4:5], v[16:17] neg_lo:[0,1] neg_hi:[0,1]
	v_pk_add_f32 v[114:115], v[8:9], v[32:33]
	v_pk_add_f32 v[116:117], v[8:9], v[32:33] neg_lo:[0,1] neg_hi:[0,1]
	v_pk_add_f32 v[118:119], v[26:27], v[24:25]
	v_pk_add_f32 v[120:121], v[26:27], v[24:25] neg_lo:[0,1] neg_hi:[0,1]
	v_pk_add_f32 v[122:123], v[14:15], v[30:31]
	v_pk_add_f32 v[124:125], v[14:15], v[30:31] neg_lo:[0,1] neg_hi:[0,1]
	v_pk_add_f32 v[126:127], v[6:7], v[18:19]
	v_pk_add_f32 v[128:129], v[6:7], v[18:19] neg_lo:[0,1] neg_hi:[0,1]
	v_mov_b32_e32 v4, v131
	v_mov_b32_e32 v5, v3
	v_mov_b64_e32 v[6:7], v[2:3]
	s_and_saveexec_b64 s[50:51], s[0:1]
	s_xor_b64 s[0:1], exec, s[50:51]
	s_cbranch_execz .LBB0_576
	v_pk_add_f32 v[4:5], v[96:97], v[112:113]
	v_pk_add_f32 v[24:25], v[96:97], v[112:113] neg_lo:[0,1] neg_hi:[0,1]
	v_pk_add_f32 v[148:149], v[130:131], v[128:129]
	v_pk_add_f32 v[8:9], v[130:131], v[128:129] neg_lo:[0,1] neg_hi:[0,1]
	v_pk_add_f32 v[128:129], v[126:127], v[92:93]
	v_pk_add_f32 v[10:11], v[126:127], v[92:93] neg_lo:[0,1] neg_hi:[0,1]
	v_pk_add_f32 v[92:93], v[84:85], v[124:125]
	v_pk_add_f32 v[12:13], v[84:85], v[124:125] neg_lo:[0,1] neg_hi:[0,1]
	v_pk_add_f32 v[84:85], v[122:123], v[86:87]
	v_pk_add_f32 v[14:15], v[122:123], v[86:87] neg_lo:[0,1] neg_hi:[0,1]
	v_pk_add_f32 v[86:87], v[88:89], v[120:121]
	v_pk_add_f32 v[16:17], v[88:89], v[120:121] neg_lo:[0,1] neg_hi:[0,1]
	v_pk_add_f32 v[88:89], v[118:119], v[72:73]
	v_pk_add_f32 v[18:19], v[118:119], v[72:73] neg_lo:[0,1] neg_hi:[0,1]
	v_pk_add_f32 v[72:73], v[78:79], v[116:117]
	v_pk_add_f32 v[20:21], v[78:79], v[116:117] neg_lo:[0,1] neg_hi:[0,1]
	v_pk_add_f32 v[78:79], v[114:115], v[94:95]
	v_pk_add_f32 v[22:23], v[114:115], v[94:95] neg_lo:[0,1] neg_hi:[0,1]
	v_mov_b32_e32 v6, v4
	v_mov_b32_e32 v7, v25
	v_pk_mov_b32 v[4:5], v[4:5], v[24:25] op_sel:[1,0]
	v_pk_add_f32 v[94:95], v[110:111], v[50:51]
	v_pk_add_f32 v[24:25], v[110:111], v[50:51] neg_lo:[0,1] neg_hi:[0,1]
	v_pk_add_f32 v[50:51], v[66:67], v[108:109]
	v_pk_add_f32 v[26:27], v[66:67], v[108:109] neg_lo:[0,1] neg_hi:[0,1]
	v_pk_add_f32 v[66:67], v[106:107], v[80:81]
	v_pk_add_f32 v[28:29], v[106:107], v[80:81] neg_lo:[0,1] neg_hi:[0,1]
	v_pk_add_f32 v[80:81], v[82:83], v[104:105]
	v_pk_add_f32 v[30:31], v[82:83], v[104:105] neg_lo:[0,1] neg_hi:[0,1]
	v_pk_add_f32 v[82:83], v[102:103], v[68:69]
	v_pk_add_f32 v[32:33], v[102:103], v[68:69] neg_lo:[0,1] neg_hi:[0,1]
	v_pk_add_f32 v[68:69], v[60:61], v[100:101]
	v_pk_add_f32 v[34:35], v[60:61], v[100:101] neg_lo:[0,1] neg_hi:[0,1]
	v_pk_add_f32 v[60:61], v[98:99], v[90:91]
	v_pk_add_f32 v[36:37], v[98:99], v[90:91] neg_lo:[0,1] neg_hi:[0,1]
	v_pk_mul_f32 v[6:7], v[6:7], 0.5 op_sel_hi:[1,0]
	v_pk_mul_f32 v[4:5], v[4:5], s[46:47]
	v_mov_b32_e32 v39, v8
	v_mov_b32_e32 v38, v149
	v_mov_b32_e32 v41, v10
	v_mov_b32_e32 v40, v129
	v_mov_b32_e32 v43, v12
	v_mov_b32_e32 v42, v93
	v_mov_b32_e32 v45, v14
	v_mov_b32_e32 v44, v85
	v_mov_b32_e32 v47, v16
	v_mov_b32_e32 v46, v87
	v_mov_b32_e32 v49, v18
	v_mov_b32_e32 v48, v89
	v_mov_b32_e32 v53, v20
	v_mov_b32_e32 v52, v73
	v_mov_b32_e32 v55, v22
	v_mov_b32_e32 v54, v79
	v_mov_b32_e32 v57, v24
	v_mov_b32_e32 v56, v95
	v_mov_b32_e32 v59, v26
	v_mov_b32_e32 v58, v51
	v_mov_b32_e32 v63, v28
	v_mov_b32_e32 v62, v67
	v_mov_b32_e32 v65, v30
	v_mov_b32_e32 v64, v81
	v_mov_b32_e32 v71, v32
	v_mov_b32_e32 v70, v83
	v_mov_b32_e32 v75, v34
	v_mov_b32_e32 v74, v69
	v_mov_b32_e32 v77, v36
	v_mov_b32_e32 v76, v61
	v_mov_b32_e32 v8, v148
	v_mov_b32_e32 v10, v128
	v_mov_b32_e32 v12, v92
	v_mov_b32_e32 v14, v84
	v_mov_b32_e32 v16, v86
	v_mov_b32_e32 v18, v88
	v_mov_b32_e32 v20, v72
	v_mov_b32_e32 v22, v78
	v_mov_b32_e32 v24, v94
	v_mov_b32_e32 v26, v50
	v_mov_b32_e32 v28, v66
	v_mov_b32_e32 v30, v80
	v_mov_b32_e32 v32, v82
	v_mov_b32_e32 v34, v68
	v_mov_b32_e32 v36, v60
